# all flat_load/flat_store converted to global_load/global_store (same addresses, vmcnt-only tracking) on top of the previous version
# speedup vs baseline: 1.0030x; 1.0020x over previous
; #define LAS __attribute__((address_space(3)))
; DI unsigned pk2(float a, float b) { f32x2 v = {a, b}; bf16v2 r = __builtin_convertvector(v, bf16v2); return __builtin_bit_cast(unsigned, r); }
; DI void tr_item(const float* src, size_t sld, bf16_t* dst, size_t dld, const float* ksc, LAS unsigned* scr, int lane) {
;     ...
;         LAS unsigned* d = scr + (4 * ng) * 33 + 4 * i + kq;
;         d[0] = pk2(a[0], b[0]); d[33] = pk2(a[1], b[1]); d[66] = pk2(a[2], b[2]); d[99] = pk2(a[3], b[3]);
;     }
;     asm volatile("s_waitcnt lgkmcnt(0)" ::: "memory");
; #pragma unroll
;     for (int j = 0; j < 8; ++j) {
;         const int n = (lane >> 3) + 8 * j, c = lane & 7;
;         const LAS unsigned* s = scr + n * 33 + 4 * c;
;         u32x4 o; o.x = s[0]; o.y = s[1]; o.z = s[2]; o.w = s[3];
;         *(u32x4*)(dst + (size_t)n * dld + 8 * c) = o;
;     }
;     asm volatile("s_waitcnt lgkmcnt(0)" ::: "memory");
.LBB0_11:
	s_waitcnt vmcnt(0) lgkmcnt(0)
	v_cvt_pk_bf16_f32 v2, v2, v6
	v_cvt_pk_bf16_f32 v3, v3, v7
	s_ashr_i32 s21, s20, 31
	ds_write2_b32 v13, v2, v3 offset0:28 offset1:61
	v_cvt_pk_bf16_f32 v2, v4, v8
	v_cvt_pk_bf16_f32 v3, v5, v9
	s_lshl_b64 s[4:5], s[20:21], 18
	ds_write2_b32 v13, v2, v3 offset0:94 offset1:127
	s_add_u32 s6, s57, s4
	s_waitcnt lgkmcnt(0)
	v_add_u32_e32 v144, v143, v51
	s_addc_u32 s20, s58, s5
	s_lshl_b64 s[4:5], s[22:23], 1
	ds_read2_b32 v[2:3], v144 offset1:1
	ds_read2_b32 v[4:5], v144 offset0:2 offset1:3
	s_add_u32 s4, s6, s4
	s_addc_u32 s5, s20, s5
	v_lshlrev_b32_e32 v14, 1, v142
	v_lshl_add_u64 v[6:7], s[4:5], 0, v[14:15]
	v_lshl_add_u64 v[8:9], v[6:7], 0, v[114:115]
	s_waitcnt lgkmcnt(0)
	global_store_dwordx4 v[8:9], v[2:5], off
	v_lshl_add_u64 v[8:9], v[6:7], 0, v[116:117]
	s_nop 0
	v_add_u32_e32 v2, 0x420, v144
	v_add_u32_e32 v4, 0x428, v144
	ds_read2_b32 v[2:3], v2 offset1:1
	ds_read2_b32 v[4:5], v4 offset1:1
	s_waitcnt lgkmcnt(0)
	global_store_dwordx4 v[8:9], v[2:5], off
	s_nop 1
	v_add_u32_e32 v2, 0x840, v144
	v_add_u32_e32 v4, 0x848, v144
	ds_read2_b32 v[2:3], v2 offset1:1
	ds_read2_b32 v[4:5], v4 offset1:1
	v_lshl_add_u64 v[8:9], v[6:7], 0, v[118:119]
	s_waitcnt lgkmcnt(0)
	global_store_dwordx4 v[8:9], v[2:5], off
	s_nop 1
	v_add_u32_e32 v2, 0xc60, v144
	v_add_u32_e32 v4, 0xc68, v144
	ds_read2_b32 v[2:3], v2 offset1:1
	ds_read2_b32 v[4:5], v4 offset1:1
	v_lshl_add_u64 v[8:9], v[6:7], 0, v[120:121]
	s_waitcnt lgkmcnt(0)
	global_store_dwordx4 v[8:9], v[2:5], off
	s_nop 1
	v_add_u32_e32 v2, 0x1080, v144
	v_add_u32_e32 v4, 0x1088, v144
	ds_read2_b32 v[2:3], v2 offset1:1
	ds_read2_b32 v[4:5], v4 offset1:1
	v_lshl_add_u64 v[8:9], v[6:7], 0, v[122:123]
	s_waitcnt lgkmcnt(0)
	global_store_dwordx4 v[8:9], v[2:5], off
	s_nop 1
	v_add_u32_e32 v2, 0x14a0, v144
	v_add_u32_e32 v4, 0x14a8, v144
	ds_read2_b32 v[2:3], v2 offset1:1
	ds_read2_b32 v[4:5], v4 offset1:1
	v_lshl_add_u64 v[8:9], v[6:7], 0, v[124:125]
	s_waitcnt lgkmcnt(0)
	global_store_dwordx4 v[8:9], v[2:5], off
	s_nop 1
	v_add_u32_e32 v2, 0x18c0, v144
	v_add_u32_e32 v4, 0x18c8, v144
	ds_read2_b32 v[2:3], v2 offset1:1
	ds_read2_b32 v[4:5], v4 offset1:1
	v_lshl_add_u64 v[8:9], v[6:7], 0, v[126:127]
	v_lshl_add_u64 v[6:7], v[6:7], 0, v[128:129]
	s_waitcnt lgkmcnt(0)
	global_store_dwordx4 v[8:9], v[2:5], off
	s_nop 1
	v_add_u32_e32 v2, 0x1ce0, v144
	v_add_u32_e32 v4, 0x1ce8, v144
	ds_read2_b32 v[2:3], v2 offset1:1
	ds_read2_b32 v[4:5], v4 offset1:1
	s_waitcnt lgkmcnt(0)
	global_store_dwordx4 v[6:7], v[2:5], off
	s_waitcnt lgkmcnt(0)

; #define LAS __attribute__((address_space(3)))
; template <int I> DI const float* kin() { return (const float*)karg64<I * 8>(); }
; DI unsigned pk2(float a, float b) { f32x2 v = {a, b}; bf16v2 r = __builtin_convertvector(v, bf16v2); return __builtin_bit_cast(unsigned, r); }
; DI void tr_item(const float* src, size_t sld, bf16_t* dst, size_t dld, const float* ksc, LAS unsigned* scr, int lane) {
;     ...
;     for (int i = 0; i < 8; ++i) {
;         const int k = 8 * i + 2 * kq;
;         f32x4 a = *(const f32x4*)(src + (size_t)k * sld + 4 * ng);
;         f32x4 b = *(const f32x4*)(src + (size_t)(k + 1) * sld + 4 * ng);
;         if (ksc) { a *= ksc[k]; b *= ksc[k + 1]; }
;         LAS unsigned* d = scr + (4 * ng) * 33 + 4 * i + kq;
;         d[0] = pk2(a[0], b[0]); d[33] = pk2(a[1], b[1]); d[66] = pk2(a[2], b[2]); d[99] = pk2(a[3], b[3]);
;     }
;     asm volatile("s_waitcnt lgkmcnt(0)" ::: "memory");
; #pragma unroll
;     for (int j = 0; j < 8; ++j) {
;         const int n = (lane >> 3) + 8 * j, c = lane & 7;
;         const LAS unsigned* s = scr + n * 33 + 4 * c;
;         u32x4 o; o.x = s[0]; o.y = s[1]; o.z = s[2]; o.w = s[3];
;         *(u32x4*)(dst + (size_t)n * dld + 8 * c) = o;
;     }
;     asm volatile("s_waitcnt lgkmcnt(0)" ::: "memory");
; DI void phase_prologue(const Ctx& c) {
;     ...
;         { const int wsel = r / (8 * I_LRU), rr = r - wsel * 8 * I_LRU, blk = rr / I_LRU, sub = rr - blk * I_LRU;
;           conv_matrix_item((wsel ? kin<14>() : kin<12>()) + ((size_t)l * 8 + blk) * 16384, 128, 128, lruw + (((size_t)l * 2 + wsel) * 8 + blk) * 16384, nullptr, sub, scr, c.lane); }
.LBB0_23:
	s_bfe_u32 s25, s56, 0x30002
	s_and_b32 s6, s56, 2
	s_lshl_b64 s[22:23], s[20:21], 19
	s_add_u32 s4, s4, s22
	s_addc_u32 s5, s5, s23
	s_lshl_b32 s22, s25, 16
	s_add_u32 s22, s4, s22
	s_addc_u32 s23, s5, 0
	s_lshr_b32 s24, s24, 2
	s_lshl_b64 s[4:5], s[20:21], 4
	s_and_b32 s24, s24, 0x3ffffff8
	s_add_u32 s4, s4, s24
	s_addc_u32 s5, s5, 0
	s_or_b32 s4, s4, s25
	s_lshl_b64 s[4:5], s[4:5], 15
	s_lshl_b32 s24, s6, 14
	s_add_u32 s22, s22, s24
	s_addc_u32 s23, s23, 0
	s_add_u32 s22, s22, s30
	s_addc_u32 s23, s23, 0
	v_lshlrev_b32_e32 v14, 2, v12
	v_lshl_add_u64 v[2:3], s[22:23], 0, v[14:15]
	v_lshl_add_u64 v[144:145], v[2:3], 0, v[10:11]
	global_load_dwordx4 v[2:5], v[144:145], off
	global_load_dwordx4 v[6:9], v[144:145], off offset:512
	v_add_co_u32_e32 v146, vcc, s31, v144
	s_add_u32 s4, s11, s4
	s_nop 0
	v_addc_co_u32_e32 v147, vcc, 0, v145, vcc
	s_addc_u32 s5, s28, s5
	s_lshl_b32 s6, s6, 6
	s_add_u32 s4, s4, s6
	v_lshlrev_b32_e32 v14, 1, v142
	s_addc_u32 s5, s5, 0
	s_waitcnt vmcnt(0) lgkmcnt(0)
	v_cvt_pk_bf16_f32 v2, v2, v6
	v_cvt_pk_bf16_f32 v3, v3, v7
	v_cvt_pk_bf16_f32 v4, v4, v8
	v_cvt_pk_bf16_f32 v5, v5, v9
	ds_write_b32 v13, v2
	ds_write_b32 v13, v3 offset:132
	ds_write_b32 v13, v4 offset:264
	ds_write_b32 v13, v5 offset:396
	global_load_dwordx4 v[2:5], v[146:147], off
	global_load_dwordx4 v[6:9], v[146:147], off offset:512
	v_add_co_u32_e32 v146, vcc, s34, v144
	s_waitcnt vmcnt(0) lgkmcnt(0)
	v_cvt_pk_bf16_f32 v2, v2, v6
	v_addc_co_u32_e32 v147, vcc, 0, v145, vcc
	v_cvt_pk_bf16_f32 v3, v3, v7
	v_cvt_pk_bf16_f32 v4, v4, v8
	v_cvt_pk_bf16_f32 v5, v5, v9
	ds_write_b32 v13, v2 offset:16
	ds_write_b32 v13, v3 offset:148
	ds_write_b32 v13, v4 offset:280
	ds_write_b32 v13, v5 offset:412
	global_load_dwordx4 v[2:5], v[146:147], off
	global_load_dwordx4 v[6:9], v[146:147], off offset:512
	v_add_co_u32_e32 v146, vcc, s35, v144
	s_waitcnt vmcnt(0) lgkmcnt(0)
	v_cvt_pk_bf16_f32 v2, v2, v6
	v_addc_co_u32_e32 v147, vcc, 0, v145, vcc
	v_cvt_pk_bf16_f32 v3, v3, v7
	v_cvt_pk_bf16_f32 v4, v4, v8
	v_cvt_pk_bf16_f32 v5, v5, v9
	ds_write_b32 v13, v2 offset:32
	ds_write_b32 v13, v3 offset:164
	ds_write_b32 v13, v4 offset:296
	ds_write_b32 v13, v5 offset:428
	global_load_dwordx4 v[2:5], v[146:147], off
	global_load_dwordx4 v[6:9], v[146:147], off offset:512
	v_add_co_u32_e32 v146, vcc, s36, v144
	s_waitcnt vmcnt(0) lgkmcnt(0)
	v_cvt_pk_bf16_f32 v2, v2, v6
	v_addc_co_u32_e32 v147, vcc, 0, v145, vcc
	v_cvt_pk_bf16_f32 v3, v3, v7
	v_cvt_pk_bf16_f32 v4, v4, v8
	v_cvt_pk_bf16_f32 v5, v5, v9
	ds_write_b32 v13, v2 offset:48
	ds_write_b32 v13, v3 offset:180
	ds_write_b32 v13, v4 offset:312
	ds_write_b32 v13, v5 offset:444
	global_load_dwordx4 v[2:5], v[146:147], off
	global_load_dwordx4 v[6:9], v[146:147], off offset:512
	v_add_co_u32_e32 v146, vcc, s37, v144
	s_waitcnt vmcnt(0) lgkmcnt(0)
	v_cvt_pk_bf16_f32 v2, v2, v6
	v_addc_co_u32_e32 v147, vcc, 0, v145, vcc
	v_cvt_pk_bf16_f32 v3, v3, v7
	v_cvt_pk_bf16_f32 v4, v4, v8
	v_cvt_pk_bf16_f32 v5, v5, v9
	ds_write_b32 v13, v2 offset:64
	ds_write_b32 v13, v3 offset:196
	ds_write_b32 v13, v4 offset:328
	ds_write_b32 v13, v5 offset:460
	global_load_dwordx4 v[2:5], v[146:147], off
	global_load_dwordx4 v[6:9], v[146:147], off offset:512
	v_add_co_u32_e32 v146, vcc, s38, v144
	s_waitcnt vmcnt(0) lgkmcnt(0)
	v_cvt_pk_bf16_f32 v2, v2, v6
	v_addc_co_u32_e32 v147, vcc, 0, v145, vcc
	v_cvt_pk_bf16_f32 v3, v3, v7
	v_cvt_pk_bf16_f32 v4, v4, v8
	v_cvt_pk_bf16_f32 v5, v5, v9
	ds_write_b32 v13, v2 offset:80
	ds_write_b32 v13, v3 offset:212
	ds_write_b32 v13, v4 offset:344
	ds_write_b32 v13, v5 offset:476
	global_load_dwordx4 v[2:5], v[146:147], off
	global_load_dwordx4 v[6:9], v[146:147], off offset:512
	v_add_co_u32_e32 v144, vcc, s39, v144
	s_waitcnt vmcnt(0) lgkmcnt(0)
	v_cvt_pk_bf16_f32 v2, v2, v6
	v_addc_co_u32_e32 v145, vcc, 0, v145, vcc
	v_cvt_pk_bf16_f32 v3, v3, v7
	v_cvt_pk_bf16_f32 v4, v4, v8
	v_cvt_pk_bf16_f32 v5, v5, v9
	ds_write_b32 v13, v2 offset:96
	ds_write_b32 v13, v3 offset:228
	ds_write_b32 v13, v4 offset:360
	ds_write_b32 v13, v5 offset:492
	global_load_dwordx4 v[2:5], v[144:145], off
	global_load_dwordx4 v[6:9], v[144:145], off offset:512
	v_add_u32_e32 v144, v143, v51
	v_add_u32_e32 v145, 0x420, v144
	v_add_u32_e32 v146, 0x428, v144
	s_waitcnt vmcnt(0) lgkmcnt(0)
	v_cvt_pk_bf16_f32 v2, v2, v6
	v_cvt_pk_bf16_f32 v3, v3, v7
	v_cvt_pk_bf16_f32 v4, v4, v8
	v_cvt_pk_bf16_f32 v5, v5, v9
	ds_write_b32 v13, v2 offset:112
	ds_write_b32 v13, v3 offset:244
	ds_write_b32 v13, v4 offset:376
	ds_write_b32 v13, v5 offset:508
	s_waitcnt lgkmcnt(0)
	ds_read2_b32 v[2:3], v144 offset1:1
	ds_read2_b32 v[4:5], v144 offset0:2 offset1:3
	v_lshl_add_u64 v[6:7], s[4:5], 0, v[14:15]
	v_lshl_add_u64 v[8:9], v[6:7], 0, v[16:17]
	v_add_u32_e32 v14, 0x840, v144
	s_mov_b64 s[4:5], 0
	s_waitcnt lgkmcnt(0)
	global_store_dwordx4 v[8:9], v[2:5], off
	ds_read2_b32 v[2:3], v145 offset1:1
	ds_read2_b32 v[4:5], v146 offset1:1
	v_lshl_add_u64 v[8:9], v[6:7], 0, v[18:19]
	v_add_u32_e32 v145, 0x848, v144
	s_waitcnt lgkmcnt(0)
	global_store_dwordx4 v[8:9], v[2:5], off
	ds_read2_b32 v[2:3], v14 offset1:1
	ds_read2_b32 v[4:5], v145 offset1:1
	v_lshl_add_u64 v[8:9], v[6:7], 0, v[20:21]
	v_add_u32_e32 v14, 0xc60, v144
	v_add_u32_e32 v145, 0xc68, v144
	s_waitcnt lgkmcnt(0)
	global_store_dwordx4 v[8:9], v[2:5], off
	ds_read2_b32 v[2:3], v14 offset1:1
	ds_read2_b32 v[4:5], v145 offset1:1
	v_lshl_add_u64 v[8:9], v[6:7], 0, v[22:23]
	v_add_u32_e32 v14, 0x1080, v144
	v_add_u32_e32 v145, 0x1088, v144
	s_waitcnt lgkmcnt(0)
	global_store_dwordx4 v[8:9], v[2:5], off
	ds_read2_b32 v[2:3], v14 offset1:1
	ds_read2_b32 v[4:5], v145 offset1:1
	v_lshl_add_u64 v[8:9], v[6:7], 0, v[24:25]
	v_add_u32_e32 v14, 0x14a0, v144
	v_add_u32_e32 v145, 0x14a8, v144
	s_waitcnt lgkmcnt(0)
	global_store_dwordx4 v[8:9], v[2:5], off
	ds_read2_b32 v[2:3], v14 offset1:1
	ds_read2_b32 v[4:5], v145 offset1:1
	v_lshl_add_u64 v[8:9], v[6:7], 0, v[26:27]
	v_add_u32_e32 v14, 0x18c0, v144
	v_add_u32_e32 v145, 0x18c8, v144
	s_waitcnt lgkmcnt(0)
	global_store_dwordx4 v[8:9], v[2:5], off
	ds_read2_b32 v[2:3], v14 offset1:1
	ds_read2_b32 v[4:5], v145 offset1:1
	v_lshl_add_u64 v[8:9], v[6:7], 0, v[28:29]
	v_add_u32_e32 v14, 0x1ce0, v144
	v_add_u32_e32 v144, 0x1ce8, v144
	v_lshl_add_u64 v[6:7], v[6:7], 0, v[30:31]
	s_waitcnt lgkmcnt(0)
	global_store_dwordx4 v[8:9], v[2:5], off
	ds_read2_b32 v[2:3], v14 offset1:1
	ds_read2_b32 v[4:5], v144 offset1:1
	s_waitcnt lgkmcnt(0)
	global_store_dwordx4 v[6:7], v[2:5], off
	s_waitcnt lgkmcnt(0)
; template <int I> DI const float* kin() { return (const float*)karg64<I * 8>(); }
; DI void phase_prologue(const Ctx& c) {
;     ...
;         if (r < I_DN) { conv_matrix_item(kin<23>() + (size_t)l * DFF * DM, DFF, DM, Wl + WL_DOWN, nullptr, r, scr, c.lane); continue; } r -= I_DN;
.LBB0_24:
	s_and_b64 vcc, exec, s[4:5]
	s_cbranch_vccz .LBB0_26
; #define LAS __attribute__((address_space(3)))
; template <int I> DI const float* kin() { return (const float*)karg64<I * 8>(); }
; DI unsigned pk2(float a, float b) { f32x2 v = {a, b}; bf16v2 r = __builtin_convertvector(v, bf16v2); return __builtin_bit_cast(unsigned, r); }
; DI void tr_item(const float* src, size_t sld, bf16_t* dst, size_t dld, const float* ksc, LAS unsigned* scr, int lane) {
;     const int ng = lane & 15, kq = lane >> 4;
; #pragma unroll
;     for (int i = 0; i < 8; ++i) {
;         const int k = 8 * i + 2 * kq;
;         f32x4 a = *(const f32x4*)(src + (size_t)k * sld + 4 * ng);
;         f32x4 b = *(const f32x4*)(src + (size_t)(k + 1) * sld + 4 * ng);
;         if (ksc) { a *= ksc[k]; b *= ksc[k + 1]; }
;         LAS unsigned* d = scr + (4 * ng) * 33 + 4 * i + kq;
;         d[0] = pk2(a[0], b[0]); d[33] = pk2(a[1], b[1]); d[66] = pk2(a[2], b[2]); d[99] = pk2(a[3], b[3]);
;     }
;     asm volatile("s_waitcnt lgkmcnt(0)" ::: "memory");
; #pragma unroll
;     for (int j = 0; j < 8; ++j) {
;         const int n = (lane >> 3) + 8 * j, c = lane & 7;
;         const LAS unsigned* s = scr + n * 33 + 4 * c;
;         u32x4 o; o.x = s[0]; o.y = s[1]; o.z = s[2]; o.w = s[3];
;         *(u32x4*)(dst + (size_t)n * dld + 8 * c) = o;
;     }
;     asm volatile("s_waitcnt lgkmcnt(0)" ::: "memory");
; DI void phase_prologue(const Ctx& c) {
;     ...
;         if (r < I_DN) { conv_matrix_item(kin<23>() + (size_t)l * DFF * DM, DFF, DM, Wl + WL_DOWN, nullptr, r, scr, c.lane); continue; } r -= I_DN;
	s_add_i32 s6, s26, 0xffffcd00
	s_lshl_b64 s[22:23], s[20:21], 26
	s_load_dwordx2 s[4:5], s[0:1], 0xb8
	s_waitcnt lgkmcnt(0)
	s_add_u32 s24, s4, s22
	s_addc_u32 s25, s5, s23
	s_lshr_b32 s4, s6, 5
	s_lshl_b32 s6, s4, 17
	s_and_b32 s5, s56, 31
	s_lshl_b64 s[22:23], s[6:7], 2
	s_add_u32 s6, s24, s22
	s_addc_u32 s23, s25, s23
	s_lshl_b32 s22, s5, 8
	s_add_u32 s22, s6, s22
	s_addc_u32 s23, s23, 0
	v_lshlrev_b32_e32 v14, 2, v12
	v_lshl_add_u64 v[2:3], s[22:23], 0, v[14:15]
	v_lshl_add_u64 v[144:145], v[2:3], 0, v[32:33]
	v_add_co_u32_e32 v6, vcc, s34, v144
	s_lshl_b32 s5, s5, 20
	s_nop 0
	v_addc_co_u32_e32 v7, vcc, 0, v145, vcc
	global_load_dwordx4 v[2:5], v[144:145], off
	s_nop 0
	global_load_dwordx4 v[6:9], v[6:7], off
	v_add_co_u32_e32 v146, vcc, s40, v144
	s_add_u32 s5, s57, s5
	s_nop 0
	v_addc_co_u32_e32 v147, vcc, 0, v145, vcc
	v_add_co_u32_e32 v148, vcc, s41, v144
	s_addc_u32 s6, s58, 0
	s_nop 0
	v_addc_co_u32_e32 v149, vcc, 0, v145, vcc
	s_lshl_b32 s4, s4, 7
	s_add_u32 s4, s5, s4
	v_lshlrev_b32_e32 v14, 1, v142
	s_addc_u32 s5, s6, 0
	s_waitcnt vmcnt(0) lgkmcnt(0)
	v_cvt_pk_bf16_f32 v2, v2, v6
	v_cvt_pk_bf16_f32 v3, v3, v7
	v_cvt_pk_bf16_f32 v4, v4, v8
	v_cvt_pk_bf16_f32 v5, v5, v9
	ds_write_b32 v13, v2
	ds_write_b32 v13, v3 offset:132
	ds_write_b32 v13, v4 offset:264
	ds_write_b32 v13, v5 offset:396
	global_load_dwordx4 v[2:5], v[146:147], off
	global_load_dwordx4 v[6:9], v[148:149], off
	v_add_co_u32_e32 v146, vcc, s42, v144
	s_waitcnt vmcnt(0) lgkmcnt(0)
	v_cvt_pk_bf16_f32 v2, v2, v6
	v_addc_co_u32_e32 v147, vcc, 0, v145, vcc
	v_add_co_u32_e32 v148, vcc, s43, v144
	v_cvt_pk_bf16_f32 v3, v3, v7
	v_cvt_pk_bf16_f32 v4, v4, v8
	v_cvt_pk_bf16_f32 v5, v5, v9
	ds_write_b32 v13, v2 offset:16
	ds_write_b32 v13, v3 offset:148
	ds_write_b32 v13, v4 offset:280
	ds_write_b32 v13, v5 offset:412
	v_addc_co_u32_e32 v149, vcc, 0, v145, vcc
	global_load_dwordx4 v[2:5], v[146:147], off
	global_load_dwordx4 v[6:9], v[148:149], off
	v_add_co_u32_e32 v146, vcc, s29, v144
	s_waitcnt vmcnt(0) lgkmcnt(0)
	v_cvt_pk_bf16_f32 v2, v2, v6
	v_addc_co_u32_e32 v147, vcc, 0, v145, vcc
	v_add_co_u32_e32 v148, vcc, s44, v144
	v_cvt_pk_bf16_f32 v3, v3, v7
	v_cvt_pk_bf16_f32 v4, v4, v8
	v_cvt_pk_bf16_f32 v5, v5, v9
	ds_write_b32 v13, v2 offset:32
	ds_write_b32 v13, v3 offset:164
	ds_write_b32 v13, v4 offset:296
	ds_write_b32 v13, v5 offset:428
	v_addc_co_u32_e32 v149, vcc, 0, v145, vcc
	global_load_dwordx4 v[2:5], v[146:147], off
	global_load_dwordx4 v[6:9], v[148:149], off
	v_add_co_u32_e32 v146, vcc, s45, v144
	s_waitcnt vmcnt(0) lgkmcnt(0)
	v_cvt_pk_bf16_f32 v2, v2, v6
	v_addc_co_u32_e32 v147, vcc, 0, v145, vcc
	v_add_co_u32_e32 v148, vcc, s46, v144
	v_cvt_pk_bf16_f32 v3, v3, v7
	v_cvt_pk_bf16_f32 v4, v4, v8
	v_cvt_pk_bf16_f32 v5, v5, v9
	ds_write_b32 v13, v2 offset:48
	ds_write_b32 v13, v3 offset:180
	ds_write_b32 v13, v4 offset:312
	ds_write_b32 v13, v5 offset:444
	v_addc_co_u32_e32 v149, vcc, 0, v145, vcc
	global_load_dwordx4 v[2:5], v[146:147], off
	global_load_dwordx4 v[6:9], v[148:149], off
	v_add_co_u32_e32 v146, vcc, s47, v144
	s_waitcnt vmcnt(0) lgkmcnt(0)
	v_cvt_pk_bf16_f32 v2, v2, v6
	v_addc_co_u32_e32 v147, vcc, 0, v145, vcc
	v_add_co_u32_e32 v148, vcc, s48, v144
	v_cvt_pk_bf16_f32 v3, v3, v7
	v_cvt_pk_bf16_f32 v4, v4, v8
	v_cvt_pk_bf16_f32 v5, v5, v9
	ds_write_b32 v13, v2 offset:64
	ds_write_b32 v13, v3 offset:196
	ds_write_b32 v13, v4 offset:328
	ds_write_b32 v13, v5 offset:460
	v_addc_co_u32_e32 v149, vcc, 0, v145, vcc
	global_load_dwordx4 v[2:5], v[146:147], off
	global_load_dwordx4 v[6:9], v[148:149], off
	v_add_co_u32_e32 v146, vcc, s49, v144
	s_waitcnt vmcnt(0) lgkmcnt(0)
	v_cvt_pk_bf16_f32 v2, v2, v6
	v_addc_co_u32_e32 v147, vcc, 0, v145, vcc
	v_add_co_u32_e32 v148, vcc, s50, v144
	v_cvt_pk_bf16_f32 v3, v3, v7
	v_cvt_pk_bf16_f32 v4, v4, v8
	v_cvt_pk_bf16_f32 v5, v5, v9
	ds_write_b32 v13, v2 offset:80
	ds_write_b32 v13, v3 offset:212
	ds_write_b32 v13, v4 offset:344
	ds_write_b32 v13, v5 offset:476
	v_addc_co_u32_e32 v149, vcc, 0, v145, vcc
	global_load_dwordx4 v[2:5], v[146:147], off
	global_load_dwordx4 v[6:9], v[148:149], off
	v_add_co_u32_e32 v146, vcc, s51, v144
	s_waitcnt vmcnt(0) lgkmcnt(0)
	v_cvt_pk_bf16_f32 v2, v2, v6
	v_addc_co_u32_e32 v147, vcc, 0, v145, vcc
	v_add_co_u32_e32 v144, vcc, s52, v144
	v_cvt_pk_bf16_f32 v3, v3, v7
	v_cvt_pk_bf16_f32 v4, v4, v8
	v_cvt_pk_bf16_f32 v5, v5, v9
	ds_write_b32 v13, v2 offset:96
	ds_write_b32 v13, v3 offset:228
	ds_write_b32 v13, v4 offset:360
	ds_write_b32 v13, v5 offset:492
	v_addc_co_u32_e32 v145, vcc, 0, v145, vcc
	global_load_dwordx4 v[2:5], v[146:147], off
	global_load_dwordx4 v[6:9], v[144:145], off
	v_add_u32_e32 v144, v143, v51
	v_add_u32_e32 v145, 0x420, v144
	v_add_u32_e32 v146, 0x428, v144
	s_waitcnt vmcnt(0) lgkmcnt(0)
	v_cvt_pk_bf16_f32 v2, v2, v6
	v_cvt_pk_bf16_f32 v3, v3, v7
	v_cvt_pk_bf16_f32 v4, v4, v8
	v_cvt_pk_bf16_f32 v5, v5, v9
	ds_write_b32 v13, v2 offset:112
	ds_write_b32 v13, v3 offset:244
	ds_write_b32 v13, v4 offset:376
	ds_write_b32 v13, v5 offset:508
	s_waitcnt lgkmcnt(0)
	ds_read2_b32 v[2:3], v144 offset1:1
	ds_read2_b32 v[4:5], v144 offset0:2 offset1:3
	v_lshl_add_u64 v[6:7], s[4:5], 0, v[14:15]
	v_lshl_add_u64 v[6:7], v[6:7], 0, s[12:13]
	v_lshl_add_u64 v[8:9], v[6:7], 0, v[34:35]
	v_add_u32_e32 v14, 0x840, v144
	s_waitcnt lgkmcnt(0)
	global_store_dwordx4 v[8:9], v[2:5], off
	ds_read2_b32 v[2:3], v145 offset1:1
	ds_read2_b32 v[4:5], v146 offset1:1
	v_lshl_add_u64 v[8:9], v[6:7], 0, v[36:37]
	v_add_u32_e32 v145, 0x848, v144
	s_waitcnt lgkmcnt(0)
	global_store_dwordx4 v[8:9], v[2:5], off
	ds_read2_b32 v[2:3], v14 offset1:1
	ds_read2_b32 v[4:5], v145 offset1:1
	v_lshl_add_u64 v[8:9], v[6:7], 0, v[38:39]
	v_add_u32_e32 v14, 0xc60, v144
	v_add_u32_e32 v145, 0xc68, v144
	s_waitcnt lgkmcnt(0)
	global_store_dwordx4 v[8:9], v[2:5], off
	ds_read2_b32 v[2:3], v14 offset1:1
	ds_read2_b32 v[4:5], v145 offset1:1
	v_lshl_add_u64 v[8:9], v[6:7], 0, v[40:41]
	v_add_u32_e32 v14, 0x1080, v144
	v_add_u32_e32 v145, 0x1088, v144
	s_waitcnt lgkmcnt(0)
	global_store_dwordx4 v[8:9], v[2:5], off
	ds_read2_b32 v[2:3], v14 offset1:1
	ds_read2_b32 v[4:5], v145 offset1:1
	v_lshl_add_u64 v[8:9], v[6:7], 0, v[42:43]
	v_add_u32_e32 v14, 0x14a0, v144
	v_add_u32_e32 v145, 0x14a8, v144
	s_waitcnt lgkmcnt(0)
	global_store_dwordx4 v[8:9], v[2:5], off
	ds_read2_b32 v[2:3], v14 offset1:1
	ds_read2_b32 v[4:5], v145 offset1:1
	v_lshl_add_u64 v[8:9], v[6:7], 0, v[44:45]
	v_add_u32_e32 v14, 0x18c0, v144
	v_add_u32_e32 v145, 0x18c8, v144
	s_waitcnt lgkmcnt(0)
	global_store_dwordx4 v[8:9], v[2:5], off
	ds_read2_b32 v[2:3], v14 offset1:1
	ds_read2_b32 v[4:5], v145 offset1:1
	v_lshl_add_u64 v[8:9], v[6:7], 0, v[46:47]
	v_add_u32_e32 v14, 0x1ce0, v144
	v_add_u32_e32 v144, 0x1ce8, v144
	v_lshl_add_u64 v[6:7], v[6:7], 0, v[48:49]
	s_waitcnt lgkmcnt(0)
	global_store_dwordx4 v[8:9], v[2:5], off
	ds_read2_b32 v[2:3], v14 offset1:1
	ds_read2_b32 v[4:5], v144 offset1:1
	s_waitcnt lgkmcnt(0)
	global_store_dwordx4 v[6:7], v[2:5], off
	s_waitcnt lgkmcnt(0)

; #define LAS __attribute__((address_space(3)))
; template <int I> DI const float* kin() { return (const float*)karg64<I * 8>(); }
; DI unsigned pk2(float a, float b) { f32x2 v = {a, b}; bf16v2 r = __builtin_convertvector(v, bf16v2); return __builtin_bit_cast(unsigned, r); }
; DI void tr_item(const float* src, size_t sld, bf16_t* dst, size_t dld, const float* ksc, LAS unsigned* scr, int lane) {
;     const int ng = lane & 15, kq = lane >> 4;
; #pragma unroll
;     for (int i = 0; i < 8; ++i) {
;         const int k = 8 * i + 2 * kq;
;         f32x4 a = *(const f32x4*)(src + (size_t)k * sld + 4 * ng);
;         f32x4 b = *(const f32x4*)(src + (size_t)(k + 1) * sld + 4 * ng);
;         if (ksc) { a *= ksc[k]; b *= ksc[k + 1]; }
;         LAS unsigned* d = scr + (4 * ng) * 33 + 4 * i + kq;
;         d[0] = pk2(a[0], b[0]); d[33] = pk2(a[1], b[1]); d[66] = pk2(a[2], b[2]); d[99] = pk2(a[3], b[3]);
;     }
; DI void phase_prologue(const Ctx& c) {
;     ...
;         if (r < I_UP) { conv_matrix_item(kin<22>() + (size_t)l * DM * DFF, DM, DFF, Wl + WL_UP, kin<21>() + l * DM, r, scr, c.lane); continue; } r -= I_UP;
.LBB0_27:
	s_andn2_b64 vcc, exec, s[4:5]
	s_cbranch_vccnz .LBB0_45
	s_add_i32 s6, s26, 0xffffdd00
	s_lshl_b64 s[22:23], s[20:21], 26
	s_load_dwordx2 s[4:5], s[0:1], 0xb0
	s_waitcnt lgkmcnt(0)
	s_add_u32 s59, s4, s22
	s_addc_u32 s60, s5, s23
	s_lshl_b32 s22, s20, 11
	s_ashr_i32 s23, s22, 31
	s_lshl_b64 s[22:23], s[22:23], 2
	s_load_dwordx2 s[4:5], s[0:1], 0xa8
	s_waitcnt lgkmcnt(0)
	s_add_u32 s24, s4, s22
	s_addc_u32 s25, s5, s23
	s_lshr_b32 s61, s6, 7
	s_lshl_b32 s6, s61, 6
	s_lshl_b64 s[22:23], s[6:7], 2
	s_add_u32 s22, s24, s22
	s_addc_u32 s23, s25, s23
	s_lshl_b32 s24, s61, 19
	s_mov_b32 s25, s7
	s_and_b32 s27, s26, 0x7f
	s_lshl_b64 s[24:25], s[24:25], 2
	s_add_u32 s24, s59, s24
	s_addc_u32 s25, s60, s25
	s_lshl_b32 s59, s27, 8
	s_add_u32 s24, s24, s59
	s_addc_u32 s25, s25, 0
	v_lshlrev_b32_e32 v14, 2, v12
	v_lshl_add_u64 v[144:145], s[24:25], 0, v[14:15]
	v_lshl_add_u64 v[2:3], v[144:145], 0, v[52:53]
	v_lshl_add_u64 v[6:7], v[144:145], 0, v[54:55]
	global_load_dwordx4 v[2:5], v[2:3], off
	s_nop 0
	global_load_dwordx4 v[6:9], v[6:7], off
	s_cmp_lg_u64 s[4:5], 0
	s_cselect_b64 s[24:25], -1, 0
	s_cmp_eq_u64 s[4:5], 0
	s_cbranch_scc1 .LBB0_30
	v_lshlrev_b32_e32 v14, 2, v50
	v_lshl_add_u64 v[146:147], s[22:23], 0, v[14:15]
	global_load_dwordx2 v[146:147], v[146:147], off
	s_waitcnt vmcnt(0) lgkmcnt(0)
	v_pk_mul_f32 v[4:5], v[4:5], v[146:147] op_sel_hi:[1,0]
	v_pk_mul_f32 v[2:3], v[2:3], v[146:147] op_sel_hi:[1,0]
	v_pk_mul_f32 v[8:9], v[8:9], v[146:147] op_sel:[0,1]
	v_pk_mul_f32 v[6:7], v[6:7], v[146:147] op_sel:[0,1]
.LBB0_30:
	s_waitcnt vmcnt(0) lgkmcnt(0)
	v_cvt_pk_bf16_f32 v2, v2, v6
	v_cvt_pk_bf16_f32 v3, v3, v7
	ds_write2_b32 v13, v2, v3 offset1:33
	v_cvt_pk_bf16_f32 v2, v4, v8
	v_cvt_pk_bf16_f32 v3, v5, v9
	ds_write2_b32 v13, v2, v3 offset0:66 offset1:99
	v_lshl_add_u64 v[2:3], v[144:145], 0, v[60:61]
	v_lshl_add_u64 v[6:7], v[144:145], 0, v[64:65]
	global_load_dwordx4 v[2:5], v[2:3], off
	s_nop 0
	global_load_dwordx4 v[6:9], v[6:7], off
	v_cndmask_b32_e64 v14, 0, 1, s[24:25]
	v_cmp_ne_u32_e64 s[4:5], 1, v14
	s_andn2_b64 vcc, exec, s[24:25]
	s_cbranch_vccnz .LBB0_32
	v_lshlrev_b32_e32 v14, 2, v50
	v_lshl_add_u64 v[146:147], s[22:23], 0, v[14:15]
	global_load_dwordx2 v[146:147], v[146:147], off offset:32
	s_waitcnt vmcnt(0) lgkmcnt(0)
	v_pk_mul_f32 v[4:5], v[4:5], v[146:147] op_sel_hi:[1,0]
	v_pk_mul_f32 v[2:3], v[2:3], v[146:147] op_sel_hi:[1,0]
	v_pk_mul_f32 v[8:9], v[8:9], v[146:147] op_sel:[0,1]
	v_pk_mul_f32 v[6:7], v[6:7], v[146:147] op_sel:[0,1]
.LBB0_32:
	s_waitcnt vmcnt(0) lgkmcnt(0)
	v_cvt_pk_bf16_f32 v2, v2, v6
	v_cvt_pk_bf16_f32 v3, v3, v7
	ds_write2_b32 v13, v2, v3 offset0:4 offset1:37
	v_cvt_pk_bf16_f32 v2, v4, v8
	v_cvt_pk_bf16_f32 v3, v5, v9
	ds_write2_b32 v13, v2, v3 offset0:70 offset1:103
	v_lshl_add_u64 v[2:3], v[144:145], 0, v[68:69]
	v_lshl_add_u64 v[6:7], v[144:145], 0, v[72:73]
	global_load_dwordx4 v[2:5], v[2:3], off
	s_nop 0
	global_load_dwordx4 v[6:9], v[6:7], off
	s_and_b64 vcc, exec, s[4:5]
	s_cbranch_vccnz .LBB0_34
	v_lshlrev_b32_e32 v14, 2, v50
	v_lshl_add_u64 v[146:147], s[22:23], 0, v[14:15]
	global_load_dwordx2 v[146:147], v[146:147], off offset:64
	s_waitcnt vmcnt(0) lgkmcnt(0)
	v_pk_mul_f32 v[4:5], v[4:5], v[146:147] op_sel_hi:[1,0]
	v_pk_mul_f32 v[2:3], v[2:3], v[146:147] op_sel_hi:[1,0]
	v_pk_mul_f32 v[8:9], v[8:9], v[146:147] op_sel:[0,1]
	v_pk_mul_f32 v[6:7], v[6:7], v[146:147] op_sel:[0,1]
.LBB0_34:
	s_waitcnt vmcnt(0) lgkmcnt(0)
	v_cvt_pk_bf16_f32 v2, v2, v6
	v_cvt_pk_bf16_f32 v3, v3, v7
	ds_write2_b32 v13, v2, v3 offset0:8 offset1:41
	v_cvt_pk_bf16_f32 v2, v4, v8
	v_cvt_pk_bf16_f32 v3, v5, v9
	ds_write2_b32 v13, v2, v3 offset0:74 offset1:107
	v_lshl_add_u64 v[2:3], v[144:145], 0, v[76:77]
	v_lshl_add_u64 v[6:7], v[144:145], 0, v[80:81]
	global_load_dwordx4 v[2:5], v[2:3], off
	s_nop 0
	global_load_dwordx4 v[6:9], v[6:7], off
	s_and_b64 vcc, exec, s[4:5]
	s_cbranch_vccnz .LBB0_36
	v_lshlrev_b32_e32 v14, 2, v50
	v_lshl_add_u64 v[146:147], s[22:23], 0, v[14:15]
	global_load_dwordx2 v[146:147], v[146:147], off offset:96
	s_waitcnt vmcnt(0) lgkmcnt(0)
	v_pk_mul_f32 v[4:5], v[4:5], v[146:147] op_sel_hi:[1,0]
	v_pk_mul_f32 v[2:3], v[2:3], v[146:147] op_sel_hi:[1,0]
	v_pk_mul_f32 v[8:9], v[8:9], v[146:147] op_sel:[0,1]
	v_pk_mul_f32 v[6:7], v[6:7], v[146:147] op_sel:[0,1]
.LBB0_36:
	s_waitcnt vmcnt(0) lgkmcnt(0)
	v_cvt_pk_bf16_f32 v2, v2, v6
	v_cvt_pk_bf16_f32 v3, v3, v7
	ds_write2_b32 v13, v2, v3 offset0:12 offset1:45
	v_cvt_pk_bf16_f32 v2, v4, v8
	v_cvt_pk_bf16_f32 v3, v5, v9
	ds_write2_b32 v13, v2, v3 offset0:78 offset1:111
	v_lshl_add_u64 v[2:3], v[144:145], 0, v[84:85]
	v_lshl_add_u64 v[6:7], v[144:145], 0, v[88:89]
	global_load_dwordx4 v[2:5], v[2:3], off
	s_nop 0
	global_load_dwordx4 v[6:9], v[6:7], off
	s_and_b64 vcc, exec, s[4:5]
	s_cbranch_vccnz .LBB0_38
	v_lshlrev_b32_e32 v14, 2, v50
	v_lshl_add_u64 v[146:147], s[22:23], 0, v[14:15]
	global_load_dwordx2 v[146:147], v[146:147], off offset:128
	s_waitcnt vmcnt(0) lgkmcnt(0)
	v_pk_mul_f32 v[4:5], v[4:5], v[146:147] op_sel_hi:[1,0]
	v_pk_mul_f32 v[2:3], v[2:3], v[146:147] op_sel_hi:[1,0]
	v_pk_mul_f32 v[8:9], v[8:9], v[146:147] op_sel:[0,1]
	v_pk_mul_f32 v[6:7], v[6:7], v[146:147] op_sel:[0,1]
; #define LAS __attribute__((address_space(3)))
; template <int I> DI const float* kin() { return (const float*)karg64<I * 8>(); }
; DI unsigned pk2(float a, float b) { f32x2 v = {a, b}; bf16v2 r = __builtin_convertvector(v, bf16v2); return __builtin_bit_cast(unsigned, r); }
; DI void tr_item(const float* src, size_t sld, bf16_t* dst, size_t dld, const float* ksc, LAS unsigned* scr, int lane) {
;     ...
;     for (int i = 0; i < 8; ++i) {
;         const int k = 8 * i + 2 * kq;
;         f32x4 a = *(const f32x4*)(src + (size_t)k * sld + 4 * ng);
;         f32x4 b = *(const f32x4*)(src + (size_t)(k + 1) * sld + 4 * ng);
;         if (ksc) { a *= ksc[k]; b *= ksc[k + 1]; }
;         LAS unsigned* d = scr + (4 * ng) * 33 + 4 * i + kq;
;         d[0] = pk2(a[0], b[0]); d[33] = pk2(a[1], b[1]); d[66] = pk2(a[2], b[2]); d[99] = pk2(a[3], b[3]);
;     }
;     asm volatile("s_waitcnt lgkmcnt(0)" ::: "memory");
; #pragma unroll
;     for (int j = 0; j < 8; ++j) {
;         const int n = (lane >> 3) + 8 * j, c = lane & 7;
;         const LAS unsigned* s = scr + n * 33 + 4 * c;
;         u32x4 o; o.x = s[0]; o.y = s[1]; o.z = s[2]; o.w = s[3];
;         *(u32x4*)(dst + (size_t)n * dld + 8 * c) = o;
;     }
;     asm volatile("s_waitcnt lgkmcnt(0)" ::: "memory");
; DI void phase_prologue(const Ctx& c) {
;     ...
;         if (r < I_UP) { conv_matrix_item(kin<22>() + (size_t)l * DM * DFF, DM, DFF, Wl + WL_UP, kin<21>() + l * DM, r, scr, c.lane); continue; } r -= I_UP;
.LBB0_38:
	s_waitcnt vmcnt(0) lgkmcnt(0)
	v_cvt_pk_bf16_f32 v2, v2, v6
	v_cvt_pk_bf16_f32 v3, v3, v7
	ds_write2_b32 v13, v2, v3 offset0:16 offset1:49
	v_cvt_pk_bf16_f32 v2, v4, v8
	v_cvt_pk_bf16_f32 v3, v5, v9
	ds_write2_b32 v13, v2, v3 offset0:82 offset1:115
	v_lshl_add_u64 v[2:3], v[144:145], 0, v[92:93]
	v_lshl_add_u64 v[6:7], v[144:145], 0, v[96:97]
	global_load_dwordx4 v[2:5], v[2:3], off
	s_nop 0
	global_load_dwordx4 v[6:9], v[6:7], off
	s_and_b64 vcc, exec, s[4:5]
	s_cbranch_vccnz .LBB0_40
	v_lshlrev_b32_e32 v14, 2, v50
	v_lshl_add_u64 v[146:147], s[22:23], 0, v[14:15]
	global_load_dwordx2 v[146:147], v[146:147], off offset:160
	s_waitcnt vmcnt(0) lgkmcnt(0)
	v_pk_mul_f32 v[4:5], v[4:5], v[146:147] op_sel_hi:[1,0]
	v_pk_mul_f32 v[2:3], v[2:3], v[146:147] op_sel_hi:[1,0]
	v_pk_mul_f32 v[8:9], v[8:9], v[146:147] op_sel:[0,1]
	v_pk_mul_f32 v[6:7], v[6:7], v[146:147] op_sel:[0,1]
.LBB0_40:
	s_waitcnt vmcnt(0) lgkmcnt(0)
	v_cvt_pk_bf16_f32 v2, v2, v6
	v_cvt_pk_bf16_f32 v3, v3, v7
	ds_write2_b32 v13, v2, v3 offset0:20 offset1:53
	v_cvt_pk_bf16_f32 v2, v4, v8
	v_cvt_pk_bf16_f32 v3, v5, v9
	ds_write2_b32 v13, v2, v3 offset0:86 offset1:119
	v_lshl_add_u64 v[2:3], v[144:145], 0, v[100:101]
	v_lshl_add_u64 v[6:7], v[144:145], 0, v[104:105]
	global_load_dwordx4 v[2:5], v[2:3], off
	s_nop 0
	global_load_dwordx4 v[6:9], v[6:7], off
	s_and_b64 vcc, exec, s[4:5]
	s_cbranch_vccnz .LBB0_42
	v_lshlrev_b32_e32 v14, 2, v50
	v_lshl_add_u64 v[146:147], s[22:23], 0, v[14:15]
	global_load_dwordx2 v[146:147], v[146:147], off offset:192
	s_waitcnt vmcnt(0) lgkmcnt(0)
	v_pk_mul_f32 v[4:5], v[4:5], v[146:147] op_sel_hi:[1,0]
	v_pk_mul_f32 v[2:3], v[2:3], v[146:147] op_sel_hi:[1,0]
	v_pk_mul_f32 v[8:9], v[8:9], v[146:147] op_sel:[0,1]
	v_pk_mul_f32 v[6:7], v[6:7], v[146:147] op_sel:[0,1]
.LBB0_42:
	s_waitcnt vmcnt(0) lgkmcnt(0)
	v_cvt_pk_bf16_f32 v2, v2, v6
	v_cvt_pk_bf16_f32 v3, v3, v7
	ds_write2_b32 v13, v2, v3 offset0:24 offset1:57
	v_cvt_pk_bf16_f32 v2, v4, v8
	v_cvt_pk_bf16_f32 v3, v5, v9
	ds_write2_b32 v13, v2, v3 offset0:90 offset1:123
	v_lshl_add_u64 v[2:3], v[144:145], 0, v[108:109]
	v_lshl_add_u64 v[6:7], v[144:145], 0, v[112:113]
	global_load_dwordx4 v[2:5], v[2:3], off
	s_nop 0
	global_load_dwordx4 v[6:9], v[6:7], off
	s_and_b64 vcc, exec, s[4:5]
	s_cbranch_vccnz .LBB0_44
	v_lshlrev_b32_e32 v14, 2, v50
	v_lshl_add_u64 v[144:145], s[22:23], 0, v[14:15]
	global_load_dwordx2 v[144:145], v[144:145], off offset:224
	s_waitcnt vmcnt(0) lgkmcnt(0)
	v_pk_mul_f32 v[4:5], v[4:5], v[144:145] op_sel_hi:[1,0]
	v_pk_mul_f32 v[2:3], v[2:3], v[144:145] op_sel_hi:[1,0]
	v_pk_mul_f32 v[8:9], v[8:9], v[144:145] op_sel:[0,1]
	v_pk_mul_f32 v[6:7], v[6:7], v[144:145] op_sel:[0,1]
.LBB0_44:
	s_waitcnt vmcnt(0) lgkmcnt(0)
	v_cvt_pk_bf16_f32 v2, v2, v6
	v_cvt_pk_bf16_f32 v3, v3, v7
	s_lshl_b32 s4, s27, 18
	ds_write2_b32 v13, v2, v3 offset0:28 offset1:61
	v_cvt_pk_bf16_f32 v2, v4, v8
	v_cvt_pk_bf16_f32 v3, v5, v9
	s_add_u32 s4, s57, s4
	ds_write2_b32 v13, v2, v3 offset0:94 offset1:127
	s_addc_u32 s5, s58, 0
	s_lshl_b32 s6, s6, 1
	s_waitcnt lgkmcnt(0)
	v_add_u32_e32 v144, v143, v51
	s_add_u32 s4, s4, s6
	ds_read2_b32 v[2:3], v144 offset1:1
	ds_read2_b32 v[4:5], v144 offset0:2 offset1:3
	s_addc_u32 s5, s5, 0
	v_lshlrev_b32_e32 v14, 1, v142
	v_lshl_add_u64 v[6:7], s[4:5], 0, v[14:15]
	v_lshl_add_u64 v[6:7], v[6:7], 0, s[14:15]
	v_lshl_add_u64 v[8:9], v[6:7], 0, v[114:115]
	s_waitcnt lgkmcnt(0)
	global_store_dwordx4 v[8:9], v[2:5], off
	v_lshl_add_u64 v[8:9], v[6:7], 0, v[116:117]
	s_nop 0
	v_add_u32_e32 v2, 0x420, v144
	v_add_u32_e32 v4, 0x428, v144
	ds_read2_b32 v[2:3], v2 offset1:1
	ds_read2_b32 v[4:5], v4 offset1:1
	s_waitcnt lgkmcnt(0)
	global_store_dwordx4 v[8:9], v[2:5], off
	s_nop 1
	v_add_u32_e32 v2, 0x840, v144
	v_add_u32_e32 v4, 0x848, v144
	ds_read2_b32 v[2:3], v2 offset1:1
	ds_read2_b32 v[4:5], v4 offset1:1
	v_lshl_add_u64 v[8:9], v[6:7], 0, v[118:119]
	s_waitcnt lgkmcnt(0)
	global_store_dwordx4 v[8:9], v[2:5], off
	s_nop 1
	v_add_u32_e32 v2, 0xc60, v144
	v_add_u32_e32 v4, 0xc68, v144
	ds_read2_b32 v[2:3], v2 offset1:1
	ds_read2_b32 v[4:5], v4 offset1:1
	v_lshl_add_u64 v[8:9], v[6:7], 0, v[120:121]
	s_waitcnt lgkmcnt(0)
	global_store_dwordx4 v[8:9], v[2:5], off
	s_nop 1
	v_add_u32_e32 v2, 0x1080, v144
	v_add_u32_e32 v4, 0x1088, v144
	ds_read2_b32 v[2:3], v2 offset1:1
	ds_read2_b32 v[4:5], v4 offset1:1
	v_lshl_add_u64 v[8:9], v[6:7], 0, v[122:123]
	s_waitcnt lgkmcnt(0)
	global_store_dwordx4 v[8:9], v[2:5], off
	s_nop 1
	v_add_u32_e32 v2, 0x14a0, v144
	v_add_u32_e32 v4, 0x14a8, v144
	ds_read2_b32 v[2:3], v2 offset1:1
	ds_read2_b32 v[4:5], v4 offset1:1
	v_lshl_add_u64 v[8:9], v[6:7], 0, v[124:125]
	s_waitcnt lgkmcnt(0)
	global_store_dwordx4 v[8:9], v[2:5], off
	s_nop 1
	v_add_u32_e32 v2, 0x18c0, v144
	v_add_u32_e32 v4, 0x18c8, v144
	ds_read2_b32 v[2:3], v2 offset1:1
	ds_read2_b32 v[4:5], v4 offset1:1
	v_lshl_add_u64 v[8:9], v[6:7], 0, v[126:127]
	v_lshl_add_u64 v[6:7], v[6:7], 0, v[128:129]
	s_waitcnt lgkmcnt(0)
	global_store_dwordx4 v[8:9], v[2:5], off
	s_nop 1
	v_add_u32_e32 v2, 0x1ce0, v144
	v_add_u32_e32 v4, 0x1ce8, v144
	ds_read2_b32 v[2:3], v2 offset1:1
	ds_read2_b32 v[4:5], v4 offset1:1
	s_waitcnt lgkmcnt(0)
	global_store_dwordx4 v[6:7], v[2:5], off
	s_waitcnt lgkmcnt(0)

; template <int I> DI const float* kin() { return (const float*)karg64<I * 8>(); }
; DI void phase_prologue(const Ctx& c) {
;     ...
;         if (r < I_OUT) { conv_matrix_item(kin<20>() + (size_t)l * DM * DM, DM, DM, Wl + WL_OUT, nullptr, r, scr, c.lane); continue; } r -= I_OUT;
.LBB0_46:
	s_andn2_b64 vcc, exec, s[4:5]
	s_cbranch_vccnz .LBB0_48
; #define LAS __attribute__((address_space(3)))
; template <int I> DI const float* kin() { return (const float*)karg64<I * 8>(); }
; DI unsigned pk2(float a, float b) { f32x2 v = {a, b}; bf16v2 r = __builtin_convertvector(v, bf16v2); return __builtin_bit_cast(unsigned, r); }
; DI void tr_item(const float* src, size_t sld, bf16_t* dst, size_t dld, const float* ksc, LAS unsigned* scr, int lane) {
;     const int ng = lane & 15, kq = lane >> 4;
; #pragma unroll
;     for (int i = 0; i < 8; ++i) {
;         const int k = 8 * i + 2 * kq;
;         f32x4 a = *(const f32x4*)(src + (size_t)k * sld + 4 * ng);
;         f32x4 b = *(const f32x4*)(src + (size_t)(k + 1) * sld + 4 * ng);
;         if (ksc) { a *= ksc[k]; b *= ksc[k + 1]; }
;         LAS unsigned* d = scr + (4 * ng) * 33 + 4 * i + kq;
;         d[0] = pk2(a[0], b[0]); d[33] = pk2(a[1], b[1]); d[66] = pk2(a[2], b[2]); d[99] = pk2(a[3], b[3]);
;     }
;     asm volatile("s_waitcnt lgkmcnt(0)" ::: "memory");
; #pragma unroll
;     for (int j = 0; j < 8; ++j) {
;         const int n = (lane >> 3) + 8 * j, c = lane & 7;
;         const LAS unsigned* s = scr + n * 33 + 4 * c;
;         u32x4 o; o.x = s[0]; o.y = s[1]; o.z = s[2]; o.w = s[3];
;         *(u32x4*)(dst + (size_t)n * dld + 8 * c) = o;
;     }
;     asm volatile("s_waitcnt lgkmcnt(0)" ::: "memory");
; DI void phase_prologue(const Ctx& c) {
;     ...
;         if (r < I_OUT) { conv_matrix_item(kin<20>() + (size_t)l * DM * DM, DM, DM, Wl + WL_OUT, nullptr, r, scr, c.lane); continue; } r -= I_OUT;
	s_add_i32 s6, s26, 0xffffe100
	s_lshl_b64 s[22:23], s[20:21], 24
	s_load_dwordx2 s[4:5], s[0:1], 0xa0
	s_waitcnt lgkmcnt(0)
	s_add_u32 s21, s4, s22
	s_addc_u32 s24, s5, s23
	s_lshr_b32 s4, s6, 5
	s_lshl_b32 s6, s4, 17
	s_and_b32 s5, s56, 31
	s_lshl_b64 s[22:23], s[6:7], 2
	s_add_u32 s6, s21, s22
	s_addc_u32 s21, s24, s23
	s_lshl_b32 s22, s5, 8
	s_add_u32 s22, s6, s22
	s_addc_u32 s23, s21, 0
	v_lshlrev_b32_e32 v14, 2, v12
	v_lshl_add_u64 v[2:3], s[22:23], 0, v[14:15]
	v_lshl_add_u64 v[144:145], v[2:3], 0, v[32:33]
	v_add_co_u32_e32 v6, vcc, s34, v144
	s_lshl_b32 s5, s5, 18
	s_nop 0
	v_addc_co_u32_e32 v7, vcc, 0, v145, vcc
	global_load_dwordx4 v[2:5], v[144:145], off
	s_nop 0
	global_load_dwordx4 v[6:9], v[6:7], off
	v_add_co_u32_e32 v146, vcc, s40, v144
	s_add_u32 s5, s57, s5
	s_nop 0
	v_addc_co_u32_e32 v147, vcc, 0, v145, vcc
	v_add_co_u32_e32 v148, vcc, s41, v144
	s_addc_u32 s6, s58, 0
	s_nop 0
	v_addc_co_u32_e32 v149, vcc, 0, v145, vcc
	s_lshl_b32 s4, s4, 7
	s_add_u32 s4, s5, s4
	v_lshlrev_b32_e32 v14, 1, v142
	s_addc_u32 s5, s6, 0
	s_waitcnt vmcnt(0) lgkmcnt(0)
	v_cvt_pk_bf16_f32 v2, v2, v6
	v_cvt_pk_bf16_f32 v3, v3, v7
	v_cvt_pk_bf16_f32 v4, v4, v8
	v_cvt_pk_bf16_f32 v5, v5, v9
	ds_write_b32 v13, v2
	ds_write_b32 v13, v3 offset:132
	ds_write_b32 v13, v4 offset:264
	ds_write_b32 v13, v5 offset:396
	global_load_dwordx4 v[2:5], v[146:147], off
	global_load_dwordx4 v[6:9], v[148:149], off
	v_add_co_u32_e32 v146, vcc, s42, v144
	s_waitcnt vmcnt(0) lgkmcnt(0)
	v_cvt_pk_bf16_f32 v2, v2, v6
	v_addc_co_u32_e32 v147, vcc, 0, v145, vcc
	v_add_co_u32_e32 v148, vcc, s43, v144
	v_cvt_pk_bf16_f32 v3, v3, v7
	v_cvt_pk_bf16_f32 v4, v4, v8
	v_cvt_pk_bf16_f32 v5, v5, v9
	ds_write_b32 v13, v2 offset:16
	ds_write_b32 v13, v3 offset:148
	ds_write_b32 v13, v4 offset:280
	ds_write_b32 v13, v5 offset:412
	v_addc_co_u32_e32 v149, vcc, 0, v145, vcc
	global_load_dwordx4 v[2:5], v[146:147], off
	global_load_dwordx4 v[6:9], v[148:149], off
	v_add_co_u32_e32 v146, vcc, s29, v144
	s_waitcnt vmcnt(0) lgkmcnt(0)
	v_cvt_pk_bf16_f32 v2, v2, v6
	v_addc_co_u32_e32 v147, vcc, 0, v145, vcc
	v_add_co_u32_e32 v148, vcc, s44, v144
	v_cvt_pk_bf16_f32 v3, v3, v7
	v_cvt_pk_bf16_f32 v4, v4, v8
	v_cvt_pk_bf16_f32 v5, v5, v9
	ds_write_b32 v13, v2 offset:32
	ds_write_b32 v13, v3 offset:164
	ds_write_b32 v13, v4 offset:296
	ds_write_b32 v13, v5 offset:428
	v_addc_co_u32_e32 v149, vcc, 0, v145, vcc
	global_load_dwordx4 v[2:5], v[146:147], off
	global_load_dwordx4 v[6:9], v[148:149], off
	v_add_co_u32_e32 v146, vcc, s45, v144
	s_waitcnt vmcnt(0) lgkmcnt(0)
	v_cvt_pk_bf16_f32 v2, v2, v6
	v_addc_co_u32_e32 v147, vcc, 0, v145, vcc
	v_add_co_u32_e32 v148, vcc, s46, v144
	v_cvt_pk_bf16_f32 v3, v3, v7
	v_cvt_pk_bf16_f32 v4, v4, v8
	v_cvt_pk_bf16_f32 v5, v5, v9
	ds_write_b32 v13, v2 offset:48
	ds_write_b32 v13, v3 offset:180
	ds_write_b32 v13, v4 offset:312
	ds_write_b32 v13, v5 offset:444
	v_addc_co_u32_e32 v149, vcc, 0, v145, vcc
	global_load_dwordx4 v[2:5], v[146:147], off
	global_load_dwordx4 v[6:9], v[148:149], off
	v_add_co_u32_e32 v146, vcc, s47, v144
	s_waitcnt vmcnt(0) lgkmcnt(0)
	v_cvt_pk_bf16_f32 v2, v2, v6
	v_addc_co_u32_e32 v147, vcc, 0, v145, vcc
	v_add_co_u32_e32 v148, vcc, s48, v144
	v_cvt_pk_bf16_f32 v3, v3, v7
	v_cvt_pk_bf16_f32 v4, v4, v8
	v_cvt_pk_bf16_f32 v5, v5, v9
	ds_write_b32 v13, v2 offset:64
	ds_write_b32 v13, v3 offset:196
	ds_write_b32 v13, v4 offset:328
	ds_write_b32 v13, v5 offset:460
	v_addc_co_u32_e32 v149, vcc, 0, v145, vcc
	global_load_dwordx4 v[2:5], v[146:147], off
	global_load_dwordx4 v[6:9], v[148:149], off
	v_add_co_u32_e32 v146, vcc, s49, v144
	s_waitcnt vmcnt(0) lgkmcnt(0)
	v_cvt_pk_bf16_f32 v2, v2, v6
	v_addc_co_u32_e32 v147, vcc, 0, v145, vcc
	v_add_co_u32_e32 v148, vcc, s50, v144
	v_cvt_pk_bf16_f32 v3, v3, v7
	v_cvt_pk_bf16_f32 v4, v4, v8
	v_cvt_pk_bf16_f32 v5, v5, v9
	ds_write_b32 v13, v2 offset:80
	ds_write_b32 v13, v3 offset:212
	ds_write_b32 v13, v4 offset:344
	ds_write_b32 v13, v5 offset:476
	v_addc_co_u32_e32 v149, vcc, 0, v145, vcc
	global_load_dwordx4 v[2:5], v[146:147], off
	global_load_dwordx4 v[6:9], v[148:149], off
	v_add_co_u32_e32 v146, vcc, s51, v144
	s_waitcnt vmcnt(0) lgkmcnt(0)
	v_cvt_pk_bf16_f32 v2, v2, v6
	v_addc_co_u32_e32 v147, vcc, 0, v145, vcc
	v_add_co_u32_e32 v144, vcc, s52, v144
	v_cvt_pk_bf16_f32 v3, v3, v7
	v_cvt_pk_bf16_f32 v4, v4, v8
	v_cvt_pk_bf16_f32 v5, v5, v9
	ds_write_b32 v13, v2 offset:96
	ds_write_b32 v13, v3 offset:228
	ds_write_b32 v13, v4 offset:360
	ds_write_b32 v13, v5 offset:492
	v_addc_co_u32_e32 v145, vcc, 0, v145, vcc
	global_load_dwordx4 v[2:5], v[146:147], off
	global_load_dwordx4 v[6:9], v[144:145], off
	v_add_u32_e32 v144, v143, v51
	v_add_u32_e32 v145, 0x420, v144
	v_add_u32_e32 v146, 0x428, v144
	s_waitcnt vmcnt(0) lgkmcnt(0)
	v_cvt_pk_bf16_f32 v2, v2, v6
	v_cvt_pk_bf16_f32 v3, v3, v7
	v_cvt_pk_bf16_f32 v4, v4, v8
	v_cvt_pk_bf16_f32 v5, v5, v9
	ds_write_b32 v13, v2 offset:112
	ds_write_b32 v13, v3 offset:244
	ds_write_b32 v13, v4 offset:376
	ds_write_b32 v13, v5 offset:508
	s_waitcnt lgkmcnt(0)
	ds_read2_b32 v[2:3], v144 offset1:1
	ds_read2_b32 v[4:5], v144 offset0:2 offset1:3
	v_lshl_add_u64 v[6:7], s[4:5], 0, v[14:15]
	v_lshl_add_u64 v[6:7], v[6:7], 0, s[16:17]
	v_lshl_add_u64 v[8:9], v[6:7], 0, v[114:115]
	v_add_u32_e32 v14, 0x840, v144
	s_waitcnt lgkmcnt(0)
	global_store_dwordx4 v[8:9], v[2:5], off
	ds_read2_b32 v[2:3], v145 offset1:1
	ds_read2_b32 v[4:5], v146 offset1:1
	v_lshl_add_u64 v[8:9], v[6:7], 0, v[116:117]
	v_add_u32_e32 v145, 0x848, v144
	s_waitcnt lgkmcnt(0)
	global_store_dwordx4 v[8:9], v[2:5], off
	ds_read2_b32 v[2:3], v14 offset1:1
	ds_read2_b32 v[4:5], v145 offset1:1
	v_lshl_add_u64 v[8:9], v[6:7], 0, v[118:119]
	v_add_u32_e32 v14, 0xc60, v144
	v_add_u32_e32 v145, 0xc68, v144
	s_waitcnt lgkmcnt(0)
	global_store_dwordx4 v[8:9], v[2:5], off
	ds_read2_b32 v[2:3], v14 offset1:1
	ds_read2_b32 v[4:5], v145 offset1:1
	v_lshl_add_u64 v[8:9], v[6:7], 0, v[120:121]
	v_add_u32_e32 v14, 0x1080, v144
	v_add_u32_e32 v145, 0x1088, v144
	s_waitcnt lgkmcnt(0)
	global_store_dwordx4 v[8:9], v[2:5], off
	ds_read2_b32 v[2:3], v14 offset1:1
	ds_read2_b32 v[4:5], v145 offset1:1
	v_lshl_add_u64 v[8:9], v[6:7], 0, v[122:123]
	v_add_u32_e32 v14, 0x14a0, v144
	v_add_u32_e32 v145, 0x14a8, v144
	s_waitcnt lgkmcnt(0)
	global_store_dwordx4 v[8:9], v[2:5], off
	ds_read2_b32 v[2:3], v14 offset1:1
	ds_read2_b32 v[4:5], v145 offset1:1
	v_lshl_add_u64 v[8:9], v[6:7], 0, v[124:125]
	v_add_u32_e32 v14, 0x18c0, v144
	v_add_u32_e32 v145, 0x18c8, v144
	s_waitcnt lgkmcnt(0)
	global_store_dwordx4 v[8:9], v[2:5], off
	ds_read2_b32 v[2:3], v14 offset1:1
	ds_read2_b32 v[4:5], v145 offset1:1
	v_lshl_add_u64 v[8:9], v[6:7], 0, v[126:127]
	v_add_u32_e32 v14, 0x1ce0, v144
	v_add_u32_e32 v144, 0x1ce8, v144
	v_lshl_add_u64 v[6:7], v[6:7], 0, v[128:129]
	s_waitcnt lgkmcnt(0)
	global_store_dwordx4 v[8:9], v[2:5], off
	ds_read2_b32 v[2:3], v14 offset1:1
	ds_read2_b32 v[4:5], v144 offset1:1
	s_waitcnt lgkmcnt(0)
	global_store_dwordx4 v[6:7], v[2:5], off
	s_waitcnt lgkmcnt(0)

; #define LAS __attribute__((address_space(3)))
; template <int I> DI const float* kin() { return (const float*)karg64<I * 8>(); }
; DI unsigned pk2(float a, float b) { f32x2 v = {a, b}; bf16v2 r = __builtin_convertvector(v, bf16v2); return __builtin_bit_cast(unsigned, r); }
; DI void tr_item(const float* src, size_t sld, bf16_t* dst, size_t dld, const float* ksc, LAS unsigned* scr, int lane) {
;     const int ng = lane & 15, kq = lane >> 4;
; #pragma unroll
;     for (int i = 0; i < 8; ++i) {
;         const int k = 8 * i + 2 * kq;
;         f32x4 a = *(const f32x4*)(src + (size_t)k * sld + 4 * ng);
;         f32x4 b = *(const f32x4*)(src + (size_t)(k + 1) * sld + 4 * ng);
;         if (ksc) { a *= ksc[k]; b *= ksc[k + 1]; }
;         LAS unsigned* d = scr + (4 * ng) * 33 + 4 * i + kq;
;         d[0] = pk2(a[0], b[0]); d[33] = pk2(a[1], b[1]); d[66] = pk2(a[2], b[2]); d[99] = pk2(a[3], b[3]);
;     }
; DI void phase_prologue(const Ctx& c) {
;     ...
;         if (r < 3 * I_BR) { const int b = r / I_BR, it2 = r - b * I_BR, kb = it2 / (DM / 64), nn = it2 - kb * (DM / 64);
;             tr_item(kin<19>() + ((size_t)l * 3 + b) * BW * DM + (size_t)kb * 64 * DM + nn * 64, (size_t)DM, Wl + WL_BR + (size_t)nn * 64 * (3 * BW) + b * BW + kb * 64, (size_t)(3 * BW), nullptr, scr, c.lane); continue; } r -= 3 * I_BR;
.LBB0_49:
	s_andn2_b64 vcc, exec, s[4:5]
	s_cbranch_vccnz .LBB0_51
	s_add_i32 s4, s26, 0xffffe700
	s_lshr_b32 s5, s4, 9
	s_bfe_u32 s4, s4, 0x40005
	s_and_b32 s6, s56, 31
	s_mul_i32 s24, s20, 3
	s_mul_hi_i32 s21, s20, 3
	s_add_u32 s24, s24, s5
	s_addc_u32 s25, s21, 0
	s_lshl_b64 s[24:25], s[24:25], 23
	s_load_dwordx2 s[22:23], s[0:1], 0x98
	s_waitcnt lgkmcnt(0)
	s_add_u32 s21, s22, s24
	s_addc_u32 s22, s23, s25
	s_lshl_b32 s23, s4, 19
	s_add_u32 s21, s21, s23
	s_addc_u32 s23, s22, 0
	s_lshl_b32 s22, s6, 8
	s_add_u32 s22, s21, s22
	s_addc_u32 s23, s23, 0
	v_lshlrev_b32_e32 v14, 2, v12
	v_lshl_add_u64 v[2:3], s[22:23], 0, v[14:15]
	v_lshl_add_u64 v[144:145], v[2:3], 0, v[32:33]
	v_add_co_u32_e32 v6, vcc, s34, v144
	s_mul_i32 s6, s6, 0x60000
	s_nop 0
	v_addc_co_u32_e32 v7, vcc, 0, v145, vcc
	global_load_dwordx4 v[2:5], v[144:145], off
	s_nop 0
	global_load_dwordx4 v[6:9], v[6:7], off
	v_add_co_u32_e32 v146, vcc, s40, v144
	s_add_u32 s6, s57, s6
	s_nop 0
	v_addc_co_u32_e32 v147, vcc, 0, v145, vcc
	v_add_co_u32_e32 v148, vcc, s41, v144
	s_addc_u32 s21, s58, 0
	s_nop 0
	v_addc_co_u32_e32 v149, vcc, 0, v145, vcc
	s_lshl_b32 s5, s5, 11
	s_add_u32 s5, s6, s5
	s_addc_u32 s6, s21, 0
	s_lshl_b32 s4, s4, 7
	s_add_u32 s4, s5, s4
	v_lshlrev_b32_e32 v14, 1, v142
	s_addc_u32 s5, s6, 0
	s_waitcnt vmcnt(0) lgkmcnt(0)
	v_cvt_pk_bf16_f32 v2, v2, v6
	v_cvt_pk_bf16_f32 v3, v3, v7
	v_cvt_pk_bf16_f32 v4, v4, v8
	v_cvt_pk_bf16_f32 v5, v5, v9
	ds_write_b32 v13, v2
	ds_write_b32 v13, v3 offset:132
	ds_write_b32 v13, v4 offset:264
	ds_write_b32 v13, v5 offset:396
	global_load_dwordx4 v[2:5], v[146:147], off
	global_load_dwordx4 v[6:9], v[148:149], off
	v_add_co_u32_e32 v146, vcc, s42, v144
	s_waitcnt vmcnt(0) lgkmcnt(0)
	v_cvt_pk_bf16_f32 v2, v2, v6
	v_addc_co_u32_e32 v147, vcc, 0, v145, vcc
	v_add_co_u32_e32 v148, vcc, s43, v144
	v_cvt_pk_bf16_f32 v3, v3, v7
	v_cvt_pk_bf16_f32 v4, v4, v8
	v_cvt_pk_bf16_f32 v5, v5, v9
	ds_write_b32 v13, v2 offset:16
	ds_write_b32 v13, v3 offset:148
	ds_write_b32 v13, v4 offset:280
	ds_write_b32 v13, v5 offset:412
	v_addc_co_u32_e32 v149, vcc, 0, v145, vcc
	global_load_dwordx4 v[2:5], v[146:147], off
	global_load_dwordx4 v[6:9], v[148:149], off
	v_add_co_u32_e32 v146, vcc, s29, v144
	s_waitcnt vmcnt(0) lgkmcnt(0)
	v_cvt_pk_bf16_f32 v2, v2, v6
	v_addc_co_u32_e32 v147, vcc, 0, v145, vcc
	v_add_co_u32_e32 v148, vcc, s44, v144
	v_cvt_pk_bf16_f32 v3, v3, v7
	v_cvt_pk_bf16_f32 v4, v4, v8
	v_cvt_pk_bf16_f32 v5, v5, v9
	ds_write_b32 v13, v2 offset:32
	ds_write_b32 v13, v3 offset:164
	ds_write_b32 v13, v4 offset:296
	ds_write_b32 v13, v5 offset:428
	v_addc_co_u32_e32 v149, vcc, 0, v145, vcc
	global_load_dwordx4 v[2:5], v[146:147], off
	global_load_dwordx4 v[6:9], v[148:149], off
	v_add_co_u32_e32 v146, vcc, s45, v144
	s_waitcnt vmcnt(0) lgkmcnt(0)
	v_cvt_pk_bf16_f32 v2, v2, v6
	v_addc_co_u32_e32 v147, vcc, 0, v145, vcc
	v_add_co_u32_e32 v148, vcc, s46, v144
	v_cvt_pk_bf16_f32 v3, v3, v7
	v_cvt_pk_bf16_f32 v4, v4, v8
	v_cvt_pk_bf16_f32 v5, v5, v9
	ds_write_b32 v13, v2 offset:48
	ds_write_b32 v13, v3 offset:180
	ds_write_b32 v13, v4 offset:312
	ds_write_b32 v13, v5 offset:444
	v_addc_co_u32_e32 v149, vcc, 0, v145, vcc
	global_load_dwordx4 v[2:5], v[146:147], off
	global_load_dwordx4 v[6:9], v[148:149], off
	v_add_co_u32_e32 v146, vcc, s47, v144
	s_waitcnt vmcnt(0) lgkmcnt(0)
	v_cvt_pk_bf16_f32 v2, v2, v6
	v_addc_co_u32_e32 v147, vcc, 0, v145, vcc
	v_add_co_u32_e32 v148, vcc, s48, v144
	v_cvt_pk_bf16_f32 v3, v3, v7
	v_cvt_pk_bf16_f32 v4, v4, v8
	v_cvt_pk_bf16_f32 v5, v5, v9
	ds_write_b32 v13, v2 offset:64
	ds_write_b32 v13, v3 offset:196
	ds_write_b32 v13, v4 offset:328
	ds_write_b32 v13, v5 offset:460
	v_addc_co_u32_e32 v149, vcc, 0, v145, vcc
	global_load_dwordx4 v[2:5], v[146:147], off
	global_load_dwordx4 v[6:9], v[148:149], off
	v_add_co_u32_e32 v146, vcc, s49, v144
	s_waitcnt vmcnt(0) lgkmcnt(0)
; #define LAS __attribute__((address_space(3)))
; template <int I> DI const float* kin() { return (const float*)karg64<I * 8>(); }
; DI unsigned pk2(float a, float b) { f32x2 v = {a, b}; bf16v2 r = __builtin_convertvector(v, bf16v2); return __builtin_bit_cast(unsigned, r); }
; DI void tr_item(const float* src, size_t sld, bf16_t* dst, size_t dld, const float* ksc, LAS unsigned* scr, int lane) {
;     ...
;     for (int i = 0; i < 8; ++i) {
;         const int k = 8 * i + 2 * kq;
;         f32x4 a = *(const f32x4*)(src + (size_t)k * sld + 4 * ng);
;         f32x4 b = *(const f32x4*)(src + (size_t)(k + 1) * sld + 4 * ng);
;         if (ksc) { a *= ksc[k]; b *= ksc[k + 1]; }
;         LAS unsigned* d = scr + (4 * ng) * 33 + 4 * i + kq;
;         d[0] = pk2(a[0], b[0]); d[33] = pk2(a[1], b[1]); d[66] = pk2(a[2], b[2]); d[99] = pk2(a[3], b[3]);
;     }
;     asm volatile("s_waitcnt lgkmcnt(0)" ::: "memory");
; #pragma unroll
;     for (int j = 0; j < 8; ++j) {
;         const int n = (lane >> 3) + 8 * j, c = lane & 7;
;         const LAS unsigned* s = scr + n * 33 + 4 * c;
;         u32x4 o; o.x = s[0]; o.y = s[1]; o.z = s[2]; o.w = s[3];
;         *(u32x4*)(dst + (size_t)n * dld + 8 * c) = o;
;     }
;     asm volatile("s_waitcnt lgkmcnt(0)" ::: "memory");
; DI void phase_prologue(const Ctx& c) {
;     ...
;             tr_item(kin<19>() + ((size_t)l * 3 + b) * BW * DM + (size_t)kb * 64 * DM + nn * 64, (size_t)DM, Wl + WL_BR + (size_t)nn * 64 * (3 * BW) + b * BW + kb * 64, (size_t)(3 * BW), nullptr, scr, c.lane); continue; } r -= 3 * I_BR;
	v_cvt_pk_bf16_f32 v2, v2, v6
	v_addc_co_u32_e32 v147, vcc, 0, v145, vcc
	v_add_co_u32_e32 v148, vcc, s50, v144
	v_cvt_pk_bf16_f32 v3, v3, v7
	v_cvt_pk_bf16_f32 v4, v4, v8
	v_cvt_pk_bf16_f32 v5, v5, v9
	ds_write_b32 v13, v2 offset:80
	ds_write_b32 v13, v3 offset:212
	ds_write_b32 v13, v4 offset:344
	ds_write_b32 v13, v5 offset:476
	v_addc_co_u32_e32 v149, vcc, 0, v145, vcc
	global_load_dwordx4 v[2:5], v[146:147], off
	global_load_dwordx4 v[6:9], v[148:149], off
	v_add_co_u32_e32 v146, vcc, s51, v144
	s_waitcnt vmcnt(0) lgkmcnt(0)
	v_cvt_pk_bf16_f32 v2, v2, v6
	v_addc_co_u32_e32 v147, vcc, 0, v145, vcc
	v_add_co_u32_e32 v144, vcc, s52, v144
	v_cvt_pk_bf16_f32 v3, v3, v7
	v_cvt_pk_bf16_f32 v4, v4, v8
	v_cvt_pk_bf16_f32 v5, v5, v9
	ds_write_b32 v13, v2 offset:96
	ds_write_b32 v13, v3 offset:228
	ds_write_b32 v13, v4 offset:360
	ds_write_b32 v13, v5 offset:492
	v_addc_co_u32_e32 v145, vcc, 0, v145, vcc
	global_load_dwordx4 v[2:5], v[146:147], off
	global_load_dwordx4 v[6:9], v[144:145], off
	v_add_u32_e32 v146, v143, v51
	v_add_u32_e32 v144, 0x420, v146
	v_add_u32_e32 v145, 0x428, v146
	v_add_u32_e32 v147, 0x840, v146
	v_add_u32_e32 v148, 0x848, v146
	v_add_u32_e32 v149, 0xc60, v146
	v_add_u32_e32 v150, 0xc68, v146
	v_add_u32_e32 v151, 0x1080, v146
	v_add_u32_e32 v152, 0x1088, v146
	s_waitcnt vmcnt(0) lgkmcnt(0)
	v_cvt_pk_bf16_f32 v2, v2, v6
	v_cvt_pk_bf16_f32 v3, v3, v7
	v_cvt_pk_bf16_f32 v4, v4, v8
	v_cvt_pk_bf16_f32 v5, v5, v9
	ds_write_b32 v13, v2 offset:112
	ds_write_b32 v13, v3 offset:244
	ds_write_b32 v13, v4 offset:376
	ds_write_b32 v13, v5 offset:508
	s_waitcnt lgkmcnt(0)
	ds_read2_b32 v[2:3], v146 offset1:1
	ds_read2_b32 v[4:5], v146 offset0:2 offset1:3
	v_lshl_add_u64 v[6:7], s[4:5], 0, v[14:15]
	v_lshl_add_u64 v[6:7], v[6:7], 0, s[18:19]
	v_lshl_add_u64 v[8:9], v[6:7], 0, v[130:131]
	v_add_u32_e32 v14, 0x14a0, v146
	s_waitcnt lgkmcnt(0)
	global_store_dwordx4 v[8:9], v[2:5], off
	ds_read2_b32 v[2:3], v144 offset1:1
	ds_read2_b32 v[4:5], v145 offset1:1
	v_add_co_u32_e32 v144, vcc, s53, v8
	s_nop 1
	v_addc_co_u32_e32 v145, vcc, 0, v9, vcc
	s_waitcnt lgkmcnt(0)
	global_store_dwordx4 v[144:145], v[2:5], off
	ds_read2_b32 v[2:3], v147 offset1:1
	ds_read2_b32 v[4:5], v148 offset1:1
	v_add_co_u32_e32 v144, vcc, s54, v8
	s_nop 1
	v_addc_co_u32_e32 v145, vcc, 0, v9, vcc
	s_waitcnt lgkmcnt(0)
	global_store_dwordx4 v[144:145], v[2:5], off
	ds_read2_b32 v[2:3], v149 offset1:1
	ds_read2_b32 v[4:5], v150 offset1:1
	v_add_co_u32_e32 v8, vcc, s55, v8
	v_add_u32_e32 v144, 0x14a8, v146
	s_nop 0
	v_addc_co_u32_e32 v9, vcc, 0, v9, vcc
	s_waitcnt lgkmcnt(0)
	global_store_dwordx4 v[8:9], v[2:5], off
	ds_read2_b32 v[2:3], v151 offset1:1
	ds_read2_b32 v[4:5], v152 offset1:1
	v_lshl_add_u64 v[8:9], v[6:7], 0, v[132:133]
	s_waitcnt lgkmcnt(0)
	global_store_dwordx4 v[8:9], v[2:5], off
	ds_read2_b32 v[2:3], v14 offset1:1
	ds_read2_b32 v[4:5], v144 offset1:1
	v_lshl_add_u64 v[8:9], v[6:7], 0, v[134:135]
	v_add_u32_e32 v14, 0x18c0, v146
	v_add_u32_e32 v144, 0x18c8, v146
	s_waitcnt lgkmcnt(0)
	global_store_dwordx4 v[8:9], v[2:5], off
	ds_read2_b32 v[2:3], v14 offset1:1
	ds_read2_b32 v[4:5], v144 offset1:1
	v_lshl_add_u64 v[8:9], v[6:7], 0, v[136:137]
	v_add_u32_e32 v14, 0x1ce0, v146
	v_add_u32_e32 v144, 0x1ce8, v146
	v_lshl_add_u64 v[6:7], v[6:7], 0, v[138:139]
	s_waitcnt lgkmcnt(0)
	global_store_dwordx4 v[8:9], v[2:5], off
	ds_read2_b32 v[2:3], v14 offset1:1
	ds_read2_b32 v[4:5], v144 offset1:1
	s_waitcnt lgkmcnt(0)
	global_store_dwordx4 v[6:7], v[2:5], off
	s_waitcnt lgkmcnt(0)

; #define LAS __attribute__((address_space(3)))
; template <int I> DI const float* kin() { return (const float*)karg64<I * 8>(); }
; DI unsigned pk2(float a, float b) { f32x2 v = {a, b}; bf16v2 r = __builtin_convertvector(v, bf16v2); return __builtin_bit_cast(unsigned, r); }
; DI void tr_item(const float* src, size_t sld, bf16_t* dst, size_t dld, const float* ksc, LAS unsigned* scr, int lane) {
;     const int ng = lane & 15, kq = lane >> 4;
; #pragma unroll
;     for (int i = 0; i < 8; ++i) {
;         const int k = 8 * i + 2 * kq;
;         f32x4 a = *(const f32x4*)(src + (size_t)k * sld + 4 * ng);
;         f32x4 b = *(const f32x4*)(src + (size_t)(k + 1) * sld + 4 * ng);
;         if (ksc) { a *= ksc[k]; b *= ksc[k + 1]; }
;         LAS unsigned* d = scr + (4 * ng) * 33 + 4 * i + kq;
;         d[0] = pk2(a[0], b[0]); d[33] = pk2(a[1], b[1]); d[66] = pk2(a[2], b[2]); d[99] = pk2(a[3], b[3]);
;     }
; DI void phase_prologue(const Ctx& c) {
;     ...
;         if (r < I_IN) { conv_matrix_item(kin<9>() + (size_t)l * DM * DIN, DM, DIN, Wl + WL_IN, kin<8>() + l * DM, r, scr, c.lane); continue; } r -= I_IN;
.LBB0_52:
	s_mul_i32 s21, s20, 0x6400000
	s_load_dwordx2 s[4:5], s[0:1], 0x48
	s_waitcnt lgkmcnt(0)
	s_mul_hi_i32 s6, s20, 0x6400000
	s_add_u32 s21, s4, s21
	s_addc_u32 s6, s5, s6
	s_lshl_b32 s22, s20, 11
	s_ashr_i32 s23, s22, 31
	s_lshl_b64 s[22:23], s[22:23], 2
	s_load_dwordx2 s[4:5], s[0:1], 64
	s_waitcnt lgkmcnt(0)
	s_add_u32 s27, s4, s22
	s_mul_hi_i32 s22, s26, 0x51eb851f
	s_addc_u32 s59, s5, s23
	s_lshr_b32 s23, s22, 31
	s_ashr_i32 s22, s22, 6
	s_add_i32 s26, s22, s23
	s_lshl_b32 s22, s26, 6
	s_ashr_i32 s23, s22, 31
	s_lshl_b64 s[24:25], s[22:23], 2
	s_add_u32 s24, s27, s24
	s_mul_i32 s27, s26, 0xffffff38
	s_mulk_i32 s20, 0x4340
	s_addc_u32 s25, s59, s25
	s_sub_i32 s20, s27, s20
	s_add_i32 s20, s56, s20
	s_mul_hi_i32 s27, s26, 0x320000
	s_mul_i32 s26, s26, 0x320000
	s_add_u32 s21, s21, s26
	s_addc_u32 s6, s6, s27
	s_lshl_b32 s26, s20, 6
	s_ashr_i32 s27, s26, 31
	s_lshl_b64 s[26:27], s[26:27], 2
	s_add_u32 s26, s21, s26
	s_addc_u32 s27, s6, s27
	v_lshlrev_b32_e32 v14, 2, v12
	v_lshl_add_u64 v[144:145], s[26:27], 0, v[14:15]
	v_lshl_add_u64 v[2:3], v[144:145], 0, v[140:141]
	v_lshl_add_u64 v[6:7], v[144:145], 0, v[56:57]
	global_load_dwordx4 v[2:5], v[2:3], off
	s_nop 0
	global_load_dwordx4 v[6:9], v[6:7], off
	s_cmp_lg_u64 s[4:5], 0
	s_cselect_b64 s[26:27], -1, 0
	s_cmp_eq_u64 s[4:5], 0
	v_lshlrev_b32_e32 v14, 2, v50
	s_cbranch_scc1 .LBB0_54
	v_lshl_add_u64 v[146:147], s[24:25], 0, v[14:15]
	global_load_dwordx2 v[146:147], v[146:147], off
	s_waitcnt vmcnt(0) lgkmcnt(0)
	v_pk_mul_f32 v[4:5], v[4:5], v[146:147] op_sel_hi:[1,0]
	v_pk_mul_f32 v[2:3], v[2:3], v[146:147] op_sel_hi:[1,0]
	v_pk_mul_f32 v[8:9], v[8:9], v[146:147] op_sel:[0,1]
	v_pk_mul_f32 v[6:7], v[6:7], v[146:147] op_sel:[0,1]
.LBB0_54:
	s_waitcnt vmcnt(0) lgkmcnt(0)
	v_cvt_pk_bf16_f32 v2, v2, v6
	v_cvt_pk_bf16_f32 v3, v3, v7
	ds_write2_b32 v13, v2, v3 offset1:33
	v_cvt_pk_bf16_f32 v2, v4, v8
	v_cvt_pk_bf16_f32 v3, v5, v9
	ds_write2_b32 v13, v2, v3 offset0:66 offset1:99
	v_lshl_add_u64 v[2:3], v[144:145], 0, v[58:59]
	v_lshl_add_u64 v[6:7], v[144:145], 0, v[62:63]
	global_load_dwordx4 v[2:5], v[2:3], off
	s_nop 0
	global_load_dwordx4 v[6:9], v[6:7], off
	v_cndmask_b32_e64 v146, 0, 1, s[26:27]
	v_cmp_ne_u32_e64 s[4:5], 1, v146
	s_andn2_b64 vcc, exec, s[26:27]
	s_cbranch_vccnz .LBB0_56
	v_lshl_add_u64 v[146:147], s[24:25], 0, v[14:15]
	global_load_dwordx2 v[146:147], v[146:147], off offset:32
	s_waitcnt vmcnt(0) lgkmcnt(0)
	v_pk_mul_f32 v[4:5], v[4:5], v[146:147] op_sel_hi:[1,0]
	v_pk_mul_f32 v[2:3], v[2:3], v[146:147] op_sel_hi:[1,0]
	v_pk_mul_f32 v[8:9], v[8:9], v[146:147] op_sel:[0,1]
	v_pk_mul_f32 v[6:7], v[6:7], v[146:147] op_sel:[0,1]
.LBB0_56:
	s_waitcnt vmcnt(0) lgkmcnt(0)
	v_cvt_pk_bf16_f32 v2, v2, v6
	v_cvt_pk_bf16_f32 v3, v3, v7
	ds_write2_b32 v13, v2, v3 offset0:4 offset1:37
	v_cvt_pk_bf16_f32 v2, v4, v8
	v_cvt_pk_bf16_f32 v3, v5, v9
	ds_write2_b32 v13, v2, v3 offset0:70 offset1:103
	v_lshl_add_u64 v[2:3], v[144:145], 0, v[66:67]
	v_lshl_add_u64 v[6:7], v[144:145], 0, v[70:71]
	global_load_dwordx4 v[2:5], v[2:3], off
	s_nop 0
	global_load_dwordx4 v[6:9], v[6:7], off
	s_and_b64 vcc, exec, s[4:5]
	s_cbranch_vccnz .LBB0_58
	v_lshl_add_u64 v[146:147], s[24:25], 0, v[14:15]
	global_load_dwordx2 v[146:147], v[146:147], off offset:64
	s_waitcnt vmcnt(0) lgkmcnt(0)
	v_pk_mul_f32 v[4:5], v[4:5], v[146:147] op_sel_hi:[1,0]
	v_pk_mul_f32 v[2:3], v[2:3], v[146:147] op_sel_hi:[1,0]
	v_pk_mul_f32 v[8:9], v[8:9], v[146:147] op_sel:[0,1]
	v_pk_mul_f32 v[6:7], v[6:7], v[146:147] op_sel:[0,1]
; #define LAS __attribute__((address_space(3)))
; DI unsigned pk2(float a, float b) { f32x2 v = {a, b}; bf16v2 r = __builtin_convertvector(v, bf16v2); return __builtin_bit_cast(unsigned, r); }
; DI void tr_item(const float* src, size_t sld, bf16_t* dst, size_t dld, const float* ksc, LAS unsigned* scr, int lane) {
;     ...
;     for (int i = 0; i < 8; ++i) {
;         const int k = 8 * i + 2 * kq;
;         f32x4 a = *(const f32x4*)(src + (size_t)k * sld + 4 * ng);
;         f32x4 b = *(const f32x4*)(src + (size_t)(k + 1) * sld + 4 * ng);
;         if (ksc) { a *= ksc[k]; b *= ksc[k + 1]; }
;         LAS unsigned* d = scr + (4 * ng) * 33 + 4 * i + kq;
;         d[0] = pk2(a[0], b[0]); d[33] = pk2(a[1], b[1]); d[66] = pk2(a[2], b[2]); d[99] = pk2(a[3], b[3]);
;     }
.LBB0_58:
	s_waitcnt vmcnt(0) lgkmcnt(0)
	v_cvt_pk_bf16_f32 v2, v2, v6
	v_cvt_pk_bf16_f32 v3, v3, v7
	ds_write2_b32 v13, v2, v3 offset0:8 offset1:41
	v_cvt_pk_bf16_f32 v2, v4, v8
	v_cvt_pk_bf16_f32 v3, v5, v9
	ds_write2_b32 v13, v2, v3 offset0:74 offset1:107
	v_lshl_add_u64 v[2:3], v[144:145], 0, v[74:75]
	v_lshl_add_u64 v[6:7], v[144:145], 0, v[78:79]
	global_load_dwordx4 v[2:5], v[2:3], off
	s_nop 0
	global_load_dwordx4 v[6:9], v[6:7], off
	s_and_b64 vcc, exec, s[4:5]
	s_cbranch_vccnz .LBB0_60
	v_lshl_add_u64 v[146:147], s[24:25], 0, v[14:15]
	global_load_dwordx2 v[146:147], v[146:147], off offset:96
	s_waitcnt vmcnt(0) lgkmcnt(0)
	v_pk_mul_f32 v[4:5], v[4:5], v[146:147] op_sel_hi:[1,0]
	v_pk_mul_f32 v[2:3], v[2:3], v[146:147] op_sel_hi:[1,0]
	v_pk_mul_f32 v[8:9], v[8:9], v[146:147] op_sel:[0,1]
	v_pk_mul_f32 v[6:7], v[6:7], v[146:147] op_sel:[0,1]
.LBB0_60:
	s_waitcnt vmcnt(0) lgkmcnt(0)
	v_cvt_pk_bf16_f32 v2, v2, v6
	v_cvt_pk_bf16_f32 v3, v3, v7
	ds_write2_b32 v13, v2, v3 offset0:12 offset1:45
	v_cvt_pk_bf16_f32 v2, v4, v8
	v_cvt_pk_bf16_f32 v3, v5, v9
	ds_write2_b32 v13, v2, v3 offset0:78 offset1:111
	v_lshl_add_u64 v[2:3], v[144:145], 0, v[82:83]
	v_lshl_add_u64 v[6:7], v[144:145], 0, v[86:87]
	global_load_dwordx4 v[2:5], v[2:3], off
	s_nop 0
	global_load_dwordx4 v[6:9], v[6:7], off
	s_and_b64 vcc, exec, s[4:5]
	s_cbranch_vccnz .LBB0_62
	v_lshl_add_u64 v[146:147], s[24:25], 0, v[14:15]
	global_load_dwordx2 v[146:147], v[146:147], off offset:128
	s_waitcnt vmcnt(0) lgkmcnt(0)
	v_pk_mul_f32 v[4:5], v[4:5], v[146:147] op_sel_hi:[1,0]
	v_pk_mul_f32 v[2:3], v[2:3], v[146:147] op_sel_hi:[1,0]
	v_pk_mul_f32 v[8:9], v[8:9], v[146:147] op_sel:[0,1]
	v_pk_mul_f32 v[6:7], v[6:7], v[146:147] op_sel:[0,1]
.LBB0_62:
	s_waitcnt vmcnt(0) lgkmcnt(0)
	v_cvt_pk_bf16_f32 v2, v2, v6
	v_cvt_pk_bf16_f32 v3, v3, v7
	ds_write2_b32 v13, v2, v3 offset0:16 offset1:49
	v_cvt_pk_bf16_f32 v2, v4, v8
	v_cvt_pk_bf16_f32 v3, v5, v9
	ds_write2_b32 v13, v2, v3 offset0:82 offset1:115
	v_lshl_add_u64 v[2:3], v[144:145], 0, v[90:91]
	v_lshl_add_u64 v[6:7], v[144:145], 0, v[94:95]
	global_load_dwordx4 v[2:5], v[2:3], off
	s_nop 0
	global_load_dwordx4 v[6:9], v[6:7], off
	s_and_b64 vcc, exec, s[4:5]
	s_cbranch_vccnz .LBB0_64
	v_lshl_add_u64 v[146:147], s[24:25], 0, v[14:15]
	global_load_dwordx2 v[146:147], v[146:147], off offset:160
	s_waitcnt vmcnt(0) lgkmcnt(0)
	v_pk_mul_f32 v[4:5], v[4:5], v[146:147] op_sel_hi:[1,0]
	v_pk_mul_f32 v[2:3], v[2:3], v[146:147] op_sel_hi:[1,0]
	v_pk_mul_f32 v[8:9], v[8:9], v[146:147] op_sel:[0,1]
	v_pk_mul_f32 v[6:7], v[6:7], v[146:147] op_sel:[0,1]
.LBB0_64:
	s_waitcnt vmcnt(0) lgkmcnt(0)
	v_cvt_pk_bf16_f32 v2, v2, v6
	v_cvt_pk_bf16_f32 v3, v3, v7
	ds_write2_b32 v13, v2, v3 offset0:20 offset1:53
	v_cvt_pk_bf16_f32 v2, v4, v8
	v_cvt_pk_bf16_f32 v3, v5, v9
	ds_write2_b32 v13, v2, v3 offset0:86 offset1:119
	v_lshl_add_u64 v[2:3], v[144:145], 0, v[98:99]
	v_lshl_add_u64 v[6:7], v[144:145], 0, v[102:103]
	global_load_dwordx4 v[2:5], v[2:3], off
	s_nop 0
	global_load_dwordx4 v[6:9], v[6:7], off
	s_and_b64 vcc, exec, s[4:5]
	s_cbranch_vccnz .LBB0_66
	v_lshl_add_u64 v[146:147], s[24:25], 0, v[14:15]
	global_load_dwordx2 v[146:147], v[146:147], off offset:192
	s_waitcnt vmcnt(0) lgkmcnt(0)
	v_pk_mul_f32 v[4:5], v[4:5], v[146:147] op_sel_hi:[1,0]
	v_pk_mul_f32 v[2:3], v[2:3], v[146:147] op_sel_hi:[1,0]
	v_pk_mul_f32 v[8:9], v[8:9], v[146:147] op_sel:[0,1]
	v_pk_mul_f32 v[6:7], v[6:7], v[146:147] op_sel:[0,1]
.LBB0_66:
	s_waitcnt vmcnt(0) lgkmcnt(0)
	v_cvt_pk_bf16_f32 v2, v2, v6
	v_cvt_pk_bf16_f32 v3, v3, v7
	ds_write2_b32 v13, v2, v3 offset0:24 offset1:57
	v_cvt_pk_bf16_f32 v2, v4, v8
	v_cvt_pk_bf16_f32 v3, v5, v9
	ds_write2_b32 v13, v2, v3 offset0:90 offset1:123
	v_lshl_add_u64 v[2:3], v[144:145], 0, v[106:107]
	v_lshl_add_u64 v[6:7], v[144:145], 0, v[110:111]
	global_load_dwordx4 v[2:5], v[2:3], off
	s_nop 0
	global_load_dwordx4 v[6:9], v[6:7], off
	s_and_b64 vcc, exec, s[4:5]
	s_cbranch_vccnz .LBB0_11
	v_lshl_add_u64 v[144:145], s[24:25], 0, v[14:15]
	global_load_dwordx2 v[144:145], v[144:145], off offset:224
	s_waitcnt vmcnt(0) lgkmcnt(0)
	v_pk_mul_f32 v[4:5], v[4:5], v[144:145] op_sel_hi:[1,0]
	v_pk_mul_f32 v[2:3], v[2:3], v[144:145] op_sel_hi:[1,0]
	v_pk_mul_f32 v[8:9], v[8:9], v[144:145] op_sel:[0,1]
	v_pk_mul_f32 v[6:7], v[6:7], v[144:145] op_sel:[0,1]
	s_branch .LBB0_11

; DI unsigned char* kws() { return (unsigned char*)karg64<208>(); }
; DI unsigned pk2(float a, float b) { f32x2 v = {a, b}; bf16v2 r = __builtin_convertvector(v, bf16v2); return __builtin_bit_cast(unsigned, r); }
; DI void phase_norm(const Ctx& c, const float* xP, const float* xS) {
;     const int gw = c.bid * NWAVES + c.wave, NGW = c.G * NWAVES;
;     bf16_t* act = (bf16_t*)(kws() + WS_ACT); float* rs = (float*)(kws() + WS_RS);
;     for (int row = gw; row < M; row += NGW) {
;         const f32x4* xr = (const f32x4*)((row < MP ? xP : xS) + (size_t)row * DM) + c.lane;
;         f32x4 v[8]; float s = 0.f;
; #pragma unroll
;         for (int j = 0; j < 8; ++j) { v[j] = xr[64 * j]; s += (v[j][0] * v[j][0] + v[j][1] * v[j][1]) + (v[j][2] * v[j][2] + v[j][3] * v[j][3]); }
;         s = wave_sum(s);
;         if (c.lane == 0) rs[row] = 1.0f / sqrtf(s * (1.0f / DM) + EPS);
;         u32x2* o = (u32x2*)(act + (size_t)row * DM) + c.lane;
; #pragma unroll
;         for (int j = 0; j < 8; ++j) { u32x2 w; w.x = pk2(v[j][0], v[j][1]); w.y = pk2(v[j][2], v[j][3]); o[64 * j] = w; }
;     }
; }
.LBB0_70:
	s_or_b64 exec, exec, s[22:23]
	v_cvt_pk_bf16_f32 v2, v2, v3
	v_cvt_pk_bf16_f32 v3, v4, v5
	global_store_dwordx2 v[34:35], v[2:3], off offset:2048
	v_cvt_pk_bf16_f32 v2, v6, v7
	v_cvt_pk_bf16_f32 v3, v8, v9
	s_add_i32 s8, s8, s10
	v_cvt_pk_bf16_f32 v26, v26, v27
	v_cvt_pk_bf16_f32 v27, v28, v29
	global_store_dwordx2 v[34:35], v[2:3], off offset:2560
	v_cvt_pk_bf16_f32 v2, v10, v11
	v_cvt_pk_bf16_f32 v3, v12, v13
	s_add_u32 s14, s14, s16
	global_store_dwordx2 v[34:35], v[26:27], off
	v_cvt_pk_bf16_f32 v26, v30, v31
	v_cvt_pk_bf16_f32 v27, v32, v33
	v_cvt_pk_bf16_f32 v22, v22, v23
	v_cvt_pk_bf16_f32 v23, v24, v25
	v_cvt_pk_bf16_f32 v18, v18, v19
	v_cvt_pk_bf16_f32 v19, v20, v21
	global_store_dwordx2 v[34:35], v[2:3], off offset:3072
	v_cvt_pk_bf16_f32 v2, v14, v15
	v_cvt_pk_bf16_f32 v3, v16, v17
	s_addc_u32 s15, s15, s17
	global_store_dwordx2 v[34:35], v[26:27], off offset:512
	global_store_dwordx2 v[34:35], v[22:23], off offset:1024
	global_store_dwordx2 v[34:35], v[18:19], off offset:1536
	global_store_dwordx2 v[34:35], v[2:3], off offset:3584
	v_lshl_add_u64 v[34:35], v[34:35], 0, s[18:19]
	s_cmpk_lt_i32 s8, 0x4800
	v_lshl_add_u64 v[36:37], v[36:37], 0, s[20:21]
	s_cbranch_scc0 .LBB0_73
.LBB0_71:
	s_cmpk_lt_i32 s8, 0x4000
	s_cselect_b32 s7, s13, s24
	s_cselect_b32 s6, s12, s3
	v_lshl_add_u64 v[18:19], s[6:7], 0, v[36:37]
	v_add_co_u32_e32 v20, vcc, 0xfffff000, v18
	global_load_dwordx4 v[2:5], v[18:19], off
	global_load_dwordx4 v[6:9], v[18:19], off offset:1024
	global_load_dwordx4 v[10:13], v[18:19], off offset:2048
	global_load_dwordx4 v[14:17], v[18:19], off offset:3072
	v_addc_co_u32_e32 v21, vcc, -1, v19, vcc
	global_load_dwordx4 v[26:29], v[20:21], off
	v_add_co_u32_e32 v20, vcc, 0xfffff400, v18
	s_waitcnt vmcnt(0) lgkmcnt(0)
	v_mul_f32_e32 v45, v3, v3
	v_addc_co_u32_e32 v21, vcc, -1, v19, vcc
	v_add_co_u32_e32 v22, vcc, 0xfffff800, v18
	global_load_dwordx4 v[30:33], v[20:21], off
	s_nop 0
	v_addc_co_u32_e32 v23, vcc, -1, v19, vcc
	v_add_co_u32_e32 v18, vcc, 0xfffffc00, v18
	global_load_dwordx4 v[22:25], v[22:23], off
	s_nop 0
	v_addc_co_u32_e32 v19, vcc, -1, v19, vcc
	global_load_dwordx4 v[18:21], v[18:19], off
	v_mul_f32_e32 v46, v5, v5
	v_mul_f32_e32 v47, v7, v7
	v_mul_f32_e32 v48, v9, v9
	v_mul_f32_e32 v49, v11, v11
	v_mul_f32_e32 v50, v13, v13
	v_fmac_f32_e32 v45, v2, v2
	v_fmac_f32_e32 v46, v4, v4
	v_fmac_f32_e32 v47, v6, v6
	v_fmac_f32_e32 v48, v8, v8
	v_fmac_f32_e32 v49, v10, v10
	v_fmac_f32_e32 v50, v12, v12
	v_mul_f32_e32 v53, v27, v27
	v_mul_f32_e32 v54, v29, v29
	v_add_f32_e32 v45, v45, v46
	v_add_f32_e32 v46, v47, v48
	v_add_f32_e32 v47, v49, v50
	v_fmac_f32_e32 v53, v26, v26
	v_fmac_f32_e32 v54, v28, v28
	v_add_f32_e32 v50, v53, v54
	v_mul_f32_e32 v51, v15, v15
	v_mul_f32_e32 v52, v17, v17
	v_fmac_f32_e32 v51, v14, v14
	v_fmac_f32_e32 v52, v16, v16
	s_waitcnt vmcnt(0) lgkmcnt(0)
	v_mul_f32_e32 v48, v31, v31
	v_mul_f32_e32 v49, v33, v33
	v_fmac_f32_e32 v48, v30, v30
	v_fmac_f32_e32 v49, v32, v32
	v_add_f32_e32 v48, v48, v49
	v_mul_f32_e32 v53, v23, v23
	v_mul_f32_e32 v54, v25, v25
	v_fmac_f32_e32 v53, v22, v22
	v_fmac_f32_e32 v54, v24, v24
	v_mul_f32_e32 v49, v19, v19
	v_mul_f32_e32 v55, v21, v21
	v_add_f32_e32 v48, v50, v48
	v_add_f32_e32 v50, v53, v54
	v_fmac_f32_e32 v49, v18, v18
	v_fmac_f32_e32 v55, v20, v20
	v_add_f32_e32 v48, v48, v50
	v_add_f32_e32 v49, v49, v55
	v_add_f32_e32 v48, v48, v49
	v_add_f32_e32 v45, v48, v45
	v_add_f32_e32 v45, v45, v46
	v_add_f32_e32 v45, v45, v47
	v_add_f32_e32 v46, v51, v52
	v_add_f32_e32 v45, v45, v46
	ds_bpermute_b32 v46, v38, v45
	s_waitcnt lgkmcnt(0)
	v_add_f32_e32 v45, v45, v46
	ds_bpermute_b32 v46, v39, v45
	s_waitcnt lgkmcnt(0)
	v_add_f32_e32 v45, v45, v46
	ds_bpermute_b32 v46, v40, v45
	s_waitcnt lgkmcnt(0)
	v_add_f32_e32 v45, v45, v46
	ds_bpermute_b32 v46, v41, v45
	s_waitcnt lgkmcnt(0)
	v_add_f32_e32 v45, v45, v46
	ds_bpermute_b32 v46, v42, v45
	s_waitcnt lgkmcnt(0)
	v_add_f32_e32 v45, v45, v46
	ds_bpermute_b32 v46, v43, v45
	s_and_saveexec_b64 s[22:23], s[4:5]
	s_cbranch_execz .LBB0_70
	s_waitcnt lgkmcnt(0)
	v_add_f32_e32 v45, v45, v46
	v_fmamk_f32 v45, v45, 0x3a000000, v1
	v_mul_f32_e32 v46, 0x4f800000, v45
	v_cmp_gt_f32_e32 vcc, s9, v45
	s_nop 1
	v_cndmask_b32_e32 v45, v45, v46, vcc
	v_sqrt_f32_e32 v46, v45
	s_nop 0
	v_add_u32_e32 v47, -1, v46
	v_fma_f32 v49, -v47, v46, v45
	v_add_u32_e32 v48, 1, v46
	v_cmp_ge_f32_e64 s[6:7], 0, v49
	s_nop 1
	v_cndmask_b32_e64 v47, v46, v47, s[6:7]
	v_fma_f32 v46, -v48, v46, v45
	v_cmp_lt_f32_e64 s[6:7], 0, v46
	s_nop 1
	v_cndmask_b32_e64 v46, v47, v48, s[6:7]
	v_mul_f32_e32 v47, 0x37800000, v46
	v_cndmask_b32_e32 v46, v46, v47, vcc
	v_cmp_class_f32_e32 vcc, v45, v44
	s_nop 1
	v_cndmask_b32_e32 v45, v46, v45, vcc
	v_div_scale_f32 v46, s[6:7], v45, v45, 1.0
	v_rcp_f32_e32 v47, v46
	s_nop 0
	v_fma_f32 v48, -v46, v47, 1.0
	v_fmac_f32_e32 v47, v48, v47
	v_div_scale_f32 v48, vcc, 1.0, v45, 1.0
	v_mul_f32_e32 v49, v48, v47
	v_fma_f32 v50, -v46, v49, v48
	v_fmac_f32_e32 v49, v50, v47
	v_fma_f32 v46, -v46, v49, v48
	v_div_fmas_f32 v46, v46, v47, v49
	v_div_fixup_f32 v45, v46, v45, 1.0
	v_mov_b64_e32 v[46:47], s[14:15]
	global_store_dword v[46:47], v45, off
	s_branch .LBB0_70

; DI unsigned xb_ld(unsigned* p)              { return __hip_atomic_load(p, __ATOMIC_RELAXED, __HIP_MEMORY_SCOPE_AGENT); }
; DI void xcd_barrier_complete(unsigned* bar, unsigned x, unsigned& nloc, unsigned& nx) {
;     const unsigned G = gridDim.x * gridDim.y * gridDim.z;
;     unsigned sum, cnt, mine, sp = 0u;
;     for (;;) {
;         sum = 0u; cnt = 0u; mine = 0u;
; #pragma unroll
;         for (unsigned j = 0; j < 16; ++j) { const unsigned c = xb_ld(&bar[XB_XCNT(j)]); sum += c; cnt += (c > 0u) ? 1u : 0u; mine = (j == x) ? c : mine; }
;         if (sum == G) break;
;         __builtin_amdgcn_s_sleep(1);
;         if ((++sp & 255u) == 0u) { if (xb_ld(&bar[XB_TMO])) break; if (sp > XB_SPIN_CAP) { atomicAdd(&bar[XB_TMO], 1u); break; } }
;     }
;     nloc = mine > 0u ? mine : 1u; nx = cnt > 0u ? cnt : 1u;
; }
.LBB0_79:
	global_load_dword v26, v[2:3], off offset:1024 sc1
	global_load_dword v1, v[2:3], off offset:1280 sc1
	global_load_dword v12, v[2:3], off offset:1536 sc1
	global_load_dword v13, v[2:3], off offset:1792 sc1
	global_load_dword v14, v[2:3], off offset:2048 sc1
	global_load_dword v15, v[2:3], off offset:2304 sc1
	global_load_dword v16, v[2:3], off offset:2560 sc1
	global_load_dword v17, v[2:3], off offset:2816 sc1
	global_load_dword v18, v[2:3], off offset:3072 sc1
	global_load_dword v19, v[2:3], off offset:3328 sc1
	global_load_dword v20, v[2:3], off offset:3584 sc1
	global_load_dword v21, v[2:3], off offset:3840 sc1
	global_load_dword v22, v[4:5], off sc1
	global_load_dword v23, v[6:7], off sc1
	global_load_dword v24, v[8:9], off sc1
	global_load_dword v25, v[10:11], off sc1
	s_or_b64 s[10:11], s[10:11], exec
	s_or_b64 s[8:9], s[8:9], exec
	s_waitcnt vmcnt(0) lgkmcnt(0)
	v_add_u32_e32 v27, v1, v26
	v_add_u32_e32 v27, v27, v12
	v_add_u32_e32 v27, v27, v13
	v_add_u32_e32 v27, v27, v14
	v_add_u32_e32 v27, v27, v15
	v_add_u32_e32 v27, v27, v16
	v_add_u32_e32 v27, v27, v17
	v_add_u32_e32 v27, v27, v18
	v_add_u32_e32 v27, v27, v19
	v_add_u32_e32 v27, v27, v20
	v_add_u32_e32 v27, v27, v21
	v_add_u32_e32 v27, v27, v22
	v_add_u32_e32 v27, v27, v23
	v_add_u32_e32 v27, v27, v24
	v_add_u32_e32 v27, v27, v25
	v_cmp_ne_u32_e32 vcc, s3, v27
	s_and_saveexec_b64 s[12:13], vcc
	s_cbranch_execz .LBB0_78
	s_and_b32 s16, s22, 0xff
	s_mov_b64 s[14:15], -1
	s_cmp_eq_u32 s16, 0
	s_mov_b64 s[18:19], -1
	s_mov_b64 s[16:17], -1
	s_sleep 1
	s_cbranch_scc1 .LBB0_82
	s_and_saveexec_b64 s[20:21], s[18:19]
	s_cbranch_execz .LBB0_77
	s_branch .LBB0_85
.LBB0_82:
	global_load_dword v27, v[2:3], off offset:512 sc1
	s_mov_b64 s[18:19], 0
	s_waitcnt vmcnt(0) lgkmcnt(0)
	v_cmp_eq_u32_e32 vcc, 0, v27
	s_and_saveexec_b64 s[20:21], vcc
	s_cmp_lt_u32 s22, 0x100001
	s_cselect_b64 s[18:19], -1, 0
	s_xor_b64 s[16:17], exec, -1
	s_and_b64 s[18:19], s[18:19], exec
	s_or_b64 exec, exec, s[20:21]
	s_and_saveexec_b64 s[20:21], s[18:19]
	s_cbranch_execz .LBB0_77

; DI unsigned xb_ld(unsigned* p)              { return __hip_atomic_load(p, __ATOMIC_RELAXED, __HIP_MEMORY_SCOPE_AGENT); }
; DI unsigned xb_add(unsigned* p, unsigned v) { return __hip_atomic_fetch_add(p, v, __ATOMIC_RELAXED, __HIP_MEMORY_SCOPE_AGENT); }
; #define XB_SPIN(cond, bar) do { unsigned _sp = 0; while (cond) { __builtin_amdgcn_s_sleep(1); \
;     if ((++_sp & 255u) == 0u) { if (xb_ld(&(bar)[XB_TMO])) break; if (_sp > XB_SPIN_CAP) { atomicAdd(&(bar)[XB_TMO], 1u); break; } } } } while (0)
; DI void xcd_barrier(const XcdBarrier& b) {
;     ...
;     if (threadIdx.x == 0) {
;         unsigned* bar = b.bar;
;         __builtin_amdgcn_s_waitcnt(0);
;         unsigned nloc = b.st[0], nx = b.st[1];
;         if (nloc == 0u) { xcd_barrier_complete(bar, b.x, nloc, nx); b.st[0] = nloc; b.st[1] = nx; }
;         const unsigned old = xb_add(&bar[XB_XSUB(b.x)], 1u);
;         const unsigned gen = old / nloc;
;         if (old + 1u == (gen + 1u) * nloc) {
;             __builtin_amdgcn_fence(__ATOMIC_RELEASE, "agent");
;             asm volatile("s_waitcnt vmcnt(0)" ::: "memory");
;             const unsigned og = xb_add(&bar[XB_TOP], 1u);
;             const unsigned tg = og / nx;
;             if (og + 1u == (tg + 1u) * nx) xb_add(&bar[XB_TOPGEN], 1u);
;             else XB_SPIN(xb_ld(&bar[XB_TOPGEN]) == tg, bar);
;             __builtin_amdgcn_fence(__ATOMIC_ACQUIRE, "agent");
;             xb_add(&bar[XB_XGEN(b.x)], 1u);
;             asm volatile("s_waitcnt vmcnt(0)" ::: "memory");
;         } else {
;             XB_SPIN(xb_ld(&bar[XB_XGEN(b.x)]) == gen, bar);
.LBB0_89:
	s_lshl_b32 s3, s33, 8
	s_add_u32 s24, s38, s3
	s_addc_u32 s3, s39, 0
	v_mov_b32_e32 v1, s24
	v_add_co_u32_e32 v6, vcc, 0x1000, v1
	v_mov_b32_e32 v1, s3
	s_nop 0
	v_addc_co_u32_e32 v7, vcc, 0, v1, vcc
	v_mov_b32_e32 v1, 1
	flat_atomic_add v1, v[6:7], v1 offset:1024 sc0
	v_cvt_f32_u32_e32 v3, v4
	v_sub_u32_e32 v5, 0, v4
	v_rcp_iflag_f32_e32 v3, v3
	s_nop 0
	v_mul_f32_e32 v3, 0x4f7ffffe, v3
	v_cvt_u32_f32_e32 v3, v3
	v_mul_lo_u32 v5, v5, v3
	v_mul_hi_u32 v5, v3, v5
	v_add_u32_e32 v3, v3, v5
	s_waitcnt vmcnt(0) lgkmcnt(0)
	v_mul_hi_u32 v3, v1, v3
	v_mul_lo_u32 v5, v3, v4
	v_add_u32_e32 v6, 1, v1
	v_sub_u32_e32 v1, v1, v5
	v_add_u32_e32 v7, 1, v3
	v_cmp_ge_u32_e32 vcc, v1, v4
	v_sub_u32_e32 v5, v1, v4
	s_nop 0
	v_cndmask_b32_e32 v3, v3, v7, vcc
	v_cndmask_b32_e32 v1, v1, v5, vcc
	v_add_u32_e32 v5, 1, v3
	v_cmp_ge_u32_e32 vcc, v1, v4
	s_nop 1
	v_cndmask_b32_e32 v1, v3, v5, vcc
	v_mad_u64_u32 v[4:5], s[4:5], v4, v1, v[4:5]
	v_cmp_ne_u32_e32 vcc, v6, v4
	s_and_saveexec_b64 s[4:5], vcc
	s_xor_b64 s[4:5], exec, s[4:5]
	s_cbranch_execz .LBB0_102
	v_mov_b32_e32 v2, s24
	v_add_co_u32_e32 v2, vcc, 0x2000, v2
	v_mov_b32_e32 v3, s3
	s_nop 0
	v_addc_co_u32_e32 v3, vcc, 0, v3, vcc
	global_load_dword v2, v[2:3], off offset:1024 sc1
	s_add_u32 s8, s24, 0x2400
	s_addc_u32 s9, s3, 0
	s_waitcnt vmcnt(0) lgkmcnt(0)
	v_cmp_eq_u32_e32 vcc, v2, v1
	s_and_saveexec_b64 s[6:7], vcc
	s_cbranch_execz .LBB0_101
	s_mov_b32 s25, 1
	s_mov_b64 s[10:11], 0
	s_branch .LBB0_93

; DI unsigned xb_ld(unsigned* p)              { return __hip_atomic_load(p, __ATOMIC_RELAXED, __HIP_MEMORY_SCOPE_AGENT); }
; #define XB_SPIN(cond, bar) do { unsigned _sp = 0; while (cond) { __builtin_amdgcn_s_sleep(1); \
;     if ((++_sp & 255u) == 0u) { if (xb_ld(&(bar)[XB_TMO])) break; if (_sp > XB_SPIN_CAP) { atomicAdd(&(bar)[XB_TMO], 1u); break; } } } } while (0)
; DI void xcd_barrier(const XcdBarrier& b) {
;     ...
;             XB_SPIN(xb_ld(&bar[XB_XGEN(b.x)]) == gen, bar);
.LBB0_93:
	s_and_b32 s18, s25, 0xff
	s_mov_b64 s[16:17], -1
	s_cmp_lg_u32 s18, 0
	s_mov_b64 s[18:19], -1
	s_sleep 1
	s_cbranch_scc1 .LBB0_97
	v_mov_b64_e32 v[2:3], s[38:39]
	global_load_dword v2, v[2:3], off offset:512 sc1
	s_mov_b64 s[18:19], 0
	s_mov_b64 s[20:21], -1
	s_waitcnt vmcnt(0) lgkmcnt(0)
	v_cmp_eq_u32_e32 vcc, 0, v2
	s_and_saveexec_b64 s[22:23], vcc
	s_cmp_lt_u32 s25, 0x100001
	s_cselect_b64 s[18:19], -1, 0
	s_xor_b64 s[20:21], exec, -1
	s_and_b64 s[18:19], s[18:19], exec
	s_or_b64 exec, exec, s[22:23]
.LBB0_97:
	s_andn2_b64 s[14:15], s[14:15], exec
	s_and_b64 s[20:21], s[20:21], exec
	s_or_b64 s[14:15], s[14:15], s[20:21]
	s_and_saveexec_b64 s[20:21], s[18:19]
	s_cbranch_execz .LBB0_92
	v_mov_b64_e32 v[2:3], s[8:9]
	global_load_dword v2, v[2:3], off sc1
	s_add_i32 s25, s25, 1
	s_or_b64 s[14:15], s[14:15], exec
	s_waitcnt vmcnt(0) lgkmcnt(0)
	v_cmp_ne_u32_e32 vcc, v2, v1
	s_orn2_b64 s[16:17], vcc, exec
	s_branch .LBB0_92

; DI unsigned xb_ld(unsigned* p)              { return __hip_atomic_load(p, __ATOMIC_RELAXED, __HIP_MEMORY_SCOPE_AGENT); }
; DI unsigned xb_add(unsigned* p, unsigned v) { return __hip_atomic_fetch_add(p, v, __ATOMIC_RELAXED, __HIP_MEMORY_SCOPE_AGENT); }
; #define XB_SPIN(cond, bar) do { unsigned _sp = 0; while (cond) { __builtin_amdgcn_s_sleep(1); \
;     if ((++_sp & 255u) == 0u) { if (xb_ld(&(bar)[XB_TMO])) break; if (_sp > XB_SPIN_CAP) { atomicAdd(&(bar)[XB_TMO], 1u); break; } } } } while (0)
; DI void xcd_barrier(const XcdBarrier& b) {
;     ...
;         if (old + 1u == (gen + 1u) * nloc) {
;             __builtin_amdgcn_fence(__ATOMIC_RELEASE, "agent");
;             asm volatile("s_waitcnt vmcnt(0)" ::: "memory");
;             const unsigned og = xb_add(&bar[XB_TOP], 1u);
;             const unsigned tg = og / nx;
;             if (og + 1u == (tg + 1u) * nx) xb_add(&bar[XB_TOPGEN], 1u);
;             else XB_SPIN(xb_ld(&bar[XB_TOPGEN]) == tg, bar);
.LBB0_102:
	s_andn2_saveexec_b64 s[4:5], s[4:5]
	s_cbranch_execz .LBB0_118
	v_mov_b32_e32 v1, s38
	v_add_co_u32_e32 v4, vcc, 0x3000, v1
	v_mov_b32_e32 v1, s39
	buffer_wbl2 sc1
	s_waitcnt vmcnt(0)
	v_addc_co_u32_e32 v5, vcc, 0, v1, vcc
	v_mov_b32_e32 v1, 1
	flat_atomic_add v1, v[4:5], v1 offset:1024 sc0
	v_cvt_f32_u32_e32 v3, v2
	v_sub_u32_e32 v4, 0, v2
	s_add_u32 s4, s38, 0x3500
	s_addc_u32 s5, s39, 0
	v_rcp_iflag_f32_e32 v3, v3
	s_mov_b64 s[8:9], -1
	v_mul_f32_e32 v3, 0x4f7ffffe, v3
	v_cvt_u32_f32_e32 v3, v3
	v_mul_lo_u32 v4, v4, v3
	v_mul_hi_u32 v4, v3, v4
	v_add_u32_e32 v3, v3, v4
	s_waitcnt vmcnt(0) lgkmcnt(0)
	v_mul_hi_u32 v3, v1, v3
	v_mul_lo_u32 v5, v3, v2
	v_add_u32_e32 v4, 1, v1
	v_sub_u32_e32 v1, v1, v5
	v_add_u32_e32 v6, 1, v3
	v_cmp_ge_u32_e32 vcc, v1, v2
	v_sub_u32_e32 v5, v1, v2
	s_nop 0
	v_cndmask_b32_e32 v3, v3, v6, vcc
	v_cndmask_b32_e32 v1, v1, v5, vcc
	v_add_u32_e32 v5, 1, v3
	v_cmp_ge_u32_e32 vcc, v1, v2
	s_nop 1
	v_cndmask_b32_e32 v1, v3, v5, vcc
	v_mad_u64_u32 v[2:3], s[6:7], v2, v1, v[2:3]
	v_cmp_ne_u32_e32 vcc, v4, v2
	v_mov_b64_e32 v[2:3], s[4:5]
	s_and_saveexec_b64 s[6:7], vcc
	s_cbranch_execz .LBB0_115
	v_mov_b64_e32 v[2:3], s[4:5]
	global_load_dword v2, v[2:3], off sc1
	s_mov_b64 s[12:13], 0
	s_waitcnt vmcnt(0) lgkmcnt(0)
	v_cmp_eq_u32_e32 vcc, v2, v1
	s_and_saveexec_b64 s[10:11], vcc
	s_cbranch_execz .LBB0_114
	s_add_u32 s8, s38, 0x200
	s_addc_u32 s9, s39, 0
	s_mov_b32 s25, 1
	s_branch .LBB0_107

; DI unsigned xb_ld(unsigned* p)              { return __hip_atomic_load(p, __ATOMIC_RELAXED, __HIP_MEMORY_SCOPE_AGENT); }
; #define XB_SPIN(cond, bar) do { unsigned _sp = 0; while (cond) { __builtin_amdgcn_s_sleep(1); \
;     if ((++_sp & 255u) == 0u) { if (xb_ld(&(bar)[XB_TMO])) break; if (_sp > XB_SPIN_CAP) { atomicAdd(&(bar)[XB_TMO], 1u); break; } } } } while (0)
; DI void xcd_barrier(const XcdBarrier& b) {
;     ...
;             else XB_SPIN(xb_ld(&bar[XB_TOPGEN]) == tg, bar);
.LBB0_109:
	v_mov_b64_e32 v[2:3], s[8:9]
	global_load_dword v2, v[2:3], off sc1
	s_mov_b64 s[18:19], 0
	s_mov_b64 s[16:17], -1
	s_waitcnt vmcnt(0) lgkmcnt(0)
	v_cmp_eq_u32_e32 vcc, 0, v2
	s_and_saveexec_b64 s[20:21], vcc
	s_cmp_lt_u32 s25, 0x100001
	s_cselect_b64 s[18:19], -1, 0
	s_xor_b64 s[16:17], exec, -1
	s_and_b64 s[18:19], s[18:19], exec
	s_or_b64 exec, exec, s[20:21]
	s_mov_b64 s[20:21], -1
	s_and_saveexec_b64 s[22:23], s[18:19]
	s_cbranch_execz .LBB0_106
.LBB0_112:
	v_mov_b64_e32 v[2:3], s[4:5]
	global_load_dword v2, v[2:3], off sc1
	s_add_i32 s25, s25, 1
	s_or_b64 s[16:17], s[16:17], exec
	s_waitcnt vmcnt(0) lgkmcnt(0)
	v_cmp_ne_u32_e32 vcc, v2, v1
	s_orn2_b64 s[20:21], vcc, exec
	s_branch .LBB0_106

; #define LAS __attribute__((address_space(3)))
; DI u32x2 packq8(const f32x4 v0, const f32x4 v1) { u32x2 w; w.x = pk4q8(v0); w.y = pk4q8(v1); return w; }
; DI u32x4 pack8(const f32x4 v0, const f32x4 v1) { u32x4 w; w.x = pk2(v0[0], v0[1]); w.y = pk2(v0[2], v0[3]); w.z = pk2(v1[0], v1[1]); w.w = pk2(v1[2], v1[3]); return w; }
;     DI void operator()(const f32x4 (&acc)[2][2][4][2], const Unit& u, int wr, int wc, int fr, int fq, const LAS float* rsl) const {
;         const int row0 = u.pm * BM + wr * 64 + fr, col0 = u.pn * BM + wc * 32 + 8 * fq;
;         const bool gate = u.pn >= C_G / BM;
; #pragma unroll
;         for (int ai = 0; ai < 2; ++ai)
; #pragma unroll
;             for (int m = 0; m < 4; ++m) {
;                 const int row = row0 + ai * HALF + m * 16;
;                 if (u.ks < 0) {
;                     const float s = rsl[wr * 64 + fr + ai * HALF + m * 16];
;                     bf16_t* rowp = Z + (size_t)row * ZLD + col0;
;                     unsigned char* gq = GT + ((size_t)u.pm * 24 + (u.pn - 26)) * 65536 + (((((wr * 4 + wc) * 2 + ai) * 4 + m) * 64 + fq * 16 + fr) << 4);
;                     u32x4 gw;
; #pragma unroll
;                     for (int bj = 0; bj < 2; ++bj) {
;                         f32x4 v0 = acc[ai][bj][m][0] * s, v1 = acc[ai][bj][m][1] * s;
;                         if (gate) {
; #pragma unroll
;                             for (int j = 0; j < 4; ++j) { v0[j] = __builtin_amdgcn_rcpf(1.0f + __expf(-v0[j])); v1[j] = __builtin_amdgcn_rcpf(1.0f + __expf(-v1[j])); }
;                             const u32x2 w8 = packq8(v0, v1); if (bj == 0) { gw.x = w8.x; gw.y = w8.y; } else { gw.z = w8.x; gw.w = w8.y; }
;                         } else *(u32x4*)(rowp + bj * HALF) = pack8(v0, v1);
;                     }
;                     if (gate) *(u32x4*)gq = gw;
;                 } else {
;                     float* pp = part + (((size_t)u.ks * 16 + (u.pn - 26)) * 256 + (row - 71 * BM)) * 256 + wc * 32 + 8 * fq;
; #pragma unroll
;                     for (int bj = 0; bj < 2; ++bj) { *(f32x4*)(pp + bj * HALF) = acc[ai][bj][m][0]; *(f32x4*)(pp + bj * HALF + 4) = acc[ai][bj][m][1]; }
;                 }
.LBB0_159:
	s_cmp_gt_i32 s34, 25
	s_cselect_b64 s[4:5], -1, 0
	s_cmp_lt_i32 s34, 26
	s_cselect_b64 s[8:9], -1, 0
	s_cmp_gt_i32 s12, -1
	v_lshl_add_u32 v156, s26, 8, v1
	s_cselect_b64 s[40:41], -1, 0
	s_mov_b64 s[42:43], -1
	s_and_b64 vcc, exec, s[40:41]
	v_ashrrev_i32_e32 v157, 31, v156
	v_lshlrev_b32_e32 v2, 2, v144
	s_cbranch_vccz .LBB0_161
	s_ashr_i32 s35, s34, 31
	s_lshl_b64 s[42:43], s[34:35], 18
	s_lshl_b64 s[80:81], s[12:13], 22
	s_add_u32 s35, s66, s42
	s_addc_u32 s43, s67, s43
	s_add_u32 s42, s35, s80
	v_lshlrev_b64 v[52:53], 10, v[156:157]
	s_addc_u32 s43, s43, s81
	v_lshl_add_u64 v[52:53], s[42:43], 0, v[52:53]
	s_lshl_b32 s42, s71, 2
	s_mov_b32 s43, s13
	v_lshl_add_u64 v[52:53], v[52:53], 0, s[42:43]
	s_mov_b32 s42, 0xfe7c0000
	v_lshl_add_u64 v[52:53], v[52:53], 0, v[2:3]
	s_mov_b32 s43, -1
	v_lshl_add_u64 v[54:55], v[52:53], 0, s[42:43]
	v_add_co_u32_e32 v52, vcc, 0xfe7c0000, v52
	s_mov_b64 s[42:43], 0
	s_nop 0
	v_addc_co_u32_e32 v53, vcc, -1, v53, vcc
	global_store_dwordx4 v[52:53], v[132:135], off
	global_store_dwordx4 v[54:55], v[128:131], off offset:16
	global_store_dwordx4 v[54:55], v[124:127], off offset:512
	global_store_dwordx4 v[54:55], v[120:123], off offset:528
.LBB0_161:
	s_lshl_b32 s35, s78, 10
	s_and_b32 s35, s35, 0x400
	v_lshl_or_b32 v158, s34, 8, v165
	v_ashrrev_i32_e32 v159, 31, v158
	s_andn2_b64 vcc, exec, s[42:43]
	v_add_u32_e32 v167, s35, v164
	s_cbranch_vccnz .LBB0_170
	ds_read_b32 v162, v167
	v_mov_b64_e32 v[52:53], s[46:47]
	v_mad_i64_i32 v[52:53], s[42:43], v156, s31, v[52:53]
	v_lshl_add_u64 v[160:161], v[158:159], 1, v[52:53]
	s_waitcnt lgkmcnt(0)
	v_pk_mul_f32 v[134:135], v[134:135], v[162:163] op_sel_hi:[1,0]
	v_pk_mul_f32 v[132:133], v[132:133], v[162:163] op_sel_hi:[1,0]
	v_pk_mul_f32 v[130:131], v[130:131], v[162:163] op_sel_hi:[1,0]
	v_pk_mul_f32 v[128:129], v[128:129], v[162:163] op_sel_hi:[1,0]
	s_mov_b64 s[42:43], -1
	s_and_b64 vcc, exec, s[8:9]
	s_cbranch_vccz .LBB0_164
	v_cvt_pk_bf16_f32 v52, v132, v133
	v_cvt_pk_bf16_f32 v53, v134, v135
	v_cvt_pk_bf16_f32 v54, v128, v129
	v_cvt_pk_bf16_f32 v55, v130, v131
	global_store_dwordx4 v[160:161], v[52:55], off
	s_mov_b64 s[42:43], 0

; DI u32x2 packq8(const f32x4 v0, const f32x4 v1) { u32x2 w; w.x = pk4q8(v0); w.y = pk4q8(v1); return w; }
; DI u32x4 pack8(const f32x4 v0, const f32x4 v1) { u32x4 w; w.x = pk2(v0[0], v0[1]); w.y = pk2(v0[2], v0[3]); w.z = pk2(v1[0], v1[1]); w.w = pk2(v1[2], v1[3]); return w; }
;     DI void operator()(const f32x4 (&acc)[2][2][4][2], const Unit& u, int wr, int wc, int fr, int fq, const LAS float* rsl) const {
;     ...
;             for (int m = 0; m < 4; ++m) {
;                 const int row = row0 + ai * HALF + m * 16;
;                 if (u.ks < 0) {
;                     const float s = rsl[wr * 64 + fr + ai * HALF + m * 16];
;                     bf16_t* rowp = Z + (size_t)row * ZLD + col0;
;                     unsigned char* gq = GT + ((size_t)u.pm * 24 + (u.pn - 26)) * 65536 + (((((wr * 4 + wc) * 2 + ai) * 4 + m) * 64 + fq * 16 + fr) << 4);
;                     u32x4 gw;
; #pragma unroll
;                     for (int bj = 0; bj < 2; ++bj) {
;                         f32x4 v0 = acc[ai][bj][m][0] * s, v1 = acc[ai][bj][m][1] * s;
;                         if (gate) {
; #pragma unroll
;                             for (int j = 0; j < 4; ++j) { v0[j] = __builtin_amdgcn_rcpf(1.0f + __expf(-v0[j])); v1[j] = __builtin_amdgcn_rcpf(1.0f + __expf(-v1[j])); }
;                             const u32x2 w8 = packq8(v0, v1); if (bj == 0) { gw.x = w8.x; gw.y = w8.y; } else { gw.z = w8.x; gw.w = w8.y; }
;                         } else *(u32x4*)(rowp + bj * HALF) = pack8(v0, v1);
;                     }
;                     if (gate) *(u32x4*)gq = gw;
;                 } else {
;                     float* pp = part + (((size_t)u.ks * 16 + (u.pn - 26)) * 256 + (row - 71 * BM)) * 256 + wc * 32 + 8 * fq;
; #pragma unroll
;                     for (int bj = 0; bj < 2; ++bj) { *(f32x4*)(pp + bj * HALF) = acc[ai][bj][m][0]; *(f32x4*)(pp + bj * HALF + 4) = acc[ai][bj][m][1]; }
;                 }
.LBB0_169:
	s_sub_i32 s43, s34, 26
	s_mul_i32 s42, s26, 24
	s_ashr_i32 s53, s43, 31
	s_mul_hi_i32 s35, s26, 24
	s_add_u32 s42, s42, s43
	s_addc_u32 s43, s35, s53
	s_lshl_b64 s[42:43], s[42:43], 16
	v_lshl_add_u64 v[120:121], v[146:147], 0, s[42:43]
	global_store_dwordx4 v[120:121], v[52:55], off
.LBB0_170:
	v_cndmask_b32_e64 v120, 0, 1, s[40:41]
	v_cmp_ne_u32_e64 s[42:43], 1, v120
	s_andn2_b64 vcc, exec, s[40:41]
	s_mov_b64 s[40:41], -1
	s_cbranch_vccnz .LBB0_172
	s_ashr_i32 s35, s34, 31
	s_lshl_b64 s[40:41], s[34:35], 18
	s_lshl_b64 s[78:79], s[12:13], 22
	s_add_u32 s35, s66, s40
	s_addc_u32 s41, s67, s41
	s_add_u32 s40, s35, s78
	v_lshlrev_b64 v[120:121], 10, v[156:157]
	s_addc_u32 s41, s41, s79
	v_lshl_add_u64 v[120:121], s[40:41], 0, v[120:121]
	s_lshl_b32 s40, s71, 2
	s_mov_b32 s41, s13
	v_lshl_add_u64 v[120:121], v[120:121], 0, s[40:41]
	s_mov_b32 s40, 0xfe7c4000
	v_lshl_add_u64 v[120:121], v[120:121], 0, v[2:3]
	s_mov_b32 s41, -1
	v_lshl_add_u64 v[122:123], v[120:121], 0, s[40:41]
	v_add_co_u32_e32 v120, vcc, 0xfe7c4000, v120
	s_mov_b64 s[40:41], 0
	s_nop 0
	v_addc_co_u32_e32 v121, vcc, -1, v121, vcc
	global_store_dwordx4 v[120:121], v[116:119], off
	global_store_dwordx4 v[122:123], v[112:115], off offset:16
	global_store_dwordx4 v[122:123], v[108:111], off offset:512
	global_store_dwordx4 v[122:123], v[104:107], off offset:528
.LBB0_172:
	v_cndmask_b32_e64 v120, 0, 1, s[8:9]
	s_andn2_b64 vcc, exec, s[40:41]
	v_cmp_ne_u32_e64 s[40:41], 1, v120
	s_cbranch_vccnz .LBB0_181
	ds_read_b32 v122, v167 offset:64
	v_or_b32_e32 v123, 16, v156
	v_mov_b64_e32 v[120:121], s[46:47]
	v_mad_i64_i32 v[120:121], s[8:9], v123, s31, v[120:121]
	v_lshl_add_u64 v[120:121], v[158:159], 1, v[120:121]
	s_waitcnt lgkmcnt(0)
	v_pk_mul_f32 v[118:119], v[118:119], v[122:123] op_sel_hi:[1,0]
	v_pk_mul_f32 v[116:117], v[116:117], v[122:123] op_sel_hi:[1,0]
	v_pk_mul_f32 v[114:115], v[114:115], v[122:123] op_sel_hi:[1,0]
	v_pk_mul_f32 v[112:113], v[112:113], v[122:123] op_sel_hi:[1,0]
	s_and_b64 vcc, exec, s[40:41]
	s_mov_b64 s[8:9], -1
	s_cbranch_vccnz .LBB0_175
	v_cvt_pk_bf16_f32 v124, v116, v117
	v_cvt_pk_bf16_f32 v125, v118, v119
	v_cvt_pk_bf16_f32 v126, v112, v113
	v_cvt_pk_bf16_f32 v127, v114, v115
	s_mov_b64 s[8:9], 0
	global_store_dwordx4 v[120:121], v[124:127], off

; DI u32x2 packq8(const f32x4 v0, const f32x4 v1) { u32x2 w; w.x = pk4q8(v0); w.y = pk4q8(v1); return w; }
; DI u32x4 pack8(const f32x4 v0, const f32x4 v1) { u32x4 w; w.x = pk2(v0[0], v0[1]); w.y = pk2(v0[2], v0[3]); w.z = pk2(v1[0], v1[1]); w.w = pk2(v1[2], v1[3]); return w; }
;     DI void operator()(const f32x4 (&acc)[2][2][4][2], const Unit& u, int wr, int wc, int fr, int fq, const LAS float* rsl) const {
;     ...
;             for (int m = 0; m < 4; ++m) {
;                 const int row = row0 + ai * HALF + m * 16;
;                 if (u.ks < 0) {
;                     const float s = rsl[wr * 64 + fr + ai * HALF + m * 16];
;                     bf16_t* rowp = Z + (size_t)row * ZLD + col0;
;                     unsigned char* gq = GT + ((size_t)u.pm * 24 + (u.pn - 26)) * 65536 + (((((wr * 4 + wc) * 2 + ai) * 4 + m) * 64 + fq * 16 + fr) << 4);
;                     u32x4 gw;
; #pragma unroll
;                     for (int bj = 0; bj < 2; ++bj) {
;                         f32x4 v0 = acc[ai][bj][m][0] * s, v1 = acc[ai][bj][m][1] * s;
;                         if (gate) {
; #pragma unroll
;                             for (int j = 0; j < 4; ++j) { v0[j] = __builtin_amdgcn_rcpf(1.0f + __expf(-v0[j])); v1[j] = __builtin_amdgcn_rcpf(1.0f + __expf(-v1[j])); }
;                             const u32x2 w8 = packq8(v0, v1); if (bj == 0) { gw.x = w8.x; gw.y = w8.y; } else { gw.z = w8.x; gw.w = w8.y; }
;                         } else *(u32x4*)(rowp + bj * HALF) = pack8(v0, v1);
;                     }
;                     if (gate) *(u32x4*)gq = gw;
;                 } else {
;                     float* pp = part + (((size_t)u.ks * 16 + (u.pn - 26)) * 256 + (row - 71 * BM)) * 256 + wc * 32 + 8 * fq;
; #pragma unroll
;                     for (int bj = 0; bj < 2; ++bj) { *(f32x4*)(pp + bj * HALF) = acc[ai][bj][m][0]; *(f32x4*)(pp + bj * HALF + 4) = acc[ai][bj][m][1]; }
;                 }
.LBB0_180:
	s_sub_i32 s35, s34, 26
	s_mul_i32 s8, s26, 24
	s_ashr_i32 s53, s35, 31
	s_mul_hi_i32 s9, s26, 24
	s_add_u32 s8, s8, s35
	s_addc_u32 s9, s9, s53
	s_lshl_b64 s[8:9], s[8:9], 16
	v_lshl_add_u64 v[104:105], v[146:147], 0, s[8:9]
	global_store_dwordx4 v[104:105], v[52:55], off offset:1024
.LBB0_181:
	s_and_b64 vcc, exec, s[42:43]
	s_mov_b64 s[8:9], -1
	s_cbranch_vccnz .LBB0_183
	s_ashr_i32 s35, s34, 31
	s_lshl_b64 s[8:9], s[34:35], 18
	s_lshl_b64 s[78:79], s[12:13], 22
	s_add_u32 s8, s66, s8
	s_addc_u32 s9, s67, s9
	s_add_u32 s8, s8, s78
	v_lshlrev_b64 v[104:105], 10, v[156:157]
	s_addc_u32 s9, s9, s79
	v_lshl_add_u64 v[104:105], s[8:9], 0, v[104:105]
	s_lshl_b32 s8, s71, 2
	s_mov_b32 s9, s13
	v_lshl_add_u64 v[104:105], v[104:105], 0, s[8:9]
	s_mov_b32 s8, 0xfe7c8000
	v_lshl_add_u64 v[104:105], v[104:105], 0, v[2:3]
	s_mov_b32 s9, -1
	v_lshl_add_u64 v[106:107], v[104:105], 0, s[8:9]
	v_add_co_u32_e32 v104, vcc, 0xfe7c8000, v104
	s_mov_b64 s[8:9], 0
	s_nop 0
	v_addc_co_u32_e32 v105, vcc, -1, v105, vcc
	global_store_dwordx4 v[104:105], v[100:103], off
	global_store_dwordx4 v[106:107], v[96:99], off offset:16
	global_store_dwordx4 v[106:107], v[92:95], off offset:512
	global_store_dwordx4 v[106:107], v[88:91], off offset:528
.LBB0_183:
	s_andn2_b64 vcc, exec, s[8:9]
	s_cbranch_vccnz .LBB0_192
	ds_read_b32 v106, v167 offset:128
	v_or_b32_e32 v107, 32, v156
	v_mov_b64_e32 v[104:105], s[46:47]
	v_mad_i64_i32 v[104:105], s[8:9], v107, s31, v[104:105]
	v_lshl_add_u64 v[104:105], v[158:159], 1, v[104:105]
	s_waitcnt lgkmcnt(0)
	v_pk_mul_f32 v[102:103], v[102:103], v[106:107] op_sel_hi:[1,0]
	v_pk_mul_f32 v[100:101], v[100:101], v[106:107] op_sel_hi:[1,0]
	v_pk_mul_f32 v[98:99], v[98:99], v[106:107] op_sel_hi:[1,0]
	v_pk_mul_f32 v[96:97], v[96:97], v[106:107] op_sel_hi:[1,0]
	s_and_b64 vcc, exec, s[40:41]
	s_mov_b64 s[8:9], -1
	s_cbranch_vccnz .LBB0_186
	v_cvt_pk_bf16_f32 v108, v100, v101
	v_cvt_pk_bf16_f32 v109, v102, v103
	v_cvt_pk_bf16_f32 v110, v96, v97
	v_cvt_pk_bf16_f32 v111, v98, v99
	s_mov_b64 s[8:9], 0
	global_store_dwordx4 v[104:105], v[108:111], off

; DI u32x2 packq8(const f32x4 v0, const f32x4 v1) { u32x2 w; w.x = pk4q8(v0); w.y = pk4q8(v1); return w; }
; DI u32x4 pack8(const f32x4 v0, const f32x4 v1) { u32x4 w; w.x = pk2(v0[0], v0[1]); w.y = pk2(v0[2], v0[3]); w.z = pk2(v1[0], v1[1]); w.w = pk2(v1[2], v1[3]); return w; }
;     DI void operator()(const f32x4 (&acc)[2][2][4][2], const Unit& u, int wr, int wc, int fr, int fq, const LAS float* rsl) const {
;     ...
;             for (int m = 0; m < 4; ++m) {
;                 const int row = row0 + ai * HALF + m * 16;
;                 if (u.ks < 0) {
;                     const float s = rsl[wr * 64 + fr + ai * HALF + m * 16];
;                     bf16_t* rowp = Z + (size_t)row * ZLD + col0;
;                     unsigned char* gq = GT + ((size_t)u.pm * 24 + (u.pn - 26)) * 65536 + (((((wr * 4 + wc) * 2 + ai) * 4 + m) * 64 + fq * 16 + fr) << 4);
;                     u32x4 gw;
; #pragma unroll
;                     for (int bj = 0; bj < 2; ++bj) {
;                         f32x4 v0 = acc[ai][bj][m][0] * s, v1 = acc[ai][bj][m][1] * s;
;                         if (gate) {
; #pragma unroll
;                             for (int j = 0; j < 4; ++j) { v0[j] = __builtin_amdgcn_rcpf(1.0f + __expf(-v0[j])); v1[j] = __builtin_amdgcn_rcpf(1.0f + __expf(-v1[j])); }
;                             const u32x2 w8 = packq8(v0, v1); if (bj == 0) { gw.x = w8.x; gw.y = w8.y; } else { gw.z = w8.x; gw.w = w8.y; }
;                         } else *(u32x4*)(rowp + bj * HALF) = pack8(v0, v1);
;                     }
;                     if (gate) *(u32x4*)gq = gw;
;                 } else {
;                     float* pp = part + (((size_t)u.ks * 16 + (u.pn - 26)) * 256 + (row - 71 * BM)) * 256 + wc * 32 + 8 * fq;
; #pragma unroll
;                     for (int bj = 0; bj < 2; ++bj) { *(f32x4*)(pp + bj * HALF) = acc[ai][bj][m][0]; *(f32x4*)(pp + bj * HALF + 4) = acc[ai][bj][m][1]; }
;                 }
.LBB0_191:
	s_sub_i32 s35, s34, 26
	s_mul_i32 s8, s26, 24
	s_ashr_i32 s53, s35, 31
	s_mul_hi_i32 s9, s26, 24
	s_add_u32 s8, s8, s35
	s_addc_u32 s9, s9, s53
	s_lshl_b64 s[8:9], s[8:9], 16
	v_lshl_add_u64 v[88:89], v[146:147], 0, s[8:9]
	global_store_dwordx4 v[88:89], v[52:55], off offset:2048
.LBB0_192:
	s_and_b64 vcc, exec, s[42:43]
	s_mov_b64 s[8:9], -1
	s_cbranch_vccnz .LBB0_194
	s_ashr_i32 s35, s34, 31
	s_lshl_b64 s[8:9], s[34:35], 18
	s_lshl_b64 s[78:79], s[12:13], 22
	s_add_u32 s8, s66, s8
	s_addc_u32 s9, s67, s9
	s_add_u32 s8, s8, s78
	v_lshlrev_b64 v[88:89], 10, v[156:157]
	s_addc_u32 s9, s9, s79
	v_lshl_add_u64 v[88:89], s[8:9], 0, v[88:89]
	s_lshl_b32 s8, s71, 2
	s_mov_b32 s9, s13
	v_lshl_add_u64 v[88:89], v[88:89], 0, s[8:9]
	s_mov_b32 s8, 0xfe7cc000
	v_lshl_add_u64 v[88:89], v[88:89], 0, v[2:3]
	s_mov_b32 s9, -1
	v_lshl_add_u64 v[90:91], v[88:89], 0, s[8:9]
	v_add_co_u32_e32 v88, vcc, 0xfe7cc000, v88
	s_mov_b64 s[8:9], 0
	s_nop 0
	v_addc_co_u32_e32 v89, vcc, -1, v89, vcc
	global_store_dwordx4 v[88:89], v[84:87], off
	global_store_dwordx4 v[90:91], v[80:83], off offset:16
	global_store_dwordx4 v[90:91], v[76:79], off offset:512
	global_store_dwordx4 v[90:91], v[72:75], off offset:528
.LBB0_194:
	s_andn2_b64 vcc, exec, s[8:9]
	s_cbranch_vccnz .LBB0_203
	ds_read_b32 v90, v167 offset:192
	v_or_b32_e32 v91, 48, v156
	v_mov_b64_e32 v[88:89], s[46:47]
	v_mad_i64_i32 v[88:89], s[8:9], v91, s31, v[88:89]
	v_lshl_add_u64 v[88:89], v[158:159], 1, v[88:89]
	s_waitcnt lgkmcnt(0)
	v_pk_mul_f32 v[86:87], v[86:87], v[90:91] op_sel_hi:[1,0]
	v_pk_mul_f32 v[84:85], v[84:85], v[90:91] op_sel_hi:[1,0]
	v_pk_mul_f32 v[82:83], v[82:83], v[90:91] op_sel_hi:[1,0]
	v_pk_mul_f32 v[80:81], v[80:81], v[90:91] op_sel_hi:[1,0]
	s_and_b64 vcc, exec, s[40:41]
	s_mov_b64 s[8:9], -1
	s_cbranch_vccnz .LBB0_197
	v_cvt_pk_bf16_f32 v92, v84, v85
	v_cvt_pk_bf16_f32 v93, v86, v87
	v_cvt_pk_bf16_f32 v94, v80, v81
	v_cvt_pk_bf16_f32 v95, v82, v83
	s_mov_b64 s[8:9], 0
	global_store_dwordx4 v[88:89], v[92:95], off

; DI u32x2 packq8(const f32x4 v0, const f32x4 v1) { u32x2 w; w.x = pk4q8(v0); w.y = pk4q8(v1); return w; }
; DI u32x4 pack8(const f32x4 v0, const f32x4 v1) { u32x4 w; w.x = pk2(v0[0], v0[1]); w.y = pk2(v0[2], v0[3]); w.z = pk2(v1[0], v1[1]); w.w = pk2(v1[2], v1[3]); return w; }
;     DI void operator()(const f32x4 (&acc)[2][2][4][2], const Unit& u, int wr, int wc, int fr, int fq, const LAS float* rsl) const {
;     ...
;             for (int m = 0; m < 4; ++m) {
;                 const int row = row0 + ai * HALF + m * 16;
;                 if (u.ks < 0) {
;                     const float s = rsl[wr * 64 + fr + ai * HALF + m * 16];
;                     bf16_t* rowp = Z + (size_t)row * ZLD + col0;
;                     unsigned char* gq = GT + ((size_t)u.pm * 24 + (u.pn - 26)) * 65536 + (((((wr * 4 + wc) * 2 + ai) * 4 + m) * 64 + fq * 16 + fr) << 4);
;                     u32x4 gw;
; #pragma unroll
;                     for (int bj = 0; bj < 2; ++bj) {
;                         f32x4 v0 = acc[ai][bj][m][0] * s, v1 = acc[ai][bj][m][1] * s;
;                         if (gate) {
; #pragma unroll
;                             for (int j = 0; j < 4; ++j) { v0[j] = __builtin_amdgcn_rcpf(1.0f + __expf(-v0[j])); v1[j] = __builtin_amdgcn_rcpf(1.0f + __expf(-v1[j])); }
;                             const u32x2 w8 = packq8(v0, v1); if (bj == 0) { gw.x = w8.x; gw.y = w8.y; } else { gw.z = w8.x; gw.w = w8.y; }
;                         } else *(u32x4*)(rowp + bj * HALF) = pack8(v0, v1);
;                     }
;                     if (gate) *(u32x4*)gq = gw;
;                 } else {
;                     float* pp = part + (((size_t)u.ks * 16 + (u.pn - 26)) * 256 + (row - 71 * BM)) * 256 + wc * 32 + 8 * fq;
; #pragma unroll
;                     for (int bj = 0; bj < 2; ++bj) { *(f32x4*)(pp + bj * HALF) = acc[ai][bj][m][0]; *(f32x4*)(pp + bj * HALF + 4) = acc[ai][bj][m][1]; }
;                 }
.LBB0_202:
	s_sub_i32 s35, s34, 26
	s_mul_i32 s8, s26, 24
	s_ashr_i32 s53, s35, 31
	s_mul_hi_i32 s9, s26, 24
	s_add_u32 s8, s8, s35
	s_addc_u32 s9, s9, s53
	s_lshl_b64 s[8:9], s[8:9], 16
	v_lshl_add_u64 v[72:73], v[146:147], 0, s[8:9]
	global_store_dwordx4 v[72:73], v[52:55], off offset:3072
.LBB0_203:
	s_and_b64 vcc, exec, s[42:43]
	s_mov_b64 s[8:9], -1
	s_cbranch_vccnz .LBB0_205
	s_ashr_i32 s35, s34, 31
	s_lshl_b64 s[8:9], s[34:35], 18
	s_lshl_b64 s[78:79], s[12:13], 22
	s_add_u32 s8, s66, s8
	s_addc_u32 s9, s67, s9
	s_add_u32 s8, s8, s78
	v_lshlrev_b64 v[72:73], 10, v[156:157]
	s_addc_u32 s9, s9, s79
	v_lshl_add_u64 v[72:73], s[8:9], 0, v[72:73]
	s_lshl_b32 s8, s71, 2
	s_mov_b32 s9, s13
	v_lshl_add_u64 v[72:73], v[72:73], 0, s[8:9]
	s_mov_b32 s8, 0xfe7e0000
	v_lshl_add_u64 v[72:73], v[72:73], 0, v[2:3]
	s_mov_b32 s9, -1
	v_lshl_add_u64 v[74:75], v[72:73], 0, s[8:9]
	v_add_co_u32_e32 v72, vcc, 0xfe7e0000, v72
	s_mov_b64 s[8:9], 0
	s_nop 0
	v_addc_co_u32_e32 v73, vcc, -1, v73, vcc
	global_store_dwordx4 v[72:73], v[68:71], off
	global_store_dwordx4 v[74:75], v[64:67], off offset:16
	global_store_dwordx4 v[74:75], v[60:63], off offset:512
	global_store_dwordx4 v[74:75], v[56:59], off offset:528
.LBB0_205:
	s_andn2_b64 vcc, exec, s[8:9]
	s_cbranch_vccnz .LBB0_214
	ds_read_b32 v74, v167 offset:512
	v_add_u32_e32 v75, 0x80, v156
	v_mov_b64_e32 v[72:73], s[46:47]
	v_mad_i64_i32 v[72:73], s[8:9], v75, s31, v[72:73]
	v_lshl_add_u64 v[72:73], v[158:159], 1, v[72:73]
	s_waitcnt lgkmcnt(0)
	v_pk_mul_f32 v[70:71], v[70:71], v[74:75] op_sel_hi:[1,0]
	v_pk_mul_f32 v[68:69], v[68:69], v[74:75] op_sel_hi:[1,0]
	v_pk_mul_f32 v[66:67], v[66:67], v[74:75] op_sel_hi:[1,0]
	v_pk_mul_f32 v[64:65], v[64:65], v[74:75] op_sel_hi:[1,0]
	s_and_b64 vcc, exec, s[40:41]
	s_mov_b64 s[8:9], -1
	s_cbranch_vccnz .LBB0_208
	v_cvt_pk_bf16_f32 v76, v68, v69
	v_cvt_pk_bf16_f32 v77, v70, v71
	v_cvt_pk_bf16_f32 v78, v64, v65
	v_cvt_pk_bf16_f32 v79, v66, v67
	s_mov_b64 s[8:9], 0
	global_store_dwordx4 v[72:73], v[76:79], off

; DI u32x2 packq8(const f32x4 v0, const f32x4 v1) { u32x2 w; w.x = pk4q8(v0); w.y = pk4q8(v1); return w; }
; DI u32x4 pack8(const f32x4 v0, const f32x4 v1) { u32x4 w; w.x = pk2(v0[0], v0[1]); w.y = pk2(v0[2], v0[3]); w.z = pk2(v1[0], v1[1]); w.w = pk2(v1[2], v1[3]); return w; }
;     DI void operator()(const f32x4 (&acc)[2][2][4][2], const Unit& u, int wr, int wc, int fr, int fq, const LAS float* rsl) const {
;     ...
;             for (int m = 0; m < 4; ++m) {
;                 const int row = row0 + ai * HALF + m * 16;
;                 if (u.ks < 0) {
;                     const float s = rsl[wr * 64 + fr + ai * HALF + m * 16];
;                     bf16_t* rowp = Z + (size_t)row * ZLD + col0;
;                     unsigned char* gq = GT + ((size_t)u.pm * 24 + (u.pn - 26)) * 65536 + (((((wr * 4 + wc) * 2 + ai) * 4 + m) * 64 + fq * 16 + fr) << 4);
;                     u32x4 gw;
; #pragma unroll
;                     for (int bj = 0; bj < 2; ++bj) {
;                         f32x4 v0 = acc[ai][bj][m][0] * s, v1 = acc[ai][bj][m][1] * s;
;                         if (gate) {
; #pragma unroll
;                             for (int j = 0; j < 4; ++j) { v0[j] = __builtin_amdgcn_rcpf(1.0f + __expf(-v0[j])); v1[j] = __builtin_amdgcn_rcpf(1.0f + __expf(-v1[j])); }
;                             const u32x2 w8 = packq8(v0, v1); if (bj == 0) { gw.x = w8.x; gw.y = w8.y; } else { gw.z = w8.x; gw.w = w8.y; }
;                         } else *(u32x4*)(rowp + bj * HALF) = pack8(v0, v1);
;                     }
;                     if (gate) *(u32x4*)gq = gw;
;                 } else {
;                     float* pp = part + (((size_t)u.ks * 16 + (u.pn - 26)) * 256 + (row - 71 * BM)) * 256 + wc * 32 + 8 * fq;
; #pragma unroll
;                     for (int bj = 0; bj < 2; ++bj) { *(f32x4*)(pp + bj * HALF) = acc[ai][bj][m][0]; *(f32x4*)(pp + bj * HALF + 4) = acc[ai][bj][m][1]; }
;                 }
.LBB0_213:
	s_sub_i32 s35, s34, 26
	s_mul_i32 s8, s26, 24
	s_ashr_i32 s53, s35, 31
	s_mul_hi_i32 s9, s26, 24
	s_add_u32 s8, s8, s35
	s_addc_u32 s9, s9, s53
	s_lshl_b64 s[8:9], s[8:9], 16
	v_lshl_add_u64 v[56:57], v[148:149], 0, s[8:9]
	global_store_dwordx4 v[56:57], v[52:55], off
.LBB0_214:
	s_and_b64 vcc, exec, s[42:43]
	s_mov_b64 s[8:9], -1
	s_cbranch_vccnz .LBB0_216
	s_ashr_i32 s35, s34, 31
	s_lshl_b64 s[8:9], s[34:35], 18
	s_lshl_b64 s[78:79], s[12:13], 22
	s_add_u32 s8, s66, s8
	s_addc_u32 s9, s67, s9
	s_add_u32 s8, s8, s78
	v_lshlrev_b64 v[56:57], 10, v[156:157]
	s_addc_u32 s9, s9, s79
	v_lshl_add_u64 v[56:57], s[8:9], 0, v[56:57]
	s_lshl_b32 s8, s71, 2
	s_mov_b32 s9, s13
	v_lshl_add_u64 v[56:57], v[56:57], 0, s[8:9]
	s_mov_b32 s8, 0xfe7e4000
	v_lshl_add_u64 v[56:57], v[56:57], 0, v[2:3]
	s_mov_b32 s9, -1
	v_lshl_add_u64 v[58:59], v[56:57], 0, s[8:9]
	v_add_co_u32_e32 v56, vcc, 0xfe7e4000, v56
	s_mov_b64 s[8:9], 0
	s_nop 0
	v_addc_co_u32_e32 v57, vcc, -1, v57, vcc
	global_store_dwordx4 v[56:57], v[48:51], off
	global_store_dwordx4 v[58:59], v[44:47], off offset:16
	global_store_dwordx4 v[58:59], v[40:43], off offset:512
	global_store_dwordx4 v[58:59], v[36:39], off offset:528
.LBB0_216:
	s_andn2_b64 vcc, exec, s[8:9]
	s_cbranch_vccnz .LBB0_225
	ds_read_b32 v58, v167 offset:576
	v_add_u32_e32 v59, 0x90, v156
	v_mov_b64_e32 v[56:57], s[46:47]
	v_mad_i64_i32 v[56:57], s[8:9], v59, s31, v[56:57]
	v_lshl_add_u64 v[56:57], v[158:159], 1, v[56:57]
	s_waitcnt lgkmcnt(0)
	v_pk_mul_f32 v[50:51], v[50:51], v[58:59] op_sel_hi:[1,0]
	v_pk_mul_f32 v[48:49], v[48:49], v[58:59] op_sel_hi:[1,0]
	v_pk_mul_f32 v[46:47], v[46:47], v[58:59] op_sel_hi:[1,0]
	v_pk_mul_f32 v[44:45], v[44:45], v[58:59] op_sel_hi:[1,0]
	s_and_b64 vcc, exec, s[40:41]
	s_mov_b64 s[8:9], -1
	s_cbranch_vccnz .LBB0_219
	v_cvt_pk_bf16_f32 v60, v48, v49
	v_cvt_pk_bf16_f32 v61, v50, v51
	v_cvt_pk_bf16_f32 v62, v44, v45
	v_cvt_pk_bf16_f32 v63, v46, v47
	s_mov_b64 s[8:9], 0
	global_store_dwordx4 v[56:57], v[60:63], off

; DI u32x2 packq8(const f32x4 v0, const f32x4 v1) { u32x2 w; w.x = pk4q8(v0); w.y = pk4q8(v1); return w; }
; DI u32x4 pack8(const f32x4 v0, const f32x4 v1) { u32x4 w; w.x = pk2(v0[0], v0[1]); w.y = pk2(v0[2], v0[3]); w.z = pk2(v1[0], v1[1]); w.w = pk2(v1[2], v1[3]); return w; }
;     DI void operator()(const f32x4 (&acc)[2][2][4][2], const Unit& u, int wr, int wc, int fr, int fq, const LAS float* rsl) const {
;     ...
;             for (int m = 0; m < 4; ++m) {
;                 const int row = row0 + ai * HALF + m * 16;
;                 if (u.ks < 0) {
;                     const float s = rsl[wr * 64 + fr + ai * HALF + m * 16];
;                     bf16_t* rowp = Z + (size_t)row * ZLD + col0;
;                     unsigned char* gq = GT + ((size_t)u.pm * 24 + (u.pn - 26)) * 65536 + (((((wr * 4 + wc) * 2 + ai) * 4 + m) * 64 + fq * 16 + fr) << 4);
;                     u32x4 gw;
; #pragma unroll
;                     for (int bj = 0; bj < 2; ++bj) {
;                         f32x4 v0 = acc[ai][bj][m][0] * s, v1 = acc[ai][bj][m][1] * s;
;                         if (gate) {
; #pragma unroll
;                             for (int j = 0; j < 4; ++j) { v0[j] = __builtin_amdgcn_rcpf(1.0f + __expf(-v0[j])); v1[j] = __builtin_amdgcn_rcpf(1.0f + __expf(-v1[j])); }
;                             const u32x2 w8 = packq8(v0, v1); if (bj == 0) { gw.x = w8.x; gw.y = w8.y; } else { gw.z = w8.x; gw.w = w8.y; }
;                         } else *(u32x4*)(rowp + bj * HALF) = pack8(v0, v1);
;                     }
;                     if (gate) *(u32x4*)gq = gw;
;                 } else {
;                     float* pp = part + (((size_t)u.ks * 16 + (u.pn - 26)) * 256 + (row - 71 * BM)) * 256 + wc * 32 + 8 * fq;
; #pragma unroll
;                     for (int bj = 0; bj < 2; ++bj) { *(f32x4*)(pp + bj * HALF) = acc[ai][bj][m][0]; *(f32x4*)(pp + bj * HALF + 4) = acc[ai][bj][m][1]; }
;                 }
.LBB0_224:
	s_sub_i32 s35, s34, 26
	s_mul_i32 s8, s26, 24
	s_ashr_i32 s53, s35, 31
	s_mul_hi_i32 s9, s26, 24
	s_add_u32 s8, s8, s35
	s_addc_u32 s9, s9, s53
	s_lshl_b64 s[8:9], s[8:9], 16
	v_lshl_add_u64 v[36:37], v[148:149], 0, s[8:9]
	global_store_dwordx4 v[36:37], v[52:55], off offset:1024
.LBB0_225:
	s_and_b64 vcc, exec, s[42:43]
	s_mov_b64 s[8:9], -1
	s_cbranch_vccnz .LBB0_227
	s_ashr_i32 s35, s34, 31
	s_lshl_b64 s[8:9], s[34:35], 18
	s_lshl_b64 s[78:79], s[12:13], 22
	s_add_u32 s8, s66, s8
	s_addc_u32 s9, s67, s9
	s_add_u32 s8, s8, s78
	v_lshlrev_b64 v[36:37], 10, v[156:157]
	s_addc_u32 s9, s9, s79
	v_lshl_add_u64 v[36:37], s[8:9], 0, v[36:37]
	s_lshl_b32 s8, s71, 2
	s_mov_b32 s9, s13
	v_lshl_add_u64 v[36:37], v[36:37], 0, s[8:9]
	s_mov_b32 s8, 0xfe7e8000
	v_lshl_add_u64 v[36:37], v[36:37], 0, v[2:3]
	s_mov_b32 s9, -1
	v_lshl_add_u64 v[38:39], v[36:37], 0, s[8:9]
	v_add_co_u32_e32 v36, vcc, 0xfe7e8000, v36
	s_mov_b64 s[8:9], 0
	s_nop 0
	v_addc_co_u32_e32 v37, vcc, -1, v37, vcc
	global_store_dwordx4 v[36:37], v[32:35], off
	global_store_dwordx4 v[38:39], v[28:31], off offset:16
	global_store_dwordx4 v[38:39], v[24:27], off offset:512
	global_store_dwordx4 v[38:39], v[20:23], off offset:528
.LBB0_227:
	s_andn2_b64 vcc, exec, s[8:9]
	s_cbranch_vccnz .LBB0_236
	ds_read_b32 v38, v167 offset:640
	v_add_u32_e32 v39, 0xa0, v156
	v_mov_b64_e32 v[36:37], s[46:47]
	v_mad_i64_i32 v[36:37], s[8:9], v39, s31, v[36:37]
	v_lshl_add_u64 v[36:37], v[158:159], 1, v[36:37]
	s_waitcnt lgkmcnt(0)
	v_pk_mul_f32 v[34:35], v[34:35], v[38:39] op_sel_hi:[1,0]
	v_pk_mul_f32 v[32:33], v[32:33], v[38:39] op_sel_hi:[1,0]
	v_pk_mul_f32 v[30:31], v[30:31], v[38:39] op_sel_hi:[1,0]
	v_pk_mul_f32 v[28:29], v[28:29], v[38:39] op_sel_hi:[1,0]
	s_and_b64 vcc, exec, s[40:41]
	s_mov_b64 s[8:9], -1
	s_cbranch_vccnz .LBB0_230
	v_cvt_pk_bf16_f32 v40, v32, v33
	v_cvt_pk_bf16_f32 v41, v34, v35
	v_cvt_pk_bf16_f32 v42, v28, v29
	v_cvt_pk_bf16_f32 v43, v30, v31
	s_mov_b64 s[8:9], 0
	global_store_dwordx4 v[36:37], v[40:43], off

; DI u32x2 packq8(const f32x4 v0, const f32x4 v1) { u32x2 w; w.x = pk4q8(v0); w.y = pk4q8(v1); return w; }
; DI u32x4 pack8(const f32x4 v0, const f32x4 v1) { u32x4 w; w.x = pk2(v0[0], v0[1]); w.y = pk2(v0[2], v0[3]); w.z = pk2(v1[0], v1[1]); w.w = pk2(v1[2], v1[3]); return w; }
;     DI void operator()(const f32x4 (&acc)[2][2][4][2], const Unit& u, int wr, int wc, int fr, int fq, const LAS float* rsl) const {
;     ...
;             for (int m = 0; m < 4; ++m) {
;                 const int row = row0 + ai * HALF + m * 16;
;                 if (u.ks < 0) {
;                     const float s = rsl[wr * 64 + fr + ai * HALF + m * 16];
;                     bf16_t* rowp = Z + (size_t)row * ZLD + col0;
;                     unsigned char* gq = GT + ((size_t)u.pm * 24 + (u.pn - 26)) * 65536 + (((((wr * 4 + wc) * 2 + ai) * 4 + m) * 64 + fq * 16 + fr) << 4);
;                     u32x4 gw;
; #pragma unroll
;                     for (int bj = 0; bj < 2; ++bj) {
;                         f32x4 v0 = acc[ai][bj][m][0] * s, v1 = acc[ai][bj][m][1] * s;
;                         if (gate) {
; #pragma unroll
;                             for (int j = 0; j < 4; ++j) { v0[j] = __builtin_amdgcn_rcpf(1.0f + __expf(-v0[j])); v1[j] = __builtin_amdgcn_rcpf(1.0f + __expf(-v1[j])); }
;                             const u32x2 w8 = packq8(v0, v1); if (bj == 0) { gw.x = w8.x; gw.y = w8.y; } else { gw.z = w8.x; gw.w = w8.y; }
;                         } else *(u32x4*)(rowp + bj * HALF) = pack8(v0, v1);
;                     }
;                     if (gate) *(u32x4*)gq = gw;
;                 } else {
;                     float* pp = part + (((size_t)u.ks * 16 + (u.pn - 26)) * 256 + (row - 71 * BM)) * 256 + wc * 32 + 8 * fq;
; #pragma unroll
;                     for (int bj = 0; bj < 2; ++bj) { *(f32x4*)(pp + bj * HALF) = acc[ai][bj][m][0]; *(f32x4*)(pp + bj * HALF + 4) = acc[ai][bj][m][1]; }
;                 }
.LBB0_235:
	s_sub_i32 s35, s34, 26
	s_mul_i32 s8, s26, 24
	s_ashr_i32 s53, s35, 31
	s_mul_hi_i32 s9, s26, 24
	s_add_u32 s8, s8, s35
	s_addc_u32 s9, s9, s53
	s_lshl_b64 s[8:9], s[8:9], 16
	v_lshl_add_u64 v[20:21], v[148:149], 0, s[8:9]
	global_store_dwordx4 v[20:21], v[52:55], off offset:2048
.LBB0_236:
	s_and_b64 vcc, exec, s[42:43]
	s_mov_b64 s[8:9], -1
	s_cbranch_vccnz .LBB0_238
	s_ashr_i32 s35, s34, 31
	s_lshl_b64 s[8:9], s[34:35], 18
	s_lshl_b64 s[42:43], s[12:13], 22
	s_add_u32 s8, s66, s8
	s_addc_u32 s9, s67, s9
	s_add_u32 s8, s8, s42
	v_lshlrev_b64 v[20:21], 10, v[156:157]
	s_addc_u32 s9, s9, s43
	v_lshl_add_u64 v[20:21], s[8:9], 0, v[20:21]
	s_lshl_b32 s12, s71, 2
	v_lshl_add_u64 v[20:21], v[20:21], 0, s[12:13]
	s_mov_b32 s8, 0xfe7ec000
	v_lshl_add_u64 v[20:21], v[20:21], 0, v[2:3]
	s_mov_b32 s9, -1
	v_lshl_add_u64 v[22:23], v[20:21], 0, s[8:9]
	v_add_co_u32_e32 v20, vcc, 0xfe7ec000, v20
	s_mov_b64 s[8:9], 0
	s_nop 0
	v_addc_co_u32_e32 v21, vcc, -1, v21, vcc
	global_store_dwordx4 v[20:21], v[16:19], off
	global_store_dwordx4 v[22:23], v[12:15], off offset:16
	global_store_dwordx4 v[22:23], v[8:11], off offset:512
	global_store_dwordx4 v[22:23], v[4:7], off offset:528
.LBB0_238:
	s_andn2_b64 vcc, exec, s[8:9]
	s_cbranch_vccnz .LBB0_247
	ds_read_b32 v22, v167 offset:704
	v_add_u32_e32 v2, 0xb0, v156
	v_mov_b64_e32 v[20:21], s[46:47]
	v_mad_i64_i32 v[20:21], s[8:9], v2, s31, v[20:21]
	v_lshl_add_u64 v[20:21], v[158:159], 1, v[20:21]
	s_waitcnt lgkmcnt(0)
	v_pk_mul_f32 v[18:19], v[18:19], v[22:23] op_sel_hi:[1,0]
	v_pk_mul_f32 v[16:17], v[16:17], v[22:23] op_sel_hi:[1,0]
	v_pk_mul_f32 v[14:15], v[14:15], v[22:23] op_sel_hi:[1,0]
	v_pk_mul_f32 v[12:13], v[12:13], v[22:23] op_sel_hi:[1,0]
	s_and_b64 vcc, exec, s[40:41]
	s_mov_b64 s[8:9], -1
	s_cbranch_vccnz .LBB0_241
	v_cvt_pk_bf16_f32 v24, v16, v17
	v_cvt_pk_bf16_f32 v25, v18, v19
	v_cvt_pk_bf16_f32 v26, v12, v13
	v_cvt_pk_bf16_f32 v27, v14, v15
	s_mov_b64 s[8:9], 0
	global_store_dwordx4 v[20:21], v[24:27], off

; DI u32x2 packq8(const f32x4 v0, const f32x4 v1) { u32x2 w; w.x = pk4q8(v0); w.y = pk4q8(v1); return w; }
; DI u32x4 pack8(const f32x4 v0, const f32x4 v1) { u32x4 w; w.x = pk2(v0[0], v0[1]); w.y = pk2(v0[2], v0[3]); w.z = pk2(v1[0], v1[1]); w.w = pk2(v1[2], v1[3]); return w; }
;     DI void operator()(const f32x4 (&acc)[2][2][4][2], const Unit& u, int wr, int wc, int fr, int fq, const LAS float* rsl) const {
;     ...
;                             const u32x2 w8 = packq8(v0, v1); if (bj == 0) { gw.x = w8.x; gw.y = w8.y; } else { gw.z = w8.x; gw.w = w8.y; }
;                         } else *(u32x4*)(rowp + bj * HALF) = pack8(v0, v1);
;                     }
;                     if (gate) *(u32x4*)gq = gw;
.LBB0_246:
	s_sub_i32 s8, s34, 26
	s_mul_i32 s4, s26, 24
	s_ashr_i32 s9, s8, 31
	s_mul_hi_i32 s5, s26, 24
	s_add_u32 s4, s4, s8
	s_addc_u32 s5, s5, s9
	s_lshl_b64 s[4:5], s[4:5], 16
	v_lshl_add_u64 v[4:5], v[148:149], 0, s[4:5]
	global_store_dwordx4 v[4:5], v[52:55], off offset:3072

; DI u32x2 packq8(const f32x4 v0, const f32x4 v1) { u32x2 w; w.x = pk4q8(v0); w.y = pk4q8(v1); return w; }
; DI u32x4 pack8(const f32x4 v0, const f32x4 v1) { u32x4 w; w.x = pk2(v0[0], v0[1]); w.y = pk2(v0[2], v0[3]); w.z = pk2(v1[0], v1[1]); w.w = pk2(v1[2], v1[3]); return w; }
;     DI void operator()(const f32x4 (&acc)[2][2][4][2], const Unit& u, int wr, int wc, int fr, int fq, const LAS float* rsl) const {
;     ...
;                     for (int bj = 0; bj < 2; ++bj) {
;                         f32x4 v0 = acc[ai][bj][m][0] * s, v1 = acc[ai][bj][m][1] * s;
;                         if (gate) {
; #pragma unroll
;                             for (int j = 0; j < 4; ++j) { v0[j] = __builtin_amdgcn_rcpf(1.0f + __expf(-v0[j])); v1[j] = __builtin_amdgcn_rcpf(1.0f + __expf(-v1[j])); }
;                             const u32x2 w8 = packq8(v0, v1); if (bj == 0) { gw.x = w8.x; gw.y = w8.y; } else { gw.z = w8.x; gw.w = w8.y; }
;                         } else *(u32x4*)(rowp + bj * HALF) = pack8(v0, v1);
;                     }
.LBB0_252:
	v_cvt_pk_bf16_f32 v128, v124, v125
	v_cvt_pk_bf16_f32 v129, v126, v127
	v_cvt_pk_bf16_f32 v130, v120, v121
	v_cvt_pk_bf16_f32 v131, v122, v123
	global_store_dwordx4 v[160:161], v[128:131], off offset:256
	s_cbranch_execnz .LBB0_168

; DI u32x2 packq8(const f32x4 v0, const f32x4 v1) { u32x2 w; w.x = pk4q8(v0); w.y = pk4q8(v1); return w; }
; DI u32x4 pack8(const f32x4 v0, const f32x4 v1) { u32x4 w; w.x = pk2(v0[0], v0[1]); w.y = pk2(v0[2], v0[3]); w.z = pk2(v1[0], v1[1]); w.w = pk2(v1[2], v1[3]); return w; }
;     DI void operator()(const f32x4 (&acc)[2][2][4][2], const Unit& u, int wr, int wc, int fr, int fq, const LAS float* rsl) const {
;     ...
;                     for (int bj = 0; bj < 2; ++bj) {
;                         f32x4 v0 = acc[ai][bj][m][0] * s, v1 = acc[ai][bj][m][1] * s;
;                         if (gate) {
; #pragma unroll
;                             for (int j = 0; j < 4; ++j) { v0[j] = __builtin_amdgcn_rcpf(1.0f + __expf(-v0[j])); v1[j] = __builtin_amdgcn_rcpf(1.0f + __expf(-v1[j])); }
;                             const u32x2 w8 = packq8(v0, v1); if (bj == 0) { gw.x = w8.x; gw.y = w8.y; } else { gw.z = w8.x; gw.w = w8.y; }
;                         } else *(u32x4*)(rowp + bj * HALF) = pack8(v0, v1);
;                     }
.LBB0_254:
	v_cvt_pk_bf16_f32 v112, v108, v109
	v_cvt_pk_bf16_f32 v113, v110, v111
	v_cvt_pk_bf16_f32 v114, v104, v105
	v_cvt_pk_bf16_f32 v115, v106, v107
	global_store_dwordx4 v[120:121], v[112:115], off offset:256
	s_cbranch_execnz .LBB0_179

; DI u32x2 packq8(const f32x4 v0, const f32x4 v1) { u32x2 w; w.x = pk4q8(v0); w.y = pk4q8(v1); return w; }
; DI u32x4 pack8(const f32x4 v0, const f32x4 v1) { u32x4 w; w.x = pk2(v0[0], v0[1]); w.y = pk2(v0[2], v0[3]); w.z = pk2(v1[0], v1[1]); w.w = pk2(v1[2], v1[3]); return w; }
;     DI void operator()(const f32x4 (&acc)[2][2][4][2], const Unit& u, int wr, int wc, int fr, int fq, const LAS float* rsl) const {
;     ...
;                     for (int bj = 0; bj < 2; ++bj) {
;                         f32x4 v0 = acc[ai][bj][m][0] * s, v1 = acc[ai][bj][m][1] * s;
;                         if (gate) {
; #pragma unroll
;                             for (int j = 0; j < 4; ++j) { v0[j] = __builtin_amdgcn_rcpf(1.0f + __expf(-v0[j])); v1[j] = __builtin_amdgcn_rcpf(1.0f + __expf(-v1[j])); }
;                             const u32x2 w8 = packq8(v0, v1); if (bj == 0) { gw.x = w8.x; gw.y = w8.y; } else { gw.z = w8.x; gw.w = w8.y; }
;                         } else *(u32x4*)(rowp + bj * HALF) = pack8(v0, v1);
;                     }
.LBB0_256:
	v_cvt_pk_bf16_f32 v96, v92, v93
	v_cvt_pk_bf16_f32 v97, v94, v95
	v_cvt_pk_bf16_f32 v98, v88, v89
	v_cvt_pk_bf16_f32 v99, v90, v91
	global_store_dwordx4 v[104:105], v[96:99], off offset:256
	s_cbranch_execnz .LBB0_190

; DI u32x2 packq8(const f32x4 v0, const f32x4 v1) { u32x2 w; w.x = pk4q8(v0); w.y = pk4q8(v1); return w; }
; DI u32x4 pack8(const f32x4 v0, const f32x4 v1) { u32x4 w; w.x = pk2(v0[0], v0[1]); w.y = pk2(v0[2], v0[3]); w.z = pk2(v1[0], v1[1]); w.w = pk2(v1[2], v1[3]); return w; }
;     DI void operator()(const f32x4 (&acc)[2][2][4][2], const Unit& u, int wr, int wc, int fr, int fq, const LAS float* rsl) const {
;     ...
;                     for (int bj = 0; bj < 2; ++bj) {
;                         f32x4 v0 = acc[ai][bj][m][0] * s, v1 = acc[ai][bj][m][1] * s;
;                         if (gate) {
; #pragma unroll
;                             for (int j = 0; j < 4; ++j) { v0[j] = __builtin_amdgcn_rcpf(1.0f + __expf(-v0[j])); v1[j] = __builtin_amdgcn_rcpf(1.0f + __expf(-v1[j])); }
;                             const u32x2 w8 = packq8(v0, v1); if (bj == 0) { gw.x = w8.x; gw.y = w8.y; } else { gw.z = w8.x; gw.w = w8.y; }
;                         } else *(u32x4*)(rowp + bj * HALF) = pack8(v0, v1);
;                     }
.LBB0_258:
	v_cvt_pk_bf16_f32 v80, v76, v77
	v_cvt_pk_bf16_f32 v81, v78, v79
	v_cvt_pk_bf16_f32 v82, v72, v73
	v_cvt_pk_bf16_f32 v83, v74, v75
	global_store_dwordx4 v[88:89], v[80:83], off offset:256
	s_cbranch_execnz .LBB0_201

; DI u32x2 packq8(const f32x4 v0, const f32x4 v1) { u32x2 w; w.x = pk4q8(v0); w.y = pk4q8(v1); return w; }
; DI u32x4 pack8(const f32x4 v0, const f32x4 v1) { u32x4 w; w.x = pk2(v0[0], v0[1]); w.y = pk2(v0[2], v0[3]); w.z = pk2(v1[0], v1[1]); w.w = pk2(v1[2], v1[3]); return w; }
;     DI void operator()(const f32x4 (&acc)[2][2][4][2], const Unit& u, int wr, int wc, int fr, int fq, const LAS float* rsl) const {
;     ...
;                     for (int bj = 0; bj < 2; ++bj) {
;                         f32x4 v0 = acc[ai][bj][m][0] * s, v1 = acc[ai][bj][m][1] * s;
;                         if (gate) {
; #pragma unroll
;                             for (int j = 0; j < 4; ++j) { v0[j] = __builtin_amdgcn_rcpf(1.0f + __expf(-v0[j])); v1[j] = __builtin_amdgcn_rcpf(1.0f + __expf(-v1[j])); }
;                             const u32x2 w8 = packq8(v0, v1); if (bj == 0) { gw.x = w8.x; gw.y = w8.y; } else { gw.z = w8.x; gw.w = w8.y; }
;                         } else *(u32x4*)(rowp + bj * HALF) = pack8(v0, v1);
;                     }
.LBB0_260:
	v_cvt_pk_bf16_f32 v64, v60, v61
	v_cvt_pk_bf16_f32 v65, v62, v63
	v_cvt_pk_bf16_f32 v66, v56, v57
	v_cvt_pk_bf16_f32 v67, v58, v59
	global_store_dwordx4 v[72:73], v[64:67], off offset:256
	s_cbranch_execnz .LBB0_212

; DI u32x2 packq8(const f32x4 v0, const f32x4 v1) { u32x2 w; w.x = pk4q8(v0); w.y = pk4q8(v1); return w; }
; DI u32x4 pack8(const f32x4 v0, const f32x4 v1) { u32x4 w; w.x = pk2(v0[0], v0[1]); w.y = pk2(v0[2], v0[3]); w.z = pk2(v1[0], v1[1]); w.w = pk2(v1[2], v1[3]); return w; }
;     DI void operator()(const f32x4 (&acc)[2][2][4][2], const Unit& u, int wr, int wc, int fr, int fq, const LAS float* rsl) const {
;     ...
;                     for (int bj = 0; bj < 2; ++bj) {
;                         f32x4 v0 = acc[ai][bj][m][0] * s, v1 = acc[ai][bj][m][1] * s;
;                         if (gate) {
; #pragma unroll
;                             for (int j = 0; j < 4; ++j) { v0[j] = __builtin_amdgcn_rcpf(1.0f + __expf(-v0[j])); v1[j] = __builtin_amdgcn_rcpf(1.0f + __expf(-v1[j])); }
;                             const u32x2 w8 = packq8(v0, v1); if (bj == 0) { gw.x = w8.x; gw.y = w8.y; } else { gw.z = w8.x; gw.w = w8.y; }
;                         } else *(u32x4*)(rowp + bj * HALF) = pack8(v0, v1);
;                     }
.LBB0_262:
	v_cvt_pk_bf16_f32 v44, v40, v41
	v_cvt_pk_bf16_f32 v45, v42, v43
	v_cvt_pk_bf16_f32 v46, v36, v37
	v_cvt_pk_bf16_f32 v47, v38, v39
	global_store_dwordx4 v[56:57], v[44:47], off offset:256
	s_cbranch_execnz .LBB0_223

; DI u32x2 packq8(const f32x4 v0, const f32x4 v1) { u32x2 w; w.x = pk4q8(v0); w.y = pk4q8(v1); return w; }
; DI u32x4 pack8(const f32x4 v0, const f32x4 v1) { u32x4 w; w.x = pk2(v0[0], v0[1]); w.y = pk2(v0[2], v0[3]); w.z = pk2(v1[0], v1[1]); w.w = pk2(v1[2], v1[3]); return w; }
;     DI void operator()(const f32x4 (&acc)[2][2][4][2], const Unit& u, int wr, int wc, int fr, int fq, const LAS float* rsl) const {
;     ...
;                     for (int bj = 0; bj < 2; ++bj) {
;                         f32x4 v0 = acc[ai][bj][m][0] * s, v1 = acc[ai][bj][m][1] * s;
;                         if (gate) {
; #pragma unroll
;                             for (int j = 0; j < 4; ++j) { v0[j] = __builtin_amdgcn_rcpf(1.0f + __expf(-v0[j])); v1[j] = __builtin_amdgcn_rcpf(1.0f + __expf(-v1[j])); }
;                             const u32x2 w8 = packq8(v0, v1); if (bj == 0) { gw.x = w8.x; gw.y = w8.y; } else { gw.z = w8.x; gw.w = w8.y; }
;                         } else *(u32x4*)(rowp + bj * HALF) = pack8(v0, v1);
;                     }
.LBB0_264:
	v_cvt_pk_bf16_f32 v28, v24, v25
	v_cvt_pk_bf16_f32 v29, v26, v27
	v_cvt_pk_bf16_f32 v30, v20, v21
	v_cvt_pk_bf16_f32 v31, v22, v23
	global_store_dwordx4 v[36:37], v[28:31], off offset:256
	s_cbranch_execnz .LBB0_234

; DI u32x2 packq8(const f32x4 v0, const f32x4 v1) { u32x2 w; w.x = pk4q8(v0); w.y = pk4q8(v1); return w; }
; DI u32x4 pack8(const f32x4 v0, const f32x4 v1) { u32x4 w; w.x = pk2(v0[0], v0[1]); w.y = pk2(v0[2], v0[3]); w.z = pk2(v1[0], v1[1]); w.w = pk2(v1[2], v1[3]); return w; }
;     DI void operator()(const f32x4 (&acc)[2][2][4][2], const Unit& u, int wr, int wc, int fr, int fq, const LAS float* rsl) const {
;     ...
;                     for (int bj = 0; bj < 2; ++bj) {
;                         f32x4 v0 = acc[ai][bj][m][0] * s, v1 = acc[ai][bj][m][1] * s;
;                         if (gate) {
; #pragma unroll
;                             for (int j = 0; j < 4; ++j) { v0[j] = __builtin_amdgcn_rcpf(1.0f + __expf(-v0[j])); v1[j] = __builtin_amdgcn_rcpf(1.0f + __expf(-v1[j])); }
;                             const u32x2 w8 = packq8(v0, v1); if (bj == 0) { gw.x = w8.x; gw.y = w8.y; } else { gw.z = w8.x; gw.w = w8.y; }
;                         } else *(u32x4*)(rowp + bj * HALF) = pack8(v0, v1);
;                     }
.LBB0_266:
	v_cvt_pk_bf16_f32 v12, v8, v9
	v_cvt_pk_bf16_f32 v13, v10, v11
	v_cvt_pk_bf16_f32 v14, v4, v5
	v_cvt_pk_bf16_f32 v15, v6, v7
	global_store_dwordx4 v[20:21], v[12:15], off offset:256
	s_cbranch_execnz .LBB0_245

; DI unsigned pk2(float a, float b) { f32x2 v = {a, b}; bf16v2 r = __builtin_convertvector(v, bf16v2); return __builtin_bit_cast(unsigned, r); }
; DI void cvt_f32_bf16(const float* s, bf16_t* d, size_t n8, size_t gt, size_t NT) {
;     for (size_t i = gt; i < n8; i += NT) { const f32x4 a = ((const f32x4*)s)[2 * i], b = ((const f32x4*)s)[2 * i + 1]; u32x4 w; w.x = pk2(a[0], a[1]); w.y = pk2(a[2], a[3]); w.z = pk2(b[0], b[1]); w.w = pk2(b[2], b[3]); ((u32x4*)d)[i] = w; }
; }
.LBB0_272:
	global_load_dwordx4 v[14:17], v[10:11], off
	global_load_dwordx4 v[18:21], v[10:11], off offset:16
	v_lshl_add_u64 v[12:13], v[12:13], 0, s[4:5]
	v_cmp_lt_u64_e64 s[40:41], s[26:27], v[12:13]
	v_lshl_add_u64 v[10:11], v[10:11], 0, s[42:43]
	s_or_b64 s[44:45], s[40:41], s[44:45]
	s_waitcnt vmcnt(0) lgkmcnt(0)
	v_cvt_pk_bf16_f32 v14, v14, v15
	v_cvt_pk_bf16_f32 v15, v16, v17
	v_cvt_pk_bf16_f32 v16, v18, v19
	v_cvt_pk_bf16_f32 v17, v20, v21
	global_store_dwordx4 v[8:9], v[14:17], off
	v_lshl_add_u64 v[8:9], v[8:9], 0, s[38:39]
	s_andn2_b64 exec, exec, s[44:45]
	s_cbranch_execnz .LBB0_272

; DI unsigned pk2(float a, float b) { f32x2 v = {a, b}; bf16v2 r = __builtin_convertvector(v, bf16v2); return __builtin_bit_cast(unsigned, r); }
; DI void cvt_f32_bf16(const float* s, bf16_t* d, size_t n8, size_t gt, size_t NT) {
;     for (size_t i = gt; i < n8; i += NT) { const f32x4 a = ((const f32x4*)s)[2 * i], b = ((const f32x4*)s)[2 * i + 1]; u32x4 w; w.x = pk2(a[0], a[1]); w.y = pk2(a[2], a[3]); w.z = pk2(b[0], b[1]); w.w = pk2(b[2], b[3]); ((u32x4*)d)[i] = w; }
; }
.LBB0_275:
	global_load_dwordx4 v[14:17], v[10:11], off
	global_load_dwordx4 v[18:21], v[10:11], off offset:16
	v_lshl_add_u64 v[12:13], v[12:13], 0, s[4:5]
	v_cmp_lt_u64_e32 vcc, s[26:27], v[12:13]
	v_lshl_add_u64 v[10:11], v[10:11], 0, s[40:41]
	s_or_b64 s[42:43], vcc, s[42:43]
	s_waitcnt vmcnt(0) lgkmcnt(0)
	v_cvt_pk_bf16_f32 v14, v14, v15
	v_cvt_pk_bf16_f32 v15, v16, v17
	v_cvt_pk_bf16_f32 v16, v18, v19
	v_cvt_pk_bf16_f32 v17, v20, v21
	global_store_dwordx4 v[8:9], v[14:17], off
	v_lshl_add_u64 v[8:9], v[8:9], 0, s[38:39]
	s_andn2_b64 exec, exec, s[42:43]
	s_cbranch_execnz .LBB0_275

; DI unsigned pk2(float a, float b) { f32x2 v = {a, b}; bf16v2 r = __builtin_convertvector(v, bf16v2); return __builtin_bit_cast(unsigned, r); }
; DI void cvt_f32_bf16(const float* s, bf16_t* d, size_t n8, size_t gt, size_t NT) {
;     for (size_t i = gt; i < n8; i += NT) { const f32x4 a = ((const f32x4*)s)[2 * i], b = ((const f32x4*)s)[2 * i + 1]; u32x4 w; w.x = pk2(a[0], a[1]); w.y = pk2(a[2], a[3]); w.z = pk2(b[0], b[1]); w.w = pk2(b[2], b[3]); ((u32x4*)d)[i] = w; }
; }
.LBB0_281:
	global_load_dwordx4 v[10:13], v[6:7], off
	global_load_dwordx4 v[14:17], v[6:7], off offset:16
	v_lshl_add_u64 v[4:5], v[4:5], 0, s[4:5]
	v_cmp_lt_u64_e32 vcc, s[26:27], v[4:5]
	v_lshl_add_u64 v[6:7], v[6:7], 0, s[8:9]
	s_or_b64 s[40:41], vcc, s[40:41]
	s_waitcnt vmcnt(0) lgkmcnt(0)
	v_cvt_pk_bf16_f32 v10, v10, v11
	v_cvt_pk_bf16_f32 v11, v12, v13
	v_cvt_pk_bf16_f32 v12, v14, v15
	v_cvt_pk_bf16_f32 v13, v16, v17
	global_store_dwordx4 v[8:9], v[10:13], off
	v_lshl_add_u64 v[8:9], v[8:9], 0, s[38:39]
	s_andn2_b64 exec, exec, s[40:41]
	s_cbranch_execnz .LBB0_281

; DI unsigned xb_ld(unsigned* p)              { return __hip_atomic_load(p, __ATOMIC_RELAXED, __HIP_MEMORY_SCOPE_AGENT); }
; DI void xcd_barrier_complete(unsigned* bar, unsigned x, unsigned& nloc, unsigned& nx) {
;     const unsigned G = gridDim.x * gridDim.y * gridDim.z;
;     unsigned sum, cnt, mine, sp = 0u;
;     for (;;) {
;         sum = 0u; cnt = 0u; mine = 0u;
; #pragma unroll
;         for (unsigned j = 0; j < 16; ++j) { const unsigned c = xb_ld(&bar[XB_XCNT(j)]); sum += c; cnt += (c > 0u) ? 1u : 0u; mine = (j == x) ? c : mine; }
;         if (sum == G) break;
;         __builtin_amdgcn_s_sleep(1);
;         if ((++sp & 255u) == 0u) { if (xb_ld(&bar[XB_TMO])) break; if (sp > XB_SPIN_CAP) { atomicAdd(&bar[XB_TMO], 1u); break; } }
;     }
;     nloc = mine > 0u ? mine : 1u; nx = cnt > 0u ? cnt : 1u;
; }
.LBB0_289:
	v_mov_b64_e32 v[14:15], s[8:9]
	global_load_dword v2, v[14:15], off offset:1024 sc1
	global_load_dword v1, v[14:15], off offset:1280 sc1
	global_load_dword v4, v[14:15], off offset:1536 sc1
	s_or_b64 s[48:49], s[48:49], exec
	s_or_b64 s[46:47], s[46:47], exec
	s_waitcnt vmcnt(0) lgkmcnt(0)
	v_add_u32_e32 v5, v1, v2
	v_add_u32_e32 v6, v5, v4
	global_load_dword v5, v[14:15], off offset:1792 sc1
	s_waitcnt vmcnt(0) lgkmcnt(0)
	v_add_u32_e32 v7, v6, v5
	global_load_dword v6, v[14:15], off offset:2048 sc1
	s_waitcnt vmcnt(0) lgkmcnt(0)
	v_add_u32_e32 v8, v7, v6
	global_load_dword v7, v[14:15], off offset:2304 sc1
	s_waitcnt vmcnt(0) lgkmcnt(0)
	v_add_u32_e32 v9, v8, v7
	global_load_dword v8, v[14:15], off offset:2560 sc1
	s_waitcnt vmcnt(0) lgkmcnt(0)
	v_add_u32_e32 v10, v9, v8
	global_load_dword v9, v[14:15], off offset:2816 sc1
	s_waitcnt vmcnt(0) lgkmcnt(0)
	v_add_u32_e32 v11, v10, v9
	global_load_dword v10, v[14:15], off offset:3072 sc1
	s_waitcnt vmcnt(0) lgkmcnt(0)
	v_add_u32_e32 v12, v11, v10
	global_load_dword v11, v[14:15], off offset:3328 sc1
	s_waitcnt vmcnt(0) lgkmcnt(0)
	v_add_u32_e32 v13, v12, v11
	global_load_dword v12, v[14:15], off offset:3584 sc1
	s_waitcnt vmcnt(0) lgkmcnt(0)
	v_add_u32_e32 v16, v13, v12
	global_load_dword v13, v[14:15], off offset:3840 sc1
	v_mov_b64_e32 v[14:15], s[34:35]
	global_load_dword v14, v[14:15], off sc1
	s_waitcnt vmcnt(0) lgkmcnt(0)
	v_add_u32_e32 v16, v16, v13
	v_add_u32_e32 v18, v16, v14
	v_mov_b64_e32 v[16:17], s[38:39]
	global_load_dword v15, v[16:17], off sc1
	v_mov_b64_e32 v[16:17], s[18:19]
	global_load_dword v16, v[16:17], off sc1
	s_waitcnt vmcnt(0) lgkmcnt(0)
	v_add_u32_e32 v18, v18, v15
	v_add_u32_e32 v20, v18, v16
	v_mov_b64_e32 v[18:19], s[40:41]
	global_load_dword v17, v[18:19], off sc1
	s_waitcnt vmcnt(0) lgkmcnt(0)
	v_add_u32_e32 v18, v20, v17
	v_cmp_ne_u32_e32 vcc, s11, v18
	s_and_saveexec_b64 s[50:51], vcc
	s_cbranch_execz .LBB0_288
	s_and_b32 s22, s12, 0xff
	s_mov_b64 s[52:53], -1
	s_cmp_eq_u32 s22, 0
	s_mov_b64 s[56:57], -1
	s_mov_b64 s[54:55], -1
	s_sleep 1
	s_cbranch_scc1 .LBB0_292
	s_and_saveexec_b64 s[58:59], s[56:57]
	s_cbranch_execz .LBB0_287
	s_branch .LBB0_295
.LBB0_292:
	v_mov_b64_e32 v[18:19], s[8:9]
	global_load_dword v18, v[18:19], off offset:512 sc1
	s_mov_b64 s[56:57], 0
	s_waitcnt vmcnt(0) lgkmcnt(0)
	v_cmp_eq_u32_e32 vcc, 0, v18
	s_and_saveexec_b64 s[58:59], vcc
	s_cmp_lt_u32 s12, 0x100001
	s_cselect_b64 s[22:23], -1, 0
	s_xor_b64 s[54:55], exec, -1
	s_and_b64 s[56:57], s[22:23], exec
	s_or_b64 exec, exec, s[58:59]
	s_and_saveexec_b64 s[58:59], s[56:57]
	s_cbranch_execz .LBB0_287

; DI unsigned xb_ld(unsigned* p)              { return __hip_atomic_load(p, __ATOMIC_RELAXED, __HIP_MEMORY_SCOPE_AGENT); }
; DI unsigned xb_add(unsigned* p, unsigned v) { return __hip_atomic_fetch_add(p, v, __ATOMIC_RELAXED, __HIP_MEMORY_SCOPE_AGENT); }
; #define XB_SPIN(cond, bar) do { unsigned _sp = 0; while (cond) { __builtin_amdgcn_s_sleep(1); \
;     if ((++_sp & 255u) == 0u) { if (xb_ld(&(bar)[XB_TMO])) break; if (_sp > XB_SPIN_CAP) { atomicAdd(&(bar)[XB_TMO], 1u); break; } } } } while (0)
; DI void xcd_barrier(const XcdBarrier& b) {
;     ...
;     if (threadIdx.x == 0) {
;         unsigned* bar = b.bar;
;         __builtin_amdgcn_s_waitcnt(0);
;         unsigned nloc = b.st[0], nx = b.st[1];
;         if (nloc == 0u) { xcd_barrier_complete(bar, b.x, nloc, nx); b.st[0] = nloc; b.st[1] = nx; }
;         const unsigned old = xb_add(&bar[XB_XSUB(b.x)], 1u);
;         const unsigned gen = old / nloc;
;         if (old + 1u == (gen + 1u) * nloc) {
;             __builtin_amdgcn_fence(__ATOMIC_RELEASE, "agent");
;             asm volatile("s_waitcnt vmcnt(0)" ::: "memory");
;             const unsigned og = xb_add(&bar[XB_TOP], 1u);
;             const unsigned tg = og / nx;
;             if (og + 1u == (tg + 1u) * nx) xb_add(&bar[XB_TOPGEN], 1u);
;             else XB_SPIN(xb_ld(&bar[XB_TOPGEN]) == tg, bar);
;             __builtin_amdgcn_fence(__ATOMIC_ACQUIRE, "agent");
;             xb_add(&bar[XB_XGEN(b.x)], 1u);
;             asm volatile("s_waitcnt vmcnt(0)" ::: "memory");
;         } else {
;             XB_SPIN(xb_ld(&bar[XB_XGEN(b.x)]) == gen, bar);
.LBB0_299:
	v_readlane_b32 s11, v253, 48
	s_lshl_b32 s11, s11, 2
	s_add_u32 s12, s8, s11
	s_addc_u32 s11, s9, 0
	v_mov_b32_e32 v1, s12
	v_add_co_u32_e32 v6, vcc, 0x1000, v1
	v_mov_b32_e32 v1, s11
	s_nop 0
	v_addc_co_u32_e32 v7, vcc, 0, v1, vcc
	flat_atomic_add v5, v[6:7], v218 offset:1024 sc0
	v_cvt_f32_u32_e32 v1, v4
	v_sub_u32_e32 v6, 0, v4
	v_rcp_iflag_f32_e32 v1, v1
	s_nop 0
	v_mul_f32_e32 v1, 0x4f7ffffe, v1
	v_cvt_u32_f32_e32 v1, v1
	v_mul_lo_u32 v6, v6, v1
	v_mul_hi_u32 v6, v1, v6
	v_add_u32_e32 v1, v1, v6
	s_waitcnt vmcnt(0) lgkmcnt(0)
	v_mul_hi_u32 v1, v5, v1
	v_mul_lo_u32 v6, v1, v4
	v_sub_u32_e32 v6, v5, v6
	v_cmp_ge_u32_e32 vcc, v6, v4
	v_add_u32_e32 v7, 1, v1
	s_nop 0
	v_cndmask_b32_e32 v1, v1, v7, vcc
	v_sub_u32_e32 v7, v6, v4
	v_cndmask_b32_e32 v6, v6, v7, vcc
	v_cmp_ge_u32_e32 vcc, v6, v4
	v_add_u32_e32 v6, 1, v1
	s_nop 0
	v_cndmask_b32_e32 v1, v1, v6, vcc
	v_add_u32_e32 v6, 1, v5
	v_mad_u64_u32 v[4:5], s[18:19], v4, v1, v[4:5]
	v_cmp_ne_u32_e32 vcc, v6, v4
	s_and_saveexec_b64 s[18:19], vcc
	s_xor_b64 s[18:19], exec, s[18:19]
	s_cbranch_execz .LBB0_312
	v_mov_b32_e32 v2, s12
	v_add_co_u32_e32 v4, vcc, 0x2000, v2
	v_mov_b32_e32 v2, s11
	s_nop 0
	v_addc_co_u32_e32 v5, vcc, 0, v2, vcc
	global_load_dword v2, v[4:5], off offset:1024 sc1
	s_add_u32 s38, s12, 0x2400
	s_addc_u32 s39, s11, 0
	s_waitcnt vmcnt(0) lgkmcnt(0)
	v_cmp_eq_u32_e32 vcc, v2, v1
	s_and_saveexec_b64 s[34:35], vcc
	s_cbranch_execz .LBB0_311
	s_mov_b32 s22, 1
	s_mov_b64 s[40:41], 0
	s_branch .LBB0_303

; DI unsigned xb_ld(unsigned* p)              { return __hip_atomic_load(p, __ATOMIC_RELAXED, __HIP_MEMORY_SCOPE_AGENT); }
; #define XB_SPIN(cond, bar) do { unsigned _sp = 0; while (cond) { __builtin_amdgcn_s_sleep(1); \
;     if ((++_sp & 255u) == 0u) { if (xb_ld(&(bar)[XB_TMO])) break; if (_sp > XB_SPIN_CAP) { atomicAdd(&(bar)[XB_TMO], 1u); break; } } } } while (0)
; DI void xcd_barrier(const XcdBarrier& b) {
;     ...
;             XB_SPIN(xb_ld(&bar[XB_XGEN(b.x)]) == gen, bar);
.LBB0_303:
	s_and_b32 s23, s22, 0xff
	s_mov_b64 s[46:47], -1
	s_cmp_lg_u32 s23, 0
	s_mov_b64 s[48:49], -1
	s_sleep 1
	s_cbranch_scc1 .LBB0_307
	v_mov_b64_e32 v[4:5], s[8:9]
	global_load_dword v2, v[4:5], off offset:512 sc1
	s_mov_b64 s[48:49], 0
	s_mov_b64 s[50:51], -1
	s_waitcnt vmcnt(0) lgkmcnt(0)
	v_cmp_eq_u32_e32 vcc, 0, v2
	s_and_saveexec_b64 s[52:53], vcc
	s_cmp_lt_u32 s22, 0x100001
	s_cselect_b64 s[26:27], -1, 0
	s_xor_b64 s[50:51], exec, -1
	s_and_b64 s[48:49], s[26:27], exec
	s_or_b64 exec, exec, s[52:53]
.LBB0_307:
	s_andn2_b64 s[26:27], s[44:45], exec
	s_and_b64 s[44:45], s[50:51], exec
	s_or_b64 s[44:45], s[26:27], s[44:45]
	s_and_saveexec_b64 s[50:51], s[48:49]
	s_cbranch_execz .LBB0_302
	v_mov_b64_e32 v[4:5], s[38:39]
	global_load_dword v2, v[4:5], off sc1
	s_add_i32 s22, s22, 1
	s_or_b64 s[44:45], s[44:45], exec
	s_waitcnt vmcnt(0) lgkmcnt(0)
	v_cmp_ne_u32_e32 vcc, v2, v1
	s_orn2_b64 s[46:47], vcc, exec
	s_branch .LBB0_302

; DI unsigned xb_ld(unsigned* p)              { return __hip_atomic_load(p, __ATOMIC_RELAXED, __HIP_MEMORY_SCOPE_AGENT); }
; DI unsigned xb_add(unsigned* p, unsigned v) { return __hip_atomic_fetch_add(p, v, __ATOMIC_RELAXED, __HIP_MEMORY_SCOPE_AGENT); }
; #define XB_SPIN(cond, bar) do { unsigned _sp = 0; while (cond) { __builtin_amdgcn_s_sleep(1); \
;     if ((++_sp & 255u) == 0u) { if (xb_ld(&(bar)[XB_TMO])) break; if (_sp > XB_SPIN_CAP) { atomicAdd(&(bar)[XB_TMO], 1u); break; } } } } while (0)
; DI void xcd_barrier(const XcdBarrier& b) {
;     ...
;         if (old + 1u == (gen + 1u) * nloc) {
;             __builtin_amdgcn_fence(__ATOMIC_RELEASE, "agent");
;             asm volatile("s_waitcnt vmcnt(0)" ::: "memory");
;             const unsigned og = xb_add(&bar[XB_TOP], 1u);
;             const unsigned tg = og / nx;
;             if (og + 1u == (tg + 1u) * nx) xb_add(&bar[XB_TOPGEN], 1u);
;             else XB_SPIN(xb_ld(&bar[XB_TOPGEN]) == tg, bar);
.LBB0_312:
	s_andn2_saveexec_b64 s[18:19], s[18:19]
	s_cbranch_execz .LBB0_328
	v_mov_b32_e32 v1, s8
	v_add_co_u32_e32 v4, vcc, 0x3000, v1
	v_mov_b32_e32 v1, s9
	buffer_wbl2 sc1
	s_waitcnt vmcnt(0)
	v_addc_co_u32_e32 v5, vcc, 0, v1, vcc
	flat_atomic_add v4, v[4:5], v218 offset:1024 sc0
	v_cvt_f32_u32_e32 v1, v2
	v_sub_u32_e32 v5, 0, v2
	s_mov_b64 s[38:39], -1
	v_rcp_iflag_f32_e32 v1, v1
	s_nop 0
	v_mul_f32_e32 v1, 0x4f7ffffe, v1
	v_cvt_u32_f32_e32 v1, v1
	v_mul_lo_u32 v5, v5, v1
	v_mul_hi_u32 v5, v1, v5
	v_add_u32_e32 v1, v1, v5
	s_waitcnt vmcnt(0) lgkmcnt(0)
	v_mul_hi_u32 v1, v4, v1
	v_mul_lo_u32 v5, v1, v2
	v_sub_u32_e32 v5, v4, v5
	v_cmp_ge_u32_e32 vcc, v5, v2
	v_add_u32_e32 v6, 1, v1
	s_nop 0
	v_cndmask_b32_e32 v1, v1, v6, vcc
	v_sub_u32_e32 v6, v5, v2
	v_cndmask_b32_e32 v5, v5, v6, vcc
	v_cmp_ge_u32_e32 vcc, v5, v2
	v_add_u32_e32 v5, 1, v1
	v_add_u32_e32 v6, 1, v4
	v_cndmask_b32_e32 v1, v1, v5, vcc
	v_mad_u64_u32 v[4:5], s[18:19], v2, v1, v[2:3]
	s_add_u32 s18, s8, 0x3500
	s_addc_u32 s19, s9, 0
	v_cmp_ne_u32_e32 vcc, v6, v4
	v_mov_b64_e32 v[4:5], s[18:19]
	s_and_saveexec_b64 s[34:35], vcc
	s_cbranch_execz .LBB0_325
	v_mov_b64_e32 v[4:5], s[18:19]
	global_load_dword v2, v[4:5], off sc1
	s_mov_b64 s[42:43], 0
	s_waitcnt vmcnt(0) lgkmcnt(0)
	v_cmp_eq_u32_e32 vcc, v2, v1
	s_and_saveexec_b64 s[40:41], vcc
	s_cbranch_execz .LBB0_324
	s_add_u32 s38, s8, 0x200
	s_addc_u32 s39, s9, 0
	s_mov_b32 s22, 1
	s_mov_b64 s[8:9], 0
	s_branch .LBB0_317

; DI unsigned xb_ld(unsigned* p)              { return __hip_atomic_load(p, __ATOMIC_RELAXED, __HIP_MEMORY_SCOPE_AGENT); }
; DI unsigned xb_add(unsigned* p, unsigned v) { return __hip_atomic_fetch_add(p, v, __ATOMIC_RELAXED, __HIP_MEMORY_SCOPE_AGENT); }
; #define XB_SPIN(cond, bar) do { unsigned _sp = 0; while (cond) { __builtin_amdgcn_s_sleep(1); \
;     if ((++_sp & 255u) == 0u) { if (xb_ld(&(bar)[XB_TMO])) break; if (_sp > XB_SPIN_CAP) { atomicAdd(&(bar)[XB_TMO], 1u); break; } } } } while (0)
; DI void xcd_barrier(const XcdBarrier& b) {
;     ...
;             else XB_SPIN(xb_ld(&bar[XB_TOPGEN]) == tg, bar);
;             __builtin_amdgcn_fence(__ATOMIC_ACQUIRE, "agent");
;             xb_add(&bar[XB_XGEN(b.x)], 1u);
;             asm volatile("s_waitcnt vmcnt(0)" ::: "memory");
;         } else {
;             XB_SPIN(xb_ld(&bar[XB_XGEN(b.x)]) == gen, bar);
.LBB0_319:
	v_mov_b64_e32 v[4:5], s[38:39]
	global_load_dword v2, v[4:5], off sc1
	s_mov_b64 s[48:49], 0
	s_mov_b64 s[46:47], -1
	s_waitcnt vmcnt(0) lgkmcnt(0)
	v_cmp_eq_u32_e32 vcc, 0, v2
	s_and_saveexec_b64 s[50:51], vcc
	s_cmp_lt_u32 s22, 0x100001
	s_cselect_b64 s[26:27], -1, 0
	s_xor_b64 s[46:47], exec, -1
	s_and_b64 s[48:49], s[26:27], exec
	s_or_b64 exec, exec, s[50:51]
	s_and_saveexec_b64 s[50:51], s[48:49]
	s_cbranch_execz .LBB0_316
.LBB0_322:
	v_mov_b64_e32 v[4:5], s[18:19]
	global_load_dword v2, v[4:5], off sc1
	s_add_i32 s22, s22, 1
	s_or_b64 s[46:47], s[46:47], exec
	s_waitcnt vmcnt(0) lgkmcnt(0)
	v_cmp_ne_u32_e32 vcc, v2, v1
	s_orn2_b64 s[44:45], vcc, exec
	s_branch .LBB0_316

; DI unsigned char* kws() { return (unsigned char*)karg64<208>(); }
; DI u32x2 packq8(const f32x4 v0, const f32x4 v1) { u32x2 w; w.x = pk4q8(v0); w.y = pk4q8(v1); return w; }
; DI void inproj_tail_combine(const Ctx& c) {
;     const float* part = (const float*)(kws() + WS_PART); const float* rs = (const float*)(kws() + WS_RS); bf16_t* Z = (bf16_t*)(kws() + WS_Z);
;     for (int i = c.bid * NTHR + c.tid; i < 16 * 8192; i += c.G * NTHR) {
;         const int tile = i >> 13, e = i & 8191, r = e >> 5, c8 = (e & 31) * 8, row = 71 * 256 + r;
;         const float* p = part + ((size_t)tile * 256 + r) * 256 + c8;
;         f32x4 v0 = *(const f32x4*)p, v1 = *(const f32x4*)(p + 4);
; #pragma unroll
;         for (int ks = 1; ks < 8; ++ks) { v0 += *(const f32x4*)(p + (size_t)ks * 16 * 65536); v1 += *(const f32x4*)(p + (size_t)ks * 16 * 65536 + 4); }
;         const float sc = rs[row];
; #pragma unroll
;         for (int j = 0; j < 4; ++j) { v0[j] = __builtin_amdgcn_rcpf(1.0f + __expf(-v0[j] * sc)); v1[j] = __builtin_amdgcn_rcpf(1.0f + __expf(-v1[j] * sc)); }
;         const int fo = ((((((r >> 6) & 1) * 4 + ((c8 >> 5) & 3)) * 2 + (r >> 7)) * 4 + ((r >> 4) & 3)) * 64 + ((c8 >> 3) & 3) * 16 + (r & 15)) * 16 + (c8 >> 7) * 8;
;         *(u32x2*)((unsigned char*)(kws() + WS_GATE) + ((size_t)71 * 24 + tile) * 65536 + fo) = pg8::packq8(v0, v1);
;     }
; }
.LBB0_336:
	v_ashrrev_i32_e32 v4, 13, v6
	v_ashrrev_i32_e32 v5, 31, v4
	v_bfe_u32 v9, v6, 5, 8
	v_lshlrev_b64 v[10:11], 18, v[4:5]
	v_and_b32_e32 v12, 0xf8, v8
	v_lshl_add_u64 v[10:11], s[18:19], 0, v[10:11]
	v_lshlrev_b32_e32 v2, 10, v9
	v_lshl_add_u64 v[10:11], v[10:11], 0, v[2:3]
	v_lshlrev_b32_e32 v2, 2, v12
	v_lshl_add_u64 v[22:23], v[10:11], 0, v[2:3]
	s_mov_b32 s23, 0x400000
	v_add_co_u32_e32 v24, vcc, s23, v22
	global_load_dwordx4 v[10:13], v[22:23], off
	global_load_dwordx4 v[14:17], v[22:23], off offset:16
	v_addc_co_u32_e32 v25, vcc, 0, v23, vcc
	global_load_dwordx4 v[18:21], v[24:25], off
	s_mov_b32 s23, 0x800000
	v_lshlrev_b32_e32 v2, 2, v9
	v_lshlrev_b64 v[4:5], 16, v[4:5]
	s_waitcnt vmcnt(0) lgkmcnt(0)
	v_pk_add_f32 v[20:21], v[12:13], v[20:21]
	v_pk_add_f32 v[18:19], v[10:11], v[18:19]
	global_load_dwordx4 v[10:13], v[24:25], off offset:16
	v_add_co_u32_e32 v24, vcc, s23, v22
	s_mov_b32 s23, 0xc00000
	s_nop 0
	v_addc_co_u32_e32 v25, vcc, 0, v23, vcc
	s_waitcnt vmcnt(0) lgkmcnt(0)
	v_pk_add_f32 v[16:17], v[16:17], v[12:13]
	v_pk_add_f32 v[14:15], v[14:15], v[10:11]
	global_load_dwordx4 v[10:13], v[24:25], off
	s_waitcnt vmcnt(0) lgkmcnt(0)
	v_pk_add_f32 v[20:21], v[20:21], v[12:13]
	v_pk_add_f32 v[18:19], v[18:19], v[10:11]
	global_load_dwordx4 v[10:13], v[24:25], off offset:16
	v_add_co_u32_e32 v24, vcc, s23, v22
	s_mov_b32 s23, 0x1400000
	s_nop 0
	v_addc_co_u32_e32 v25, vcc, 0, v23, vcc
	s_waitcnt vmcnt(0) lgkmcnt(0)
	v_pk_add_f32 v[16:17], v[16:17], v[12:13]
	v_pk_add_f32 v[14:15], v[14:15], v[10:11]
	global_load_dwordx4 v[10:13], v[24:25], off
	s_waitcnt vmcnt(0) lgkmcnt(0)
	v_pk_add_f32 v[20:21], v[20:21], v[12:13]
	v_pk_add_f32 v[18:19], v[18:19], v[10:11]
	global_load_dwordx4 v[10:13], v[24:25], off offset:16
	v_add_co_u32_e32 v24, vcc, s97, v22
	s_waitcnt vmcnt(0) lgkmcnt(0)
	v_pk_add_f32 v[16:17], v[16:17], v[12:13]
	v_addc_co_u32_e32 v25, vcc, 0, v23, vcc
	v_pk_add_f32 v[14:15], v[14:15], v[10:11]
	global_load_dwordx4 v[10:13], v[24:25], off
	s_waitcnt vmcnt(0) lgkmcnt(0)
	v_pk_add_f32 v[20:21], v[20:21], v[12:13]
	v_pk_add_f32 v[18:19], v[18:19], v[10:11]
	global_load_dwordx4 v[10:13], v[24:25], off offset:16
	v_add_co_u32_e32 v24, vcc, s23, v22
	s_mov_b32 s23, 0x1800000
	s_nop 0
	v_addc_co_u32_e32 v25, vcc, 0, v23, vcc
	s_waitcnt vmcnt(0) lgkmcnt(0)
	v_pk_add_f32 v[16:17], v[16:17], v[12:13]
	v_pk_add_f32 v[14:15], v[14:15], v[10:11]
	global_load_dwordx4 v[10:13], v[24:25], off
	s_waitcnt vmcnt(0) lgkmcnt(0)
	v_pk_add_f32 v[20:21], v[20:21], v[12:13]
	v_pk_add_f32 v[18:19], v[18:19], v[10:11]
	global_load_dwordx4 v[10:13], v[24:25], off offset:16
	v_add_co_u32_e32 v24, vcc, s23, v22
	s_mov_b32 s23, 0x1c00000
	s_nop 0
	v_addc_co_u32_e32 v25, vcc, 0, v23, vcc
	v_add_co_u32_e32 v22, vcc, s23, v22
	s_mov_b32 s23, 0x15000
	s_nop 0
	v_addc_co_u32_e32 v23, vcc, 0, v23, vcc
	s_waitcnt vmcnt(0) lgkmcnt(0)
	v_pk_add_f32 v[16:17], v[16:17], v[12:13]
	v_pk_add_f32 v[14:15], v[14:15], v[10:11]
	global_load_dwordx4 v[10:13], v[24:25], off
	s_waitcnt vmcnt(0) lgkmcnt(0)
	v_pk_add_f32 v[20:21], v[20:21], v[12:13]
	v_pk_add_f32 v[18:19], v[18:19], v[10:11]
	global_load_dwordx4 v[10:13], v[24:25], off offset:16
	s_waitcnt vmcnt(0) lgkmcnt(0)
	v_pk_add_f32 v[16:17], v[16:17], v[12:13]
	v_pk_add_f32 v[14:15], v[14:15], v[10:11]
	global_load_dwordx4 v[10:13], v[22:23], off
	s_waitcnt vmcnt(0) lgkmcnt(0)
	v_pk_add_f32 v[20:21], v[20:21], v[12:13]
	v_pk_add_f32 v[18:19], v[18:19], v[10:11]
	global_load_dwordx4 v[10:13], v[22:23], off offset:16
	s_waitcnt vmcnt(0) lgkmcnt(0)
	v_pk_add_f32 v[14:15], v[14:15], v[10:11]
	v_lshl_add_u64 v[10:11], s[4:5], 0, v[2:3]
	v_add_co_u32_e32 v10, vcc, s23, v10
	v_pk_add_f32 v[12:13], v[16:17], v[12:13]
	s_nop 0
	v_addc_co_u32_e32 v11, vcc, 0, v11, vcc
	global_load_dword v2, v[10:11], off offset:3072
	v_lshrrev_b32_e32 v17, 5, v8
	s_load_dwordx2 s[26:27], s[0:1], 0xd0
	s_waitcnt lgkmcnt(0)
	s_waitcnt vmcnt(0) lgkmcnt(0)
	v_mul_f32_e64 v9, v2, -v18
	v_mul_f32_e32 v9, 0x3fb8aa3b, v9
	v_mul_f32_e64 v10, v2, -v19
	v_exp_f32_e32 v9, v9
	v_mul_f32_e32 v10, 0x3fb8aa3b, v10
	v_exp_f32_e32 v10, v10
	v_mul_f32_e64 v12, v2, -v12
	v_add_f32_e32 v9, 1.0, v9
	v_rcp_f32_e32 v11, v9
	v_mul_f32_e64 v9, v2, -v14
	v_add_f32_e32 v10, 1.0, v10
	v_mul_f32_e32 v9, 0x3fb8aa3b, v9
	v_rcp_f32_e32 v14, v10
	v_mul_f32_e64 v10, v2, -v15
	v_mul_f32_e64 v15, v2, -v20
	v_mul_f32_e64 v16, v2, -v21
	v_mul_f32_e64 v2, v2, -v13
	v_exp_f32_e32 v9, v9
	v_mul_f32_e32 v10, 0x3fb8aa3b, v10
	v_mul_f32_e32 v2, 0x3fb8aa3b, v2
	v_exp_f32_e32 v10, v10
	v_exp_f32_e32 v2, v2
	v_mul_f32_e32 v15, 0x3fb8aa3b, v15
	v_mul_f32_e32 v12, 0x3fb8aa3b, v12
	v_add_f32_e32 v9, 1.0, v9
	v_exp_f32_e32 v15, v15
	v_exp_f32_e32 v12, v12
	v_rcp_f32_e32 v9, v9
	v_add_f32_e32 v10, 1.0, v10
	v_add_f32_e32 v2, 1.0, v2
	v_rcp_f32_e32 v10, v10
	v_mul_f32_e32 v16, 0x3fb8aa3b, v16
	v_rcp_f32_e32 v13, v2
	v_lshrrev_b32_e32 v2, 9, v6
	v_exp_f32_e32 v16, v16
	v_and_b32_e32 v2, 4, v2
	v_add_f32_e32 v15, 1.0, v15
	v_add_f32_e32 v12, 1.0, v12
	v_and_or_b32 v2, v17, 3, v2
	v_lshrrev_b32_e32 v17, 10, v6
	v_rcp_f32_e32 v15, v15
	v_rcp_f32_e32 v12, v12
	v_lshlrev_b32_e32 v2, 3, v2
	v_and_b32_e32 v17, 4, v17
	v_bfe_u32 v18, v6, 9, 2
	v_mul_f32_e32 v11, 0x437f0000, v11
	v_mul_f32_e32 v9, 0x437f0000, v9
	v_or3_b32 v2, v2, v17, v18
	v_rndne_f32_e32 v11, v11
	v_mul_f32_e32 v14, 0x437f0000, v14
	v_rndne_f32_e32 v9, v9
	v_mul_f32_e32 v10, 0x437f0000, v10
	v_add_f32_e32 v16, 1.0, v16
	v_lshlrev_b32_e32 v2, 6, v2
	v_and_b32_e32 v17, 48, v7
	v_bfe_u32 v18, v6, 5, 4
	v_max_f32_e32 v11, 1.0, v11
	v_rndne_f32_e32 v14, v14
	v_max_f32_e32 v9, 1.0, v9
	v_rndne_f32_e32 v10, v10
	v_rcp_f32_e32 v16, v16
	v_or3_b32 v2, v2, v17, v18
	v_lshrrev_b32_e32 v17, 4, v8
	v_cvt_pk_u8_f32 v11, v11, 0, 0
	v_max_f32_e32 v14, 1.0, v14
	v_cvt_pk_u8_f32 v9, v9, 0, 0
	v_max_f32_e32 v10, 1.0, v10
	v_and_b32_e32 v17, 8, v17
	v_cvt_pk_u8_f32 v11, v14, 1, v11
	v_mul_f32_e32 v14, 0x437f0000, v15
	v_cvt_pk_u8_f32 v9, v10, 1, v9
	v_mul_f32_e32 v10, 0x437f0000, v12
	v_lshl_or_b32 v2, v2, 4, v17
	v_rndne_f32_e32 v14, v14
	v_rndne_f32_e32 v10, v10
	v_lshl_add_u64 v[4:5], s[26:27], 0, v[4:5]
	v_max_f32_e32 v14, 1.0, v14
	v_max_f32_e32 v10, 1.0, v10
	v_lshl_add_u64 v[4:5], v[4:5], 0, v[2:3]
	v_cvt_pk_u8_f32 v11, v14, 2, v11
	v_mul_f32_e32 v14, 0x437f0000, v16
	v_cvt_pk_u8_f32 v9, v10, 2, v9
	v_mul_f32_e32 v10, 0x437f0000, v13
	v_add_co_u32_e32 v4, vcc, 0x5b8d6000, v4
	v_rndne_f32_e32 v14, v14
	v_rndne_f32_e32 v10, v10
	v_addc_co_u32_e32 v5, vcc, 0, v5, vcc
	v_add_u32_e32 v6, s11, v6
	v_max_f32_e32 v14, 1.0, v14
	v_max_f32_e32 v10, 1.0, v10
	v_cmp_lt_i32_e32 vcc, s38, v6
	v_cvt_pk_u8_f32 v14, v14, 3, v11
	v_cvt_pk_u8_f32 v15, v10, 3, v9
	v_add_u32_e32 v7, s12, v7
	v_add_u32_e32 v8, s22, v8
	s_or_b64 s[34:35], vcc, s[34:35]
	global_store_dwordx2 v[4:5], v[14:15], off
	s_andn2_b64 exec, exec, s[34:35]
	s_cbranch_execnz .LBB0_336
	s_or_b64 exec, exec, s[34:35]
; #define LAS __attribute__((address_space(3)))
; DI void lru_local_phase(const Ctx& c, int l) {
;     ...
;     int u = c.bid; if (u >= nunits) return;
;     const int cg = c.tid & 15, tk = c.tid >> 4;
;     const int fr = c.lane & 15, fq = c.lane >> 4, w = c.wave;
;     const int chl = c.tid & 127, q = c.tid >> 7;
;     int nblk_cur = -1;
;     LAS float* cwl = tot + 1024;
;     bf16x8 bwa[4], bwx[4]; float ba = 0.f, bx = 0.f, c8 = 0.f;
;     u32x4 pre[2][4];
;     ...
;     LRU_PREFETCH(u);
.LBB0_338:
	s_or_b64 exec, exec, s[8:9]
	v_readlane_b32 s18, v254, 17
	v_bfe_u32 v165, v132, 4, 2
	v_readlane_b32 s19, v254, 18
	s_ashr_i32 s11, s10, 6
	v_and_b32_e32 v164, 15, v132
	v_lshlrev_b32_e32 v166, 2, v165
	s_mov_b64 s[4:5], -1
	s_and_b64 vcc, exec, s[18:19]
	s_load_dwordx2 s[8:9], s[0:1], 0xd0
	s_waitcnt lgkmcnt(0)
	s_cbranch_vccz .LBB0_437
	s_add_u32 s4, s8, 0x26456000
	v_ashrrev_i32_e32 v134, 4, v132
	s_addc_u32 s5, s9, 0
	v_readlane_b32 s8, v253, 50
	v_cmp_gt_i32_e64 s[40:41], 3, v134
	v_readlane_b32 s9, v253, 51
	s_and_b64 s[8:9], s[8:9], s[40:41]
	s_xor_b64 s[18:19], s[8:9], -1
	v_readlane_b32 s8, v254, 62
	s_add_u32 s8, s4, s8
	s_addc_u32 s9, s5, 0
	v_lshlrev_b32_e32 v2, 4, v164
	v_add_u32_e32 v139, -3, v134
	v_lshl_add_u64 v[36:37], s[8:9], 0, v[2:3]
	s_and_saveexec_b64 s[8:9], s[18:19]
	s_cbranch_execz .LBB0_341
	v_readlane_b32 s12, v253, 52
	s_nop 1
	v_add_u32_e32 v4, s12, v139
	v_mad_i64_i32 v[4:5], s[18:19], v4, s31, v[36:37]
	global_load_dwordx4 v[4:7], v[4:5], off
.LBB0_341:
	s_or_b64 exec, exec, s[8:9]
	v_readlane_b32 s8, v253, 50
	v_cmp_gt_i32_e64 s[42:43], 2, v134
	v_readlane_b32 s9, v253, 51
	s_and_b64 s[8:9], s[8:9], s[42:43]
	v_add_u32_e32 v167, -2, v134
	s_xor_b64 s[18:19], s[8:9], -1
	s_and_saveexec_b64 s[8:9], s[18:19]
	s_cbranch_execz .LBB0_343
	v_readlane_b32 s12, v253, 52
	s_nop 1
	v_add_u32_e32 v8, s12, v167
	v_mad_i64_i32 v[8:9], s[18:19], v8, s31, v[36:37]
	global_load_dwordx4 v[8:11], v[8:9], off
.LBB0_343:
	s_or_b64 exec, exec, s[8:9]
	v_readlane_b32 s8, v253, 50
	v_cmp_gt_i32_e64 s[44:45], 1, v134
	v_readlane_b32 s9, v253, 51
	s_and_b64 s[8:9], s[8:9], s[44:45]
	v_add_u32_e32 v168, -1, v134
	s_xor_b64 s[18:19], s[8:9], -1
	s_and_saveexec_b64 s[8:9], s[18:19]
	s_cbranch_execz .LBB0_345
	v_readlane_b32 s12, v253, 52
	s_nop 1
	v_add_u32_e32 v12, s12, v168
	v_mad_i64_i32 v[12:13], s[18:19], v12, s31, v[36:37]
	global_load_dwordx4 v[12:15], v[12:13], off
.LBB0_345:
	s_or_b64 exec, exec, s[8:9]
	v_readlane_b32 s8, v253, 50
	v_cmp_gt_i32_e64 s[46:47], 0, v134
	v_readlane_b32 s9, v253, 51
	s_and_b64 s[8:9], s[8:9], s[46:47]
	s_xor_b64 s[18:19], s[8:9], -1
	s_and_saveexec_b64 s[8:9], s[18:19]
	s_cbranch_execz .LBB0_347
	v_readlane_b32 s12, v253, 52
	s_nop 1
	v_add_u32_e32 v16, s12, v134
	v_mad_i64_i32 v[16:17], s[18:19], v16, s31, v[36:37]
	global_load_dwordx4 v[16:19], v[16:17], off
.LBB0_347:
	s_or_b64 exec, exec, s[8:9]
	s_movk_i32 s8, 0xffe3
	v_cmp_gt_i32_e64 s[48:49], s8, v134
	v_readlane_b32 s8, v253, 50
	v_readlane_b32 s9, v253, 51
	s_and_b64 s[8:9], s[8:9], s[48:49]
	v_add_u32_e32 v169, 29, v134
	s_xor_b64 s[18:19], s[8:9], -1
	s_and_saveexec_b64 s[8:9], s[18:19]
	s_cbranch_execz .LBB0_349
	v_readlane_b32 s12, v253, 52
	s_nop 1
	v_add_u32_e32 v20, s12, v169
	v_mad_i64_i32 v[20:21], s[18:19], v20, s31, v[36:37]
	global_load_dwordx4 v[20:23], v[20:21], off
.LBB0_349:
	s_or_b64 exec, exec, s[8:9]
	s_movk_i32 s8, 0xffe2
	v_cmp_gt_i32_e64 s[50:51], s8, v134
	v_readlane_b32 s8, v253, 50
	v_readlane_b32 s9, v253, 51
	s_and_b64 s[8:9], s[8:9], s[50:51]
	v_add_u32_e32 v170, 30, v134
	s_xor_b64 s[18:19], s[8:9], -1
	s_and_saveexec_b64 s[8:9], s[18:19]
	s_cbranch_execz .LBB0_351
	v_readlane_b32 s12, v253, 52
	s_nop 1
	v_add_u32_e32 v24, s12, v170
	v_mad_i64_i32 v[24:25], s[18:19], v24, s31, v[36:37]
	global_load_dwordx4 v[24:27], v[24:25], off
.LBB0_351:
	s_or_b64 exec, exec, s[8:9]
	s_movk_i32 s8, 0xffe1
	v_cmp_gt_i32_e64 s[52:53], s8, v134
	v_readlane_b32 s8, v253, 50
	v_readlane_b32 s9, v253, 51
	s_and_b64 s[8:9], s[8:9], s[52:53]
	v_add_u32_e32 v171, 31, v134
	s_xor_b64 s[18:19], s[8:9], -1
	s_and_saveexec_b64 s[8:9], s[18:19]
	s_cbranch_execz .LBB0_353
	v_readlane_b32 s12, v253, 52
	s_nop 1
	v_add_u32_e32 v28, s12, v171
	v_mad_i64_i32 v[28:29], s[18:19], v28, s31, v[36:37]
	global_load_dwordx4 v[28:31], v[28:29], off
.LBB0_353:
	s_or_b64 exec, exec, s[8:9]
	s_movk_i32 s8, 0xffe0
	v_cmp_gt_i32_e64 s[54:55], s8, v134
	v_readlane_b32 s8, v253, 50
	v_readlane_b32 s9, v253, 51
	s_and_b64 s[8:9], s[8:9], s[54:55]
	v_add_u32_e32 v136, 32, v134
	s_xor_b64 s[18:19], s[8:9], -1
	s_and_saveexec_b64 s[8:9], s[18:19]
	s_cbranch_execz .LBB0_355
	v_readlane_b32 s12, v253, 52
	s_nop 1
	v_add_u32_e32 v32, s12, v136
	v_mad_i64_i32 v[32:33], s[18:19], v32, s31, v[36:37]
	global_load_dwordx4 v[32:35], v[32:33], off

; template <int I> DI const float* kin() { return (const float*)karg64<I * 8>(); }
; DI void lru_local_phase(const Ctx& c, int l) {
;     ...
;         if (nblk != nblk_cur) {
;             nblk_cur = nblk;
;             __syncthreads();
;             for (int i = c.tid; i < 640; i += NTHR) { const int k = i >> 7, cc = i & 127; cwl[i] = k < 4 ? kin<10>()[(size_t)l * 4 * 1024 + k * 1024 + ch0 + cc] : kin<11>()[(size_t)l * 1024 + ch0 + cc]; }
;             __syncthreads();
.LBB0_360:
	s_or_b64 exec, exec, s[64:65]
	v_lshl_add_u64 v[36:37], v[36:37], 0, s[12:13]
	v_lshl_add_u64 v[36:37], v[36:37], 0, v[2:3]
	global_load_dword v36, v[36:37], off
	s_movk_i32 s27, 0x7f
	v_add_u32_e32 v37, 0x200, v39
	v_cmp_lt_i32_e32 vcc, s27, v39
	s_or_b64 s[8:9], vcc, s[8:9]
	v_mov_b32_e32 v39, v37
	s_waitcnt vmcnt(0) lgkmcnt(0)
	ds_write_b32 v38, v36
	v_add_u32_e32 v38, 0x800, v38
	s_andn2_b64 exec, exec, s[8:9]
	s_cbranch_execz .LBB0_365

; template <int I> DI const float* kin() { return (const float*)karg64<I * 8>(); }
; DI unsigned char* kws() { return (unsigned char*)karg64<208>(); }
; DI void lru_local_phase(const Ctx& c, int l) {
;     ...
;             const bf16_t* wat = (const bf16_t*)(kws() + WS_LRUW) + (((size_t)l * 2 + 0) * 8 + nblk) * 16384 + (size_t)(16 * w + fr) * 128 + 8 * fq;
;             const bf16_t* wxt = wat + (size_t)8 * 16384;
; #pragma unroll
;             for (int ks = 0; ks < 4; ++ks) { bwa[ks] = *(const bf16x8*)(wat + 32 * ks); bwx[ks] = *(const bf16x8*)(wxt + 32 * ks); }
;             const int ch = ch0 + 16 * w + fr;
;             ba = kin<13>()[(size_t)l * 1024 + ch]; bx = kin<15>()[(size_t)l * 1024 + ch]; c8 = 8.0f * log1pf(expf(-kin<16>()[(size_t)l * 1024 + ch]));
.LBB0_365:
	s_or_b64 exec, exec, s[4:5]
	s_waitcnt lgkmcnt(0)
	s_barrier
	s_load_dwordx2 s[4:5], s[0:1], 0xd0
	s_waitcnt lgkmcnt(0)
	s_add_u32 s4, s4, s34
	s_addc_u32 s5, s5, s35
	s_lshl_b32 s8, s66, 15
	s_add_u32 s4, s4, s8
	s_addc_u32 s5, s5, 0
	v_lshl_add_u64 v[36:37], s[4:5], 0, v[142:143]
	v_mov_b32_e32 v163, v3
	v_lshl_add_u64 v[40:41], v[36:37], 0, v[162:163]
	s_mov_b64 s[4:5], 0x256000
	v_lshl_add_u64 v[60:61], v[40:41], 0, s[4:5]
	s_mov_b32 s4, 0x256000
	v_add_co_u32_e32 v36, vcc, s4, v40
	v_add_u32_e32 v68, s26, v140
	s_nop 0
	v_addc_co_u32_e32 v37, vcc, 0, v41, vcc
	s_mov_b32 s4, 0x296000
	v_ashrrev_i32_e32 v69, 31, v68
	v_add_co_u32_e32 v64, vcc, s4, v40
	v_lshl_add_u64 v[68:69], s[18:19], 0, v[68:69]
	s_nop 0
	v_addc_co_u32_e32 v65, vcc, 0, v41, vcc
	v_lshlrev_b64 v[68:69], 2, v[68:69]
	global_load_dwordx4 v[36:39], v[36:37], off
	s_nop 0
	global_load_dwordx4 v[44:47], v[64:65], off
	global_load_dwordx4 v[40:43], v[60:61], off offset:64
	global_load_dwordx4 v[52:55], v[64:65], off offset:64
	global_load_dwordx4 v[48:51], v[60:61], off offset:128
	global_load_dwordx4 v[56:59], v[64:65], off offset:128
	s_nop 0
	global_load_dwordx4 v[60:63], v[60:61], off offset:192
	s_nop 0
	global_load_dwordx4 v[64:67], v[64:65], off offset:192
	s_load_dwordx2 s[4:5], s[0:1], 0x68
	s_waitcnt lgkmcnt(0)
	s_mov_b32 s27, s66
	v_lshl_add_u64 v[70:71], s[4:5], 0, v[68:69]
	global_load_dword v163, v[70:71], off
	s_load_dwordx2 s[4:5], s[0:1], 0x78
	s_waitcnt lgkmcnt(0)
	s_nop 0
	v_lshl_add_u64 v[70:71], s[4:5], 0, v[68:69]
	global_load_dword v235, v[70:71], off
	s_load_dwordx2 s[4:5], s[0:1], 0x80
	s_waitcnt lgkmcnt(0)
	s_nop 0
	v_lshl_add_u64 v[68:69], s[4:5], 0, v[68:69]
	global_load_dword v68, v[68:69], off
	s_mov_b32 s4, 0xbfb8aa3b
	s_waitcnt vmcnt(0) lgkmcnt(0)
	v_mul_f32_e32 v69, 0xbfb8aa3b, v68
	v_fma_f32 v70, v68, s4, -v69
	v_rndne_f32_e32 v71, v69
	v_fmac_f32_e32 v70, 0xb2a5705f, v68
	v_sub_f32_e32 v69, v69, v71
	v_add_f32_e32 v69, v69, v70
	v_exp_f32_e32 v69, v69
	v_cvt_i32_f32_e32 v70, v71
	s_mov_b32 s4, 0x42ce8ed0
	v_cmp_nlt_f32_e32 vcc, s4, v68
	s_mov_b32 s4, 0xc2b17218
	v_ldexp_f32 v69, v69, v70
	v_cndmask_b32_e32 v69, 0, v69, vcc
	v_cmp_ngt_f32_e32 vcc, s4, v68
	s_mov_b32 s4, 0x3f2aaaab
	s_nop 0
	v_cndmask_b32_e32 v68, v222, v69, vcc
	v_add_f32_e32 v69, 1.0, v68
	v_add_f32_e32 v70, -1.0, v69
	v_sub_f32_e32 v71, v70, v69
	v_add_f32_e32 v71, 1.0, v71
	v_sub_f32_e32 v70, v68, v70
	v_add_f32_e32 v72, v70, v71
	v_frexp_mant_f32_e32 v70, v69
	v_cmp_gt_f32_e32 vcc, s4, v70
	v_cvt_f64_f32_e32 v[70:71], v69
	v_frexp_exp_i32_f64_e32 v70, v[70:71]
	v_subbrev_co_u32_e32 v78, vcc, 0, v70, vcc
	v_sub_u32_e32 v70, 0, v78
	v_ldexp_f32 v69, v69, v70
	v_ldexp_f32 v70, v72, v70
	v_add_f32_e32 v72, -1.0, v69
	v_add_f32_e32 v71, 1.0, v72
	v_sub_f32_e32 v71, v69, v71
	v_add_f32_e32 v73, v70, v71
	v_add_f32_e32 v71, 1.0, v69
	v_add_f32_e32 v74, -1.0, v71
	v_sub_f32_e32 v69, v69, v74
	v_add_f32_e32 v69, v70, v69
	v_add_f32_e32 v79, v71, v69
	v_rcp_f32_e32 v80, v79
	v_sub_f32_e32 v70, v71, v79
	v_add_f32_e32 v71, v72, v73
	v_add_f32_e32 v69, v69, v70
	v_mul_f32_e32 v82, v71, v80
	v_sub_f32_e32 v70, v72, v71
	v_mul_f32_e32 v72, v79, v82
	v_fma_f32 v74, v82, v79, -v72
	v_fmac_f32_e32 v74, v82, v69
	v_add_f32_e32 v81, v73, v70
	v_add_f32_e32 v70, v72, v74
	v_sub_f32_e32 v73, v71, v70
	v_pk_add_f32 v[76:77], v[70:71], v[72:73] neg_lo:[0,1] neg_hi:[0,1]
	v_mov_b32_e32 v75, v70
	v_pk_add_f32 v[70:71], v[76:77], v[74:75] neg_lo:[0,1] neg_hi:[0,1]
	s_mov_b32 s4, 0x3f317218
	v_add_f32_e32 v71, v81, v71
	v_add_f32_e32 v70, v70, v71
	v_add_f32_e32 v71, v73, v70
	v_mul_f32_e32 v81, v80, v71
	v_mul_f32_e32 v72, v79, v81
	v_fma_f32 v74, v81, v79, -v72
	v_fmac_f32_e32 v74, v81, v69
	v_sub_f32_e32 v69, v73, v71
	v_add_f32_e32 v69, v70, v69
	v_add_f32_e32 v70, v72, v74
	v_sub_f32_e32 v73, v71, v70
	v_pk_add_f32 v[76:77], v[70:71], v[72:73] neg_lo:[0,1] neg_hi:[0,1]
	v_mov_b32_e32 v75, v70
	v_pk_add_f32 v[70:71], v[76:77], v[74:75] neg_lo:[0,1] neg_hi:[0,1]
	s_nop 0
	v_add_f32_e32 v69, v69, v71
	v_add_f32_e32 v69, v70, v69
	v_add_f32_e32 v71, v82, v81
	v_add_f32_e32 v69, v73, v69
	v_sub_f32_e32 v70, v71, v82
	v_mul_f32_e32 v69, v80, v69
	v_sub_f32_e32 v70, v81, v70
	v_add_f32_e32 v69, v70, v69
	v_add_f32_e32 v72, v71, v69
	v_mul_f32_e32 v74, v72, v72
	v_mov_b32_e32 v70, 0x3ecc95a3
	v_fmamk_f32 v70, v74, 0x3e9b6dac, v70
	v_fmaak_f32 v197, v74, v70, 0x3f2aaada
	v_cvt_f32_i32_e32 v70, v78
	v_sub_f32_e32 v71, v72, v71
	v_sub_f32_e32 v69, v69, v71
	v_mul_f32_e32 v71, v72, v74
	v_pk_mul_f32 v[74:75], v[70:71], v[196:197]
	v_ldexp_f32 v73, v72, 1
	v_fma_f32 v72, v70, s4, -v74
	v_fmac_f32_e32 v72, 0xb102e308, v70
	v_pk_add_f32 v[70:71], v[74:75], v[72:73]
	v_ldexp_f32 v69, v69, 1
	v_sub_f32_e32 v73, v71, v73
	v_sub_f32_e32 v73, v75, v73
	v_add_f32_e32 v77, v69, v73
	v_mov_b32_e32 v76, v74
	v_pk_add_f32 v[74:75], v[70:71], v[74:75] neg_lo:[0,1] neg_hi:[0,1]
	v_pk_add_f32 v[78:79], v[70:71], v[76:77]
	v_mov_b32_e32 v73, v70
	v_mov_b32_e32 v75, v79
	v_pk_add_f32 v[80:81], v[72:73], v[74:75] neg_lo:[0,1] neg_hi:[0,1]
	v_pk_add_f32 v[72:73], v[72:73], v[74:75]
	v_mov_b32_e32 v76, v77
	v_pk_add_f32 v[74:75], v[72:73], v[70:71] op_sel:[1,0] op_sel_hi:[0,1] neg_lo:[0,1] neg_hi:[0,1]
	v_pk_add_f32 v[82:83], v[78:79], v[74:75] op_sel_hi:[1,0] neg_lo:[0,1] neg_hi:[0,1]
	v_mov_b32_e32 v78, v79
	v_mov_b32_e32 v79, v73
	v_pk_mov_b32 v[74:75], v[70:71], v[74:75] op_sel:[1,0]
	v_mov_b32_e32 v77, v70
	v_pk_add_f32 v[74:75], v[78:79], v[74:75] neg_lo:[0,1] neg_hi:[0,1]
	v_mov_b32_e32 v82, v80
	v_pk_add_f32 v[70:71], v[76:77], v[74:75] neg_lo:[0,1] neg_hi:[0,1]
	v_mov_b32_e32 v81, v73
	v_pk_add_f32 v[74:75], v[82:83], v[70:71]
	s_mov_b32 s4, 0x7f800000
	v_pk_add_f32 v[76:77], v[74:75], v[74:75] op_sel:[0,1] op_sel_hi:[1,0]
	v_cmp_neq_f32_e32 vcc, s4, v68
	v_pk_add_f32 v[72:73], v[72:73], v[76:77] op_sel:[1,0] op_sel_hi:[0,1]
	v_mov_b32_e32 v75, v72
	v_pk_add_f32 v[78:79], v[74:75], v[80:81] neg_lo:[0,1] neg_hi:[0,1]
	v_mov_b32_e32 v71, v76
	v_sub_f32_e32 v69, v74, v78
	v_pk_add_f32 v[70:71], v[70:71], v[78:79] neg_lo:[0,1] neg_hi:[0,1]
	v_sub_f32_e32 v69, v80, v69
	v_add_f32_e32 v69, v70, v69
	v_add_f32_e32 v69, v69, v71
	v_add_f32_e32 v69, v72, v69
	s_mov_b32 s4, 0x33800000
	v_cndmask_b32_e32 v69, v222, v69, vcc
	v_cmp_lt_f32_e64 vcc, |v68|, s4
	s_nop 1
	v_cndmask_b32_e32 v68, v69, v68, vcc
	v_mul_f32_e32 v197, 0x41000000, v68

; template <int I> DI const float* kin() { return (const float*)karg64<I * 8>(); }
; DI float bflo(unsigned w) { return __uint_as_float(w << 16); }
; DI float bfhi(unsigned w) { return __uint_as_float(w & 0xffff0000u); }
; DI void lru_local_phase(const Ctx& c, int l) {
;     ...
;             for (int k = 0; k < 4; ++k) {
;                 const int ts = tt - 3 + k;
;                 f32x4 x0, x1;
;                 if (ts >= 0 || (!smp && !first)) { const u32x4 v = pre[hh][k];
;                     x0 = (f32x4){bflo(v.x), bfhi(v.x), bflo(v.y), bfhi(v.y)}; x1 = (f32x4){bflo(v.z), bfhi(v.z), bflo(v.w), bfhi(v.w)};
;                 } else if (smp) {
;                     const float* sp = kin<2>() + (((size_t)l * 32 + bs) * 3 + (3 + ts)) * 1024 + ch0 + 8 * cg;
;                     x0 = *(const f32x4*)sp; x1 = *(const f32x4*)(sp + 4);
;                 } else { x0 = (f32x4){0.f, 0.f, 0.f, 0.f}; x1 = x0; }
.LBB0_368:
	s_or_saveexec_b64 s[94:95], s[64:65]
	s_mul_i32 s66, s66, 3
	s_mul_hi_u32 s64, s5, 3
	v_cndmask_b32_e64 v84, 0, 1, s[8:9]
	s_add_i32 s73, s64, s66
	s_mul_i32 s72, s5, 3
	v_cmp_ne_u32_e64 s[64:65], 1, v84
	s_xor_b64 exec, exec, s[94:95]
	s_cbranch_execz .LBB0_371
	v_mov_b32_e32 v79, 0
	s_and_b64 vcc, exec, s[64:65]
	v_mov_b32_e32 v78, 0
	v_mov_b32_e32 v77, 0
	v_mov_b32_e32 v76, 0
	v_mov_b32_e32 v83, 0
	v_mov_b32_e32 v82, 0
	v_mov_b32_e32 v81, 0
	v_mov_b32_e32 v80, 0
	s_cbranch_vccnz .LBB0_371
	v_lshl_add_u64 v[76:77], s[72:73], 0, v[134:135]
	s_load_dwordx2 s[66:67], s[0:1], 16
	s_waitcnt lgkmcnt(0)
	v_lshlrev_b64 v[76:77], 12, v[76:77]
	v_lshl_add_u64 v[76:77], s[66:67], 0, v[76:77]
	s_lshl_b32 s66, s26, 2
	s_mov_b32 s67, s13
	v_lshl_add_u64 v[76:77], v[76:77], 0, s[66:67]
	v_mov_b32_e32 v145, v3
	v_lshl_add_u64 v[80:81], v[76:77], 0, v[144:145]
	global_load_dwordx4 v[76:79], v[80:81], off
	s_nop 0
	global_load_dwordx4 v[80:83], v[80:81], off offset:16

; template <int I> DI const float* kin() { return (const float*)karg64<I * 8>(); }
; DI float bflo(unsigned w) { return __uint_as_float(w << 16); }
; DI float bfhi(unsigned w) { return __uint_as_float(w & 0xffff0000u); }
; DI void lru_local_phase(const Ctx& c, int l) {
;     ...
;             for (int k = 0; k < 4; ++k) {
;                 const int ts = tt - 3 + k;
;                 f32x4 x0, x1;
;                 if (ts >= 0 || (!smp && !first)) { const u32x4 v = pre[hh][k];
;                     x0 = (f32x4){bflo(v.x), bfhi(v.x), bflo(v.y), bfhi(v.y)}; x1 = (f32x4){bflo(v.z), bfhi(v.z), bflo(v.w), bfhi(v.w)};
;                 } else if (smp) {
;                     const float* sp = kin<2>() + (((size_t)l * 32 + bs) * 3 + (3 + ts)) * 1024 + ch0 + 8 * cg;
;                     x0 = *(const f32x4*)sp; x1 = *(const f32x4*)(sp + 4);
;                 } else { x0 = (f32x4){0.f, 0.f, 0.f, 0.f}; x1 = x0; }
.LBB0_373:
	s_andn2_saveexec_b64 s[94:95], s[94:95]
	s_cbranch_execz .LBB0_376
	v_mov_b32_e32 v95, 0
	s_and_b64 vcc, exec, s[64:65]
	v_mov_b32_e32 v94, 0
	v_mov_b32_e32 v93, 0
	v_mov_b32_e32 v92, 0
	v_mov_b32_e32 v99, 0
	v_mov_b32_e32 v98, 0
	v_mov_b32_e32 v97, 0
	v_mov_b32_e32 v96, 0
	s_cbranch_vccnz .LBB0_376
	v_lshl_add_u64 v[92:93], s[72:73], 0, v[146:147]
	s_load_dwordx2 s[66:67], s[0:1], 16
	s_waitcnt lgkmcnt(0)
	v_lshlrev_b64 v[92:93], 12, v[92:93]
	v_lshl_add_u64 v[92:93], s[66:67], 0, v[92:93]
	s_lshl_b32 s66, s26, 2
	s_mov_b32 s67, s13
	v_lshl_add_u64 v[92:93], v[92:93], 0, s[66:67]
	v_mov_b32_e32 v145, v3
	v_lshl_add_u64 v[96:97], v[92:93], 0, v[144:145]
	global_load_dwordx4 v[92:95], v[96:97], off
	s_nop 0
	global_load_dwordx4 v[96:99], v[96:97], off offset:16

; template <int I> DI const float* kin() { return (const float*)karg64<I * 8>(); }
; DI float bflo(unsigned w) { return __uint_as_float(w << 16); }
; DI float bfhi(unsigned w) { return __uint_as_float(w & 0xffff0000u); }
; DI void lru_local_phase(const Ctx& c, int l) {
;     ...
;             for (int k = 0; k < 4; ++k) {
;                 const int ts = tt - 3 + k;
;                 f32x4 x0, x1;
;                 if (ts >= 0 || (!smp && !first)) { const u32x4 v = pre[hh][k];
;                     x0 = (f32x4){bflo(v.x), bfhi(v.x), bflo(v.y), bfhi(v.y)}; x1 = (f32x4){bflo(v.z), bfhi(v.z), bflo(v.w), bfhi(v.w)};
;                 } else if (smp) {
;                     const float* sp = kin<2>() + (((size_t)l * 32 + bs) * 3 + (3 + ts)) * 1024 + ch0 + 8 * cg;
;                     x0 = *(const f32x4*)sp; x1 = *(const f32x4*)(sp + 4);
;                 } else { x0 = (f32x4){0.f, 0.f, 0.f, 0.f}; x1 = x0; }
.LBB0_378:
	s_andn2_saveexec_b64 s[94:95], s[94:95]
	s_cbranch_execz .LBB0_381
	v_mov_b32_e32 v107, 0
	s_and_b64 vcc, exec, s[64:65]
	v_mov_b32_e32 v106, 0
	v_mov_b32_e32 v105, 0
	v_mov_b32_e32 v104, 0
	v_mov_b32_e32 v115, 0
	v_mov_b32_e32 v114, 0
	v_mov_b32_e32 v113, 0
	v_mov_b32_e32 v112, 0
	s_cbranch_vccnz .LBB0_381
	v_lshl_add_u64 v[104:105], s[72:73], 0, v[148:149]
	s_load_dwordx2 s[66:67], s[0:1], 16
	s_waitcnt lgkmcnt(0)
	v_lshlrev_b64 v[104:105], 12, v[104:105]
	v_lshl_add_u64 v[104:105], s[66:67], 0, v[104:105]
	s_lshl_b32 s66, s26, 2
	s_mov_b32 s67, s13
	v_lshl_add_u64 v[104:105], v[104:105], 0, s[66:67]
	v_mov_b32_e32 v145, v3
	v_lshl_add_u64 v[112:113], v[104:105], 0, v[144:145]
	global_load_dwordx4 v[104:107], v[112:113], off
	s_nop 0
	global_load_dwordx4 v[112:115], v[112:113], off offset:16

; #define LAS __attribute__((address_space(3)))
; template <int I> DI const float* kin() { return (const float*)karg64<I * 8>(); }
; DI float bflo(unsigned w) { return __uint_as_float(w << 16); }
; DI float bfhi(unsigned w) { return __uint_as_float(w & 0xffff0000u); }
; DI unsigned pk2(float a, float b) { f32x2 v = {a, b}; bf16v2 r = __builtin_convertvector(v, bf16v2); return __builtin_bit_cast(unsigned, r); }
; DI void lru_local_phase(const Ctx& c, int l) {
;     ...
; #pragma unroll
;         for (int hh = 0; hh < 2; ++hh) {
;             const int tt = tk + 32 * hh;
;             f32x4 a0 = *(const LAS f32x4*)(cwl + 512 + 8 * cg), a1 = *(const LAS f32x4*)(cwl + 512 + 8 * cg + 4);
; #pragma unroll
;             for (int k = 0; k < 4; ++k) {
;                 const int ts = tt - 3 + k;
;                 f32x4 x0, x1;
;                 if (ts >= 0 || (!smp && !first)) { const u32x4 v = pre[hh][k];
;                     x0 = (f32x4){bflo(v.x), bfhi(v.x), bflo(v.y), bfhi(v.y)}; x1 = (f32x4){bflo(v.z), bfhi(v.z), bflo(v.w), bfhi(v.w)};
;                 } else if (smp) {
;                     const float* sp = kin<2>() + (((size_t)l * 32 + bs) * 3 + (3 + ts)) * 1024 + ch0 + 8 * cg;
;                     x0 = *(const f32x4*)sp; x1 = *(const f32x4*)(sp + 4);
;                 } else { x0 = (f32x4){0.f, 0.f, 0.f, 0.f}; x1 = x0; }
;                 a0 += *(const LAS f32x4*)(cwl + k * 128 + 8 * cg) * x0; a1 += *(const LAS f32x4*)(cwl + k * 128 + 8 * cg + 4) * x1;
;             }
;             *(LAS f32x4*)(uf + tt * 132 + 8 * cg) = a0; *(LAS f32x4*)(uf + tt * 132 + 8 * cg + 4) = a1;
;             u32x4 pw; pw.x = pk2(a0[0], a0[1]); pw.y = pk2(a0[2], a0[3]); pw.z = pk2(a1[0], a1[1]); pw.w = pk2(a1[2], a1[3]);
;             *(LAS u32x4*)(ub + tt * 272 + 16 * cg) = pw;
;         }
.LBB0_383:
	s_andn2_saveexec_b64 s[94:95], s[94:95]
	s_cbranch_execz .LBB0_386
	v_mov_b32_e32 v127, 0
	s_and_b64 vcc, exec, s[64:65]
	v_mov_b32_e32 v126, 0
	v_mov_b32_e32 v125, 0
	v_mov_b32_e32 v124, 0
	v_mov_b32_e32 v131, 0
	v_mov_b32_e32 v130, 0
	v_mov_b32_e32 v129, 0
	v_mov_b32_e32 v128, 0
	s_cbranch_vccnz .LBB0_386
	v_lshl_add_u64 v[124:125], s[72:73], 0, v[150:151]
	s_load_dwordx2 s[66:67], s[0:1], 16
	s_waitcnt lgkmcnt(0)
	v_lshlrev_b64 v[124:125], 12, v[124:125]
	v_lshl_add_u64 v[124:125], s[66:67], 0, v[124:125]
	s_lshl_b32 s66, s26, 2
	s_mov_b32 s67, s13
	v_lshl_add_u64 v[124:125], v[124:125], 0, s[66:67]
	v_mov_b32_e32 v145, v3
	v_lshl_add_u64 v[128:129], v[124:125], 0, v[144:145]
	global_load_dwordx4 v[124:127], v[128:129], off
	s_nop 0
	global_load_dwordx4 v[128:131], v[128:129], off offset:16
.LBB0_386:
	s_or_b64 exec, exec, s[94:95]
	s_waitcnt vmcnt(0) lgkmcnt(0)
	v_pk_fma_f32 v[74:75], v[78:79], v[90:91], v[74:75]
	v_pk_fma_f32 v[72:73], v[76:77], v[88:89], v[72:73]
	v_pk_fma_f32 v[70:71], v[82:83], v[86:87], v[70:71]
	v_pk_fma_f32 v[68:69], v[80:81], v[84:85], v[68:69]
	v_pk_fma_f32 v[74:75], v[94:95], v[110:111], v[74:75]
	v_pk_fma_f32 v[72:73], v[92:93], v[108:109], v[72:73]
	v_pk_fma_f32 v[76:77], v[98:99], v[102:103], v[70:71]
	v_pk_fma_f32 v[78:79], v[96:97], v[100:101], v[68:69]
	v_pk_fma_f32 v[80:81], v[106:107], v[122:123], v[74:75]
	ds_read_b128 v[68:71], v173 offset:1536
	v_pk_fma_f32 v[82:83], v[104:105], v[120:121], v[72:73]
	ds_read_b128 v[72:75], v173 offset:1552
	v_pk_fma_f32 v[76:77], v[114:115], v[118:119], v[76:77]
	v_pk_fma_f32 v[78:79], v[112:113], v[116:117], v[78:79]
	s_waitcnt lgkmcnt(1)
	v_pk_fma_f32 v[70:71], v[126:127], v[70:71], v[80:81]
	v_pk_fma_f32 v[68:69], v[124:125], v[68:69], v[82:83]
	s_waitcnt lgkmcnt(0)
	v_pk_fma_f32 v[74:75], v[130:131], v[74:75], v[76:77]
	v_pk_fma_f32 v[72:73], v[128:129], v[72:73], v[78:79]
	ds_write_b128 v233, v[68:71]
	ds_write_b128 v233, v[72:75] offset:16
	v_cvt_pk_bf16_f32 v68, v68, v69
	v_cvt_pk_bf16_f32 v69, v70, v71
	v_cvt_pk_bf16_f32 v70, v72, v73
	v_cvt_pk_bf16_f32 v71, v74, v75
	ds_write_b128 v234, v[68:71] offset:33792
	ds_read_b128 v[72:75], v141
	ds_read_b128 v[68:71], v141 offset:16
	s_and_b64 s[66:67], s[48:49], s[88:89]
	s_xor_b64 s[66:67], s[66:67], -1
	s_and_saveexec_b64 s[78:79], s[66:67]
	s_xor_b64 s[94:95], exec, s[78:79]
	v_lshlrev_b32_e32 v76, 16, v20
	v_and_b32_e32 v77, 0xffff0000, v20
	v_lshlrev_b32_e32 v78, 16, v21
	v_and_b32_e32 v79, 0xffff0000, v21
	v_lshlrev_b32_e32 v80, 16, v22
	v_and_b32_e32 v81, 0xffff0000, v22
	v_lshlrev_b32_e32 v82, 16, v23
	v_and_b32_e32 v83, 0xffff0000, v23
	s_andn2_saveexec_b64 s[94:95], s[94:95]
	s_cbranch_execz .LBB0_391
	v_mov_b32_e32 v79, 0
	s_and_b64 vcc, exec, s[64:65]
	v_mov_b32_e32 v78, 0
	v_mov_b32_e32 v77, 0
	v_mov_b32_e32 v76, 0
	v_mov_b32_e32 v83, 0
	v_mov_b32_e32 v82, 0
	v_mov_b32_e32 v81, 0
	v_mov_b32_e32 v80, 0
	s_cbranch_vccnz .LBB0_391
	v_lshl_add_u64 v[76:77], s[72:73], 0, v[136:137]
	s_load_dwordx2 s[66:67], s[0:1], 16
	s_waitcnt lgkmcnt(0)
	v_lshlrev_b64 v[76:77], 12, v[76:77]
	v_lshl_add_u64 v[76:77], s[66:67], 0, v[76:77]
	s_lshl_b32 s66, s26, 2
	s_mov_b32 s67, s13
	v_lshl_add_u64 v[76:77], v[76:77], 0, s[66:67]
	v_mov_b32_e32 v145, v3
	v_lshl_add_u64 v[80:81], v[76:77], 0, v[144:145]
	global_load_dwordx4 v[76:79], v[80:81], off
	s_nop 0
	global_load_dwordx4 v[80:83], v[80:81], off offset:16
.LBB0_391:
	s_or_b64 exec, exec, s[94:95]
	ds_read_b128 v[88:91], v173
	ds_read_b128 v[84:87], v173 offset:16
	s_and_b64 s[66:67], s[50:51], s[88:89]
	s_xor_b64 s[66:67], s[66:67], -1
	s_and_saveexec_b64 s[78:79], s[66:67]
	s_xor_b64 s[94:95], exec, s[78:79]
	v_lshlrev_b32_e32 v92, 16, v24
	v_and_b32_e32 v93, 0xffff0000, v24
	v_lshlrev_b32_e32 v94, 16, v25
	v_and_b32_e32 v95, 0xffff0000, v25
	v_lshlrev_b32_e32 v96, 16, v26
	v_and_b32_e32 v97, 0xffff0000, v26
	v_lshlrev_b32_e32 v98, 16, v27
	v_and_b32_e32 v99, 0xffff0000, v27
	s_andn2_saveexec_b64 s[94:95], s[94:95]
	s_cbranch_execz .LBB0_396
	v_mov_b32_e32 v95, 0
	s_and_b64 vcc, exec, s[64:65]
	v_mov_b32_e32 v94, 0
	v_mov_b32_e32 v93, 0
	v_mov_b32_e32 v92, 0
	v_mov_b32_e32 v99, 0
	v_mov_b32_e32 v98, 0
	v_mov_b32_e32 v97, 0
	v_mov_b32_e32 v96, 0
	s_cbranch_vccnz .LBB0_396
	v_lshl_add_u64 v[92:93], s[72:73], 0, v[152:153]
	s_load_dwordx2 s[66:67], s[0:1], 16
	s_waitcnt lgkmcnt(0)
	v_lshlrev_b64 v[92:93], 12, v[92:93]
	v_lshl_add_u64 v[92:93], s[66:67], 0, v[92:93]
	s_lshl_b32 s66, s26, 2
	s_mov_b32 s67, s13
	v_lshl_add_u64 v[92:93], v[92:93], 0, s[66:67]
	v_mov_b32_e32 v145, v3
	v_lshl_add_u64 v[96:97], v[92:93], 0, v[144:145]
	global_load_dwordx4 v[92:95], v[96:97], off
	s_nop 0
	global_load_dwordx4 v[96:99], v[96:97], off offset:16
.LBB0_396:
	s_or_b64 exec, exec, s[94:95]
	ds_read_b128 v[108:111], v173 offset:512
	ds_read_b128 v[100:103], v173 offset:528
	s_and_b64 s[66:67], s[52:53], s[88:89]
	s_xor_b64 s[66:67], s[66:67], -1
	s_and_saveexec_b64 s[78:79], s[66:67]
	s_xor_b64 s[94:95], exec, s[78:79]
	v_lshlrev_b32_e32 v104, 16, v28
	v_and_b32_e32 v105, 0xffff0000, v28
	v_lshlrev_b32_e32 v106, 16, v29
	v_and_b32_e32 v107, 0xffff0000, v29
	v_lshlrev_b32_e32 v112, 16, v30
	v_and_b32_e32 v113, 0xffff0000, v30
	v_lshlrev_b32_e32 v114, 16, v31
	v_and_b32_e32 v115, 0xffff0000, v31
	s_andn2_saveexec_b64 s[94:95], s[94:95]
	s_cbranch_execz .LBB0_401
	v_mov_b32_e32 v107, 0
	s_and_b64 vcc, exec, s[64:65]
	v_mov_b32_e32 v106, 0
	v_mov_b32_e32 v105, 0
	v_mov_b32_e32 v104, 0
	v_mov_b32_e32 v115, 0
	v_mov_b32_e32 v114, 0
	v_mov_b32_e32 v113, 0
	v_mov_b32_e32 v112, 0
	s_cbranch_vccnz .LBB0_401
	v_lshl_add_u64 v[104:105], s[72:73], 0, v[154:155]
	s_load_dwordx2 s[66:67], s[0:1], 16
	s_waitcnt lgkmcnt(0)
	v_lshlrev_b64 v[104:105], 12, v[104:105]
	v_lshl_add_u64 v[104:105], s[66:67], 0, v[104:105]
	s_lshl_b32 s66, s26, 2
	s_mov_b32 s67, s13
	v_lshl_add_u64 v[104:105], v[104:105], 0, s[66:67]
	v_mov_b32_e32 v145, v3
	v_lshl_add_u64 v[112:113], v[104:105], 0, v[144:145]
	global_load_dwordx4 v[104:107], v[112:113], off
	s_nop 0
	global_load_dwordx4 v[112:115], v[112:113], off offset:16
; #define LAS __attribute__((address_space(3)))
; template <int I> DI const float* kin() { return (const float*)karg64<I * 8>(); }
; DI float bflo(unsigned w) { return __uint_as_float(w << 16); }
; DI float bfhi(unsigned w) { return __uint_as_float(w & 0xffff0000u); }
; DI unsigned pk2(float a, float b) { f32x2 v = {a, b}; bf16v2 r = __builtin_convertvector(v, bf16v2); return __builtin_bit_cast(unsigned, r); }
; DI void lru_local_phase(const Ctx& c, int l) {
;     ...
; #pragma unroll
;         for (int hh = 0; hh < 2; ++hh) {
;             const int tt = tk + 32 * hh;
;             f32x4 a0 = *(const LAS f32x4*)(cwl + 512 + 8 * cg), a1 = *(const LAS f32x4*)(cwl + 512 + 8 * cg + 4);
; #pragma unroll
;             for (int k = 0; k < 4; ++k) {
;                 const int ts = tt - 3 + k;
;                 f32x4 x0, x1;
;                 if (ts >= 0 || (!smp && !first)) { const u32x4 v = pre[hh][k];
;                     x0 = (f32x4){bflo(v.x), bfhi(v.x), bflo(v.y), bfhi(v.y)}; x1 = (f32x4){bflo(v.z), bfhi(v.z), bflo(v.w), bfhi(v.w)};
;                 } else if (smp) {
;                     const float* sp = kin<2>() + (((size_t)l * 32 + bs) * 3 + (3 + ts)) * 1024 + ch0 + 8 * cg;
;                     x0 = *(const f32x4*)sp; x1 = *(const f32x4*)(sp + 4);
;                 } else { x0 = (f32x4){0.f, 0.f, 0.f, 0.f}; x1 = x0; }
;                 a0 += *(const LAS f32x4*)(cwl + k * 128 + 8 * cg) * x0; a1 += *(const LAS f32x4*)(cwl + k * 128 + 8 * cg + 4) * x1;
;             }
;             *(LAS f32x4*)(uf + tt * 132 + 8 * cg) = a0; *(LAS f32x4*)(uf + tt * 132 + 8 * cg + 4) = a1;
;             u32x4 pw; pw.x = pk2(a0[0], a0[1]); pw.y = pk2(a0[2], a0[3]); pw.z = pk2(a1[0], a1[1]); pw.w = pk2(a1[2], a1[3]);
;             *(LAS u32x4*)(ub + tt * 272 + 16 * cg) = pw;
;         }
;         if (u + c.G < nunits) LRU_PREFETCH(u + c.G);
.LBB0_401:
	s_or_b64 exec, exec, s[94:95]
	ds_read_b128 v[120:123], v173 offset:1024
	ds_read_b128 v[116:119], v173 offset:1040
	s_and_b64 s[66:67], s[54:55], s[88:89]
	s_xor_b64 s[66:67], s[66:67], -1
	s_and_saveexec_b64 s[78:79], s[66:67]
	s_xor_b64 s[88:89], exec, s[78:79]
	v_lshlrev_b32_e32 v124, 16, v32
	v_and_b32_e32 v125, 0xffff0000, v32
	v_lshlrev_b32_e32 v126, 16, v33
	v_and_b32_e32 v127, 0xffff0000, v33
	v_lshlrev_b32_e32 v128, 16, v34
	v_and_b32_e32 v129, 0xffff0000, v34
	v_lshlrev_b32_e32 v130, 16, v35
	v_and_b32_e32 v131, 0xffff0000, v35
	s_andn2_saveexec_b64 s[88:89], s[88:89]
	s_cbranch_execz .LBB0_406
	v_mov_b32_e32 v127, 0
	s_and_b64 vcc, exec, s[64:65]
	v_mov_b32_e32 v126, 0
	v_mov_b32_e32 v125, 0
	v_mov_b32_e32 v124, 0
	v_mov_b32_e32 v131, 0
	v_mov_b32_e32 v130, 0
	v_mov_b32_e32 v129, 0
	v_mov_b32_e32 v128, 0
	s_cbranch_vccnz .LBB0_406
	v_lshl_add_u64 v[124:125], s[72:73], 0, v[156:157]
	s_load_dwordx2 s[64:65], s[0:1], 16
	s_waitcnt lgkmcnt(0)
	v_lshlrev_b64 v[124:125], 12, v[124:125]
	v_lshl_add_u64 v[124:125], s[64:65], 0, v[124:125]
	s_lshl_b32 s64, s26, 2
	s_mov_b32 s65, s13
	v_lshl_add_u64 v[124:125], v[124:125], 0, s[64:65]
	v_mov_b32_e32 v145, v3
	v_lshl_add_u64 v[128:129], v[124:125], 0, v[144:145]
	global_load_dwordx4 v[124:127], v[128:129], off
	s_nop 0
	global_load_dwordx4 v[128:131], v[128:129], off offset:16
.LBB0_406:
	s_or_b64 exec, exec, s[88:89]
	s_waitcnt vmcnt(0) lgkmcnt(0)
	v_pk_fma_f32 v[74:75], v[78:79], v[90:91], v[74:75]
	v_pk_fma_f32 v[72:73], v[76:77], v[88:89], v[72:73]
	v_pk_fma_f32 v[70:71], v[82:83], v[86:87], v[70:71]
	v_pk_fma_f32 v[68:69], v[80:81], v[84:85], v[68:69]
	v_pk_fma_f32 v[74:75], v[94:95], v[110:111], v[74:75]
	v_pk_fma_f32 v[72:73], v[92:93], v[108:109], v[72:73]
	v_pk_fma_f32 v[76:77], v[98:99], v[102:103], v[70:71]
	v_pk_fma_f32 v[78:79], v[96:97], v[100:101], v[68:69]
	v_pk_fma_f32 v[80:81], v[106:107], v[122:123], v[74:75]
	ds_read_b128 v[68:71], v173 offset:1536
	v_pk_fma_f32 v[82:83], v[104:105], v[120:121], v[72:73]
	ds_read_b128 v[72:75], v173 offset:1552
	s_add_i32 s23, s23, s81
	v_pk_fma_f32 v[76:77], v[114:115], v[118:119], v[76:77]
	v_pk_fma_f32 v[78:79], v[112:113], v[116:117], v[78:79]
	s_cmpk_gt_i32 s23, 0x8ff
	s_waitcnt lgkmcnt(1)
	v_pk_fma_f32 v[70:71], v[126:127], v[70:71], v[80:81]
	v_pk_fma_f32 v[68:69], v[124:125], v[68:69], v[82:83]
	s_waitcnt lgkmcnt(0)
	v_pk_fma_f32 v[74:75], v[130:131], v[74:75], v[76:77]
	v_pk_fma_f32 v[72:73], v[128:129], v[72:73], v[78:79]
	s_cselect_b64 s[64:65], -1, 0
	ds_write_b128 v233, v[68:71] offset:16896
	ds_write_b128 v233, v[72:75] offset:16912
	v_cvt_pk_bf16_f32 v68, v68, v69
	v_cvt_pk_bf16_f32 v69, v70, v71
	v_cvt_pk_bf16_f32 v70, v72, v73
	v_cvt_pk_bf16_f32 v71, v74, v75
	s_and_b64 vcc, exec, s[64:65]
	ds_write_b128 v234, v[68:71] offset:42496
	s_cbranch_vccnz .LBB0_424
	s_ashr_i32 s5, s23, 3
	s_cmpk_gt_i32 s5, 0xff
	s_cselect_b64 s[66:67], -1, 0
	s_and_b32 s71, s23, 0x3f8
	s_cmp_eq_u32 s71, 0
	s_cselect_b64 s[72:73], -1, 0
	s_or_b64 s[72:73], s[66:67], s[72:73]
	s_lshl_b32 s66, s23, 8
	s_and_b32 s66, s66, 0x700
	s_mov_b32 s67, s13
	v_lshl_add_u64 v[68:69], v[158:159], 0, s[66:67]
	s_and_b64 s[66:67], s[40:41], s[72:73]
	s_lshl_b32 s5, s5, 6
	s_xor_b64 s[66:67], s[66:67], -1
	s_and_saveexec_b64 s[88:89], s[66:67]
	s_cbranch_execz .LBB0_409
	v_add_u32_e32 v4, s5, v139
	v_mad_i64_i32 v[4:5], s[66:67], v4, s31, v[68:69]
	global_load_dwordx4 v[4:7], v[4:5], off
.LBB0_409:
	s_or_b64 exec, exec, s[88:89]
	s_and_b64 s[66:67], s[42:43], s[72:73]
	s_xor_b64 s[66:67], s[66:67], -1
	s_and_saveexec_b64 s[88:89], s[66:67]
	s_cbranch_execz .LBB0_411
	v_add_u32_e32 v8, s5, v167
	v_mad_i64_i32 v[8:9], s[66:67], v8, s31, v[68:69]
	global_load_dwordx4 v[8:11], v[8:9], off
.LBB0_411:
	s_or_b64 exec, exec, s[88:89]
	s_and_b64 s[66:67], s[44:45], s[72:73]
	s_xor_b64 s[66:67], s[66:67], -1
	s_and_saveexec_b64 s[88:89], s[66:67]
	s_cbranch_execz .LBB0_413
	v_add_u32_e32 v12, s5, v168
	v_mad_i64_i32 v[12:13], s[66:67], v12, s31, v[68:69]
	global_load_dwordx4 v[12:15], v[12:13], off
.LBB0_413:
	s_or_b64 exec, exec, s[88:89]
	s_and_b64 s[66:67], s[46:47], s[72:73]
	s_xor_b64 s[66:67], s[66:67], -1
	s_and_saveexec_b64 s[88:89], s[66:67]
	s_cbranch_execz .LBB0_415
	v_add_u32_e32 v16, s5, v134
	v_mad_i64_i32 v[16:17], s[66:67], v16, s31, v[68:69]
	global_load_dwordx4 v[16:19], v[16:17], off
.LBB0_415:
	s_or_b64 exec, exec, s[88:89]
	s_and_b64 s[66:67], s[48:49], s[72:73]
	s_xor_b64 s[66:67], s[66:67], -1
	s_and_saveexec_b64 s[88:89], s[66:67]
	s_cbranch_execz .LBB0_417
	v_add_u32_e32 v20, s5, v169
	v_mad_i64_i32 v[20:21], s[66:67], v20, s31, v[68:69]
	global_load_dwordx4 v[20:23], v[20:21], off
.LBB0_417:
	s_or_b64 exec, exec, s[88:89]
	s_and_b64 s[66:67], s[50:51], s[72:73]
	s_xor_b64 s[66:67], s[66:67], -1
	s_and_saveexec_b64 s[88:89], s[66:67]
	s_cbranch_execz .LBB0_419
	v_add_u32_e32 v24, s5, v170
	v_mad_i64_i32 v[24:25], s[66:67], v24, s31, v[68:69]
	global_load_dwordx4 v[24:27], v[24:25], off
.LBB0_419:
	s_or_b64 exec, exec, s[88:89]
	s_and_b64 s[66:67], s[52:53], s[72:73]
	s_xor_b64 s[66:67], s[66:67], -1
	s_and_saveexec_b64 s[88:89], s[66:67]
	s_cbranch_execz .LBB0_421
	v_add_u32_e32 v28, s5, v171
	v_mad_i64_i32 v[28:29], s[66:67], v28, s31, v[68:69]
	global_load_dwordx4 v[28:31], v[28:29], off
.LBB0_421:
	s_or_b64 exec, exec, s[88:89]
	s_and_b64 s[66:67], s[54:55], s[72:73]
	s_xor_b64 s[66:67], s[66:67], -1
	s_and_saveexec_b64 s[72:73], s[66:67]
	s_cbranch_execz .LBB0_423
	v_add_u32_e32 v32, s5, v136
	v_mad_i64_i32 v[32:33], s[66:67], v32, s31, v[68:69]
	global_load_dwordx4 v[32:35], v[32:33], off

; #define LAS __attribute__((address_space(3)))
; DI void lru_local_phase(const Ctx& c, int l) {
;     ...
;         __syncthreads();
;         {
;             f32x4 ar[4], ai[4];
; #pragma unroll
;             for (int mt = 0; mt < 4; ++mt) { ar[mt] = (f32x4){0.f, 0.f, 0.f, 0.f}; ai[mt] = ar[mt]; }
; #pragma unroll
;             for (int ks = 0; ks < 4; ++ks)
; #pragma unroll
;                 for (int mt = 0; mt < 4; ++mt) {
;                     const bf16x8 af = *(const LAS bf16x8*)(ub + (mt * 16 + fr) * 272 + (ks * 32 + fq * 8) * 2);
;                     ar[mt] = __builtin_amdgcn_mfma_f32_16x16x32_bf16(af, bwa[ks], ar[mt], 0, 0, 0);
;                     ai[mt] = __builtin_amdgcn_mfma_f32_16x16x32_bf16(af, bwx[ks], ai[mt], 0, 0, 0);
;                 }
;             const int chw = 16 * w + fr;
; #pragma unroll
;             for (int mt = 0; mt < 4; ++mt)
; #pragma unroll
;                 for (int j = 0; j < 4; ++j) {
;                     const int tok = mt * 16 + fq * 4 + j;
;                     const float r = __builtin_amdgcn_rcpf(1.0f + __expf(-(ar[mt][j] + ba))), ig = __builtin_amdgcn_rcpf(1.0f + __expf(-(ai[mt][j] + bx)));
;                     const float la = -c8 * r, a = __expf(la), x2 = 2.0f * la;
;                     const float omt = -x2 * (1.0f + x2 * (0.5f + x2 * (0.16666667f + x2 * (0.041666668f + x2 * (0.0083333338f + x2 * 0.0013888889f)))));
;                     const float om = x2 > -0.25f ? omt : 1.0f - a * a;
;                     const float bb = __builtin_amdgcn_sqrtf(om) * (ig * uf[tok * 132 + chw]);
;                     sa[tok * 128 + chw] = a; sb[tok * 128 + chw] = bb;
;                 }
.LBB0_424:
	s_waitcnt lgkmcnt(0)
	s_barrier
	ds_read_b128 v[68:71], v230 offset:33792
	ds_read_b128 v[100:103], v230 offset:33856
	ds_read_b128 v[76:79], v230 offset:38144
	ds_read_b128 v[84:87], v230 offset:42496
	ds_read_b128 v[92:95], v230 offset:46848
	s_mov_b32 s5, 0
	s_waitcnt lgkmcnt(0)
	v_mfma_f32_16x16x32_bf16 v[72:75], v[68:71], v[36:39], 0
	s_and_b64 s[66:67], s[56:57], s[8:9]
	v_mfma_f32_16x16x32_bf16 v[68:71], v[68:71], v[44:47], 0
	v_mfma_f32_16x16x32_bf16 v[72:75], v[100:103], v[40:43], v[72:75]
	v_mfma_f32_16x16x32_bf16 v[68:71], v[100:103], v[52:55], v[68:71]
	ds_read_b128 v[100:103], v230 offset:38208
	v_mfma_f32_16x16x32_bf16 v[80:83], v[76:79], v[36:39], 0
	v_mfma_f32_16x16x32_bf16 v[76:79], v[76:79], v[44:47], 0
	s_waitcnt lgkmcnt(0)
	v_mfma_f32_16x16x32_bf16 v[80:83], v[100:103], v[40:43], v[80:83]
	v_mfma_f32_16x16x32_bf16 v[76:79], v[100:103], v[52:55], v[76:79]
	ds_read_b128 v[100:103], v230 offset:42560
	v_mfma_f32_16x16x32_bf16 v[88:91], v[84:87], v[36:39], 0
	v_mfma_f32_16x16x32_bf16 v[84:87], v[84:87], v[44:47], 0
	s_waitcnt lgkmcnt(0)
	v_mfma_f32_16x16x32_bf16 v[88:91], v[100:103], v[40:43], v[88:91]
	v_mfma_f32_16x16x32_bf16 v[84:87], v[100:103], v[52:55], v[84:87]
	ds_read_b128 v[100:103], v230 offset:46912
	v_mfma_f32_16x16x32_bf16 v[96:99], v[92:95], v[36:39], 0
	v_mfma_f32_16x16x32_bf16 v[92:95], v[92:95], v[44:47], 0
	s_waitcnt lgkmcnt(0)
	v_mfma_f32_16x16x32_bf16 v[96:99], v[100:103], v[40:43], v[96:99]
	v_mfma_f32_16x16x32_bf16 v[92:95], v[100:103], v[52:55], v[92:95]
	ds_read_b128 v[100:103], v230 offset:33920
	s_waitcnt lgkmcnt(0)
	v_mfma_f32_16x16x32_bf16 v[72:75], v[100:103], v[48:51], v[72:75]
	v_mfma_f32_16x16x32_bf16 v[68:71], v[100:103], v[56:59], v[68:71]
	ds_read_b128 v[100:103], v230 offset:38272
	s_waitcnt lgkmcnt(0)
	v_mfma_f32_16x16x32_bf16 v[80:83], v[100:103], v[48:51], v[80:83]
	v_mfma_f32_16x16x32_bf16 v[76:79], v[100:103], v[56:59], v[76:79]
	ds_read_b128 v[100:103], v230 offset:42624
	s_waitcnt lgkmcnt(0)
	v_mfma_f32_16x16x32_bf16 v[104:107], v[100:103], v[48:51], v[88:91]
	v_mfma_f32_16x16x32_bf16 v[100:103], v[100:103], v[56:59], v[84:87]
	s_nop 2
	ds_read_b128 v[84:87], v230 offset:46976
	s_waitcnt lgkmcnt(0)
	v_mfma_f32_16x16x32_bf16 v[108:111], v[84:87], v[48:51], v[96:99]
	v_mfma_f32_16x16x32_bf16 v[112:115], v[84:87], v[56:59], v[92:95]
	ds_read_b128 v[84:87], v230 offset:33984
	s_waitcnt lgkmcnt(0)
	v_mfma_f32_16x16x32_bf16 v[92:95], v[84:87], v[64:67], v[68:71]
	s_nop 2
	ds_read_b128 v[68:71], v230 offset:38336
	s_nop 3
	v_add_f32_e32 v92, v235, v92
	v_mfma_f32_16x16x32_bf16 v[96:99], v[84:87], v[60:63], v[72:75]
	v_mul_f32_e32 v92, 0xbfb8aa3b, v92
	v_exp_f32_e32 v92, v92
	v_add_f32_e32 v93, v235, v93
	s_waitcnt lgkmcnt(0)
	v_mfma_f32_16x16x32_bf16 v[88:91], v[68:71], v[60:63], v[80:83]
	v_add_f32_e32 v92, 1.0, v92
	s_nop 1
	v_add_f32_e32 v96, v163, v96
	v_mul_f32_e32 v96, 0xbfb8aa3b, v96
	v_exp_f32_e32 v96, v96
	v_mfma_f32_16x16x32_bf16 v[84:87], v[68:71], v[64:67], v[76:79]
	ds_read_b128 v[68:71], v230 offset:42688
	v_rcp_f32_e32 v92, v92
	v_add_f32_e32 v96, 1.0, v96
	v_rcp_f32_e32 v96, v96
	s_waitcnt lgkmcnt(0)
	v_mfma_f32_16x16x32_bf16 v[76:79], v[68:71], v[64:67], v[100:103]
	v_mul_f32_e64 v96, v96, -v197
	s_nop 1
	v_mul_f32_e32 v100, 0x3fb8aa3b, v96
	v_add_f32_e32 v96, v96, v96
	v_fmamk_f32 v101, v96, 0x3ab60b61, v219
	v_exp_f32_e32 v100, v100
	v_fmaak_f32 v101, v96, v101, 0x3d2aaaab
	v_fmaak_f32 v101, v96, v101, 0x3e2aaaab
	v_fma_f32 v101, v96, v101, 0.5
	v_fma_f32 v101, v96, v101, 1.0
	v_mul_f32_e64 v101, v101, -v96
	v_cmp_lt_f32_e32 vcc, s76, v96
	v_fma_f32 v96, -v100, v100, 1.0
	v_mfma_f32_16x16x32_bf16 v[80:83], v[68:71], v[60:63], v[104:107]
	ds_read_b128 v[68:71], v230 offset:47040
	v_cndmask_b32_e32 v96, v96, v101, vcc
	ds_read_b32 v101, v231
	v_sqrt_f32_e32 v96, v96
	v_mul_f32_e32 v93, 0xbfb8aa3b, v93
	v_exp_f32_e32 v93, v93
	v_add_f32_e32 v88, v163, v88
	s_waitcnt lgkmcnt(0)
	v_mul_f32_e32 v92, v92, v101
	v_mul_f32_e32 v92, v92, v96
	ds_write_b32 v174, v100 offset:51200
	ds_write_b32 v175, v92
	v_add_f32_e32 v92, v163, v97
	v_mul_f32_e32 v92, 0xbfb8aa3b, v92
	v_exp_f32_e32 v92, v92
	v_add_f32_e32 v93, 1.0, v93
	v_rcp_f32_e32 v93, v93
	v_mul_f32_e32 v88, 0xbfb8aa3b, v88
	v_add_f32_e32 v92, 1.0, v92
	v_rcp_f32_e32 v92, v92
	v_exp_f32_e32 v88, v88
	v_add_f32_e32 v84, v235, v84
	v_mul_f32_e32 v84, 0xbfb8aa3b, v84
	v_mul_f32_e64 v92, v92, -v197
	v_mul_f32_e32 v96, 0x3fb8aa3b, v92
	v_add_f32_e32 v92, v92, v92
	v_fmamk_f32 v97, v92, 0x3ab60b61, v219
	v_exp_f32_e32 v96, v96
	v_fmaak_f32 v97, v92, v97, 0x3d2aaaab
	v_fmaak_f32 v97, v92, v97, 0x3e2aaaab
	v_fma_f32 v97, v92, v97, 0.5
	v_fma_f32 v97, v92, v97, 1.0
	v_mul_f32_e64 v97, v97, -v92
	v_cmp_lt_f32_e32 vcc, s76, v92
	v_fma_f32 v92, -v96, v96, 1.0
	v_add_f32_e32 v88, 1.0, v88
	v_cndmask_b32_e32 v92, v92, v97, vcc
	ds_read_b32 v97, v232
	v_sqrt_f32_e32 v92, v92
	v_rcp_f32_e32 v88, v88
	v_exp_f32_e32 v84, v84
	v_add_f32_e32 v85, v235, v85
	s_waitcnt lgkmcnt(0)
	v_mul_f32_e32 v93, v93, v97
	v_mul_f32_e32 v92, v93, v92
	ds_write_b32 v176, v96 offset:51200
	ds_write_b32 v177, v92
	v_add_f32_e32 v92, v163, v98
	v_mul_f32_e32 v92, 0xbfb8aa3b, v92
	v_exp_f32_e32 v92, v92
	v_add_f32_e32 v93, v235, v94
	v_mul_f32_e32 v93, 0xbfb8aa3b, v93
	v_exp_f32_e32 v93, v93
	v_add_f32_e32 v92, 1.0, v92
	v_rcp_f32_e32 v92, v92
	v_mul_f32_e64 v88, v88, -v197
	v_add_f32_e32 v93, 1.0, v93
	v_rcp_f32_e32 v93, v93
	v_mul_f32_e64 v92, v92, -v197
	v_mul_f32_e32 v94, 0x3fb8aa3b, v92
	v_add_f32_e32 v92, v92, v92
	v_fmamk_f32 v96, v92, 0x3ab60b61, v219
	v_exp_f32_e32 v94, v94
	v_fmaak_f32 v96, v92, v96, 0x3d2aaaab
	v_fmaak_f32 v96, v92, v96, 0x3e2aaaab
	v_fma_f32 v96, v92, v96, 0.5
	v_fma_f32 v96, v92, v96, 1.0
	v_mul_f32_e64 v96, v96, -v92
	v_cmp_lt_f32_e32 vcc, s76, v92
	v_fma_f32 v92, -v94, v94, 1.0
	v_add_f32_e32 v84, 1.0, v84
	v_cndmask_b32_e32 v92, v92, v96, vcc
	ds_read_b32 v96, v232 offset:528
	v_sqrt_f32_e32 v92, v92
	v_rcp_f32_e32 v84, v84
	v_mul_f32_e32 v85, 0xbfb8aa3b, v85
	v_exp_f32_e32 v85, v85
	s_waitcnt lgkmcnt(0)
; DI void lru_local_phase(const Ctx& c, int l) {
;     ...
;             const int chw = 16 * w + fr;
; #pragma unroll
;             for (int mt = 0; mt < 4; ++mt)
; #pragma unroll
;                 for (int j = 0; j < 4; ++j) {
;                     const int tok = mt * 16 + fq * 4 + j;
;                     const float r = __builtin_amdgcn_rcpf(1.0f + __expf(-(ar[mt][j] + ba))), ig = __builtin_amdgcn_rcpf(1.0f + __expf(-(ai[mt][j] + bx)));
;                     const float la = -c8 * r, a = __expf(la), x2 = 2.0f * la;
;                     const float omt = -x2 * (1.0f + x2 * (0.5f + x2 * (0.16666667f + x2 * (0.041666668f + x2 * (0.0083333338f + x2 * 0.0013888889f)))));
;                     const float om = x2 > -0.25f ? omt : 1.0f - a * a;
;                     const float bb = __builtin_amdgcn_sqrtf(om) * (ig * uf[tok * 132 + chw]);
;                     sa[tok * 128 + chw] = a; sb[tok * 128 + chw] = bb;
;                 }
	v_mul_f32_e32 v93, v93, v96
	v_mul_f32_e32 v92, v93, v92
	ds_write_b32 v178, v94 offset:51200
	ds_write_b32 v179, v92
	v_add_f32_e32 v92, v163, v99
	v_mul_f32_e32 v92, 0xbfb8aa3b, v92
	v_exp_f32_e32 v92, v92
	v_add_f32_e32 v93, v235, v95
	v_mul_f32_e32 v93, 0xbfb8aa3b, v93
	v_exp_f32_e32 v93, v93
	v_add_f32_e32 v92, 1.0, v92
	v_rcp_f32_e32 v92, v92
	v_add_f32_e32 v85, 1.0, v85
	v_add_f32_e32 v93, 1.0, v93
	v_rcp_f32_e32 v93, v93
	v_mul_f32_e64 v92, v92, -v197
	v_mul_f32_e32 v94, 0x3fb8aa3b, v92
	v_add_f32_e32 v92, v92, v92
	v_fmamk_f32 v95, v92, 0x3ab60b61, v219
	v_exp_f32_e32 v94, v94
	v_fmaak_f32 v95, v92, v95, 0x3d2aaaab
	v_fmaak_f32 v95, v92, v95, 0x3e2aaaab
	v_fma_f32 v95, v92, v95, 0.5
	v_fma_f32 v95, v92, v95, 1.0
	v_mul_f32_e64 v95, v95, -v92
	v_cmp_lt_f32_e32 vcc, s76, v92
	v_fma_f32 v92, -v94, v94, 1.0
	v_rcp_f32_e32 v85, v85
	v_cndmask_b32_e32 v92, v92, v95, vcc
	ds_read_b32 v95, v232 offset:1056
	v_sqrt_f32_e32 v92, v92
	v_add_f32_e32 v80, v163, v80
	v_mul_f32_e32 v80, 0xbfb8aa3b, v80
	v_exp_f32_e32 v80, v80
	s_waitcnt lgkmcnt(0)
	v_mul_f32_e32 v93, v93, v95
	v_mul_f32_e32 v92, v92, v93
	ds_write_b32 v180, v94 offset:51200
	ds_write_b32 v181, v92
	v_mul_f32_e32 v92, 0x3fb8aa3b, v88
	v_add_f32_e32 v88, v88, v88
	v_fmamk_f32 v93, v88, 0x3ab60b61, v219
	v_exp_f32_e32 v92, v92
	v_fmaak_f32 v93, v88, v93, 0x3d2aaaab
	v_fmaak_f32 v93, v88, v93, 0x3e2aaaab
	v_fma_f32 v93, v88, v93, 0.5
	v_fma_f32 v93, v88, v93, 1.0
	v_mul_f32_e64 v93, v93, -v88
	v_cmp_lt_f32_e32 vcc, s76, v88
	v_fma_f32 v88, -v92, v92, 1.0
	v_add_f32_e32 v80, 1.0, v80
	v_cndmask_b32_e32 v88, v88, v93, vcc
	ds_read_b32 v93, v232 offset:7920
	v_sqrt_f32_e32 v88, v88
	v_rcp_f32_e32 v80, v80
	v_add_f32_e32 v76, v235, v76
	v_mul_f32_e32 v76, 0xbfb8aa3b, v76
	s_waitcnt lgkmcnt(0)
	v_mul_f32_e32 v84, v84, v93
	v_mul_f32_e32 v84, v88, v84
	ds_write_b32 v182, v92 offset:51200
	ds_write_b32 v183, v84
	v_add_f32_e32 v84, v163, v89
	v_mul_f32_e32 v84, 0xbfb8aa3b, v84
	v_exp_f32_e32 v84, v84
	v_mul_f32_e64 v80, v80, -v197
	v_exp_f32_e32 v76, v76
	v_add_f32_e32 v77, v235, v77
	v_add_f32_e32 v84, 1.0, v84
	v_rcp_f32_e32 v84, v84
	v_add_f32_e32 v76, 1.0, v76
	v_rcp_f32_e32 v76, v76
	v_mul_f32_e32 v77, 0xbfb8aa3b, v77
	v_mul_f32_e64 v84, v84, -v197
	v_mul_f32_e32 v88, 0x3fb8aa3b, v84
	v_add_f32_e32 v84, v84, v84
	v_fmamk_f32 v89, v84, 0x3ab60b61, v219
	v_exp_f32_e32 v88, v88
	v_fmaak_f32 v89, v84, v89, 0x3d2aaaab
	v_fmaak_f32 v89, v84, v89, 0x3e2aaaab
	v_fma_f32 v89, v84, v89, 0.5
	v_fma_f32 v89, v84, v89, 1.0
	v_mul_f32_e64 v89, v89, -v84
	v_cmp_lt_f32_e32 vcc, s76, v84
	v_fma_f32 v84, -v88, v88, 1.0
	v_exp_f32_e32 v77, v77
	v_cndmask_b32_e32 v84, v84, v89, vcc
	ds_read_b32 v89, v232 offset:8448
	v_sqrt_f32_e32 v84, v84
	v_add_f32_e32 v77, 1.0, v77
	v_rcp_f32_e32 v77, v77
	v_mfma_f32_16x16x32_bf16 v[72:75], v[68:71], v[60:63], v[108:111]
	s_waitcnt lgkmcnt(0)
	v_mul_f32_e32 v85, v85, v89
	v_mul_f32_e32 v84, v84, v85
	ds_write_b32 v185, v88 offset:51200
	ds_write_b32 v186, v84
	v_add_f32_e32 v84, v163, v90
	v_mul_f32_e32 v84, 0xbfb8aa3b, v84
	v_exp_f32_e32 v84, v84
	v_add_f32_e32 v85, v235, v86
	v_mul_f32_e32 v85, 0xbfb8aa3b, v85
	v_exp_f32_e32 v85, v85
	v_add_f32_e32 v84, 1.0, v84
	v_rcp_f32_e32 v84, v84
	v_add_f32_e32 v72, v163, v72
	v_add_f32_e32 v85, 1.0, v85
	v_rcp_f32_e32 v85, v85
	v_mul_f32_e64 v84, v84, -v197
	v_mul_f32_e32 v86, 0x3fb8aa3b, v84
	v_add_f32_e32 v84, v84, v84
	v_fmamk_f32 v88, v84, 0x3ab60b61, v219
	v_exp_f32_e32 v86, v86
	v_fmaak_f32 v88, v84, v88, 0x3d2aaaab
	v_fmaak_f32 v88, v84, v88, 0x3e2aaaab
	v_fma_f32 v88, v84, v88, 0.5
	v_fma_f32 v88, v84, v88, 1.0
	v_mul_f32_e64 v88, v88, -v84
	v_cmp_lt_f32_e32 vcc, s76, v84
	v_fma_f32 v84, -v86, v86, 1.0
	v_mul_f32_e32 v72, 0xbfb8aa3b, v72
	v_cndmask_b32_e32 v84, v84, v88, vcc
	ds_read_b32 v88, v232 offset:8976
	v_sqrt_f32_e32 v84, v84
	v_exp_f32_e32 v72, v72
	v_mfma_f32_16x16x32_bf16 v[68:71], v[68:71], v[64:67], v[112:115]
	s_waitcnt lgkmcnt(0)
	v_mul_f32_e32 v85, v85, v88
	v_mul_f32_e32 v84, v84, v85
	ds_write_b32 v187, v86 offset:51200
	ds_write_b32 v188, v84
	v_add_f32_e32 v84, v163, v91
	v_mul_f32_e32 v84, 0xbfb8aa3b, v84
	v_exp_f32_e32 v84, v84
	v_add_f32_e32 v85, v235, v87
	v_mul_f32_e32 v85, 0xbfb8aa3b, v85
	v_exp_f32_e32 v85, v85
	v_add_f32_e32 v84, 1.0, v84
	v_rcp_f32_e32 v84, v84
	v_add_f32_e32 v72, 1.0, v72
	v_add_f32_e32 v85, 1.0, v85
	v_rcp_f32_e32 v85, v85
	v_mul_f32_e64 v84, v84, -v197
	v_mul_f32_e32 v86, 0x3fb8aa3b, v84
	v_add_f32_e32 v84, v84, v84
	v_fmamk_f32 v87, v84, 0x3ab60b61, v219
	v_exp_f32_e32 v86, v86
	v_fmaak_f32 v87, v84, v87, 0x3d2aaaab
	v_fmaak_f32 v87, v84, v87, 0x3e2aaaab
	v_fma_f32 v87, v84, v87, 0.5
	v_fma_f32 v87, v84, v87, 1.0
	v_mul_f32_e64 v87, v87, -v84
	v_cmp_lt_f32_e32 vcc, s76, v84
	v_fma_f32 v84, -v86, v86, 1.0
	v_rcp_f32_e32 v72, v72
	v_cndmask_b32_e32 v84, v84, v87, vcc
	ds_read_b32 v87, v232 offset:9504
	v_sqrt_f32_e32 v84, v84
	v_mul_f32_e64 v72, v72, -v197
	v_add_f32_e32 v68, v235, v68
	v_mul_f32_e32 v68, 0xbfb8aa3b, v68
	s_waitcnt lgkmcnt(0)
	v_mul_f32_e32 v85, v85, v87
	v_mul_f32_e32 v84, v84, v85
	ds_write_b32 v189, v86 offset:51200
	ds_write_b32 v190, v84
	v_mul_f32_e32 v84, 0x3fb8aa3b, v80
	v_add_f32_e32 v80, v80, v80
	v_fmamk_f32 v85, v80, 0x3ab60b61, v219
	v_exp_f32_e32 v84, v84
	v_fmaak_f32 v85, v80, v85, 0x3d2aaaab
	v_fmaak_f32 v85, v80, v85, 0x3e2aaaab
	v_fma_f32 v85, v80, v85, 0.5
	v_fma_f32 v85, v80, v85, 1.0
	v_mul_f32_e64 v85, v85, -v80
	v_cmp_lt_f32_e32 vcc, s76, v80
	v_fma_f32 v80, -v84, v84, 1.0
	v_exp_f32_e32 v68, v68
	v_cndmask_b32_e32 v80, v80, v85, vcc
	ds_read_b32 v85, v232 offset:16368
	v_sqrt_f32_e32 v80, v80
	v_add_f32_e32 v68, 1.0, v68
	v_rcp_f32_e32 v68, v68
	v_add_f32_e32 v69, v235, v69
	s_waitcnt lgkmcnt(0)
; template <int I> DI const float* kin() { return (const float*)karg64<I * 8>(); }
; DI void lru_local_phase(const Ctx& c, int l) {
;     ...
;             const int chw = 16 * w + fr;
; #pragma unroll
;             for (int mt = 0; mt < 4; ++mt)
; #pragma unroll
;                 for (int j = 0; j < 4; ++j) {
;                     const int tok = mt * 16 + fq * 4 + j;
;                     const float r = __builtin_amdgcn_rcpf(1.0f + __expf(-(ar[mt][j] + ba))), ig = __builtin_amdgcn_rcpf(1.0f + __expf(-(ai[mt][j] + bx)));
;                     const float la = -c8 * r, a = __expf(la), x2 = 2.0f * la;
;                     const float omt = -x2 * (1.0f + x2 * (0.5f + x2 * (0.16666667f + x2 * (0.041666668f + x2 * (0.0083333338f + x2 * 0.0013888889f)))));
;                     const float om = x2 > -0.25f ? omt : 1.0f - a * a;
;                     const float bb = __builtin_amdgcn_sqrtf(om) * (ig * uf[tok * 132 + chw]);
;                     sa[tok * 128 + chw] = a; sb[tok * 128 + chw] = bb;
;                 }
;         }
;         __syncthreads();
;         {
;             float h = (smp && q == 0) ? kin<3>()[((size_t)l * 32 + bs) * 1024 + ch0 + chl] : 0.f, A = 1.f;
	v_mul_f32_e32 v76, v76, v85
	v_mul_f32_e32 v76, v80, v76
	ds_write_b32 v191, v84 offset:51200
	ds_write_b32 v192, v76
	v_add_f32_e32 v76, v163, v81
	v_mul_f32_e32 v76, 0xbfb8aa3b, v76
	v_exp_f32_e32 v76, v76
	v_mul_f32_e32 v69, 0xbfb8aa3b, v69
	v_exp_f32_e32 v69, v69
	v_add_f32_e32 v76, 1.0, v76
	v_rcp_f32_e32 v76, v76
	v_add_f32_e32 v69, 1.0, v69
	v_rcp_f32_e32 v69, v69
	v_mul_f32_e64 v76, v76, -v197
	v_mul_f32_e32 v80, 0x3fb8aa3b, v76
	v_add_f32_e32 v76, v76, v76
	v_fmamk_f32 v81, v76, 0x3ab60b61, v219
	v_exp_f32_e32 v80, v80
	v_fmaak_f32 v81, v76, v81, 0x3d2aaaab
	v_fmaak_f32 v81, v76, v81, 0x3e2aaaab
	v_fma_f32 v81, v76, v81, 0.5
	v_fma_f32 v81, v76, v81, 1.0
	v_mul_f32_e64 v81, v81, -v76
	v_cmp_lt_f32_e32 vcc, s76, v76
	v_fma_f32 v76, -v80, v80, 1.0
	s_nop 0
	v_cndmask_b32_e32 v76, v76, v81, vcc
	ds_read_b32 v81, v232 offset:16896
	v_sqrt_f32_e32 v76, v76
	s_waitcnt lgkmcnt(0)
	v_mul_f32_e32 v77, v77, v81
	v_mul_f32_e32 v76, v76, v77
	ds_write_b32 v193, v80 offset:51200
	ds_write_b32 v194, v76
	v_add_f32_e32 v76, v163, v82
	v_mul_f32_e32 v76, 0xbfb8aa3b, v76
	v_exp_f32_e32 v76, v76
	v_add_f32_e32 v77, v235, v78
	v_mul_f32_e32 v77, 0xbfb8aa3b, v77
	v_exp_f32_e32 v77, v77
	v_add_f32_e32 v76, 1.0, v76
	v_rcp_f32_e32 v76, v76
	v_add_f32_e32 v77, 1.0, v77
	v_rcp_f32_e32 v77, v77
	v_mul_f32_e64 v76, v76, -v197
	v_mul_f32_e32 v78, 0x3fb8aa3b, v76
	v_add_f32_e32 v76, v76, v76
	v_fmamk_f32 v80, v76, 0x3ab60b61, v219
	v_exp_f32_e32 v78, v78
	v_fmaak_f32 v80, v76, v80, 0x3d2aaaab
	v_fmaak_f32 v80, v76, v80, 0x3e2aaaab
	v_fma_f32 v80, v76, v80, 0.5
	v_fma_f32 v80, v76, v80, 1.0
	v_mul_f32_e64 v80, v80, -v76
	v_cmp_lt_f32_e32 vcc, s76, v76
	v_fma_f32 v76, -v78, v78, 1.0
	s_nop 0
	v_cndmask_b32_e32 v76, v76, v80, vcc
	ds_read_b32 v80, v232 offset:17424
	v_sqrt_f32_e32 v76, v76
	s_waitcnt lgkmcnt(0)
	v_mul_f32_e32 v77, v77, v80
	v_mul_f32_e32 v76, v76, v77
	ds_write_b32 v195, v78 offset:51200
	ds_write_b32 v204, v76
	v_add_f32_e32 v76, v163, v83
	v_mul_f32_e32 v76, 0xbfb8aa3b, v76
	v_exp_f32_e32 v76, v76
	v_add_f32_e32 v77, v235, v79
	v_mul_f32_e32 v77, 0xbfb8aa3b, v77
	v_exp_f32_e32 v77, v77
	v_add_f32_e32 v76, 1.0, v76
	v_rcp_f32_e32 v76, v76
	v_add_f32_e32 v77, 1.0, v77
	v_rcp_f32_e32 v77, v77
	v_mul_f32_e64 v76, v76, -v197
	v_mul_f32_e32 v78, 0x3fb8aa3b, v76
	v_add_f32_e32 v76, v76, v76
	v_fmamk_f32 v79, v76, 0x3ab60b61, v219
	v_exp_f32_e32 v78, v78
	v_fmaak_f32 v79, v76, v79, 0x3d2aaaab
	v_fmaak_f32 v79, v76, v79, 0x3e2aaaab
	v_fma_f32 v79, v76, v79, 0.5
	v_fma_f32 v79, v76, v79, 1.0
	v_mul_f32_e64 v79, v79, -v76
	v_cmp_lt_f32_e32 vcc, s76, v76
	v_fma_f32 v76, -v78, v78, 1.0
	s_nop 0
	v_cndmask_b32_e32 v76, v76, v79, vcc
	ds_read_b32 v79, v232 offset:17952
	v_sqrt_f32_e32 v76, v76
	s_waitcnt lgkmcnt(0)
	v_mul_f32_e32 v77, v77, v79
	v_mul_f32_e32 v76, v76, v77
	ds_write_b32 v205, v78 offset:51200
	ds_write_b32 v206, v76
	v_mul_f32_e32 v76, 0x3fb8aa3b, v72
	v_add_f32_e32 v72, v72, v72
	v_fmamk_f32 v77, v72, 0x3ab60b61, v219
	v_exp_f32_e32 v76, v76
	v_fmaak_f32 v77, v72, v77, 0x3d2aaaab
	v_fmaak_f32 v77, v72, v77, 0x3e2aaaab
	v_fma_f32 v77, v72, v77, 0.5
	v_fma_f32 v77, v72, v77, 1.0
	v_mul_f32_e64 v77, v77, -v72
	v_cmp_lt_f32_e32 vcc, s76, v72
	v_fma_f32 v72, -v76, v76, 1.0
	s_nop 0
	v_cndmask_b32_e32 v72, v72, v77, vcc
	ds_read_b32 v77, v232 offset:24816
	v_sqrt_f32_e32 v72, v72
	s_waitcnt lgkmcnt(0)
	v_mul_f32_e32 v68, v68, v77
	v_mul_f32_e32 v68, v72, v68
	ds_write_b32 v207, v76 offset:51200
	ds_write_b32 v208, v68
	v_add_f32_e32 v68, v163, v73
	v_mul_f32_e32 v68, 0xbfb8aa3b, v68
	v_exp_f32_e32 v68, v68
	s_nop 0
	v_add_f32_e32 v68, 1.0, v68
	v_rcp_f32_e32 v68, v68
	s_nop 0
	v_mul_f32_e64 v68, v68, -v197
	v_mul_f32_e32 v72, 0x3fb8aa3b, v68
	v_add_f32_e32 v68, v68, v68
	v_fmamk_f32 v73, v68, 0x3ab60b61, v219
	v_exp_f32_e32 v72, v72
	v_fmaak_f32 v73, v68, v73, 0x3d2aaaab
	v_fmaak_f32 v73, v68, v73, 0x3e2aaaab
	v_fma_f32 v73, v68, v73, 0.5
	v_fma_f32 v73, v68, v73, 1.0
	v_mul_f32_e64 v73, v73, -v68
	v_cmp_lt_f32_e32 vcc, s76, v68
	v_fma_f32 v68, -v72, v72, 1.0
	s_nop 0
	v_cndmask_b32_e32 v68, v68, v73, vcc
	ds_read_b32 v73, v232 offset:25344
	v_sqrt_f32_e32 v68, v68
	s_waitcnt lgkmcnt(0)
	v_mul_f32_e32 v69, v69, v73
	v_mul_f32_e32 v68, v68, v69
	ds_write_b32 v209, v72 offset:51200
	ds_write_b32 v210, v68
	v_add_f32_e32 v68, v163, v74
	v_mul_f32_e32 v68, 0xbfb8aa3b, v68
	v_exp_f32_e32 v68, v68
	v_add_f32_e32 v69, v235, v70
	v_mul_f32_e32 v69, 0xbfb8aa3b, v69
	v_exp_f32_e32 v69, v69
	v_add_f32_e32 v68, 1.0, v68
	v_rcp_f32_e32 v68, v68
	v_add_f32_e32 v69, 1.0, v69
	v_rcp_f32_e32 v69, v69
	v_mul_f32_e64 v68, v68, -v197
	v_mul_f32_e32 v70, 0x3fb8aa3b, v68
	v_add_f32_e32 v68, v68, v68
	v_fmamk_f32 v72, v68, 0x3ab60b61, v219
	v_exp_f32_e32 v70, v70
	v_fmaak_f32 v72, v68, v72, 0x3d2aaaab
	v_fmaak_f32 v72, v68, v72, 0x3e2aaaab
	v_fma_f32 v72, v68, v72, 0.5
	v_fma_f32 v72, v68, v72, 1.0
	v_mul_f32_e64 v72, v72, -v68
	v_cmp_lt_f32_e32 vcc, s76, v68
	v_fma_f32 v68, -v70, v70, 1.0
	s_nop 0
	v_cndmask_b32_e32 v68, v68, v72, vcc
	ds_read_b32 v72, v232 offset:25872
	v_sqrt_f32_e32 v68, v68
	s_waitcnt lgkmcnt(0)
	v_mul_f32_e32 v69, v69, v72
	v_mul_f32_e32 v68, v68, v69
	ds_write_b32 v211, v70 offset:51200
	ds_write_b32 v212, v68
	v_add_f32_e32 v68, v163, v75
	v_mul_f32_e32 v68, 0xbfb8aa3b, v68
	v_exp_f32_e32 v68, v68
	v_add_f32_e32 v69, v235, v71
	v_mul_f32_e32 v69, 0xbfb8aa3b, v69
	v_exp_f32_e32 v69, v69
	v_add_f32_e32 v68, 1.0, v68
	v_rcp_f32_e32 v68, v68
	v_add_f32_e32 v69, 1.0, v69
	v_rcp_f32_e32 v69, v69
	v_mul_f32_e64 v68, v68, -v197
	v_mul_f32_e32 v70, 0x3fb8aa3b, v68
	v_add_f32_e32 v68, v68, v68
	v_fmamk_f32 v71, v68, 0x3ab60b61, v219
	v_exp_f32_e32 v70, v70
	v_fmaak_f32 v71, v68, v71, 0x3d2aaaab
	v_fmaak_f32 v71, v68, v71, 0x3e2aaaab
	v_fma_f32 v71, v68, v71, 0.5
	v_fma_f32 v71, v68, v71, 1.0
	v_mul_f32_e64 v71, v71, -v68
	v_cmp_lt_f32_e32 vcc, s76, v68
	v_fma_f32 v68, -v70, v70, 1.0
	s_nop 0
	v_cndmask_b32_e32 v68, v68, v71, vcc
	ds_read_b32 v71, v232 offset:26400
	v_sqrt_f32_e32 v68, v68
	s_waitcnt lgkmcnt(0)
	v_mul_f32_e32 v69, v69, v71
	v_mul_f32_e32 v68, v68, v69
	v_mov_b32_e32 v69, 0
	ds_write_b32 v213, v70 offset:51200
	ds_write_b32 v214, v68
	s_waitcnt lgkmcnt(0)
	s_barrier
	s_and_saveexec_b64 s[8:9], s[66:67]
	s_cbranch_execz .LBB0_426
	s_load_dwordx2 s[66:67], s[0:1], 24
	s_waitcnt lgkmcnt(0)
	s_add_u32 s71, s66, s74
	s_addc_u32 s72, s67, s75
	s_lshl_b64 s[66:67], s[12:13], 12
	s_add_u32 s12, s71, s66
	s_addc_u32 s67, s72, s67
	s_lshl_b32 s66, s26, 2
	s_add_u32 s66, s12, s66
	s_addc_u32 s67, s67, 0
	v_lshl_add_u64 v[68:69], v[132:133], 2, s[66:67]
	global_load_dword v69, v[68:69], off

; DI unsigned char* kws() { return (unsigned char*)karg64<208>(); }
; DI unsigned pk2(float a, float b) { f32x2 v = {a, b}; bf16v2 r = __builtin_convertvector(v, bf16v2); return __builtin_bit_cast(unsigned, r); }
; DI void lru_local_phase(const Ctx& c, int l) {
;     ...
;         {
;             float cin = 0.f, Apre = 1.f;
;             for (int qq = 0; qq < q; ++qq) { const float A = tot[(qq * 128 + chl) * 2], h = tot[(qq * 128 + chl) * 2 + 1]; cin = A * cin + h; Apre *= A; }
;             unsigned* hc = (unsigned*)(kws() + WS_R1) + (size_t)row0 * 1024 + ch0 + chl;
;             float h = 0.f, A = 1.f;
; #pragma unroll 4
;             for (int t = 16 * q; t < 16 * q + 16; ++t) { h = sb[t * 128 + chl] + sa[t * 128 + chl] * cin; A = sa[t * 128 + chl] * Apre; hc[(size_t)t * 1024] = pk2(h, A); }
;             if (q == 3) { f32x2 ag = {A, h}; *(f32x2*)((float*)(kws() + WS_AGG) + ((size_t)chunk * 1024 + ch0 + chl) * 2) = ag; }
;         }
.LBB0_433:
	v_add_u32_e32 v76, s5, v216
	v_add_u32_e32 v70, 0x16800, v76
	ds_read_b32 v74, v70
	ds_read2st64_b32 v[70:71], v76 offset0:232 offset1:234
	s_addk_i32 s5, 0x800
	s_cmp_eq_u32 s5, 0
	s_waitcnt lgkmcnt(0)
	v_fmac_f32_e32 v74, v73, v70
	v_mul_f32_e32 v70, v72, v70
	v_cvt_pk_bf16_f32 v70, v74, v70
	v_add_co_u32_e32 v74, vcc, 0xffffd000, v68
	s_nop 1
	v_addc_co_u32_e32 v75, vcc, -1, v69, vcc
	global_store_dword v[74:75], v70, off
	v_add_u32_e32 v70, 0x16a00, v76
	ds_read_b32 v70, v70
	s_waitcnt lgkmcnt(0)
	v_fmac_f32_e32 v70, v73, v71
	v_mul_f32_e32 v71, v72, v71
	v_cvt_pk_bf16_f32 v74, v70, v71
	v_add_co_u32_e32 v70, vcc, 0xffffe000, v68
	s_nop 1
	v_addc_co_u32_e32 v71, vcc, -1, v69, vcc
	global_store_dword v[70:71], v74, off
	v_add_u32_e32 v70, 0x16c00, v76
	ds_read_b32 v70, v70
	ds_read2st64_b32 v[74:75], v76 offset0:236 offset1:238
	s_waitcnt lgkmcnt(0)
	v_fmac_f32_e32 v70, v73, v74
	v_mul_f32_e32 v71, v72, v74
	v_cvt_pk_bf16_f32 v74, v70, v71
	v_add_co_u32_e32 v70, vcc, 0xfffff000, v68
	s_nop 1
	v_addc_co_u32_e32 v71, vcc, -1, v69, vcc
	global_store_dword v[70:71], v74, off
	v_add_u32_e32 v70, 0x16e00, v76
	ds_read_b32 v71, v70
	v_mul_f32_e32 v70, v72, v75
	s_waitcnt lgkmcnt(0)
	v_fmac_f32_e32 v71, v73, v75
	v_cvt_pk_bf16_f32 v74, v71, v70
	global_store_dword v[68:69], v74, off
	v_lshl_add_u64 v[68:69], v[68:69], 0, s[16:17]
	s_cbranch_scc0 .LBB0_433
	s_and_saveexec_b64 s[8:9], s[60:61]
	s_cbranch_execz .LBB0_356
	s_ashr_i32 s5, s4, 31
	s_lshl_b64 s[4:5], s[4:5], 10
	v_mov_b32_e32 v68, s26
	v_or3_b32 v69, s5, 0, 0
	v_or3_b32 v68, s4, v68, v138
	s_load_dwordx2 s[66:67], s[0:1], 0xd0
	s_waitcnt lgkmcnt(0)
	s_nop 0
	v_lshl_add_u64 v[68:69], v[68:69], 3, s[66:67]
	v_add_co_u32_e32 v68, vcc, 0x16000, v68
	s_nop 1
	v_addc_co_u32_e32 v69, vcc, 0, v69, vcc
	global_store_dwordx2 v[68:69], v[70:71], off
	s_branch .LBB0_356

; DI unsigned pk2(float a, float b) { f32x2 v = {a, b}; bf16v2 r = __builtin_convertvector(v, bf16v2); return __builtin_bit_cast(unsigned, r); }
; template <int MODE, class Src>
; DI void attn_item(LAS unsigned char* lds, const Src& src, const bf16_t* Qp  , bf16_t* Op  , int nband, int jj0, float sink_l2, const LAS float* tbl, int qbase, int tid) {
;     ...
;     const float inv = 1.0f / lrun;
; #pragma unroll
;     for (int db = 0; db < 4; ++db)
; #pragma unroll
;         for (int gp = 0; gp < 4; gp += 2) {
;             u32x2 a, b;
;             a.x = pk2(o[db][4 * gp] * inv, o[db][4 * gp + 1] * inv); a.y = pk2(o[db][4 * gp + 2] * inv, o[db][4 * gp + 3] * inv);
;             b.x = pk2(o[db][4 * gp + 4] * inv, o[db][4 * gp + 5] * inv); b.y = pk2(o[db][4 * gp + 6] * inv, o[db][4 * gp + 7] * inv);
;             const auto r0 = __builtin_amdgcn_permlane32_swap(a.x, b.x, false, false); const auto r1 = __builtin_amdgcn_permlane32_swap(a.y, b.y, false, false);
;             u32x4 w; w.x = r0[0]; w.y = r1[0]; w.z = r0[1]; w.w = r1[1];
;             *(u32x4*)(Op + (size_t)r * 3072 + db * 32 + 8 * gp + 8 * h) = w;
;         }
.LBB0_441:
	s_mul_hi_i32 s4, s56, 0x1800
	s_mulk_i32 s56, 0x1800
	s_add_u32 s5, s18, s56
	s_addc_u32 s18, s19, s4
	s_add_u32 s4, s5, s8
	s_addc_u32 s5, s18, s9
	v_div_scale_f32 v1, s[8:9], v135, v135, 1.0
	v_rcp_f32_e32 v2, v1
	v_mov_b32_e32 v137, v3
	v_mov_b32_e32 v139, v3
	s_add_i32 s23, s23, s81
	v_fma_f32 v68, -v1, v2, 1.0
	v_fmac_f32_e32 v2, v68, v2
	v_div_scale_f32 v68, vcc, 1.0, v135, 1.0
	v_mul_f32_e32 v69, v68, v2
	v_fma_f32 v70, -v1, v69, v68
	v_fmac_f32_e32 v69, v70, v2
	v_fma_f32 v1, -v1, v69, v68
	v_div_fmas_f32 v1, v1, v2, v69
	v_div_fixup_f32 v2, v1, v135, 1.0
	v_lshl_add_u64 v[68:69], s[4:5], 0, v[136:137]
	v_lshl_add_u64 v[68:69], v[68:69], 0, v[138:139]
	s_mov_b64 s[4:5], 0x45856800
	v_pk_mul_f32 v[52:53], v[2:3], v[52:53] op_sel_hi:[0,1]
	v_pk_mul_f32 v[54:55], v[2:3], v[54:55] op_sel_hi:[0,1]
	v_pk_mul_f32 v[36:37], v[2:3], v[36:37] op_sel_hi:[0,1]
	v_pk_mul_f32 v[38:39], v[2:3], v[38:39] op_sel_hi:[0,1]
	v_pk_mul_f32 v[20:21], v[2:3], v[20:21] op_sel_hi:[0,1]
	v_pk_mul_f32 v[22:23], v[2:3], v[22:23] op_sel_hi:[0,1]
	v_pk_mul_f32 v[4:5], v[2:3], v[4:5] op_sel_hi:[0,1]
	v_pk_mul_f32 v[6:7], v[2:3], v[6:7] op_sel_hi:[0,1]
	v_lshl_add_u64 v[70:71], v[68:69], 0, s[4:5]
	v_cvt_pk_bf16_f32 v52, v52, v53
	v_cvt_pk_bf16_f32 v53, v54, v55
	v_pk_mul_f32 v[54:55], v[2:3], v[56:57] op_sel_hi:[0,1]
	v_pk_mul_f32 v[56:57], v[2:3], v[58:59] op_sel_hi:[0,1]
	s_mov_b32 s4, 0x45856000
	v_cvt_pk_bf16_f32 v36, v36, v37
	v_cvt_pk_bf16_f32 v37, v38, v39
	v_pk_mul_f32 v[38:39], v[2:3], v[40:41] op_sel_hi:[0,1]
	v_pk_mul_f32 v[40:41], v[2:3], v[42:43] op_sel_hi:[0,1]
	v_cvt_pk_bf16_f32 v20, v20, v21
	v_cvt_pk_bf16_f32 v21, v22, v23
	v_pk_mul_f32 v[22:23], v[2:3], v[24:25] op_sel_hi:[0,1]
	v_pk_mul_f32 v[24:25], v[2:3], v[26:27] op_sel_hi:[0,1]
	v_cvt_pk_bf16_f32 v4, v4, v5
	v_cvt_pk_bf16_f32 v5, v6, v7
	v_pk_mul_f32 v[6:7], v[2:3], v[8:9] op_sel_hi:[0,1]
	v_pk_mul_f32 v[8:9], v[2:3], v[10:11] op_sel_hi:[0,1]
	v_cvt_pk_bf16_f32 v54, v54, v55
	v_cvt_pk_bf16_f32 v55, v56, v57
	v_add_co_u32_e32 v56, vcc, s4, v68
	v_cvt_pk_bf16_f32 v38, v38, v39
	v_cvt_pk_bf16_f32 v39, v40, v41
	v_cvt_pk_bf16_f32 v22, v22, v23
	v_cvt_pk_bf16_f32 v23, v24, v25
	v_cvt_pk_bf16_f32 v6, v6, v7
	v_cvt_pk_bf16_f32 v7, v8, v9
	v_permlane32_swap_b32_e32 v52, v54
	v_permlane32_swap_b32_e32 v53, v55
	v_addc_co_u32_e32 v57, vcc, 0, v69, vcc
	v_permlane32_swap_b32_e32 v36, v38
	v_permlane32_swap_b32_e32 v37, v39
	v_permlane32_swap_b32_e32 v20, v22
	v_permlane32_swap_b32_e32 v21, v23
	v_permlane32_swap_b32_e32 v4, v6
	v_permlane32_swap_b32_e32 v5, v7
	global_store_dwordx4 v[56:57], v[52:55], off offset:2048
	global_store_dwordx4 v[70:71], v[36:39], off offset:64
	global_store_dwordx4 v[70:71], v[20:23], off offset:128
	v_pk_mul_f32 v[52:53], v[2:3], v[60:61] op_sel_hi:[0,1]
	v_pk_mul_f32 v[54:55], v[2:3], v[62:63] op_sel_hi:[0,1]
	v_pk_mul_f32 v[36:37], v[2:3], v[44:45] op_sel_hi:[0,1]
	v_pk_mul_f32 v[38:39], v[2:3], v[46:47] op_sel_hi:[0,1]
	v_pk_mul_f32 v[20:21], v[2:3], v[28:29] op_sel_hi:[0,1]
	v_pk_mul_f32 v[22:23], v[2:3], v[30:31] op_sel_hi:[0,1]
	global_store_dwordx4 v[70:71], v[4:7], off offset:192
	v_cvt_pk_bf16_f32 v52, v52, v53
	v_cvt_pk_bf16_f32 v53, v54, v55
	v_pk_mul_f32 v[4:5], v[2:3], v[12:13] op_sel_hi:[0,1]
	v_pk_mul_f32 v[6:7], v[2:3], v[14:15] op_sel_hi:[0,1]
	v_pk_mul_f32 v[54:55], v[2:3], v[64:65] op_sel_hi:[0,1]
	v_pk_mul_f32 v[56:57], v[2:3], v[66:67] op_sel_hi:[0,1]
	v_cvt_pk_bf16_f32 v36, v36, v37
	v_cvt_pk_bf16_f32 v37, v38, v39
	v_pk_mul_f32 v[38:39], v[2:3], v[48:49] op_sel_hi:[0,1]
	v_pk_mul_f32 v[40:41], v[2:3], v[50:51] op_sel_hi:[0,1]
	v_cvt_pk_bf16_f32 v20, v20, v21
	v_cvt_pk_bf16_f32 v21, v22, v23
	v_pk_mul_f32 v[22:23], v[2:3], v[32:33] op_sel_hi:[0,1]
	v_pk_mul_f32 v[24:25], v[2:3], v[34:35] op_sel_hi:[0,1]
	v_cvt_pk_bf16_f32 v4, v4, v5
	v_cvt_pk_bf16_f32 v5, v6, v7
	v_pk_mul_f32 v[6:7], v[2:3], v[16:17] op_sel_hi:[0,1]
	v_pk_mul_f32 v[8:9], v[2:3], v[18:19] op_sel_hi:[0,1]
	v_cvt_pk_bf16_f32 v54, v54, v55
	v_cvt_pk_bf16_f32 v55, v56, v57
	v_cvt_pk_bf16_f32 v38, v38, v39
	v_cvt_pk_bf16_f32 v39, v40, v41
	v_cvt_pk_bf16_f32 v22, v22, v23
	v_cvt_pk_bf16_f32 v23, v24, v25
	v_cvt_pk_bf16_f32 v6, v6, v7
	v_cvt_pk_bf16_f32 v7, v8, v9
	v_permlane32_swap_b32_e32 v52, v54
	v_permlane32_swap_b32_e32 v53, v55
	v_permlane32_swap_b32_e32 v36, v38
	v_permlane32_swap_b32_e32 v37, v39
	v_permlane32_swap_b32_e32 v20, v22
	v_permlane32_swap_b32_e32 v21, v23
	v_permlane32_swap_b32_e32 v4, v6
	v_permlane32_swap_b32_e32 v5, v7
	s_cmp_ge_i32 s23, s12
	global_store_dwordx4 v[70:71], v[52:55], off offset:32
	global_store_dwordx4 v[70:71], v[36:39], off offset:96
	global_store_dwordx4 v[70:71], v[20:23], off offset:160
	global_store_dwordx4 v[70:71], v[4:7], off offset:224
	s_cbranch_scc1 .LBB0_504
; #define LAS __attribute__((address_space(3)))
; template <int I> DI const float* kin() { return (const float*)karg64<I * 8>(); }
; #define WSP(T, off) ((T*)(kws() + (off)))
; #define REP(j) for (int rep_ = 0; rep_ < 1 + ((PROBE_MASK >> (j)) & 1); ++rep_)
; template <int MODE, class Src>
; DI void attn_item(LAS unsigned char* lds, const Src& src, const bf16_t* Qp  , bf16_t* Op  , int nband, int jj0, float sink_l2, const LAS float* tbl, int qbase, int tid) {
;     ...
;     const int lane = tid & 63, w = __builtin_amdgcn_readfirstlane(tid >> 6), r = lane & 31, h = lane >> 5;
;     const int hl = MODE ? (w >> 1) : 0;
;     const int lq = lane >> 4, chp = lane & 15;
;     ...
;     bf16x8 qf[8];
; #pragma unroll
;     for (int ks = 0; ks < 8; ++ks) qf[ks] = *(const bf16x8*)(Qp + (size_t)r * ZLD + ks * 16 + h * 8);
;     f32x16 o[4];
; #pragma unroll
;     for (int db = 0; db < 4; ++db)
; #pragma unroll
;         for (int i = 0; i < 16; ++i) o[db][i] = 0.f;
;     float mrun = MODE == 0 ? sink_l2 : -1e30f, lrun = MODE == 0 ? 1.f : 0.f;
;     const float sc = 0.08838834764831845f * LOG2E;
;     const LAS unsigned char* Kt = lds + hl * 16384 + 256 * r;
;     const int kx = 16 * (h ^ (((r & 3) << 2) | ((r >> 2) & 3)));
;     const int blk = (lane >> 4) & 1, q = (lane & 15) >> 2, p = lane & 3;
;     const LAS unsigned char* Vt = lds + 65536 + hl * 16384 + 256 * (4 * h + q) + 8 * (p & 1);
;     const int vlo = 2 * blk + (p >> 1);
;     ATT_ISSUE(jj0, false); ATT_ISSUE(jj0, true);
; __global__ void __launch_bounds__(NTHR, 2) fwd_kernel(Args args) {
;     ...
;             REP(13) for (int u = c.bid; u < (c.G >= 128 ? 512 : NCHUNK * 2); u += c.G) {
;                 const int chunk = u >> 1, kv = u & 1, head = kv * 4 + (c.wave >> 1), qh = c.wave & 1;
;                 const bf16_t* Z = WSP(bf16_t, WS_Z);
;                 SrcSwa src{Z, WSP(bf16_t, WS_KCB), WSP(bf16_t, WS_VTCB), chunk, kv};
;                 const int n = chunk & 127, jj0 = (chunk < 256 && n < 2) ? 2 - n : 0;
;                 attn_item<0>(c.lds, src, Z + (size_t)(chunk * 64 + qh * 32) * ZLD + C_QB + head * 128, WSP(bf16_t, WS_BR) + (size_t)(chunk * 64 + qh * 32) * 3072 + 1024 + head * 128, 3, jj0,
;                              kin<17>()[l * 8 + head] * LOG2E, nullptr, 0, c.tid);
.LBB0_442:
	s_and_b32 s58, s23, 1
	s_lshl_b32 s4, s58, 2
	s_ashr_i32 s52, s23, 1
	s_add_i32 s42, s4, s10
	s_load_dwordx2 s[46:47], s[0:1], 0xd0
	s_waitcnt lgkmcnt(0)
	s_add_u32 s53, s46, 0x26456000
	s_addc_u32 s54, s47, 0
	s_load_dwordx2 s[4:5], s[0:1], 0xd0
	s_waitcnt lgkmcnt(0)
	s_add_u32 s26, s4, 0x38456000
	s_addc_u32 s27, s5, 0
	s_and_b32 s38, s52, 0x7f
	s_cmpk_gt_i32 s52, 0xff
	s_cselect_b64 s[4:5], -1, 0
	s_cmpk_lt_i32 s52, 0x100
	s_cselect_b64 s[8:9], -1, 0
	s_cmp_lt_u32 s38, 2
	s_cselect_b64 s[18:19], -1, 0
	s_and_b64 s[8:9], s[8:9], s[18:19]
	s_sub_i32 s18, 2, s38
	s_and_b64 s[8:9], s[8:9], exec
	s_cselect_b32 s55, s18, 0
	s_lshl_b32 s8, s52, 6
	s_or_b32 s56, s8, s11
	s_mul_i32 s9, s56, 0x3400
	s_mul_hi_i32 s8, s56, 0x3400
	s_add_u32 s18, s53, s9
	s_addc_u32 s19, s54, s8
	s_lshl_b32 s8, s42, 7
	s_ashr_i32 s9, s8, 31
	s_lshl_b64 s[8:9], s[8:9], 1
	s_add_u32 s38, s18, s8
	s_addc_u32 s39, s19, s9
	s_add_i32 s42, s42, s22
	s_ashr_i32 s43, s42, 31
	v_mov_b32_e32 v135, v3
	s_load_dwordx2 s[34:35], s[0:1], 0xd0
	s_waitcnt lgkmcnt(0)
	s_load_dwordx2 s[18:19], s[0:1], 0xd0
	s_waitcnt lgkmcnt(0)
	s_load_dwordx2 s[40:41], s[0:1], 0x88
	s_waitcnt lgkmcnt(0)
	s_lshl_b64 s[42:43], s[42:43], 2
	v_lshl_add_u64 v[6:7], s[38:39], 0, v[134:135]
	v_mov_b32_e32 v139, v3
	s_add_u32 s40, s40, s42
	v_lshl_add_u64 v[6:7], v[6:7], 0, v[138:139]
	s_addc_u32 s41, s41, s43
	v_lshl_add_u64 v[8:9], v[6:7], 0, s[28:29]
	v_add_co_u32_e32 v6, vcc, s33, v6
	v_mov_b64_e32 v[4:5], s[40:41]
	s_nop 0
	v_addc_co_u32_e32 v7, vcc, 0, v7, vcc
	global_load_dword v4, v[4:5], off
	s_nop 0
	global_load_dwordx4 v[100:103], v[6:7], off
	global_load_dwordx4 v[104:107], v[8:9], off offset:32
	global_load_dwordx4 v[108:111], v[8:9], off offset:64
	global_load_dwordx4 v[112:115], v[8:9], off offset:96
	global_load_dwordx4 v[116:119], v[8:9], off offset:128
	global_load_dwordx4 v[120:123], v[8:9], off offset:160
	global_load_dwordx4 v[124:127], v[8:9], off offset:192
	global_load_dwordx4 v[128:131], v[8:9], off offset:224
	s_cmp_gt_i32 s55, 1
	s_cselect_b64 s[38:39], -1, 0
	s_lshl_b32 s65, s55, 6
	v_readfirstlane_b32 s48, v132
	s_add_i32 s63, s65, 0xffff8000
	s_mov_b64 s[44:45], -1
	s_and_b64 vcc, exec, s[4:5]
	s_mul_hi_u32 s64, s52, 0xd0000
	s_mul_i32 s66, s52, 0xd0000
	s_cbranch_vccz .LBB0_448
	s_mov_b64 s[42:43], -1
	s_and_b64 vcc, exec, s[38:39]
	s_cbranch_vccz .LBB0_445
	s_add_u32 s40, s53, s66
	s_addc_u32 s41, s54, s64
	s_add_u32 s40, s40, 0x1800
	s_addc_u32 s41, s41, 0
	s_mov_b64 s[42:43], 0

; DI unsigned xb_ld(unsigned* p)              { return __hip_atomic_load(p, __ATOMIC_RELAXED, __HIP_MEMORY_SCOPE_AGENT); }
; DI void xcd_barrier_complete(unsigned* bar, unsigned x, unsigned& nloc, unsigned& nx) {
;     const unsigned G = gridDim.x * gridDim.y * gridDim.z;
;     unsigned sum, cnt, mine, sp = 0u;
;     for (;;) {
;         sum = 0u; cnt = 0u; mine = 0u;
; #pragma unroll
;         for (unsigned j = 0; j < 16; ++j) { const unsigned c = xb_ld(&bar[XB_XCNT(j)]); sum += c; cnt += (c > 0u) ? 1u : 0u; mine = (j == x) ? c : mine; }
;         if (sum == G) break;
;         __builtin_amdgcn_s_sleep(1);
;         if ((++sp & 255u) == 0u) { if (xb_ld(&bar[XB_TMO])) break; if (sp > XB_SPIN_CAP) { atomicAdd(&bar[XB_TMO], 1u); break; } }
;     }
;     nloc = mine > 0u ? mine : 1u; nx = cnt > 0u ? cnt : 1u;
; }
.LBB0_510:
	v_mov_b64_e32 v[14:15], s[8:9]
	global_load_dword v2, v[14:15], off offset:1024 sc1
	global_load_dword v1, v[14:15], off offset:1280 sc1
	global_load_dword v4, v[14:15], off offset:1536 sc1
	s_or_b64 s[48:49], s[48:49], exec
	s_or_b64 s[46:47], s[46:47], exec
	s_waitcnt vmcnt(0) lgkmcnt(0)
	v_add_u32_e32 v5, v1, v2
	v_add_u32_e32 v6, v5, v4
	global_load_dword v5, v[14:15], off offset:1792 sc1
	s_waitcnt vmcnt(0) lgkmcnt(0)
	v_add_u32_e32 v7, v6, v5
	global_load_dword v6, v[14:15], off offset:2048 sc1
	s_waitcnt vmcnt(0) lgkmcnt(0)
	v_add_u32_e32 v8, v7, v6
	global_load_dword v7, v[14:15], off offset:2304 sc1
	s_waitcnt vmcnt(0) lgkmcnt(0)
	v_add_u32_e32 v9, v8, v7
	global_load_dword v8, v[14:15], off offset:2560 sc1
	s_waitcnt vmcnt(0) lgkmcnt(0)
	v_add_u32_e32 v10, v9, v8
	global_load_dword v9, v[14:15], off offset:2816 sc1
	s_waitcnt vmcnt(0) lgkmcnt(0)
	v_add_u32_e32 v11, v10, v9
	global_load_dword v10, v[14:15], off offset:3072 sc1
	s_waitcnt vmcnt(0) lgkmcnt(0)
	v_add_u32_e32 v12, v11, v10
	global_load_dword v11, v[14:15], off offset:3328 sc1
	s_waitcnt vmcnt(0) lgkmcnt(0)
	v_add_u32_e32 v13, v12, v11
	global_load_dword v12, v[14:15], off offset:3584 sc1
	s_waitcnt vmcnt(0) lgkmcnt(0)
	v_add_u32_e32 v16, v13, v12
	global_load_dword v13, v[14:15], off offset:3840 sc1
	v_mov_b64_e32 v[14:15], s[18:19]
	global_load_dword v14, v[14:15], off sc1
	s_waitcnt vmcnt(0) lgkmcnt(0)
	v_add_u32_e32 v16, v16, v13
	v_add_u32_e32 v18, v16, v14
	v_mov_b64_e32 v[16:17], s[34:35]
	global_load_dword v15, v[16:17], off sc1
	v_mov_b64_e32 v[16:17], s[38:39]
	global_load_dword v16, v[16:17], off sc1
	s_waitcnt vmcnt(0) lgkmcnt(0)
	v_add_u32_e32 v18, v18, v15
	v_add_u32_e32 v20, v18, v16
	v_mov_b64_e32 v[18:19], s[40:41]
	global_load_dword v17, v[18:19], off sc1
	s_waitcnt vmcnt(0) lgkmcnt(0)
	v_add_u32_e32 v18, v20, v17
	v_cmp_ne_u32_e32 vcc, s11, v18
	s_and_saveexec_b64 s[50:51], vcc
	s_cbranch_execz .LBB0_509
	s_and_b32 s22, s12, 0xff
	s_mov_b64 s[52:53], -1
	s_cmp_eq_u32 s22, 0
	s_mov_b64 s[56:57], -1
	s_mov_b64 s[54:55], -1
	s_sleep 1
	s_cbranch_scc1 .LBB0_513
	s_and_saveexec_b64 s[58:59], s[56:57]
	s_cbranch_execz .LBB0_508
	s_branch .LBB0_516

; template <int I> DI const float* kin() { return (const float*)karg64<I * 8>(); }
; __global__ void __launch_bounds__(NTHR, 2) fwd_kernel(Args args) {
;     ...
;             for (int i = c.tid; i < 8 * 257; i += NTHR) { const int hh = i / 257, e = i - hh * 257; tbl[hh * 260 + e] = kin<18>()[(size_t)l * 8 * 257 + i] * LOG2E; }
.LBB0_557:
	s_load_dwordx2 s[10:11], s[0:1], 0x90
	s_waitcnt lgkmcnt(0)
	v_add_u32_e32 v8, 0x200, v2
	v_lshl_add_u64 v[6:7], s[10:11], 0, v[4:5]
	global_load_dword v6, v[6:7], off
	s_mov_b32 s10, 0x7f807f81
	v_mul_hi_i32 v7, v2, s10
	v_lshrrev_b32_e32 v9, 31, v7
	v_ashrrev_i32_e32 v7, 7, v7
	s_movk_i32 s10, 0x607
	v_add_u32_e32 v7, v7, v9
	v_cmp_lt_i32_e32 vcc, s10, v2
	v_mov_b32_e32 v2, v8
	v_mul_i32_i24_e32 v8, 0x410, v7
	v_mul_i32_i24_e32 v7, 0xfffffbfc, v7
	v_lshl_add_u64 v[4:5], v[4:5], 0, s[36:37]
	s_or_b64 s[8:9], vcc, s[8:9]
	v_add3_u32 v7, v8, v7, v1
	v_add_u32_e32 v1, 0x800, v1
	s_waitcnt vmcnt(0) lgkmcnt(0)
	v_mul_f32_e32 v6, 0x3fb8aa3b, v6
	ds_write_b32 v7, v6
	s_andn2_b64 exec, exec, s[8:9]
	s_cbranch_execnz .LBB0_557
	s_or_b64 exec, exec, s[8:9]

; DI unsigned pk2(float a, float b) { f32x2 v = {a, b}; bf16v2 r = __builtin_convertvector(v, bf16v2); return __builtin_bit_cast(unsigned, r); }
; DI void attn_quad(LAS unsigned char* lds, const bf16_t* Z, bf16_t* BR, int c0  , int head, const LAS float* tbl, int tid) {
;     ...
;     asm volatile("s_waitcnt lgkmcnt(0)" ::: "memory"); __builtin_amdgcn_s_barrier(); asm volatile("" ::: "memory");
;     const float inv = 1.0f / lrun;
; #pragma unroll
;     for (int db = 0; db < 4; ++db)
; #pragma unroll
;         for (int gp = 0; gp < 4; gp += 2) {
;             u32x2 a, b;
;             a.x = pk2(o[db][4 * gp] * inv, o[db][4 * gp + 1] * inv); a.y = pk2(o[db][4 * gp + 2] * inv, o[db][4 * gp + 3] * inv);
;             b.x = pk2(o[db][4 * gp + 4] * inv, o[db][4 * gp + 5] * inv); b.y = pk2(o[db][4 * gp + 6] * inv, o[db][4 * gp + 7] * inv);
;             const auto r0 = __builtin_amdgcn_permlane32_swap(a.x, b.x, false, false); const auto r1 = __builtin_amdgcn_permlane32_swap(a.y, b.y, false, false);
;             u32x4 w; w.x = r0[0]; w.y = r1[0]; w.z = r0[1]; w.w = r1[1];
;             *(u32x4*)(Op + (size_t)r * 3072 + db * 32 + 8 * gp + 8 * h) = w;
;         }
.LBB0_562:
	s_mul_i32 s5, s10, 0x1800
	s_mul_hi_i32 s4, s10, 0x1800
	s_add_u32 s5, s40, s5
	s_addc_u32 s10, s41, s4
	s_lshl_b32 s4, s11, 1
	s_add_u32 s4, s5, s4
	s_addc_u32 s5, s10, 0
	v_div_scale_f32 v2, s[10:11], v145, v145, 1.0
	v_rcp_f32_e32 v68, v2
	v_mov_b32_e32 v151, v3
	v_mov_b32_e32 v149, v3
	s_waitcnt lgkmcnt(0)
	v_fma_f32 v69, -v2, v68, 1.0
	v_fmac_f32_e32 v68, v69, v68
	v_div_scale_f32 v69, vcc, 1.0, v145, 1.0
	v_mul_f32_e32 v70, v69, v68
	v_fma_f32 v71, -v2, v70, v69
	v_fmac_f32_e32 v70, v71, v68
	v_fma_f32 v2, -v2, v70, v69
	v_div_fmas_f32 v2, v2, v68, v70
	v_div_fixup_f32 v2, v2, v145, 1.0
	v_lshl_add_u64 v[68:69], s[4:5], 0, v[150:151]
	v_lshl_add_u64 v[68:69], v[68:69], 0, v[148:149]
	s_mov_b64 s[4:5], 0x45857000
	v_pk_mul_f32 v[52:53], v[52:53], v[2:3] op_sel_hi:[1,0]
	v_pk_mul_f32 v[54:55], v[54:55], v[2:3] op_sel_hi:[1,0]
	v_pk_mul_f32 v[36:37], v[36:37], v[2:3] op_sel_hi:[1,0]
	v_pk_mul_f32 v[38:39], v[38:39], v[2:3] op_sel_hi:[1,0]
	v_pk_mul_f32 v[20:21], v[20:21], v[2:3] op_sel_hi:[1,0]
	v_pk_mul_f32 v[22:23], v[22:23], v[2:3] op_sel_hi:[1,0]
	v_pk_mul_f32 v[4:5], v[4:5], v[2:3] op_sel_hi:[1,0]
	v_pk_mul_f32 v[6:7], v[6:7], v[2:3] op_sel_hi:[1,0]
	v_lshl_add_u64 v[70:71], v[68:69], 0, s[4:5]
	v_cvt_pk_bf16_f32 v52, v52, v53
	v_cvt_pk_bf16_f32 v53, v54, v55
	v_pk_mul_f32 v[54:55], v[56:57], v[2:3] op_sel_hi:[1,0]
	v_pk_mul_f32 v[56:57], v[58:59], v[2:3] op_sel_hi:[1,0]
	s_mov_b32 s4, 0x45857000
	v_cvt_pk_bf16_f32 v36, v36, v37
	v_cvt_pk_bf16_f32 v37, v38, v39
	v_pk_mul_f32 v[38:39], v[40:41], v[2:3] op_sel_hi:[1,0]
	v_pk_mul_f32 v[40:41], v[42:43], v[2:3] op_sel_hi:[1,0]
	v_cvt_pk_bf16_f32 v20, v20, v21
	v_cvt_pk_bf16_f32 v21, v22, v23
	v_pk_mul_f32 v[22:23], v[24:25], v[2:3] op_sel_hi:[1,0]
	v_pk_mul_f32 v[24:25], v[26:27], v[2:3] op_sel_hi:[1,0]
	v_cvt_pk_bf16_f32 v4, v4, v5
	v_cvt_pk_bf16_f32 v5, v6, v7
	v_pk_mul_f32 v[6:7], v[8:9], v[2:3] op_sel_hi:[1,0]
	v_pk_mul_f32 v[8:9], v[10:11], v[2:3] op_sel_hi:[1,0]
	v_cvt_pk_bf16_f32 v54, v54, v55
	v_cvt_pk_bf16_f32 v55, v56, v57
	v_add_co_u32_e32 v56, vcc, s4, v68
	v_cvt_pk_bf16_f32 v38, v38, v39
	v_cvt_pk_bf16_f32 v39, v40, v41
	v_cvt_pk_bf16_f32 v22, v22, v23
	v_cvt_pk_bf16_f32 v23, v24, v25
	v_cvt_pk_bf16_f32 v6, v6, v7
	v_cvt_pk_bf16_f32 v7, v8, v9
	v_permlane32_swap_b32_e32 v52, v54
	v_permlane32_swap_b32_e32 v53, v55
	v_addc_co_u32_e32 v57, vcc, 0, v69, vcc
	v_permlane32_swap_b32_e32 v36, v38
	v_permlane32_swap_b32_e32 v37, v39
	v_permlane32_swap_b32_e32 v20, v22
	v_permlane32_swap_b32_e32 v21, v23
	v_permlane32_swap_b32_e32 v4, v6
	v_permlane32_swap_b32_e32 v5, v7
	s_barrier
	global_store_dwordx4 v[56:57], v[52:55], off
	global_store_dwordx4 v[70:71], v[36:39], off offset:64
	global_store_dwordx4 v[70:71], v[20:23], off offset:128
	v_pk_mul_f32 v[52:53], v[60:61], v[2:3] op_sel_hi:[1,0]
	v_pk_mul_f32 v[54:55], v[62:63], v[2:3] op_sel_hi:[1,0]
	v_pk_mul_f32 v[36:37], v[44:45], v[2:3] op_sel_hi:[1,0]
	v_pk_mul_f32 v[38:39], v[46:47], v[2:3] op_sel_hi:[1,0]
	v_pk_mul_f32 v[20:21], v[28:29], v[2:3] op_sel_hi:[1,0]
	v_pk_mul_f32 v[22:23], v[30:31], v[2:3] op_sel_hi:[1,0]
	global_store_dwordx4 v[70:71], v[4:7], off offset:192
	v_cvt_pk_bf16_f32 v52, v52, v53
	v_cvt_pk_bf16_f32 v53, v54, v55
	v_pk_mul_f32 v[4:5], v[12:13], v[2:3] op_sel_hi:[1,0]
	v_pk_mul_f32 v[6:7], v[14:15], v[2:3] op_sel_hi:[1,0]
	v_pk_mul_f32 v[54:55], v[64:65], v[2:3] op_sel_hi:[1,0]
	v_pk_mul_f32 v[56:57], v[66:67], v[2:3] op_sel_hi:[1,0]
	v_cvt_pk_bf16_f32 v36, v36, v37
	v_cvt_pk_bf16_f32 v37, v38, v39
	v_pk_mul_f32 v[38:39], v[48:49], v[2:3] op_sel_hi:[1,0]
	v_pk_mul_f32 v[40:41], v[50:51], v[2:3] op_sel_hi:[1,0]
	v_cvt_pk_bf16_f32 v20, v20, v21
	v_cvt_pk_bf16_f32 v21, v22, v23
	v_pk_mul_f32 v[22:23], v[32:33], v[2:3] op_sel_hi:[1,0]
	v_pk_mul_f32 v[24:25], v[34:35], v[2:3] op_sel_hi:[1,0]
	v_cvt_pk_bf16_f32 v4, v4, v5
	v_cvt_pk_bf16_f32 v5, v6, v7
	v_pk_mul_f32 v[6:7], v[16:17], v[2:3] op_sel_hi:[1,0]
	v_pk_mul_f32 v[8:9], v[18:19], v[2:3] op_sel_hi:[1,0]
	v_cvt_pk_bf16_f32 v54, v54, v55
	v_cvt_pk_bf16_f32 v55, v56, v57
	v_cvt_pk_bf16_f32 v38, v38, v39
	v_cvt_pk_bf16_f32 v39, v40, v41
	v_cvt_pk_bf16_f32 v22, v22, v23
	v_cvt_pk_bf16_f32 v23, v24, v25
	v_cvt_pk_bf16_f32 v6, v6, v7
	v_cvt_pk_bf16_f32 v7, v8, v9
	s_add_i32 s34, s34, s44
	v_permlane32_swap_b32_e32 v52, v54
	v_permlane32_swap_b32_e32 v53, v55
	v_permlane32_swap_b32_e32 v36, v38
	v_permlane32_swap_b32_e32 v37, v39
	v_permlane32_swap_b32_e32 v20, v22
	v_permlane32_swap_b32_e32 v21, v23
	v_permlane32_swap_b32_e32 v4, v6
	v_permlane32_swap_b32_e32 v5, v7
	s_cmpk_gt_i32 s34, 0x1ff
	global_store_dwordx4 v[70:71], v[52:55], off offset:32
	global_store_dwordx4 v[70:71], v[36:39], off offset:96
	global_store_dwordx4 v[70:71], v[20:23], off offset:160
	global_store_dwordx4 v[70:71], v[4:7], off offset:224
	s_cbranch_scc1 .LBB0_594
; #define LAS __attribute__((address_space(3)))
; DI void attn_quad(LAS unsigned char* lds, const bf16_t* Z, bf16_t* BR, int c0  , int head, const LAS float* tbl, int tid) {
;     const int lane = tid & 63, w = __builtin_amdgcn_readfirstlane(tid >> 6), r = lane & 31, h = lane >> 5;
;     const int qc = w >> 1, qh = w & 1;
;     const int lq = lane >> 4, chp = lane & 15;
;     const int n0 = c0 & 127, j0 = n0 < 8 ? 8 - n0 : 0;
;     const bf16_t* Qp = Z + (size_t)((c0 + qc) * 64 + qh * 32) * ZLD + C_QC + head * 128;
;     bf16_t* Op = BR + (size_t)((c0 + qc) * 64 + qh * 32) * 3072 + 2048 + head * 128;
;     ...
;     bf16x8 qf[8];
; #pragma unroll
;     for (int ks = 0; ks < 8; ++ks) qf[ks] = *(const bf16x8*)(Qp + (size_t)r * ZLD + ks * 16 + h * 8);
;     f32x16 o[4];
; #pragma unroll
;     for (int db = 0; db < 4; ++db)
; #pragma unroll
;         for (int i = 0; i < 16; ++i) o[db][i] = 0.f;
;     float mrun = -1e30f, lrun = 0.f;
;     const float sc = 0.08838834764831845f * LOG2E;
;     const int kx = 16 * (h ^ (((r & 3) << 2) | ((r >> 2) & 3)));
;     const int blk = (lane >> 4) & 1, q = (lane & 15) >> 2, p = lane & 3;
;     const int vlo = 2 * blk + (p >> 1);
;     const int qbase = qh * 32;
;     AQ_ISSUE(j0); if (j0 + 1 < 12) AQ_ISSUE(j0 + 1); if (j0 + 2 < 12) AQ_ISSUE(j0 + 2);
.LBB0_563:
	s_and_b32 s4, s34, 7
	s_mul_i32 s10, s4, 0x410
	s_ashr_i32 s5, s34, 1
	s_add_i32 s22, s10, 0
	v_readfirstlane_b32 s10, v146
	s_and_b32 s26, s5, -4
	s_ashr_i32 s35, s10, 6
	s_ashr_i32 s23, s10, 7
	s_and_b32 s43, s5, 0x7c
	s_add_i32 s5, s23, s26
	s_lshl_b32 s10, s35, 5
	s_lshl_b32 s5, s5, 6
	s_and_b32 s27, s10, 32
	s_or_b32 s10, s5, s27
	s_add_i32 s22, s22, 0x20100
	s_mul_i32 s11, s10, 0x3400
	s_mul_hi_i32 s5, s10, 0x3400
	s_add_u32 s38, s8, s11
	s_addc_u32 s5, s9, s5
	s_lshl_b32 s11, s4, 7
	s_lshl_b32 s42, s4, 8
	s_add_u32 s4, s38, s42
	s_addc_u32 s5, s5, 0
	v_lshlrev_b32_e32 v2, 1, v182
	v_lshl_add_u64 v[4:5], s[4:5], 0, v[2:3]
	v_mov_b32_e32 v149, v3
	v_lshl_add_u64 v[4:5], v[4:5], 0, v[148:149]
	s_mov_b64 s[4:5], 0x1c00
	v_sub_u32_e64 v12, 8, s43 clamp
	v_lshl_add_u64 v[6:7], v[4:5], 0, s[4:5]
	v_readfirstlane_b32 s4, v12
	s_add_i32 s45, s26, s4
	s_mul_i32 s46, s45, 0xd0000
	s_add_i32 s4, s45, -8
	s_add_i32 s5, s46, 0xff980000
	s_mul_hi_i32 s4, s4, 0xd0000
	s_add_u32 s5, s8, s5
	s_addc_u32 s4, s9, s4
	s_add_u32 s5, s5, s42
	s_addc_u32 s38, s4, 0
	s_add_u32 s4, s5, 0x2400
	s_addc_u32 s5, s38, 0
	s_lshl_b32 s47, s35, 3
	s_lshl_b32 s38, s35, 1
	v_add_co_u32_e32 v4, vcc, s33, v4
	v_or_b32_e32 v2, s47, v180
	s_and_b32 s38, s38, 2
	s_movk_i32 s49, 0x1a00
	v_addc_co_u32_e32 v5, vcc, 0, v5, vcc
	v_bitop3_b32 v13, s38, v177, v181 bitop3:0x36
	v_mad_i64_i32 v[132:133], s[38:39], v2, s49, 0
	s_load_dwordx2 s[40:41], s[0:1], 0xd0
	s_waitcnt lgkmcnt(0)
	s_waitcnt lgkmcnt(0)
	global_load_dwordx4 v[124:127], v[6:7], off offset:32
	global_load_dwordx4 v[120:123], v[6:7], off offset:64
	global_load_dwordx4 v[116:119], v[6:7], off offset:96
	global_load_dwordx4 v[112:115], v[6:7], off offset:128
	global_load_dwordx4 v[108:111], v[6:7], off offset:160
	global_load_dwordx4 v[104:107], v[6:7], off offset:192
	global_load_dwordx4 v[128:131], v[4:5], off offset:3072
	global_load_dwordx4 v[100:103], v[6:7], off offset:224
	v_lshlrev_b64 v[4:5], 1, v[132:133]
	s_lshl_b32 s35, s35, 11
	v_lshl_add_u64 v[6:7], s[4:5], 0, v[4:5]
	v_lshlrev_b32_e32 v2, 4, v13
	s_add_i32 s48, s35, 0
	v_lshl_add_u64 v[6:7], v[6:7], 0, v[2:3]
	s_mov_b32 m0, s48
	s_or_b32 s47, s47, 4
	global_load_lds_dwordx4 v[6:7], off
	v_lshl_add_u64 v[6:7], v[6:7], 0, s[36:37]
	s_add_i32 m0, s48, 0x4000
	s_bfe_u32 s38, s47, 0x20002
	global_load_lds_dwordx4 v[6:7], off
	v_or_b32_e32 v6, s47, v180
	v_bitop3_b32 v14, s38, v177, v181 bitop3:0x36
	v_mad_i64_i32 v[134:135], s[38:39], v6, s49, 0
	v_lshlrev_b64 v[6:7], 1, v[134:135]
	s_lshl_b32 s38, s47, 8
	v_lshl_add_u64 v[8:9], s[4:5], 0, v[6:7]
	v_lshlrev_b32_e32 v10, 4, v14
	v_mov_b32_e32 v11, v3
	s_add_i32 s39, s38, 0
	v_lshl_add_u64 v[8:9], v[8:9], 0, v[10:11]
	s_mov_b32 m0, s39
	s_add_i32 s4, s45, -7
	global_load_lds_dwordx4 v[8:9], off
	s_add_i32 m0, s39, 0x4000
	s_add_i32 s5, s46, 0xffa50000
	s_mul_hi_i32 s4, s4, 0xd0000
	s_add_u32 s5, s8, s5
	s_addc_u32 s4, s9, s4
	s_add_u32 s5, s5, s42
	s_addc_u32 s47, s4, 0
	s_add_u32 s4, s5, 0x2400
	v_lshl_add_u64 v[8:9], v[8:9], 0, s[36:37]
	s_addc_u32 s5, s47, 0
	global_load_lds_dwordx4 v[8:9], off
	v_lshl_add_u64 v[8:9], s[4:5], 0, v[4:5]
	v_lshl_add_u64 v[8:9], v[8:9], 0, v[2:3]
	s_add_i32 m0, s48, 0x8000
	s_add_i32 s45, s45, -6
	global_load_lds_dwordx4 v[8:9], off
	v_lshl_add_u64 v[8:9], v[8:9], 0, s[36:37]
	s_add_i32 m0, s48, 0xc000
	s_add_i32 s46, s46, 0xffb20000
	global_load_lds_dwordx4 v[8:9], off
	v_lshl_add_u64 v[8:9], s[4:5], 0, v[6:7]
	v_lshl_add_u64 v[8:9], v[8:9], 0, v[10:11]
	s_add_i32 m0, s39, 0x8000
	s_mul_hi_i32 s4, s45, 0xd0000
	global_load_lds_dwordx4 v[8:9], off
	s_add_i32 m0, s39, 0xc000
	s_add_u32 s5, s8, s46
	s_addc_u32 s4, s9, s4
	s_add_u32 s5, s5, s42
	s_addc_u32 s39, s4, 0
	s_add_u32 s4, s5, 0x2400
	s_addc_u32 s5, s39, 0
	v_lshl_add_u64 v[8:9], v[8:9], 0, s[36:37]
	v_lshl_add_u64 v[4:5], s[4:5], 0, v[4:5]
	global_load_lds_dwordx4 v[8:9], off
	v_lshl_add_u64 v[4:5], v[4:5], 0, v[2:3]
	s_add_i32 m0, s18, s35
	v_lshlrev_b32_e32 v20, 3, v14
	global_load_lds_dwordx4 v[4:5], off
	v_lshl_add_u64 v[4:5], v[4:5], 0, s[36:37]
	s_add_i32 m0, s19, s35
	v_mov_b32_e32 v18, v3
	global_load_lds_dwordx4 v[4:5], off
	v_lshl_add_u64 v[4:5], s[4:5], 0, v[6:7]
	v_lshl_add_u64 v[4:5], v[4:5], 0, v[10:11]
	s_add_i32 m0, s18, s38
	s_min_u32 s4, s43, 8
	global_load_lds_dwordx4 v[4:5], off
	v_lshl_add_u64 v[4:5], v[4:5], 0, s[36:37]
	s_add_i32 m0, s19, s38
	s_lshl_b32 s5, s4, 15
	global_load_lds_dwordx4 v[4:5], off
	s_lshl_b32 s45, s4, 6
	s_add_i32 s4, s23, s4
	s_lshl_b32 s4, s4, 6
	v_mov_b32_e32 v19, v3
	v_readfirstlane_b32 s42, v12
	v_lshlrev_b32_e32 v2, 3, v13
	s_or_b32 s4, s27, s4
	v_mov_b32_e32 v4, v3
	v_mov_b32_e32 v5, v3
	v_mov_b32_e32 v6, v3
	v_mov_b32_e32 v7, v3
	v_mov_b32_e32 v8, v3
	v_mov_b32_e32 v9, v3
	v_mov_b32_e32 v10, v3
	v_mov_b32_e32 v12, v3
	v_mov_b32_e32 v13, v3
	v_mov_b32_e32 v14, v3
	v_mov_b32_e32 v15, v3
	v_mov_b32_e32 v16, v3
	v_mov_b32_e32 v17, v3
	v_lshlrev_b32_e32 v136, 1, v20
	v_mov_b64_e32 v[34:35], v[18:19]
	v_mov_b64_e32 v[50:51], v[18:19]
	v_mov_b64_e32 v[66:67], v[18:19]
	s_mov_b32 s39, 0
	s_sub_i32 s43, 0x58000, s5
	v_add_u32_e32 v151, s4, v144
	s_sub_i32 s46, 0, s23
	v_mov_b32_e32 v145, 0
	v_mov_b32_e32 v149, 0xf149f2ca
	v_lshlrev_b32_e32 v2, 1, v2
	v_mov_b64_e32 v[32:33], v[16:17]
	v_mov_b64_e32 v[30:31], v[14:15]
	v_mov_b64_e32 v[28:29], v[12:13]
	v_mov_b64_e32 v[26:27], v[10:11]
	v_mov_b64_e32 v[24:25], v[8:9]
	v_mov_b64_e32 v[22:23], v[6:7]
	v_mov_b64_e32 v[20:21], v[4:5]
	v_mov_b64_e32 v[48:49], v[16:17]
	v_mov_b64_e32 v[46:47], v[14:15]
	v_mov_b64_e32 v[44:45], v[12:13]
	v_mov_b64_e32 v[42:43], v[10:11]
	v_mov_b64_e32 v[40:41], v[8:9]
	v_mov_b64_e32 v[38:39], v[6:7]
	v_mov_b64_e32 v[36:37], v[4:5]
	v_mov_b64_e32 v[64:65], v[16:17]
	v_mov_b64_e32 v[62:63], v[14:15]
	v_mov_b64_e32 v[60:61], v[12:13]
	v_mov_b64_e32 v[58:59], v[10:11]
	v_mov_b64_e32 v[56:57], v[8:9]
	v_mov_b64_e32 v[54:55], v[6:7]
	v_mov_b64_e32 v[52:53], v[4:5]
	s_waitcnt vmcnt(0)
	s_branch .LBB0_566

; DI unsigned pk2(float a, float b) { f32x2 v = {a, b}; bf16v2 r = __builtin_convertvector(v, bf16v2); return __builtin_bit_cast(unsigned, r); }
; #define WSP(T, off) ((T*)(kws() + (off)))
; template <int MODE, class Src>
; DI void attn_item(LAS unsigned char* lds, const Src& src, const bf16_t* Qp  , bf16_t* Op  , int nband, int jj0, float sink_l2, const LAS float* tbl, int qbase, int tid) {
;     ...
;     const float inv = 1.0f / lrun;
; #pragma unroll
;     for (int db = 0; db < 4; ++db)
; #pragma unroll
;         for (int gp = 0; gp < 4; gp += 2) {
;             u32x2 a, b;
;             a.x = pk2(o[db][4 * gp] * inv, o[db][4 * gp + 1] * inv); a.y = pk2(o[db][4 * gp + 2] * inv, o[db][4 * gp + 3] * inv);
;             b.x = pk2(o[db][4 * gp + 4] * inv, o[db][4 * gp + 5] * inv); b.y = pk2(o[db][4 * gp + 6] * inv, o[db][4 * gp + 7] * inv);
;             const auto r0 = __builtin_amdgcn_permlane32_swap(a.x, b.x, false, false); const auto r1 = __builtin_amdgcn_permlane32_swap(a.y, b.y, false, false);
;             u32x4 w; w.x = r0[0]; w.y = r1[0]; w.z = r0[1]; w.w = r1[1];
;             *(u32x4*)(Op + (size_t)r * 3072 + db * 32 + 8 * gp + 8 * h) = w;
;         }
; __global__ void __launch_bounds__(NTHR, 2) fwd_kernel(Args args) {
;     ...
;                     for (int u = c.bid; u < 64; u += (nsmp ? nsmp : c.G)) {
;                         const int hg = u & 1, chunk = 256 + (u >> 1), head = hg * 4 + (c.wave >> 1), qh = c.wave & 1;
;                         const bf16_t* Z = WSP(bf16_t, WS_Z);
;                         SrcCb src{Z, WSP(bf16_t, WS_KCC), WSP(bf16_t, WS_VTCC), chunk, hg * 4};
;                         attn_item<1>(c.lds, src, Z + (size_t)(chunk * 64 + qh * 32) * ZLD + C_QC + head * 128, WSP(bf16_t, WS_BR) + (size_t)(chunk * 64 + qh * 32) * 3072 + 2048 + head * 128, 9, 0,
;                                      0.f, tbl + head * 260, qh * 32, c.tid);
.LBB0_597:
	s_mul_hi_i32 s4, s45, 0x1800
	s_mulk_i32 s45, 0x1800
	s_add_u32 s5, s38, s45
	s_addc_u32 s8, s39, s4
	s_add_u32 s4, s5, s34
	s_addc_u32 s5, s8, s35
	v_div_scale_f32 v2, s[8:9], v192, v192, 1.0
	v_rcp_f32_e32 v4, v2
	v_mov_b32_e32 v151, v3
	v_mov_b32_e32 v149, v3
	s_add_i32 s23, s23, s22
	v_fma_f32 v5, -v2, v4, 1.0
	v_fmac_f32_e32 v4, v5, v4
	v_div_scale_f32 v5, vcc, 1.0, v192, 1.0
	v_mul_f32_e32 v6, v5, v4
	v_fma_f32 v7, -v2, v6, v5
	v_fmac_f32_e32 v6, v7, v4
	v_fma_f32 v2, -v2, v6, v5
	v_div_fmas_f32 v2, v2, v4, v6
	v_div_fixup_f32 v2, v2, v192, 1.0
	v_lshl_add_u64 v[4:5], s[4:5], 0, v[150:151]
	v_lshl_add_u64 v[8:9], v[4:5], 0, v[148:149]
	s_mov_b64 s[4:5], 0x45857000
	v_pk_mul_f32 v[4:5], v[2:3], v[66:67] op_sel_hi:[0,1]
	v_pk_mul_f32 v[6:7], v[2:3], v[68:69] op_sel_hi:[0,1]
	v_lshl_add_u64 v[10:11], v[8:9], 0, s[4:5]
	v_cvt_pk_bf16_f32 v4, v4, v5
	v_cvt_pk_bf16_f32 v5, v6, v7
	v_pk_mul_f32 v[6:7], v[2:3], v[70:71] op_sel_hi:[0,1]
	v_pk_mul_f32 v[12:13], v[2:3], v[72:73] op_sel_hi:[0,1]
	s_mov_b32 s4, 0x45857000
	v_cvt_pk_bf16_f32 v6, v6, v7
	v_cvt_pk_bf16_f32 v7, v12, v13
	v_add_co_u32_e32 v8, vcc, s4, v8
	v_permlane32_swap_b32_e32 v4, v6
	v_permlane32_swap_b32_e32 v5, v7
	v_addc_co_u32_e32 v9, vcc, 0, v9, vcc
	global_store_dwordx4 v[8:9], v[4:7], off
	v_pk_mul_f32 v[8:9], v[2:3], v[80:81] op_sel_hi:[0,1]
	s_cmp_gt_i32 s23, 63
	v_pk_mul_f32 v[4:5], v[2:3], v[74:75] op_sel_hi:[0,1]
	v_pk_mul_f32 v[6:7], v[2:3], v[76:77] op_sel_hi:[0,1]
	v_cvt_pk_bf16_f32 v4, v4, v5
	v_cvt_pk_bf16_f32 v5, v6, v7
	v_pk_mul_f32 v[6:7], v[2:3], v[78:79] op_sel_hi:[0,1]
	v_cvt_pk_bf16_f32 v6, v6, v7
	v_cvt_pk_bf16_f32 v7, v8, v9
	s_nop 0
	v_permlane32_swap_b32_e32 v4, v6
	v_permlane32_swap_b32_e32 v5, v7
	global_store_dwordx4 v[10:11], v[4:7], off offset:32
	v_pk_mul_f32 v[8:9], v[2:3], v[56:57] op_sel_hi:[0,1]
	s_mov_b32 s97, 0x1000000
	v_pk_mul_f32 v[4:5], v[2:3], v[50:51] op_sel_hi:[0,1]
	v_pk_mul_f32 v[6:7], v[2:3], v[52:53] op_sel_hi:[0,1]
	v_cvt_pk_bf16_f32 v4, v4, v5
	v_cvt_pk_bf16_f32 v5, v6, v7
	v_pk_mul_f32 v[6:7], v[2:3], v[54:55] op_sel_hi:[0,1]
	v_cvt_pk_bf16_f32 v6, v6, v7
	v_cvt_pk_bf16_f32 v7, v8, v9
	s_nop 0
	v_permlane32_swap_b32_e32 v4, v6
	v_permlane32_swap_b32_e32 v5, v7
	global_store_dwordx4 v[10:11], v[4:7], off offset:64
	v_pk_mul_f32 v[8:9], v[2:3], v[64:65] op_sel_hi:[0,1]
	s_movk_i32 s88, 0xf000
	v_pk_mul_f32 v[4:5], v[2:3], v[58:59] op_sel_hi:[0,1]
	v_pk_mul_f32 v[6:7], v[2:3], v[60:61] op_sel_hi:[0,1]
	v_cvt_pk_bf16_f32 v4, v4, v5
	v_cvt_pk_bf16_f32 v5, v6, v7
	v_pk_mul_f32 v[6:7], v[2:3], v[62:63] op_sel_hi:[0,1]
	v_cvt_pk_bf16_f32 v6, v6, v7
	v_cvt_pk_bf16_f32 v7, v8, v9
	s_nop 0
	v_permlane32_swap_b32_e32 v4, v6
	v_permlane32_swap_b32_e32 v5, v7
	global_store_dwordx4 v[10:11], v[4:7], off offset:96
	v_pk_mul_f32 v[8:9], v[2:3], v[40:41] op_sel_hi:[0,1]
	s_nop 0
	v_pk_mul_f32 v[4:5], v[2:3], v[34:35] op_sel_hi:[0,1]
	v_pk_mul_f32 v[6:7], v[2:3], v[36:37] op_sel_hi:[0,1]
	v_cvt_pk_bf16_f32 v4, v4, v5
	v_cvt_pk_bf16_f32 v5, v6, v7
	v_pk_mul_f32 v[6:7], v[2:3], v[38:39] op_sel_hi:[0,1]
	v_cvt_pk_bf16_f32 v6, v6, v7
	v_cvt_pk_bf16_f32 v7, v8, v9
	s_nop 0
	v_permlane32_swap_b32_e32 v4, v6
	v_permlane32_swap_b32_e32 v5, v7
	global_store_dwordx4 v[10:11], v[4:7], off offset:128
	v_pk_mul_f32 v[8:9], v[2:3], v[48:49] op_sel_hi:[0,1]
	s_nop 0
	v_pk_mul_f32 v[4:5], v[2:3], v[42:43] op_sel_hi:[0,1]
	v_pk_mul_f32 v[6:7], v[2:3], v[44:45] op_sel_hi:[0,1]
	v_cvt_pk_bf16_f32 v4, v4, v5
	v_cvt_pk_bf16_f32 v5, v6, v7
	v_pk_mul_f32 v[6:7], v[2:3], v[46:47] op_sel_hi:[0,1]
	v_cvt_pk_bf16_f32 v6, v6, v7
	v_cvt_pk_bf16_f32 v7, v8, v9
	s_nop 0
	v_permlane32_swap_b32_e32 v4, v6
	v_permlane32_swap_b32_e32 v5, v7
	global_store_dwordx4 v[10:11], v[4:7], off offset:160
	v_pk_mul_f32 v[8:9], v[2:3], v[24:25] op_sel_hi:[0,1]
	s_nop 0
	v_pk_mul_f32 v[4:5], v[2:3], v[18:19] op_sel_hi:[0,1]
	v_pk_mul_f32 v[6:7], v[2:3], v[20:21] op_sel_hi:[0,1]
	v_cvt_pk_bf16_f32 v4, v4, v5
	v_cvt_pk_bf16_f32 v5, v6, v7
	v_pk_mul_f32 v[6:7], v[2:3], v[22:23] op_sel_hi:[0,1]
	v_cvt_pk_bf16_f32 v6, v6, v7
	v_cvt_pk_bf16_f32 v7, v8, v9
	s_nop 0
	v_permlane32_swap_b32_e32 v4, v6
	v_permlane32_swap_b32_e32 v5, v7
	global_store_dwordx4 v[10:11], v[4:7], off offset:192
	v_pk_mul_f32 v[8:9], v[2:3], v[32:33] op_sel_hi:[0,1]
	s_nop 0
	v_pk_mul_f32 v[4:5], v[2:3], v[26:27] op_sel_hi:[0,1]
	v_pk_mul_f32 v[6:7], v[2:3], v[28:29] op_sel_hi:[0,1]
	v_cvt_pk_bf16_f32 v4, v4, v5
	v_cvt_pk_bf16_f32 v5, v6, v7
	v_pk_mul_f32 v[6:7], v[2:3], v[30:31] op_sel_hi:[0,1]
	v_cvt_pk_bf16_f32 v6, v6, v7
	v_cvt_pk_bf16_f32 v7, v8, v9
	s_nop 0
	v_permlane32_swap_b32_e32 v4, v6
	v_permlane32_swap_b32_e32 v5, v7
	global_store_dwordx4 v[10:11], v[4:7], off offset:224
	s_cbranch_scc1 .LBB0_750
.LBB0_598:
	s_lshl_b32 s4, s23, 2
	s_ashr_i32 s56, s23, 1
	s_and_b32 s52, s4, 4
	s_add_i32 s57, s56, 0x100
	s_add_i32 s60, s52, s10
	s_load_dwordx2 s[42:43], s[0:1], 0xd0
	s_waitcnt lgkmcnt(0)
	s_add_u32 s58, s42, 0x26456000
	s_addc_u32 s59, s43, 0
	s_load_dwordx2 s[4:5], s[0:1], 0xd0
	s_waitcnt lgkmcnt(0)
	s_add_u32 s26, s4, 0x38856000
	s_addc_u32 s27, s5, 0
	s_lshl_b32 s8, s57, 6
	s_or_b32 s45, s8, s11
	s_mul_i32 s9, s45, 0x3400
	s_mul_hi_i32 s8, s45, 0x3400
	s_add_u32 s12, s58, s9
	s_addc_u32 s38, s59, s8
	s_lshl_b32 s8, s60, 7
	s_ashr_i32 s9, s8, 31
	s_lshl_b64 s[34:35], s[8:9], 1
	s_add_u32 s8, s12, s34
	s_addc_u32 s9, s38, s35
	v_lshlrev_b32_e32 v2, 1, v182
	v_lshl_add_u64 v[4:5], s[8:9], 0, v[2:3]
	v_mov_b32_e32 v149, v3
	v_lshl_add_u64 v[4:5], v[4:5], 0, v[148:149]
	s_mov_b64 s[8:9], 0x1c00
	v_lshl_add_u64 v[6:7], v[4:5], 0, s[8:9]
	v_add_co_u32_e32 v4, vcc, s33, v4
	s_load_dwordx2 s[4:5], s[0:1], 0xd0
	s_waitcnt lgkmcnt(0)
	s_load_dwordx2 s[38:39], s[0:1], 0xd0
	s_waitcnt lgkmcnt(0)
	s_cmp_gt_i32 s56, -1
	s_nop 0
	v_addc_co_u32_e32 v5, vcc, 0, v5, vcc
	s_waitcnt lgkmcnt(0)
	global_load_dwordx4 v[114:117], v[4:5], off offset:3072
	global_load_dwordx4 v[118:121], v[6:7], off offset:32
	global_load_dwordx4 v[122:125], v[6:7], off offset:64
	global_load_dwordx4 v[126:129], v[6:7], off offset:96
	global_load_dwordx4 v[130:133], v[6:7], off offset:128
	global_load_dwordx4 v[134:137], v[6:7], off offset:160
	global_load_dwordx4 v[138:141], v[6:7], off offset:192
	global_load_dwordx4 v[142:145], v[6:7], off offset:224
	s_cselect_b64 s[50:51], -1, 0
	v_readfirstlane_b32 s53, v146
	s_mov_b64 s[40:41], -1
	s_and_b64 vcc, exec, s[50:51]
	s_cbranch_vccz .LBB0_600
	s_lshl_b32 s8, s57, 9
	s_add_i32 s12, s8, 0xfffe0000
	s_lshl_b64 s[8:9], s[12:13], 11
	s_add_u32 s8, s26, s8
	s_addc_u32 s9, s27, s9
	s_mov_b64 s[40:41], 0

; #define LAS __attribute__((address_space(3)))
; template <int I> DI const float* kin() { return (const float*)karg64<I * 8>(); }
; #define WSP(T, off) ((T*)(kws() + (off)))
; template <int MODE, class Src>
; DI void attn_item(LAS unsigned char* lds, const Src& src, const bf16_t* Qp  , bf16_t* Op  , int nband, int jj0, float sink_l2, const LAS float* tbl, int qbase, int tid) {
;     ...
;     const int lane = tid & 63, w = __builtin_amdgcn_readfirstlane(tid >> 6), r = lane & 31, h = lane >> 5;
;     const int hl = MODE ? (w >> 1) : 0;
;     const int lq = lane >> 4, chp = lane & 15;
;     ...
;     bf16x8 qf[8];
; #pragma unroll
;     for (int ks = 0; ks < 8; ++ks) qf[ks] = *(const bf16x8*)(Qp + (size_t)r * ZLD + ks * 16 + h * 8);
;     f32x16 o[4];
; #pragma unroll
;     for (int db = 0; db < 4; ++db)
; #pragma unroll
;         for (int i = 0; i < 16; ++i) o[db][i] = 0.f;
;     float mrun = MODE == 0 ? sink_l2 : -1e30f, lrun = MODE == 0 ? 1.f : 0.f;
;     const float sc = 0.08838834764831845f * LOG2E;
;     const LAS unsigned char* Kt = lds + hl * 16384 + 256 * r;
;     const int kx = 16 * (h ^ (((r & 3) << 2) | ((r >> 2) & 3)));
;     const int blk = (lane >> 4) & 1, q = (lane & 15) >> 2, p = lane & 3;
;     const LAS unsigned char* Vt = lds + 65536 + hl * 16384 + 256 * (4 * h + q) + 8 * (p & 1);
;     const int vlo = 2 * blk + (p >> 1);
;     ATT_ISSUE(jj0, false); ATT_ISSUE(jj0, true);
; __global__ void __launch_bounds__(NTHR, 2) fwd_kernel(Args args) {
;     ...
;                     if (nsmp) {
;                         const int u = 512 + c.bid, chunk = u >> 1, kv = u & 1, head = kv * 4 + (c.wave >> 1), qh = c.wave & 1;
;                         const bf16_t* Z = WSP(bf16_t, WS_Z);
;                         SrcSwa src{Z, WSP(bf16_t, WS_KCB), WSP(bf16_t, WS_VTCB), chunk, kv};
;                         attn_item<0>(c.lds, src, Z + (size_t)(chunk * 64 + qh * 32) * ZLD + C_QB + head * 128, WSP(bf16_t, WS_BR) + (size_t)(chunk * 64 + qh * 32) * 3072 + 1024 + head * 128, 3, 0,
;                                      kin<17>()[l * 8 + head] * LOG2E, nullptr, 0, c.tid);
.LBB0_750:
	s_and_b64 vcc, exec, s[18:19]
	s_cbranch_vccz .LBB0_780
	v_readlane_b32 s4, v253, 59
	s_add_i32 s8, s10, s4
	v_readlane_b32 s4, v253, 60
	s_lshl_b32 s9, s70, 3
	s_or_b32 s10, s11, s4
	s_lshl_b32 s4, s8, 7
	s_add_i32 s22, s8, s9
	s_ashr_i32 s5, s4, 31
	s_ashr_i32 s23, s22, 31
	s_add_i32 s38, 0, 0x10000
	s_load_dwordx2 s[18:19], s[0:1], 0xd0
	s_waitcnt lgkmcnt(0)
	s_add_u32 s39, s18, 0x26456000
	s_addc_u32 s40, s19, 0
	s_load_dwordx2 s[8:9], s[0:1], 0xd0
	s_waitcnt lgkmcnt(0)
	s_add_u32 s41, s8, 0x38456000
	s_addc_u32 s42, s9, 0
	s_load_dwordx2 s[8:9], s[0:1], 0xd0
	s_waitcnt lgkmcnt(0)
	s_add_u32 s43, s8, 0x38656000
	s_mul_i32 s12, s10, 0x3400
	s_addc_u32 s50, s9, 0
	s_mul_hi_i32 s11, s10, 0x3400
	s_add_u32 s8, s39, s12
	s_addc_u32 s9, s40, s11
	s_lshl_b64 s[4:5], s[4:5], 1
	s_add_u32 s26, s8, s4
	s_addc_u32 s27, s9, s5
	s_lshl_b64 s[22:23], s[22:23], 2
	s_load_dwordx2 s[8:9], s[0:1], 0xd0
	s_waitcnt lgkmcnt(0)
	s_load_dwordx2 s[34:35], s[0:1], 0x88
	s_waitcnt lgkmcnt(0)
	s_add_u32 s22, s34, s22
	v_readfirstlane_b32 s11, v146
	s_addc_u32 s23, s35, s23
	s_ashr_i32 s11, s11, 3
	s_and_b32 s12, s11, -8
	s_lshr_b32 s11, s11, 2
	s_and_b32 s11, s11, 2
	v_readlane_b32 s56, v253, 63
	v_mov_b64_e32 v[4:5], s[22:23]
	v_lshlrev_b32_e32 v2, 1, v182
	v_bitop3_b32 v13, s11, v177, v181 bitop3:0x36
	v_readlane_b32 s57, v254, 0
	s_add_u32 s11, s41, s56
	global_load_dword v12, v[4:5], off
	v_lshl_add_u64 v[4:5], s[26:27], 0, v[2:3]
	s_addc_u32 s26, s42, s57
	v_readlane_b32 s22, v254, 1
	s_add_u32 s45, s39, s22
	v_readlane_b32 s22, v254, 58
	s_addc_u32 s51, s40, s22
	s_add_u32 s27, s45, 0x1800
	v_readlane_b32 s54, v254, 24
	s_addc_u32 s34, s51, 0
	v_readlane_b32 s55, v254, 25
	v_mov_b32_e32 v149, v3
	s_and_b64 s[22:23], s[54:55], exec
	v_lshl_add_u64 v[4:5], v[4:5], 0, v[148:149]
	s_cselect_b32 s23, s27, s11
	v_readlane_b32 s11, v254, 2
	v_lshl_add_u64 v[6:7], v[4:5], 0, s[28:29]
	v_add_co_u32_e32 v4, vcc, s33, v4
	s_cselect_b32 s22, s34, s26
	s_lshl_b32 s11, s11, 1
	v_addc_co_u32_e32 v5, vcc, 0, v5, vcc
	v_or_b32_e32 v152, s12, v180
	s_add_u32 s26, s23, s11
	v_readlane_b32 s34, v254, 26
	s_waitcnt lgkmcnt(0)
	global_load_dwordx4 v[114:117], v[6:7], off offset:32
	global_load_dwordx4 v[118:121], v[6:7], off offset:64
	global_load_dwordx4 v[122:125], v[6:7], off offset:96
	global_load_dwordx4 v[126:129], v[6:7], off offset:128
	global_load_dwordx4 v[130:133], v[6:7], off offset:160
	global_load_dwordx4 v[134:137], v[6:7], off offset:192
	global_load_dwordx4 v[138:141], v[4:5], off
	global_load_dwordx4 v[142:145], v[6:7], off offset:224
	s_addc_u32 s27, s22, 0
	v_mad_i64_i32 v[4:5], s[22:23], s34, v152, 0
	v_lshlrev_b64 v[4:5], 1, v[4:5]
	s_lshl_b32 s52, s12, 8
	v_lshl_add_u64 v[6:7], s[26:27], 0, v[4:5]
	v_lshlrev_b32_e32 v2, 4, v13
	s_add_i32 s22, s52, 0
	s_or_b32 s12, s12, 4
	v_lshl_add_u64 v[6:7], v[6:7], 0, v[2:3]
	s_mov_b32 m0, s22
	v_or_b32_e32 v154, s12, v180
	s_bfe_u32 s23, s12, 0x20002
	s_lshl_b32 s12, s12, 8
	global_load_lds_dwordx4 v[6:7], off
	v_bitop3_b32 v14, s23, v177, v181 bitop3:0x36
	v_mad_i64_i32 v[6:7], s[34:35], s34, v154, 0
	s_add_i32 s23, s12, 0
	s_add_u32 s34, s43, s56
	s_addc_u32 s35, s50, s57
	s_add_u32 s45, s45, 0x1a00
	v_lshlrev_b64 v[6:7], 1, v[6:7]
	s_addc_u32 s51, s51, 0
	v_lshl_add_u64 v[8:9], s[26:27], 0, v[6:7]
	s_and_b64 s[26:27], s[54:55], exec
	s_cselect_b32 s26, s45, s34
	s_cselect_b32 s27, s51, s35
	s_add_u32 s26, s26, s11
	v_lshlrev_b32_e32 v10, 4, v14
	v_mov_b32_e32 v11, v3
	s_addc_u32 s27, s27, 0
	v_lshl_add_u64 v[8:9], v[8:9], 0, v[10:11]
	s_mov_b32 m0, s23
	v_lshl_add_u64 v[4:5], s[26:27], 0, v[4:5]
	global_load_lds_dwordx4 v[8:9], off
	v_lshl_add_u64 v[4:5], v[4:5], 0, v[2:3]
	s_add_i32 m0, s38, s52
	v_lshl_add_u32 v1, v1, 10, s38
	global_load_lds_dwordx4 v[4:5], off
	v_lshl_add_u64 v[4:5], s[26:27], 0, v[6:7]
	v_lshl_add_u64 v[4:5], v[4:5], 0, v[10:11]
	s_add_i32 m0, s38, s12
	v_readlane_b32 s12, v252, 5
	global_load_lds_dwordx4 v[4:5], off
	s_add_u32 s12, s39, s12
	v_readlane_b32 s26, v254, 60
	s_addc_u32 s34, s40, s26
	s_add_u32 s26, s12, 0x1800
	s_addc_u32 s27, s34, 0
	v_readlane_b32 s38, v254, 3
	v_readlane_b32 s39, v254, 4
	s_add_u32 s45, s41, s38
	s_addc_u32 s52, s42, s39
	s_add_u32 s53, s12, 0x1a00
	s_addc_u32 s54, s34, 0
	v_lshlrev_b32_e32 v2, 6, v177
	s_add_u32 s55, s43, s38
	v_and_b32_e32 v2, 0x300, v2
	s_addc_u32 s56, s50, s39
	v_readlane_b32 s12, v252, 6
	v_mov_b32_e32 v16, v3
	v_mov_b32_e32 v17, v3
	v_add3_u32 v155, v1, v2, v179
	s_waitcnt vmcnt(0)
	v_mul_f32_e32 v157, 0x3fb8aa3b, v12
	v_lshlrev_b32_e32 v156, 3, v13
	v_lshlrev_b32_e32 v158, 3, v14
	s_add_u32 s57, s18, s12
	v_readlane_b32 s12, v254, 61
	v_mov_b32_e32 v2, v3
	v_mov_b32_e32 v4, v3
	v_mov_b32_e32 v5, v3
	v_mov_b32_e32 v6, v3
	v_mov_b32_e32 v7, v3
	v_mov_b32_e32 v8, v3
	v_mov_b32_e32 v9, v3
	v_mov_b32_e32 v10, v3
	v_mov_b32_e32 v12, v3
	v_mov_b32_e32 v13, v3
	v_mov_b32_e32 v14, v3
	v_mov_b32_e32 v15, v3
	v_mov_b64_e32 v[32:33], v[16:17]
	v_mov_b64_e32 v[48:49], v[16:17]
	v_mov_b64_e32 v[64:65], v[16:17]
	v_mov_b64_e32 v[80:81], v[16:17]
	v_add_u32_e32 v153, 0, v178
	v_ashrrev_i32_e32 v1, 31, v152
	v_ashrrev_i32_e32 v149, 31, v154
	s_addc_u32 s58, s19, s12
	v_mov_b32_e32 v151, 1.0
	s_mov_b64 s[18:19], 0
	v_mov_b64_e32 v[30:31], v[14:15]
	v_mov_b64_e32 v[28:29], v[12:13]
	v_mov_b64_e32 v[26:27], v[10:11]
	v_mov_b64_e32 v[24:25], v[8:9]
	v_mov_b64_e32 v[22:23], v[6:7]
	v_mov_b64_e32 v[20:21], v[4:5]
	v_mov_b64_e32 v[18:19], v[2:3]
	v_mov_b64_e32 v[46:47], v[14:15]
	v_mov_b64_e32 v[44:45], v[12:13]
	v_mov_b64_e32 v[42:43], v[10:11]
	v_mov_b64_e32 v[40:41], v[8:9]
	v_mov_b64_e32 v[38:39], v[6:7]
	v_mov_b64_e32 v[36:37], v[4:5]
	v_mov_b64_e32 v[34:35], v[2:3]
	v_mov_b64_e32 v[62:63], v[14:15]
	v_mov_b64_e32 v[60:61], v[12:13]
	v_mov_b64_e32 v[58:59], v[10:11]
	v_mov_b64_e32 v[56:57], v[8:9]
	v_mov_b64_e32 v[54:55], v[6:7]
	v_mov_b64_e32 v[52:53], v[4:5]
	v_mov_b64_e32 v[50:51], v[2:3]
	v_mov_b64_e32 v[78:79], v[14:15]
	v_mov_b64_e32 v[76:77], v[12:13]
	v_mov_b64_e32 v[74:75], v[10:11]
	v_mov_b64_e32 v[72:73], v[8:9]
	v_mov_b64_e32 v[70:71], v[6:7]
	v_mov_b64_e32 v[68:69], v[4:5]
	v_mov_b64_e32 v[66:67], v[2:3]
	s_branch .LBB0_754

; DI unsigned pk2(float a, float b) { f32x2 v = {a, b}; bf16v2 r = __builtin_convertvector(v, bf16v2); return __builtin_bit_cast(unsigned, r); }
; template <int MODE, class Src>
; DI void attn_item(LAS unsigned char* lds, const Src& src, const bf16_t* Qp  , bf16_t* Op  , int nband, int jj0, float sink_l2, const LAS float* tbl, int qbase, int tid) {
;     ...
;     const float inv = 1.0f / lrun;
; #pragma unroll
;     for (int db = 0; db < 4; ++db)
; #pragma unroll
;         for (int gp = 0; gp < 4; gp += 2) {
;             u32x2 a, b;
;             a.x = pk2(o[db][4 * gp] * inv, o[db][4 * gp + 1] * inv); a.y = pk2(o[db][4 * gp + 2] * inv, o[db][4 * gp + 3] * inv);
;             b.x = pk2(o[db][4 * gp + 4] * inv, o[db][4 * gp + 5] * inv); b.y = pk2(o[db][4 * gp + 6] * inv, o[db][4 * gp + 7] * inv);
;             const auto r0 = __builtin_amdgcn_permlane32_swap(a.x, b.x, false, false); const auto r1 = __builtin_amdgcn_permlane32_swap(a.y, b.y, false, false);
;             u32x4 w; w.x = r0[0]; w.y = r1[0]; w.z = r0[1]; w.w = r1[1];
;             *(u32x4*)(Op + (size_t)r * 3072 + db * 32 + 8 * gp + 8 * h) = w;
;         }
.LBB0_779:
	s_mul_hi_i32 s11, s10, 0x1800
	s_mulk_i32 s10, 0x1800
	s_add_u32 s8, s8, s10
	s_addc_u32 s9, s9, s11
	s_add_u32 s4, s8, s4
	s_addc_u32 s5, s9, s5
	v_div_scale_f32 v1, s[8:9], v151, v151, 1.0
	v_rcp_f32_e32 v2, v1
	v_mov_b32_e32 v149, v3
	v_fma_f32 v4, -v1, v2, 1.0
	v_fmac_f32_e32 v2, v4, v2
	v_div_scale_f32 v4, vcc, 1.0, v151, 1.0
	v_mul_f32_e32 v5, v4, v2
	v_fma_f32 v6, -v1, v5, v4
	v_fmac_f32_e32 v5, v6, v2
	v_fma_f32 v1, -v1, v5, v4
	v_div_fmas_f32 v1, v1, v2, v5
	v_div_fixup_f32 v2, v1, v151, 1.0
	v_mov_b32_e32 v151, v3
	v_lshl_add_u64 v[4:5], s[4:5], 0, v[150:151]
	v_lshl_add_u64 v[8:9], v[4:5], 0, v[148:149]
	s_mov_b64 s[4:5], 0x45856800
	v_pk_mul_f32 v[4:5], v[2:3], v[66:67] op_sel_hi:[0,1]
	v_pk_mul_f32 v[6:7], v[2:3], v[68:69] op_sel_hi:[0,1]
	v_lshl_add_u64 v[10:11], v[8:9], 0, s[4:5]
	v_cvt_pk_bf16_f32 v4, v4, v5
	v_cvt_pk_bf16_f32 v5, v6, v7
	v_pk_mul_f32 v[6:7], v[2:3], v[70:71] op_sel_hi:[0,1]
	v_pk_mul_f32 v[12:13], v[2:3], v[72:73] op_sel_hi:[0,1]
	s_mov_b32 s4, 0x45856000
	v_cvt_pk_bf16_f32 v6, v6, v7
	v_cvt_pk_bf16_f32 v7, v12, v13
	v_add_co_u32_e32 v8, vcc, s4, v8
	v_permlane32_swap_b32_e32 v4, v6
	v_permlane32_swap_b32_e32 v5, v7
	v_addc_co_u32_e32 v9, vcc, 0, v9, vcc
	global_store_dwordx4 v[8:9], v[4:7], off offset:2048
	v_pk_mul_f32 v[8:9], v[2:3], v[80:81] op_sel_hi:[0,1]
	s_nop 0
	v_pk_mul_f32 v[4:5], v[2:3], v[74:75] op_sel_hi:[0,1]
	v_pk_mul_f32 v[6:7], v[2:3], v[76:77] op_sel_hi:[0,1]
	v_cvt_pk_bf16_f32 v4, v4, v5
	v_cvt_pk_bf16_f32 v5, v6, v7
	v_pk_mul_f32 v[6:7], v[2:3], v[78:79] op_sel_hi:[0,1]
	v_cvt_pk_bf16_f32 v6, v6, v7
	v_cvt_pk_bf16_f32 v7, v8, v9
	s_nop 0
	v_permlane32_swap_b32_e32 v4, v6
	v_permlane32_swap_b32_e32 v5, v7
	global_store_dwordx4 v[10:11], v[4:7], off offset:32
	v_pk_mul_f32 v[8:9], v[2:3], v[56:57] op_sel_hi:[0,1]
	s_nop 0
	v_pk_mul_f32 v[4:5], v[2:3], v[50:51] op_sel_hi:[0,1]
	v_pk_mul_f32 v[6:7], v[2:3], v[52:53] op_sel_hi:[0,1]
	v_cvt_pk_bf16_f32 v4, v4, v5
	v_cvt_pk_bf16_f32 v5, v6, v7
	v_pk_mul_f32 v[6:7], v[2:3], v[54:55] op_sel_hi:[0,1]
	v_cvt_pk_bf16_f32 v6, v6, v7
	v_cvt_pk_bf16_f32 v7, v8, v9
	s_nop 0
	v_permlane32_swap_b32_e32 v4, v6
	v_permlane32_swap_b32_e32 v5, v7
	global_store_dwordx4 v[10:11], v[4:7], off offset:64
	v_pk_mul_f32 v[8:9], v[2:3], v[64:65] op_sel_hi:[0,1]
	s_nop 0
	v_pk_mul_f32 v[4:5], v[2:3], v[58:59] op_sel_hi:[0,1]
	v_pk_mul_f32 v[6:7], v[2:3], v[60:61] op_sel_hi:[0,1]
	v_cvt_pk_bf16_f32 v4, v4, v5
	v_cvt_pk_bf16_f32 v5, v6, v7
	v_pk_mul_f32 v[6:7], v[2:3], v[62:63] op_sel_hi:[0,1]
	v_cvt_pk_bf16_f32 v6, v6, v7
	v_cvt_pk_bf16_f32 v7, v8, v9
	s_nop 0
	v_permlane32_swap_b32_e32 v4, v6
	v_permlane32_swap_b32_e32 v5, v7
	global_store_dwordx4 v[10:11], v[4:7], off offset:96
	v_pk_mul_f32 v[8:9], v[2:3], v[40:41] op_sel_hi:[0,1]
	s_nop 0
	v_pk_mul_f32 v[4:5], v[2:3], v[34:35] op_sel_hi:[0,1]
	v_pk_mul_f32 v[6:7], v[2:3], v[36:37] op_sel_hi:[0,1]
	v_cvt_pk_bf16_f32 v4, v4, v5
	v_cvt_pk_bf16_f32 v5, v6, v7
	v_pk_mul_f32 v[6:7], v[2:3], v[38:39] op_sel_hi:[0,1]
	v_cvt_pk_bf16_f32 v6, v6, v7
	v_cvt_pk_bf16_f32 v7, v8, v9
	s_nop 0
	v_permlane32_swap_b32_e32 v4, v6
	v_permlane32_swap_b32_e32 v5, v7
	global_store_dwordx4 v[10:11], v[4:7], off offset:128
	v_pk_mul_f32 v[8:9], v[2:3], v[48:49] op_sel_hi:[0,1]
	s_nop 0
	v_pk_mul_f32 v[4:5], v[2:3], v[42:43] op_sel_hi:[0,1]
	v_pk_mul_f32 v[6:7], v[2:3], v[44:45] op_sel_hi:[0,1]
	v_cvt_pk_bf16_f32 v4, v4, v5
	v_cvt_pk_bf16_f32 v5, v6, v7
	v_pk_mul_f32 v[6:7], v[2:3], v[46:47] op_sel_hi:[0,1]
	v_cvt_pk_bf16_f32 v6, v6, v7
	v_cvt_pk_bf16_f32 v7, v8, v9
	s_nop 0
	v_permlane32_swap_b32_e32 v4, v6
	v_permlane32_swap_b32_e32 v5, v7
	global_store_dwordx4 v[10:11], v[4:7], off offset:160
	v_pk_mul_f32 v[8:9], v[2:3], v[24:25] op_sel_hi:[0,1]
	s_nop 0
	v_pk_mul_f32 v[4:5], v[2:3], v[18:19] op_sel_hi:[0,1]
	v_pk_mul_f32 v[6:7], v[2:3], v[20:21] op_sel_hi:[0,1]
	v_cvt_pk_bf16_f32 v4, v4, v5
	v_cvt_pk_bf16_f32 v5, v6, v7
	v_pk_mul_f32 v[6:7], v[2:3], v[22:23] op_sel_hi:[0,1]
	v_cvt_pk_bf16_f32 v6, v6, v7
	v_cvt_pk_bf16_f32 v7, v8, v9
	s_nop 0
	v_permlane32_swap_b32_e32 v4, v6
	v_permlane32_swap_b32_e32 v5, v7
	global_store_dwordx4 v[10:11], v[4:7], off offset:192
	v_pk_mul_f32 v[8:9], v[2:3], v[32:33] op_sel_hi:[0,1]
	s_nop 0
	v_pk_mul_f32 v[4:5], v[2:3], v[26:27] op_sel_hi:[0,1]
	v_pk_mul_f32 v[6:7], v[2:3], v[28:29] op_sel_hi:[0,1]
	v_cvt_pk_bf16_f32 v4, v4, v5
	v_cvt_pk_bf16_f32 v5, v6, v7
	v_pk_mul_f32 v[6:7], v[2:3], v[30:31] op_sel_hi:[0,1]
	v_cvt_pk_bf16_f32 v6, v6, v7
	v_cvt_pk_bf16_f32 v7, v8, v9
	s_nop 0
	v_permlane32_swap_b32_e32 v4, v6
	v_permlane32_swap_b32_e32 v5, v7
	global_store_dwordx4 v[10:11], v[4:7], off offset:224

; DI unsigned char* kws() { return (unsigned char*)karg64<208>(); }
; DI void lru_fix_unit(const Ctx& c, int l, int chunk, int half) {
;     const int cg4 = c.tid & 127, tq = c.tid >> 7, ch = half * 512 + 4 * cg4; const bool smp = chunk >= 256; const int n = smp ? 0 : (chunk & 127);
;     f32x4 cr = {0.f, 0.f, 0.f, 0.f};
;     const f32x4* ag = (const f32x4*)((const float*)(kws() + WS_AGG) + ((size_t)(chunk - n) * 1024 + ch) * 2);
;     int i = 0;
;     for (; i + 8 <= n; i += 8) {
;         f32x4 a[8][2];
; #pragma unroll
;         for (int j = 0; j < 8; ++j) { a[j][0] = ag[(size_t)(i + j) * 512]; a[j][1] = ag[(size_t)(i + j) * 512 + 1]; }
; #pragma unroll
;         for (int j = 0; j < 8; ++j) { cr[0] = a[j][0][0] * cr[0] + a[j][0][1]; cr[1] = a[j][0][2] * cr[1] + a[j][0][3]; cr[2] = a[j][1][0] * cr[2] + a[j][1][1]; cr[3] = a[j][1][2] * cr[3] + a[j][1][3]; }
;     }
.LBB0_785:
	v_add_co_u32_e32 v4, vcc, 0xffff1ff0, v60
	s_mov_b32 s9, s12
	s_nop 0
	v_addc_co_u32_e32 v5, vcc, -1, v61, vcc
	global_load_dwordx4 v[20:23], v[4:5], off
	v_add_co_u32_e32 v4, vcc, 0xffff2000, v60
	s_movk_i32 s12, 0x8000
	s_nop 0
	v_addc_co_u32_e32 v5, vcc, -1, v61, vcc
	global_load_dwordx4 v[8:11], v[4:5], off
	v_add_co_u32_e32 v4, vcc, 0xffff3ff0, v60
	s_waitcnt vmcnt(0) lgkmcnt(0)
	v_mov_b32_e32 v66, v20
	v_addc_co_u32_e32 v5, vcc, -1, v61, vcc
	global_load_dwordx4 v[28:31], v[4:5], off
	v_add_co_u32_e32 v4, vcc, 0xffff4000, v60
	v_mov_b32_e32 v67, v22
	s_nop 0
	v_addc_co_u32_e32 v5, vcc, -1, v61, vcc
	global_load_dwordx4 v[12:15], v[4:5], off
	v_add_co_u32_e32 v4, vcc, 0xffff5ff0, v60
	v_mov_b32_e32 v22, v21
	s_nop 0
	v_addc_co_u32_e32 v5, vcc, -1, v61, vcc
	global_load_dwordx4 v[16:19], v[4:5], off
	v_add_co_u32_e32 v4, vcc, 0xffff6000, v60
	v_pk_fma_f32 v[20:21], v[70:71], v[66:67], v[22:23]
	s_nop 0
	v_addc_co_u32_e32 v5, vcc, -1, v61, vcc
	v_add_co_u32_e32 v24, vcc, 0xffff7ff0, v60
	global_load_dwordx4 v[4:7], v[4:5], off
	s_nop 0
	v_addc_co_u32_e32 v25, vcc, -1, v61, vcc
	v_add_co_u32_e32 v32, vcc, s12, v60
	s_movk_i32 s12, 0xe000
	s_nop 0
	v_addc_co_u32_e32 v33, vcc, -1, v61, vcc
	v_add_co_u32_e32 v36, vcc, 0xffff9ff0, v60
	global_load_dwordx4 v[32:35], v[32:33], off
	s_nop 0
	v_addc_co_u32_e32 v37, vcc, -1, v61, vcc
	global_load_dwordx4 v[44:47], v[36:37], off
	v_add_co_u32_e32 v36, vcc, 0xffffa000, v60
	global_load_dwordx4 v[24:27], v[24:25], off
	s_nop 0
	v_addc_co_u32_e32 v37, vcc, -1, v61, vcc
	v_add_co_u32_e32 v40, vcc, 0xffffbff0, v60
	global_load_dwordx4 v[36:39], v[36:37], off
	s_nop 0
	v_addc_co_u32_e32 v41, vcc, -1, v61, vcc
	global_load_dwordx4 v[48:51], v[40:41], off
	v_add_co_u32_e32 v40, vcc, 0xffffc000, v60
	s_waitcnt vmcnt(0) lgkmcnt(0)
	v_mov_b32_e32 v22, v28
	v_addc_co_u32_e32 v41, vcc, -1, v61, vcc
	v_add_co_u32_e32 v52, vcc, 0xffffdff0, v60
	global_load_dwordx4 v[40:43], v[40:41], off
	s_nop 0
	v_addc_co_u32_e32 v53, vcc, -1, v61, vcc
	v_add_co_u32_e32 v56, vcc, s12, v60
	global_load_dwordx4 v[52:55], v[52:53], off
	s_nop 0
	v_addc_co_u32_e32 v57, vcc, -1, v61, vcc
	v_add_co_u32_e32 v62, vcc, -16, v60
	global_load_dwordx4 v[56:59], v[56:57], off
	s_nop 0
	v_addc_co_u32_e32 v63, vcc, -1, v61, vcc
	global_load_dwordx4 v[62:65], v[62:63], off
	s_nop 0
	global_load_dwordx4 v[72:75], v[60:61], off
	v_mov_b32_e32 v23, v30
	v_mov_b32_e32 v30, v29
	v_mov_b32_e32 v28, v8
	v_mov_b32_e32 v29, v10
	v_mov_b32_e32 v10, v9
	v_pk_fma_f32 v[8:9], v[68:69], v[28:29], v[10:11]
	v_mov_b32_e32 v10, v12
	v_mov_b32_e32 v11, v14
	v_mov_b32_e32 v14, v13
	v_pk_fma_f32 v[20:21], v[20:21], v[22:23], v[30:31]
	v_mov_b32_e32 v22, v16
	v_mov_b32_e32 v23, v18
	v_pk_fma_f32 v[8:9], v[8:9], v[10:11], v[14:15]
	v_mov_b32_e32 v10, v4
	v_mov_b32_e32 v11, v6
	v_mov_b32_e32 v18, v17
	v_mov_b32_e32 v6, v5
	v_pk_fma_f32 v[12:13], v[20:21], v[22:23], v[18:19]
	v_mov_b32_e32 v14, v24
	v_mov_b32_e32 v15, v26
	v_mov_b32_e32 v26, v25
	v_pk_fma_f32 v[4:5], v[8:9], v[10:11], v[6:7]
	v_mov_b32_e32 v6, v32
	v_mov_b32_e32 v7, v34
	v_mov_b32_e32 v34, v33
	v_pk_fma_f32 v[12:13], v[12:13], v[14:15], v[26:27]
	v_mov_b32_e32 v14, v44
	v_mov_b32_e32 v15, v46
	v_mov_b32_e32 v46, v45
	v_pk_fma_f32 v[4:5], v[4:5], v[6:7], v[34:35]
	v_mov_b32_e32 v6, v36
	v_mov_b32_e32 v7, v38
	v_mov_b32_e32 v38, v37
	v_pk_fma_f32 v[12:13], v[12:13], v[14:15], v[46:47]
	v_mov_b32_e32 v14, v48
	v_mov_b32_e32 v15, v50
	v_mov_b32_e32 v50, v49
	v_pk_fma_f32 v[4:5], v[4:5], v[6:7], v[38:39]
	v_pk_fma_f32 v[12:13], v[12:13], v[14:15], v[50:51]
	s_add_i32 s12, s9, 8
	s_add_i32 s9, s9, 16
	v_lshl_add_u64 v[60:61], v[60:61], 0, s[90:91]
	s_cmp_gt_u32 s9, s8
	s_waitcnt vmcnt(0) lgkmcnt(0)
	v_mov_b32_e32 v6, v40
	v_mov_b32_e32 v7, v42
	v_mov_b32_e32 v42, v41
	v_pk_fma_f32 v[4:5], v[4:5], v[6:7], v[42:43]
	v_mov_b32_e32 v14, v52
	v_mov_b32_e32 v15, v54
	v_mov_b32_e32 v54, v53
	v_pk_fma_f32 v[12:13], v[12:13], v[14:15], v[54:55]
	v_mov_b32_e32 v6, v56
	v_mov_b32_e32 v7, v58
	v_mov_b32_e32 v58, v57
	v_mov_b32_e32 v14, v62
	v_mov_b32_e32 v15, v64
	v_mov_b32_e32 v64, v63
	v_pk_fma_f32 v[4:5], v[4:5], v[6:7], v[58:59]
	v_mov_b32_e32 v6, v72
	v_mov_b32_e32 v7, v74
	v_mov_b32_e32 v74, v73
	v_pk_fma_f32 v[70:71], v[12:13], v[14:15], v[64:65]
	v_pk_fma_f32 v[68:69], v[4:5], v[6:7], v[74:75]
	s_cbranch_scc0 .LBB0_785
	s_cmp_ge_u32 s12, s8
	s_cbranch_scc0 .LBB0_788
	s_branch .LBB0_790

; DI unsigned char* kws() { return (unsigned char*)karg64<208>(); }
; DI void lru_fix_unit(const Ctx& c, int l, int chunk, int half) {
;     ...
;     for (; i < n; ++i) { const f32x4 a0 = ag[(size_t)i * 512], a1 = ag[(size_t)i * 512 + 1]; cr[0] = a0[0] * cr[0] + a0[1]; cr[1] = a0[2] * cr[1] + a0[3]; cr[2] = a1[0] * cr[2] + a1[1]; cr[3] = a1[2] * cr[3] + a1[3]; }
;     const unsigned* hc = (const unsigned*)(kws() + WS_R1) + (size_t)(chunk * 64 + tq) * 1024 + ch;
;     const bf16_t* zg = (const bf16_t*)(kws() + WS_Z) + (size_t)(chunk * 64 + tq) * ZLD + C_AG + ch;
;     bf16_t* br = (bf16_t*)(kws() + WS_BR) + (size_t)(chunk * 64 + tq) * 3072 + ch;
;     u32x4 hv[16]; u32x2 gv[16];
; #pragma unroll
;     for (int k = 0; k < 16; ++k) { hv[k] = *(const u32x4*)(hc + (size_t)(4 * k) * 1024); gv[k] = *(const u32x2*)(zg + (size_t)(4 * k) * ZLD); }
.LBB0_789:
	v_add_co_u32_e32 v6, vcc, -16, v4
	s_add_i32 s12, s12, 1
	s_nop 0
	v_addc_co_u32_e32 v7, vcc, -1, v5, vcc
	global_load_dwordx4 v[6:9], v[6:7], off
	s_nop 0
	global_load_dwordx4 v[10:13], v[4:5], off
	v_lshl_add_u64 v[4:5], v[4:5], 0, s[92:93]
	s_cmp_lt_u32 s12, s8
	s_waitcnt vmcnt(0) lgkmcnt(0)
	v_mov_b32_e32 v14, v6
	v_mov_b32_e32 v15, v8
	v_mov_b32_e32 v8, v7
	v_mov_b32_e32 v6, v10
	v_mov_b32_e32 v7, v12
	v_mov_b32_e32 v12, v11
	v_pk_fma_f32 v[70:71], v[70:71], v[14:15], v[8:9]
	v_pk_fma_f32 v[68:69], v[68:69], v[6:7], v[12:13]
	s_cbranch_scc1 .LBB0_789
.LBB0_790:
	s_lshl_b32 s4, s10, 9
	v_lshl_add_u32 v4, s42, 6, v1
	s_and_b32 s4, s4, 0x200
	v_ashrrev_i32_e32 v5, 31, v4
	v_or_b32_e32 v10, s4, v106
	s_load_dwordx2 s[4:5], s[0:1], 0xd0
	s_waitcnt lgkmcnt(0)
	v_lshlrev_b64 v[6:7], 12, v[4:5]
	v_lshl_add_u64 v[6:7], s[4:5], 0, v[6:7]
	s_load_dwordx2 s[4:5], s[0:1], 0xd0
	s_waitcnt lgkmcnt(0)
	v_lshlrev_b32_e32 v72, 1, v10
	v_mov_b64_e32 v[8:9], s[4:5]
	v_mad_i64_i32 v[8:9], s[4:5], v4, s31, v[8:9]
	v_mov_b32_e32 v73, v3
	s_load_dwordx2 s[4:5], s[0:1], 0xd0
	s_waitcnt lgkmcnt(0)
	v_lshl_add_u64 v[74:75], v[8:9], 0, v[72:73]
	v_mov_b64_e32 v[8:9], s[4:5]
	s_movk_i32 s4, 0x1800
	v_lshlrev_b32_e32 v2, 2, v10
	v_mad_i64_i32 v[108:109], s[4:5], v4, s4, v[8:9]
	v_lshl_add_u64 v[6:7], v[6:7], 0, v[2:3]
	s_mov_b32 s4, 0x3c856000
	v_add_co_u32_e32 v4, vcc, s4, v6
	s_mov_b32 s4, 0x26456000
	s_nop 0
	v_addc_co_u32_e32 v5, vcc, 0, v7, vcc
	global_load_dwordx4 v[64:67], v[4:5], off
	v_add_co_u32_e32 v4, vcc, s4, v74
	s_mov_b32 s4, 0x3c85a000
	s_nop 0
	v_addc_co_u32_e32 v5, vcc, 0, v75, vcc
	global_load_dwordx2 v[104:105], v[4:5], off offset:2048
	v_add_co_u32_e32 v4, vcc, s4, v6
	s_mov_b32 s4, 0x26463000
	s_nop 0
	v_addc_co_u32_e32 v5, vcc, 0, v7, vcc
	global_load_dwordx4 v[60:63], v[4:5], off
	v_add_co_u32_e32 v4, vcc, s4, v74
	s_mov_b32 s4, 0x3c85e000
	s_nop 0
	v_addc_co_u32_e32 v5, vcc, 0, v75, vcc
	global_load_dwordx2 v[102:103], v[4:5], off offset:2048
	v_add_co_u32_e32 v4, vcc, s4, v6
	s_mov_b32 s4, 0x26470000
	s_nop 0
	v_addc_co_u32_e32 v5, vcc, 0, v7, vcc
	global_load_dwordx4 v[56:59], v[4:5], off
	v_add_co_u32_e32 v4, vcc, s4, v74
	s_mov_b32 s4, 0x3c862000
	s_nop 0
	v_addc_co_u32_e32 v5, vcc, 0, v75, vcc
	global_load_dwordx2 v[100:101], v[4:5], off offset:2048
	v_add_co_u32_e32 v4, vcc, s4, v6
	s_mov_b32 s4, 0x2647d000
	s_nop 0
	v_addc_co_u32_e32 v5, vcc, 0, v7, vcc
	global_load_dwordx4 v[52:55], v[4:5], off
	v_add_co_u32_e32 v4, vcc, s4, v74
	s_mov_b32 s4, 0x3c866000
	s_nop 0
	v_addc_co_u32_e32 v5, vcc, 0, v75, vcc
	global_load_dwordx2 v[98:99], v[4:5], off offset:2048
	v_add_co_u32_e32 v4, vcc, s4, v6
	s_mov_b32 s4, 0x2648a000
	s_nop 0
	v_addc_co_u32_e32 v5, vcc, 0, v7, vcc
	global_load_dwordx4 v[48:51], v[4:5], off
	v_add_co_u32_e32 v4, vcc, s4, v74
	s_mov_b32 s4, 0x3c86a000
	s_nop 0
	v_addc_co_u32_e32 v5, vcc, 0, v75, vcc
	global_load_dwordx2 v[96:97], v[4:5], off offset:2048
	v_add_co_u32_e32 v4, vcc, s4, v6
	s_mov_b32 s4, 0x26497000
	s_nop 0
	v_addc_co_u32_e32 v5, vcc, 0, v7, vcc
	global_load_dwordx4 v[44:47], v[4:5], off
	v_add_co_u32_e32 v4, vcc, s4, v74
	s_mov_b32 s4, 0x3c86e000
	s_nop 0
	v_addc_co_u32_e32 v5, vcc, 0, v75, vcc
	global_load_dwordx2 v[94:95], v[4:5], off offset:2048
	v_add_co_u32_e32 v4, vcc, s4, v6
	s_mov_b32 s4, 0x264a4000
	s_nop 0
	v_addc_co_u32_e32 v5, vcc, 0, v7, vcc
	global_load_dwordx4 v[40:43], v[4:5], off
	v_add_co_u32_e32 v4, vcc, s4, v74
	s_mov_b32 s4, 0x3c872000
	s_nop 0
	v_addc_co_u32_e32 v5, vcc, 0, v75, vcc
	global_load_dwordx2 v[92:93], v[4:5], off offset:2048
	v_add_co_u32_e32 v4, vcc, s4, v6
	s_mov_b32 s4, 0x264b1000
	s_nop 0
	v_addc_co_u32_e32 v5, vcc, 0, v7, vcc
	global_load_dwordx4 v[36:39], v[4:5], off
	v_add_co_u32_e32 v4, vcc, s4, v74
	s_mov_b32 s4, 0x3c876000
	s_nop 0
	v_addc_co_u32_e32 v5, vcc, 0, v75, vcc
	global_load_dwordx2 v[90:91], v[4:5], off offset:2048
	v_add_co_u32_e32 v4, vcc, s4, v6
	s_mov_b32 s4, 0x264be000
	s_nop 0
	v_addc_co_u32_e32 v5, vcc, 0, v7, vcc
	global_load_dwordx4 v[32:35], v[4:5], off
	v_add_co_u32_e32 v4, vcc, s4, v74
	s_mov_b32 s4, 0x3c87a000
	s_nop 0
	v_addc_co_u32_e32 v5, vcc, 0, v75, vcc
	global_load_dwordx2 v[88:89], v[4:5], off offset:2048
	v_add_co_u32_e32 v4, vcc, s4, v6
	s_mov_b32 s4, 0x264cb000
	s_nop 0
	v_addc_co_u32_e32 v5, vcc, 0, v7, vcc
	global_load_dwordx4 v[28:31], v[4:5], off
	v_add_co_u32_e32 v4, vcc, s4, v74
	s_mov_b32 s4, 0x3c87e000
	s_nop 0
	v_addc_co_u32_e32 v5, vcc, 0, v75, vcc
	global_load_dwordx2 v[86:87], v[4:5], off offset:2048
	v_add_co_u32_e32 v4, vcc, s4, v6
	s_mov_b32 s4, 0x264d8000
	s_nop 0
	v_addc_co_u32_e32 v5, vcc, 0, v7, vcc
	global_load_dwordx4 v[24:27], v[4:5], off
	v_add_co_u32_e32 v4, vcc, s4, v74
	s_mov_b32 s4, 0x3c882000
	s_nop 0
	v_addc_co_u32_e32 v5, vcc, 0, v75, vcc
	v_lshl_add_u64 v[72:73], v[108:109], 0, v[72:73]
	s_waitcnt vmcnt(0) lgkmcnt(0)
; DI float bflo(unsigned w) { return __uint_as_float(w << 16); }
; DI float bfhi(unsigned w) { return __uint_as_float(w & 0xffff0000u); }
; DI unsigned pk2(float a, float b) { f32x2 v = {a, b}; bf16v2 r = __builtin_convertvector(v, bf16v2); return __builtin_bit_cast(unsigned, r); }
; DI float gelu_tanh(float x) { const float u = 0.7978845608028654f * (x + 0.044715f * x * x * x); const float e = __expf(-2.0f * u); return x * (1.0f / (1.0f + e)); }
; DI void lru_fix_unit(const Ctx& c, int l, int chunk, int half) {
;     ...
;     for (int k = 0; k < 16; ++k) { hv[k] = *(const u32x4*)(hc + (size_t)(4 * k) * 1024); gv[k] = *(const u32x2*)(zg + (size_t)(4 * k) * ZLD); }
;     f32x4 h = {0.f, 0.f, 0.f, 0.f};
; #pragma unroll
;     for (int k = 0; k < 16; ++k) {
;         h[0] = bflo(hv[k].x) + bfhi(hv[k].x) * cr[0]; h[1] = bflo(hv[k].y) + bfhi(hv[k].y) * cr[1]; h[2] = bflo(hv[k].z) + bfhi(hv[k].z) * cr[2]; h[3] = bflo(hv[k].w) + bfhi(hv[k].w) * cr[3];
;         u32x2 w; w.x = pk2(h[0] * gelu_tanh(bflo(gv[k].x)), h[1] * gelu_tanh(bfhi(gv[k].x))); w.y = pk2(h[2] * gelu_tanh(bflo(gv[k].y)), h[3] * gelu_tanh(bfhi(gv[k].y)));
;         *(u32x2*)(br + (size_t)(4 * k) * 3072) = w;
	v_lshlrev_b32_e32 v109, 16, v65
	v_lshlrev_b32_e32 v108, 16, v64
	v_and_b32_e32 v65, 0xffff0000, v65
	v_and_b32_e32 v64, 0xffff0000, v64
	global_load_dwordx2 v[84:85], v[4:5], off offset:2048
	v_add_co_u32_e32 v4, vcc, s4, v6
	v_pk_fma_f32 v[64:65], v[70:71], v[64:65], v[108:109]
	v_lshlrev_b32_e32 v108, 16, v104
	v_addc_co_u32_e32 v5, vcc, 0, v7, vcc
	s_mov_b32 s4, 0x264e5000
	v_and_b32_e32 v109, 0xffff0000, v104
	v_mul_f32_e32 v104, 0x3d372713, v108
	global_load_dwordx4 v[20:23], v[4:5], off
	v_add_co_u32_e32 v4, vcc, s4, v74
	v_mul_f32_e32 v104, v104, v108
	v_mov_b32_e32 v107, v108
	v_addc_co_u32_e32 v5, vcc, 0, v75, vcc
	s_mov_b32 s4, 0x3c886000
	v_fmac_f32_e32 v107, v104, v107
	global_load_dwordx2 v[82:83], v[4:5], off offset:2048
	v_add_co_u32_e32 v4, vcc, s4, v6
	v_mul_f32_e32 v104, 0x3f4c422a, v107
	s_nop 0
	v_addc_co_u32_e32 v5, vcc, 0, v7, vcc
	s_mov_b32 s4, 0x264f2000
	v_mul_f32_e32 v104, -2.0, v104
	global_load_dwordx4 v[16:19], v[4:5], off
	v_add_co_u32_e32 v4, vcc, s4, v74
	v_mul_f32_e32 v104, 0x3fb8aa3b, v104
	s_nop 0
	v_addc_co_u32_e32 v5, vcc, 0, v75, vcc
	s_mov_b32 s4, 0x3c88a000
	v_exp_f32_e32 v110, v104
	v_mul_f32_e32 v104, 0x3d372713, v109
	global_load_dwordx2 v[80:81], v[4:5], off offset:2048
	v_add_co_u32_e32 v4, vcc, s4, v6
	v_mul_f32_e32 v104, v104, v109
	v_mov_b32_e32 v107, v109
	v_addc_co_u32_e32 v5, vcc, 0, v7, vcc
	s_mov_b32 s4, 0x264ff000
	v_fmac_f32_e32 v107, v104, v107
	global_load_dwordx4 v[12:15], v[4:5], off
	v_add_co_u32_e32 v4, vcc, s4, v74
	v_mul_f32_e32 v104, 0x3f4c422a, v107
	s_nop 0
	v_addc_co_u32_e32 v5, vcc, 0, v75, vcc
	s_mov_b32 s4, 0x3c88e000
	v_mul_f32_e32 v104, -2.0, v104
	global_load_dwordx2 v[78:79], v[4:5], off offset:2048
	v_add_co_u32_e32 v4, vcc, s4, v6
	v_mul_f32_e32 v104, 0x3fb8aa3b, v104
	s_nop 0
	v_addc_co_u32_e32 v5, vcc, 0, v7, vcc
	s_mov_b32 s4, 0x2650c000
	v_exp_f32_e32 v111, v104
	global_load_dwordx4 v[8:11], v[4:5], off
	v_add_co_u32_e32 v4, vcc, s4, v74
	s_mov_b32 s4, 0x3c892000
	s_nop 0
	v_addc_co_u32_e32 v5, vcc, 0, v75, vcc
	global_load_dwordx2 v[76:77], v[4:5], off offset:2048
	v_add_co_u32_e32 v4, vcc, s4, v6
	s_mov_b32 s4, 0x26519000
	s_nop 0
	v_addc_co_u32_e32 v5, vcc, 0, v7, vcc
	v_pk_add_f32 v[110:111], v[110:111], 1.0 op_sel_hi:[1,0]
	v_add_co_u32_e32 v74, vcc, s4, v74
	v_div_scale_f32 v104, s[4:5], v111, v111, 1.0
	v_rcp_f32_e32 v107, v104
	v_addc_co_u32_e32 v75, vcc, 0, v75, vcc
	global_load_dwordx4 v[4:7], v[4:5], off
	v_fma_f32 v112, -v104, v107, 1.0
	v_fmac_f32_e32 v107, v112, v107
	v_div_scale_f32 v112, vcc, 1.0, v111, 1.0
	v_mul_f32_e32 v113, v112, v107
	v_fma_f32 v114, -v104, v113, v112
	v_fmac_f32_e32 v113, v114, v107
	v_fma_f32 v104, -v104, v113, v112
	v_div_fmas_f32 v104, v104, v107, v113
	v_div_fixup_f32 v111, v104, v111, 1.0
	v_div_scale_f32 v104, s[4:5], v110, v110, 1.0
	v_rcp_f32_e32 v107, v104
	global_load_dwordx2 v[74:75], v[74:75], off offset:2048
	v_fma_f32 v112, -v104, v107, 1.0
	v_fmac_f32_e32 v107, v112, v107
	v_div_scale_f32 v112, vcc, 1.0, v110, 1.0
	v_mul_f32_e32 v113, v112, v107
	v_fma_f32 v114, -v104, v113, v112
	v_fmac_f32_e32 v113, v114, v107
	v_fma_f32 v104, -v104, v113, v112
	v_div_fmas_f32 v104, v104, v107, v113
	v_div_fixup_f32 v110, v104, v110, 1.0
	v_pk_mul_f32 v[108:109], v[110:111], v[108:109]
	v_lshlrev_b32_e32 v104, 16, v105
	v_pk_mul_f32 v[64:65], v[64:65], v[108:109]
	v_mov_b32_e32 v107, v104
	v_cvt_pk_bf16_f32 v64, v64, v65
	v_mul_f32_e32 v65, 0x3d372713, v104
	v_mul_f32_e32 v65, v65, v104
	v_fmac_f32_e32 v107, v65, v107
	v_mul_f32_e32 v65, 0x3f4c422a, v107
	v_mul_f32_e32 v65, -2.0, v65
	v_lshlrev_b32_e32 v109, 16, v67
	v_lshlrev_b32_e32 v108, 16, v66
	v_and_b32_e32 v67, 0xffff0000, v67
	v_and_b32_e32 v66, 0xffff0000, v66
	v_and_b32_e32 v105, 0xffff0000, v105
	v_mul_f32_e32 v65, 0x3fb8aa3b, v65
	v_pk_fma_f32 v[66:67], v[68:69], v[66:67], v[108:109]
	v_exp_f32_e32 v108, v65
	v_mul_f32_e32 v65, 0x3d372713, v105
	v_mul_f32_e32 v65, v65, v105
	v_mov_b32_e32 v107, v105
	v_fmac_f32_e32 v107, v65, v107
	v_mul_f32_e32 v65, 0x3f4c422a, v107
	v_mul_f32_e32 v65, -2.0, v65
	v_mul_f32_e32 v65, 0x3fb8aa3b, v65
	v_exp_f32_e32 v109, v65
	s_nop 0
	v_pk_add_f32 v[108:109], v[108:109], 1.0 op_sel_hi:[1,0]
	s_nop 0
	v_div_scale_f32 v65, s[4:5], v109, v109, 1.0
	v_rcp_f32_e32 v107, v65
	s_nop 0
	v_fma_f32 v110, -v65, v107, 1.0
	v_fmac_f32_e32 v107, v110, v107
	v_div_scale_f32 v110, vcc, 1.0, v109, 1.0
	v_mul_f32_e32 v111, v110, v107
	v_fma_f32 v112, -v65, v111, v110
	v_fmac_f32_e32 v111, v112, v107
	v_fma_f32 v65, -v65, v111, v110
	v_div_fmas_f32 v65, v65, v107, v111
	v_div_fixup_f32 v109, v65, v109, 1.0
	v_div_scale_f32 v65, s[4:5], v108, v108, 1.0
	v_rcp_f32_e32 v107, v65
	s_mov_b32 s4, 0x45856000
	v_fma_f32 v110, -v65, v107, 1.0
	v_fmac_f32_e32 v107, v110, v107
	v_div_scale_f32 v110, vcc, 1.0, v108, 1.0
	v_mul_f32_e32 v111, v110, v107
	v_fma_f32 v112, -v65, v111, v110
	v_fmac_f32_e32 v111, v112, v107
	v_fma_f32 v65, -v65, v111, v110
	v_div_fmas_f32 v65, v65, v107, v111
	v_div_fixup_f32 v108, v65, v108, 1.0
	v_pk_mul_f32 v[104:105], v[108:109], v[104:105]
	s_nop 0
	v_pk_mul_f32 v[66:67], v[66:67], v[104:105]
	s_nop 0
	v_cvt_pk_bf16_f32 v65, v66, v67
	v_add_co_u32_e32 v66, vcc, s4, v72
	s_nop 1
	v_addc_co_u32_e32 v67, vcc, 0, v73, vcc
	global_store_dwordx2 v[66:67], v[64:65], off
	v_lshlrev_b32_e32 v65, 16, v61
	v_lshlrev_b32_e32 v64, 16, v60
	v_and_b32_e32 v61, 0xffff0000, v61
	v_and_b32_e32 v60, 0xffff0000, v60
	v_pk_fma_f32 v[60:61], v[70:71], v[60:61], v[64:65]
	v_lshlrev_b32_e32 v64, 16, v102
	v_mul_f32_e32 v66, 0x3d372713, v64
	v_mul_f32_e32 v66, v66, v64
	v_mov_b32_e32 v67, v64
	v_and_b32_e32 v65, 0xffff0000, v102
	v_fmac_f32_e32 v67, v66, v67
; DI float bflo(unsigned w) { return __uint_as_float(w << 16); }
; DI float bfhi(unsigned w) { return __uint_as_float(w & 0xffff0000u); }
; DI unsigned pk2(float a, float b) { f32x2 v = {a, b}; bf16v2 r = __builtin_convertvector(v, bf16v2); return __builtin_bit_cast(unsigned, r); }
; DI float gelu_tanh(float x) { const float u = 0.7978845608028654f * (x + 0.044715f * x * x * x); const float e = __expf(-2.0f * u); return x * (1.0f / (1.0f + e)); }
; DI void lru_fix_unit(const Ctx& c, int l, int chunk, int half) {
;     ...
;     for (int k = 0; k < 16; ++k) {
;         h[0] = bflo(hv[k].x) + bfhi(hv[k].x) * cr[0]; h[1] = bflo(hv[k].y) + bfhi(hv[k].y) * cr[1]; h[2] = bflo(hv[k].z) + bfhi(hv[k].z) * cr[2]; h[3] = bflo(hv[k].w) + bfhi(hv[k].w) * cr[3];
;         u32x2 w; w.x = pk2(h[0] * gelu_tanh(bflo(gv[k].x)), h[1] * gelu_tanh(bfhi(gv[k].x))); w.y = pk2(h[2] * gelu_tanh(bflo(gv[k].y)), h[3] * gelu_tanh(bfhi(gv[k].y)));
;         *(u32x2*)(br + (size_t)(4 * k) * 3072) = w;
;     }
	v_mul_f32_e32 v66, 0x3f4c422a, v67
	v_mul_f32_e32 v67, 0x3d372713, v65
	v_mul_f32_e32 v67, v67, v65
	v_mov_b32_e32 v102, v65
	v_fmac_f32_e32 v102, v67, v102
	v_mul_f32_e32 v67, 0x3f4c422a, v102
	v_mul_f32_e32 v66, -2.0, v66
	v_mul_f32_e32 v67, -2.0, v67
	v_mul_f32_e32 v66, 0x3fb8aa3b, v66
	v_mul_f32_e32 v67, 0x3fb8aa3b, v67
	v_exp_f32_e32 v66, v66
	v_exp_f32_e32 v67, v67
	s_nop 0
	v_pk_add_f32 v[66:67], v[66:67], 1.0 op_sel_hi:[1,0]
	s_nop 0
	v_div_scale_f32 v102, s[4:5], v67, v67, 1.0
	v_rcp_f32_e32 v104, v102
	s_nop 0
	v_fma_f32 v105, -v102, v104, 1.0
	v_fmac_f32_e32 v104, v105, v104
	v_div_scale_f32 v105, vcc, 1.0, v67, 1.0
	v_mul_f32_e32 v107, v105, v104
	v_fma_f32 v108, -v102, v107, v105
	v_fmac_f32_e32 v107, v108, v104
	v_fma_f32 v102, -v102, v107, v105
	v_div_fmas_f32 v102, v102, v104, v107
	v_div_fixup_f32 v67, v102, v67, 1.0
	v_div_scale_f32 v102, s[4:5], v66, v66, 1.0
	v_rcp_f32_e32 v104, v102
	s_nop 0
	v_fma_f32 v105, -v102, v104, 1.0
	v_fmac_f32_e32 v104, v105, v104
	v_div_scale_f32 v105, vcc, 1.0, v66, 1.0
	v_mul_f32_e32 v107, v105, v104
	v_fma_f32 v108, -v102, v107, v105
	v_fmac_f32_e32 v107, v108, v104
	v_fma_f32 v102, -v102, v107, v105
	v_div_fmas_f32 v102, v102, v104, v107
	v_div_fixup_f32 v66, v102, v66, 1.0
	v_pk_mul_f32 v[64:65], v[66:67], v[64:65]
	s_nop 0
	v_pk_mul_f32 v[60:61], v[60:61], v[64:65]
	v_lshlrev_b32_e32 v65, 16, v63
	v_lshlrev_b32_e32 v64, 16, v62
	v_and_b32_e32 v63, 0xffff0000, v63
	v_and_b32_e32 v62, 0xffff0000, v62
	v_pk_fma_f32 v[62:63], v[68:69], v[62:63], v[64:65]
	v_lshlrev_b32_e32 v64, 16, v103
	v_cvt_pk_bf16_f32 v60, v60, v61
	v_mul_f32_e32 v61, 0x3d372713, v64
	v_mul_f32_e32 v61, v61, v64
	v_mov_b32_e32 v66, v64
	v_fmac_f32_e32 v66, v61, v66
	v_mul_f32_e32 v61, 0x3f4c422a, v66
	v_mul_f32_e32 v61, -2.0, v61
	v_and_b32_e32 v65, 0xffff0000, v103
	v_mul_f32_e32 v61, 0x3fb8aa3b, v61
	v_exp_f32_e32 v66, v61
	v_mul_f32_e32 v61, 0x3d372713, v65
	v_mul_f32_e32 v61, v61, v65
	v_mov_b32_e32 v67, v65
	v_fmac_f32_e32 v67, v61, v67
	v_mul_f32_e32 v61, 0x3f4c422a, v67
	v_mul_f32_e32 v61, -2.0, v61
	v_mul_f32_e32 v61, 0x3fb8aa3b, v61
	v_exp_f32_e32 v67, v61
	s_nop 0
	v_pk_add_f32 v[66:67], v[66:67], 1.0 op_sel_hi:[1,0]
	s_nop 0
	v_div_scale_f32 v61, s[4:5], v67, v67, 1.0
	v_rcp_f32_e32 v102, v61
	s_nop 0
	v_fma_f32 v103, -v61, v102, 1.0
	v_fmac_f32_e32 v102, v103, v102
	v_div_scale_f32 v103, vcc, 1.0, v67, 1.0
	v_mul_f32_e32 v104, v103, v102
	v_fma_f32 v105, -v61, v104, v103
	v_fmac_f32_e32 v104, v105, v102
	v_fma_f32 v61, -v61, v104, v103
	v_div_fmas_f32 v61, v61, v102, v104
	v_div_fixup_f32 v67, v61, v67, 1.0
	v_div_scale_f32 v61, s[4:5], v66, v66, 1.0
	v_rcp_f32_e32 v102, v61
	s_mov_b32 s4, 0x4585c000
	v_fma_f32 v103, -v61, v102, 1.0
	v_fmac_f32_e32 v102, v103, v102
	v_div_scale_f32 v103, vcc, 1.0, v66, 1.0
	v_mul_f32_e32 v104, v103, v102
	v_fma_f32 v105, -v61, v104, v103
	v_fmac_f32_e32 v104, v105, v102
	v_fma_f32 v61, -v61, v104, v103
	v_div_fmas_f32 v61, v61, v102, v104
	v_div_fixup_f32 v66, v61, v66, 1.0
	v_pk_mul_f32 v[64:65], v[66:67], v[64:65]
	s_nop 0
	v_pk_mul_f32 v[62:63], v[62:63], v[64:65]
	s_nop 0
	v_cvt_pk_bf16_f32 v61, v62, v63
	v_add_co_u32_e32 v62, vcc, s4, v72
	s_nop 1
	v_addc_co_u32_e32 v63, vcc, 0, v73, vcc
	global_store_dwordx2 v[62:63], v[60:61], off
	v_lshlrev_b32_e32 v61, 16, v57
	v_lshlrev_b32_e32 v60, 16, v56
	v_and_b32_e32 v57, 0xffff0000, v57
	v_and_b32_e32 v56, 0xffff0000, v56
	v_pk_fma_f32 v[56:57], v[70:71], v[56:57], v[60:61]
	v_lshlrev_b32_e32 v60, 16, v100
	v_mul_f32_e32 v62, 0x3d372713, v60
	v_mul_f32_e32 v62, v62, v60
	v_mov_b32_e32 v63, v60
	v_and_b32_e32 v61, 0xffff0000, v100
	v_fmac_f32_e32 v63, v62, v63
	v_mul_f32_e32 v62, 0x3f4c422a, v63
	v_mul_f32_e32 v63, 0x3d372713, v61
	v_mul_f32_e32 v63, v63, v61
	v_mov_b32_e32 v64, v61
	v_fmac_f32_e32 v64, v63, v64
	v_mul_f32_e32 v63, 0x3f4c422a, v64
	v_mul_f32_e32 v62, -2.0, v62
	v_mul_f32_e32 v63, -2.0, v63
	v_mul_f32_e32 v62, 0x3fb8aa3b, v62
	v_mul_f32_e32 v63, 0x3fb8aa3b, v63
	v_exp_f32_e32 v62, v62
	v_exp_f32_e32 v63, v63
	s_nop 0
	v_pk_add_f32 v[62:63], v[62:63], 1.0 op_sel_hi:[1,0]
	s_nop 0
	v_div_scale_f32 v64, s[4:5], v63, v63, 1.0
	v_rcp_f32_e32 v65, v64
	s_nop 0
	v_fma_f32 v66, -v64, v65, 1.0
	v_fmac_f32_e32 v65, v66, v65
	v_div_scale_f32 v66, vcc, 1.0, v63, 1.0
	v_mul_f32_e32 v67, v66, v65
	v_fma_f32 v100, -v64, v67, v66
	v_fmac_f32_e32 v67, v100, v65
	v_fma_f32 v64, -v64, v67, v66
	v_div_fmas_f32 v64, v64, v65, v67
	v_div_fixup_f32 v63, v64, v63, 1.0
	v_div_scale_f32 v64, s[4:5], v62, v62, 1.0
	v_rcp_f32_e32 v65, v64
	s_nop 0
	v_fma_f32 v66, -v64, v65, 1.0
	v_fmac_f32_e32 v65, v66, v65
	v_div_scale_f32 v66, vcc, 1.0, v62, 1.0
	v_mul_f32_e32 v67, v66, v65
	v_fma_f32 v100, -v64, v67, v66
	v_fmac_f32_e32 v67, v100, v65
	v_fma_f32 v64, -v64, v67, v66
	v_div_fmas_f32 v64, v64, v65, v67
	v_div_fixup_f32 v62, v64, v62, 1.0
	v_pk_mul_f32 v[60:61], v[62:63], v[60:61]
	s_nop 0
	v_pk_mul_f32 v[56:57], v[56:57], v[60:61]
	v_lshlrev_b32_e32 v61, 16, v59
	v_lshlrev_b32_e32 v60, 16, v58
	v_and_b32_e32 v59, 0xffff0000, v59
	v_and_b32_e32 v58, 0xffff0000, v58
	v_pk_fma_f32 v[58:59], v[68:69], v[58:59], v[60:61]
	v_lshlrev_b32_e32 v60, 16, v101
	v_cvt_pk_bf16_f32 v56, v56, v57
	v_mul_f32_e32 v57, 0x3d372713, v60
	v_mul_f32_e32 v57, v57, v60
	v_mov_b32_e32 v62, v60
	v_fmac_f32_e32 v62, v57, v62
	v_mul_f32_e32 v57, 0x3f4c422a, v62
	v_mul_f32_e32 v57, -2.0, v57
	v_and_b32_e32 v61, 0xffff0000, v101
	v_mul_f32_e32 v57, 0x3fb8aa3b, v57
	v_exp_f32_e32 v62, v57
	v_mul_f32_e32 v57, 0x3d372713, v61
	v_mul_f32_e32 v57, v57, v61
	v_mov_b32_e32 v63, v61
	v_fmac_f32_e32 v63, v57, v63
	v_mul_f32_e32 v57, 0x3f4c422a, v63
	v_mul_f32_e32 v57, -2.0, v57
; DI float bflo(unsigned w) { return __uint_as_float(w << 16); }
; DI float bfhi(unsigned w) { return __uint_as_float(w & 0xffff0000u); }
; DI unsigned pk2(float a, float b) { f32x2 v = {a, b}; bf16v2 r = __builtin_convertvector(v, bf16v2); return __builtin_bit_cast(unsigned, r); }
; DI float gelu_tanh(float x) { const float u = 0.7978845608028654f * (x + 0.044715f * x * x * x); const float e = __expf(-2.0f * u); return x * (1.0f / (1.0f + e)); }
; DI void lru_fix_unit(const Ctx& c, int l, int chunk, int half) {
;     ...
;     for (int k = 0; k < 16; ++k) {
;         h[0] = bflo(hv[k].x) + bfhi(hv[k].x) * cr[0]; h[1] = bflo(hv[k].y) + bfhi(hv[k].y) * cr[1]; h[2] = bflo(hv[k].z) + bfhi(hv[k].z) * cr[2]; h[3] = bflo(hv[k].w) + bfhi(hv[k].w) * cr[3];
;         u32x2 w; w.x = pk2(h[0] * gelu_tanh(bflo(gv[k].x)), h[1] * gelu_tanh(bfhi(gv[k].x))); w.y = pk2(h[2] * gelu_tanh(bflo(gv[k].y)), h[3] * gelu_tanh(bfhi(gv[k].y)));
;         *(u32x2*)(br + (size_t)(4 * k) * 3072) = w;
;     }
	v_mul_f32_e32 v57, 0x3fb8aa3b, v57
	v_exp_f32_e32 v63, v57
	s_nop 0
	v_pk_add_f32 v[62:63], v[62:63], 1.0 op_sel_hi:[1,0]
	s_nop 0
	v_div_scale_f32 v57, s[4:5], v63, v63, 1.0
	v_rcp_f32_e32 v64, v57
	s_nop 0
	v_fma_f32 v65, -v57, v64, 1.0
	v_fmac_f32_e32 v64, v65, v64
	v_div_scale_f32 v65, vcc, 1.0, v63, 1.0
	v_mul_f32_e32 v66, v65, v64
	v_fma_f32 v67, -v57, v66, v65
	v_fmac_f32_e32 v66, v67, v64
	v_fma_f32 v57, -v57, v66, v65
	v_div_fmas_f32 v57, v57, v64, v66
	v_div_fixup_f32 v63, v57, v63, 1.0
	v_div_scale_f32 v57, s[4:5], v62, v62, 1.0
	v_rcp_f32_e32 v64, v57
	s_mov_b32 s4, 0x45862000
	v_fma_f32 v65, -v57, v64, 1.0
	v_fmac_f32_e32 v64, v65, v64
	v_div_scale_f32 v65, vcc, 1.0, v62, 1.0
	v_mul_f32_e32 v66, v65, v64
	v_fma_f32 v67, -v57, v66, v65
	v_fmac_f32_e32 v66, v67, v64
	v_fma_f32 v57, -v57, v66, v65
	v_div_fmas_f32 v57, v57, v64, v66
	v_div_fixup_f32 v62, v57, v62, 1.0
	v_pk_mul_f32 v[60:61], v[62:63], v[60:61]
	s_nop 0
	v_pk_mul_f32 v[58:59], v[58:59], v[60:61]
	s_nop 0
	v_cvt_pk_bf16_f32 v57, v58, v59
	v_add_co_u32_e32 v58, vcc, s4, v72
	s_nop 1
	v_addc_co_u32_e32 v59, vcc, 0, v73, vcc
	global_store_dwordx2 v[58:59], v[56:57], off
	v_lshlrev_b32_e32 v57, 16, v53
	v_lshlrev_b32_e32 v56, 16, v52
	v_and_b32_e32 v53, 0xffff0000, v53
	v_and_b32_e32 v52, 0xffff0000, v52
	v_pk_fma_f32 v[52:53], v[70:71], v[52:53], v[56:57]
	v_lshlrev_b32_e32 v56, 16, v98
	v_mul_f32_e32 v58, 0x3d372713, v56
	v_mul_f32_e32 v58, v58, v56
	v_mov_b32_e32 v59, v56
	v_and_b32_e32 v57, 0xffff0000, v98
	v_fmac_f32_e32 v59, v58, v59
	v_mul_f32_e32 v58, 0x3f4c422a, v59
	v_mul_f32_e32 v59, 0x3d372713, v57
	v_mul_f32_e32 v59, v59, v57
	v_mov_b32_e32 v60, v57
	v_fmac_f32_e32 v60, v59, v60
	v_mul_f32_e32 v59, 0x3f4c422a, v60
	v_mul_f32_e32 v58, -2.0, v58
	v_mul_f32_e32 v59, -2.0, v59
	v_mul_f32_e32 v58, 0x3fb8aa3b, v58
	v_mul_f32_e32 v59, 0x3fb8aa3b, v59
	v_exp_f32_e32 v58, v58
	v_exp_f32_e32 v59, v59
	s_nop 0
	v_pk_add_f32 v[58:59], v[58:59], 1.0 op_sel_hi:[1,0]
	s_nop 0
	v_div_scale_f32 v60, s[4:5], v59, v59, 1.0
	v_rcp_f32_e32 v61, v60
	s_nop 0
	v_fma_f32 v62, -v60, v61, 1.0
	v_fmac_f32_e32 v61, v62, v61
	v_div_scale_f32 v62, vcc, 1.0, v59, 1.0
	v_mul_f32_e32 v63, v62, v61
	v_fma_f32 v64, -v60, v63, v62
	v_fmac_f32_e32 v63, v64, v61
	v_fma_f32 v60, -v60, v63, v62
	v_div_fmas_f32 v60, v60, v61, v63
	v_div_fixup_f32 v59, v60, v59, 1.0
	v_div_scale_f32 v60, s[4:5], v58, v58, 1.0
	v_rcp_f32_e32 v61, v60
	s_nop 0
	v_fma_f32 v62, -v60, v61, 1.0
	v_fmac_f32_e32 v61, v62, v61
	v_div_scale_f32 v62, vcc, 1.0, v58, 1.0
	v_mul_f32_e32 v63, v62, v61
	v_fma_f32 v64, -v60, v63, v62
	v_fmac_f32_e32 v63, v64, v61
	v_fma_f32 v60, -v60, v63, v62
	v_div_fmas_f32 v60, v60, v61, v63
	v_div_fixup_f32 v58, v60, v58, 1.0
	v_pk_mul_f32 v[56:57], v[58:59], v[56:57]
	s_nop 0
	v_pk_mul_f32 v[52:53], v[52:53], v[56:57]
	v_lshlrev_b32_e32 v57, 16, v55
	v_lshlrev_b32_e32 v56, 16, v54
	v_and_b32_e32 v55, 0xffff0000, v55
	v_and_b32_e32 v54, 0xffff0000, v54
	v_pk_fma_f32 v[54:55], v[68:69], v[54:55], v[56:57]
	v_lshlrev_b32_e32 v56, 16, v99
	v_cvt_pk_bf16_f32 v52, v52, v53
	v_mul_f32_e32 v53, 0x3d372713, v56
	v_mul_f32_e32 v53, v53, v56
	v_mov_b32_e32 v58, v56
	v_fmac_f32_e32 v58, v53, v58
	v_mul_f32_e32 v53, 0x3f4c422a, v58
	v_mul_f32_e32 v53, -2.0, v53
	v_and_b32_e32 v57, 0xffff0000, v99
	v_mul_f32_e32 v53, 0x3fb8aa3b, v53
	v_exp_f32_e32 v58, v53
	v_mul_f32_e32 v53, 0x3d372713, v57
	v_mul_f32_e32 v53, v53, v57
	v_mov_b32_e32 v59, v57
	v_fmac_f32_e32 v59, v53, v59
	v_mul_f32_e32 v53, 0x3f4c422a, v59
	v_mul_f32_e32 v53, -2.0, v53
	v_mul_f32_e32 v53, 0x3fb8aa3b, v53
	v_exp_f32_e32 v59, v53
	s_nop 0
	v_pk_add_f32 v[58:59], v[58:59], 1.0 op_sel_hi:[1,0]
	s_nop 0
	v_div_scale_f32 v53, s[4:5], v59, v59, 1.0
	v_rcp_f32_e32 v60, v53
	s_nop 0
	v_fma_f32 v61, -v53, v60, 1.0
	v_fmac_f32_e32 v60, v61, v60
	v_div_scale_f32 v61, vcc, 1.0, v59, 1.0
	v_mul_f32_e32 v62, v61, v60
	v_fma_f32 v63, -v53, v62, v61
	v_fmac_f32_e32 v62, v63, v60
	v_fma_f32 v53, -v53, v62, v61
	v_div_fmas_f32 v53, v53, v60, v62
	v_div_fixup_f32 v59, v53, v59, 1.0
	v_div_scale_f32 v53, s[4:5], v58, v58, 1.0
	v_rcp_f32_e32 v60, v53
	s_mov_b32 s4, 0x45868000
	v_fma_f32 v61, -v53, v60, 1.0
	v_fmac_f32_e32 v60, v61, v60
	v_div_scale_f32 v61, vcc, 1.0, v58, 1.0
	v_mul_f32_e32 v62, v61, v60
	v_fma_f32 v63, -v53, v62, v61
	v_fmac_f32_e32 v62, v63, v60
	v_fma_f32 v53, -v53, v62, v61
	v_div_fmas_f32 v53, v53, v60, v62
	v_div_fixup_f32 v58, v53, v58, 1.0
	v_pk_mul_f32 v[56:57], v[58:59], v[56:57]
	s_nop 0
	v_pk_mul_f32 v[54:55], v[54:55], v[56:57]
	s_nop 0
	v_cvt_pk_bf16_f32 v53, v54, v55
	v_add_co_u32_e32 v54, vcc, s4, v72
	s_nop 1
	v_addc_co_u32_e32 v55, vcc, 0, v73, vcc
	global_store_dwordx2 v[54:55], v[52:53], off
	v_lshlrev_b32_e32 v53, 16, v49
	v_lshlrev_b32_e32 v52, 16, v48
	v_and_b32_e32 v49, 0xffff0000, v49
	v_and_b32_e32 v48, 0xffff0000, v48
	v_pk_fma_f32 v[48:49], v[70:71], v[48:49], v[52:53]
	v_lshlrev_b32_e32 v52, 16, v96
	v_mul_f32_e32 v54, 0x3d372713, v52
	v_mul_f32_e32 v54, v54, v52
	v_mov_b32_e32 v55, v52
	v_and_b32_e32 v53, 0xffff0000, v96
	v_fmac_f32_e32 v55, v54, v55
	v_mul_f32_e32 v54, 0x3f4c422a, v55
	v_mul_f32_e32 v55, 0x3d372713, v53
	v_mul_f32_e32 v55, v55, v53
	v_mov_b32_e32 v56, v53
	v_fmac_f32_e32 v56, v55, v56
	v_mul_f32_e32 v55, 0x3f4c422a, v56
	v_mul_f32_e32 v54, -2.0, v54
	v_mul_f32_e32 v55, -2.0, v55
	v_mul_f32_e32 v54, 0x3fb8aa3b, v54
	v_mul_f32_e32 v55, 0x3fb8aa3b, v55
	v_exp_f32_e32 v54, v54
	v_exp_f32_e32 v55, v55
	s_nop 0
	v_pk_add_f32 v[54:55], v[54:55], 1.0 op_sel_hi:[1,0]
	s_nop 0
	v_div_scale_f32 v56, s[4:5], v55, v55, 1.0
	v_rcp_f32_e32 v57, v56
	s_nop 0
	v_fma_f32 v58, -v56, v57, 1.0
	v_fmac_f32_e32 v57, v58, v57
; DI float bflo(unsigned w) { return __uint_as_float(w << 16); }
; DI float bfhi(unsigned w) { return __uint_as_float(w & 0xffff0000u); }
; DI unsigned pk2(float a, float b) { f32x2 v = {a, b}; bf16v2 r = __builtin_convertvector(v, bf16v2); return __builtin_bit_cast(unsigned, r); }
; DI float gelu_tanh(float x) { const float u = 0.7978845608028654f * (x + 0.044715f * x * x * x); const float e = __expf(-2.0f * u); return x * (1.0f / (1.0f + e)); }
; DI void lru_fix_unit(const Ctx& c, int l, int chunk, int half) {
;     ...
;     for (int k = 0; k < 16; ++k) {
;         h[0] = bflo(hv[k].x) + bfhi(hv[k].x) * cr[0]; h[1] = bflo(hv[k].y) + bfhi(hv[k].y) * cr[1]; h[2] = bflo(hv[k].z) + bfhi(hv[k].z) * cr[2]; h[3] = bflo(hv[k].w) + bfhi(hv[k].w) * cr[3];
;         u32x2 w; w.x = pk2(h[0] * gelu_tanh(bflo(gv[k].x)), h[1] * gelu_tanh(bfhi(gv[k].x))); w.y = pk2(h[2] * gelu_tanh(bflo(gv[k].y)), h[3] * gelu_tanh(bfhi(gv[k].y)));
;         *(u32x2*)(br + (size_t)(4 * k) * 3072) = w;
;     }
	v_div_scale_f32 v58, vcc, 1.0, v55, 1.0
	v_mul_f32_e32 v59, v58, v57
	v_fma_f32 v60, -v56, v59, v58
	v_fmac_f32_e32 v59, v60, v57
	v_fma_f32 v56, -v56, v59, v58
	v_div_fmas_f32 v56, v56, v57, v59
	v_div_fixup_f32 v55, v56, v55, 1.0
	v_div_scale_f32 v56, s[4:5], v54, v54, 1.0
	v_rcp_f32_e32 v57, v56
	s_nop 0
	v_fma_f32 v58, -v56, v57, 1.0
	v_fmac_f32_e32 v57, v58, v57
	v_div_scale_f32 v58, vcc, 1.0, v54, 1.0
	v_mul_f32_e32 v59, v58, v57
	v_fma_f32 v60, -v56, v59, v58
	v_fmac_f32_e32 v59, v60, v57
	v_fma_f32 v56, -v56, v59, v58
	v_div_fmas_f32 v56, v56, v57, v59
	v_div_fixup_f32 v54, v56, v54, 1.0
	v_pk_mul_f32 v[52:53], v[54:55], v[52:53]
	s_nop 0
	v_pk_mul_f32 v[48:49], v[48:49], v[52:53]
	v_lshlrev_b32_e32 v53, 16, v51
	v_lshlrev_b32_e32 v52, 16, v50
	v_and_b32_e32 v51, 0xffff0000, v51
	v_and_b32_e32 v50, 0xffff0000, v50
	v_pk_fma_f32 v[50:51], v[68:69], v[50:51], v[52:53]
	v_lshlrev_b32_e32 v52, 16, v97
	v_cvt_pk_bf16_f32 v48, v48, v49
	v_mul_f32_e32 v49, 0x3d372713, v52
	v_mul_f32_e32 v49, v49, v52
	v_mov_b32_e32 v54, v52
	v_fmac_f32_e32 v54, v49, v54
	v_mul_f32_e32 v49, 0x3f4c422a, v54
	v_mul_f32_e32 v49, -2.0, v49
	v_and_b32_e32 v53, 0xffff0000, v97
	v_mul_f32_e32 v49, 0x3fb8aa3b, v49
	v_exp_f32_e32 v54, v49
	v_mul_f32_e32 v49, 0x3d372713, v53
	v_mul_f32_e32 v49, v49, v53
	v_mov_b32_e32 v55, v53
	v_fmac_f32_e32 v55, v49, v55
	v_mul_f32_e32 v49, 0x3f4c422a, v55
	v_mul_f32_e32 v49, -2.0, v49
	v_mul_f32_e32 v49, 0x3fb8aa3b, v49
	v_exp_f32_e32 v55, v49
	s_nop 0
	v_pk_add_f32 v[54:55], v[54:55], 1.0 op_sel_hi:[1,0]
	s_nop 0
	v_div_scale_f32 v49, s[4:5], v55, v55, 1.0
	v_rcp_f32_e32 v56, v49
	s_nop 0
	v_fma_f32 v57, -v49, v56, 1.0
	v_fmac_f32_e32 v56, v57, v56
	v_div_scale_f32 v57, vcc, 1.0, v55, 1.0
	v_mul_f32_e32 v58, v57, v56
	v_fma_f32 v59, -v49, v58, v57
	v_fmac_f32_e32 v58, v59, v56
	v_fma_f32 v49, -v49, v58, v57
	v_div_fmas_f32 v49, v49, v56, v58
	v_div_fixup_f32 v55, v49, v55, 1.0
	v_div_scale_f32 v49, s[4:5], v54, v54, 1.0
	v_rcp_f32_e32 v56, v49
	s_mov_b32 s4, 0x4586e000
	v_fma_f32 v57, -v49, v56, 1.0
	v_fmac_f32_e32 v56, v57, v56
	v_div_scale_f32 v57, vcc, 1.0, v54, 1.0
	v_mul_f32_e32 v58, v57, v56
	v_fma_f32 v59, -v49, v58, v57
	v_fmac_f32_e32 v58, v59, v56
	v_fma_f32 v49, -v49, v58, v57
	v_div_fmas_f32 v49, v49, v56, v58
	v_div_fixup_f32 v54, v49, v54, 1.0
	v_pk_mul_f32 v[52:53], v[54:55], v[52:53]
	s_nop 0
	v_pk_mul_f32 v[50:51], v[50:51], v[52:53]
	s_nop 0
	v_cvt_pk_bf16_f32 v49, v50, v51
	v_add_co_u32_e32 v50, vcc, s4, v72
	s_nop 1
	v_addc_co_u32_e32 v51, vcc, 0, v73, vcc
	global_store_dwordx2 v[50:51], v[48:49], off
	v_lshlrev_b32_e32 v49, 16, v45
	v_lshlrev_b32_e32 v48, 16, v44
	v_and_b32_e32 v45, 0xffff0000, v45
	v_and_b32_e32 v44, 0xffff0000, v44
	v_pk_fma_f32 v[44:45], v[70:71], v[44:45], v[48:49]
	v_lshlrev_b32_e32 v48, 16, v94
	v_mul_f32_e32 v50, 0x3d372713, v48
	v_mul_f32_e32 v50, v50, v48
	v_mov_b32_e32 v51, v48
	v_and_b32_e32 v49, 0xffff0000, v94
	v_fmac_f32_e32 v51, v50, v51
	v_mul_f32_e32 v50, 0x3f4c422a, v51
	v_mul_f32_e32 v51, 0x3d372713, v49
	v_mul_f32_e32 v51, v51, v49
	v_mov_b32_e32 v52, v49
	v_fmac_f32_e32 v52, v51, v52
	v_mul_f32_e32 v51, 0x3f4c422a, v52
	v_mul_f32_e32 v50, -2.0, v50
	v_mul_f32_e32 v51, -2.0, v51
	v_mul_f32_e32 v50, 0x3fb8aa3b, v50
	v_mul_f32_e32 v51, 0x3fb8aa3b, v51
	v_exp_f32_e32 v50, v50
	v_exp_f32_e32 v51, v51
	s_nop 0
	v_pk_add_f32 v[50:51], v[50:51], 1.0 op_sel_hi:[1,0]
	s_nop 0
	v_div_scale_f32 v52, s[4:5], v51, v51, 1.0
	v_rcp_f32_e32 v53, v52
	s_nop 0
	v_fma_f32 v54, -v52, v53, 1.0
	v_fmac_f32_e32 v53, v54, v53
	v_div_scale_f32 v54, vcc, 1.0, v51, 1.0
	v_mul_f32_e32 v55, v54, v53
	v_fma_f32 v56, -v52, v55, v54
	v_fmac_f32_e32 v55, v56, v53
	v_fma_f32 v52, -v52, v55, v54
	v_div_fmas_f32 v52, v52, v53, v55
	v_div_fixup_f32 v51, v52, v51, 1.0
	v_div_scale_f32 v52, s[4:5], v50, v50, 1.0
	v_rcp_f32_e32 v53, v52
	s_nop 0
	v_fma_f32 v54, -v52, v53, 1.0
	v_fmac_f32_e32 v53, v54, v53
	v_div_scale_f32 v54, vcc, 1.0, v50, 1.0
	v_mul_f32_e32 v55, v54, v53
	v_fma_f32 v56, -v52, v55, v54
	v_fmac_f32_e32 v55, v56, v53
	v_fma_f32 v52, -v52, v55, v54
	v_div_fmas_f32 v52, v52, v53, v55
	v_div_fixup_f32 v50, v52, v50, 1.0
	v_pk_mul_f32 v[48:49], v[50:51], v[48:49]
	s_nop 0
	v_pk_mul_f32 v[44:45], v[44:45], v[48:49]
	v_lshlrev_b32_e32 v49, 16, v47
	v_lshlrev_b32_e32 v48, 16, v46
	v_and_b32_e32 v47, 0xffff0000, v47
	v_and_b32_e32 v46, 0xffff0000, v46
	v_pk_fma_f32 v[46:47], v[68:69], v[46:47], v[48:49]
	v_lshlrev_b32_e32 v48, 16, v95
	v_cvt_pk_bf16_f32 v44, v44, v45
	v_mul_f32_e32 v45, 0x3d372713, v48
	v_mul_f32_e32 v45, v45, v48
	v_mov_b32_e32 v50, v48
	v_fmac_f32_e32 v50, v45, v50
	v_mul_f32_e32 v45, 0x3f4c422a, v50
	v_mul_f32_e32 v45, -2.0, v45
	v_and_b32_e32 v49, 0xffff0000, v95
	v_mul_f32_e32 v45, 0x3fb8aa3b, v45
	v_exp_f32_e32 v50, v45
	v_mul_f32_e32 v45, 0x3d372713, v49
	v_mul_f32_e32 v45, v45, v49
	v_mov_b32_e32 v51, v49
	v_fmac_f32_e32 v51, v45, v51
	v_mul_f32_e32 v45, 0x3f4c422a, v51
	v_mul_f32_e32 v45, -2.0, v45
	v_mul_f32_e32 v45, 0x3fb8aa3b, v45
	v_exp_f32_e32 v51, v45
	s_nop 0
	v_pk_add_f32 v[50:51], v[50:51], 1.0 op_sel_hi:[1,0]
	s_nop 0
	v_div_scale_f32 v45, s[4:5], v51, v51, 1.0
	v_rcp_f32_e32 v52, v45
	s_nop 0
	v_fma_f32 v53, -v45, v52, 1.0
	v_fmac_f32_e32 v52, v53, v52
	v_div_scale_f32 v53, vcc, 1.0, v51, 1.0
	v_mul_f32_e32 v54, v53, v52
	v_fma_f32 v55, -v45, v54, v53
	v_fmac_f32_e32 v54, v55, v52
	v_fma_f32 v45, -v45, v54, v53
	v_div_fmas_f32 v45, v45, v52, v54
	v_div_fixup_f32 v51, v45, v51, 1.0
	v_div_scale_f32 v45, s[4:5], v50, v50, 1.0
	v_rcp_f32_e32 v52, v45
	s_mov_b32 s4, 0x45874000
	v_fma_f32 v53, -v45, v52, 1.0
	v_fmac_f32_e32 v52, v53, v52
	v_div_scale_f32 v53, vcc, 1.0, v50, 1.0
; DI float bflo(unsigned w) { return __uint_as_float(w << 16); }
; DI float bfhi(unsigned w) { return __uint_as_float(w & 0xffff0000u); }
; DI unsigned pk2(float a, float b) { f32x2 v = {a, b}; bf16v2 r = __builtin_convertvector(v, bf16v2); return __builtin_bit_cast(unsigned, r); }
; DI float gelu_tanh(float x) { const float u = 0.7978845608028654f * (x + 0.044715f * x * x * x); const float e = __expf(-2.0f * u); return x * (1.0f / (1.0f + e)); }
; DI void lru_fix_unit(const Ctx& c, int l, int chunk, int half) {
;     ...
;     for (int k = 0; k < 16; ++k) {
;         h[0] = bflo(hv[k].x) + bfhi(hv[k].x) * cr[0]; h[1] = bflo(hv[k].y) + bfhi(hv[k].y) * cr[1]; h[2] = bflo(hv[k].z) + bfhi(hv[k].z) * cr[2]; h[3] = bflo(hv[k].w) + bfhi(hv[k].w) * cr[3];
;         u32x2 w; w.x = pk2(h[0] * gelu_tanh(bflo(gv[k].x)), h[1] * gelu_tanh(bfhi(gv[k].x))); w.y = pk2(h[2] * gelu_tanh(bflo(gv[k].y)), h[3] * gelu_tanh(bfhi(gv[k].y)));
;         *(u32x2*)(br + (size_t)(4 * k) * 3072) = w;
;     }
	v_mul_f32_e32 v54, v53, v52
	v_fma_f32 v55, -v45, v54, v53
	v_fmac_f32_e32 v54, v55, v52
	v_fma_f32 v45, -v45, v54, v53
	v_div_fmas_f32 v45, v45, v52, v54
	v_div_fixup_f32 v50, v45, v50, 1.0
	v_pk_mul_f32 v[48:49], v[50:51], v[48:49]
	s_nop 0
	v_pk_mul_f32 v[46:47], v[46:47], v[48:49]
	s_nop 0
	v_cvt_pk_bf16_f32 v45, v46, v47
	v_add_co_u32_e32 v46, vcc, s4, v72
	s_nop 1
	v_addc_co_u32_e32 v47, vcc, 0, v73, vcc
	global_store_dwordx2 v[46:47], v[44:45], off
	v_lshlrev_b32_e32 v45, 16, v41
	v_lshlrev_b32_e32 v44, 16, v40
	v_and_b32_e32 v41, 0xffff0000, v41
	v_and_b32_e32 v40, 0xffff0000, v40
	v_pk_fma_f32 v[40:41], v[70:71], v[40:41], v[44:45]
	v_lshlrev_b32_e32 v44, 16, v92
	v_mul_f32_e32 v46, 0x3d372713, v44
	v_mul_f32_e32 v46, v46, v44
	v_mov_b32_e32 v47, v44
	v_and_b32_e32 v45, 0xffff0000, v92
	v_fmac_f32_e32 v47, v46, v47
	v_mul_f32_e32 v46, 0x3f4c422a, v47
	v_mul_f32_e32 v47, 0x3d372713, v45
	v_mul_f32_e32 v47, v47, v45
	v_mov_b32_e32 v48, v45
	v_fmac_f32_e32 v48, v47, v48
	v_mul_f32_e32 v47, 0x3f4c422a, v48
	v_mul_f32_e32 v46, -2.0, v46
	v_mul_f32_e32 v47, -2.0, v47
	v_mul_f32_e32 v46, 0x3fb8aa3b, v46
	v_mul_f32_e32 v47, 0x3fb8aa3b, v47
	v_exp_f32_e32 v46, v46
	v_exp_f32_e32 v47, v47
	s_nop 0
	v_pk_add_f32 v[46:47], v[46:47], 1.0 op_sel_hi:[1,0]
	s_nop 0
	v_div_scale_f32 v48, s[4:5], v47, v47, 1.0
	v_rcp_f32_e32 v49, v48
	s_nop 0
	v_fma_f32 v50, -v48, v49, 1.0
	v_fmac_f32_e32 v49, v50, v49
	v_div_scale_f32 v50, vcc, 1.0, v47, 1.0
	v_mul_f32_e32 v51, v50, v49
	v_fma_f32 v52, -v48, v51, v50
	v_fmac_f32_e32 v51, v52, v49
	v_fma_f32 v48, -v48, v51, v50
	v_div_fmas_f32 v48, v48, v49, v51
	v_div_fixup_f32 v47, v48, v47, 1.0
	v_div_scale_f32 v48, s[4:5], v46, v46, 1.0
	v_rcp_f32_e32 v49, v48
	s_nop 0
	v_fma_f32 v50, -v48, v49, 1.0
	v_fmac_f32_e32 v49, v50, v49
	v_div_scale_f32 v50, vcc, 1.0, v46, 1.0
	v_mul_f32_e32 v51, v50, v49
	v_fma_f32 v52, -v48, v51, v50
	v_fmac_f32_e32 v51, v52, v49
	v_fma_f32 v48, -v48, v51, v50
	v_div_fmas_f32 v48, v48, v49, v51
	v_div_fixup_f32 v46, v48, v46, 1.0
	v_pk_mul_f32 v[44:45], v[46:47], v[44:45]
	s_nop 0
	v_pk_mul_f32 v[40:41], v[40:41], v[44:45]
	v_lshlrev_b32_e32 v45, 16, v43
	v_lshlrev_b32_e32 v44, 16, v42
	v_and_b32_e32 v43, 0xffff0000, v43
	v_and_b32_e32 v42, 0xffff0000, v42
	v_pk_fma_f32 v[42:43], v[68:69], v[42:43], v[44:45]
	v_lshlrev_b32_e32 v44, 16, v93
	v_cvt_pk_bf16_f32 v40, v40, v41
	v_mul_f32_e32 v41, 0x3d372713, v44
	v_mul_f32_e32 v41, v41, v44
	v_mov_b32_e32 v46, v44
	v_fmac_f32_e32 v46, v41, v46
	v_mul_f32_e32 v41, 0x3f4c422a, v46
	v_mul_f32_e32 v41, -2.0, v41
	v_and_b32_e32 v45, 0xffff0000, v93
	v_mul_f32_e32 v41, 0x3fb8aa3b, v41
	v_exp_f32_e32 v46, v41
	v_mul_f32_e32 v41, 0x3d372713, v45
	v_mul_f32_e32 v41, v41, v45
	v_mov_b32_e32 v47, v45
	v_fmac_f32_e32 v47, v41, v47
	v_mul_f32_e32 v41, 0x3f4c422a, v47
	v_mul_f32_e32 v41, -2.0, v41
	v_mul_f32_e32 v41, 0x3fb8aa3b, v41
	v_exp_f32_e32 v47, v41
	s_nop 0
	v_pk_add_f32 v[46:47], v[46:47], 1.0 op_sel_hi:[1,0]
	s_nop 0
	v_div_scale_f32 v41, s[4:5], v47, v47, 1.0
	v_rcp_f32_e32 v48, v41
	s_nop 0
	v_fma_f32 v49, -v41, v48, 1.0
	v_fmac_f32_e32 v48, v49, v48
	v_div_scale_f32 v49, vcc, 1.0, v47, 1.0
	v_mul_f32_e32 v50, v49, v48
	v_fma_f32 v51, -v41, v50, v49
	v_fmac_f32_e32 v50, v51, v48
	v_fma_f32 v41, -v41, v50, v49
	v_div_fmas_f32 v41, v41, v48, v50
	v_div_fixup_f32 v47, v41, v47, 1.0
	v_div_scale_f32 v41, s[4:5], v46, v46, 1.0
	v_rcp_f32_e32 v48, v41
	s_mov_b32 s4, 0x4587a000
	v_fma_f32 v49, -v41, v48, 1.0
	v_fmac_f32_e32 v48, v49, v48
	v_div_scale_f32 v49, vcc, 1.0, v46, 1.0
	v_mul_f32_e32 v50, v49, v48
	v_fma_f32 v51, -v41, v50, v49
	v_fmac_f32_e32 v50, v51, v48
	v_fma_f32 v41, -v41, v50, v49
	v_div_fmas_f32 v41, v41, v48, v50
	v_div_fixup_f32 v46, v41, v46, 1.0
	v_pk_mul_f32 v[44:45], v[46:47], v[44:45]
	s_nop 0
	v_pk_mul_f32 v[42:43], v[42:43], v[44:45]
	s_nop 0
	v_cvt_pk_bf16_f32 v41, v42, v43
	v_add_co_u32_e32 v42, vcc, s4, v72
	s_nop 1
	v_addc_co_u32_e32 v43, vcc, 0, v73, vcc
	global_store_dwordx2 v[42:43], v[40:41], off
	v_lshlrev_b32_e32 v41, 16, v37
	v_lshlrev_b32_e32 v40, 16, v36
	v_and_b32_e32 v37, 0xffff0000, v37
	v_and_b32_e32 v36, 0xffff0000, v36
	v_pk_fma_f32 v[36:37], v[70:71], v[36:37], v[40:41]
	v_lshlrev_b32_e32 v40, 16, v90
	v_mul_f32_e32 v42, 0x3d372713, v40
	v_mul_f32_e32 v42, v42, v40
	v_mov_b32_e32 v43, v40
	v_and_b32_e32 v41, 0xffff0000, v90
	v_fmac_f32_e32 v43, v42, v43
	v_mul_f32_e32 v42, 0x3f4c422a, v43
	v_mul_f32_e32 v43, 0x3d372713, v41
	v_mul_f32_e32 v43, v43, v41
	v_mov_b32_e32 v44, v41
	v_fmac_f32_e32 v44, v43, v44
	v_mul_f32_e32 v43, 0x3f4c422a, v44
	v_mul_f32_e32 v42, -2.0, v42
	v_mul_f32_e32 v43, -2.0, v43
	v_mul_f32_e32 v42, 0x3fb8aa3b, v42
	v_mul_f32_e32 v43, 0x3fb8aa3b, v43
	v_exp_f32_e32 v42, v42
	v_exp_f32_e32 v43, v43
	s_nop 0
	v_pk_add_f32 v[42:43], v[42:43], 1.0 op_sel_hi:[1,0]
	s_nop 0
	v_div_scale_f32 v44, s[4:5], v43, v43, 1.0
	v_rcp_f32_e32 v45, v44
	s_nop 0
	v_fma_f32 v46, -v44, v45, 1.0
	v_fmac_f32_e32 v45, v46, v45
	v_div_scale_f32 v46, vcc, 1.0, v43, 1.0
	v_mul_f32_e32 v47, v46, v45
	v_fma_f32 v48, -v44, v47, v46
	v_fmac_f32_e32 v47, v48, v45
	v_fma_f32 v44, -v44, v47, v46
	v_div_fmas_f32 v44, v44, v45, v47
	v_div_fixup_f32 v43, v44, v43, 1.0
	v_div_scale_f32 v44, s[4:5], v42, v42, 1.0
	v_rcp_f32_e32 v45, v44
	s_nop 0
	v_fma_f32 v46, -v44, v45, 1.0
	v_fmac_f32_e32 v45, v46, v45
	v_div_scale_f32 v46, vcc, 1.0, v42, 1.0
	v_mul_f32_e32 v47, v46, v45
	v_fma_f32 v48, -v44, v47, v46
	v_fmac_f32_e32 v47, v48, v45
	v_fma_f32 v44, -v44, v47, v46
	v_div_fmas_f32 v44, v44, v45, v47
	v_div_fixup_f32 v42, v44, v42, 1.0
	v_pk_mul_f32 v[40:41], v[42:43], v[40:41]
	s_nop 0
	v_pk_mul_f32 v[36:37], v[36:37], v[40:41]
; DI float bflo(unsigned w) { return __uint_as_float(w << 16); }
; DI float bfhi(unsigned w) { return __uint_as_float(w & 0xffff0000u); }
; DI unsigned pk2(float a, float b) { f32x2 v = {a, b}; bf16v2 r = __builtin_convertvector(v, bf16v2); return __builtin_bit_cast(unsigned, r); }
; DI float gelu_tanh(float x) { const float u = 0.7978845608028654f * (x + 0.044715f * x * x * x); const float e = __expf(-2.0f * u); return x * (1.0f / (1.0f + e)); }
; DI void lru_fix_unit(const Ctx& c, int l, int chunk, int half) {
;     ...
;     for (int k = 0; k < 16; ++k) {
;         h[0] = bflo(hv[k].x) + bfhi(hv[k].x) * cr[0]; h[1] = bflo(hv[k].y) + bfhi(hv[k].y) * cr[1]; h[2] = bflo(hv[k].z) + bfhi(hv[k].z) * cr[2]; h[3] = bflo(hv[k].w) + bfhi(hv[k].w) * cr[3];
;         u32x2 w; w.x = pk2(h[0] * gelu_tanh(bflo(gv[k].x)), h[1] * gelu_tanh(bfhi(gv[k].x))); w.y = pk2(h[2] * gelu_tanh(bflo(gv[k].y)), h[3] * gelu_tanh(bfhi(gv[k].y)));
;         *(u32x2*)(br + (size_t)(4 * k) * 3072) = w;
;     }
	v_lshlrev_b32_e32 v41, 16, v39
	v_lshlrev_b32_e32 v40, 16, v38
	v_and_b32_e32 v39, 0xffff0000, v39
	v_and_b32_e32 v38, 0xffff0000, v38
	v_pk_fma_f32 v[38:39], v[68:69], v[38:39], v[40:41]
	v_lshlrev_b32_e32 v40, 16, v91
	v_cvt_pk_bf16_f32 v36, v36, v37
	v_mul_f32_e32 v37, 0x3d372713, v40
	v_mul_f32_e32 v37, v37, v40
	v_mov_b32_e32 v42, v40
	v_fmac_f32_e32 v42, v37, v42
	v_mul_f32_e32 v37, 0x3f4c422a, v42
	v_mul_f32_e32 v37, -2.0, v37
	v_and_b32_e32 v41, 0xffff0000, v91
	v_mul_f32_e32 v37, 0x3fb8aa3b, v37
	v_exp_f32_e32 v42, v37
	v_mul_f32_e32 v37, 0x3d372713, v41
	v_mul_f32_e32 v37, v37, v41
	v_mov_b32_e32 v43, v41
	v_fmac_f32_e32 v43, v37, v43
	v_mul_f32_e32 v37, 0x3f4c422a, v43
	v_mul_f32_e32 v37, -2.0, v37
	v_mul_f32_e32 v37, 0x3fb8aa3b, v37
	v_exp_f32_e32 v43, v37
	s_nop 0
	v_pk_add_f32 v[42:43], v[42:43], 1.0 op_sel_hi:[1,0]
	s_nop 0
	v_div_scale_f32 v37, s[4:5], v43, v43, 1.0
	v_rcp_f32_e32 v44, v37
	s_nop 0
	v_fma_f32 v45, -v37, v44, 1.0
	v_fmac_f32_e32 v44, v45, v44
	v_div_scale_f32 v45, vcc, 1.0, v43, 1.0
	v_mul_f32_e32 v46, v45, v44
	v_fma_f32 v47, -v37, v46, v45
	v_fmac_f32_e32 v46, v47, v44
	v_fma_f32 v37, -v37, v46, v45
	v_div_fmas_f32 v37, v37, v44, v46
	v_div_fixup_f32 v43, v37, v43, 1.0
	v_div_scale_f32 v37, s[4:5], v42, v42, 1.0
	v_rcp_f32_e32 v44, v37
	s_mov_b32 s4, 0x45880000
	v_fma_f32 v45, -v37, v44, 1.0
	v_fmac_f32_e32 v44, v45, v44
	v_div_scale_f32 v45, vcc, 1.0, v42, 1.0
	v_mul_f32_e32 v46, v45, v44
	v_fma_f32 v47, -v37, v46, v45
	v_fmac_f32_e32 v46, v47, v44
	v_fma_f32 v37, -v37, v46, v45
	v_div_fmas_f32 v37, v37, v44, v46
	v_div_fixup_f32 v42, v37, v42, 1.0
	v_pk_mul_f32 v[40:41], v[42:43], v[40:41]
	s_nop 0
	v_pk_mul_f32 v[38:39], v[38:39], v[40:41]
	s_nop 0
	v_cvt_pk_bf16_f32 v37, v38, v39
	v_add_co_u32_e32 v38, vcc, s4, v72
	s_nop 1
	v_addc_co_u32_e32 v39, vcc, 0, v73, vcc
	global_store_dwordx2 v[38:39], v[36:37], off
	v_lshlrev_b32_e32 v37, 16, v33
	v_lshlrev_b32_e32 v36, 16, v32
	v_and_b32_e32 v33, 0xffff0000, v33
	v_and_b32_e32 v32, 0xffff0000, v32
	v_pk_fma_f32 v[32:33], v[70:71], v[32:33], v[36:37]
	v_lshlrev_b32_e32 v36, 16, v88
	v_mul_f32_e32 v38, 0x3d372713, v36
	v_mul_f32_e32 v38, v38, v36
	v_mov_b32_e32 v39, v36
	v_and_b32_e32 v37, 0xffff0000, v88
	v_fmac_f32_e32 v39, v38, v39
	v_mul_f32_e32 v38, 0x3f4c422a, v39
	v_mul_f32_e32 v39, 0x3d372713, v37
	v_mul_f32_e32 v39, v39, v37
	v_mov_b32_e32 v40, v37
	v_fmac_f32_e32 v40, v39, v40
	v_mul_f32_e32 v39, 0x3f4c422a, v40
	v_mul_f32_e32 v38, -2.0, v38
	v_mul_f32_e32 v39, -2.0, v39
	v_mul_f32_e32 v38, 0x3fb8aa3b, v38
	v_mul_f32_e32 v39, 0x3fb8aa3b, v39
	v_exp_f32_e32 v38, v38
	v_exp_f32_e32 v39, v39
	s_nop 0
	v_pk_add_f32 v[38:39], v[38:39], 1.0 op_sel_hi:[1,0]
	s_nop 0
	v_div_scale_f32 v40, s[4:5], v39, v39, 1.0
	v_rcp_f32_e32 v41, v40
	s_nop 0
	v_fma_f32 v42, -v40, v41, 1.0
	v_fmac_f32_e32 v41, v42, v41
	v_div_scale_f32 v42, vcc, 1.0, v39, 1.0
	v_mul_f32_e32 v43, v42, v41
	v_fma_f32 v44, -v40, v43, v42
	v_fmac_f32_e32 v43, v44, v41
	v_fma_f32 v40, -v40, v43, v42
	v_div_fmas_f32 v40, v40, v41, v43
	v_div_fixup_f32 v39, v40, v39, 1.0
	v_div_scale_f32 v40, s[4:5], v38, v38, 1.0
	v_rcp_f32_e32 v41, v40
	s_nop 0
	v_fma_f32 v42, -v40, v41, 1.0
	v_fmac_f32_e32 v41, v42, v41
	v_div_scale_f32 v42, vcc, 1.0, v38, 1.0
	v_mul_f32_e32 v43, v42, v41
	v_fma_f32 v44, -v40, v43, v42
	v_fmac_f32_e32 v43, v44, v41
	v_fma_f32 v40, -v40, v43, v42
	v_div_fmas_f32 v40, v40, v41, v43
	v_div_fixup_f32 v38, v40, v38, 1.0
	v_pk_mul_f32 v[36:37], v[38:39], v[36:37]
	s_nop 0
	v_pk_mul_f32 v[32:33], v[32:33], v[36:37]
	v_lshlrev_b32_e32 v37, 16, v35
	v_lshlrev_b32_e32 v36, 16, v34
	v_and_b32_e32 v35, 0xffff0000, v35
	v_and_b32_e32 v34, 0xffff0000, v34
	v_pk_fma_f32 v[34:35], v[68:69], v[34:35], v[36:37]
	v_lshlrev_b32_e32 v36, 16, v89
	v_cvt_pk_bf16_f32 v32, v32, v33
	v_mul_f32_e32 v33, 0x3d372713, v36
	v_mul_f32_e32 v33, v33, v36
	v_mov_b32_e32 v38, v36
	v_fmac_f32_e32 v38, v33, v38
	v_mul_f32_e32 v33, 0x3f4c422a, v38
	v_mul_f32_e32 v33, -2.0, v33
	v_and_b32_e32 v37, 0xffff0000, v89
	v_mul_f32_e32 v33, 0x3fb8aa3b, v33
	v_exp_f32_e32 v38, v33
	v_mul_f32_e32 v33, 0x3d372713, v37
	v_mul_f32_e32 v33, v33, v37
	v_mov_b32_e32 v39, v37
	v_fmac_f32_e32 v39, v33, v39
	v_mul_f32_e32 v33, 0x3f4c422a, v39
	v_mul_f32_e32 v33, -2.0, v33
	v_mul_f32_e32 v33, 0x3fb8aa3b, v33
	v_exp_f32_e32 v39, v33
	s_nop 0
	v_pk_add_f32 v[38:39], v[38:39], 1.0 op_sel_hi:[1,0]
	s_nop 0
	v_div_scale_f32 v33, s[4:5], v39, v39, 1.0
	v_rcp_f32_e32 v40, v33
	s_nop 0
	v_fma_f32 v41, -v33, v40, 1.0
	v_fmac_f32_e32 v40, v41, v40
	v_div_scale_f32 v41, vcc, 1.0, v39, 1.0
	v_mul_f32_e32 v42, v41, v40
	v_fma_f32 v43, -v33, v42, v41
	v_fmac_f32_e32 v42, v43, v40
	v_fma_f32 v33, -v33, v42, v41
	v_div_fmas_f32 v33, v33, v40, v42
	v_div_fixup_f32 v39, v33, v39, 1.0
	v_div_scale_f32 v33, s[4:5], v38, v38, 1.0
	v_rcp_f32_e32 v40, v33
	s_mov_b32 s4, 0x45886000
	v_fma_f32 v41, -v33, v40, 1.0
	v_fmac_f32_e32 v40, v41, v40
	v_div_scale_f32 v41, vcc, 1.0, v38, 1.0
	v_mul_f32_e32 v42, v41, v40
	v_fma_f32 v43, -v33, v42, v41
	v_fmac_f32_e32 v42, v43, v40
	v_fma_f32 v33, -v33, v42, v41
	v_div_fmas_f32 v33, v33, v40, v42
	v_div_fixup_f32 v38, v33, v38, 1.0
	v_pk_mul_f32 v[36:37], v[38:39], v[36:37]
	s_nop 0
	v_pk_mul_f32 v[34:35], v[34:35], v[36:37]
	s_nop 0
	v_cvt_pk_bf16_f32 v33, v34, v35
	v_add_co_u32_e32 v34, vcc, s4, v72
	s_nop 1
	v_addc_co_u32_e32 v35, vcc, 0, v73, vcc
	global_store_dwordx2 v[34:35], v[32:33], off
	v_lshlrev_b32_e32 v33, 16, v29
	v_lshlrev_b32_e32 v32, 16, v28
	v_and_b32_e32 v29, 0xffff0000, v29
	v_and_b32_e32 v28, 0xffff0000, v28
	v_pk_fma_f32 v[28:29], v[70:71], v[28:29], v[32:33]
	v_lshlrev_b32_e32 v32, 16, v86
; DI float bflo(unsigned w) { return __uint_as_float(w << 16); }
; DI float bfhi(unsigned w) { return __uint_as_float(w & 0xffff0000u); }
; DI unsigned pk2(float a, float b) { f32x2 v = {a, b}; bf16v2 r = __builtin_convertvector(v, bf16v2); return __builtin_bit_cast(unsigned, r); }
; DI float gelu_tanh(float x) { const float u = 0.7978845608028654f * (x + 0.044715f * x * x * x); const float e = __expf(-2.0f * u); return x * (1.0f / (1.0f + e)); }
; DI void lru_fix_unit(const Ctx& c, int l, int chunk, int half) {
;     ...
;     for (int k = 0; k < 16; ++k) {
;         h[0] = bflo(hv[k].x) + bfhi(hv[k].x) * cr[0]; h[1] = bflo(hv[k].y) + bfhi(hv[k].y) * cr[1]; h[2] = bflo(hv[k].z) + bfhi(hv[k].z) * cr[2]; h[3] = bflo(hv[k].w) + bfhi(hv[k].w) * cr[3];
;         u32x2 w; w.x = pk2(h[0] * gelu_tanh(bflo(gv[k].x)), h[1] * gelu_tanh(bfhi(gv[k].x))); w.y = pk2(h[2] * gelu_tanh(bflo(gv[k].y)), h[3] * gelu_tanh(bfhi(gv[k].y)));
;         *(u32x2*)(br + (size_t)(4 * k) * 3072) = w;
;     }
	v_mul_f32_e32 v34, 0x3d372713, v32
	v_mul_f32_e32 v34, v34, v32
	v_mov_b32_e32 v35, v32
	v_and_b32_e32 v33, 0xffff0000, v86
	v_fmac_f32_e32 v35, v34, v35
	v_mul_f32_e32 v34, 0x3f4c422a, v35
	v_mul_f32_e32 v35, 0x3d372713, v33
	v_mul_f32_e32 v35, v35, v33
	v_mov_b32_e32 v36, v33
	v_fmac_f32_e32 v36, v35, v36
	v_mul_f32_e32 v35, 0x3f4c422a, v36
	v_mul_f32_e32 v34, -2.0, v34
	v_mul_f32_e32 v35, -2.0, v35
	v_mul_f32_e32 v34, 0x3fb8aa3b, v34
	v_mul_f32_e32 v35, 0x3fb8aa3b, v35
	v_exp_f32_e32 v34, v34
	v_exp_f32_e32 v35, v35
	s_nop 0
	v_pk_add_f32 v[34:35], v[34:35], 1.0 op_sel_hi:[1,0]
	s_nop 0
	v_div_scale_f32 v36, s[4:5], v35, v35, 1.0
	v_rcp_f32_e32 v37, v36
	s_nop 0
	v_fma_f32 v38, -v36, v37, 1.0
	v_fmac_f32_e32 v37, v38, v37
	v_div_scale_f32 v38, vcc, 1.0, v35, 1.0
	v_mul_f32_e32 v39, v38, v37
	v_fma_f32 v40, -v36, v39, v38
	v_fmac_f32_e32 v39, v40, v37
	v_fma_f32 v36, -v36, v39, v38
	v_div_fmas_f32 v36, v36, v37, v39
	v_div_fixup_f32 v35, v36, v35, 1.0
	v_div_scale_f32 v36, s[4:5], v34, v34, 1.0
	v_rcp_f32_e32 v37, v36
	s_nop 0
	v_fma_f32 v38, -v36, v37, 1.0
	v_fmac_f32_e32 v37, v38, v37
	v_div_scale_f32 v38, vcc, 1.0, v34, 1.0
	v_mul_f32_e32 v39, v38, v37
	v_fma_f32 v40, -v36, v39, v38
	v_fmac_f32_e32 v39, v40, v37
	v_fma_f32 v36, -v36, v39, v38
	v_div_fmas_f32 v36, v36, v37, v39
	v_div_fixup_f32 v34, v36, v34, 1.0
	v_pk_mul_f32 v[32:33], v[34:35], v[32:33]
	s_nop 0
	v_pk_mul_f32 v[28:29], v[28:29], v[32:33]
	v_lshlrev_b32_e32 v33, 16, v31
	v_lshlrev_b32_e32 v32, 16, v30
	v_and_b32_e32 v31, 0xffff0000, v31
	v_and_b32_e32 v30, 0xffff0000, v30
	v_pk_fma_f32 v[30:31], v[68:69], v[30:31], v[32:33]
	v_lshlrev_b32_e32 v32, 16, v87
	v_cvt_pk_bf16_f32 v28, v28, v29
	v_mul_f32_e32 v29, 0x3d372713, v32
	v_mul_f32_e32 v29, v29, v32
	v_mov_b32_e32 v34, v32
	v_fmac_f32_e32 v34, v29, v34
	v_mul_f32_e32 v29, 0x3f4c422a, v34
	v_mul_f32_e32 v29, -2.0, v29
	v_and_b32_e32 v33, 0xffff0000, v87
	v_mul_f32_e32 v29, 0x3fb8aa3b, v29
	v_exp_f32_e32 v34, v29
	v_mul_f32_e32 v29, 0x3d372713, v33
	v_mul_f32_e32 v29, v29, v33
	v_mov_b32_e32 v35, v33
	v_fmac_f32_e32 v35, v29, v35
	v_mul_f32_e32 v29, 0x3f4c422a, v35
	v_mul_f32_e32 v29, -2.0, v29
	v_mul_f32_e32 v29, 0x3fb8aa3b, v29
	v_exp_f32_e32 v35, v29
	s_nop 0
	v_pk_add_f32 v[34:35], v[34:35], 1.0 op_sel_hi:[1,0]
	s_nop 0
	v_div_scale_f32 v29, s[4:5], v35, v35, 1.0
	v_rcp_f32_e32 v36, v29
	s_nop 0
	v_fma_f32 v37, -v29, v36, 1.0
	v_fmac_f32_e32 v36, v37, v36
	v_div_scale_f32 v37, vcc, 1.0, v35, 1.0
	v_mul_f32_e32 v38, v37, v36
	v_fma_f32 v39, -v29, v38, v37
	v_fmac_f32_e32 v38, v39, v36
	v_fma_f32 v29, -v29, v38, v37
	v_div_fmas_f32 v29, v29, v36, v38
	v_div_fixup_f32 v35, v29, v35, 1.0
	v_div_scale_f32 v29, s[4:5], v34, v34, 1.0
	v_rcp_f32_e32 v36, v29
	s_mov_b32 s4, 0x4588c000
	v_fma_f32 v37, -v29, v36, 1.0
	v_fmac_f32_e32 v36, v37, v36
	v_div_scale_f32 v37, vcc, 1.0, v34, 1.0
	v_mul_f32_e32 v38, v37, v36
	v_fma_f32 v39, -v29, v38, v37
	v_fmac_f32_e32 v38, v39, v36
	v_fma_f32 v29, -v29, v38, v37
	v_div_fmas_f32 v29, v29, v36, v38
	v_div_fixup_f32 v34, v29, v34, 1.0
	v_pk_mul_f32 v[32:33], v[34:35], v[32:33]
	s_nop 0
	v_pk_mul_f32 v[30:31], v[30:31], v[32:33]
	s_nop 0
	v_cvt_pk_bf16_f32 v29, v30, v31
	v_add_co_u32_e32 v30, vcc, s4, v72
	s_nop 1
	v_addc_co_u32_e32 v31, vcc, 0, v73, vcc
	global_store_dwordx2 v[30:31], v[28:29], off
	v_lshlrev_b32_e32 v29, 16, v25
	v_lshlrev_b32_e32 v28, 16, v24
	v_and_b32_e32 v25, 0xffff0000, v25
	v_and_b32_e32 v24, 0xffff0000, v24
	v_pk_fma_f32 v[24:25], v[70:71], v[24:25], v[28:29]
	s_waitcnt vmcnt(0) lgkmcnt(0)
	v_lshlrev_b32_e32 v28, 16, v84
	v_mul_f32_e32 v30, 0x3d372713, v28
	v_mul_f32_e32 v30, v30, v28
	v_mov_b32_e32 v31, v28
	v_and_b32_e32 v29, 0xffff0000, v84
	v_fmac_f32_e32 v31, v30, v31
	v_mul_f32_e32 v30, 0x3f4c422a, v31
	v_mul_f32_e32 v31, 0x3d372713, v29
	v_mul_f32_e32 v31, v31, v29
	v_mov_b32_e32 v32, v29
	v_fmac_f32_e32 v32, v31, v32
	v_mul_f32_e32 v31, 0x3f4c422a, v32
	v_mul_f32_e32 v30, -2.0, v30
	v_mul_f32_e32 v31, -2.0, v31
	v_mul_f32_e32 v30, 0x3fb8aa3b, v30
	v_mul_f32_e32 v31, 0x3fb8aa3b, v31
	v_exp_f32_e32 v30, v30
	v_exp_f32_e32 v31, v31
	s_nop 0
	v_pk_add_f32 v[30:31], v[30:31], 1.0 op_sel_hi:[1,0]
	s_nop 0
	v_div_scale_f32 v32, s[4:5], v31, v31, 1.0
	v_rcp_f32_e32 v33, v32
	s_nop 0
	v_fma_f32 v34, -v32, v33, 1.0
	v_fmac_f32_e32 v33, v34, v33
	v_div_scale_f32 v34, vcc, 1.0, v31, 1.0
	v_mul_f32_e32 v35, v34, v33
	v_fma_f32 v36, -v32, v35, v34
	v_fmac_f32_e32 v35, v36, v33
	v_fma_f32 v32, -v32, v35, v34
	v_div_fmas_f32 v32, v32, v33, v35
	v_div_fixup_f32 v31, v32, v31, 1.0
	v_div_scale_f32 v32, s[4:5], v30, v30, 1.0
	v_rcp_f32_e32 v33, v32
	s_nop 0
	v_fma_f32 v34, -v32, v33, 1.0
	v_fmac_f32_e32 v33, v34, v33
	v_div_scale_f32 v34, vcc, 1.0, v30, 1.0
	v_mul_f32_e32 v35, v34, v33
	v_fma_f32 v36, -v32, v35, v34
	v_fmac_f32_e32 v35, v36, v33
	v_fma_f32 v32, -v32, v35, v34
	v_div_fmas_f32 v32, v32, v33, v35
	v_div_fixup_f32 v30, v32, v30, 1.0
	v_pk_mul_f32 v[28:29], v[30:31], v[28:29]
	s_nop 0
	v_pk_mul_f32 v[24:25], v[24:25], v[28:29]
	v_lshlrev_b32_e32 v29, 16, v27
	v_lshlrev_b32_e32 v28, 16, v26
	v_and_b32_e32 v27, 0xffff0000, v27
	v_and_b32_e32 v26, 0xffff0000, v26
	v_pk_fma_f32 v[26:27], v[68:69], v[26:27], v[28:29]
	v_lshlrev_b32_e32 v28, 16, v85
	v_cvt_pk_bf16_f32 v24, v24, v25
	v_mul_f32_e32 v25, 0x3d372713, v28
	v_mul_f32_e32 v25, v25, v28
	v_mov_b32_e32 v30, v28
	v_fmac_f32_e32 v30, v25, v30
	v_mul_f32_e32 v25, 0x3f4c422a, v30
	v_mul_f32_e32 v25, -2.0, v25
	v_and_b32_e32 v29, 0xffff0000, v85
	v_mul_f32_e32 v25, 0x3fb8aa3b, v25
	v_exp_f32_e32 v30, v25
	v_mul_f32_e32 v25, 0x3d372713, v29
	v_mul_f32_e32 v25, v25, v29
	v_mov_b32_e32 v31, v29
; DI float bflo(unsigned w) { return __uint_as_float(w << 16); }
; DI float bfhi(unsigned w) { return __uint_as_float(w & 0xffff0000u); }
; DI unsigned pk2(float a, float b) { f32x2 v = {a, b}; bf16v2 r = __builtin_convertvector(v, bf16v2); return __builtin_bit_cast(unsigned, r); }
; DI float gelu_tanh(float x) { const float u = 0.7978845608028654f * (x + 0.044715f * x * x * x); const float e = __expf(-2.0f * u); return x * (1.0f / (1.0f + e)); }
; DI void lru_fix_unit(const Ctx& c, int l, int chunk, int half) {
;     ...
;     for (int k = 0; k < 16; ++k) {
;         h[0] = bflo(hv[k].x) + bfhi(hv[k].x) * cr[0]; h[1] = bflo(hv[k].y) + bfhi(hv[k].y) * cr[1]; h[2] = bflo(hv[k].z) + bfhi(hv[k].z) * cr[2]; h[3] = bflo(hv[k].w) + bfhi(hv[k].w) * cr[3];
;         u32x2 w; w.x = pk2(h[0] * gelu_tanh(bflo(gv[k].x)), h[1] * gelu_tanh(bfhi(gv[k].x))); w.y = pk2(h[2] * gelu_tanh(bflo(gv[k].y)), h[3] * gelu_tanh(bfhi(gv[k].y)));
;         *(u32x2*)(br + (size_t)(4 * k) * 3072) = w;
;     }
	v_fmac_f32_e32 v31, v25, v31
	v_mul_f32_e32 v25, 0x3f4c422a, v31
	v_mul_f32_e32 v25, -2.0, v25
	v_mul_f32_e32 v25, 0x3fb8aa3b, v25
	v_exp_f32_e32 v31, v25
	s_nop 0
	v_pk_add_f32 v[30:31], v[30:31], 1.0 op_sel_hi:[1,0]
	s_nop 0
	v_div_scale_f32 v25, s[4:5], v31, v31, 1.0
	v_rcp_f32_e32 v32, v25
	s_nop 0
	v_fma_f32 v33, -v25, v32, 1.0
	v_fmac_f32_e32 v32, v33, v32
	v_div_scale_f32 v33, vcc, 1.0, v31, 1.0
	v_mul_f32_e32 v34, v33, v32
	v_fma_f32 v35, -v25, v34, v33
	v_fmac_f32_e32 v34, v35, v32
	v_fma_f32 v25, -v25, v34, v33
	v_div_fmas_f32 v25, v25, v32, v34
	v_div_fixup_f32 v31, v25, v31, 1.0
	v_div_scale_f32 v25, s[4:5], v30, v30, 1.0
	v_rcp_f32_e32 v32, v25
	s_mov_b32 s4, 0x45892000
	v_fma_f32 v33, -v25, v32, 1.0
	v_fmac_f32_e32 v32, v33, v32
	v_div_scale_f32 v33, vcc, 1.0, v30, 1.0
	v_mul_f32_e32 v34, v33, v32
	v_fma_f32 v35, -v25, v34, v33
	v_fmac_f32_e32 v34, v35, v32
	v_fma_f32 v25, -v25, v34, v33
	v_div_fmas_f32 v25, v25, v32, v34
	v_div_fixup_f32 v30, v25, v30, 1.0
	v_pk_mul_f32 v[28:29], v[30:31], v[28:29]
	s_nop 0
	v_pk_mul_f32 v[26:27], v[26:27], v[28:29]
	s_nop 0
	v_cvt_pk_bf16_f32 v25, v26, v27
	v_add_co_u32_e32 v26, vcc, s4, v72
	s_nop 1
	v_addc_co_u32_e32 v27, vcc, 0, v73, vcc
	global_store_dwordx2 v[26:27], v[24:25], off
	v_lshlrev_b32_e32 v25, 16, v21
	v_lshlrev_b32_e32 v24, 16, v20
	v_and_b32_e32 v21, 0xffff0000, v21
	v_and_b32_e32 v20, 0xffff0000, v20
	v_pk_fma_f32 v[20:21], v[70:71], v[20:21], v[24:25]
	v_lshlrev_b32_e32 v24, 16, v82
	v_mul_f32_e32 v26, 0x3d372713, v24
	v_mul_f32_e32 v26, v26, v24
	v_mov_b32_e32 v27, v24
	v_and_b32_e32 v25, 0xffff0000, v82
	v_fmac_f32_e32 v27, v26, v27
	v_mul_f32_e32 v26, 0x3f4c422a, v27
	v_mul_f32_e32 v27, 0x3d372713, v25
	v_mul_f32_e32 v27, v27, v25
	v_mov_b32_e32 v28, v25
	v_fmac_f32_e32 v28, v27, v28
	v_mul_f32_e32 v27, 0x3f4c422a, v28
	v_mul_f32_e32 v26, -2.0, v26
	v_mul_f32_e32 v27, -2.0, v27
	v_mul_f32_e32 v26, 0x3fb8aa3b, v26
	v_mul_f32_e32 v27, 0x3fb8aa3b, v27
	v_exp_f32_e32 v26, v26
	v_exp_f32_e32 v27, v27
	s_nop 0
	v_pk_add_f32 v[26:27], v[26:27], 1.0 op_sel_hi:[1,0]
	s_nop 0
	v_div_scale_f32 v28, s[4:5], v27, v27, 1.0
	v_rcp_f32_e32 v29, v28
	s_nop 0
	v_fma_f32 v30, -v28, v29, 1.0
	v_fmac_f32_e32 v29, v30, v29
	v_div_scale_f32 v30, vcc, 1.0, v27, 1.0
	v_mul_f32_e32 v31, v30, v29
	v_fma_f32 v32, -v28, v31, v30
	v_fmac_f32_e32 v31, v32, v29
	v_fma_f32 v28, -v28, v31, v30
	v_div_fmas_f32 v28, v28, v29, v31
	v_div_fixup_f32 v27, v28, v27, 1.0
	v_div_scale_f32 v28, s[4:5], v26, v26, 1.0
	v_rcp_f32_e32 v29, v28
	s_nop 0
	v_fma_f32 v30, -v28, v29, 1.0
	v_fmac_f32_e32 v29, v30, v29
	v_div_scale_f32 v30, vcc, 1.0, v26, 1.0
	v_mul_f32_e32 v31, v30, v29
	v_fma_f32 v32, -v28, v31, v30
	v_fmac_f32_e32 v31, v32, v29
	v_fma_f32 v28, -v28, v31, v30
	v_div_fmas_f32 v28, v28, v29, v31
	v_div_fixup_f32 v26, v28, v26, 1.0
	v_pk_mul_f32 v[24:25], v[26:27], v[24:25]
	s_nop 0
	v_pk_mul_f32 v[20:21], v[20:21], v[24:25]
	v_lshlrev_b32_e32 v25, 16, v23
	v_lshlrev_b32_e32 v24, 16, v22
	v_and_b32_e32 v23, 0xffff0000, v23
	v_and_b32_e32 v22, 0xffff0000, v22
	v_pk_fma_f32 v[22:23], v[68:69], v[22:23], v[24:25]
	v_lshlrev_b32_e32 v24, 16, v83
	v_cvt_pk_bf16_f32 v20, v20, v21
	v_mul_f32_e32 v21, 0x3d372713, v24
	v_mul_f32_e32 v21, v21, v24
	v_mov_b32_e32 v26, v24
	v_fmac_f32_e32 v26, v21, v26
	v_mul_f32_e32 v21, 0x3f4c422a, v26
	v_mul_f32_e32 v21, -2.0, v21
	v_and_b32_e32 v25, 0xffff0000, v83
	v_mul_f32_e32 v21, 0x3fb8aa3b, v21
	v_exp_f32_e32 v26, v21
	v_mul_f32_e32 v21, 0x3d372713, v25
	v_mul_f32_e32 v21, v21, v25
	v_mov_b32_e32 v27, v25
	v_fmac_f32_e32 v27, v21, v27
	v_mul_f32_e32 v21, 0x3f4c422a, v27
	v_mul_f32_e32 v21, -2.0, v21
	v_mul_f32_e32 v21, 0x3fb8aa3b, v21
	v_exp_f32_e32 v27, v21
	s_nop 0
	v_pk_add_f32 v[26:27], v[26:27], 1.0 op_sel_hi:[1,0]
	s_nop 0
	v_div_scale_f32 v21, s[4:5], v27, v27, 1.0
	v_rcp_f32_e32 v28, v21
	s_nop 0
	v_fma_f32 v29, -v21, v28, 1.0
	v_fmac_f32_e32 v28, v29, v28
	v_div_scale_f32 v29, vcc, 1.0, v27, 1.0
	v_mul_f32_e32 v30, v29, v28
	v_fma_f32 v31, -v21, v30, v29
	v_fmac_f32_e32 v30, v31, v28
	v_fma_f32 v21, -v21, v30, v29
	v_div_fmas_f32 v21, v21, v28, v30
	v_div_fixup_f32 v27, v21, v27, 1.0
	v_div_scale_f32 v21, s[4:5], v26, v26, 1.0
	v_rcp_f32_e32 v28, v21
	s_mov_b32 s4, 0x45898000
	v_fma_f32 v29, -v21, v28, 1.0
	v_fmac_f32_e32 v28, v29, v28
	v_div_scale_f32 v29, vcc, 1.0, v26, 1.0
	v_mul_f32_e32 v30, v29, v28
	v_fma_f32 v31, -v21, v30, v29
	v_fmac_f32_e32 v30, v31, v28
	v_fma_f32 v21, -v21, v30, v29
	v_div_fmas_f32 v21, v21, v28, v30
	v_div_fixup_f32 v26, v21, v26, 1.0
	v_pk_mul_f32 v[24:25], v[26:27], v[24:25]
	s_nop 0
	v_pk_mul_f32 v[22:23], v[22:23], v[24:25]
	s_nop 0
	v_cvt_pk_bf16_f32 v21, v22, v23
	v_add_co_u32_e32 v22, vcc, s4, v72
	s_nop 1
	v_addc_co_u32_e32 v23, vcc, 0, v73, vcc
	global_store_dwordx2 v[22:23], v[20:21], off
	v_lshlrev_b32_e32 v21, 16, v17
	v_lshlrev_b32_e32 v20, 16, v16
	v_and_b32_e32 v17, 0xffff0000, v17
	v_and_b32_e32 v16, 0xffff0000, v16
	v_pk_fma_f32 v[16:17], v[70:71], v[16:17], v[20:21]
	v_lshlrev_b32_e32 v20, 16, v80
	v_mul_f32_e32 v22, 0x3d372713, v20
	v_mul_f32_e32 v22, v22, v20
	v_mov_b32_e32 v23, v20
	v_and_b32_e32 v21, 0xffff0000, v80
	v_fmac_f32_e32 v23, v22, v23
	v_mul_f32_e32 v22, 0x3f4c422a, v23
	v_mul_f32_e32 v23, 0x3d372713, v21
	v_mul_f32_e32 v23, v23, v21
	v_mov_b32_e32 v24, v21
	v_fmac_f32_e32 v24, v23, v24
	v_mul_f32_e32 v23, 0x3f4c422a, v24
	v_mul_f32_e32 v22, -2.0, v22
	v_mul_f32_e32 v23, -2.0, v23
	v_mul_f32_e32 v22, 0x3fb8aa3b, v22
	v_mul_f32_e32 v23, 0x3fb8aa3b, v23
	v_exp_f32_e32 v22, v22
	v_exp_f32_e32 v23, v23
	s_nop 0
	v_pk_add_f32 v[22:23], v[22:23], 1.0 op_sel_hi:[1,0]
	s_nop 0
	v_div_scale_f32 v24, s[4:5], v23, v23, 1.0
; DI float bflo(unsigned w) { return __uint_as_float(w << 16); }
; DI float bfhi(unsigned w) { return __uint_as_float(w & 0xffff0000u); }
; DI unsigned pk2(float a, float b) { f32x2 v = {a, b}; bf16v2 r = __builtin_convertvector(v, bf16v2); return __builtin_bit_cast(unsigned, r); }
; DI float gelu_tanh(float x) { const float u = 0.7978845608028654f * (x + 0.044715f * x * x * x); const float e = __expf(-2.0f * u); return x * (1.0f / (1.0f + e)); }
; DI void lru_fix_unit(const Ctx& c, int l, int chunk, int half) {
;     ...
;     for (int k = 0; k < 16; ++k) {
;         h[0] = bflo(hv[k].x) + bfhi(hv[k].x) * cr[0]; h[1] = bflo(hv[k].y) + bfhi(hv[k].y) * cr[1]; h[2] = bflo(hv[k].z) + bfhi(hv[k].z) * cr[2]; h[3] = bflo(hv[k].w) + bfhi(hv[k].w) * cr[3];
;         u32x2 w; w.x = pk2(h[0] * gelu_tanh(bflo(gv[k].x)), h[1] * gelu_tanh(bfhi(gv[k].x))); w.y = pk2(h[2] * gelu_tanh(bflo(gv[k].y)), h[3] * gelu_tanh(bfhi(gv[k].y)));
;         *(u32x2*)(br + (size_t)(4 * k) * 3072) = w;
;     }
	v_rcp_f32_e32 v25, v24
	s_nop 0
	v_fma_f32 v26, -v24, v25, 1.0
	v_fmac_f32_e32 v25, v26, v25
	v_div_scale_f32 v26, vcc, 1.0, v23, 1.0
	v_mul_f32_e32 v27, v26, v25
	v_fma_f32 v28, -v24, v27, v26
	v_fmac_f32_e32 v27, v28, v25
	v_fma_f32 v24, -v24, v27, v26
	v_div_fmas_f32 v24, v24, v25, v27
	v_div_fixup_f32 v23, v24, v23, 1.0
	v_div_scale_f32 v24, s[4:5], v22, v22, 1.0
	v_rcp_f32_e32 v25, v24
	s_nop 0
	v_fma_f32 v26, -v24, v25, 1.0
	v_fmac_f32_e32 v25, v26, v25
	v_div_scale_f32 v26, vcc, 1.0, v22, 1.0
	v_mul_f32_e32 v27, v26, v25
	v_fma_f32 v28, -v24, v27, v26
	v_fmac_f32_e32 v27, v28, v25
	v_fma_f32 v24, -v24, v27, v26
	v_div_fmas_f32 v24, v24, v25, v27
	v_div_fixup_f32 v22, v24, v22, 1.0
	v_pk_mul_f32 v[20:21], v[22:23], v[20:21]
	s_nop 0
	v_pk_mul_f32 v[16:17], v[16:17], v[20:21]
	v_lshlrev_b32_e32 v21, 16, v19
	v_lshlrev_b32_e32 v20, 16, v18
	v_and_b32_e32 v19, 0xffff0000, v19
	v_and_b32_e32 v18, 0xffff0000, v18
	v_pk_fma_f32 v[18:19], v[68:69], v[18:19], v[20:21]
	v_lshlrev_b32_e32 v20, 16, v81
	v_cvt_pk_bf16_f32 v16, v16, v17
	v_mul_f32_e32 v17, 0x3d372713, v20
	v_mul_f32_e32 v17, v17, v20
	v_mov_b32_e32 v22, v20
	v_fmac_f32_e32 v22, v17, v22
	v_mul_f32_e32 v17, 0x3f4c422a, v22
	v_mul_f32_e32 v17, -2.0, v17
	v_and_b32_e32 v21, 0xffff0000, v81
	v_mul_f32_e32 v17, 0x3fb8aa3b, v17
	v_exp_f32_e32 v22, v17
	v_mul_f32_e32 v17, 0x3d372713, v21
	v_mul_f32_e32 v17, v17, v21
	v_mov_b32_e32 v23, v21
	v_fmac_f32_e32 v23, v17, v23
	v_mul_f32_e32 v17, 0x3f4c422a, v23
	v_mul_f32_e32 v17, -2.0, v17
	v_mul_f32_e32 v17, 0x3fb8aa3b, v17
	v_exp_f32_e32 v23, v17
	s_nop 0
	v_pk_add_f32 v[22:23], v[22:23], 1.0 op_sel_hi:[1,0]
	s_nop 0
	v_div_scale_f32 v17, s[4:5], v23, v23, 1.0
	v_rcp_f32_e32 v24, v17
	s_nop 0
	v_fma_f32 v25, -v17, v24, 1.0
	v_fmac_f32_e32 v24, v25, v24
	v_div_scale_f32 v25, vcc, 1.0, v23, 1.0
	v_mul_f32_e32 v26, v25, v24
	v_fma_f32 v27, -v17, v26, v25
	v_fmac_f32_e32 v26, v27, v24
	v_fma_f32 v17, -v17, v26, v25
	v_div_fmas_f32 v17, v17, v24, v26
	v_div_fixup_f32 v23, v17, v23, 1.0
	v_div_scale_f32 v17, s[4:5], v22, v22, 1.0
	v_rcp_f32_e32 v24, v17
	s_mov_b32 s4, 0x4589e000
	v_fma_f32 v25, -v17, v24, 1.0
	v_fmac_f32_e32 v24, v25, v24
	v_div_scale_f32 v25, vcc, 1.0, v22, 1.0
	v_mul_f32_e32 v26, v25, v24
	v_fma_f32 v27, -v17, v26, v25
	v_fmac_f32_e32 v26, v27, v24
	v_fma_f32 v17, -v17, v26, v25
	v_div_fmas_f32 v17, v17, v24, v26
	v_div_fixup_f32 v22, v17, v22, 1.0
	v_pk_mul_f32 v[20:21], v[22:23], v[20:21]
	s_nop 0
	v_pk_mul_f32 v[18:19], v[18:19], v[20:21]
	s_nop 0
	v_cvt_pk_bf16_f32 v17, v18, v19
	v_add_co_u32_e32 v18, vcc, s4, v72
	s_nop 1
	v_addc_co_u32_e32 v19, vcc, 0, v73, vcc
	global_store_dwordx2 v[18:19], v[16:17], off
	v_lshlrev_b32_e32 v17, 16, v13
	v_lshlrev_b32_e32 v16, 16, v12
	v_and_b32_e32 v13, 0xffff0000, v13
	v_and_b32_e32 v12, 0xffff0000, v12
	v_pk_fma_f32 v[12:13], v[70:71], v[12:13], v[16:17]
	v_lshlrev_b32_e32 v16, 16, v78
	v_mul_f32_e32 v18, 0x3d372713, v16
	v_mul_f32_e32 v18, v18, v16
	v_mov_b32_e32 v19, v16
	v_and_b32_e32 v17, 0xffff0000, v78
	v_fmac_f32_e32 v19, v18, v19
	v_mul_f32_e32 v18, 0x3f4c422a, v19
	v_mul_f32_e32 v19, 0x3d372713, v17
	v_mul_f32_e32 v19, v19, v17
	v_mov_b32_e32 v20, v17
	v_fmac_f32_e32 v20, v19, v20
	v_mul_f32_e32 v19, 0x3f4c422a, v20
	v_mul_f32_e32 v18, -2.0, v18
	v_mul_f32_e32 v19, -2.0, v19
	v_mul_f32_e32 v18, 0x3fb8aa3b, v18
	v_mul_f32_e32 v19, 0x3fb8aa3b, v19
	v_exp_f32_e32 v18, v18
	v_exp_f32_e32 v19, v19
	s_nop 0
	v_pk_add_f32 v[18:19], v[18:19], 1.0 op_sel_hi:[1,0]
	s_nop 0
	v_div_scale_f32 v20, s[4:5], v19, v19, 1.0
	v_rcp_f32_e32 v21, v20
	s_nop 0
	v_fma_f32 v22, -v20, v21, 1.0
	v_fmac_f32_e32 v21, v22, v21
	v_div_scale_f32 v22, vcc, 1.0, v19, 1.0
	v_mul_f32_e32 v23, v22, v21
	v_fma_f32 v24, -v20, v23, v22
	v_fmac_f32_e32 v23, v24, v21
	v_fma_f32 v20, -v20, v23, v22
	v_div_fmas_f32 v20, v20, v21, v23
	v_div_fixup_f32 v19, v20, v19, 1.0
	v_div_scale_f32 v20, s[4:5], v18, v18, 1.0
	v_rcp_f32_e32 v21, v20
	s_nop 0
	v_fma_f32 v22, -v20, v21, 1.0
	v_fmac_f32_e32 v21, v22, v21
	v_div_scale_f32 v22, vcc, 1.0, v18, 1.0
	v_mul_f32_e32 v23, v22, v21
	v_fma_f32 v24, -v20, v23, v22
	v_fmac_f32_e32 v23, v24, v21
	v_fma_f32 v20, -v20, v23, v22
	v_div_fmas_f32 v20, v20, v21, v23
	v_div_fixup_f32 v18, v20, v18, 1.0
	v_pk_mul_f32 v[16:17], v[18:19], v[16:17]
	s_nop 0
	v_pk_mul_f32 v[12:13], v[12:13], v[16:17]
	v_lshlrev_b32_e32 v17, 16, v15
	v_lshlrev_b32_e32 v16, 16, v14
	v_and_b32_e32 v15, 0xffff0000, v15
	v_and_b32_e32 v14, 0xffff0000, v14
	v_pk_fma_f32 v[14:15], v[68:69], v[14:15], v[16:17]
	v_lshlrev_b32_e32 v16, 16, v79
	v_cvt_pk_bf16_f32 v12, v12, v13
	v_mul_f32_e32 v13, 0x3d372713, v16
	v_mul_f32_e32 v13, v13, v16
	v_mov_b32_e32 v18, v16
	v_fmac_f32_e32 v18, v13, v18
	v_mul_f32_e32 v13, 0x3f4c422a, v18
	v_mul_f32_e32 v13, -2.0, v13
	v_and_b32_e32 v17, 0xffff0000, v79
	v_mul_f32_e32 v13, 0x3fb8aa3b, v13
	v_exp_f32_e32 v18, v13
	v_mul_f32_e32 v13, 0x3d372713, v17
	v_mul_f32_e32 v13, v13, v17
	v_mov_b32_e32 v19, v17
	v_fmac_f32_e32 v19, v13, v19
	v_mul_f32_e32 v13, 0x3f4c422a, v19
	v_mul_f32_e32 v13, -2.0, v13
	v_mul_f32_e32 v13, 0x3fb8aa3b, v13
	v_exp_f32_e32 v19, v13
	s_nop 0
	v_pk_add_f32 v[18:19], v[18:19], 1.0 op_sel_hi:[1,0]
	s_nop 0
	v_div_scale_f32 v13, s[4:5], v19, v19, 1.0
	v_rcp_f32_e32 v20, v13
	s_nop 0
	v_fma_f32 v21, -v13, v20, 1.0
	v_fmac_f32_e32 v20, v21, v20
	v_div_scale_f32 v21, vcc, 1.0, v19, 1.0
	v_mul_f32_e32 v22, v21, v20
	v_fma_f32 v23, -v13, v22, v21
	v_fmac_f32_e32 v22, v23, v20
	v_fma_f32 v13, -v13, v22, v21
	v_div_fmas_f32 v13, v13, v20, v22
	v_div_fixup_f32 v19, v13, v19, 1.0
	v_div_scale_f32 v13, s[4:5], v18, v18, 1.0
	v_rcp_f32_e32 v20, v13
	s_mov_b32 s4, 0x458a4000
; DI float bflo(unsigned w) { return __uint_as_float(w << 16); }
; DI float bfhi(unsigned w) { return __uint_as_float(w & 0xffff0000u); }
; DI unsigned pk2(float a, float b) { f32x2 v = {a, b}; bf16v2 r = __builtin_convertvector(v, bf16v2); return __builtin_bit_cast(unsigned, r); }
; DI float gelu_tanh(float x) { const float u = 0.7978845608028654f * (x + 0.044715f * x * x * x); const float e = __expf(-2.0f * u); return x * (1.0f / (1.0f + e)); }
; DI void lru_fix_unit(const Ctx& c, int l, int chunk, int half) {
;     ...
;     for (int k = 0; k < 16; ++k) {
;         h[0] = bflo(hv[k].x) + bfhi(hv[k].x) * cr[0]; h[1] = bflo(hv[k].y) + bfhi(hv[k].y) * cr[1]; h[2] = bflo(hv[k].z) + bfhi(hv[k].z) * cr[2]; h[3] = bflo(hv[k].w) + bfhi(hv[k].w) * cr[3];
;         u32x2 w; w.x = pk2(h[0] * gelu_tanh(bflo(gv[k].x)), h[1] * gelu_tanh(bfhi(gv[k].x))); w.y = pk2(h[2] * gelu_tanh(bflo(gv[k].y)), h[3] * gelu_tanh(bfhi(gv[k].y)));
;         *(u32x2*)(br + (size_t)(4 * k) * 3072) = w;
;     }
	v_fma_f32 v21, -v13, v20, 1.0
	v_fmac_f32_e32 v20, v21, v20
	v_div_scale_f32 v21, vcc, 1.0, v18, 1.0
	v_mul_f32_e32 v22, v21, v20
	v_fma_f32 v23, -v13, v22, v21
	v_fmac_f32_e32 v22, v23, v20
	v_fma_f32 v13, -v13, v22, v21
	v_div_fmas_f32 v13, v13, v20, v22
	v_div_fixup_f32 v18, v13, v18, 1.0
	v_pk_mul_f32 v[16:17], v[18:19], v[16:17]
	s_nop 0
	v_pk_mul_f32 v[14:15], v[14:15], v[16:17]
	s_nop 0
	v_cvt_pk_bf16_f32 v13, v14, v15
	v_add_co_u32_e32 v14, vcc, s4, v72
	s_nop 1
	v_addc_co_u32_e32 v15, vcc, 0, v73, vcc
	global_store_dwordx2 v[14:15], v[12:13], off
	v_lshlrev_b32_e32 v13, 16, v9
	v_lshlrev_b32_e32 v12, 16, v8
	v_and_b32_e32 v9, 0xffff0000, v9
	v_and_b32_e32 v8, 0xffff0000, v8
	v_pk_fma_f32 v[8:9], v[70:71], v[8:9], v[12:13]
	v_lshlrev_b32_e32 v12, 16, v76
	v_mul_f32_e32 v14, 0x3d372713, v12
	v_mul_f32_e32 v14, v14, v12
	v_mov_b32_e32 v15, v12
	v_and_b32_e32 v13, 0xffff0000, v76
	v_fmac_f32_e32 v15, v14, v15
	v_mul_f32_e32 v14, 0x3f4c422a, v15
	v_mul_f32_e32 v15, 0x3d372713, v13
	v_mul_f32_e32 v15, v15, v13
	v_mov_b32_e32 v16, v13
	v_fmac_f32_e32 v16, v15, v16
	v_mul_f32_e32 v15, 0x3f4c422a, v16
	v_mul_f32_e32 v14, -2.0, v14
	v_mul_f32_e32 v15, -2.0, v15
	v_mul_f32_e32 v14, 0x3fb8aa3b, v14
	v_mul_f32_e32 v15, 0x3fb8aa3b, v15
	v_exp_f32_e32 v14, v14
	v_exp_f32_e32 v15, v15
	s_nop 0
	v_pk_add_f32 v[14:15], v[14:15], 1.0 op_sel_hi:[1,0]
	s_nop 0
	v_div_scale_f32 v16, s[4:5], v15, v15, 1.0
	v_rcp_f32_e32 v17, v16
	s_nop 0
	v_fma_f32 v18, -v16, v17, 1.0
	v_fmac_f32_e32 v17, v18, v17
	v_div_scale_f32 v18, vcc, 1.0, v15, 1.0
	v_mul_f32_e32 v19, v18, v17
	v_fma_f32 v20, -v16, v19, v18
	v_fmac_f32_e32 v19, v20, v17
	v_fma_f32 v16, -v16, v19, v18
	v_div_fmas_f32 v16, v16, v17, v19
	v_div_fixup_f32 v15, v16, v15, 1.0
	v_div_scale_f32 v16, s[4:5], v14, v14, 1.0
	v_rcp_f32_e32 v17, v16
	s_nop 0
	v_fma_f32 v18, -v16, v17, 1.0
	v_fmac_f32_e32 v17, v18, v17
	v_div_scale_f32 v18, vcc, 1.0, v14, 1.0
	v_mul_f32_e32 v19, v18, v17
	v_fma_f32 v20, -v16, v19, v18
	v_fmac_f32_e32 v19, v20, v17
	v_fma_f32 v16, -v16, v19, v18
	v_div_fmas_f32 v16, v16, v17, v19
	v_div_fixup_f32 v14, v16, v14, 1.0
	v_pk_mul_f32 v[12:13], v[14:15], v[12:13]
	s_nop 0
	v_pk_mul_f32 v[8:9], v[8:9], v[12:13]
	v_lshlrev_b32_e32 v13, 16, v11
	v_lshlrev_b32_e32 v12, 16, v10
	v_and_b32_e32 v11, 0xffff0000, v11
	v_and_b32_e32 v10, 0xffff0000, v10
	v_pk_fma_f32 v[10:11], v[68:69], v[10:11], v[12:13]
	v_lshlrev_b32_e32 v12, 16, v77
	v_cvt_pk_bf16_f32 v8, v8, v9
	v_mul_f32_e32 v9, 0x3d372713, v12
	v_mul_f32_e32 v9, v9, v12
	v_mov_b32_e32 v14, v12
	v_fmac_f32_e32 v14, v9, v14
	v_mul_f32_e32 v9, 0x3f4c422a, v14
	v_mul_f32_e32 v9, -2.0, v9
	v_and_b32_e32 v13, 0xffff0000, v77
	v_mul_f32_e32 v9, 0x3fb8aa3b, v9
	v_exp_f32_e32 v14, v9
	v_mul_f32_e32 v9, 0x3d372713, v13
	v_mul_f32_e32 v9, v9, v13
	v_mov_b32_e32 v15, v13
	v_fmac_f32_e32 v15, v9, v15
	v_mul_f32_e32 v9, 0x3f4c422a, v15
	v_mul_f32_e32 v9, -2.0, v9
	v_mul_f32_e32 v9, 0x3fb8aa3b, v9
	v_exp_f32_e32 v15, v9
	s_nop 0
	v_pk_add_f32 v[14:15], v[14:15], 1.0 op_sel_hi:[1,0]
	s_nop 0
	v_div_scale_f32 v9, s[4:5], v15, v15, 1.0
	v_rcp_f32_e32 v16, v9
	s_nop 0
	v_fma_f32 v17, -v9, v16, 1.0
	v_fmac_f32_e32 v16, v17, v16
	v_div_scale_f32 v17, vcc, 1.0, v15, 1.0
	v_mul_f32_e32 v18, v17, v16
	v_fma_f32 v19, -v9, v18, v17
	v_fmac_f32_e32 v18, v19, v16
	v_fma_f32 v9, -v9, v18, v17
	v_div_fmas_f32 v9, v9, v16, v18
	v_div_fixup_f32 v15, v9, v15, 1.0
	v_div_scale_f32 v9, s[4:5], v14, v14, 1.0
	v_rcp_f32_e32 v16, v9
	s_mov_b32 s4, 0x458aa000
	v_fma_f32 v17, -v9, v16, 1.0
	v_fmac_f32_e32 v16, v17, v16
	v_div_scale_f32 v17, vcc, 1.0, v14, 1.0
	v_mul_f32_e32 v18, v17, v16
	v_fma_f32 v19, -v9, v18, v17
	v_fmac_f32_e32 v18, v19, v16
	v_fma_f32 v9, -v9, v18, v17
	v_div_fmas_f32 v9, v9, v16, v18
	v_div_fixup_f32 v14, v9, v14, 1.0
	v_pk_mul_f32 v[12:13], v[14:15], v[12:13]
	s_nop 0
	v_pk_mul_f32 v[10:11], v[10:11], v[12:13]
; DI float* kout() { return (float*)karg64<200>(); }
; DI float bflo(unsigned w) { return __uint_as_float(w << 16); }
; DI float bfhi(unsigned w) { return __uint_as_float(w & 0xffff0000u); }
; DI unsigned pk2(float a, float b) { f32x2 v = {a, b}; bf16v2 r = __builtin_convertvector(v, bf16v2); return __builtin_bit_cast(unsigned, r); }
; DI float gelu_tanh(float x) { const float u = 0.7978845608028654f * (x + 0.044715f * x * x * x); const float e = __expf(-2.0f * u); return x * (1.0f / (1.0f + e)); }
; DI void lru_fix_unit(const Ctx& c, int l, int chunk, int half) {
;     ...
;     for (int k = 0; k < 16; ++k) {
;         h[0] = bflo(hv[k].x) + bfhi(hv[k].x) * cr[0]; h[1] = bflo(hv[k].y) + bfhi(hv[k].y) * cr[1]; h[2] = bflo(hv[k].z) + bfhi(hv[k].z) * cr[2]; h[3] = bflo(hv[k].w) + bfhi(hv[k].w) * cr[3];
;         u32x2 w; w.x = pk2(h[0] * gelu_tanh(bflo(gv[k].x)), h[1] * gelu_tanh(bfhi(gv[k].x))); w.y = pk2(h[2] * gelu_tanh(bflo(gv[k].y)), h[3] * gelu_tanh(bfhi(gv[k].y)));
;         *(u32x2*)(br + (size_t)(4 * k) * 3072) = w;
;     }
;     if (tq == 3) {
;         if (smp) *(f32x4*)(kout() + O_SLRU + ((size_t)l * 32 + (chunk - 256)) * 1024 + ch) = h;
;         else if (n == 127) *(f32x4*)(kout() + O_PLRU + ((size_t)l * 2 + (chunk >> 7)) * 1024 + ch) = h;
	s_nop 0
	v_cvt_pk_bf16_f32 v9, v10, v11
	v_add_co_u32_e32 v10, vcc, s4, v72
	s_nop 1
	v_addc_co_u32_e32 v11, vcc, 0, v73, vcc
	global_store_dwordx2 v[10:11], v[8:9], off
	v_lshlrev_b32_e32 v9, 16, v5
	v_lshlrev_b32_e32 v8, 16, v4
	v_and_b32_e32 v5, 0xffff0000, v5
	v_and_b32_e32 v4, 0xffff0000, v4
	v_pk_fma_f32 v[4:5], v[70:71], v[4:5], v[8:9]
	v_lshlrev_b32_e32 v8, 16, v74
	v_mul_f32_e32 v10, 0x3d372713, v8
	v_mul_f32_e32 v10, v10, v8
	v_mov_b32_e32 v11, v8
	v_and_b32_e32 v9, 0xffff0000, v74
	v_fmac_f32_e32 v11, v10, v11
	v_mul_f32_e32 v10, 0x3f4c422a, v11
	v_mul_f32_e32 v11, 0x3d372713, v9
	v_mul_f32_e32 v11, v11, v9
	v_mov_b32_e32 v12, v9
	v_fmac_f32_e32 v12, v11, v12
	v_mul_f32_e32 v11, 0x3f4c422a, v12
	v_mul_f32_e32 v10, -2.0, v10
	v_mul_f32_e32 v11, -2.0, v11
	v_mul_f32_e32 v10, 0x3fb8aa3b, v10
	v_mul_f32_e32 v11, 0x3fb8aa3b, v11
	v_exp_f32_e32 v10, v10
	v_exp_f32_e32 v11, v11
	s_nop 0
	v_pk_add_f32 v[10:11], v[10:11], 1.0 op_sel_hi:[1,0]
	s_nop 0
	v_div_scale_f32 v12, s[4:5], v11, v11, 1.0
	v_rcp_f32_e32 v13, v12
	s_nop 0
	v_fma_f32 v14, -v12, v13, 1.0
	v_fmac_f32_e32 v13, v14, v13
	v_div_scale_f32 v14, vcc, 1.0, v11, 1.0
	v_mul_f32_e32 v15, v14, v13
	v_fma_f32 v16, -v12, v15, v14
	v_fmac_f32_e32 v15, v16, v13
	v_fma_f32 v12, -v12, v15, v14
	v_div_fmas_f32 v12, v12, v13, v15
	v_div_fixup_f32 v11, v12, v11, 1.0
	v_div_scale_f32 v12, s[4:5], v10, v10, 1.0
	v_rcp_f32_e32 v13, v12
	s_nop 0
	v_fma_f32 v14, -v12, v13, 1.0
	v_fmac_f32_e32 v13, v14, v13
	v_div_scale_f32 v14, vcc, 1.0, v10, 1.0
	v_mul_f32_e32 v15, v14, v13
	v_fma_f32 v16, -v12, v15, v14
	v_fmac_f32_e32 v15, v16, v13
	v_fma_f32 v12, -v12, v15, v14
	v_div_fmas_f32 v12, v12, v13, v15
	v_div_fixup_f32 v10, v12, v10, 1.0
	v_pk_mul_f32 v[8:9], v[10:11], v[8:9]
	v_lshlrev_b32_e32 v11, 16, v7
	v_lshlrev_b32_e32 v10, 16, v6
	v_and_b32_e32 v7, 0xffff0000, v7
	v_and_b32_e32 v6, 0xffff0000, v6
	v_pk_mul_f32 v[8:9], v[4:5], v[8:9]
	v_pk_fma_f32 v[6:7], v[68:69], v[6:7], v[10:11]
	v_lshlrev_b32_e32 v10, 16, v75
	v_cvt_pk_bf16_f32 v8, v8, v9
	v_mul_f32_e32 v9, 0x3d372713, v10
	v_mul_f32_e32 v9, v9, v10
	v_mov_b32_e32 v12, v10
	v_fmac_f32_e32 v12, v9, v12
	v_mul_f32_e32 v9, 0x3f4c422a, v12
	v_mul_f32_e32 v9, -2.0, v9
	v_and_b32_e32 v11, 0xffff0000, v75
	v_mul_f32_e32 v9, 0x3fb8aa3b, v9
	v_exp_f32_e32 v12, v9
	v_mul_f32_e32 v9, 0x3d372713, v11
	v_mul_f32_e32 v9, v9, v11
	v_mov_b32_e32 v13, v11
	v_fmac_f32_e32 v13, v9, v13
	v_mul_f32_e32 v9, 0x3f4c422a, v13
	v_mul_f32_e32 v9, -2.0, v9
	v_mul_f32_e32 v9, 0x3fb8aa3b, v9
	v_exp_f32_e32 v13, v9
	s_nop 0
	v_pk_add_f32 v[12:13], v[12:13], 1.0 op_sel_hi:[1,0]
	s_nop 0
	v_div_scale_f32 v9, s[4:5], v13, v13, 1.0
	v_rcp_f32_e32 v14, v9
	s_nop 0
	v_fma_f32 v15, -v9, v14, 1.0
	v_fmac_f32_e32 v14, v15, v14
	v_div_scale_f32 v15, vcc, 1.0, v13, 1.0
	v_mul_f32_e32 v16, v15, v14
	v_fma_f32 v17, -v9, v16, v15
	v_fmac_f32_e32 v16, v17, v14
	v_fma_f32 v9, -v9, v16, v15
	v_div_fmas_f32 v9, v9, v14, v16
	v_div_fixup_f32 v13, v9, v13, 1.0
	v_div_scale_f32 v9, s[4:5], v12, v12, 1.0
	v_rcp_f32_e32 v14, v9
	s_nop 0
	v_fma_f32 v15, -v9, v14, 1.0
	v_fmac_f32_e32 v14, v15, v14
	v_div_scale_f32 v15, vcc, 1.0, v12, 1.0
	v_mul_f32_e32 v16, v15, v14
	v_fma_f32 v17, -v9, v16, v15
	v_fmac_f32_e32 v16, v17, v14
	v_fma_f32 v9, -v9, v16, v15
	v_div_fmas_f32 v9, v9, v14, v16
	v_div_fixup_f32 v12, v9, v12, 1.0
	v_pk_mul_f32 v[10:11], v[12:13], v[10:11]
	s_nop 0
	v_pk_mul_f32 v[10:11], v[6:7], v[10:11]
	s_nop 0
	v_cvt_pk_bf16_f32 v9, v10, v11
	v_add_co_u32_e32 v10, vcc, 0x458b0000, v72
	s_nop 1
	v_addc_co_u32_e32 v11, vcc, 0, v73, vcc
	global_store_dwordx2 v[10:11], v[8:9], off
	s_and_saveexec_b64 s[4:5], s[40:41]
	s_cbranch_execz .LBB0_782
	s_cmpk_lt_i32 s42, 0x100
	s_cbranch_scc0 .LBB0_795
	s_mov_b64 s[34:35], 0
	s_cmpk_eq_i32 s8, 0x7f
	s_mov_b64 s[38:39], 0
	s_cbranch_scc1 .LBB0_796
	s_and_b64 vcc, exec, s[34:35]
	s_cbranch_vccnz .LBB0_797

; DI float* kout() { return (float*)karg64<200>(); }
; DI void lru_fix_unit(const Ctx& c, int l, int chunk, int half) {
;     ...
;     if (tq == 3) {
;         if (smp) *(f32x4*)(kout() + O_SLRU + ((size_t)l * 32 + (chunk - 256)) * 1024 + ch) = h;
;         else if (n == 127) *(f32x4*)(kout() + O_PLRU + ((size_t)l * 2 + (chunk >> 7)) * 1024 + ch) = h;
;     }
.LBB0_798:
	s_lshl_b64 s[18:19], s[18:19], 12
	s_add_u32 s8, s8, s18
	s_addc_u32 s9, s9, s19
	v_lshl_add_u64 v[8:9], s[8:9], 0, v[2:3]
	global_store_dwordx4 v[8:9], v[4:7], off
	s_branch .LBB0_782

; DI float bflo(unsigned w) { return __uint_as_float(w << 16); }
; DI float bfhi(unsigned w) { return __uint_as_float(w & 0xffff0000u); }
; DI void copy_state(const Ctx& c, float* dst, int nb, int rows, int width, int row0, int bstride, int col) {
;     ...
;     for (size_t i = (size_t)c.bid * NTHR + c.tid; i < total; i += (size_t)c.G * NTHR) {
;         const int e = (int)(i % w8); const size_t rt = i / w8; const int t = (int)(rt % rows), b = (int)(rt / rows);
;         const u32x4 v = *(const u32x4*)(Z + (size_t)(row0 + b * bstride + t) * ZLD + col + 8 * e);
;         f32x4* d = (f32x4*)(dst + ((size_t)(b * rows + t) * width + 8 * e));
;         d[0] = (f32x4){bflo(v.x), bfhi(v.x), bflo(v.y), bfhi(v.y)}; d[1] = (f32x4){bflo(v.z), bfhi(v.z), bflo(v.w), bfhi(v.w)};
;     }
.LBB0_801:
	v_lshrrev_b16_e32 v1, 7, v6
	s_mov_b64 s[10:11], 0x180
	v_add_u16_e32 v2, -3, v1
	v_cmp_gt_u64_e32 vcc, s[10:11], v[6:7]
	s_mov_b64 s[10:11], 0x17f
	v_mov_b32_e32 v8, 0x3ffd
	v_cndmask_b32_e32 v1, v2, v1, vcc
	v_cmp_lt_u64_e32 vcc, s[10:11], v[6:7]
	v_mov_b32_e32 v2, 0x1ffd
	v_and_b32_e32 v1, 0xffff, v1
	v_cndmask_b32_e32 v2, v2, v8, vcc
	v_add_u32_e32 v2, v2, v1
	v_mul_u32_u24_e32 v2, 0x3400, v2
	v_lshl_add_u64 v[8:9], s[34:35], 0, v[2:3]
	v_lshlrev_b32_e32 v2, 3, v6
	v_and_b32_e32 v14, 0x3f8, v2
	v_lshlrev_b32_e32 v2, 1, v14
	v_lshl_add_u64 v[8:9], v[8:9], 0, v[2:3]
	global_load_dwordx4 v[8:11], v[8:9], off
	v_cndmask_b32_e64 v2, 0, 3, vcc
	v_add_lshl_u32 v2, v2, v1, 12
	v_lshl_add_u64 v[6:7], v[6:7], 0, s[4:5]
	s_mov_b64 s[10:11], 0x2ff
	v_lshl_add_u64 v[12:13], s[18:19], 0, v[2:3]
	v_lshlrev_b32_e32 v2, 2, v14
	v_cmp_lt_u64_e32 vcc, s[10:11], v[6:7]
	v_lshl_add_u64 v[16:17], v[12:13], 0, v[2:3]
	s_or_b64 s[38:39], vcc, s[38:39]
	s_waitcnt vmcnt(0) lgkmcnt(0)
	v_lshlrev_b32_e32 v12, 16, v8
	v_and_b32_e32 v13, 0xffff0000, v8
	v_lshlrev_b32_e32 v14, 16, v9
	v_and_b32_e32 v15, 0xffff0000, v9
	v_lshlrev_b32_e32 v8, 16, v10
	v_and_b32_e32 v9, 0xffff0000, v10
	v_lshlrev_b32_e32 v10, 16, v11
	v_and_b32_e32 v11, 0xffff0000, v11
	global_store_dwordx4 v[16:17], v[12:15], off
	global_store_dwordx4 v[16:17], v[8:11], off offset:16
	s_andn2_b64 exec, exec, s[38:39]
	s_cbranch_execnz .LBB0_801

; DI float bflo(unsigned w) { return __uint_as_float(w << 16); }
; DI float bfhi(unsigned w) { return __uint_as_float(w & 0xffff0000u); }
; DI void copy_state(const Ctx& c, float* dst, int nb, int rows, int width, int row0, int bstride, int col) {
;     ...
;     for (size_t i = (size_t)c.bid * NTHR + c.tid; i < total; i += (size_t)c.G * NTHR) {
;         const int e = (int)(i % w8); const size_t rt = i / w8; const int t = (int)(rt % rows), b = (int)(rt / rows);
;         const u32x4 v = *(const u32x4*)(Z + (size_t)(row0 + b * bstride + t) * ZLD + col + 8 * e);
;         f32x4* d = (f32x4*)(dst + ((size_t)(b * rows + t) * width + 8 * e));
;         d[0] = (f32x4){bflo(v.x), bfhi(v.x), bflo(v.y), bfhi(v.y)}; d[1] = (f32x4){bflo(v.z), bfhi(v.z), bflo(v.w), bfhi(v.w)};
;     }
.LBB0_804:
	v_lshrrev_b16_e32 v2, 7, v10
	s_movk_i32 s10, 0xab
	v_mul_lo_u16_sdwa v2, v2, s10 dst_sel:DWORD dst_unused:UNUSED_PAD src0_sel:BYTE_0 src1_sel:DWORD
	v_lshrrev_b16_e32 v16, 9, v2
	v_lshrrev_b32_e32 v1, 7, v10
	v_mul_lo_u16_e32 v2, 3, v16
	v_sub_u16_e32 v1, v1, v2
	v_and_b32_e32 v1, 0xff, v1
	v_lshlrev_b32_e32 v2, 6, v16
	s_movk_i32 s10, 0x403d
	v_add3_u32 v2, v1, v2, s10
	v_mul_u32_u24_e32 v2, 0x3400, v2
	v_and_b32_e32 v18, 0x3f8, v8
	v_lshl_add_u64 v[12:13], s[34:35], 0, v[2:3]
	v_lshlrev_b32_e32 v2, 1, v18
	v_lshl_add_u64 v[12:13], v[12:13], 0, v[2:3]
	global_load_dwordx4 v[12:15], v[12:13], off
	v_mul_u32_u24_e32 v2, 3, v16
	v_add_lshl_u32 v2, v2, v1, 12
	v_lshl_add_u64 v[10:11], v[10:11], 0, s[4:5]
	s_mov_b64 s[10:11], 0x2fff
	v_lshl_add_u64 v[16:17], s[18:19], 0, v[2:3]
	v_lshlrev_b32_e32 v2, 2, v18
	v_cmp_lt_u64_e32 vcc, s[10:11], v[10:11]
	v_lshl_add_u64 v[20:21], v[16:17], 0, v[2:3]
	v_lshl_add_u64 v[8:9], v[8:9], 0, s[38:39]
	s_or_b64 s[40:41], vcc, s[40:41]
	s_waitcnt vmcnt(0) lgkmcnt(0)
	v_lshlrev_b32_e32 v16, 16, v12
	v_and_b32_e32 v17, 0xffff0000, v12
	v_lshlrev_b32_e32 v18, 16, v13
	v_and_b32_e32 v19, 0xffff0000, v13
	v_lshlrev_b32_e32 v12, 16, v14
	v_and_b32_e32 v13, 0xffff0000, v14
	v_lshlrev_b32_e32 v14, 16, v15
	v_and_b32_e32 v15, 0xffff0000, v15
	global_store_dwordx4 v[20:21], v[16:19], off
	global_store_dwordx4 v[20:21], v[12:15], off offset:16
	s_andn2_b64 exec, exec, s[40:41]
	s_cbranch_execnz .LBB0_804

; DI float bflo(unsigned w) { return __uint_as_float(w << 16); }
; DI float bfhi(unsigned w) { return __uint_as_float(w & 0xffff0000u); }
; DI void copy_state(const Ctx& c, float* dst, int nb, int rows, int width, int row0, int bstride, int col) {
;     ...
;     for (size_t i = (size_t)c.bid * NTHR + c.tid; i < total; i += (size_t)c.G * NTHR) {
;         const int e = (int)(i % w8); const size_t rt = i / w8; const int t = (int)(rt % rows), b = (int)(rt / rows);
;         const u32x4 v = *(const u32x4*)(Z + (size_t)(row0 + b * bstride + t) * ZLD + col + 8 * e);
;         f32x4* d = (f32x4*)(dst + ((size_t)(b * rows + t) * width + 8 * e));
;         d[0] = (f32x4){bflo(v.x), bfhi(v.x), bflo(v.y), bfhi(v.y)}; d[1] = (f32x4){bflo(v.z), bfhi(v.z), bflo(v.w), bfhi(v.w)};
;     }
.LBB0_807:
	v_lshrrev_b16_e32 v1, 5, v8
	v_add_u16_e32 v2, 0xff80, v1
	v_cmp_gt_u64_e64 s[40:41], s[28:29], v[8:9]
	s_nop 1
	v_cndmask_b32_e64 v1, v2, v1, s[40:41]
	v_cmp_lt_u64_e64 s[40:41], s[22:23], v[8:9]
	v_and_b32_e32 v1, 0xffff, v1
	s_nop 0
	v_cndmask_b32_e64 v2, v224, v225, s[40:41]
	v_add_u32_e32 v2, v2, v1
	v_mul_u32_u24_e32 v2, 0x3400, v2
	v_lshl_add_u64 v[10:11], s[38:39], 0, v[2:3]
	v_lshlrev_b32_e32 v2, 3, v8
	v_and_b32_e32 v16, 0xf8, v2
	v_lshlrev_b32_e32 v2, 1, v16
	v_lshl_add_u64 v[10:11], v[10:11], 0, v[2:3]
	global_load_dwordx4 v[10:13], v[10:11], off
	v_cndmask_b32_e64 v2, 0, v226, s[40:41]
	v_add_lshl_u32 v2, v2, v1, 10
	v_lshl_add_u64 v[8:9], v[8:9], 0, s[4:5]
	v_lshl_add_u64 v[14:15], s[34:35], 0, v[2:3]
	v_lshlrev_b32_e32 v2, 2, v16
	v_cmp_lt_u64_e64 s[40:41], s[26:27], v[8:9]
	v_lshl_add_u64 v[18:19], v[14:15], 0, v[2:3]
	s_or_b64 s[42:43], s[40:41], s[42:43]
	s_waitcnt vmcnt(0) lgkmcnt(0)
	v_lshlrev_b32_e32 v14, 16, v10
	v_and_b32_e32 v15, 0xffff0000, v10
	v_lshlrev_b32_e32 v16, 16, v11
	v_and_b32_e32 v17, 0xffff0000, v11
	v_lshlrev_b32_e32 v10, 16, v12
	v_and_b32_e32 v11, 0xffff0000, v12
	v_lshlrev_b32_e32 v12, 16, v13
	v_and_b32_e32 v13, 0xffff0000, v13
	global_store_dwordx4 v[18:19], v[14:17], off
	global_store_dwordx4 v[18:19], v[10:13], off offset:16
	s_andn2_b64 exec, exec, s[42:43]
	s_cbranch_execnz .LBB0_807

; DI float bflo(unsigned w) { return __uint_as_float(w << 16); }
; DI float bfhi(unsigned w) { return __uint_as_float(w & 0xffff0000u); }
; DI void copy_state(const Ctx& c, float* dst, int nb, int rows, int width, int row0, int bstride, int col) {
;     ...
;     for (size_t i = (size_t)c.bid * NTHR + c.tid; i < total; i += (size_t)c.G * NTHR) {
;         const int e = (int)(i % w8); const size_t rt = i / w8; const int t = (int)(rt % rows), b = (int)(rt / rows);
;         const u32x4 v = *(const u32x4*)(Z + (size_t)(row0 + b * bstride + t) * ZLD + col + 8 * e);
;         f32x4* d = (f32x4*)(dst + ((size_t)(b * rows + t) * width + 8 * e));
;         d[0] = (f32x4){bflo(v.x), bfhi(v.x), bflo(v.y), bfhi(v.y)}; d[1] = (f32x4){bflo(v.z), bfhi(v.z), bflo(v.w), bfhi(v.w)};
;     }
.LBB0_810:
	v_lshrrev_b16_e32 v1, 5, v8
	v_add_u16_e32 v2, 0xff80, v1
	v_cmp_gt_u64_e32 vcc, s[28:29], v[8:9]
	s_nop 1
	v_cndmask_b32_e32 v1, v2, v1, vcc
	v_cmp_lt_u64_e32 vcc, s[22:23], v[8:9]
	v_and_b32_e32 v1, 0xffff, v1
	s_nop 0
	v_cndmask_b32_e32 v2, v224, v225, vcc
	v_add_u32_e32 v2, v2, v1
	v_mul_u32_u24_e32 v2, 0x3400, v2
	v_lshl_add_u64 v[10:11], s[34:35], 0, v[2:3]
	v_lshlrev_b32_e32 v2, 3, v8
	v_and_b32_e32 v16, 0xf8, v2
	v_lshlrev_b32_e32 v2, 1, v16
	v_lshl_add_u64 v[10:11], v[10:11], 0, v[2:3]
	global_load_dwordx4 v[10:13], v[10:11], off
	v_cndmask_b32_e32 v2, 0, v226, vcc
	v_add_lshl_u32 v2, v2, v1, 10
	v_lshl_add_u64 v[8:9], v[8:9], 0, s[4:5]
	v_lshl_add_u64 v[14:15], s[8:9], 0, v[2:3]
	v_lshlrev_b32_e32 v2, 2, v16
	v_cmp_lt_u64_e32 vcc, s[26:27], v[8:9]
	v_lshl_add_u64 v[18:19], v[14:15], 0, v[2:3]
	s_or_b64 s[38:39], vcc, s[38:39]
	s_waitcnt vmcnt(0) lgkmcnt(0)
	v_lshlrev_b32_e32 v14, 16, v10
	v_and_b32_e32 v15, 0xffff0000, v10
	v_lshlrev_b32_e32 v16, 16, v11
	v_and_b32_e32 v17, 0xffff0000, v11
	v_lshlrev_b32_e32 v10, 16, v12
	v_and_b32_e32 v11, 0xffff0000, v12
	v_lshlrev_b32_e32 v12, 16, v13
	v_and_b32_e32 v13, 0xffff0000, v13
	global_store_dwordx4 v[18:19], v[14:17], off
	global_store_dwordx4 v[18:19], v[10:13], off offset:16
	s_andn2_b64 exec, exec, s[38:39]
	s_cbranch_execnz .LBB0_810

; DI float bflo(unsigned w) { return __uint_as_float(w << 16); }
; DI float bfhi(unsigned w) { return __uint_as_float(w & 0xffff0000u); }
; DI void copy_state(const Ctx& c, float* dst, int nb, int rows, int width, int row0, int bstride, int col) {
;     ...
;     for (size_t i = (size_t)c.bid * NTHR + c.tid; i < total; i += (size_t)c.G * NTHR) {
;         const int e = (int)(i % w8); const size_t rt = i / w8; const int t = (int)(rt % rows), b = (int)(rt / rows);
;         const u32x4 v = *(const u32x4*)(Z + (size_t)(row0 + b * bstride + t) * ZLD + col + 8 * e);
;         f32x4* d = (f32x4*)(dst + ((size_t)(b * rows + t) * width + 8 * e));
;         d[0] = (f32x4){bflo(v.x), bfhi(v.x), bflo(v.y), bfhi(v.y)}; d[1] = (f32x4){bflo(v.z), bfhi(v.z), bflo(v.w), bfhi(v.w)};
;     }
.LBB0_813:
	v_lshrrev_b32_e32 v1, 7, v8
	v_add_u16_e32 v2, 0xfe00, v1
	v_cmp_gt_u64_e64 s[40:41], s[90:91], v[8:9]
	s_nop 1
	v_cndmask_b32_e64 v1, v2, v1, s[40:41]
	v_cmp_lt_u64_e64 s[40:41], s[6:7], v[8:9]
	v_and_b32_e32 v1, 0xffff, v1
	s_nop 0
	v_cndmask_b32_e64 v2, v227, v228, s[40:41]
	v_add_u32_e32 v2, v2, v1
	v_mul_u32_u24_e32 v2, 0x3400, v2
	v_lshl_add_u64 v[10:11], s[38:39], 0, v[2:3]
	v_lshlrev_b32_e32 v2, 3, v8
	v_and_b32_e32 v16, 0x3f8, v2
	v_lshlrev_b32_e32 v2, 1, v16
	v_lshl_add_u64 v[10:11], v[10:11], 0, v[2:3]
	global_load_dwordx4 v[10:13], v[10:11], off
	v_cndmask_b32_e64 v2, 0, v229, s[40:41]
	v_add_lshl_u32 v2, v2, v1, 12
	v_lshl_add_u64 v[8:9], v[8:9], 0, s[4:5]
	v_lshl_add_u64 v[14:15], s[34:35], 0, v[2:3]
	v_lshlrev_b32_e32 v2, 2, v16
	v_cmp_lt_u64_e64 s[40:41], s[22:23], v[8:9]
	v_lshl_add_u64 v[18:19], v[14:15], 0, v[2:3]
	s_or_b64 s[42:43], s[40:41], s[42:43]
	s_waitcnt vmcnt(0) lgkmcnt(0)
	v_lshlrev_b32_e32 v14, 16, v10
	v_and_b32_e32 v15, 0xffff0000, v10
	v_lshlrev_b32_e32 v16, 16, v11
	v_and_b32_e32 v17, 0xffff0000, v11
	v_lshlrev_b32_e32 v10, 16, v12
	v_and_b32_e32 v11, 0xffff0000, v12
	v_lshlrev_b32_e32 v12, 16, v13
	v_and_b32_e32 v13, 0xffff0000, v13
	global_store_dwordx4 v[18:19], v[14:17], off
	global_store_dwordx4 v[18:19], v[10:13], off offset:16
	s_andn2_b64 exec, exec, s[42:43]
	s_cbranch_execnz .LBB0_813

; DI float bflo(unsigned w) { return __uint_as_float(w << 16); }
; DI float bfhi(unsigned w) { return __uint_as_float(w & 0xffff0000u); }
; DI void copy_state(const Ctx& c, float* dst, int nb, int rows, int width, int row0, int bstride, int col) {
;     ...
;     for (size_t i = (size_t)c.bid * NTHR + c.tid; i < total; i += (size_t)c.G * NTHR) {
;         const int e = (int)(i % w8); const size_t rt = i / w8; const int t = (int)(rt % rows), b = (int)(rt / rows);
;         const u32x4 v = *(const u32x4*)(Z + (size_t)(row0 + b * bstride + t) * ZLD + col + 8 * e);
;         f32x4* d = (f32x4*)(dst + ((size_t)(b * rows + t) * width + 8 * e));
;         d[0] = (f32x4){bflo(v.x), bfhi(v.x), bflo(v.y), bfhi(v.y)}; d[1] = (f32x4){bflo(v.z), bfhi(v.z), bflo(v.w), bfhi(v.w)};
;     }
.LBB0_816:
	v_lshrrev_b32_e32 v1, 7, v8
	v_add_u16_e32 v2, 0xfe00, v1
	v_cmp_gt_u64_e32 vcc, s[90:91], v[8:9]
	s_nop 1
	v_cndmask_b32_e32 v1, v2, v1, vcc
	v_cmp_lt_u64_e32 vcc, s[6:7], v[8:9]
	v_and_b32_e32 v1, 0xffff, v1
	s_nop 0
	v_cndmask_b32_e32 v2, v227, v228, vcc
	v_add_u32_e32 v2, v2, v1
	v_mul_u32_u24_e32 v2, 0x3400, v2
	v_lshl_add_u64 v[10:11], s[34:35], 0, v[2:3]
	v_lshlrev_b32_e32 v2, 3, v8
	v_and_b32_e32 v16, 0x3f8, v2
	v_lshlrev_b32_e32 v2, 1, v16
	v_lshl_add_u64 v[10:11], v[10:11], 0, v[2:3]
	global_load_dwordx4 v[10:13], v[10:11], off
	v_cndmask_b32_e32 v2, 0, v229, vcc
	v_add_lshl_u32 v2, v2, v1, 12
	v_lshl_add_u64 v[8:9], v[8:9], 0, s[4:5]
	v_lshl_add_u64 v[14:15], s[8:9], 0, v[2:3]
	v_lshlrev_b32_e32 v2, 2, v16
	v_cmp_lt_u64_e32 vcc, s[22:23], v[8:9]
	v_lshl_add_u64 v[18:19], v[14:15], 0, v[2:3]
	s_or_b64 s[38:39], vcc, s[38:39]
	s_waitcnt vmcnt(0) lgkmcnt(0)
	v_lshlrev_b32_e32 v14, 16, v10
	v_and_b32_e32 v15, 0xffff0000, v10
	v_lshlrev_b32_e32 v16, 16, v11
	v_and_b32_e32 v17, 0xffff0000, v11
	v_lshlrev_b32_e32 v10, 16, v12
	v_and_b32_e32 v11, 0xffff0000, v12
	v_lshlrev_b32_e32 v12, 16, v13
	v_and_b32_e32 v13, 0xffff0000, v13
	global_store_dwordx4 v[18:19], v[14:17], off
	global_store_dwordx4 v[18:19], v[10:13], off offset:16
	s_andn2_b64 exec, exec, s[38:39]
	s_cbranch_execnz .LBB0_816

; DI float bflo(unsigned w) { return __uint_as_float(w << 16); }
; DI float bfhi(unsigned w) { return __uint_as_float(w & 0xffff0000u); }
; DI void copy_state(const Ctx& c, float* dst, int nb, int rows, int width, int row0, int bstride, int col) {
;     ...
;     for (size_t i = (size_t)c.bid * NTHR + c.tid; i < total; i += (size_t)c.G * NTHR) {
;         const int e = (int)(i % w8); const size_t rt = i / w8; const int t = (int)(rt % rows), b = (int)(rt / rows);
;         const u32x4 v = *(const u32x4*)(Z + (size_t)(row0 + b * bstride + t) * ZLD + col + 8 * e);
;         f32x4* d = (f32x4*)(dst + ((size_t)(b * rows + t) * width + 8 * e));
;         d[0] = (f32x4){bflo(v.x), bfhi(v.x), bflo(v.y), bfhi(v.y)}; d[1] = (f32x4){bflo(v.z), bfhi(v.z), bflo(v.w), bfhi(v.w)};
;     }
.LBB0_819:
	v_lshrrev_b32_e32 v1, 5, v10
	v_mul_lo_u32 v2, v1, s31
	v_and_b32_e32 v18, 0xf8, v8
	v_lshl_add_u64 v[12:13], s[34:35], 0, v[2:3]
	v_lshlrev_b32_e32 v2, 1, v18
	v_lshl_add_u64 v[12:13], v[12:13], 0, v[2:3]
	v_add_co_u32_e32 v12, vcc, 0x33457000, v12
	v_lshlrev_b32_e32 v2, 8, v1
	s_nop 0
	v_addc_co_u32_e32 v13, vcc, 0, v13, vcc
	global_load_dwordx4 v[12:15], v[12:13], off offset:2048
	v_lshl_add_u64 v[10:11], v[10:11], 0, s[4:5]
	v_lshl_add_u64 v[16:17], v[2:3], 2, s[38:39]
	v_lshlrev_b32_e32 v2, 2, v18
	v_cmp_lt_u64_e32 vcc, s[6:7], v[10:11]
	v_lshl_add_u64 v[20:21], v[16:17], 0, v[2:3]
	v_lshl_add_u64 v[8:9], v[8:9], 0, s[42:43]
	s_or_b64 s[46:47], vcc, s[46:47]
	s_waitcnt vmcnt(0) lgkmcnt(0)
	v_lshlrev_b32_e32 v16, 16, v12
	v_and_b32_e32 v17, 0xffff0000, v12
	v_lshlrev_b32_e32 v18, 16, v13
	v_and_b32_e32 v19, 0xffff0000, v13
	v_lshlrev_b32_e32 v12, 16, v14
	v_and_b32_e32 v13, 0xffff0000, v14
	v_lshlrev_b32_e32 v14, 16, v15
	v_and_b32_e32 v15, 0xffff0000, v15
	global_store_dwordx4 v[20:21], v[16:19], off
	global_store_dwordx4 v[20:21], v[12:15], off offset:16
	s_andn2_b64 exec, exec, s[46:47]
	s_cbranch_execnz .LBB0_819

; DI float bflo(unsigned w) { return __uint_as_float(w << 16); }
; DI float bfhi(unsigned w) { return __uint_as_float(w & 0xffff0000u); }
; DI void copy_state(const Ctx& c, float* dst, int nb, int rows, int width, int row0, int bstride, int col) {
;     ...
;     for (size_t i = (size_t)c.bid * NTHR + c.tid; i < total; i += (size_t)c.G * NTHR) {
;         const int e = (int)(i % w8); const size_t rt = i / w8; const int t = (int)(rt % rows), b = (int)(rt / rows);
;         const u32x4 v = *(const u32x4*)(Z + (size_t)(row0 + b * bstride + t) * ZLD + col + 8 * e);
;         f32x4* d = (f32x4*)(dst + ((size_t)(b * rows + t) * width + 8 * e));
;         d[0] = (f32x4){bflo(v.x), bfhi(v.x), bflo(v.y), bfhi(v.y)}; d[1] = (f32x4){bflo(v.z), bfhi(v.z), bflo(v.w), bfhi(v.w)};
;     }
.LBB0_822:
	v_lshrrev_b32_e32 v1, 5, v10
	v_mul_lo_u32 v2, v1, s31
	v_and_b32_e32 v18, 0xf8, v8
	v_lshl_add_u64 v[12:13], s[34:35], 0, v[2:3]
	v_lshlrev_b32_e32 v2, 1, v18
	v_lshl_add_u64 v[12:13], v[12:13], 0, v[2:3]
	v_add_co_u32_e32 v12, vcc, 0x33457000, v12
	v_lshlrev_b32_e32 v2, 8, v1
	s_nop 0
	v_addc_co_u32_e32 v13, vcc, 0, v13, vcc
	global_load_dwordx4 v[12:15], v[12:13], off offset:2560
	v_lshl_add_u64 v[10:11], v[10:11], 0, s[4:5]
	v_lshl_add_u64 v[16:17], v[2:3], 2, s[8:9]
	v_lshlrev_b32_e32 v2, 2, v18
	v_cmp_lt_u64_e32 vcc, s[6:7], v[10:11]
	v_lshl_add_u64 v[20:21], v[16:17], 0, v[2:3]
	v_lshl_add_u64 v[8:9], v[8:9], 0, s[38:39]
	s_or_b64 s[40:41], vcc, s[40:41]
	s_waitcnt vmcnt(0) lgkmcnt(0)
	v_lshlrev_b32_e32 v16, 16, v12
	v_and_b32_e32 v17, 0xffff0000, v12
	v_lshlrev_b32_e32 v18, 16, v13
	v_and_b32_e32 v19, 0xffff0000, v13
	v_lshlrev_b32_e32 v12, 16, v14
	v_and_b32_e32 v13, 0xffff0000, v14
	v_lshlrev_b32_e32 v14, 16, v15
	v_and_b32_e32 v15, 0xffff0000, v15
	global_store_dwordx4 v[20:21], v[16:19], off
	global_store_dwordx4 v[20:21], v[12:15], off offset:16
	s_andn2_b64 exec, exec, s[40:41]
	s_cbranch_execnz .LBB0_822

; DI float bflo(unsigned w) { return __uint_as_float(w << 16); }
; DI float bfhi(unsigned w) { return __uint_as_float(w & 0xffff0000u); }
; DI void copy_state(const Ctx& c, float* dst, int nb, int rows, int width, int row0, int bstride, int col) {
;     ...
;     for (size_t i = (size_t)c.bid * NTHR + c.tid; i < total; i += (size_t)c.G * NTHR) {
;         const int e = (int)(i % w8); const size_t rt = i / w8; const int t = (int)(rt % rows), b = (int)(rt / rows);
;         const u32x4 v = *(const u32x4*)(Z + (size_t)(row0 + b * bstride + t) * ZLD + col + 8 * e);
;         f32x4* d = (f32x4*)(dst + ((size_t)(b * rows + t) * width + 8 * e));
;         d[0] = (f32x4){bflo(v.x), bfhi(v.x), bflo(v.y), bfhi(v.y)}; d[1] = (f32x4){bflo(v.z), bfhi(v.z), bflo(v.w), bfhi(v.w)};
;     }
.LBB0_825:
	v_alignbit_b32 v1, v11, v10, 7
	v_mov_b64_e32 v[12:13], s[34:35]
	v_mad_u64_u32 v[12:13], s[10:11], v1, s31, v[12:13]
	v_mov_b32_e32 v2, v13
	v_lshrrev_b32_e32 v1, 7, v11
	v_mad_u64_u32 v[14:15], s[10:11], v1, s31, v[2:3]
	v_and_b32_e32 v1, 0x3f8, v8
	v_mov_b32_e32 v13, v14
	v_lshlrev_b32_e32 v2, 1, v1
	v_lshl_add_u64 v[12:13], v[12:13], 0, v[2:3]
	v_add_co_u32_e64 v12, s[40:41], s12, v12
	v_lshrrev_b64 v[16:17], 7, v[10:11]
	s_nop 0
	v_addc_co_u32_e64 v13, s[40:41], 0, v13, s[40:41]
	global_load_dwordx4 v[12:15], v[12:13], off offset:1024
	v_lshlrev_b64 v[16:17], 12, v[16:17]
	v_lshl_add_u64 v[10:11], v[10:11], 0, s[4:5]
	v_lshl_add_u64 v[16:17], s[38:39], 0, v[16:17]
	v_lshlrev_b32_e32 v2, 2, v1
	v_cmp_lt_u64_e64 s[40:41], s[22:23], v[10:11]
	v_lshl_add_u64 v[20:21], v[16:17], 0, v[2:3]
	v_lshl_add_u64 v[8:9], v[8:9], 0, s[42:43]
	s_or_b64 s[46:47], s[40:41], s[46:47]
	s_waitcnt vmcnt(0) lgkmcnt(0)
	v_lshlrev_b32_e32 v16, 16, v12
	v_and_b32_e32 v17, 0xffff0000, v12
	v_lshlrev_b32_e32 v18, 16, v13
	v_and_b32_e32 v19, 0xffff0000, v13
	v_lshlrev_b32_e32 v12, 16, v14
	v_and_b32_e32 v13, 0xffff0000, v14
	v_lshlrev_b32_e32 v14, 16, v15
	v_and_b32_e32 v15, 0xffff0000, v15
	global_store_dwordx4 v[20:21], v[16:19], off
	global_store_dwordx4 v[20:21], v[12:15], off offset:16
	s_andn2_b64 exec, exec, s[46:47]
	s_cbranch_execnz .LBB0_825

; DI float bflo(unsigned w) { return __uint_as_float(w << 16); }
; DI float bfhi(unsigned w) { return __uint_as_float(w & 0xffff0000u); }
; DI void copy_state(const Ctx& c, float* dst, int nb, int rows, int width, int row0, int bstride, int col) {
;     ...
;     for (size_t i = (size_t)c.bid * NTHR + c.tid; i < total; i += (size_t)c.G * NTHR) {
;         const int e = (int)(i % w8); const size_t rt = i / w8; const int t = (int)(rt % rows), b = (int)(rt / rows);
;         const u32x4 v = *(const u32x4*)(Z + (size_t)(row0 + b * bstride + t) * ZLD + col + 8 * e);
;         f32x4* d = (f32x4*)(dst + ((size_t)(b * rows + t) * width + 8 * e));
;         d[0] = (f32x4){bflo(v.x), bfhi(v.x), bflo(v.y), bfhi(v.y)}; d[1] = (f32x4){bflo(v.z), bfhi(v.z), bflo(v.w), bfhi(v.w)};
;     }
.LBB0_828:
	v_alignbit_b32 v1, v5, v4, 7
	v_mov_b64_e32 v[8:9], s[34:35]
	v_mad_u64_u32 v[8:9], s[10:11], v1, s31, v[8:9]
	v_mov_b32_e32 v2, v9
	v_lshrrev_b32_e32 v1, 7, v5
	v_mad_u64_u32 v[10:11], s[10:11], v1, s31, v[2:3]
	v_and_b32_e32 v1, 0x3f8, v6
	v_mov_b32_e32 v9, v10
	v_lshlrev_b32_e32 v2, 1, v1
	v_lshl_add_u64 v[8:9], v[8:9], 0, v[2:3]
	v_add_co_u32_e32 v8, vcc, s12, v8
	v_lshrrev_b64 v[12:13], 7, v[4:5]
	s_nop 0
	v_addc_co_u32_e32 v9, vcc, 0, v9, vcc
	global_load_dwordx4 v[8:11], v[8:9], off offset:3072
	v_lshlrev_b64 v[12:13], 12, v[12:13]
	v_lshl_add_u64 v[4:5], v[4:5], 0, s[4:5]
	v_lshl_add_u64 v[12:13], s[8:9], 0, v[12:13]
	v_lshlrev_b32_e32 v2, 2, v1
	v_cmp_lt_u64_e32 vcc, s[22:23], v[4:5]
	v_lshl_add_u64 v[16:17], v[12:13], 0, v[2:3]
	v_lshl_add_u64 v[6:7], v[6:7], 0, s[38:39]
	s_or_b64 s[40:41], vcc, s[40:41]
	s_waitcnt vmcnt(0) lgkmcnt(0)
	v_lshlrev_b32_e32 v12, 16, v8
	v_and_b32_e32 v13, 0xffff0000, v8
	v_lshlrev_b32_e32 v14, 16, v9
	v_and_b32_e32 v15, 0xffff0000, v9
	v_lshlrev_b32_e32 v8, 16, v10
	v_and_b32_e32 v9, 0xffff0000, v10
	v_lshlrev_b32_e32 v10, 16, v11
	v_and_b32_e32 v11, 0xffff0000, v11
	global_store_dwordx4 v[16:17], v[12:15], off
	global_store_dwordx4 v[16:17], v[8:11], off offset:16
	s_andn2_b64 exec, exec, s[40:41]
	s_cbranch_execnz .LBB0_828

;     DI void hook(f32x4 (&acc)[2][2][4][2], const Unit& u, int r, int wr, int wc, int fr_, int fq_) const {
;     ...
;                 const unsigned char* gp = Z + ((size_t)u.pm * 24 + (r - 1) * 8 + u.pn) * 65536 + (((((wr * 4 + wc) * 2 + ai) * 4 + m) * 64 + fq * 16 + fr) << 4);
;                 const u32x4 gn = *(const u32x4*)gp, gd = *(const u32x4*)(gp + 8 * 65536);
; #pragma unroll
;                 for (int bj = 0; bj < 2; ++bj) {
;                     f32x4 n0, n1, d0, d1; unpackq8(bj ? (u32x2){gn.z, gn.w} : (u32x2){gn.x, gn.y}, n0, n1); unpackq8(bj ? (u32x2){gd.z, gd.w} : (u32x2){gd.x, gd.y}, d0, d1);
; #pragma unroll
;                     for (int j = 0; j < 4; ++j) { acc[ai][bj][m][0][j] *= n0[j] * __builtin_amdgcn_rcpf(d0[j]); acc[ai][bj][m][1][j] *= n1[j] * __builtin_amdgcn_rcpf(d1[j]); }
;                 }
.LBB0_904:
	s_andn2_b64 vcc, exec, s[4:5]
	s_cbranch_vccnz .LBB0_906
	v_mov_b32_e32 v2, v1
	v_mov_b32_e32 v4, v160
	s_add_u32 s4, s34, s22
	s_addc_u32 s5, s35, 0
	v_lshlrev_b32_e32 v2, 4, v2
	s_lshl_b64 s[4:5], s[4:5], 16
	v_lshl_add_u32 v2, v4, 8, v2
	s_add_u32 s4, s71, s4
	v_add_u32_e32 v4, s82, v2
	s_addc_u32 s5, s72, s5
	v_ashrrev_i32_e32 v5, 31, v4
	v_lshl_add_u64 v[138:139], s[4:5], 0, v[4:5]
	v_add_co_u32_e32 v4, vcc, s77, v138
	global_load_dwordx4 v[134:137], v[138:139], off
	s_nop 0
	v_addc_co_u32_e32 v5, vcc, 0, v139, vcc
	global_load_dwordx4 v[166:169], v[4:5], off
	s_waitcnt vmcnt(0) lgkmcnt(0)
	v_cvt_f32_ubyte3_e32 v173, v134
	v_cvt_f32_ubyte2_e32 v172, v134
	v_cvt_f32_ubyte1_e32 v175, v134
	v_cvt_f32_ubyte2_e32 v165, v166
	v_cvt_f32_ubyte3_e32 v171, v166
	v_cvt_f32_ubyte0_e32 v140, v166
	v_cvt_f32_ubyte1_e32 v141, v166
	v_cvt_f32_ubyte0_e32 v158, v167
	v_cvt_f32_ubyte1_e32 v159, v167
	v_cvt_f32_ubyte2_e32 v170, v167
	v_cvt_f32_ubyte3_e32 v176, v167
	v_rcp_iflag_f32_e32 v166, v165
	v_rcp_iflag_f32_e32 v167, v171
	v_rcp_iflag_f32_e32 v140, v140
	v_rcp_iflag_f32_e32 v141, v141
	v_rcp_iflag_f32_e32 v158, v158
	v_rcp_iflag_f32_e32 v159, v159
	v_rcp_iflag_f32_e32 v170, v170
	v_cvt_f32_ubyte0_e32 v174, v134
	v_pk_mul_f32 v[166:167], v[166:167], v[172:173]
	v_rcp_iflag_f32_e32 v171, v176
	v_pk_mul_f32 v[140:141], v[140:141], v[174:175]
	v_pk_mul_f32 v[132:133], v[132:133], v[166:167]
	v_cvt_f32_ubyte1_e32 v167, v135
	v_cvt_f32_ubyte0_e32 v166, v135
	v_pk_mul_f32 v[130:131], v[130:131], v[140:141]
	v_cvt_f32_ubyte3_e32 v141, v135
	v_cvt_f32_ubyte2_e32 v140, v135
	v_pk_mul_f32 v[134:135], v[158:159], v[166:167]
	v_cvt_f32_ubyte2_e32 v158, v168
	v_pk_mul_f32 v[126:127], v[126:127], v[134:135]
	v_cvt_f32_ubyte0_e32 v134, v168
	v_cvt_f32_ubyte1_e32 v135, v168
	v_cvt_f32_ubyte3_e32 v159, v168
	v_pk_mul_f32 v[140:141], v[170:171], v[140:141]
	v_rcp_iflag_f32_e32 v134, v134
	v_rcp_iflag_f32_e32 v135, v135
	v_rcp_iflag_f32_e32 v158, v158
	v_rcp_iflag_f32_e32 v159, v159
	v_pk_mul_f32 v[128:129], v[128:129], v[140:141]
	v_cvt_f32_ubyte0_e32 v140, v169
	v_cvt_f32_ubyte1_e32 v141, v169
	v_cvt_f32_ubyte2_e32 v165, v169
	v_cvt_f32_ubyte3_e32 v167, v169
	v_rcp_iflag_f32_e32 v140, v140
	v_rcp_iflag_f32_e32 v141, v141
	v_rcp_iflag_f32_e32 v166, v165
	v_rcp_iflag_f32_e32 v167, v167
	v_cvt_f32_ubyte3_e32 v169, v136
	v_cvt_f32_ubyte2_e32 v168, v136
	v_cvt_f32_ubyte1_e32 v171, v136
	v_cvt_f32_ubyte0_e32 v170, v136
	v_pk_mul_f32 v[134:135], v[134:135], v[170:171]
	v_pk_mul_f32 v[158:159], v[158:159], v[168:169]
	v_pk_mul_f32 v[122:123], v[122:123], v[134:135]
	v_pk_mul_f32 v[124:125], v[124:125], v[158:159]
	v_cvt_f32_ubyte3_e32 v135, v137
	v_cvt_f32_ubyte2_e32 v134, v137
	v_cvt_f32_ubyte1_e32 v159, v137
	v_cvt_f32_ubyte0_e32 v158, v137
	v_pk_mul_f32 v[136:137], v[140:141], v[158:159]
	v_pk_mul_f32 v[134:135], v[166:167], v[134:135]
	v_pk_mul_f32 v[118:119], v[118:119], v[136:137]
	v_pk_mul_f32 v[120:121], v[120:121], v[134:135]
	global_load_dwordx4 v[134:137], v[138:139], off offset:1024
	global_load_dwordx4 v[166:169], v[4:5], off offset:1024
	s_waitcnt vmcnt(0) lgkmcnt(0)
	v_cvt_f32_ubyte3_e32 v173, v134
	v_cvt_f32_ubyte2_e32 v165, v166
	v_cvt_f32_ubyte3_e32 v171, v166
	v_cvt_f32_ubyte0_e32 v140, v166
	v_cvt_f32_ubyte1_e32 v141, v166
	v_cvt_f32_ubyte0_e32 v158, v167
	v_cvt_f32_ubyte1_e32 v159, v167
	v_cvt_f32_ubyte2_e32 v170, v167
	v_cvt_f32_ubyte3_e32 v176, v167
	v_rcp_iflag_f32_e32 v166, v165
	v_rcp_iflag_f32_e32 v167, v171
	v_rcp_iflag_f32_e32 v140, v140
	v_rcp_iflag_f32_e32 v141, v141
	v_rcp_iflag_f32_e32 v158, v158
	v_rcp_iflag_f32_e32 v159, v159
	v_cvt_f32_ubyte2_e32 v172, v134
	v_rcp_iflag_f32_e32 v170, v170
	v_cvt_f32_ubyte1_e32 v175, v134
	v_cvt_f32_ubyte0_e32 v174, v134
	v_pk_mul_f32 v[166:167], v[166:167], v[172:173]
	v_rcp_iflag_f32_e32 v171, v176
	v_pk_mul_f32 v[140:141], v[140:141], v[174:175]
	v_pk_mul_f32 v[116:117], v[116:117], v[166:167]
	v_cvt_f32_ubyte1_e32 v167, v135
	v_cvt_f32_ubyte0_e32 v166, v135
	v_pk_mul_f32 v[114:115], v[114:115], v[140:141]
	v_cvt_f32_ubyte3_e32 v141, v135
	v_cvt_f32_ubyte2_e32 v140, v135
	v_pk_mul_f32 v[134:135], v[158:159], v[166:167]
	v_cvt_f32_ubyte2_e32 v158, v168
	v_pk_mul_f32 v[110:111], v[110:111], v[134:135]
	v_cvt_f32_ubyte0_e32 v134, v168
	v_cvt_f32_ubyte1_e32 v135, v168
	v_cvt_f32_ubyte3_e32 v159, v168
	v_pk_mul_f32 v[140:141], v[170:171], v[140:141]
	v_rcp_iflag_f32_e32 v134, v134
	v_rcp_iflag_f32_e32 v135, v135
	v_rcp_iflag_f32_e32 v158, v158
	v_rcp_iflag_f32_e32 v159, v159
	v_pk_mul_f32 v[112:113], v[112:113], v[140:141]
	v_cvt_f32_ubyte0_e32 v140, v169
	v_cvt_f32_ubyte1_e32 v141, v169
	v_cvt_f32_ubyte2_e32 v165, v169
	v_cvt_f32_ubyte3_e32 v167, v169
	v_rcp_iflag_f32_e32 v140, v140
	v_rcp_iflag_f32_e32 v141, v141
	v_rcp_iflag_f32_e32 v166, v165
	v_rcp_iflag_f32_e32 v167, v167
	v_cvt_f32_ubyte3_e32 v169, v136
	v_cvt_f32_ubyte2_e32 v168, v136
	v_cvt_f32_ubyte1_e32 v171, v136
	v_cvt_f32_ubyte0_e32 v170, v136
	v_pk_mul_f32 v[134:135], v[134:135], v[170:171]
	v_pk_mul_f32 v[158:159], v[158:159], v[168:169]
	v_pk_mul_f32 v[106:107], v[106:107], v[134:135]
	v_pk_mul_f32 v[108:109], v[108:109], v[158:159]
	v_cvt_f32_ubyte3_e32 v135, v137
	v_cvt_f32_ubyte2_e32 v134, v137
	v_cvt_f32_ubyte1_e32 v159, v137
	v_cvt_f32_ubyte0_e32 v158, v137
	v_pk_mul_f32 v[136:137], v[140:141], v[158:159]
	v_pk_mul_f32 v[134:135], v[166:167], v[134:135]
	v_pk_mul_f32 v[102:103], v[102:103], v[136:137]
	v_pk_mul_f32 v[104:105], v[104:105], v[134:135]
	global_load_dwordx4 v[134:137], v[138:139], off offset:2048
	global_load_dwordx4 v[166:169], v[4:5], off offset:2048
	s_waitcnt vmcnt(0) lgkmcnt(0)
;     DI void hook(f32x4 (&acc)[2][2][4][2], const Unit& u, int r, int wr, int wc, int fr_, int fq_) const {
;     ...
;                 const unsigned char* gp = Z + ((size_t)u.pm * 24 + (r - 1) * 8 + u.pn) * 65536 + (((((wr * 4 + wc) * 2 + ai) * 4 + m) * 64 + fq * 16 + fr) << 4);
;                 const u32x4 gn = *(const u32x4*)gp, gd = *(const u32x4*)(gp + 8 * 65536);
; #pragma unroll
;                 for (int bj = 0; bj < 2; ++bj) {
;                     f32x4 n0, n1, d0, d1; unpackq8(bj ? (u32x2){gn.z, gn.w} : (u32x2){gn.x, gn.y}, n0, n1); unpackq8(bj ? (u32x2){gd.z, gd.w} : (u32x2){gd.x, gd.y}, d0, d1);
; #pragma unroll
;                     for (int j = 0; j < 4; ++j) { acc[ai][bj][m][0][j] *= n0[j] * __builtin_amdgcn_rcpf(d0[j]); acc[ai][bj][m][1][j] *= n1[j] * __builtin_amdgcn_rcpf(d1[j]); }
;                 }
	v_cvt_f32_ubyte3_e32 v173, v134
	v_cvt_f32_ubyte2_e32 v165, v166
	v_cvt_f32_ubyte3_e32 v171, v166
	v_cvt_f32_ubyte0_e32 v140, v166
	v_cvt_f32_ubyte1_e32 v141, v166
	v_cvt_f32_ubyte0_e32 v158, v167
	v_cvt_f32_ubyte1_e32 v159, v167
	v_cvt_f32_ubyte2_e32 v170, v167
	v_cvt_f32_ubyte3_e32 v176, v167
	v_rcp_iflag_f32_e32 v166, v165
	v_rcp_iflag_f32_e32 v167, v171
	v_rcp_iflag_f32_e32 v140, v140
	v_rcp_iflag_f32_e32 v141, v141
	v_rcp_iflag_f32_e32 v158, v158
	v_rcp_iflag_f32_e32 v159, v159
	v_cvt_f32_ubyte2_e32 v172, v134
	v_rcp_iflag_f32_e32 v170, v170
	v_cvt_f32_ubyte1_e32 v175, v134
	v_cvt_f32_ubyte0_e32 v174, v134
	v_pk_mul_f32 v[166:167], v[166:167], v[172:173]
	v_rcp_iflag_f32_e32 v171, v176
	v_pk_mul_f32 v[140:141], v[140:141], v[174:175]
	v_pk_mul_f32 v[100:101], v[100:101], v[166:167]
	v_cvt_f32_ubyte1_e32 v167, v135
	v_cvt_f32_ubyte0_e32 v166, v135
	v_pk_mul_f32 v[98:99], v[98:99], v[140:141]
	v_cvt_f32_ubyte3_e32 v141, v135
	v_cvt_f32_ubyte2_e32 v140, v135
	v_pk_mul_f32 v[134:135], v[158:159], v[166:167]
	v_cvt_f32_ubyte2_e32 v158, v168
	v_pk_mul_f32 v[94:95], v[94:95], v[134:135]
	v_cvt_f32_ubyte0_e32 v134, v168
	v_cvt_f32_ubyte1_e32 v135, v168
	v_cvt_f32_ubyte3_e32 v159, v168
	v_pk_mul_f32 v[140:141], v[170:171], v[140:141]
	v_rcp_iflag_f32_e32 v134, v134
	v_rcp_iflag_f32_e32 v135, v135
	v_rcp_iflag_f32_e32 v158, v158
	v_rcp_iflag_f32_e32 v159, v159
	v_pk_mul_f32 v[96:97], v[96:97], v[140:141]
	v_cvt_f32_ubyte0_e32 v140, v169
	v_cvt_f32_ubyte1_e32 v141, v169
	v_cvt_f32_ubyte2_e32 v165, v169
	v_cvt_f32_ubyte3_e32 v167, v169
	v_rcp_iflag_f32_e32 v140, v140
	v_rcp_iflag_f32_e32 v141, v141
	v_rcp_iflag_f32_e32 v166, v165
	v_rcp_iflag_f32_e32 v167, v167
	v_cvt_f32_ubyte3_e32 v169, v136
	v_cvt_f32_ubyte2_e32 v168, v136
	v_cvt_f32_ubyte1_e32 v171, v136
	v_cvt_f32_ubyte0_e32 v170, v136
	v_pk_mul_f32 v[134:135], v[134:135], v[170:171]
	v_pk_mul_f32 v[158:159], v[158:159], v[168:169]
	v_pk_mul_f32 v[90:91], v[90:91], v[134:135]
	v_pk_mul_f32 v[92:93], v[92:93], v[158:159]
	v_cvt_f32_ubyte3_e32 v135, v137
	v_cvt_f32_ubyte2_e32 v134, v137
	v_cvt_f32_ubyte1_e32 v159, v137
	v_cvt_f32_ubyte0_e32 v158, v137
	v_pk_mul_f32 v[136:137], v[140:141], v[158:159]
	v_pk_mul_f32 v[134:135], v[166:167], v[134:135]
	v_pk_mul_f32 v[86:87], v[86:87], v[136:137]
	v_pk_mul_f32 v[88:89], v[88:89], v[134:135]
	global_load_dwordx4 v[134:137], v[138:139], off offset:3072
	s_nop 0
	global_load_dwordx4 v[138:141], v[4:5], off offset:3072
	s_waitcnt vmcnt(0) lgkmcnt(0)
	v_cvt_f32_ubyte1_e32 v171, v134
	v_cvt_f32_ubyte0_e32 v4, v138
	v_cvt_f32_ubyte1_e32 v5, v138
	v_rcp_iflag_f32_e32 v4, v4
	v_rcp_iflag_f32_e32 v5, v5
	v_cvt_f32_ubyte2_e32 v158, v138
	v_cvt_f32_ubyte3_e32 v159, v138
	v_cvt_f32_ubyte2_e32 v166, v139
	v_cvt_f32_ubyte3_e32 v167, v139
	v_rcp_iflag_f32_e32 v158, v158
	v_rcp_iflag_f32_e32 v166, v166
	v_rcp_iflag_f32_e32 v159, v159
	v_rcp_iflag_f32_e32 v167, v167
	v_cvt_f32_ubyte0_e32 v138, v139
	v_cvt_f32_ubyte1_e32 v165, v139
	v_cvt_f32_ubyte0_e32 v170, v134
	v_rcp_iflag_f32_e32 v138, v138
	v_rcp_iflag_f32_e32 v139, v165
	v_pk_mul_f32 v[4:5], v[4:5], v[170:171]
	v_cvt_f32_ubyte3_e32 v169, v134
	v_cvt_f32_ubyte2_e32 v168, v134
	v_pk_mul_f32 v[82:83], v[82:83], v[4:5]
	v_cvt_f32_ubyte3_e32 v5, v135
	v_cvt_f32_ubyte2_e32 v4, v135
	v_pk_mul_f32 v[158:159], v[158:159], v[168:169]
	v_pk_mul_f32 v[4:5], v[166:167], v[4:5]
	v_pk_mul_f32 v[84:85], v[84:85], v[158:159]
	v_cvt_f32_ubyte1_e32 v159, v135
	v_cvt_f32_ubyte0_e32 v158, v135
	v_pk_mul_f32 v[80:81], v[80:81], v[4:5]
	v_cvt_f32_ubyte0_e32 v4, v140
	v_cvt_f32_ubyte1_e32 v5, v140
	v_pk_mul_f32 v[134:135], v[138:139], v[158:159]
	v_rcp_iflag_f32_e32 v4, v4
	v_rcp_iflag_f32_e32 v5, v5
	v_pk_mul_f32 v[78:79], v[78:79], v[134:135]
	v_cvt_f32_ubyte2_e32 v138, v140
	v_cvt_f32_ubyte3_e32 v139, v140
	v_cvt_f32_ubyte0_e32 v134, v141
	v_cvt_f32_ubyte1_e32 v135, v141
	v_cvt_f32_ubyte2_e32 v140, v141
	v_cvt_f32_ubyte3_e32 v141, v141
	v_rcp_iflag_f32_e32 v140, v140
	v_rcp_iflag_f32_e32 v141, v141
	v_rcp_iflag_f32_e32 v138, v138
	v_rcp_iflag_f32_e32 v139, v139
	v_cvt_f32_ubyte1_e32 v167, v136
	v_cvt_f32_ubyte0_e32 v166, v136
	v_pk_mul_f32 v[4:5], v[4:5], v[166:167]
	v_rcp_iflag_f32_e32 v134, v134
	v_rcp_iflag_f32_e32 v135, v135
	v_pk_mul_f32 v[74:75], v[74:75], v[4:5]
	v_cvt_f32_ubyte3_e32 v5, v137
	v_cvt_f32_ubyte2_e32 v4, v137
	v_cvt_f32_ubyte3_e32 v159, v136
	v_cvt_f32_ubyte2_e32 v158, v136
	v_pk_mul_f32 v[4:5], v[140:141], v[4:5]
	v_pk_mul_f32 v[138:139], v[138:139], v[158:159]
	v_pk_mul_f32 v[72:73], v[72:73], v[4:5]
	v_add_u32_e32 v4, s83, v2
	v_pk_mul_f32 v[76:77], v[76:77], v[138:139]
	v_cvt_f32_ubyte1_e32 v139, v137
	v_cvt_f32_ubyte0_e32 v138, v137
	v_ashrrev_i32_e32 v5, 31, v4
	v_pk_mul_f32 v[134:135], v[134:135], v[138:139]
	v_lshl_add_u64 v[138:139], s[4:5], 0, v[4:5]
	v_add_co_u32_e32 v4, vcc, s77, v138
	v_pk_mul_f32 v[70:71], v[70:71], v[134:135]
	s_nop 0
	v_addc_co_u32_e32 v5, vcc, 0, v139, vcc
	global_load_dwordx4 v[134:137], v[138:139], off
	global_load_dwordx4 v[166:169], v[4:5], off
	s_waitcnt vmcnt(0) lgkmcnt(0)
;     DI void hook(f32x4 (&acc)[2][2][4][2], const Unit& u, int r, int wr, int wc, int fr_, int fq_) const {
;     ...
;                 const unsigned char* gp = Z + ((size_t)u.pm * 24 + (r - 1) * 8 + u.pn) * 65536 + (((((wr * 4 + wc) * 2 + ai) * 4 + m) * 64 + fq * 16 + fr) << 4);
;                 const u32x4 gn = *(const u32x4*)gp, gd = *(const u32x4*)(gp + 8 * 65536);
; #pragma unroll
;                 for (int bj = 0; bj < 2; ++bj) {
;                     f32x4 n0, n1, d0, d1; unpackq8(bj ? (u32x2){gn.z, gn.w} : (u32x2){gn.x, gn.y}, n0, n1); unpackq8(bj ? (u32x2){gd.z, gd.w} : (u32x2){gd.x, gd.y}, d0, d1);
; #pragma unroll
;                     for (int j = 0; j < 4; ++j) { acc[ai][bj][m][0][j] *= n0[j] * __builtin_amdgcn_rcpf(d0[j]); acc[ai][bj][m][1][j] *= n1[j] * __builtin_amdgcn_rcpf(d1[j]); }
;                 }
	v_cvt_f32_ubyte3_e32 v173, v134
	v_cvt_f32_ubyte2_e32 v165, v166
	v_cvt_f32_ubyte3_e32 v171, v166
	v_cvt_f32_ubyte0_e32 v2, v166
	v_cvt_f32_ubyte1_e32 v141, v166
	v_cvt_f32_ubyte0_e32 v158, v167
	v_cvt_f32_ubyte1_e32 v159, v167
	v_cvt_f32_ubyte2_e32 v170, v167
	v_cvt_f32_ubyte3_e32 v176, v167
	v_rcp_iflag_f32_e32 v166, v165
	v_rcp_iflag_f32_e32 v167, v171
	v_rcp_iflag_f32_e32 v140, v2
	v_rcp_iflag_f32_e32 v141, v141
	v_rcp_iflag_f32_e32 v158, v158
	v_rcp_iflag_f32_e32 v159, v159
	v_cvt_f32_ubyte2_e32 v172, v134
	v_rcp_iflag_f32_e32 v170, v170
	v_cvt_f32_ubyte1_e32 v175, v134
	v_cvt_f32_ubyte0_e32 v174, v134
	v_pk_mul_f32 v[166:167], v[166:167], v[172:173]
	v_rcp_iflag_f32_e32 v171, v176
	v_pk_mul_f32 v[140:141], v[140:141], v[174:175]
	v_pk_mul_f32 v[68:69], v[68:69], v[166:167]
	v_cvt_f32_ubyte1_e32 v167, v135
	v_cvt_f32_ubyte0_e32 v166, v135
	v_pk_mul_f32 v[66:67], v[66:67], v[140:141]
	v_cvt_f32_ubyte3_e32 v141, v135
	v_cvt_f32_ubyte2_e32 v140, v135
	v_pk_mul_f32 v[134:135], v[158:159], v[166:167]
	v_cvt_f32_ubyte0_e32 v2, v168
	v_pk_mul_f32 v[62:63], v[62:63], v[134:135]
	v_cvt_f32_ubyte1_e32 v135, v168
	v_cvt_f32_ubyte2_e32 v158, v168
	v_cvt_f32_ubyte3_e32 v159, v168
	v_pk_mul_f32 v[140:141], v[170:171], v[140:141]
	v_rcp_iflag_f32_e32 v134, v2
	v_rcp_iflag_f32_e32 v135, v135
	v_rcp_iflag_f32_e32 v158, v158
	v_rcp_iflag_f32_e32 v159, v159
	v_pk_mul_f32 v[64:65], v[64:65], v[140:141]
	v_cvt_f32_ubyte0_e32 v140, v169
	v_cvt_f32_ubyte1_e32 v141, v169
	v_cvt_f32_ubyte2_e32 v165, v169
	v_cvt_f32_ubyte3_e32 v167, v169
	v_rcp_iflag_f32_e32 v140, v140
	v_rcp_iflag_f32_e32 v141, v141
	v_rcp_iflag_f32_e32 v166, v165
	v_rcp_iflag_f32_e32 v167, v167
	v_cvt_f32_ubyte3_e32 v169, v136
	v_cvt_f32_ubyte2_e32 v168, v136
	v_cvt_f32_ubyte1_e32 v171, v136
	v_cvt_f32_ubyte0_e32 v170, v136
	v_pk_mul_f32 v[134:135], v[134:135], v[170:171]
	v_pk_mul_f32 v[158:159], v[158:159], v[168:169]
	v_pk_mul_f32 v[58:59], v[58:59], v[134:135]
	v_pk_mul_f32 v[60:61], v[60:61], v[158:159]
	v_cvt_f32_ubyte3_e32 v135, v137
	v_cvt_f32_ubyte2_e32 v134, v137
	v_cvt_f32_ubyte1_e32 v159, v137
	v_cvt_f32_ubyte0_e32 v158, v137
	v_pk_mul_f32 v[136:137], v[140:141], v[158:159]
	v_pk_mul_f32 v[134:135], v[166:167], v[134:135]
	v_pk_mul_f32 v[54:55], v[54:55], v[136:137]
	v_pk_mul_f32 v[56:57], v[56:57], v[134:135]
	global_load_dwordx4 v[134:137], v[138:139], off offset:1024
	global_load_dwordx4 v[166:169], v[4:5], off offset:1024
	s_waitcnt vmcnt(0) lgkmcnt(0)
	v_cvt_f32_ubyte3_e32 v173, v134
	v_cvt_f32_ubyte2_e32 v165, v166
	v_cvt_f32_ubyte3_e32 v171, v166
	v_cvt_f32_ubyte0_e32 v2, v166
	v_cvt_f32_ubyte1_e32 v141, v166
	v_cvt_f32_ubyte0_e32 v158, v167
	v_cvt_f32_ubyte1_e32 v159, v167
	v_cvt_f32_ubyte2_e32 v170, v167
	v_cvt_f32_ubyte3_e32 v176, v167
	v_rcp_iflag_f32_e32 v166, v165
	v_rcp_iflag_f32_e32 v167, v171
	v_rcp_iflag_f32_e32 v140, v2
	v_rcp_iflag_f32_e32 v141, v141
	v_rcp_iflag_f32_e32 v158, v158
	v_rcp_iflag_f32_e32 v159, v159
	v_cvt_f32_ubyte2_e32 v172, v134
	v_rcp_iflag_f32_e32 v170, v170
	v_cvt_f32_ubyte1_e32 v175, v134
	v_cvt_f32_ubyte0_e32 v174, v134
	v_pk_mul_f32 v[166:167], v[166:167], v[172:173]
	v_rcp_iflag_f32_e32 v171, v176
	v_pk_mul_f32 v[140:141], v[140:141], v[174:175]
	v_pk_mul_f32 v[52:53], v[52:53], v[166:167]
	v_cvt_f32_ubyte1_e32 v167, v135
	v_cvt_f32_ubyte0_e32 v166, v135
	v_pk_mul_f32 v[50:51], v[50:51], v[140:141]
	v_cvt_f32_ubyte3_e32 v141, v135
	v_cvt_f32_ubyte2_e32 v140, v135
	v_pk_mul_f32 v[134:135], v[158:159], v[166:167]
	v_cvt_f32_ubyte0_e32 v2, v168
	v_pk_mul_f32 v[46:47], v[46:47], v[134:135]
	v_cvt_f32_ubyte1_e32 v135, v168
	v_cvt_f32_ubyte2_e32 v158, v168
	v_cvt_f32_ubyte3_e32 v159, v168
	v_pk_mul_f32 v[140:141], v[170:171], v[140:141]
	v_rcp_iflag_f32_e32 v134, v2
	v_rcp_iflag_f32_e32 v135, v135
	v_rcp_iflag_f32_e32 v158, v158
	v_rcp_iflag_f32_e32 v159, v159
	v_pk_mul_f32 v[48:49], v[48:49], v[140:141]
	v_cvt_f32_ubyte0_e32 v140, v169
	v_cvt_f32_ubyte1_e32 v141, v169
	v_cvt_f32_ubyte2_e32 v165, v169
	v_cvt_f32_ubyte3_e32 v167, v169
	v_rcp_iflag_f32_e32 v140, v140
	v_rcp_iflag_f32_e32 v141, v141
	v_rcp_iflag_f32_e32 v166, v165
	v_rcp_iflag_f32_e32 v167, v167
	v_cvt_f32_ubyte3_e32 v169, v136
	v_cvt_f32_ubyte2_e32 v168, v136
	v_cvt_f32_ubyte1_e32 v171, v136
	v_cvt_f32_ubyte0_e32 v170, v136
	v_pk_mul_f32 v[134:135], v[134:135], v[170:171]
	v_pk_mul_f32 v[158:159], v[158:159], v[168:169]
	v_pk_mul_f32 v[42:43], v[42:43], v[134:135]
	v_pk_mul_f32 v[44:45], v[44:45], v[158:159]
	v_cvt_f32_ubyte3_e32 v135, v137
	v_cvt_f32_ubyte2_e32 v134, v137
	v_cvt_f32_ubyte1_e32 v159, v137
	v_cvt_f32_ubyte0_e32 v158, v137
	v_pk_mul_f32 v[136:137], v[140:141], v[158:159]
	v_pk_mul_f32 v[134:135], v[166:167], v[134:135]
	v_pk_mul_f32 v[38:39], v[38:39], v[136:137]
	v_pk_mul_f32 v[40:41], v[40:41], v[134:135]
	global_load_dwordx4 v[134:137], v[138:139], off offset:2048
	global_load_dwordx4 v[166:169], v[4:5], off offset:2048
	s_waitcnt vmcnt(0) lgkmcnt(0)
;     DI void hook(f32x4 (&acc)[2][2][4][2], const Unit& u, int r, int wr, int wc, int fr_, int fq_) const {
;     ...
;                 const unsigned char* gp = Z + ((size_t)u.pm * 24 + (r - 1) * 8 + u.pn) * 65536 + (((((wr * 4 + wc) * 2 + ai) * 4 + m) * 64 + fq * 16 + fr) << 4);
;                 const u32x4 gn = *(const u32x4*)gp, gd = *(const u32x4*)(gp + 8 * 65536);
; #pragma unroll
;                 for (int bj = 0; bj < 2; ++bj) {
;                     f32x4 n0, n1, d0, d1; unpackq8(bj ? (u32x2){gn.z, gn.w} : (u32x2){gn.x, gn.y}, n0, n1); unpackq8(bj ? (u32x2){gd.z, gd.w} : (u32x2){gd.x, gd.y}, d0, d1);
; #pragma unroll
;                     for (int j = 0; j < 4; ++j) { acc[ai][bj][m][0][j] *= n0[j] * __builtin_amdgcn_rcpf(d0[j]); acc[ai][bj][m][1][j] *= n1[j] * __builtin_amdgcn_rcpf(d1[j]); }
;                 }
	v_cvt_f32_ubyte3_e32 v173, v134
	v_cvt_f32_ubyte2_e32 v165, v166
	v_cvt_f32_ubyte3_e32 v171, v166
	v_cvt_f32_ubyte0_e32 v2, v166
	v_cvt_f32_ubyte1_e32 v141, v166
	v_cvt_f32_ubyte0_e32 v158, v167
	v_cvt_f32_ubyte1_e32 v159, v167
	v_cvt_f32_ubyte2_e32 v170, v167
	v_cvt_f32_ubyte3_e32 v176, v167
	v_rcp_iflag_f32_e32 v166, v165
	v_rcp_iflag_f32_e32 v167, v171
	v_rcp_iflag_f32_e32 v140, v2
	v_rcp_iflag_f32_e32 v141, v141
	v_rcp_iflag_f32_e32 v158, v158
	v_rcp_iflag_f32_e32 v159, v159
	v_cvt_f32_ubyte2_e32 v172, v134
	v_rcp_iflag_f32_e32 v170, v170
	v_cvt_f32_ubyte1_e32 v175, v134
	v_cvt_f32_ubyte0_e32 v174, v134
	v_pk_mul_f32 v[166:167], v[166:167], v[172:173]
	v_rcp_iflag_f32_e32 v171, v176
	v_pk_mul_f32 v[140:141], v[140:141], v[174:175]
	v_pk_mul_f32 v[36:37], v[36:37], v[166:167]
	v_cvt_f32_ubyte1_e32 v167, v135
	v_cvt_f32_ubyte0_e32 v166, v135
	v_pk_mul_f32 v[34:35], v[34:35], v[140:141]
	v_cvt_f32_ubyte3_e32 v141, v135
	v_cvt_f32_ubyte2_e32 v140, v135
	v_pk_mul_f32 v[134:135], v[158:159], v[166:167]
	v_cvt_f32_ubyte0_e32 v2, v168
	v_pk_mul_f32 v[30:31], v[30:31], v[134:135]
	v_cvt_f32_ubyte1_e32 v135, v168
	v_cvt_f32_ubyte2_e32 v158, v168
	v_cvt_f32_ubyte3_e32 v159, v168
	v_pk_mul_f32 v[140:141], v[170:171], v[140:141]
	v_rcp_iflag_f32_e32 v134, v2
	v_rcp_iflag_f32_e32 v135, v135
	v_rcp_iflag_f32_e32 v158, v158
	v_rcp_iflag_f32_e32 v159, v159
	v_pk_mul_f32 v[32:33], v[32:33], v[140:141]
	v_cvt_f32_ubyte0_e32 v140, v169
	v_cvt_f32_ubyte1_e32 v141, v169
	v_cvt_f32_ubyte2_e32 v165, v169
	v_cvt_f32_ubyte3_e32 v167, v169
	v_rcp_iflag_f32_e32 v140, v140
	v_rcp_iflag_f32_e32 v141, v141
	v_rcp_iflag_f32_e32 v166, v165
	v_rcp_iflag_f32_e32 v167, v167
	v_cvt_f32_ubyte3_e32 v169, v136
	v_cvt_f32_ubyte2_e32 v168, v136
	v_cvt_f32_ubyte1_e32 v171, v136
	v_cvt_f32_ubyte0_e32 v170, v136
	v_pk_mul_f32 v[134:135], v[134:135], v[170:171]
	v_pk_mul_f32 v[158:159], v[158:159], v[168:169]
	v_pk_mul_f32 v[26:27], v[26:27], v[134:135]
	v_pk_mul_f32 v[28:29], v[28:29], v[158:159]
	v_cvt_f32_ubyte3_e32 v135, v137
	v_cvt_f32_ubyte2_e32 v134, v137
	v_cvt_f32_ubyte1_e32 v159, v137
	v_cvt_f32_ubyte0_e32 v158, v137
	v_pk_mul_f32 v[136:137], v[140:141], v[158:159]
	v_pk_mul_f32 v[134:135], v[166:167], v[134:135]
	v_pk_mul_f32 v[22:23], v[22:23], v[136:137]
	v_pk_mul_f32 v[24:25], v[24:25], v[134:135]
	global_load_dwordx4 v[134:137], v[138:139], off offset:3072
	s_nop 0
	global_load_dwordx4 v[138:141], v[4:5], off offset:3072
	s_waitcnt vmcnt(0) lgkmcnt(0)
	v_cvt_f32_ubyte1_e32 v171, v134
	v_cvt_f32_ubyte0_e32 v2, v138
	v_cvt_f32_ubyte1_e32 v5, v138
	v_cvt_f32_ubyte2_e32 v158, v138
	v_cvt_f32_ubyte3_e32 v159, v138
	v_rcp_iflag_f32_e32 v4, v2
	v_rcp_iflag_f32_e32 v5, v5
	v_cvt_f32_ubyte2_e32 v166, v139
	v_cvt_f32_ubyte3_e32 v167, v139
	v_rcp_iflag_f32_e32 v158, v158
	v_rcp_iflag_f32_e32 v159, v159
	v_cvt_f32_ubyte0_e32 v138, v139
	v_cvt_f32_ubyte1_e32 v165, v139
	v_rcp_iflag_f32_e32 v166, v166
	v_rcp_iflag_f32_e32 v167, v167
	v_rcp_iflag_f32_e32 v138, v138
	v_rcp_iflag_f32_e32 v139, v165
	v_cvt_f32_ubyte0_e32 v170, v134
	v_cvt_f32_ubyte3_e32 v169, v134
	v_cvt_f32_ubyte2_e32 v168, v134
	v_pk_mul_f32 v[4:5], v[4:5], v[170:171]
	v_pk_mul_f32 v[158:159], v[158:159], v[168:169]
	v_pk_mul_f32 v[18:19], v[18:19], v[4:5]
	v_cvt_f32_ubyte3_e32 v5, v135
	v_cvt_f32_ubyte2_e32 v4, v135
	v_pk_mul_f32 v[20:21], v[20:21], v[158:159]
	v_cvt_f32_ubyte1_e32 v159, v135
	v_cvt_f32_ubyte0_e32 v158, v135
	v_pk_mul_f32 v[4:5], v[166:167], v[4:5]
	v_pk_mul_f32 v[134:135], v[138:139], v[158:159]
	v_pk_mul_f32 v[16:17], v[16:17], v[4:5]
	v_cvt_f32_ubyte0_e32 v2, v140
	v_cvt_f32_ubyte1_e32 v5, v140
	v_cvt_f32_ubyte2_e32 v138, v140
	v_cvt_f32_ubyte3_e32 v139, v140
	v_rcp_iflag_f32_e32 v4, v2
	v_rcp_iflag_f32_e32 v5, v5
	v_rcp_iflag_f32_e32 v138, v138
	v_rcp_iflag_f32_e32 v139, v139
	v_pk_mul_f32 v[14:15], v[14:15], v[134:135]
	v_cvt_f32_ubyte0_e32 v134, v141
	v_cvt_f32_ubyte1_e32 v135, v141
	v_cvt_f32_ubyte2_e32 v140, v141
	v_cvt_f32_ubyte3_e32 v141, v141
	v_rcp_iflag_f32_e32 v134, v134
	v_rcp_iflag_f32_e32 v135, v135
	v_rcp_iflag_f32_e32 v140, v140
	v_rcp_iflag_f32_e32 v141, v141
	v_cvt_f32_ubyte3_e32 v159, v136
	v_cvt_f32_ubyte2_e32 v158, v136
	v_cvt_f32_ubyte1_e32 v167, v136
	v_cvt_f32_ubyte0_e32 v166, v136
	v_pk_mul_f32 v[4:5], v[4:5], v[166:167]
	v_pk_mul_f32 v[138:139], v[138:139], v[158:159]
	v_pk_mul_f32 v[10:11], v[10:11], v[4:5]
	v_pk_mul_f32 v[12:13], v[12:13], v[138:139]
	v_cvt_f32_ubyte3_e32 v5, v137
	v_cvt_f32_ubyte2_e32 v4, v137
	v_cvt_f32_ubyte1_e32 v139, v137
	v_cvt_f32_ubyte0_e32 v138, v137
	v_pk_mul_f32 v[134:135], v[134:135], v[138:139]
	v_pk_mul_f32 v[4:5], v[140:141], v[4:5]
	v_pk_mul_f32 v[6:7], v[6:7], v[134:135]
	v_pk_mul_f32 v[8:9], v[8:9], v[4:5]

; DI u32x4 pack8(const f32x4 v0, const f32x4 v1) { u32x4 w; w.x = pk2(v0[0], v0[1]); w.y = pk2(v0[2], v0[3]); w.z = pk2(v1[0], v1[1]); w.w = pk2(v1[2], v1[3]); return w; }
;     DI void operator()(const f32x4 (&acc)[2][2][4][2], const Unit& u, int wr, int wc, int fr, int fq, const LAS float* rsl) const {
;     ...
;                 const int row = row0 + ai * HALF + m * 16;
;                 const u32x4 gs = *(const u32x4*)(Z + ((size_t)u.pm * 24 + r * 8 + u.pn) * 65536 + (((((wr * 4 + wc) * 2 + ai) * 4 + m) * 64 + fq * 16 + fr) << 4));
; #pragma unroll
;                 for (int bj = 0; bj < 2; ++bj) {
;                     f32x4 s0, s1; unpackq8(bj ? (u32x2){gs.z, gs.w} : (u32x2){gs.x, gs.y}, s0, s1);
;                     const f32x4 v0 = acc[ai][bj][m][0] * (s0 * (1.0f / 255.0f)), v1 = acc[ai][bj][m][1] * (s1 * (1.0f / 255.0f));
;                     if (u.ks < 0) *(u32x4*)(act + (size_t)row * DM + col0 + bj * HALF) = pack8(v0, v1);
;                     else { float* pp = part + ((size_t)u.ks * MS + (row - MP)) * DM + col0 + bj * HALF; *(f32x4*)pp = v0; *(f32x4*)(pp + 4) = v1; }
.LBB0_910:
	s_lshl_b32 s8, s12, 3
	s_and_b64 s[4:5], s[56:57], exec
	s_cselect_b32 s4, 16, s8
	s_add_u32 s4, s34, s4
	s_addc_u32 s5, s35, 0
	s_lshl_b64 s[4:5], s[4:5], 16
	s_add_u32 s4, s71, s4
	s_addc_u32 s5, s72, s5
	v_lshl_add_u64 v[140:141], s[4:5], 0, v[150:151]
	global_load_dwordx4 v[134:137], v[140:141], off
	v_lshl_add_u32 v138, s11, 8, v161
	v_ashrrev_i32_e32 v139, 31, v138
	s_brev_b32 s8, 31
	v_lshl_or_b32 v4, s88, 8, v163
	v_lshlrev_b64 v[158:159], 13, v[138:139]
	s_mov_b32 s9, -1
	v_ashrrev_i32_e32 v5, 31, v4
	v_lshl_add_u64 v[158:159], v[158:159], 0, s[8:9]
	s_mov_b64 s[8:9], -1
	s_and_b64 vcc, exec, s[54:55]
	s_waitcnt vmcnt(0) lgkmcnt(0)
	v_cvt_f32_ubyte3_e32 v167, v134
	v_cvt_f32_ubyte2_e32 v166, v134
	v_cvt_f32_ubyte1_e32 v169, v134
	v_cvt_f32_ubyte0_e32 v168, v134
	v_cvt_f32_ubyte3_e32 v171, v135
	v_cvt_f32_ubyte2_e32 v170, v135
	v_cvt_f32_ubyte1_e32 v173, v135
	v_cvt_f32_ubyte0_e32 v172, v135
	v_pk_mul_f32 v[134:135], v[168:169], s[96:97] op_sel_hi:[1,0]
	v_pk_mul_f32 v[166:167], v[166:167], s[96:97] op_sel_hi:[1,0]
	v_pk_mul_f32 v[130:131], v[130:131], v[134:135]
	v_pk_mul_f32 v[132:133], v[132:133], v[166:167]
	v_pk_mul_f32 v[134:135], v[172:173], s[96:97] op_sel_hi:[1,0]
	v_pk_mul_f32 v[166:167], v[170:171], s[96:97] op_sel_hi:[1,0]
	v_pk_mul_f32 v[126:127], v[126:127], v[134:135]
	v_pk_mul_f32 v[128:129], v[128:129], v[166:167]
	s_mov_b32 s97, 0x1000000
	s_cbranch_vccz .LBB0_912
	s_lshl_b64 s[8:9], s[12:13], 24
	s_add_u32 s8, s73, s8
	s_addc_u32 s9, s74, s9
	v_lshl_add_u64 v[134:135], s[8:9], 0, v[158:159]
	v_lshl_add_u64 v[134:135], v[4:5], 2, v[134:135]
	global_store_dwordx4 v[134:135], v[130:133], off
	global_store_dwordx4 v[134:135], v[126:129], off offset:16
	s_mov_b64 s[8:9], 0
.LBB0_912:
	v_lshlrev_b64 v[134:135], 12, v[138:139]
	v_lshl_add_u64 v[134:135], s[44:45], 0, v[134:135]
	s_andn2_b64 vcc, exec, s[8:9]
	v_lshl_add_u64 v[134:135], v[4:5], 1, v[134:135]
	s_cbranch_vccnz .LBB0_914
	v_cvt_pk_bf16_f32 v130, v130, v131
	v_cvt_pk_bf16_f32 v131, v132, v133
	v_cvt_pk_bf16_f32 v132, v126, v127
	v_cvt_pk_bf16_f32 v133, v128, v129
	global_store_dwordx4 v[134:135], v[130:133], off
.LBB0_914:
	v_cvt_f32_ubyte3_e32 v127, v136
	v_cvt_f32_ubyte2_e32 v126, v136
	v_cvt_f32_ubyte1_e32 v129, v136
	v_cvt_f32_ubyte0_e32 v128, v136
	v_cvt_f32_ubyte3_e32 v131, v137
	v_cvt_f32_ubyte2_e32 v130, v137
	v_cvt_f32_ubyte1_e32 v133, v137
	v_cvt_f32_ubyte0_e32 v132, v137
	v_pk_mul_f32 v[128:129], v[128:129], s[96:97] op_sel_hi:[1,0]
	v_pk_mul_f32 v[126:127], v[126:127], s[96:97] op_sel_hi:[1,0]
	v_pk_mul_f32 v[122:123], v[122:123], v[128:129]
	v_pk_mul_f32 v[124:125], v[124:125], v[126:127]
	v_pk_mul_f32 v[126:127], v[132:133], s[96:97] op_sel_hi:[1,0]
	v_pk_mul_f32 v[128:129], v[130:131], s[96:97] op_sel_hi:[1,0]
	v_cndmask_b32_e64 v2, 0, 1, s[54:55]
	v_pk_mul_f32 v[120:121], v[120:121], v[128:129]
	v_pk_mul_f32 v[118:119], v[118:119], v[126:127]
	v_cmp_ne_u32_e64 s[40:41], 1, v2
	s_andn2_b64 vcc, exec, s[54:55]
	s_mov_b64 s[8:9], -1
	s_cbranch_vccnz .LBB0_916
	s_lshl_b64 s[8:9], s[12:13], 24
	s_add_u32 s8, s73, s8
	s_addc_u32 s9, s74, s9
	v_lshl_add_u64 v[126:127], s[8:9], 0, v[158:159]
	v_lshl_add_u64 v[126:127], v[4:5], 2, v[126:127]
	s_mov_b64 s[8:9], 0
	global_store_dwordx4 v[126:127], v[122:125], off offset:512
	global_store_dwordx4 v[126:127], v[118:121], off offset:528
.LBB0_916:
	s_andn2_b64 vcc, exec, s[8:9]
	s_cbranch_vccnz .LBB0_918
	v_cvt_pk_bf16_f32 v122, v122, v123
	v_cvt_pk_bf16_f32 v123, v124, v125
	v_cvt_pk_bf16_f32 v124, v118, v119
	v_cvt_pk_bf16_f32 v125, v120, v121
	global_store_dwordx4 v[134:135], v[122:125], off offset:256
.LBB0_918:
	global_load_dwordx4 v[118:121], v[140:141], off offset:1024
	s_mov_b32 s8, 0xf8020000
	v_lshlrev_b64 v[122:123], 13, v[138:139]
	s_mov_b32 s9, -1
	s_and_b64 vcc, exec, s[40:41]
	v_lshl_add_u64 v[122:123], v[122:123], 0, s[8:9]
	s_mov_b64 s[8:9], -1
	s_waitcnt vmcnt(0) lgkmcnt(0)
	v_cvt_f32_ubyte3_e32 v125, v118
	v_cvt_f32_ubyte2_e32 v124, v118
	v_cvt_f32_ubyte1_e32 v127, v118
	v_cvt_f32_ubyte0_e32 v126, v118
	v_cvt_f32_ubyte3_e32 v129, v119
	v_cvt_f32_ubyte2_e32 v128, v119
	v_cvt_f32_ubyte1_e32 v131, v119
	v_cvt_f32_ubyte0_e32 v130, v119
	v_pk_mul_f32 v[118:119], v[126:127], s[96:97] op_sel_hi:[1,0]
	v_pk_mul_f32 v[124:125], v[124:125], s[96:97] op_sel_hi:[1,0]
	v_pk_mul_f32 v[126:127], v[130:131], s[96:97] op_sel_hi:[1,0]
	v_pk_mul_f32 v[128:129], v[128:129], s[96:97] op_sel_hi:[1,0]
	v_pk_mul_f32 v[116:117], v[116:117], v[124:125]
	v_pk_mul_f32 v[114:115], v[114:115], v[118:119]
	v_pk_mul_f32 v[112:113], v[112:113], v[128:129]
	v_pk_mul_f32 v[110:111], v[110:111], v[126:127]
	s_cbranch_vccnz .LBB0_920
	s_lshl_b64 s[8:9], s[12:13], 24
	s_add_u32 s8, s73, s8
	s_addc_u32 s9, s74, s9
	v_lshl_add_u64 v[118:119], s[8:9], 0, v[122:123]
	v_lshl_add_u64 v[118:119], v[4:5], 2, v[118:119]
	s_mov_b64 s[8:9], 0
	global_store_dwordx4 v[118:119], v[114:117], off
	global_store_dwordx4 v[118:119], v[110:113], off offset:16
.LBB0_920:
	v_or_b32_e32 v118, 16, v138
	v_ashrrev_i32_e32 v119, 31, v118
	v_lshlrev_b64 v[118:119], 12, v[118:119]
	v_lshl_add_u64 v[118:119], s[44:45], 0, v[118:119]
	s_andn2_b64 vcc, exec, s[8:9]
	v_lshl_add_u64 v[118:119], v[4:5], 1, v[118:119]
	s_cbranch_vccnz .LBB0_922
	v_cvt_pk_bf16_f32 v114, v114, v115
	v_cvt_pk_bf16_f32 v115, v116, v117
	v_cvt_pk_bf16_f32 v116, v110, v111
	v_cvt_pk_bf16_f32 v117, v112, v113
	global_store_dwordx4 v[118:119], v[114:117], off
; DI u32x4 pack8(const f32x4 v0, const f32x4 v1) { u32x4 w; w.x = pk2(v0[0], v0[1]); w.y = pk2(v0[2], v0[3]); w.z = pk2(v1[0], v1[1]); w.w = pk2(v1[2], v1[3]); return w; }
;     DI void operator()(const f32x4 (&acc)[2][2][4][2], const Unit& u, int wr, int wc, int fr, int fq, const LAS float* rsl) const {
;     ...
;                 const int row = row0 + ai * HALF + m * 16;
;                 const u32x4 gs = *(const u32x4*)(Z + ((size_t)u.pm * 24 + r * 8 + u.pn) * 65536 + (((((wr * 4 + wc) * 2 + ai) * 4 + m) * 64 + fq * 16 + fr) << 4));
; #pragma unroll
;                 for (int bj = 0; bj < 2; ++bj) {
;                     f32x4 s0, s1; unpackq8(bj ? (u32x2){gs.z, gs.w} : (u32x2){gs.x, gs.y}, s0, s1);
;                     const f32x4 v0 = acc[ai][bj][m][0] * (s0 * (1.0f / 255.0f)), v1 = acc[ai][bj][m][1] * (s1 * (1.0f / 255.0f));
;                     if (u.ks < 0) *(u32x4*)(act + (size_t)row * DM + col0 + bj * HALF) = pack8(v0, v1);
;                     else { float* pp = part + ((size_t)u.ks * MS + (row - MP)) * DM + col0 + bj * HALF; *(f32x4*)pp = v0; *(f32x4*)(pp + 4) = v1; }
.LBB0_922:
	v_cvt_f32_ubyte3_e32 v111, v120
	v_cvt_f32_ubyte2_e32 v110, v120
	v_cvt_f32_ubyte1_e32 v113, v120
	v_cvt_f32_ubyte0_e32 v112, v120
	v_cvt_f32_ubyte3_e32 v115, v121
	v_cvt_f32_ubyte2_e32 v114, v121
	v_cvt_f32_ubyte1_e32 v117, v121
	v_cvt_f32_ubyte0_e32 v116, v121
	v_pk_mul_f32 v[112:113], v[112:113], s[96:97] op_sel_hi:[1,0]
	v_pk_mul_f32 v[110:111], v[110:111], s[96:97] op_sel_hi:[1,0]
	v_pk_mul_f32 v[106:107], v[106:107], v[112:113]
	v_pk_mul_f32 v[108:109], v[108:109], v[110:111]
	v_pk_mul_f32 v[110:111], v[116:117], s[96:97] op_sel_hi:[1,0]
	v_pk_mul_f32 v[112:113], v[114:115], s[96:97] op_sel_hi:[1,0]
	v_pk_mul_f32 v[102:103], v[102:103], v[110:111]
	v_pk_mul_f32 v[104:105], v[104:105], v[112:113]
	s_and_b64 vcc, exec, s[40:41]
	s_mov_b64 s[8:9], -1
	s_cbranch_vccnz .LBB0_924
	s_lshl_b64 s[8:9], s[12:13], 24
	s_add_u32 s8, s73, s8
	s_addc_u32 s9, s74, s9
	v_lshl_add_u64 v[110:111], s[8:9], 0, v[122:123]
	v_lshl_add_u64 v[110:111], v[4:5], 2, v[110:111]
	s_mov_b64 s[8:9], 0
	global_store_dwordx4 v[110:111], v[106:109], off offset:512
	global_store_dwordx4 v[110:111], v[102:105], off offset:528
.LBB0_924:
	s_andn2_b64 vcc, exec, s[8:9]
	s_cbranch_vccnz .LBB0_926
	v_cvt_pk_bf16_f32 v106, v106, v107
	v_cvt_pk_bf16_f32 v107, v108, v109
	v_cvt_pk_bf16_f32 v108, v102, v103
	v_cvt_pk_bf16_f32 v109, v104, v105
	global_store_dwordx4 v[118:119], v[106:109], off offset:256
.LBB0_926:
	global_load_dwordx4 v[102:105], v[140:141], off offset:2048
	s_mov_b32 s8, 0xf8040000
	v_lshlrev_b64 v[106:107], 13, v[138:139]
	s_mov_b32 s9, -1
	s_and_b64 vcc, exec, s[40:41]
	v_lshl_add_u64 v[106:107], v[106:107], 0, s[8:9]
	s_mov_b64 s[8:9], -1
	s_waitcnt vmcnt(0) lgkmcnt(0)
	v_cvt_f32_ubyte3_e32 v109, v102
	v_cvt_f32_ubyte2_e32 v108, v102
	v_cvt_f32_ubyte1_e32 v111, v102
	v_cvt_f32_ubyte0_e32 v110, v102
	v_cvt_f32_ubyte3_e32 v113, v103
	v_cvt_f32_ubyte2_e32 v112, v103
	v_cvt_f32_ubyte1_e32 v115, v103
	v_cvt_f32_ubyte0_e32 v114, v103
	v_pk_mul_f32 v[102:103], v[110:111], s[96:97] op_sel_hi:[1,0]
	v_pk_mul_f32 v[108:109], v[108:109], s[96:97] op_sel_hi:[1,0]
	v_pk_mul_f32 v[110:111], v[114:115], s[96:97] op_sel_hi:[1,0]
	v_pk_mul_f32 v[112:113], v[112:113], s[96:97] op_sel_hi:[1,0]
	v_pk_mul_f32 v[100:101], v[100:101], v[108:109]
	v_pk_mul_f32 v[98:99], v[98:99], v[102:103]
	v_pk_mul_f32 v[96:97], v[96:97], v[112:113]
	v_pk_mul_f32 v[94:95], v[94:95], v[110:111]
	s_cbranch_vccnz .LBB0_928
	s_lshl_b64 s[8:9], s[12:13], 24
	s_add_u32 s8, s73, s8
	s_addc_u32 s9, s74, s9
	v_lshl_add_u64 v[102:103], s[8:9], 0, v[106:107]
	v_lshl_add_u64 v[102:103], v[4:5], 2, v[102:103]
	s_mov_b64 s[8:9], 0
	global_store_dwordx4 v[102:103], v[98:101], off
	global_store_dwordx4 v[102:103], v[94:97], off offset:16
.LBB0_928:
	v_or_b32_e32 v102, 32, v138
	v_ashrrev_i32_e32 v103, 31, v102
	v_lshlrev_b64 v[102:103], 12, v[102:103]
	v_lshl_add_u64 v[102:103], s[44:45], 0, v[102:103]
	s_andn2_b64 vcc, exec, s[8:9]
	v_lshl_add_u64 v[102:103], v[4:5], 1, v[102:103]
	s_cbranch_vccnz .LBB0_930
	v_cvt_pk_bf16_f32 v98, v98, v99
	v_cvt_pk_bf16_f32 v99, v100, v101
	v_cvt_pk_bf16_f32 v100, v94, v95
	v_cvt_pk_bf16_f32 v101, v96, v97
	global_store_dwordx4 v[102:103], v[98:101], off
.LBB0_930:
	v_cvt_f32_ubyte3_e32 v95, v104
	v_cvt_f32_ubyte2_e32 v94, v104
	v_cvt_f32_ubyte1_e32 v97, v104
	v_cvt_f32_ubyte0_e32 v96, v104
	v_cvt_f32_ubyte3_e32 v99, v105
	v_cvt_f32_ubyte2_e32 v98, v105
	v_cvt_f32_ubyte1_e32 v101, v105
	v_cvt_f32_ubyte0_e32 v100, v105
	v_pk_mul_f32 v[96:97], v[96:97], s[96:97] op_sel_hi:[1,0]
	v_pk_mul_f32 v[94:95], v[94:95], s[96:97] op_sel_hi:[1,0]
	v_pk_mul_f32 v[90:91], v[90:91], v[96:97]
	v_pk_mul_f32 v[92:93], v[92:93], v[94:95]
	v_pk_mul_f32 v[94:95], v[100:101], s[96:97] op_sel_hi:[1,0]
	v_pk_mul_f32 v[96:97], v[98:99], s[96:97] op_sel_hi:[1,0]
	v_pk_mul_f32 v[86:87], v[86:87], v[94:95]
	v_pk_mul_f32 v[88:89], v[88:89], v[96:97]
	s_and_b64 vcc, exec, s[40:41]
	s_mov_b64 s[8:9], -1
	s_cbranch_vccnz .LBB0_932
	s_lshl_b64 s[8:9], s[12:13], 24
	s_add_u32 s8, s73, s8
	s_addc_u32 s9, s74, s9
	v_lshl_add_u64 v[94:95], s[8:9], 0, v[106:107]
	v_lshl_add_u64 v[94:95], v[4:5], 2, v[94:95]
	s_mov_b64 s[8:9], 0
	global_store_dwordx4 v[94:95], v[90:93], off offset:512
	global_store_dwordx4 v[94:95], v[86:89], off offset:528
.LBB0_932:
	s_andn2_b64 vcc, exec, s[8:9]
	s_cbranch_vccnz .LBB0_934
	v_cvt_pk_bf16_f32 v90, v90, v91
	v_cvt_pk_bf16_f32 v91, v92, v93
	v_cvt_pk_bf16_f32 v92, v86, v87
	v_cvt_pk_bf16_f32 v93, v88, v89
	global_store_dwordx4 v[102:103], v[90:93], off offset:256
.LBB0_934:
	global_load_dwordx4 v[86:89], v[140:141], off offset:3072
	s_mov_b32 s8, 0xf8060000
	v_lshlrev_b64 v[90:91], 13, v[138:139]
	s_mov_b32 s9, -1
	s_and_b64 vcc, exec, s[40:41]
	v_lshl_add_u64 v[90:91], v[90:91], 0, s[8:9]
	s_mov_b64 s[8:9], -1
	s_waitcnt vmcnt(0) lgkmcnt(0)
	v_cvt_f32_ubyte3_e32 v93, v86
	v_cvt_f32_ubyte2_e32 v92, v86
	v_cvt_f32_ubyte1_e32 v95, v86
	v_cvt_f32_ubyte0_e32 v94, v86
	v_cvt_f32_ubyte3_e32 v97, v87
	v_cvt_f32_ubyte2_e32 v96, v87
	v_cvt_f32_ubyte1_e32 v99, v87
	v_cvt_f32_ubyte0_e32 v98, v87
	v_pk_mul_f32 v[86:87], v[94:95], s[96:97] op_sel_hi:[1,0]
	v_pk_mul_f32 v[92:93], v[92:93], s[96:97] op_sel_hi:[1,0]
	v_pk_mul_f32 v[94:95], v[98:99], s[96:97] op_sel_hi:[1,0]
	v_pk_mul_f32 v[96:97], v[96:97], s[96:97] op_sel_hi:[1,0]
	v_pk_mul_f32 v[84:85], v[84:85], v[92:93]
	v_pk_mul_f32 v[82:83], v[82:83], v[86:87]
	v_pk_mul_f32 v[80:81], v[80:81], v[96:97]
	v_pk_mul_f32 v[78:79], v[78:79], v[94:95]
	s_cbranch_vccnz .LBB0_936
	s_lshl_b64 s[8:9], s[12:13], 24
	s_add_u32 s8, s73, s8
	s_addc_u32 s9, s74, s9
	v_lshl_add_u64 v[86:87], s[8:9], 0, v[90:91]
	v_lshl_add_u64 v[86:87], v[4:5], 2, v[86:87]
	s_mov_b64 s[8:9], 0
	global_store_dwordx4 v[86:87], v[82:85], off
	global_store_dwordx4 v[86:87], v[78:81], off offset:16
; DI u32x4 pack8(const f32x4 v0, const f32x4 v1) { u32x4 w; w.x = pk2(v0[0], v0[1]); w.y = pk2(v0[2], v0[3]); w.z = pk2(v1[0], v1[1]); w.w = pk2(v1[2], v1[3]); return w; }
;     DI void operator()(const f32x4 (&acc)[2][2][4][2], const Unit& u, int wr, int wc, int fr, int fq, const LAS float* rsl) const {
;     ...
;                 const int row = row0 + ai * HALF + m * 16;
;                 const u32x4 gs = *(const u32x4*)(Z + ((size_t)u.pm * 24 + r * 8 + u.pn) * 65536 + (((((wr * 4 + wc) * 2 + ai) * 4 + m) * 64 + fq * 16 + fr) << 4));
; #pragma unroll
;                 for (int bj = 0; bj < 2; ++bj) {
;                     f32x4 s0, s1; unpackq8(bj ? (u32x2){gs.z, gs.w} : (u32x2){gs.x, gs.y}, s0, s1);
;                     const f32x4 v0 = acc[ai][bj][m][0] * (s0 * (1.0f / 255.0f)), v1 = acc[ai][bj][m][1] * (s1 * (1.0f / 255.0f));
;                     if (u.ks < 0) *(u32x4*)(act + (size_t)row * DM + col0 + bj * HALF) = pack8(v0, v1);
;                     else { float* pp = part + ((size_t)u.ks * MS + (row - MP)) * DM + col0 + bj * HALF; *(f32x4*)pp = v0; *(f32x4*)(pp + 4) = v1; }
.LBB0_936:
	v_or_b32_e32 v86, 48, v138
	v_ashrrev_i32_e32 v87, 31, v86
	v_lshlrev_b64 v[86:87], 12, v[86:87]
	v_lshl_add_u64 v[86:87], s[44:45], 0, v[86:87]
	s_andn2_b64 vcc, exec, s[8:9]
	v_lshl_add_u64 v[86:87], v[4:5], 1, v[86:87]
	s_cbranch_vccnz .LBB0_938
	v_cvt_pk_bf16_f32 v82, v82, v83
	v_cvt_pk_bf16_f32 v83, v84, v85
	v_cvt_pk_bf16_f32 v84, v78, v79
	v_cvt_pk_bf16_f32 v85, v80, v81
	global_store_dwordx4 v[86:87], v[82:85], off
.LBB0_938:
	v_cvt_f32_ubyte3_e32 v79, v88
	v_cvt_f32_ubyte2_e32 v78, v88
	v_cvt_f32_ubyte1_e32 v81, v88
	v_cvt_f32_ubyte0_e32 v80, v88
	v_cvt_f32_ubyte3_e32 v83, v89
	v_cvt_f32_ubyte2_e32 v82, v89
	v_cvt_f32_ubyte1_e32 v85, v89
	v_cvt_f32_ubyte0_e32 v84, v89
	v_pk_mul_f32 v[80:81], v[80:81], s[96:97] op_sel_hi:[1,0]
	v_pk_mul_f32 v[78:79], v[78:79], s[96:97] op_sel_hi:[1,0]
	v_pk_mul_f32 v[74:75], v[74:75], v[80:81]
	v_pk_mul_f32 v[76:77], v[76:77], v[78:79]
	v_pk_mul_f32 v[78:79], v[84:85], s[96:97] op_sel_hi:[1,0]
	v_pk_mul_f32 v[80:81], v[82:83], s[96:97] op_sel_hi:[1,0]
	v_pk_mul_f32 v[70:71], v[70:71], v[78:79]
	v_pk_mul_f32 v[72:73], v[72:73], v[80:81]
	s_and_b64 vcc, exec, s[40:41]
	s_mov_b64 s[8:9], -1
	s_cbranch_vccnz .LBB0_940
	s_lshl_b64 s[8:9], s[12:13], 24
	s_add_u32 s8, s73, s8
	s_addc_u32 s9, s74, s9
	v_lshl_add_u64 v[78:79], s[8:9], 0, v[90:91]
	v_lshl_add_u64 v[78:79], v[4:5], 2, v[78:79]
	s_mov_b64 s[8:9], 0
	global_store_dwordx4 v[78:79], v[74:77], off offset:512
	global_store_dwordx4 v[78:79], v[70:73], off offset:528
.LBB0_940:
	s_andn2_b64 vcc, exec, s[8:9]
	s_cbranch_vccnz .LBB0_942
	v_cvt_pk_bf16_f32 v74, v74, v75
	v_cvt_pk_bf16_f32 v75, v76, v77
	v_cvt_pk_bf16_f32 v76, v70, v71
	v_cvt_pk_bf16_f32 v77, v72, v73
	global_store_dwordx4 v[86:87], v[74:77], off offset:256
.LBB0_942:
	s_nop 1
	v_lshl_add_u64 v[74:75], s[4:5], 0, v[152:153]
	v_add_co_u32_e32 v70, vcc, 0x1000, v74
	s_mov_b32 s4, 0xf8100000
	s_nop 0
	v_addc_co_u32_e32 v71, vcc, 0, v75, vcc
	global_load_dwordx4 v[70:73], v[70:71], off
	v_lshlrev_b64 v[76:77], 13, v[138:139]
	s_mov_b32 s5, -1
	v_lshl_add_u64 v[76:77], v[76:77], 0, s[4:5]
	s_and_b64 vcc, exec, s[40:41]
	s_mov_b64 s[4:5], -1
	s_waitcnt vmcnt(0) lgkmcnt(0)
	v_cvt_f32_ubyte3_e32 v79, v70
	v_cvt_f32_ubyte2_e32 v78, v70
	v_cvt_f32_ubyte1_e32 v81, v70
	v_cvt_f32_ubyte0_e32 v80, v70
	v_cvt_f32_ubyte3_e32 v83, v71
	v_cvt_f32_ubyte2_e32 v82, v71
	v_cvt_f32_ubyte1_e32 v85, v71
	v_cvt_f32_ubyte0_e32 v84, v71
	v_pk_mul_f32 v[70:71], v[80:81], s[96:97] op_sel_hi:[1,0]
	v_pk_mul_f32 v[78:79], v[78:79], s[96:97] op_sel_hi:[1,0]
	v_pk_mul_f32 v[80:81], v[84:85], s[96:97] op_sel_hi:[1,0]
	v_pk_mul_f32 v[82:83], v[82:83], s[96:97] op_sel_hi:[1,0]
	v_pk_mul_f32 v[68:69], v[68:69], v[78:79]
	v_pk_mul_f32 v[66:67], v[66:67], v[70:71]
	v_pk_mul_f32 v[64:65], v[64:65], v[82:83]
	v_pk_mul_f32 v[62:63], v[62:63], v[80:81]
	s_cbranch_vccnz .LBB0_944
	s_lshl_b64 s[4:5], s[12:13], 24
	s_add_u32 s4, s73, s4
	s_addc_u32 s5, s74, s5
	v_lshl_add_u64 v[70:71], s[4:5], 0, v[76:77]
	v_lshl_add_u64 v[70:71], v[4:5], 2, v[70:71]
	s_mov_b64 s[4:5], 0
	global_store_dwordx4 v[70:71], v[66:69], off
	global_store_dwordx4 v[70:71], v[62:65], off offset:16
.LBB0_944:
	v_lshlrev_b64 v[70:71], 12, v[138:139]
	s_mov_b64 s[8:9], 0x80000
	v_lshl_add_u64 v[70:71], v[70:71], 0, s[8:9]
	v_lshl_add_u64 v[70:71], s[44:45], 0, v[70:71]
	s_andn2_b64 vcc, exec, s[4:5]
	v_lshl_add_u64 v[70:71], v[4:5], 1, v[70:71]
	s_cbranch_vccnz .LBB0_946
	v_cvt_pk_bf16_f32 v66, v66, v67
	v_cvt_pk_bf16_f32 v67, v68, v69
	v_cvt_pk_bf16_f32 v68, v62, v63
	v_cvt_pk_bf16_f32 v69, v64, v65
	global_store_dwordx4 v[70:71], v[66:69], off
.LBB0_946:
	v_cvt_f32_ubyte3_e32 v63, v72
	v_cvt_f32_ubyte2_e32 v62, v72
	v_cvt_f32_ubyte1_e32 v65, v72
	v_cvt_f32_ubyte0_e32 v64, v72
	v_cvt_f32_ubyte3_e32 v67, v73
	v_cvt_f32_ubyte2_e32 v66, v73
	v_cvt_f32_ubyte1_e32 v69, v73
	v_cvt_f32_ubyte0_e32 v68, v73
	v_pk_mul_f32 v[64:65], v[64:65], s[96:97] op_sel_hi:[1,0]
	v_pk_mul_f32 v[62:63], v[62:63], s[96:97] op_sel_hi:[1,0]
	v_pk_mul_f32 v[58:59], v[58:59], v[64:65]
	v_pk_mul_f32 v[60:61], v[60:61], v[62:63]
	v_pk_mul_f32 v[62:63], v[68:69], s[96:97] op_sel_hi:[1,0]
	v_pk_mul_f32 v[64:65], v[66:67], s[96:97] op_sel_hi:[1,0]
	v_pk_mul_f32 v[54:55], v[54:55], v[62:63]
	v_pk_mul_f32 v[56:57], v[56:57], v[64:65]
	s_and_b64 vcc, exec, s[40:41]
	s_mov_b64 s[4:5], -1
	s_cbranch_vccnz .LBB0_948
	s_lshl_b64 s[4:5], s[12:13], 24
	s_add_u32 s4, s73, s4
	s_addc_u32 s5, s74, s5
	v_lshl_add_u64 v[62:63], s[4:5], 0, v[76:77]
	v_lshl_add_u64 v[62:63], v[4:5], 2, v[62:63]
	s_mov_b64 s[4:5], 0
	global_store_dwordx4 v[62:63], v[58:61], off offset:512
	global_store_dwordx4 v[62:63], v[54:57], off offset:528
.LBB0_948:
	s_andn2_b64 vcc, exec, s[4:5]
	s_cbranch_vccnz .LBB0_950
	v_cvt_pk_bf16_f32 v58, v58, v59
	v_cvt_pk_bf16_f32 v59, v60, v61
	v_cvt_pk_bf16_f32 v60, v54, v55
	v_cvt_pk_bf16_f32 v61, v56, v57
	global_store_dwordx4 v[70:71], v[58:61], off offset:256
.LBB0_950:
	v_add_co_u32_e32 v54, vcc, 0x1000, v74
	s_mov_b32 s4, 0xf8120000
	s_nop 0
	v_addc_co_u32_e32 v55, vcc, 0, v75, vcc
	global_load_dwordx4 v[54:57], v[54:55], off offset:1024
	v_lshlrev_b64 v[58:59], 13, v[138:139]
	s_mov_b32 s5, -1
	v_lshl_add_u64 v[58:59], v[58:59], 0, s[4:5]
	s_and_b64 vcc, exec, s[40:41]
	s_mov_b64 s[4:5], -1
	s_waitcnt vmcnt(0) lgkmcnt(0)
	v_cvt_f32_ubyte3_e32 v61, v54
	v_cvt_f32_ubyte2_e32 v60, v54
	v_cvt_f32_ubyte1_e32 v63, v54
	v_cvt_f32_ubyte0_e32 v62, v54
	v_cvt_f32_ubyte3_e32 v65, v55
	v_cvt_f32_ubyte2_e32 v64, v55
	v_cvt_f32_ubyte1_e32 v67, v55
	v_cvt_f32_ubyte0_e32 v66, v55
	v_pk_mul_f32 v[54:55], v[62:63], s[96:97] op_sel_hi:[1,0]
	v_pk_mul_f32 v[60:61], v[60:61], s[96:97] op_sel_hi:[1,0]
	v_pk_mul_f32 v[62:63], v[66:67], s[96:97] op_sel_hi:[1,0]
	v_pk_mul_f32 v[64:65], v[64:65], s[96:97] op_sel_hi:[1,0]
	v_pk_mul_f32 v[52:53], v[52:53], v[60:61]
	v_pk_mul_f32 v[50:51], v[50:51], v[54:55]
	v_pk_mul_f32 v[48:49], v[48:49], v[64:65]
	v_pk_mul_f32 v[46:47], v[46:47], v[62:63]
	s_cbranch_vccnz .LBB0_952
	s_lshl_b64 s[4:5], s[12:13], 24
	s_add_u32 s4, s73, s4
	s_addc_u32 s5, s74, s5
	v_lshl_add_u64 v[54:55], s[4:5], 0, v[58:59]
	v_lshl_add_u64 v[54:55], v[4:5], 2, v[54:55]
	s_mov_b64 s[4:5], 0
	global_store_dwordx4 v[54:55], v[50:53], off
	global_store_dwordx4 v[54:55], v[46:49], off offset:16
; DI u32x4 pack8(const f32x4 v0, const f32x4 v1) { u32x4 w; w.x = pk2(v0[0], v0[1]); w.y = pk2(v0[2], v0[3]); w.z = pk2(v1[0], v1[1]); w.w = pk2(v1[2], v1[3]); return w; }
;     DI void operator()(const f32x4 (&acc)[2][2][4][2], const Unit& u, int wr, int wc, int fr, int fq, const LAS float* rsl) const {
;     ...
;                 const int row = row0 + ai * HALF + m * 16;
;                 const u32x4 gs = *(const u32x4*)(Z + ((size_t)u.pm * 24 + r * 8 + u.pn) * 65536 + (((((wr * 4 + wc) * 2 + ai) * 4 + m) * 64 + fq * 16 + fr) << 4));
; #pragma unroll
;                 for (int bj = 0; bj < 2; ++bj) {
;                     f32x4 s0, s1; unpackq8(bj ? (u32x2){gs.z, gs.w} : (u32x2){gs.x, gs.y}, s0, s1);
;                     const f32x4 v0 = acc[ai][bj][m][0] * (s0 * (1.0f / 255.0f)), v1 = acc[ai][bj][m][1] * (s1 * (1.0f / 255.0f));
;                     if (u.ks < 0) *(u32x4*)(act + (size_t)row * DM + col0 + bj * HALF) = pack8(v0, v1);
;                     else { float* pp = part + ((size_t)u.ks * MS + (row - MP)) * DM + col0 + bj * HALF; *(f32x4*)pp = v0; *(f32x4*)(pp + 4) = v1; }
.LBB0_952:
	v_lshlrev_b64 v[54:55], 12, v[138:139]
	s_mov_b64 s[8:9], 0x90000
	v_lshl_add_u64 v[54:55], v[54:55], 0, s[8:9]
	v_lshl_add_u64 v[54:55], s[44:45], 0, v[54:55]
	s_andn2_b64 vcc, exec, s[4:5]
	v_lshl_add_u64 v[54:55], v[4:5], 1, v[54:55]
	s_cbranch_vccnz .LBB0_954
	v_cvt_pk_bf16_f32 v50, v50, v51
	v_cvt_pk_bf16_f32 v51, v52, v53
	v_cvt_pk_bf16_f32 v52, v46, v47
	v_cvt_pk_bf16_f32 v53, v48, v49
	global_store_dwordx4 v[54:55], v[50:53], off
.LBB0_954:
	v_cvt_f32_ubyte3_e32 v47, v56
	v_cvt_f32_ubyte2_e32 v46, v56
	v_cvt_f32_ubyte1_e32 v49, v56
	v_cvt_f32_ubyte0_e32 v48, v56
	v_cvt_f32_ubyte3_e32 v51, v57
	v_cvt_f32_ubyte2_e32 v50, v57
	v_cvt_f32_ubyte1_e32 v53, v57
	v_cvt_f32_ubyte0_e32 v52, v57
	v_pk_mul_f32 v[48:49], v[48:49], s[96:97] op_sel_hi:[1,0]
	v_pk_mul_f32 v[46:47], v[46:47], s[96:97] op_sel_hi:[1,0]
	v_pk_mul_f32 v[42:43], v[42:43], v[48:49]
	v_pk_mul_f32 v[44:45], v[44:45], v[46:47]
	v_pk_mul_f32 v[46:47], v[52:53], s[96:97] op_sel_hi:[1,0]
	v_pk_mul_f32 v[48:49], v[50:51], s[96:97] op_sel_hi:[1,0]
	v_pk_mul_f32 v[38:39], v[38:39], v[46:47]
	v_pk_mul_f32 v[40:41], v[40:41], v[48:49]
	s_and_b64 vcc, exec, s[40:41]
	s_mov_b64 s[4:5], -1
	s_cbranch_vccnz .LBB0_956
	s_lshl_b64 s[4:5], s[12:13], 24
	s_add_u32 s4, s73, s4
	s_addc_u32 s5, s74, s5
	v_lshl_add_u64 v[46:47], s[4:5], 0, v[58:59]
	v_lshl_add_u64 v[46:47], v[4:5], 2, v[46:47]
	s_mov_b64 s[4:5], 0
	global_store_dwordx4 v[46:47], v[42:45], off offset:512
	global_store_dwordx4 v[46:47], v[38:41], off offset:528
.LBB0_956:
	s_andn2_b64 vcc, exec, s[4:5]
	s_cbranch_vccnz .LBB0_958
	v_cvt_pk_bf16_f32 v42, v42, v43
	v_cvt_pk_bf16_f32 v43, v44, v45
	v_cvt_pk_bf16_f32 v44, v38, v39
	v_cvt_pk_bf16_f32 v45, v40, v41
	global_store_dwordx4 v[54:55], v[42:45], off offset:256
.LBB0_958:
	v_add_co_u32_e32 v38, vcc, 0x1000, v74
	s_mov_b32 s4, 0xf8140000
	s_nop 0
	v_addc_co_u32_e32 v39, vcc, 0, v75, vcc
	global_load_dwordx4 v[38:41], v[38:39], off offset:2048
	v_lshlrev_b64 v[42:43], 13, v[138:139]
	s_mov_b32 s5, -1
	v_lshl_add_u64 v[42:43], v[42:43], 0, s[4:5]
	s_and_b64 vcc, exec, s[40:41]
	s_mov_b64 s[4:5], -1
	s_waitcnt vmcnt(0) lgkmcnt(0)
	v_cvt_f32_ubyte3_e32 v45, v38
	v_cvt_f32_ubyte2_e32 v44, v38
	v_cvt_f32_ubyte1_e32 v47, v38
	v_cvt_f32_ubyte0_e32 v46, v38
	v_cvt_f32_ubyte3_e32 v49, v39
	v_cvt_f32_ubyte2_e32 v48, v39
	v_cvt_f32_ubyte1_e32 v51, v39
	v_cvt_f32_ubyte0_e32 v50, v39
	v_pk_mul_f32 v[38:39], v[46:47], s[96:97] op_sel_hi:[1,0]
	v_pk_mul_f32 v[44:45], v[44:45], s[96:97] op_sel_hi:[1,0]
	v_pk_mul_f32 v[46:47], v[50:51], s[96:97] op_sel_hi:[1,0]
	v_pk_mul_f32 v[48:49], v[48:49], s[96:97] op_sel_hi:[1,0]
	v_pk_mul_f32 v[36:37], v[36:37], v[44:45]
	v_pk_mul_f32 v[34:35], v[34:35], v[38:39]
	v_pk_mul_f32 v[32:33], v[32:33], v[48:49]
	v_pk_mul_f32 v[30:31], v[30:31], v[46:47]
	s_cbranch_vccnz .LBB0_960
	s_lshl_b64 s[4:5], s[12:13], 24
	s_add_u32 s4, s73, s4
	s_addc_u32 s5, s74, s5
	v_lshl_add_u64 v[38:39], s[4:5], 0, v[42:43]
	v_lshl_add_u64 v[38:39], v[4:5], 2, v[38:39]
	s_mov_b64 s[4:5], 0
	global_store_dwordx4 v[38:39], v[34:37], off
	global_store_dwordx4 v[38:39], v[30:33], off offset:16
.LBB0_960:
	v_lshlrev_b64 v[38:39], 12, v[138:139]
	s_mov_b64 s[8:9], 0xa0000
	v_lshl_add_u64 v[38:39], v[38:39], 0, s[8:9]
	v_lshl_add_u64 v[38:39], s[44:45], 0, v[38:39]
	s_andn2_b64 vcc, exec, s[4:5]
	v_lshl_add_u64 v[38:39], v[4:5], 1, v[38:39]
	s_cbranch_vccnz .LBB0_962
	v_cvt_pk_bf16_f32 v34, v34, v35
	v_cvt_pk_bf16_f32 v35, v36, v37
	v_cvt_pk_bf16_f32 v36, v30, v31
	v_cvt_pk_bf16_f32 v37, v32, v33
	global_store_dwordx4 v[38:39], v[34:37], off
.LBB0_962:
	v_cvt_f32_ubyte3_e32 v31, v40
	v_cvt_f32_ubyte2_e32 v30, v40
	v_cvt_f32_ubyte1_e32 v33, v40
	v_cvt_f32_ubyte0_e32 v32, v40
	v_cvt_f32_ubyte3_e32 v35, v41
	v_cvt_f32_ubyte2_e32 v34, v41
	v_cvt_f32_ubyte1_e32 v37, v41
	v_cvt_f32_ubyte0_e32 v36, v41
	v_pk_mul_f32 v[32:33], v[32:33], s[96:97] op_sel_hi:[1,0]
	v_pk_mul_f32 v[30:31], v[30:31], s[96:97] op_sel_hi:[1,0]
	v_pk_mul_f32 v[26:27], v[26:27], v[32:33]
	v_pk_mul_f32 v[28:29], v[28:29], v[30:31]
	v_pk_mul_f32 v[30:31], v[36:37], s[96:97] op_sel_hi:[1,0]
	v_pk_mul_f32 v[32:33], v[34:35], s[96:97] op_sel_hi:[1,0]
	v_pk_mul_f32 v[22:23], v[22:23], v[30:31]
	v_pk_mul_f32 v[24:25], v[24:25], v[32:33]
	s_and_b64 vcc, exec, s[40:41]
	s_mov_b64 s[4:5], -1
	s_cbranch_vccnz .LBB0_964
	s_lshl_b64 s[4:5], s[12:13], 24
	s_add_u32 s4, s73, s4
	s_addc_u32 s5, s74, s5
	v_lshl_add_u64 v[30:31], s[4:5], 0, v[42:43]
	v_lshl_add_u64 v[30:31], v[4:5], 2, v[30:31]
	s_mov_b64 s[4:5], 0
	global_store_dwordx4 v[30:31], v[26:29], off offset:512
	global_store_dwordx4 v[30:31], v[22:25], off offset:528
.LBB0_964:
	s_andn2_b64 vcc, exec, s[4:5]
	s_cbranch_vccnz .LBB0_966
	v_cvt_pk_bf16_f32 v26, v26, v27
	v_cvt_pk_bf16_f32 v27, v28, v29
	v_cvt_pk_bf16_f32 v28, v22, v23
	v_cvt_pk_bf16_f32 v29, v24, v25
	global_store_dwordx4 v[38:39], v[26:29], off offset:256
.LBB0_966:
	v_add_co_u32_e32 v22, vcc, 0x1000, v74
	s_mov_b32 s4, 0xf8160000
	s_nop 0
	v_addc_co_u32_e32 v23, vcc, 0, v75, vcc
	global_load_dwordx4 v[22:25], v[22:23], off offset:3072
	v_lshlrev_b64 v[26:27], 13, v[138:139]
	s_mov_b32 s5, -1
	v_lshl_add_u64 v[26:27], v[26:27], 0, s[4:5]
	s_and_b64 vcc, exec, s[40:41]
	s_mov_b64 s[4:5], -1
	s_waitcnt vmcnt(0) lgkmcnt(0)
	v_cvt_f32_ubyte3_e32 v29, v22
	v_cvt_f32_ubyte2_e32 v28, v22
	v_cvt_f32_ubyte1_e32 v31, v22
	v_cvt_f32_ubyte0_e32 v30, v22
	v_cvt_f32_ubyte3_e32 v33, v23
	v_cvt_f32_ubyte2_e32 v32, v23
	v_cvt_f32_ubyte1_e32 v35, v23
	v_cvt_f32_ubyte0_e32 v34, v23
	v_pk_mul_f32 v[22:23], v[30:31], s[96:97] op_sel_hi:[1,0]
	v_pk_mul_f32 v[28:29], v[28:29], s[96:97] op_sel_hi:[1,0]
	v_pk_mul_f32 v[30:31], v[34:35], s[96:97] op_sel_hi:[1,0]
	v_pk_mul_f32 v[32:33], v[32:33], s[96:97] op_sel_hi:[1,0]
	v_pk_mul_f32 v[20:21], v[20:21], v[28:29]
	v_pk_mul_f32 v[18:19], v[18:19], v[22:23]
	v_pk_mul_f32 v[16:17], v[16:17], v[32:33]
	v_pk_mul_f32 v[14:15], v[14:15], v[30:31]
	s_cbranch_vccnz .LBB0_968
	s_lshl_b64 s[4:5], s[12:13], 24
	s_add_u32 s4, s73, s4
	s_addc_u32 s5, s74, s5
	v_lshl_add_u64 v[22:23], s[4:5], 0, v[26:27]
	v_lshl_add_u64 v[22:23], v[4:5], 2, v[22:23]
	s_mov_b64 s[4:5], 0
	global_store_dwordx4 v[22:23], v[18:21], off
	global_store_dwordx4 v[22:23], v[14:17], off offset:16
.LBB0_968:
	v_lshlrev_b64 v[22:23], 12, v[138:139]
	s_mov_b64 s[8:9], 0xb0000
	v_lshl_add_u64 v[22:23], v[22:23], 0, s[8:9]
	v_lshl_add_u64 v[22:23], s[44:45], 0, v[22:23]
	s_andn2_b64 vcc, exec, s[4:5]
	v_lshl_add_u64 v[22:23], v[4:5], 1, v[22:23]
	s_cbranch_vccnz .LBB0_970
	v_cvt_pk_bf16_f32 v18, v18, v19
	v_cvt_pk_bf16_f32 v19, v20, v21
	v_cvt_pk_bf16_f32 v20, v14, v15
	v_cvt_pk_bf16_f32 v21, v16, v17
	global_store_dwordx4 v[22:23], v[18:21], off

; DI u32x4 pack8(const f32x4 v0, const f32x4 v1) { u32x4 w; w.x = pk2(v0[0], v0[1]); w.y = pk2(v0[2], v0[3]); w.z = pk2(v1[0], v1[1]); w.w = pk2(v1[2], v1[3]); return w; }
;     DI void operator()(const f32x4 (&acc)[2][2][4][2], const Unit& u, int wr, int wc, int fr, int fq, const LAS float* rsl) const {
;     ...
;                 for (int bj = 0; bj < 2; ++bj) {
;                     f32x4 s0, s1; unpackq8(bj ? (u32x2){gs.z, gs.w} : (u32x2){gs.x, gs.y}, s0, s1);
;                     const f32x4 v0 = acc[ai][bj][m][0] * (s0 * (1.0f / 255.0f)), v1 = acc[ai][bj][m][1] * (s1 * (1.0f / 255.0f));
;                     if (u.ks < 0) *(u32x4*)(act + (size_t)row * DM + col0 + bj * HALF) = pack8(v0, v1);
;                     else { float* pp = part + ((size_t)u.ks * MS + (row - MP)) * DM + col0 + bj * HALF; *(f32x4*)pp = v0; *(f32x4*)(pp + 4) = v1; }
.LBB0_973:
	s_lshl_b64 s[4:5], s[12:13], 24
	s_add_u32 s4, s73, s4
	s_addc_u32 s5, s74, s5
	v_lshl_add_u64 v[14:15], s[4:5], 0, v[26:27]
	v_lshl_add_u64 v[4:5], v[4:5], 2, v[14:15]
	global_store_dwordx4 v[4:5], v[10:13], off offset:512
	global_store_dwordx4 v[4:5], v[6:9], off offset:528
	s_cbranch_execnz .LBB0_972
.LBB0_974:
	v_cvt_pk_bf16_f32 v4, v10, v11
	v_cvt_pk_bf16_f32 v5, v12, v13
	v_cvt_pk_bf16_f32 v6, v6, v7
	v_cvt_pk_bf16_f32 v7, v8, v9
	global_store_dwordx4 v[22:23], v[4:7], off offset:256
	s_andn2_b64 vcc, exec, s[52:53]
	s_mov_b64 s[4:5], -1
	s_cbranch_vccnz .LBB0_889

; DI u32x4 pack8(const f32x4 v0, const f32x4 v1) { u32x4 w; w.x = pk2(v0[0], v0[1]); w.y = pk2(v0[2], v0[3]); w.z = pk2(v1[0], v1[1]); w.w = pk2(v1[2], v1[3]); return w; }
; DI void phase_postD(const Ctx& c) {
;     ...
;     for (size_t i = (size_t)c.bid * NTHR + c.tid; i < total; i += (size_t)c.G * NTHR) {
;         const f32x4* p = (const f32x4*)part + 2 * i; const size_t st = (size_t)MS * DM / 4;
;         const f32x4 v0 = p[0] + p[st] + p[2 * st], v1 = p[1] + p[st + 1] + p[2 * st + 1];
;         ((u32x4*)act)[i] = pg8::pack8(v0, v1);
;     }
.LBB0_1030:
	v_add_co_u32_e32 v10, vcc, 0xfdfffff0, v8
	s_mov_b32 s10, 0xfe000000
	s_nop 0
	v_addc_co_u32_e32 v11, vcc, -1, v9, vcc
	v_add_co_u32_e32 v14, vcc, 0xfefffff0, v8
	global_load_dwordx4 v[10:13], v[10:11], off
	s_nop 0
	v_addc_co_u32_e32 v15, vcc, -1, v9, vcc
	global_load_dwordx4 v[14:17], v[14:15], off
	v_lshl_add_u64 v[4:5], v[4:5], 0, s[8:9]
	s_waitcnt vmcnt(0) lgkmcnt(0)
	v_pk_add_f32 v[14:15], v[10:11], v[14:15]
	v_add_co_u32_e32 v10, vcc, -16, v8
	v_pk_add_f32 v[16:17], v[12:13], v[16:17]
	s_nop 0
	v_addc_co_u32_e32 v11, vcc, -1, v9, vcc
	global_load_dwordx4 v[10:13], v[10:11], off
	s_waitcnt vmcnt(0) lgkmcnt(0)
	v_pk_add_f32 v[20:21], v[14:15], v[10:11]
	v_add_co_u32_e32 v10, vcc, s10, v8
	s_mov_b32 s10, 0xff000000
	s_nop 0
	v_addc_co_u32_e32 v11, vcc, -1, v9, vcc
	v_add_co_u32_e32 v14, vcc, s10, v8
	v_pk_add_f32 v[18:19], v[16:17], v[12:13]
	s_nop 0
	v_addc_co_u32_e32 v15, vcc, -1, v9, vcc
	global_load_dwordx4 v[10:13], v[10:11], off
	s_mov_b64 s[10:11], 0x7ffff
	global_load_dwordx4 v[14:17], v[14:15], off
	v_cmp_lt_u64_e32 vcc, s[10:11], v[4:5]
	s_or_b64 s[40:41], vcc, s[40:41]
	s_waitcnt vmcnt(0) lgkmcnt(0)
	v_pk_add_f32 v[16:17], v[12:13], v[16:17]
	v_pk_add_f32 v[14:15], v[10:11], v[14:15]
	global_load_dwordx4 v[10:13], v[8:9], off
	v_lshl_add_u64 v[8:9], v[8:9], 0, s[38:39]
	s_waitcnt vmcnt(0) lgkmcnt(0)
	v_pk_add_f32 v[16:17], v[16:17], v[12:13]
	v_pk_add_f32 v[12:13], v[14:15], v[10:11]
	v_cvt_pk_bf16_f32 v10, v20, v21
	v_cvt_pk_bf16_f32 v11, v18, v19
	v_cvt_pk_bf16_f32 v12, v12, v13
	v_cvt_pk_bf16_f32 v13, v16, v17
	global_store_dwordx4 v[6:7], v[10:13], off
	v_lshl_add_u64 v[6:7], v[6:7], 0, s[34:35]
	s_andn2_b64 exec, exec, s[40:41]
	s_cbranch_execnz .LBB0_1030

;     DI void operator()(const f32x4 (&acc)[2][2][4][2], const Unit& u, int wr, int wc, int fr, int fq, const LAS float* rsl) const {
;     ...
;         if (!XF32 && u.ks < 0) {
; #pragma unroll
;             for (int ai = 0; ai < 2; ++ai)
; #pragma unroll
;                 for (int m = 0; m < 4; ++m)
; #pragma unroll
;                     for (int bj = 0; bj < 2; ++bj) xin[ai][m][bj] = *(const u32x4*)(act + (size_t)(row0 + ai * HALF + m * 16) * DM + col0 + bj * HALF);
;         }
.LBB0_1107:
	s_cmp_gt_i32 s12, -1
	v_lshl_add_u32 v216, s78, 8, v1
	v_lshl_or_b32 v214, s22, 8, v230
	s_cselect_b64 s[52:53], -1, 0
	v_ashrrev_i32_e32 v215, 31, v214
	s_and_b64 vcc, exec, s[52:53]
	v_ashrrev_i32_e32 v217, 31, v216
	s_cbranch_vccnz .LBB0_1109
	v_or_b32_e32 v88, 16, v216
	v_ashrrev_i32_e32 v89, 31, v88
	v_lshl_add_u64 v[84:85], v[214:215], 1, s[18:19]
	v_lshlrev_b64 v[86:87], 12, v[216:217]
	v_lshlrev_b64 v[88:89], 12, v[88:89]
	v_lshl_add_u64 v[86:87], v[84:85], 0, v[86:87]
	v_lshl_add_u64 v[88:89], v[84:85], 0, v[88:89]
	global_load_dwordx4 v[192:195], v[86:87], off
	global_load_dwordx4 v[188:191], v[86:87], off offset:256
	global_load_dwordx4 v[184:187], v[88:89], off
	global_load_dwordx4 v[180:183], v[88:89], off offset:256
	v_or_b32_e32 v88, 32, v216
	v_ashrrev_i32_e32 v89, 31, v88
	v_lshlrev_b64 v[88:89], 12, v[88:89]
	v_lshl_add_u64 v[88:89], v[84:85], 0, v[88:89]
	global_load_dwordx4 v[176:179], v[88:89], off
	global_load_dwordx4 v[172:175], v[88:89], off offset:256
	v_or_b32_e32 v88, 48, v216
	v_ashrrev_i32_e32 v89, 31, v88
	v_lshlrev_b64 v[88:89], 12, v[88:89]
	v_lshl_add_u64 v[84:85], v[84:85], 0, v[88:89]
	s_mov_b64 s[42:43], 0x80000
	v_add_co_u32_e32 v88, vcc, s77, v86
	global_load_dwordx4 v[168:171], v[84:85], off
	global_load_dwordx4 v[164:167], v[84:85], off offset:256
	v_lshl_add_u64 v[84:85], v[86:87], 0, s[42:43]
	v_addc_co_u32_e32 v89, vcc, 0, v87, vcc
	s_mov_b64 s[42:43], 0x90000
	global_load_dwordx4 v[160:163], v[88:89], off
	global_load_dwordx4 v[148:151], v[84:85], off offset:256
	v_lshl_add_u64 v[84:85], v[86:87], 0, s[42:43]
	s_mov_b32 s42, 0x90000
	v_add_co_u32_e32 v88, vcc, s42, v86
	s_mov_b64 s[42:43], 0xa0000
	s_nop 0
	v_addc_co_u32_e32 v89, vcc, 0, v87, vcc
	global_load_dwordx4 v[136:139], v[88:89], off
	global_load_dwordx4 v[124:127], v[84:85], off offset:256
	v_lshl_add_u64 v[84:85], v[86:87], 0, s[42:43]
	s_mov_b32 s42, 0xa0000
	v_add_co_u32_e32 v88, vcc, s42, v86
	s_mov_b64 s[42:43], 0xb0000
	s_nop 0
	v_addc_co_u32_e32 v89, vcc, 0, v87, vcc
	global_load_dwordx4 v[112:115], v[88:89], off
	global_load_dwordx4 v[104:107], v[84:85], off offset:256
	v_lshl_add_u64 v[84:85], v[86:87], 0, s[42:43]
	s_mov_b32 s42, 0xb0000
	v_add_co_u32_e32 v86, vcc, s42, v86
	s_nop 1
	v_addc_co_u32_e32 v87, vcc, 0, v87, vcc
	global_load_dwordx4 v[88:91], v[86:87], off
	s_nop 0
	global_load_dwordx4 v[84:87], v[84:85], off offset:256

; DI u32x4 pack8(const f32x4 v0, const f32x4 v1) { u32x4 w; w.x = pk2(v0[0], v0[1]); w.y = pk2(v0[2], v0[3]); w.z = pk2(v1[0], v1[1]); w.w = pk2(v1[2], v1[3]); return w; }
; DI void unpack8(const u32x4 w, f32x4& v0, f32x4& v1) { v0 = (f32x4){bflo(w.x), bfhi(w.x), bflo(w.y), bfhi(w.y)}; v1 = (f32x4){bflo(w.z), bfhi(w.z), bflo(w.w), bfhi(w.w)}; }
;     DI void operator()(const f32x4 (&acc)[2][2][4][2], const Unit& u, int wr, int wc, int fr, int fq, const LAS float* rsl) const {
;     ...
;                 if (u.ks < 0) {
;                     const size_t off = (size_t)row * DM + col0; float sq = 0.f;
; #pragma unroll
;                     for (int bj = 0; bj < 2; ++bj) {
;                         f32x4 x0, x1;
;                         if (XF32) { x0 = *(const f32x4*)(Xin + off + bj * HALF); x1 = *(const f32x4*)(Xin + off + bj * HALF + 4); }
;                         else unpack8(xin[ai][m][bj], x0, x1);
;                         x0 += acc[ai][bj][m][0]; x1 += acc[ai][bj][m][1];
;                         *(u32x4*)(act + off + bj * HALF) = pack8(x0, x1);
;                         sq += (x0[0] * x0[0] + x0[1] * x0[1]) + (x0[2] * x0[2] + x0[3] * x0[3]) + (x1[0] * x1[0] + x1[1] * x1[1]) + (x1[2] * x1[2] + x1[3] * x1[3]);
;                     }
;                     sq += __shfl_xor(sq, 16); sq += __shfl_xor(sq, 32);
;                     if (fq == 0) ssq[(size_t)row * 32 + u.pn * 4 + wc] = sq;
;                 } else {
; #pragma unroll
;                     for (int bj = 0; bj < 2; ++bj) { float* pp = part + ((size_t)u.ks * MS + (row - MP)) * DM + col0 + bj * HALF; *(f32x4*)pp = acc[ai][bj][m][0]; *(f32x4*)(pp + 4) = acc[ai][bj][m][1]; }
.LBB0_1126:
	s_lshl_b64 s[52:53], s[12:13], 24
	s_add_u32 s52, s65, s52
	v_lshlrev_b64 v[232:233], 13, v[216:217]
	s_addc_u32 s53, s66, s53
	v_lshl_add_u64 v[232:233], s[52:53], 0, v[232:233]
	s_brev_b32 s52, 31
	v_lshl_add_u64 v[232:233], v[214:215], 2, v[232:233]
	s_mov_b32 s53, -1
	v_lshl_add_u64 v[234:235], v[232:233], 0, s[52:53]
	v_add_co_u32_e32 v232, vcc, 0xf8000000, v232
	s_nop 1
	v_addc_co_u32_e32 v233, vcc, -1, v233, vcc
	global_store_dwordx4 v[232:233], v[156:159], off
	global_store_dwordx4 v[234:235], v[152:155], off offset:16
	global_store_dwordx4 v[234:235], v[144:147], off offset:512
	global_store_dwordx4 v[234:235], v[140:143], off offset:528
	s_cbranch_execnz .LBB0_1111
.LBB0_1127:
	s_waitcnt vmcnt(0) lgkmcnt(0)
	v_lshlrev_b32_e32 v234, 16, v192
	v_and_b32_e32 v235, 0xffff0000, v192
	v_lshlrev_b32_e32 v192, 16, v193
	v_and_b32_e32 v193, 0xffff0000, v193
	v_lshlrev_b32_e32 v236, 16, v194
	v_and_b32_e32 v237, 0xffff0000, v194
	v_lshlrev_b32_e32 v194, 16, v195
	v_and_b32_e32 v195, 0xffff0000, v195
	v_pk_add_f32 v[156:157], v[156:157], v[234:235]
	v_pk_add_f32 v[158:159], v[158:159], v[192:193]
	v_pk_add_f32 v[192:193], v[154:155], v[194:195]
	v_pk_add_f32 v[194:195], v[152:153], v[236:237]
	v_cvt_pk_bf16_f32 v152, v156, v157
	v_mul_f32_e32 v157, v157, v157
	v_fmac_f32_e32 v157, v156, v156
	v_mul_f32_e32 v156, v159, v159
	v_fmac_f32_e32 v156, v158, v158
	v_add_f32_e32 v156, v157, v156
	v_mul_f32_e32 v157, v195, v195
	v_fmac_f32_e32 v157, v194, v194
	v_add_f32_e32 v156, v157, v156
	v_mul_f32_e32 v157, v193, v193
	v_fmac_f32_e32 v157, v192, v192
	v_cvt_pk_bf16_f32 v153, v158, v159
	v_cvt_pk_bf16_f32 v155, v192, v193
	v_add_f32_e32 v192, v157, v156
	v_lshlrev_b32_e32 v156, 16, v188
	v_and_b32_e32 v157, 0xffff0000, v188
	v_lshlrev_b32_e32 v158, 16, v189
	v_and_b32_e32 v159, 0xffff0000, v189
	v_lshlrev_b32_e32 v188, 16, v190
	v_and_b32_e32 v189, 0xffff0000, v190
	v_pk_add_f32 v[146:147], v[146:147], v[158:159]
	v_pk_add_f32 v[144:145], v[144:145], v[156:157]
	v_pk_add_f32 v[158:159], v[140:141], v[188:189]
	v_mul_f32_e32 v140, v145, v145
	v_mul_f32_e32 v141, v147, v147
	v_fmac_f32_e32 v140, v144, v144
	v_fmac_f32_e32 v141, v146, v146
	v_lshlrev_b32_e32 v190, 16, v191
	v_and_b32_e32 v191, 0xffff0000, v191
	v_add_f32_e32 v140, v140, v141
	v_mul_f32_e32 v141, v159, v159
	v_pk_add_f32 v[156:157], v[142:143], v[190:191]
	v_fmac_f32_e32 v141, v158, v158
	v_add_f32_e32 v140, v141, v140
	v_mul_f32_e32 v141, v157, v157
	v_fmac_f32_e32 v141, v156, v156
	v_add_f32_e32 v140, v141, v140
	v_and_b32_e32 v141, 64, v223
	v_add_f32_e32 v143, v140, v192
	v_xor_b32_e32 v140, 16, v223
	v_add_u32_e32 v190, 64, v141
	v_cmp_lt_i32_e32 vcc, v140, v190
	v_lshlrev_b64 v[232:233], 12, v[216:217]
	v_cvt_pk_bf16_f32 v154, v194, v195
	v_cndmask_b32_e32 v140, v223, v140, vcc
	v_lshlrev_b32_e32 v140, 2, v140
	ds_bpermute_b32 v191, v140, v143
	v_lshl_add_u64 v[140:141], s[18:19], 0, v[232:233]
	v_lshl_add_u64 v[188:189], v[214:215], 1, v[140:141]
	v_xor_b32_e32 v141, 32, v223
	v_cmp_lt_i32_e32 vcc, v141, v190
	s_waitcnt lgkmcnt(0)
	v_add_f32_e32 v140, v143, v191
	v_cvt_pk_bf16_f32 v142, v144, v145
	v_cndmask_b32_e32 v141, v223, v141, vcc
	v_lshlrev_b32_e32 v141, 2, v141
	ds_bpermute_b32 v141, v141, v140
	v_cvt_pk_bf16_f32 v143, v146, v147
	v_cvt_pk_bf16_f32 v144, v158, v159
	v_cvt_pk_bf16_f32 v145, v156, v157
	global_store_dwordx4 v[188:189], v[152:155], off
	global_store_dwordx4 v[188:189], v[142:145], off offset:256
	s_and_saveexec_b64 s[52:53], s[40:41]
	s_cbranch_execz .LBB0_1129
	s_waitcnt lgkmcnt(0)
	v_add_f32_e32 v142, v140, v141
	s_lshl_b32 s54, s22, 2
	v_lshlrev_b64 v[140:141], 7, v[216:217]
	s_ashr_i32 s55, s54, 31
	v_lshl_add_u64 v[140:141], s[34:35], 0, v[140:141]
	v_lshl_add_u64 v[140:141], s[54:55], 2, v[140:141]
	s_lshl_b32 s54, s67, 2
	s_mov_b32 s55, s13
	v_lshl_add_u64 v[140:141], v[140:141], 0, s[54:55]
	global_store_dword v[140:141], v142, off

; DI u32x4 pack8(const f32x4 v0, const f32x4 v1) { u32x4 w; w.x = pk2(v0[0], v0[1]); w.y = pk2(v0[2], v0[3]); w.z = pk2(v1[0], v1[1]); w.w = pk2(v1[2], v1[3]); return w; }
; DI void unpack8(const u32x4 w, f32x4& v0, f32x4& v1) { v0 = (f32x4){bflo(w.x), bfhi(w.x), bflo(w.y), bfhi(w.y)}; v1 = (f32x4){bflo(w.z), bfhi(w.z), bflo(w.w), bfhi(w.w)}; }
;     DI void operator()(const f32x4 (&acc)[2][2][4][2], const Unit& u, int wr, int wc, int fr, int fq, const LAS float* rsl) const {
;     ...
;         for (int ai = 0; ai < 2; ++ai)
; #pragma unroll
;             for (int m = 0; m < 4; ++m) {
;                 const int row = row0 + ai * HALF + m * 16;
;                 if (u.ks < 0) {
;                     const size_t off = (size_t)row * DM + col0; float sq = 0.f;
; #pragma unroll
;                     for (int bj = 0; bj < 2; ++bj) {
;                         f32x4 x0, x1;
;                         if (XF32) { x0 = *(const f32x4*)(Xin + off + bj * HALF); x1 = *(const f32x4*)(Xin + off + bj * HALF + 4); }
;                         else unpack8(xin[ai][m][bj], x0, x1);
;                         x0 += acc[ai][bj][m][0]; x1 += acc[ai][bj][m][1];
;                         *(u32x4*)(act + off + bj * HALF) = pack8(x0, x1);
;                         sq += (x0[0] * x0[0] + x0[1] * x0[1]) + (x0[2] * x0[2] + x0[3] * x0[3]) + (x1[0] * x1[0] + x1[1] * x1[1]) + (x1[2] * x1[2] + x1[3] * x1[3]);
;                     }
;                     sq += __shfl_xor(sq, 16); sq += __shfl_xor(sq, 32);
;                     if (fq == 0) ssq[(size_t)row * 32 + u.pn * 4 + wc] = sq;
;                 } else {
; #pragma unroll
;                     for (int bj = 0; bj < 2; ++bj) { float* pp = part + ((size_t)u.ks * MS + (row - MP)) * DM + col0 + bj * HALF; *(f32x4*)pp = acc[ai][bj][m][0]; *(f32x4*)(pp + 4) = acc[ai][bj][m][1]; }
;                 }
.LBB0_1130:
	s_lshl_b64 s[52:53], s[12:13], 24
	s_add_u32 s52, s65, s52
	s_waitcnt lgkmcnt(0)
	v_lshlrev_b64 v[140:141], 13, v[216:217]
	s_addc_u32 s53, s66, s53
	v_lshl_add_u64 v[140:141], s[52:53], 0, v[140:141]
	s_mov_b32 s52, 0xf8020000
	v_lshl_add_u64 v[140:141], v[214:215], 2, v[140:141]
	s_mov_b32 s53, -1
	v_lshl_add_u64 v[142:143], v[140:141], 0, s[52:53]
	v_add_co_u32_e32 v140, vcc, 0xf8020000, v140
	s_nop 1
	v_addc_co_u32_e32 v141, vcc, -1, v141, vcc
	global_store_dwordx4 v[140:141], v[132:135], off
	global_store_dwordx4 v[142:143], v[128:131], off offset:16
	global_store_dwordx4 v[142:143], v[120:123], off offset:512
	global_store_dwordx4 v[142:143], v[116:119], off offset:528
	s_cbranch_execnz .LBB0_1113
.LBB0_1131:
	s_waitcnt vmcnt(0) lgkmcnt(0)
	v_lshlrev_b32_e32 v144, 16, v184
	v_and_b32_e32 v145, 0xffff0000, v184
	v_lshlrev_b32_e32 v146, 16, v185
	v_and_b32_e32 v147, 0xffff0000, v185
	v_lshlrev_b32_e32 v152, 16, v186
	v_and_b32_e32 v153, 0xffff0000, v186
	v_pk_add_f32 v[132:133], v[132:133], v[144:145]
	v_pk_add_f32 v[134:135], v[134:135], v[146:147]
	v_pk_add_f32 v[146:147], v[128:129], v[152:153]
	v_cvt_pk_bf16_f32 v128, v132, v133
	v_mul_f32_e32 v133, v133, v133
	v_fmac_f32_e32 v133, v132, v132
	v_mul_f32_e32 v132, v135, v135
	v_fmac_f32_e32 v132, v134, v134
	v_lshlrev_b32_e32 v154, 16, v187
	v_and_b32_e32 v155, 0xffff0000, v187
	v_add_f32_e32 v132, v133, v132
	v_mul_f32_e32 v133, v147, v147
	v_pk_add_f32 v[144:145], v[130:131], v[154:155]
	v_fmac_f32_e32 v133, v146, v146
	v_add_f32_e32 v132, v133, v132
	v_mul_f32_e32 v133, v145, v145
	v_fmac_f32_e32 v133, v144, v144
	v_cvt_pk_bf16_f32 v129, v134, v135
	v_add_f32_e32 v152, v133, v132
	v_lshlrev_b32_e32 v132, 16, v180
	v_and_b32_e32 v133, 0xffff0000, v180
	v_lshlrev_b32_e32 v134, 16, v181
	v_and_b32_e32 v135, 0xffff0000, v181
	v_cvt_pk_bf16_f32 v131, v144, v145
	v_lshlrev_b32_e32 v144, 16, v182
	v_and_b32_e32 v145, 0xffff0000, v182
	v_pk_add_f32 v[122:123], v[122:123], v[134:135]
	v_pk_add_f32 v[120:121], v[120:121], v[132:133]
	v_pk_add_f32 v[134:135], v[116:117], v[144:145]
	v_mul_f32_e32 v116, v121, v121
	v_mul_f32_e32 v117, v123, v123
	v_fmac_f32_e32 v116, v120, v120
	v_fmac_f32_e32 v117, v122, v122
	v_cvt_pk_bf16_f32 v130, v146, v147
	v_lshlrev_b32_e32 v146, 16, v183
	v_and_b32_e32 v147, 0xffff0000, v183
	v_add_f32_e32 v116, v116, v117
	v_mul_f32_e32 v117, v135, v135
	v_pk_add_f32 v[132:133], v[118:119], v[146:147]
	v_fmac_f32_e32 v117, v134, v134
	v_add_f32_e32 v116, v117, v116
	v_mul_f32_e32 v117, v133, v133
	v_fmac_f32_e32 v117, v132, v132
	v_add_f32_e32 v116, v117, v116
	v_and_b32_e32 v117, 64, v223
	v_add_f32_e32 v119, v116, v152
	v_xor_b32_e32 v116, 16, v223
	v_add_u32_e32 v144, 64, v117
	v_cmp_lt_i32_e32 vcc, v116, v144
	v_or_b32_e32 v140, 16, v216
	v_ashrrev_i32_e32 v141, 31, v140
	v_cndmask_b32_e32 v116, v223, v116, vcc
	v_lshlrev_b32_e32 v116, 2, v116
	v_lshlrev_b64 v[142:143], 12, v[140:141]
	ds_bpermute_b32 v145, v116, v119
	v_lshl_add_u64 v[116:117], s[18:19], 0, v[142:143]
	v_lshl_add_u64 v[142:143], v[214:215], 1, v[116:117]
	v_xor_b32_e32 v117, 32, v223
	v_cmp_lt_i32_e32 vcc, v117, v144
	s_waitcnt lgkmcnt(0)
	v_add_f32_e32 v116, v119, v145
	v_cvt_pk_bf16_f32 v118, v120, v121
	v_cndmask_b32_e32 v117, v223, v117, vcc
	v_lshlrev_b32_e32 v117, 2, v117
	ds_bpermute_b32 v117, v117, v116
	v_cvt_pk_bf16_f32 v119, v122, v123
	v_cvt_pk_bf16_f32 v120, v134, v135
	v_cvt_pk_bf16_f32 v121, v132, v133
	global_store_dwordx4 v[142:143], v[128:131], off
	global_store_dwordx4 v[142:143], v[118:121], off offset:256
	s_and_saveexec_b64 s[52:53], s[40:41]
	s_cbranch_execz .LBB0_1133
	s_waitcnt lgkmcnt(0)
	v_add_f32_e32 v118, v116, v117
	s_lshl_b32 s54, s22, 2
	v_lshlrev_b64 v[116:117], 7, v[140:141]
	s_ashr_i32 s55, s54, 31
	v_lshl_add_u64 v[116:117], s[34:35], 0, v[116:117]
	v_lshl_add_u64 v[116:117], s[54:55], 2, v[116:117]
	s_lshl_b32 s54, s67, 2
	s_mov_b32 s55, s13
	v_lshl_add_u64 v[116:117], v[116:117], 0, s[54:55]
	global_store_dword v[116:117], v118, off

; DI u32x4 pack8(const f32x4 v0, const f32x4 v1) { u32x4 w; w.x = pk2(v0[0], v0[1]); w.y = pk2(v0[2], v0[3]); w.z = pk2(v1[0], v1[1]); w.w = pk2(v1[2], v1[3]); return w; }
; DI void unpack8(const u32x4 w, f32x4& v0, f32x4& v1) { v0 = (f32x4){bflo(w.x), bfhi(w.x), bflo(w.y), bfhi(w.y)}; v1 = (f32x4){bflo(w.z), bfhi(w.z), bflo(w.w), bfhi(w.w)}; }
;     DI void operator()(const f32x4 (&acc)[2][2][4][2], const Unit& u, int wr, int wc, int fr, int fq, const LAS float* rsl) const {
;     ...
;         for (int ai = 0; ai < 2; ++ai)
; #pragma unroll
;             for (int m = 0; m < 4; ++m) {
;                 const int row = row0 + ai * HALF + m * 16;
;                 if (u.ks < 0) {
;                     const size_t off = (size_t)row * DM + col0; float sq = 0.f;
; #pragma unroll
;                     for (int bj = 0; bj < 2; ++bj) {
;                         f32x4 x0, x1;
;                         if (XF32) { x0 = *(const f32x4*)(Xin + off + bj * HALF); x1 = *(const f32x4*)(Xin + off + bj * HALF + 4); }
;                         else unpack8(xin[ai][m][bj], x0, x1);
;                         x0 += acc[ai][bj][m][0]; x1 += acc[ai][bj][m][1];
;                         *(u32x4*)(act + off + bj * HALF) = pack8(x0, x1);
;                         sq += (x0[0] * x0[0] + x0[1] * x0[1]) + (x0[2] * x0[2] + x0[3] * x0[3]) + (x1[0] * x1[0] + x1[1] * x1[1]) + (x1[2] * x1[2] + x1[3] * x1[3]);
;                     }
;                     sq += __shfl_xor(sq, 16); sq += __shfl_xor(sq, 32);
;                     if (fq == 0) ssq[(size_t)row * 32 + u.pn * 4 + wc] = sq;
;                 } else {
; #pragma unroll
;                     for (int bj = 0; bj < 2; ++bj) { float* pp = part + ((size_t)u.ks * MS + (row - MP)) * DM + col0 + bj * HALF; *(f32x4*)pp = acc[ai][bj][m][0]; *(f32x4*)(pp + 4) = acc[ai][bj][m][1]; }
;                 }
.LBB0_1134:
	s_lshl_b64 s[52:53], s[12:13], 24
	s_add_u32 s52, s65, s52
	s_waitcnt lgkmcnt(0)
	v_lshlrev_b64 v[116:117], 13, v[216:217]
	s_addc_u32 s53, s66, s53
	v_lshl_add_u64 v[116:117], s[52:53], 0, v[116:117]
	s_mov_b32 s52, 0xf8040000
	v_lshl_add_u64 v[116:117], v[214:215], 2, v[116:117]
	s_mov_b32 s53, -1
	v_lshl_add_u64 v[118:119], v[116:117], 0, s[52:53]
	v_add_co_u32_e32 v116, vcc, 0xf8040000, v116
	s_nop 1
	v_addc_co_u32_e32 v117, vcc, -1, v117, vcc
	global_store_dwordx4 v[116:117], v[108:111], off
	global_store_dwordx4 v[118:119], v[100:103], off offset:16
	global_store_dwordx4 v[118:119], v[96:99], off offset:512
	global_store_dwordx4 v[118:119], v[92:95], off offset:528
	s_cbranch_execnz .LBB0_1115
.LBB0_1135:
	s_waitcnt vmcnt(0) lgkmcnt(0)
	v_lshlrev_b32_e32 v120, 16, v176
	v_and_b32_e32 v121, 0xffff0000, v176
	v_lshlrev_b32_e32 v122, 16, v177
	v_and_b32_e32 v123, 0xffff0000, v177
	v_lshlrev_b32_e32 v128, 16, v178
	v_and_b32_e32 v129, 0xffff0000, v178
	v_pk_add_f32 v[108:109], v[108:109], v[120:121]
	v_pk_add_f32 v[110:111], v[110:111], v[122:123]
	v_pk_add_f32 v[122:123], v[100:101], v[128:129]
	v_cvt_pk_bf16_f32 v100, v108, v109
	v_mul_f32_e32 v109, v109, v109
	v_fmac_f32_e32 v109, v108, v108
	v_mul_f32_e32 v108, v111, v111
	v_fmac_f32_e32 v108, v110, v110
	v_lshlrev_b32_e32 v130, 16, v179
	v_and_b32_e32 v131, 0xffff0000, v179
	v_add_f32_e32 v108, v109, v108
	v_mul_f32_e32 v109, v123, v123
	v_pk_add_f32 v[120:121], v[102:103], v[130:131]
	v_fmac_f32_e32 v109, v122, v122
	v_add_f32_e32 v108, v109, v108
	v_mul_f32_e32 v109, v121, v121
	v_fmac_f32_e32 v109, v120, v120
	v_cvt_pk_bf16_f32 v101, v110, v111
	v_add_f32_e32 v128, v109, v108
	v_lshlrev_b32_e32 v108, 16, v172
	v_and_b32_e32 v109, 0xffff0000, v172
	v_lshlrev_b32_e32 v110, 16, v173
	v_and_b32_e32 v111, 0xffff0000, v173
	v_cvt_pk_bf16_f32 v103, v120, v121
	v_lshlrev_b32_e32 v120, 16, v174
	v_and_b32_e32 v121, 0xffff0000, v174
	v_pk_add_f32 v[98:99], v[98:99], v[110:111]
	v_pk_add_f32 v[96:97], v[96:97], v[108:109]
	v_pk_add_f32 v[110:111], v[92:93], v[120:121]
	v_mul_f32_e32 v92, v97, v97
	v_mul_f32_e32 v93, v99, v99
	v_fmac_f32_e32 v92, v96, v96
	v_fmac_f32_e32 v93, v98, v98
	v_cvt_pk_bf16_f32 v102, v122, v123
	v_lshlrev_b32_e32 v122, 16, v175
	v_and_b32_e32 v123, 0xffff0000, v175
	v_add_f32_e32 v92, v92, v93
	v_mul_f32_e32 v93, v111, v111
	v_pk_add_f32 v[108:109], v[94:95], v[122:123]
	v_fmac_f32_e32 v93, v110, v110
	v_add_f32_e32 v92, v93, v92
	v_mul_f32_e32 v93, v109, v109
	v_fmac_f32_e32 v93, v108, v108
	v_add_f32_e32 v92, v93, v92
	v_and_b32_e32 v93, 64, v223
	v_add_f32_e32 v95, v92, v128
	v_xor_b32_e32 v92, 16, v223
	v_add_u32_e32 v120, 64, v93
	v_cmp_lt_i32_e32 vcc, v92, v120
	v_or_b32_e32 v116, 32, v216
	v_ashrrev_i32_e32 v117, 31, v116
	v_cndmask_b32_e32 v92, v223, v92, vcc
	v_lshlrev_b32_e32 v92, 2, v92
	v_lshlrev_b64 v[118:119], 12, v[116:117]
	ds_bpermute_b32 v121, v92, v95
	v_lshl_add_u64 v[92:93], s[18:19], 0, v[118:119]
	v_lshl_add_u64 v[118:119], v[214:215], 1, v[92:93]
	v_xor_b32_e32 v93, 32, v223
	v_cmp_lt_i32_e32 vcc, v93, v120
	s_waitcnt lgkmcnt(0)
	v_add_f32_e32 v92, v95, v121
	v_cvt_pk_bf16_f32 v94, v96, v97
	v_cndmask_b32_e32 v93, v223, v93, vcc
	v_lshlrev_b32_e32 v93, 2, v93
	ds_bpermute_b32 v93, v93, v92
	v_cvt_pk_bf16_f32 v95, v98, v99
	v_cvt_pk_bf16_f32 v96, v110, v111
	v_cvt_pk_bf16_f32 v97, v108, v109
	global_store_dwordx4 v[118:119], v[100:103], off
	global_store_dwordx4 v[118:119], v[94:97], off offset:256
	s_and_saveexec_b64 s[52:53], s[40:41]
	s_cbranch_execz .LBB0_1137
	s_waitcnt lgkmcnt(0)
	v_add_f32_e32 v94, v92, v93
	s_lshl_b32 s54, s22, 2
	v_lshlrev_b64 v[92:93], 7, v[116:117]
	s_ashr_i32 s55, s54, 31
	v_lshl_add_u64 v[92:93], s[34:35], 0, v[92:93]
	v_lshl_add_u64 v[92:93], s[54:55], 2, v[92:93]
	s_lshl_b32 s54, s67, 2
	s_mov_b32 s55, s13
	v_lshl_add_u64 v[92:93], v[92:93], 0, s[54:55]
	global_store_dword v[92:93], v94, off

; DI u32x4 pack8(const f32x4 v0, const f32x4 v1) { u32x4 w; w.x = pk2(v0[0], v0[1]); w.y = pk2(v0[2], v0[3]); w.z = pk2(v1[0], v1[1]); w.w = pk2(v1[2], v1[3]); return w; }
; DI void unpack8(const u32x4 w, f32x4& v0, f32x4& v1) { v0 = (f32x4){bflo(w.x), bfhi(w.x), bflo(w.y), bfhi(w.y)}; v1 = (f32x4){bflo(w.z), bfhi(w.z), bflo(w.w), bfhi(w.w)}; }
;     DI void operator()(const f32x4 (&acc)[2][2][4][2], const Unit& u, int wr, int wc, int fr, int fq, const LAS float* rsl) const {
;     ...
;         for (int ai = 0; ai < 2; ++ai)
; #pragma unroll
;             for (int m = 0; m < 4; ++m) {
;                 const int row = row0 + ai * HALF + m * 16;
;                 if (u.ks < 0) {
;                     const size_t off = (size_t)row * DM + col0; float sq = 0.f;
; #pragma unroll
;                     for (int bj = 0; bj < 2; ++bj) {
;                         f32x4 x0, x1;
;                         if (XF32) { x0 = *(const f32x4*)(Xin + off + bj * HALF); x1 = *(const f32x4*)(Xin + off + bj * HALF + 4); }
;                         else unpack8(xin[ai][m][bj], x0, x1);
;                         x0 += acc[ai][bj][m][0]; x1 += acc[ai][bj][m][1];
;                         *(u32x4*)(act + off + bj * HALF) = pack8(x0, x1);
;                         sq += (x0[0] * x0[0] + x0[1] * x0[1]) + (x0[2] * x0[2] + x0[3] * x0[3]) + (x1[0] * x1[0] + x1[1] * x1[1]) + (x1[2] * x1[2] + x1[3] * x1[3]);
;                     }
;                     sq += __shfl_xor(sq, 16); sq += __shfl_xor(sq, 32);
;                     if (fq == 0) ssq[(size_t)row * 32 + u.pn * 4 + wc] = sq;
;                 } else {
; #pragma unroll
;                     for (int bj = 0; bj < 2; ++bj) { float* pp = part + ((size_t)u.ks * MS + (row - MP)) * DM + col0 + bj * HALF; *(f32x4*)pp = acc[ai][bj][m][0]; *(f32x4*)(pp + 4) = acc[ai][bj][m][1]; }
;                 }
.LBB0_1138:
	s_lshl_b64 s[52:53], s[12:13], 24
	s_add_u32 s52, s65, s52
	s_waitcnt lgkmcnt(0)
	v_lshlrev_b64 v[92:93], 13, v[216:217]
	s_addc_u32 s53, s66, s53
	v_lshl_add_u64 v[92:93], s[52:53], 0, v[92:93]
	s_mov_b32 s52, 0xf8060000
	v_lshl_add_u64 v[92:93], v[214:215], 2, v[92:93]
	s_mov_b32 s53, -1
	v_lshl_add_u64 v[94:95], v[92:93], 0, s[52:53]
	v_add_co_u32_e32 v92, vcc, 0xf8060000, v92
	s_nop 1
	v_addc_co_u32_e32 v93, vcc, -1, v93, vcc
	global_store_dwordx4 v[92:93], v[80:83], off
	global_store_dwordx4 v[94:95], v[76:79], off offset:16
	global_store_dwordx4 v[94:95], v[72:75], off offset:512
	global_store_dwordx4 v[94:95], v[68:71], off offset:528
	s_cbranch_execnz .LBB0_1117
.LBB0_1139:
	s_waitcnt vmcnt(0) lgkmcnt(0)
	v_lshlrev_b32_e32 v96, 16, v168
	v_and_b32_e32 v97, 0xffff0000, v168
	v_lshlrev_b32_e32 v98, 16, v169
	v_and_b32_e32 v99, 0xffff0000, v169
	v_lshlrev_b32_e32 v100, 16, v170
	v_and_b32_e32 v101, 0xffff0000, v170
	v_pk_add_f32 v[80:81], v[80:81], v[96:97]
	v_pk_add_f32 v[82:83], v[82:83], v[98:99]
	v_pk_add_f32 v[98:99], v[76:77], v[100:101]
	v_cvt_pk_bf16_f32 v76, v80, v81
	v_mul_f32_e32 v81, v81, v81
	v_fmac_f32_e32 v81, v80, v80
	v_mul_f32_e32 v80, v83, v83
	v_fmac_f32_e32 v80, v82, v82
	v_lshlrev_b32_e32 v102, 16, v171
	v_and_b32_e32 v103, 0xffff0000, v171
	v_add_f32_e32 v80, v81, v80
	v_mul_f32_e32 v81, v99, v99
	v_pk_add_f32 v[96:97], v[78:79], v[102:103]
	v_fmac_f32_e32 v81, v98, v98
	v_add_f32_e32 v80, v81, v80
	v_mul_f32_e32 v81, v97, v97
	v_fmac_f32_e32 v81, v96, v96
	v_cvt_pk_bf16_f32 v77, v82, v83
	v_add_f32_e32 v100, v81, v80
	v_lshlrev_b32_e32 v80, 16, v164
	v_and_b32_e32 v81, 0xffff0000, v164
	v_lshlrev_b32_e32 v82, 16, v165
	v_and_b32_e32 v83, 0xffff0000, v165
	v_cvt_pk_bf16_f32 v79, v96, v97
	v_lshlrev_b32_e32 v96, 16, v166
	v_and_b32_e32 v97, 0xffff0000, v166
	v_pk_add_f32 v[74:75], v[74:75], v[82:83]
	v_pk_add_f32 v[72:73], v[72:73], v[80:81]
	v_pk_add_f32 v[82:83], v[68:69], v[96:97]
	v_mul_f32_e32 v68, v73, v73
	v_mul_f32_e32 v69, v75, v75
	v_fmac_f32_e32 v68, v72, v72
	v_fmac_f32_e32 v69, v74, v74
	v_cvt_pk_bf16_f32 v78, v98, v99
	v_lshlrev_b32_e32 v98, 16, v167
	v_and_b32_e32 v99, 0xffff0000, v167
	v_add_f32_e32 v68, v68, v69
	v_mul_f32_e32 v69, v83, v83
	v_pk_add_f32 v[80:81], v[70:71], v[98:99]
	v_fmac_f32_e32 v69, v82, v82
	v_add_f32_e32 v68, v69, v68
	v_mul_f32_e32 v69, v81, v81
	v_fmac_f32_e32 v69, v80, v80
	v_add_f32_e32 v68, v69, v68
	v_and_b32_e32 v69, 64, v223
	v_add_f32_e32 v71, v68, v100
	v_xor_b32_e32 v68, 16, v223
	v_add_u32_e32 v96, 64, v69
	v_cmp_lt_i32_e32 vcc, v68, v96
	v_or_b32_e32 v92, 48, v216
	v_ashrrev_i32_e32 v93, 31, v92
	v_cndmask_b32_e32 v68, v223, v68, vcc
	v_lshlrev_b32_e32 v68, 2, v68
	v_lshlrev_b64 v[94:95], 12, v[92:93]
	ds_bpermute_b32 v97, v68, v71
	v_lshl_add_u64 v[68:69], s[18:19], 0, v[94:95]
	v_lshl_add_u64 v[94:95], v[214:215], 1, v[68:69]
	v_xor_b32_e32 v69, 32, v223
	v_cmp_lt_i32_e32 vcc, v69, v96
	s_waitcnt lgkmcnt(0)
	v_add_f32_e32 v68, v71, v97
	v_cvt_pk_bf16_f32 v70, v72, v73
	v_cndmask_b32_e32 v69, v223, v69, vcc
	v_lshlrev_b32_e32 v69, 2, v69
	ds_bpermute_b32 v69, v69, v68
	v_cvt_pk_bf16_f32 v71, v74, v75
	v_cvt_pk_bf16_f32 v72, v82, v83
	v_cvt_pk_bf16_f32 v73, v80, v81
	global_store_dwordx4 v[94:95], v[76:79], off
	global_store_dwordx4 v[94:95], v[70:73], off offset:256
	s_and_saveexec_b64 s[52:53], s[40:41]
	s_cbranch_execz .LBB0_1141
	s_waitcnt lgkmcnt(0)
	v_add_f32_e32 v70, v68, v69
	s_lshl_b32 s54, s22, 2
	v_lshlrev_b64 v[68:69], 7, v[92:93]
	s_ashr_i32 s55, s54, 31
	v_lshl_add_u64 v[68:69], s[34:35], 0, v[68:69]
	v_lshl_add_u64 v[68:69], s[54:55], 2, v[68:69]
	s_lshl_b32 s54, s67, 2
	s_mov_b32 s55, s13
	v_lshl_add_u64 v[68:69], v[68:69], 0, s[54:55]
	global_store_dword v[68:69], v70, off

; DI u32x4 pack8(const f32x4 v0, const f32x4 v1) { u32x4 w; w.x = pk2(v0[0], v0[1]); w.y = pk2(v0[2], v0[3]); w.z = pk2(v1[0], v1[1]); w.w = pk2(v1[2], v1[3]); return w; }
; DI void unpack8(const u32x4 w, f32x4& v0, f32x4& v1) { v0 = (f32x4){bflo(w.x), bfhi(w.x), bflo(w.y), bfhi(w.y)}; v1 = (f32x4){bflo(w.z), bfhi(w.z), bflo(w.w), bfhi(w.w)}; }
;     DI void operator()(const f32x4 (&acc)[2][2][4][2], const Unit& u, int wr, int wc, int fr, int fq, const LAS float* rsl) const {
;     ...
;         for (int ai = 0; ai < 2; ++ai)
; #pragma unroll
;             for (int m = 0; m < 4; ++m) {
;                 const int row = row0 + ai * HALF + m * 16;
;                 if (u.ks < 0) {
;                     const size_t off = (size_t)row * DM + col0; float sq = 0.f;
; #pragma unroll
;                     for (int bj = 0; bj < 2; ++bj) {
;                         f32x4 x0, x1;
;                         if (XF32) { x0 = *(const f32x4*)(Xin + off + bj * HALF); x1 = *(const f32x4*)(Xin + off + bj * HALF + 4); }
;                         else unpack8(xin[ai][m][bj], x0, x1);
;                         x0 += acc[ai][bj][m][0]; x1 += acc[ai][bj][m][1];
;                         *(u32x4*)(act + off + bj * HALF) = pack8(x0, x1);
;                         sq += (x0[0] * x0[0] + x0[1] * x0[1]) + (x0[2] * x0[2] + x0[3] * x0[3]) + (x1[0] * x1[0] + x1[1] * x1[1]) + (x1[2] * x1[2] + x1[3] * x1[3]);
;                     }
;                     sq += __shfl_xor(sq, 16); sq += __shfl_xor(sq, 32);
;                     if (fq == 0) ssq[(size_t)row * 32 + u.pn * 4 + wc] = sq;
;                 } else {
; #pragma unroll
;                     for (int bj = 0; bj < 2; ++bj) { float* pp = part + ((size_t)u.ks * MS + (row - MP)) * DM + col0 + bj * HALF; *(f32x4*)pp = acc[ai][bj][m][0]; *(f32x4*)(pp + 4) = acc[ai][bj][m][1]; }
;                 }
.LBB0_1142:
	s_lshl_b64 s[52:53], s[12:13], 24
	s_add_u32 s52, s65, s52
	s_waitcnt lgkmcnt(0)
	v_lshlrev_b64 v[68:69], 13, v[216:217]
	s_addc_u32 s53, s66, s53
	v_lshl_add_u64 v[68:69], s[52:53], 0, v[68:69]
	s_mov_b32 s52, 0xf8100000
	v_lshl_add_u64 v[68:69], v[214:215], 2, v[68:69]
	s_mov_b32 s53, -1
	v_lshl_add_u64 v[70:71], v[68:69], 0, s[52:53]
	v_add_co_u32_e32 v68, vcc, 0xf8100000, v68
	s_nop 1
	v_addc_co_u32_e32 v69, vcc, -1, v69, vcc
	global_store_dwordx4 v[68:69], v[64:67], off
	global_store_dwordx4 v[70:71], v[60:63], off offset:16
	global_store_dwordx4 v[70:71], v[56:59], off offset:512
	global_store_dwordx4 v[70:71], v[52:55], off offset:528
	s_cbranch_execnz .LBB0_1119
.LBB0_1143:
	s_waitcnt vmcnt(0) lgkmcnt(0)
	v_lshlrev_b32_e32 v72, 16, v160
	v_and_b32_e32 v73, 0xffff0000, v160
	v_lshlrev_b32_e32 v74, 16, v161
	v_and_b32_e32 v75, 0xffff0000, v161
	v_lshlrev_b32_e32 v76, 16, v162
	v_and_b32_e32 v77, 0xffff0000, v162
	v_pk_add_f32 v[64:65], v[64:65], v[72:73]
	v_pk_add_f32 v[66:67], v[66:67], v[74:75]
	v_pk_add_f32 v[74:75], v[60:61], v[76:77]
	v_cvt_pk_bf16_f32 v60, v64, v65
	v_mul_f32_e32 v65, v65, v65
	v_fmac_f32_e32 v65, v64, v64
	v_mul_f32_e32 v64, v67, v67
	v_fmac_f32_e32 v64, v66, v66
	v_lshlrev_b32_e32 v78, 16, v163
	v_and_b32_e32 v79, 0xffff0000, v163
	v_add_f32_e32 v64, v65, v64
	v_mul_f32_e32 v65, v75, v75
	v_pk_add_f32 v[72:73], v[62:63], v[78:79]
	v_fmac_f32_e32 v65, v74, v74
	v_add_f32_e32 v64, v65, v64
	v_mul_f32_e32 v65, v73, v73
	v_fmac_f32_e32 v65, v72, v72
	v_cvt_pk_bf16_f32 v61, v66, v67
	v_add_f32_e32 v76, v65, v64
	v_lshlrev_b32_e32 v64, 16, v148
	v_and_b32_e32 v65, 0xffff0000, v148
	v_lshlrev_b32_e32 v66, 16, v149
	v_and_b32_e32 v67, 0xffff0000, v149
	v_cvt_pk_bf16_f32 v63, v72, v73
	v_lshlrev_b32_e32 v72, 16, v150
	v_and_b32_e32 v73, 0xffff0000, v150
	v_pk_add_f32 v[58:59], v[58:59], v[66:67]
	v_pk_add_f32 v[56:57], v[56:57], v[64:65]
	v_pk_add_f32 v[66:67], v[52:53], v[72:73]
	v_mul_f32_e32 v52, v57, v57
	v_mul_f32_e32 v53, v59, v59
	v_fmac_f32_e32 v52, v56, v56
	v_fmac_f32_e32 v53, v58, v58
	v_cvt_pk_bf16_f32 v62, v74, v75
	v_lshlrev_b32_e32 v74, 16, v151
	v_and_b32_e32 v75, 0xffff0000, v151
	v_add_f32_e32 v52, v52, v53
	v_mul_f32_e32 v53, v67, v67
	v_pk_add_f32 v[64:65], v[54:55], v[74:75]
	v_fmac_f32_e32 v53, v66, v66
	v_add_f32_e32 v52, v53, v52
	v_mul_f32_e32 v53, v65, v65
	v_fmac_f32_e32 v53, v64, v64
	v_add_f32_e32 v52, v53, v52
	v_and_b32_e32 v53, 64, v223
	v_add_f32_e32 v55, v52, v76
	v_xor_b32_e32 v52, 16, v223
	v_add_u32_e32 v72, 64, v53
	v_cmp_lt_i32_e32 vcc, v52, v72
	v_add_u32_e32 v68, 0x80, v216
	v_ashrrev_i32_e32 v69, 31, v68
	v_cndmask_b32_e32 v52, v223, v52, vcc
	v_lshlrev_b32_e32 v52, 2, v52
	v_lshlrev_b64 v[70:71], 12, v[68:69]
	ds_bpermute_b32 v73, v52, v55
	v_lshl_add_u64 v[52:53], s[18:19], 0, v[70:71]
	v_lshl_add_u64 v[70:71], v[214:215], 1, v[52:53]
	v_xor_b32_e32 v53, 32, v223
	v_cmp_lt_i32_e32 vcc, v53, v72
	s_waitcnt lgkmcnt(0)
	v_add_f32_e32 v52, v55, v73
	v_cvt_pk_bf16_f32 v54, v56, v57
	v_cndmask_b32_e32 v53, v223, v53, vcc
	v_lshlrev_b32_e32 v53, 2, v53
	ds_bpermute_b32 v53, v53, v52
	v_cvt_pk_bf16_f32 v55, v58, v59
	v_cvt_pk_bf16_f32 v56, v66, v67
	v_cvt_pk_bf16_f32 v57, v64, v65
	global_store_dwordx4 v[70:71], v[60:63], off
	global_store_dwordx4 v[70:71], v[54:57], off offset:256
	s_and_saveexec_b64 s[52:53], s[40:41]
	s_cbranch_execz .LBB0_1145
	s_waitcnt lgkmcnt(0)
	v_add_f32_e32 v54, v52, v53
	s_lshl_b32 s54, s22, 2
	v_lshlrev_b64 v[52:53], 7, v[68:69]
	s_ashr_i32 s55, s54, 31
	v_lshl_add_u64 v[52:53], s[34:35], 0, v[52:53]
	v_lshl_add_u64 v[52:53], s[54:55], 2, v[52:53]
	s_lshl_b32 s54, s67, 2
	s_mov_b32 s55, s13
	v_lshl_add_u64 v[52:53], v[52:53], 0, s[54:55]
	global_store_dword v[52:53], v54, off

; DI u32x4 pack8(const f32x4 v0, const f32x4 v1) { u32x4 w; w.x = pk2(v0[0], v0[1]); w.y = pk2(v0[2], v0[3]); w.z = pk2(v1[0], v1[1]); w.w = pk2(v1[2], v1[3]); return w; }
; DI void unpack8(const u32x4 w, f32x4& v0, f32x4& v1) { v0 = (f32x4){bflo(w.x), bfhi(w.x), bflo(w.y), bfhi(w.y)}; v1 = (f32x4){bflo(w.z), bfhi(w.z), bflo(w.w), bfhi(w.w)}; }
;     DI void operator()(const f32x4 (&acc)[2][2][4][2], const Unit& u, int wr, int wc, int fr, int fq, const LAS float* rsl) const {
;     ...
;         for (int ai = 0; ai < 2; ++ai)
; #pragma unroll
;             for (int m = 0; m < 4; ++m) {
;                 const int row = row0 + ai * HALF + m * 16;
;                 if (u.ks < 0) {
;                     const size_t off = (size_t)row * DM + col0; float sq = 0.f;
; #pragma unroll
;                     for (int bj = 0; bj < 2; ++bj) {
;                         f32x4 x0, x1;
;                         if (XF32) { x0 = *(const f32x4*)(Xin + off + bj * HALF); x1 = *(const f32x4*)(Xin + off + bj * HALF + 4); }
;                         else unpack8(xin[ai][m][bj], x0, x1);
;                         x0 += acc[ai][bj][m][0]; x1 += acc[ai][bj][m][1];
;                         *(u32x4*)(act + off + bj * HALF) = pack8(x0, x1);
;                         sq += (x0[0] * x0[0] + x0[1] * x0[1]) + (x0[2] * x0[2] + x0[3] * x0[3]) + (x1[0] * x1[0] + x1[1] * x1[1]) + (x1[2] * x1[2] + x1[3] * x1[3]);
;                     }
;                     sq += __shfl_xor(sq, 16); sq += __shfl_xor(sq, 32);
;                     if (fq == 0) ssq[(size_t)row * 32 + u.pn * 4 + wc] = sq;
;                 } else {
; #pragma unroll
;                     for (int bj = 0; bj < 2; ++bj) { float* pp = part + ((size_t)u.ks * MS + (row - MP)) * DM + col0 + bj * HALF; *(f32x4*)pp = acc[ai][bj][m][0]; *(f32x4*)(pp + 4) = acc[ai][bj][m][1]; }
;                 }
.LBB0_1146:
	s_lshl_b64 s[52:53], s[12:13], 24
	s_add_u32 s52, s65, s52
	s_waitcnt lgkmcnt(0)
	v_lshlrev_b64 v[52:53], 13, v[216:217]
	s_addc_u32 s53, s66, s53
	v_lshl_add_u64 v[52:53], s[52:53], 0, v[52:53]
	s_mov_b32 s52, 0xf8120000
	v_lshl_add_u64 v[52:53], v[214:215], 2, v[52:53]
	s_mov_b32 s53, -1
	v_lshl_add_u64 v[54:55], v[52:53], 0, s[52:53]
	v_add_co_u32_e32 v52, vcc, 0xf8120000, v52
	s_nop 1
	v_addc_co_u32_e32 v53, vcc, -1, v53, vcc
	global_store_dwordx4 v[52:53], v[48:51], off
	global_store_dwordx4 v[54:55], v[44:47], off offset:16
	global_store_dwordx4 v[54:55], v[40:43], off offset:512
	global_store_dwordx4 v[54:55], v[36:39], off offset:528
	s_cbranch_execnz .LBB0_1121
.LBB0_1147:
	s_waitcnt vmcnt(0) lgkmcnt(0)
	v_lshlrev_b32_e32 v56, 16, v136
	v_and_b32_e32 v57, 0xffff0000, v136
	v_lshlrev_b32_e32 v58, 16, v137
	v_and_b32_e32 v59, 0xffff0000, v137
	v_lshlrev_b32_e32 v60, 16, v138
	v_and_b32_e32 v61, 0xffff0000, v138
	v_pk_add_f32 v[48:49], v[48:49], v[56:57]
	v_pk_add_f32 v[50:51], v[50:51], v[58:59]
	v_pk_add_f32 v[58:59], v[44:45], v[60:61]
	v_cvt_pk_bf16_f32 v44, v48, v49
	v_mul_f32_e32 v49, v49, v49
	v_fmac_f32_e32 v49, v48, v48
	v_mul_f32_e32 v48, v51, v51
	v_fmac_f32_e32 v48, v50, v50
	v_lshlrev_b32_e32 v62, 16, v139
	v_and_b32_e32 v63, 0xffff0000, v139
	v_add_f32_e32 v48, v49, v48
	v_mul_f32_e32 v49, v59, v59
	v_pk_add_f32 v[56:57], v[46:47], v[62:63]
	v_fmac_f32_e32 v49, v58, v58
	v_add_f32_e32 v48, v49, v48
	v_mul_f32_e32 v49, v57, v57
	v_fmac_f32_e32 v49, v56, v56
	v_cvt_pk_bf16_f32 v45, v50, v51
	v_add_f32_e32 v60, v49, v48
	v_lshlrev_b32_e32 v48, 16, v124
	v_and_b32_e32 v49, 0xffff0000, v124
	v_lshlrev_b32_e32 v50, 16, v125
	v_and_b32_e32 v51, 0xffff0000, v125
	v_cvt_pk_bf16_f32 v47, v56, v57
	v_lshlrev_b32_e32 v56, 16, v126
	v_and_b32_e32 v57, 0xffff0000, v126
	v_pk_add_f32 v[42:43], v[42:43], v[50:51]
	v_pk_add_f32 v[40:41], v[40:41], v[48:49]
	v_pk_add_f32 v[50:51], v[36:37], v[56:57]
	v_mul_f32_e32 v36, v41, v41
	v_mul_f32_e32 v37, v43, v43
	v_fmac_f32_e32 v36, v40, v40
	v_fmac_f32_e32 v37, v42, v42
	v_cvt_pk_bf16_f32 v46, v58, v59
	v_lshlrev_b32_e32 v58, 16, v127
	v_and_b32_e32 v59, 0xffff0000, v127
	v_add_f32_e32 v36, v36, v37
	v_mul_f32_e32 v37, v51, v51
	v_pk_add_f32 v[48:49], v[38:39], v[58:59]
	v_fmac_f32_e32 v37, v50, v50
	v_add_f32_e32 v36, v37, v36
	v_mul_f32_e32 v37, v49, v49
	v_fmac_f32_e32 v37, v48, v48
	v_add_f32_e32 v36, v37, v36
	v_and_b32_e32 v37, 64, v223
	v_add_f32_e32 v39, v36, v60
	v_xor_b32_e32 v36, 16, v223
	v_add_u32_e32 v56, 64, v37
	v_cmp_lt_i32_e32 vcc, v36, v56
	v_add_u32_e32 v52, 0x90, v216
	v_ashrrev_i32_e32 v53, 31, v52
	v_cndmask_b32_e32 v36, v223, v36, vcc
	v_lshlrev_b32_e32 v36, 2, v36
	v_lshlrev_b64 v[54:55], 12, v[52:53]
	ds_bpermute_b32 v57, v36, v39
	v_lshl_add_u64 v[36:37], s[18:19], 0, v[54:55]
	v_lshl_add_u64 v[54:55], v[214:215], 1, v[36:37]
	v_xor_b32_e32 v37, 32, v223
	v_cmp_lt_i32_e32 vcc, v37, v56
	s_waitcnt lgkmcnt(0)
	v_add_f32_e32 v36, v39, v57
	v_cvt_pk_bf16_f32 v38, v40, v41
	v_cndmask_b32_e32 v37, v223, v37, vcc
	v_lshlrev_b32_e32 v37, 2, v37
	ds_bpermute_b32 v37, v37, v36
	v_cvt_pk_bf16_f32 v39, v42, v43
	v_cvt_pk_bf16_f32 v40, v50, v51
	v_cvt_pk_bf16_f32 v41, v48, v49
	global_store_dwordx4 v[54:55], v[44:47], off
	global_store_dwordx4 v[54:55], v[38:41], off offset:256
	s_and_saveexec_b64 s[52:53], s[40:41]
	s_cbranch_execz .LBB0_1149
	s_waitcnt lgkmcnt(0)
	v_add_f32_e32 v38, v36, v37
	s_lshl_b32 s54, s22, 2
	v_lshlrev_b64 v[36:37], 7, v[52:53]
	s_ashr_i32 s55, s54, 31
	v_lshl_add_u64 v[36:37], s[34:35], 0, v[36:37]
	v_lshl_add_u64 v[36:37], s[54:55], 2, v[36:37]
	s_lshl_b32 s54, s67, 2
	s_mov_b32 s55, s13
	v_lshl_add_u64 v[36:37], v[36:37], 0, s[54:55]
	global_store_dword v[36:37], v38, off

; DI u32x4 pack8(const f32x4 v0, const f32x4 v1) { u32x4 w; w.x = pk2(v0[0], v0[1]); w.y = pk2(v0[2], v0[3]); w.z = pk2(v1[0], v1[1]); w.w = pk2(v1[2], v1[3]); return w; }
; DI void unpack8(const u32x4 w, f32x4& v0, f32x4& v1) { v0 = (f32x4){bflo(w.x), bfhi(w.x), bflo(w.y), bfhi(w.y)}; v1 = (f32x4){bflo(w.z), bfhi(w.z), bflo(w.w), bfhi(w.w)}; }
;     DI void operator()(const f32x4 (&acc)[2][2][4][2], const Unit& u, int wr, int wc, int fr, int fq, const LAS float* rsl) const {
;     ...
;         for (int ai = 0; ai < 2; ++ai)
; #pragma unroll
;             for (int m = 0; m < 4; ++m) {
;                 const int row = row0 + ai * HALF + m * 16;
;                 if (u.ks < 0) {
;                     const size_t off = (size_t)row * DM + col0; float sq = 0.f;
; #pragma unroll
;                     for (int bj = 0; bj < 2; ++bj) {
;                         f32x4 x0, x1;
;                         if (XF32) { x0 = *(const f32x4*)(Xin + off + bj * HALF); x1 = *(const f32x4*)(Xin + off + bj * HALF + 4); }
;                         else unpack8(xin[ai][m][bj], x0, x1);
;                         x0 += acc[ai][bj][m][0]; x1 += acc[ai][bj][m][1];
;                         *(u32x4*)(act + off + bj * HALF) = pack8(x0, x1);
;                         sq += (x0[0] * x0[0] + x0[1] * x0[1]) + (x0[2] * x0[2] + x0[3] * x0[3]) + (x1[0] * x1[0] + x1[1] * x1[1]) + (x1[2] * x1[2] + x1[3] * x1[3]);
;                     }
;                     sq += __shfl_xor(sq, 16); sq += __shfl_xor(sq, 32);
;                     if (fq == 0) ssq[(size_t)row * 32 + u.pn * 4 + wc] = sq;
;                 } else {
; #pragma unroll
;                     for (int bj = 0; bj < 2; ++bj) { float* pp = part + ((size_t)u.ks * MS + (row - MP)) * DM + col0 + bj * HALF; *(f32x4*)pp = acc[ai][bj][m][0]; *(f32x4*)(pp + 4) = acc[ai][bj][m][1]; }
;                 }
.LBB0_1150:
	s_lshl_b64 s[52:53], s[12:13], 24
	s_add_u32 s52, s65, s52
	s_waitcnt lgkmcnt(0)
	v_lshlrev_b64 v[36:37], 13, v[216:217]
	s_addc_u32 s53, s66, s53
	v_lshl_add_u64 v[36:37], s[52:53], 0, v[36:37]
	s_mov_b32 s52, 0xf8140000
	v_lshl_add_u64 v[36:37], v[214:215], 2, v[36:37]
	s_mov_b32 s53, -1
	v_lshl_add_u64 v[38:39], v[36:37], 0, s[52:53]
	v_add_co_u32_e32 v36, vcc, 0xf8140000, v36
	s_nop 1
	v_addc_co_u32_e32 v37, vcc, -1, v37, vcc
	global_store_dwordx4 v[36:37], v[32:35], off
	global_store_dwordx4 v[38:39], v[28:31], off offset:16
	global_store_dwordx4 v[38:39], v[24:27], off offset:512
	global_store_dwordx4 v[38:39], v[20:23], off offset:528
	s_cbranch_execnz .LBB0_1123
.LBB0_1151:
	s_waitcnt vmcnt(0) lgkmcnt(0)
	v_lshlrev_b32_e32 v40, 16, v112
	v_and_b32_e32 v41, 0xffff0000, v112
	v_lshlrev_b32_e32 v42, 16, v113
	v_and_b32_e32 v43, 0xffff0000, v113
	v_lshlrev_b32_e32 v44, 16, v114
	v_and_b32_e32 v45, 0xffff0000, v114
	v_pk_add_f32 v[32:33], v[32:33], v[40:41]
	v_pk_add_f32 v[34:35], v[34:35], v[42:43]
	v_pk_add_f32 v[42:43], v[28:29], v[44:45]
	v_cvt_pk_bf16_f32 v28, v32, v33
	v_mul_f32_e32 v33, v33, v33
	v_fmac_f32_e32 v33, v32, v32
	v_mul_f32_e32 v32, v35, v35
	v_fmac_f32_e32 v32, v34, v34
	v_lshlrev_b32_e32 v46, 16, v115
	v_and_b32_e32 v47, 0xffff0000, v115
	v_add_f32_e32 v32, v33, v32
	v_mul_f32_e32 v33, v43, v43
	v_pk_add_f32 v[40:41], v[30:31], v[46:47]
	v_fmac_f32_e32 v33, v42, v42
	v_add_f32_e32 v32, v33, v32
	v_mul_f32_e32 v33, v41, v41
	v_fmac_f32_e32 v33, v40, v40
	v_cvt_pk_bf16_f32 v29, v34, v35
	v_add_f32_e32 v44, v33, v32
	v_lshlrev_b32_e32 v32, 16, v104
	v_and_b32_e32 v33, 0xffff0000, v104
	v_lshlrev_b32_e32 v34, 16, v105
	v_and_b32_e32 v35, 0xffff0000, v105
	v_cvt_pk_bf16_f32 v31, v40, v41
	v_lshlrev_b32_e32 v40, 16, v106
	v_and_b32_e32 v41, 0xffff0000, v106
	v_pk_add_f32 v[26:27], v[26:27], v[34:35]
	v_pk_add_f32 v[24:25], v[24:25], v[32:33]
	v_pk_add_f32 v[34:35], v[20:21], v[40:41]
	v_mul_f32_e32 v20, v25, v25
	v_mul_f32_e32 v21, v27, v27
	v_fmac_f32_e32 v20, v24, v24
	v_fmac_f32_e32 v21, v26, v26
	v_cvt_pk_bf16_f32 v30, v42, v43
	v_lshlrev_b32_e32 v42, 16, v107
	v_and_b32_e32 v43, 0xffff0000, v107
	v_add_f32_e32 v20, v20, v21
	v_mul_f32_e32 v21, v35, v35
	v_pk_add_f32 v[32:33], v[22:23], v[42:43]
	v_fmac_f32_e32 v21, v34, v34
	v_add_f32_e32 v20, v21, v20
	v_mul_f32_e32 v21, v33, v33
	v_fmac_f32_e32 v21, v32, v32
	v_add_f32_e32 v20, v21, v20
	v_and_b32_e32 v21, 64, v223
	v_add_f32_e32 v23, v20, v44
	v_xor_b32_e32 v20, 16, v223
	v_add_u32_e32 v40, 64, v21
	v_cmp_lt_i32_e32 vcc, v20, v40
	v_add_u32_e32 v36, 0xa0, v216
	v_ashrrev_i32_e32 v37, 31, v36
	v_cndmask_b32_e32 v20, v223, v20, vcc
	v_lshlrev_b32_e32 v20, 2, v20
	v_lshlrev_b64 v[38:39], 12, v[36:37]
	ds_bpermute_b32 v41, v20, v23
	v_lshl_add_u64 v[20:21], s[18:19], 0, v[38:39]
	v_lshl_add_u64 v[38:39], v[214:215], 1, v[20:21]
	v_xor_b32_e32 v21, 32, v223
	v_cmp_lt_i32_e32 vcc, v21, v40
	s_waitcnt lgkmcnt(0)
	v_add_f32_e32 v20, v23, v41
	v_cvt_pk_bf16_f32 v22, v24, v25
	v_cndmask_b32_e32 v21, v223, v21, vcc
	v_lshlrev_b32_e32 v21, 2, v21
	ds_bpermute_b32 v21, v21, v20
	v_cvt_pk_bf16_f32 v23, v26, v27
	v_cvt_pk_bf16_f32 v24, v34, v35
	v_cvt_pk_bf16_f32 v25, v32, v33
	global_store_dwordx4 v[38:39], v[28:31], off
	global_store_dwordx4 v[38:39], v[22:25], off offset:256
	s_and_saveexec_b64 s[52:53], s[40:41]
	s_cbranch_execz .LBB0_1153
	s_waitcnt lgkmcnt(0)
	v_add_f32_e32 v22, v20, v21
	s_lshl_b32 s54, s22, 2
	v_lshlrev_b64 v[20:21], 7, v[36:37]
	s_ashr_i32 s55, s54, 31
	v_lshl_add_u64 v[20:21], s[34:35], 0, v[20:21]
	v_lshl_add_u64 v[20:21], s[54:55], 2, v[20:21]
	s_lshl_b32 s54, s67, 2
	s_mov_b32 s55, s13
	v_lshl_add_u64 v[20:21], v[20:21], 0, s[54:55]
	global_store_dword v[20:21], v22, off

; DI u32x4 pack8(const f32x4 v0, const f32x4 v1) { u32x4 w; w.x = pk2(v0[0], v0[1]); w.y = pk2(v0[2], v0[3]); w.z = pk2(v1[0], v1[1]); w.w = pk2(v1[2], v1[3]); return w; }
; DI void unpack8(const u32x4 w, f32x4& v0, f32x4& v1) { v0 = (f32x4){bflo(w.x), bfhi(w.x), bflo(w.y), bfhi(w.y)}; v1 = (f32x4){bflo(w.z), bfhi(w.z), bflo(w.w), bfhi(w.w)}; }
;     DI void operator()(const f32x4 (&acc)[2][2][4][2], const Unit& u, int wr, int wc, int fr, int fq, const LAS float* rsl) const {
;     ...
;         for (int ai = 0; ai < 2; ++ai)
; #pragma unroll
;             for (int m = 0; m < 4; ++m) {
;                 const int row = row0 + ai * HALF + m * 16;
;                 if (u.ks < 0) {
;                     const size_t off = (size_t)row * DM + col0; float sq = 0.f;
; #pragma unroll
;                     for (int bj = 0; bj < 2; ++bj) {
;                         f32x4 x0, x1;
;                         if (XF32) { x0 = *(const f32x4*)(Xin + off + bj * HALF); x1 = *(const f32x4*)(Xin + off + bj * HALF + 4); }
;                         else unpack8(xin[ai][m][bj], x0, x1);
;                         x0 += acc[ai][bj][m][0]; x1 += acc[ai][bj][m][1];
;                         *(u32x4*)(act + off + bj * HALF) = pack8(x0, x1);
;                         sq += (x0[0] * x0[0] + x0[1] * x0[1]) + (x0[2] * x0[2] + x0[3] * x0[3]) + (x1[0] * x1[0] + x1[1] * x1[1]) + (x1[2] * x1[2] + x1[3] * x1[3]);
;                     }
;                     sq += __shfl_xor(sq, 16); sq += __shfl_xor(sq, 32);
;                     if (fq == 0) ssq[(size_t)row * 32 + u.pn * 4 + wc] = sq;
;                 } else {
; #pragma unroll
;                     for (int bj = 0; bj < 2; ++bj) { float* pp = part + ((size_t)u.ks * MS + (row - MP)) * DM + col0 + bj * HALF; *(f32x4*)pp = acc[ai][bj][m][0]; *(f32x4*)(pp + 4) = acc[ai][bj][m][1]; }
;                 }
.LBB0_1154:
	s_lshl_b64 s[42:43], s[12:13], 24
	s_add_u32 s42, s65, s42
	s_waitcnt lgkmcnt(0)
	v_lshlrev_b64 v[20:21], 13, v[216:217]
	s_addc_u32 s43, s66, s43
	v_lshl_add_u64 v[20:21], s[42:43], 0, v[20:21]
	s_mov_b32 s42, 0xf8160000
	v_lshl_add_u64 v[20:21], v[214:215], 2, v[20:21]
	s_mov_b32 s43, -1
	v_lshl_add_u64 v[22:23], v[20:21], 0, s[42:43]
	v_add_co_u32_e32 v20, vcc, 0xf8160000, v20
	s_nop 1
	v_addc_co_u32_e32 v21, vcc, -1, v21, vcc
	global_store_dwordx4 v[20:21], v[16:19], off
	global_store_dwordx4 v[22:23], v[12:15], off offset:16
	global_store_dwordx4 v[22:23], v[8:11], off offset:512
	global_store_dwordx4 v[22:23], v[4:7], off offset:528
	s_cbranch_execnz .LBB0_1125
.LBB0_1155:
	s_waitcnt vmcnt(0) lgkmcnt(0)
	v_lshlrev_b32_e32 v24, 16, v88
	v_and_b32_e32 v25, 0xffff0000, v88
	v_lshlrev_b32_e32 v26, 16, v89
	v_and_b32_e32 v27, 0xffff0000, v89
	v_lshlrev_b32_e32 v28, 16, v90
	v_and_b32_e32 v29, 0xffff0000, v90
	v_pk_add_f32 v[16:17], v[16:17], v[24:25]
	v_pk_add_f32 v[18:19], v[18:19], v[26:27]
	v_pk_add_f32 v[26:27], v[12:13], v[28:29]
	v_cvt_pk_bf16_f32 v12, v16, v17
	v_mul_f32_e32 v17, v17, v17
	v_fmac_f32_e32 v17, v16, v16
	v_mul_f32_e32 v16, v19, v19
	v_fmac_f32_e32 v16, v18, v18
	v_lshlrev_b32_e32 v30, 16, v91
	v_and_b32_e32 v31, 0xffff0000, v91
	v_add_f32_e32 v16, v17, v16
	v_mul_f32_e32 v17, v27, v27
	v_pk_add_f32 v[24:25], v[14:15], v[30:31]
	v_fmac_f32_e32 v17, v26, v26
	v_add_f32_e32 v16, v17, v16
	v_mul_f32_e32 v17, v25, v25
	v_fmac_f32_e32 v17, v24, v24
	v_cvt_pk_bf16_f32 v13, v18, v19
	v_add_f32_e32 v28, v17, v16
	v_lshlrev_b32_e32 v16, 16, v84
	v_and_b32_e32 v17, 0xffff0000, v84
	v_lshlrev_b32_e32 v18, 16, v85
	v_and_b32_e32 v19, 0xffff0000, v85
	v_cvt_pk_bf16_f32 v15, v24, v25
	v_lshlrev_b32_e32 v24, 16, v86
	v_and_b32_e32 v25, 0xffff0000, v86
	v_pk_add_f32 v[10:11], v[10:11], v[18:19]
	v_pk_add_f32 v[8:9], v[8:9], v[16:17]
	v_pk_add_f32 v[18:19], v[4:5], v[24:25]
	v_mul_f32_e32 v4, v9, v9
	v_mul_f32_e32 v5, v11, v11
	v_fmac_f32_e32 v4, v8, v8
	v_fmac_f32_e32 v5, v10, v10
	v_cvt_pk_bf16_f32 v14, v26, v27
	v_lshlrev_b32_e32 v26, 16, v87
	v_and_b32_e32 v27, 0xffff0000, v87
	v_add_f32_e32 v4, v4, v5
	v_mul_f32_e32 v5, v19, v19
	v_pk_add_f32 v[16:17], v[6:7], v[26:27]
	v_fmac_f32_e32 v5, v18, v18
	v_add_f32_e32 v4, v5, v4
	v_mul_f32_e32 v5, v17, v17
	v_fmac_f32_e32 v5, v16, v16
	v_add_f32_e32 v4, v5, v4
	v_and_b32_e32 v5, 64, v223
	v_add_f32_e32 v7, v4, v28
	v_xor_b32_e32 v4, 16, v223
	v_add_u32_e32 v24, 64, v5
	v_cmp_lt_i32_e32 vcc, v4, v24
	v_add_u32_e32 v20, 0xb0, v216
	v_ashrrev_i32_e32 v21, 31, v20
	v_cndmask_b32_e32 v4, v223, v4, vcc
	v_lshlrev_b32_e32 v4, 2, v4
	v_lshlrev_b64 v[22:23], 12, v[20:21]
	ds_bpermute_b32 v25, v4, v7
	v_lshl_add_u64 v[4:5], s[18:19], 0, v[22:23]
	v_lshl_add_u64 v[22:23], v[214:215], 1, v[4:5]
	v_xor_b32_e32 v5, 32, v223
	v_cmp_lt_i32_e32 vcc, v5, v24
	s_waitcnt lgkmcnt(0)
	v_add_f32_e32 v4, v7, v25
	v_cvt_pk_bf16_f32 v6, v8, v9
	v_cndmask_b32_e32 v5, v223, v5, vcc
	v_lshlrev_b32_e32 v5, 2, v5
	ds_bpermute_b32 v5, v5, v4
	v_cvt_pk_bf16_f32 v7, v10, v11
	v_cvt_pk_bf16_f32 v8, v18, v19
	v_cvt_pk_bf16_f32 v9, v16, v17
	global_store_dwordx4 v[22:23], v[12:15], off
	global_store_dwordx4 v[22:23], v[6:9], off offset:256
	s_and_saveexec_b64 s[42:43], s[40:41]
	s_cbranch_execz .LBB0_1157
	s_waitcnt lgkmcnt(0)
	v_add_f32_e32 v6, v4, v5
	s_lshl_b32 s52, s22, 2
	v_lshlrev_b64 v[4:5], 7, v[20:21]
	s_ashr_i32 s53, s52, 31
	v_lshl_add_u64 v[4:5], s[34:35], 0, v[4:5]
	v_lshl_add_u64 v[4:5], s[52:53], 2, v[4:5]
	s_lshl_b32 s12, s67, 2
	v_lshl_add_u64 v[4:5], v[4:5], 0, s[12:13]
	global_store_dword v[4:5], v6, off

; DI u32x4 pack8(const f32x4 v0, const f32x4 v1) { u32x4 w; w.x = pk2(v0[0], v0[1]); w.y = pk2(v0[2], v0[3]); w.z = pk2(v1[0], v1[1]); w.w = pk2(v1[2], v1[3]); return w; }
; DI void unpack8(const u32x4 w, f32x4& v0, f32x4& v1) { v0 = (f32x4){bflo(w.x), bfhi(w.x), bflo(w.y), bfhi(w.y)}; v1 = (f32x4){bflo(w.z), bfhi(w.z), bflo(w.w), bfhi(w.w)}; }
;     DI void operator()(const f32x4 (&acc)[2][2][4][2], const Unit& u, int wr, int wc, int fr, int fq, const LAS float* rsl) const {
;     ...
;         for (int ai = 0; ai < 2; ++ai)
; #pragma unroll
;             for (int m = 0; m < 4; ++m) {
;                 const int row = row0 + ai * HALF + m * 16;
;                 if (u.ks < 0) {
;                     const size_t off = (size_t)row * DM + col0; float sq = 0.f;
; #pragma unroll
;                     for (int bj = 0; bj < 2; ++bj) {
;                         f32x4 x0, x1;
;                         if (XF32) { x0 = *(const f32x4*)(Xin + off + bj * HALF); x1 = *(const f32x4*)(Xin + off + bj * HALF + 4); }
;                         else unpack8(xin[ai][m][bj], x0, x1);
;                         x0 += acc[ai][bj][m][0]; x1 += acc[ai][bj][m][1];
;                         *(u32x4*)(act + off + bj * HALF) = pack8(x0, x1);
;                         sq += (x0[0] * x0[0] + x0[1] * x0[1]) + (x0[2] * x0[2] + x0[3] * x0[3]) + (x1[0] * x1[0] + x1[1] * x1[1]) + (x1[2] * x1[2] + x1[3] * x1[3]);
;                     }
;                     sq += __shfl_xor(sq, 16); sq += __shfl_xor(sq, 32);
;                     if (fq == 0) ssq[(size_t)row * 32 + u.pn * 4 + wc] = sq;
;                 } else {
; #pragma unroll
;                     for (int bj = 0; bj < 2; ++bj) { float* pp = part + ((size_t)u.ks * MS + (row - MP)) * DM + col0 + bj * HALF; *(f32x4*)pp = acc[ai][bj][m][0]; *(f32x4*)(pp + 4) = acc[ai][bj][m][1]; }
;                 }
.LBB0_1187:
	v_lshl_or_b32 v142, s22, 8, v147
	v_lshl_add_u32 v144, s80, 8, v1
	s_cmp_gt_i32 s12, -1
	v_ashrrev_i32_e32 v143, 31, v142
	s_mov_b64 s[42:43], -1
	s_cselect_b64 s[54:55], -1, 0
	s_cmp_lt_i32 s12, 0
	v_ashrrev_i32_e32 v145, 31, v144
	s_cbranch_scc1 .LBB0_1189
	s_lshl_b64 s[42:43], s[12:13], 24
	s_add_u32 s42, s67, s42
	v_lshlrev_b64 v[150:151], 13, v[144:145]
	s_addc_u32 s43, s71, s43
	v_lshl_add_u64 v[150:151], s[42:43], 0, v[150:151]
	s_brev_b32 s42, 31
	v_lshl_add_u64 v[150:151], v[142:143], 2, v[150:151]
	s_mov_b32 s43, -1
	v_lshl_add_u64 v[152:153], v[150:151], 0, s[42:43]
	v_add_co_u32_e32 v150, vcc, 0xf8000000, v150
	s_mov_b64 s[42:43], 0
	s_nop 0
	v_addc_co_u32_e32 v151, vcc, -1, v151, vcc
	global_store_dwordx4 v[150:151], v[128:131], off
	global_store_dwordx4 v[152:153], v[124:127], off offset:16
	global_store_dwordx4 v[152:153], v[120:123], off offset:512
	global_store_dwordx4 v[152:153], v[116:119], off offset:528
.LBB0_1189:
	s_andn2_b64 vcc, exec, s[42:43]
	s_movk_i32 s88, 0xf000
	s_cbranch_vccnz .LBB0_1193
	v_lshlrev_b64 v[150:151], 11, v[144:145]
	v_lshl_add_u64 v[158:159], v[150:151], 0, v[142:143]
	v_lshl_add_u64 v[160:161], v[158:159], 2, s[4:5]
	global_load_dwordx4 v[150:153], v[160:161], off
	global_load_dwordx4 v[154:157], v[160:161], off offset:16
	v_lshl_add_u64 v[158:159], v[158:159], 1, s[34:35]
	v_xor_b32_e32 v149, 16, v223
	s_waitcnt vmcnt(0) lgkmcnt(0)
	v_pk_add_f32 v[152:153], v[130:131], v[152:153]
	v_pk_add_f32 v[150:151], v[128:129], v[150:151]
	v_pk_add_f32 v[156:157], v[126:127], v[156:157]
	v_pk_add_f32 v[154:155], v[124:125], v[154:155]
	v_cvt_pk_bf16_f32 v124, v150, v151
	v_cvt_pk_bf16_f32 v125, v152, v153
	v_cvt_pk_bf16_f32 v126, v154, v155
	v_cvt_pk_bf16_f32 v127, v156, v157
	global_store_dwordx4 v[158:159], v[124:127], off
	global_load_dwordx4 v[124:127], v[160:161], off offset:512
	s_nop 0
	global_load_dwordx4 v[128:131], v[160:161], off offset:528
	v_mul_f32_e32 v151, v151, v151
	v_mul_f32_e32 v153, v153, v153
	v_and_b32_e32 v160, 64, v223
	v_mul_f32_e32 v155, v155, v155
	v_fmac_f32_e32 v151, v150, v150
	v_fmac_f32_e32 v153, v152, v152
	v_add_u32_e32 v160, 64, v160
	v_mul_f32_e32 v157, v157, v157
	v_fmac_f32_e32 v155, v154, v154
	v_add_f32_e32 v150, v151, v153
	v_cmp_lt_i32_e32 vcc, v149, v160
	v_fmac_f32_e32 v157, v156, v156
	v_add_f32_e32 v150, v150, v155
	v_cndmask_b32_e32 v149, v223, v149, vcc
	v_add_f32_e32 v150, v157, v150
	v_lshlrev_b32_e32 v149, 2, v149
	s_waitcnt vmcnt(0) lgkmcnt(0)
	v_pk_add_f32 v[122:123], v[122:123], v[126:127]
	v_pk_add_f32 v[120:121], v[120:121], v[124:125]
	v_pk_add_f32 v[126:127], v[116:117], v[128:129]
	v_mul_f32_e32 v116, v121, v121
	v_mul_f32_e32 v117, v123, v123
	v_pk_add_f32 v[124:125], v[118:119], v[130:131]
	v_mul_f32_e32 v118, v127, v127
	v_fmac_f32_e32 v116, v120, v120
	v_fmac_f32_e32 v117, v122, v122
	v_mul_f32_e32 v119, v125, v125
	v_fmac_f32_e32 v118, v126, v126
	v_add_f32_e32 v116, v116, v117
	v_fmac_f32_e32 v119, v124, v124
	v_add_f32_e32 v116, v116, v118
	v_add_f32_e32 v116, v119, v116
	v_add_f32_e32 v116, v150, v116
	ds_bpermute_b32 v117, v149, v116
	v_xor_b32_e32 v118, 32, v223
	v_cmp_lt_i32_e32 vcc, v118, v160
	s_waitcnt lgkmcnt(0)
	v_add_f32_e32 v116, v116, v117
	v_cndmask_b32_e32 v119, v223, v118, vcc
	v_lshlrev_b32_e32 v117, 2, v119
	ds_bpermute_b32 v117, v117, v116
	v_cvt_pk_bf16_f32 v118, v120, v121
	v_cvt_pk_bf16_f32 v119, v122, v123
	v_cvt_pk_bf16_f32 v120, v126, v127
	v_cvt_pk_bf16_f32 v121, v124, v125
	global_store_dwordx4 v[158:159], v[118:121], off offset:256
	s_and_saveexec_b64 s[42:43], s[40:41]
	s_cbranch_execz .LBB0_1192
	s_waitcnt lgkmcnt(0)
	v_add_f32_e32 v118, v116, v117
	s_lshl_b32 s56, s22, 2
	v_lshlrev_b64 v[116:117], 7, v[144:145]
	s_ashr_i32 s57, s56, 31
	v_lshl_add_u64 v[116:117], s[38:39], 0, v[116:117]
	v_lshl_add_u64 v[116:117], s[56:57], 2, v[116:117]
	s_lshl_b32 s56, s72, 2
	s_mov_b32 s57, s13
	v_lshl_add_u64 v[116:117], v[116:117], 0, s[56:57]
	global_store_dword v[116:117], v118, off

; DI u32x4 pack8(const f32x4 v0, const f32x4 v1) { u32x4 w; w.x = pk2(v0[0], v0[1]); w.y = pk2(v0[2], v0[3]); w.z = pk2(v1[0], v1[1]); w.w = pk2(v1[2], v1[3]); return w; }
; DI void unpack8(const u32x4 w, f32x4& v0, f32x4& v1) { v0 = (f32x4){bflo(w.x), bfhi(w.x), bflo(w.y), bfhi(w.y)}; v1 = (f32x4){bflo(w.z), bfhi(w.z), bflo(w.w), bfhi(w.w)}; }
;     DI void operator()(const f32x4 (&acc)[2][2][4][2], const Unit& u, int wr, int wc, int fr, int fq, const LAS float* rsl) const {
;     ...
;         for (int ai = 0; ai < 2; ++ai)
; #pragma unroll
;             for (int m = 0; m < 4; ++m) {
;                 const int row = row0 + ai * HALF + m * 16;
;                 if (u.ks < 0) {
;                     const size_t off = (size_t)row * DM + col0; float sq = 0.f;
; #pragma unroll
;                     for (int bj = 0; bj < 2; ++bj) {
;                         f32x4 x0, x1;
;                         if (XF32) { x0 = *(const f32x4*)(Xin + off + bj * HALF); x1 = *(const f32x4*)(Xin + off + bj * HALF + 4); }
;                         else unpack8(xin[ai][m][bj], x0, x1);
;                         x0 += acc[ai][bj][m][0]; x1 += acc[ai][bj][m][1];
;                         *(u32x4*)(act + off + bj * HALF) = pack8(x0, x1);
;                         sq += (x0[0] * x0[0] + x0[1] * x0[1]) + (x0[2] * x0[2] + x0[3] * x0[3]) + (x1[0] * x1[0] + x1[1] * x1[1]) + (x1[2] * x1[2] + x1[3] * x1[3]);
;                     }
;                     sq += __shfl_xor(sq, 16); sq += __shfl_xor(sq, 32);
;                     if (fq == 0) ssq[(size_t)row * 32 + u.pn * 4 + wc] = sq;
;                 } else {
; #pragma unroll
;                     for (int bj = 0; bj < 2; ++bj) { float* pp = part + ((size_t)u.ks * MS + (row - MP)) * DM + col0 + bj * HALF; *(f32x4*)pp = acc[ai][bj][m][0]; *(f32x4*)(pp + 4) = acc[ai][bj][m][1]; }
;                 }
.LBB0_1208:
	s_lshl_b64 s[54:55], s[12:13], 24
	s_add_u32 s54, s67, s54
	s_waitcnt lgkmcnt(0)
	v_lshlrev_b64 v[116:117], 13, v[144:145]
	s_addc_u32 s55, s71, s55
	v_lshl_add_u64 v[116:117], s[54:55], 0, v[116:117]
	s_mov_b32 s54, 0xf8020000
	v_lshl_add_u64 v[116:117], v[142:143], 2, v[116:117]
	s_mov_b32 s55, -1
	v_lshl_add_u64 v[118:119], v[116:117], 0, s[54:55]
	v_add_co_u32_e32 v116, vcc, 0xf8020000, v116
	s_nop 1
	v_addc_co_u32_e32 v117, vcc, -1, v117, vcc
	global_store_dwordx4 v[116:117], v[112:115], off
	global_store_dwordx4 v[118:119], v[108:111], off offset:16
	global_store_dwordx4 v[118:119], v[104:107], off offset:512
	global_store_dwordx4 v[118:119], v[100:103], off offset:528
	s_cbranch_execnz .LBB0_1195
.LBB0_1209:
	v_or_b32_e32 v116, 16, v144
	s_waitcnt lgkmcnt(0)
	v_ashrrev_i32_e32 v117, 31, v116
	v_lshlrev_b64 v[118:119], 11, v[116:117]
	v_lshl_add_u64 v[126:127], v[118:119], 0, v[142:143]
	v_lshl_add_u64 v[128:129], v[126:127], 2, s[4:5]
	global_load_dwordx4 v[118:121], v[128:129], off
	global_load_dwordx4 v[122:125], v[128:129], off offset:16
	v_lshl_add_u64 v[126:127], v[126:127], 1, s[34:35]
	s_waitcnt vmcnt(0) lgkmcnt(0)
	v_pk_add_f32 v[120:121], v[114:115], v[120:121]
	v_pk_add_f32 v[118:119], v[112:113], v[118:119]
	v_pk_add_f32 v[124:125], v[110:111], v[124:125]
	v_pk_add_f32 v[122:123], v[108:109], v[122:123]
	v_cvt_pk_bf16_f32 v108, v118, v119
	v_cvt_pk_bf16_f32 v109, v120, v121
	v_cvt_pk_bf16_f32 v110, v122, v123
	v_cvt_pk_bf16_f32 v111, v124, v125
	global_store_dwordx4 v[126:127], v[108:111], off
	global_load_dwordx4 v[108:111], v[128:129], off offset:512
	s_nop 0
	global_load_dwordx4 v[112:115], v[128:129], off offset:528
	v_mul_f32_e32 v119, v119, v119
	v_mul_f32_e32 v121, v121, v121
	v_and_b32_e32 v129, 64, v223
	v_mul_f32_e32 v123, v123, v123
	v_fmac_f32_e32 v119, v118, v118
	v_fmac_f32_e32 v121, v120, v120
	v_xor_b32_e32 v128, 16, v223
	v_add_u32_e32 v129, 64, v129
	v_mul_f32_e32 v125, v125, v125
	v_fmac_f32_e32 v123, v122, v122
	v_add_f32_e32 v118, v119, v121
	v_cmp_lt_i32_e32 vcc, v128, v129
	v_fmac_f32_e32 v125, v124, v124
	v_add_f32_e32 v118, v118, v123
	v_cndmask_b32_e32 v128, v223, v128, vcc
	v_add_f32_e32 v118, v125, v118
	v_lshlrev_b32_e32 v128, 2, v128
	s_waitcnt vmcnt(0) lgkmcnt(0)
	v_pk_add_f32 v[106:107], v[106:107], v[110:111]
	v_pk_add_f32 v[104:105], v[104:105], v[108:109]
	v_pk_add_f32 v[110:111], v[100:101], v[112:113]
	v_mul_f32_e32 v100, v105, v105
	v_mul_f32_e32 v101, v107, v107
	v_pk_add_f32 v[108:109], v[102:103], v[114:115]
	v_mul_f32_e32 v102, v111, v111
	v_fmac_f32_e32 v100, v104, v104
	v_fmac_f32_e32 v101, v106, v106
	v_mul_f32_e32 v103, v109, v109
	v_fmac_f32_e32 v102, v110, v110
	v_add_f32_e32 v100, v100, v101
	v_fmac_f32_e32 v103, v108, v108
	v_add_f32_e32 v100, v100, v102
	v_add_f32_e32 v100, v103, v100
	v_add_f32_e32 v100, v118, v100
	ds_bpermute_b32 v101, v128, v100
	v_xor_b32_e32 v102, 32, v223
	v_cmp_lt_i32_e32 vcc, v102, v129
	s_waitcnt lgkmcnt(0)
	v_add_f32_e32 v100, v100, v101
	v_cndmask_b32_e32 v103, v223, v102, vcc
	v_lshlrev_b32_e32 v101, 2, v103
	ds_bpermute_b32 v101, v101, v100
	v_cvt_pk_bf16_f32 v102, v104, v105
	v_cvt_pk_bf16_f32 v103, v106, v107
	v_cvt_pk_bf16_f32 v104, v110, v111
	v_cvt_pk_bf16_f32 v105, v108, v109
	global_store_dwordx4 v[126:127], v[102:105], off offset:256
	s_and_saveexec_b64 s[54:55], s[40:41]
	s_cbranch_execz .LBB0_1211
	s_waitcnt lgkmcnt(0)
	v_add_f32_e32 v102, v100, v101
	s_lshl_b32 s56, s22, 2
	v_lshlrev_b64 v[100:101], 7, v[116:117]
	s_ashr_i32 s57, s56, 31
	v_lshl_add_u64 v[100:101], s[38:39], 0, v[100:101]
	v_lshl_add_u64 v[100:101], s[56:57], 2, v[100:101]
	s_lshl_b32 s56, s72, 2
	s_mov_b32 s57, s13
	v_lshl_add_u64 v[100:101], v[100:101], 0, s[56:57]
	global_store_dword v[100:101], v102, off

; DI u32x4 pack8(const f32x4 v0, const f32x4 v1) { u32x4 w; w.x = pk2(v0[0], v0[1]); w.y = pk2(v0[2], v0[3]); w.z = pk2(v1[0], v1[1]); w.w = pk2(v1[2], v1[3]); return w; }
; DI void unpack8(const u32x4 w, f32x4& v0, f32x4& v1) { v0 = (f32x4){bflo(w.x), bfhi(w.x), bflo(w.y), bfhi(w.y)}; v1 = (f32x4){bflo(w.z), bfhi(w.z), bflo(w.w), bfhi(w.w)}; }
;     DI void operator()(const f32x4 (&acc)[2][2][4][2], const Unit& u, int wr, int wc, int fr, int fq, const LAS float* rsl) const {
;     ...
;         for (int ai = 0; ai < 2; ++ai)
; #pragma unroll
;             for (int m = 0; m < 4; ++m) {
;                 const int row = row0 + ai * HALF + m * 16;
;                 if (u.ks < 0) {
;                     const size_t off = (size_t)row * DM + col0; float sq = 0.f;
; #pragma unroll
;                     for (int bj = 0; bj < 2; ++bj) {
;                         f32x4 x0, x1;
;                         if (XF32) { x0 = *(const f32x4*)(Xin + off + bj * HALF); x1 = *(const f32x4*)(Xin + off + bj * HALF + 4); }
;                         else unpack8(xin[ai][m][bj], x0, x1);
;                         x0 += acc[ai][bj][m][0]; x1 += acc[ai][bj][m][1];
;                         *(u32x4*)(act + off + bj * HALF) = pack8(x0, x1);
;                         sq += (x0[0] * x0[0] + x0[1] * x0[1]) + (x0[2] * x0[2] + x0[3] * x0[3]) + (x1[0] * x1[0] + x1[1] * x1[1]) + (x1[2] * x1[2] + x1[3] * x1[3]);
;                     }
;                     sq += __shfl_xor(sq, 16); sq += __shfl_xor(sq, 32);
;                     if (fq == 0) ssq[(size_t)row * 32 + u.pn * 4 + wc] = sq;
;                 } else {
; #pragma unroll
;                     for (int bj = 0; bj < 2; ++bj) { float* pp = part + ((size_t)u.ks * MS + (row - MP)) * DM + col0 + bj * HALF; *(f32x4*)pp = acc[ai][bj][m][0]; *(f32x4*)(pp + 4) = acc[ai][bj][m][1]; }
;                 }
.LBB0_1212:
	s_lshl_b64 s[54:55], s[12:13], 24
	s_add_u32 s54, s67, s54
	s_waitcnt lgkmcnt(0)
	v_lshlrev_b64 v[100:101], 13, v[144:145]
	s_addc_u32 s55, s71, s55
	v_lshl_add_u64 v[100:101], s[54:55], 0, v[100:101]
	s_mov_b32 s54, 0xf8040000
	v_lshl_add_u64 v[100:101], v[142:143], 2, v[100:101]
	s_mov_b32 s55, -1
	v_lshl_add_u64 v[102:103], v[100:101], 0, s[54:55]
	v_add_co_u32_e32 v100, vcc, 0xf8040000, v100
	s_nop 1
	v_addc_co_u32_e32 v101, vcc, -1, v101, vcc
	global_store_dwordx4 v[100:101], v[96:99], off
	global_store_dwordx4 v[102:103], v[92:95], off offset:16
	global_store_dwordx4 v[102:103], v[88:91], off offset:512
	global_store_dwordx4 v[102:103], v[84:87], off offset:528
	s_cbranch_execnz .LBB0_1197
.LBB0_1213:
	v_or_b32_e32 v100, 32, v144
	s_waitcnt lgkmcnt(0)
	v_ashrrev_i32_e32 v101, 31, v100
	v_lshlrev_b64 v[102:103], 11, v[100:101]
	v_lshl_add_u64 v[110:111], v[102:103], 0, v[142:143]
	v_lshl_add_u64 v[112:113], v[110:111], 2, s[4:5]
	global_load_dwordx4 v[102:105], v[112:113], off
	global_load_dwordx4 v[106:109], v[112:113], off offset:16
	v_lshl_add_u64 v[110:111], v[110:111], 1, s[34:35]
	s_waitcnt vmcnt(0) lgkmcnt(0)
	v_pk_add_f32 v[104:105], v[98:99], v[104:105]
	v_pk_add_f32 v[102:103], v[96:97], v[102:103]
	v_pk_add_f32 v[108:109], v[94:95], v[108:109]
	v_pk_add_f32 v[106:107], v[92:93], v[106:107]
	v_cvt_pk_bf16_f32 v92, v102, v103
	v_cvt_pk_bf16_f32 v93, v104, v105
	v_cvt_pk_bf16_f32 v94, v106, v107
	v_cvt_pk_bf16_f32 v95, v108, v109
	global_store_dwordx4 v[110:111], v[92:95], off
	global_load_dwordx4 v[92:95], v[112:113], off offset:512
	s_nop 0
	global_load_dwordx4 v[96:99], v[112:113], off offset:528
	v_mul_f32_e32 v103, v103, v103
	v_mul_f32_e32 v105, v105, v105
	v_and_b32_e32 v113, 64, v223
	v_mul_f32_e32 v107, v107, v107
	v_fmac_f32_e32 v103, v102, v102
	v_fmac_f32_e32 v105, v104, v104
	v_xor_b32_e32 v112, 16, v223
	v_add_u32_e32 v113, 64, v113
	v_mul_f32_e32 v109, v109, v109
	v_fmac_f32_e32 v107, v106, v106
	v_add_f32_e32 v102, v103, v105
	v_cmp_lt_i32_e32 vcc, v112, v113
	v_fmac_f32_e32 v109, v108, v108
	v_add_f32_e32 v102, v102, v107
	v_cndmask_b32_e32 v112, v223, v112, vcc
	v_add_f32_e32 v102, v109, v102
	v_lshlrev_b32_e32 v112, 2, v112
	s_waitcnt vmcnt(0) lgkmcnt(0)
	v_pk_add_f32 v[90:91], v[90:91], v[94:95]
	v_pk_add_f32 v[88:89], v[88:89], v[92:93]
	v_pk_add_f32 v[94:95], v[84:85], v[96:97]
	v_mul_f32_e32 v84, v89, v89
	v_mul_f32_e32 v85, v91, v91
	v_pk_add_f32 v[92:93], v[86:87], v[98:99]
	v_mul_f32_e32 v86, v95, v95
	v_fmac_f32_e32 v84, v88, v88
	v_fmac_f32_e32 v85, v90, v90
	v_mul_f32_e32 v87, v93, v93
	v_fmac_f32_e32 v86, v94, v94
	v_add_f32_e32 v84, v84, v85
	v_fmac_f32_e32 v87, v92, v92
	v_add_f32_e32 v84, v84, v86
	v_add_f32_e32 v84, v87, v84
	v_add_f32_e32 v84, v102, v84
	ds_bpermute_b32 v85, v112, v84
	v_xor_b32_e32 v86, 32, v223
	v_cmp_lt_i32_e32 vcc, v86, v113
	s_waitcnt lgkmcnt(0)
	v_add_f32_e32 v84, v84, v85
	v_cndmask_b32_e32 v87, v223, v86, vcc
	v_lshlrev_b32_e32 v85, 2, v87
	ds_bpermute_b32 v85, v85, v84
	v_cvt_pk_bf16_f32 v86, v88, v89
	v_cvt_pk_bf16_f32 v87, v90, v91
	v_cvt_pk_bf16_f32 v88, v94, v95
	v_cvt_pk_bf16_f32 v89, v92, v93
	global_store_dwordx4 v[110:111], v[86:89], off offset:256
	s_and_saveexec_b64 s[54:55], s[40:41]
	s_cbranch_execz .LBB0_1215
	s_waitcnt lgkmcnt(0)
	v_add_f32_e32 v86, v84, v85
	s_lshl_b32 s56, s22, 2
	v_lshlrev_b64 v[84:85], 7, v[100:101]
	s_ashr_i32 s57, s56, 31
	v_lshl_add_u64 v[84:85], s[38:39], 0, v[84:85]
	v_lshl_add_u64 v[84:85], s[56:57], 2, v[84:85]
	s_lshl_b32 s56, s72, 2
	s_mov_b32 s57, s13
	v_lshl_add_u64 v[84:85], v[84:85], 0, s[56:57]
	global_store_dword v[84:85], v86, off

; DI u32x4 pack8(const f32x4 v0, const f32x4 v1) { u32x4 w; w.x = pk2(v0[0], v0[1]); w.y = pk2(v0[2], v0[3]); w.z = pk2(v1[0], v1[1]); w.w = pk2(v1[2], v1[3]); return w; }
; DI void unpack8(const u32x4 w, f32x4& v0, f32x4& v1) { v0 = (f32x4){bflo(w.x), bfhi(w.x), bflo(w.y), bfhi(w.y)}; v1 = (f32x4){bflo(w.z), bfhi(w.z), bflo(w.w), bfhi(w.w)}; }
;     DI void operator()(const f32x4 (&acc)[2][2][4][2], const Unit& u, int wr, int wc, int fr, int fq, const LAS float* rsl) const {
;     ...
;         for (int ai = 0; ai < 2; ++ai)
; #pragma unroll
;             for (int m = 0; m < 4; ++m) {
;                 const int row = row0 + ai * HALF + m * 16;
;                 if (u.ks < 0) {
;                     const size_t off = (size_t)row * DM + col0; float sq = 0.f;
; #pragma unroll
;                     for (int bj = 0; bj < 2; ++bj) {
;                         f32x4 x0, x1;
;                         if (XF32) { x0 = *(const f32x4*)(Xin + off + bj * HALF); x1 = *(const f32x4*)(Xin + off + bj * HALF + 4); }
;                         else unpack8(xin[ai][m][bj], x0, x1);
;                         x0 += acc[ai][bj][m][0]; x1 += acc[ai][bj][m][1];
;                         *(u32x4*)(act + off + bj * HALF) = pack8(x0, x1);
;                         sq += (x0[0] * x0[0] + x0[1] * x0[1]) + (x0[2] * x0[2] + x0[3] * x0[3]) + (x1[0] * x1[0] + x1[1] * x1[1]) + (x1[2] * x1[2] + x1[3] * x1[3]);
;                     }
;                     sq += __shfl_xor(sq, 16); sq += __shfl_xor(sq, 32);
;                     if (fq == 0) ssq[(size_t)row * 32 + u.pn * 4 + wc] = sq;
;                 } else {
; #pragma unroll
;                     for (int bj = 0; bj < 2; ++bj) { float* pp = part + ((size_t)u.ks * MS + (row - MP)) * DM + col0 + bj * HALF; *(f32x4*)pp = acc[ai][bj][m][0]; *(f32x4*)(pp + 4) = acc[ai][bj][m][1]; }
;                 }
.LBB0_1216:
	s_lshl_b64 s[54:55], s[12:13], 24
	s_add_u32 s54, s67, s54
	s_waitcnt lgkmcnt(0)
	v_lshlrev_b64 v[84:85], 13, v[144:145]
	s_addc_u32 s55, s71, s55
	v_lshl_add_u64 v[84:85], s[54:55], 0, v[84:85]
	s_mov_b32 s54, 0xf8060000
	v_lshl_add_u64 v[84:85], v[142:143], 2, v[84:85]
	s_mov_b32 s55, -1
	v_lshl_add_u64 v[86:87], v[84:85], 0, s[54:55]
	v_add_co_u32_e32 v84, vcc, 0xf8060000, v84
	s_nop 1
	v_addc_co_u32_e32 v85, vcc, -1, v85, vcc
	global_store_dwordx4 v[84:85], v[80:83], off
	global_store_dwordx4 v[86:87], v[76:79], off offset:16
	global_store_dwordx4 v[86:87], v[72:75], off offset:512
	global_store_dwordx4 v[86:87], v[68:71], off offset:528
	s_cbranch_execnz .LBB0_1199
.LBB0_1217:
	v_or_b32_e32 v84, 48, v144
	s_waitcnt lgkmcnt(0)
	v_ashrrev_i32_e32 v85, 31, v84
	v_lshlrev_b64 v[86:87], 11, v[84:85]
	v_lshl_add_u64 v[94:95], v[86:87], 0, v[142:143]
	v_lshl_add_u64 v[96:97], v[94:95], 2, s[4:5]
	global_load_dwordx4 v[86:89], v[96:97], off
	global_load_dwordx4 v[90:93], v[96:97], off offset:16
	v_lshl_add_u64 v[94:95], v[94:95], 1, s[34:35]
	s_waitcnt vmcnt(0) lgkmcnt(0)
	v_pk_add_f32 v[88:89], v[82:83], v[88:89]
	v_pk_add_f32 v[86:87], v[80:81], v[86:87]
	v_pk_add_f32 v[92:93], v[78:79], v[92:93]
	v_pk_add_f32 v[90:91], v[76:77], v[90:91]
	v_cvt_pk_bf16_f32 v76, v86, v87
	v_cvt_pk_bf16_f32 v77, v88, v89
	v_cvt_pk_bf16_f32 v78, v90, v91
	v_cvt_pk_bf16_f32 v79, v92, v93
	global_store_dwordx4 v[94:95], v[76:79], off
	global_load_dwordx4 v[76:79], v[96:97], off offset:512
	s_nop 0
	global_load_dwordx4 v[80:83], v[96:97], off offset:528
	v_mul_f32_e32 v87, v87, v87
	v_mul_f32_e32 v89, v89, v89
	v_and_b32_e32 v97, 64, v223
	v_mul_f32_e32 v91, v91, v91
	v_fmac_f32_e32 v87, v86, v86
	v_fmac_f32_e32 v89, v88, v88
	v_xor_b32_e32 v96, 16, v223
	v_add_u32_e32 v97, 64, v97
	v_mul_f32_e32 v93, v93, v93
	v_fmac_f32_e32 v91, v90, v90
	v_add_f32_e32 v86, v87, v89
	v_cmp_lt_i32_e32 vcc, v96, v97
	v_fmac_f32_e32 v93, v92, v92
	v_add_f32_e32 v86, v86, v91
	v_cndmask_b32_e32 v96, v223, v96, vcc
	v_add_f32_e32 v86, v93, v86
	v_lshlrev_b32_e32 v96, 2, v96
	s_waitcnt vmcnt(0) lgkmcnt(0)
	v_pk_add_f32 v[74:75], v[74:75], v[78:79]
	v_pk_add_f32 v[72:73], v[72:73], v[76:77]
	v_pk_add_f32 v[78:79], v[68:69], v[80:81]
	v_mul_f32_e32 v68, v73, v73
	v_mul_f32_e32 v69, v75, v75
	v_pk_add_f32 v[76:77], v[70:71], v[82:83]
	v_mul_f32_e32 v70, v79, v79
	v_fmac_f32_e32 v68, v72, v72
	v_fmac_f32_e32 v69, v74, v74
	v_mul_f32_e32 v71, v77, v77
	v_fmac_f32_e32 v70, v78, v78
	v_add_f32_e32 v68, v68, v69
	v_fmac_f32_e32 v71, v76, v76
	v_add_f32_e32 v68, v68, v70
	v_add_f32_e32 v68, v71, v68
	v_add_f32_e32 v68, v86, v68
	ds_bpermute_b32 v69, v96, v68
	v_xor_b32_e32 v70, 32, v223
	v_cmp_lt_i32_e32 vcc, v70, v97
	s_waitcnt lgkmcnt(0)
	v_add_f32_e32 v68, v68, v69
	v_cndmask_b32_e32 v71, v223, v70, vcc
	v_lshlrev_b32_e32 v69, 2, v71
	ds_bpermute_b32 v69, v69, v68
	v_cvt_pk_bf16_f32 v70, v72, v73
	v_cvt_pk_bf16_f32 v71, v74, v75
	v_cvt_pk_bf16_f32 v72, v78, v79
	v_cvt_pk_bf16_f32 v73, v76, v77
	global_store_dwordx4 v[94:95], v[70:73], off offset:256
	s_and_saveexec_b64 s[54:55], s[40:41]
	s_cbranch_execz .LBB0_1219
	s_waitcnt lgkmcnt(0)
	v_add_f32_e32 v70, v68, v69
	s_lshl_b32 s56, s22, 2
	v_lshlrev_b64 v[68:69], 7, v[84:85]
	s_ashr_i32 s57, s56, 31
	v_lshl_add_u64 v[68:69], s[38:39], 0, v[68:69]
	v_lshl_add_u64 v[68:69], s[56:57], 2, v[68:69]
	s_lshl_b32 s56, s72, 2
	s_mov_b32 s57, s13
	v_lshl_add_u64 v[68:69], v[68:69], 0, s[56:57]
	global_store_dword v[68:69], v70, off

; DI u32x4 pack8(const f32x4 v0, const f32x4 v1) { u32x4 w; w.x = pk2(v0[0], v0[1]); w.y = pk2(v0[2], v0[3]); w.z = pk2(v1[0], v1[1]); w.w = pk2(v1[2], v1[3]); return w; }
; DI void unpack8(const u32x4 w, f32x4& v0, f32x4& v1) { v0 = (f32x4){bflo(w.x), bfhi(w.x), bflo(w.y), bfhi(w.y)}; v1 = (f32x4){bflo(w.z), bfhi(w.z), bflo(w.w), bfhi(w.w)}; }
;     DI void operator()(const f32x4 (&acc)[2][2][4][2], const Unit& u, int wr, int wc, int fr, int fq, const LAS float* rsl) const {
;     ...
;         for (int ai = 0; ai < 2; ++ai)
; #pragma unroll
;             for (int m = 0; m < 4; ++m) {
;                 const int row = row0 + ai * HALF + m * 16;
;                 if (u.ks < 0) {
;                     const size_t off = (size_t)row * DM + col0; float sq = 0.f;
; #pragma unroll
;                     for (int bj = 0; bj < 2; ++bj) {
;                         f32x4 x0, x1;
;                         if (XF32) { x0 = *(const f32x4*)(Xin + off + bj * HALF); x1 = *(const f32x4*)(Xin + off + bj * HALF + 4); }
;                         else unpack8(xin[ai][m][bj], x0, x1);
;                         x0 += acc[ai][bj][m][0]; x1 += acc[ai][bj][m][1];
;                         *(u32x4*)(act + off + bj * HALF) = pack8(x0, x1);
;                         sq += (x0[0] * x0[0] + x0[1] * x0[1]) + (x0[2] * x0[2] + x0[3] * x0[3]) + (x1[0] * x1[0] + x1[1] * x1[1]) + (x1[2] * x1[2] + x1[3] * x1[3]);
;                     }
;                     sq += __shfl_xor(sq, 16); sq += __shfl_xor(sq, 32);
;                     if (fq == 0) ssq[(size_t)row * 32 + u.pn * 4 + wc] = sq;
;                 } else {
; #pragma unroll
;                     for (int bj = 0; bj < 2; ++bj) { float* pp = part + ((size_t)u.ks * MS + (row - MP)) * DM + col0 + bj * HALF; *(f32x4*)pp = acc[ai][bj][m][0]; *(f32x4*)(pp + 4) = acc[ai][bj][m][1]; }
;                 }
.LBB0_1220:
	s_lshl_b64 s[54:55], s[12:13], 24
	s_add_u32 s54, s67, s54
	s_waitcnt lgkmcnt(0)
	v_lshlrev_b64 v[68:69], 13, v[144:145]
	s_addc_u32 s55, s71, s55
	v_lshl_add_u64 v[68:69], s[54:55], 0, v[68:69]
	s_mov_b32 s54, 0xf8100000
	v_lshl_add_u64 v[68:69], v[142:143], 2, v[68:69]
	s_mov_b32 s55, -1
	v_lshl_add_u64 v[70:71], v[68:69], 0, s[54:55]
	v_add_co_u32_e32 v68, vcc, 0xf8100000, v68
	s_nop 1
	v_addc_co_u32_e32 v69, vcc, -1, v69, vcc
	global_store_dwordx4 v[68:69], v[64:67], off
	global_store_dwordx4 v[70:71], v[60:63], off offset:16
	global_store_dwordx4 v[70:71], v[56:59], off offset:512
	global_store_dwordx4 v[70:71], v[52:55], off offset:528
	s_cbranch_execnz .LBB0_1201
.LBB0_1221:
	v_add_u32_e32 v68, 0x80, v144
	s_waitcnt lgkmcnt(0)
	v_ashrrev_i32_e32 v69, 31, v68
	v_lshlrev_b64 v[70:71], 11, v[68:69]
	v_lshl_add_u64 v[78:79], v[70:71], 0, v[142:143]
	v_lshl_add_u64 v[80:81], v[78:79], 2, s[4:5]
	global_load_dwordx4 v[70:73], v[80:81], off
	global_load_dwordx4 v[74:77], v[80:81], off offset:16
	v_lshl_add_u64 v[78:79], v[78:79], 1, s[34:35]
	s_waitcnt vmcnt(0) lgkmcnt(0)
	v_pk_add_f32 v[72:73], v[66:67], v[72:73]
	v_pk_add_f32 v[70:71], v[64:65], v[70:71]
	v_pk_add_f32 v[76:77], v[62:63], v[76:77]
	v_pk_add_f32 v[74:75], v[60:61], v[74:75]
	v_cvt_pk_bf16_f32 v60, v70, v71
	v_cvt_pk_bf16_f32 v61, v72, v73
	v_cvt_pk_bf16_f32 v62, v74, v75
	v_cvt_pk_bf16_f32 v63, v76, v77
	global_store_dwordx4 v[78:79], v[60:63], off
	global_load_dwordx4 v[60:63], v[80:81], off offset:512
	s_nop 0
	global_load_dwordx4 v[64:67], v[80:81], off offset:528
	v_mul_f32_e32 v71, v71, v71
	v_mul_f32_e32 v73, v73, v73
	v_and_b32_e32 v81, 64, v223
	v_mul_f32_e32 v75, v75, v75
	v_fmac_f32_e32 v71, v70, v70
	v_fmac_f32_e32 v73, v72, v72
	v_xor_b32_e32 v80, 16, v223
	v_add_u32_e32 v81, 64, v81
	v_mul_f32_e32 v77, v77, v77
	v_fmac_f32_e32 v75, v74, v74
	v_add_f32_e32 v70, v71, v73
	v_cmp_lt_i32_e32 vcc, v80, v81
	v_fmac_f32_e32 v77, v76, v76
	v_add_f32_e32 v70, v70, v75
	v_cndmask_b32_e32 v80, v223, v80, vcc
	v_add_f32_e32 v70, v77, v70
	v_lshlrev_b32_e32 v80, 2, v80
	s_waitcnt vmcnt(0) lgkmcnt(0)
	v_pk_add_f32 v[58:59], v[58:59], v[62:63]
	v_pk_add_f32 v[56:57], v[56:57], v[60:61]
	v_pk_add_f32 v[62:63], v[52:53], v[64:65]
	v_mul_f32_e32 v52, v57, v57
	v_mul_f32_e32 v53, v59, v59
	v_pk_add_f32 v[60:61], v[54:55], v[66:67]
	v_mul_f32_e32 v54, v63, v63
	v_fmac_f32_e32 v52, v56, v56
	v_fmac_f32_e32 v53, v58, v58
	v_mul_f32_e32 v55, v61, v61
	v_fmac_f32_e32 v54, v62, v62
	v_add_f32_e32 v52, v52, v53
	v_fmac_f32_e32 v55, v60, v60
	v_add_f32_e32 v52, v52, v54
	v_add_f32_e32 v52, v55, v52
	v_add_f32_e32 v52, v70, v52
	ds_bpermute_b32 v53, v80, v52
	v_xor_b32_e32 v54, 32, v223
	v_cmp_lt_i32_e32 vcc, v54, v81
	s_waitcnt lgkmcnt(0)
	v_add_f32_e32 v52, v52, v53
	v_cndmask_b32_e32 v55, v223, v54, vcc
	v_lshlrev_b32_e32 v53, 2, v55
	ds_bpermute_b32 v53, v53, v52
	v_cvt_pk_bf16_f32 v54, v56, v57
	v_cvt_pk_bf16_f32 v55, v58, v59
	v_cvt_pk_bf16_f32 v56, v62, v63
	v_cvt_pk_bf16_f32 v57, v60, v61
	global_store_dwordx4 v[78:79], v[54:57], off offset:256
	s_and_saveexec_b64 s[54:55], s[40:41]
	s_cbranch_execz .LBB0_1223
	s_waitcnt lgkmcnt(0)
	v_add_f32_e32 v54, v52, v53
	s_lshl_b32 s56, s22, 2
	v_lshlrev_b64 v[52:53], 7, v[68:69]
	s_ashr_i32 s57, s56, 31
	v_lshl_add_u64 v[52:53], s[38:39], 0, v[52:53]
	v_lshl_add_u64 v[52:53], s[56:57], 2, v[52:53]
	s_lshl_b32 s56, s72, 2
	s_mov_b32 s57, s13
	v_lshl_add_u64 v[52:53], v[52:53], 0, s[56:57]
	global_store_dword v[52:53], v54, off

; DI u32x4 pack8(const f32x4 v0, const f32x4 v1) { u32x4 w; w.x = pk2(v0[0], v0[1]); w.y = pk2(v0[2], v0[3]); w.z = pk2(v1[0], v1[1]); w.w = pk2(v1[2], v1[3]); return w; }
; DI void unpack8(const u32x4 w, f32x4& v0, f32x4& v1) { v0 = (f32x4){bflo(w.x), bfhi(w.x), bflo(w.y), bfhi(w.y)}; v1 = (f32x4){bflo(w.z), bfhi(w.z), bflo(w.w), bfhi(w.w)}; }
;     DI void operator()(const f32x4 (&acc)[2][2][4][2], const Unit& u, int wr, int wc, int fr, int fq, const LAS float* rsl) const {
;     ...
;         for (int ai = 0; ai < 2; ++ai)
; #pragma unroll
;             for (int m = 0; m < 4; ++m) {
;                 const int row = row0 + ai * HALF + m * 16;
;                 if (u.ks < 0) {
;                     const size_t off = (size_t)row * DM + col0; float sq = 0.f;
; #pragma unroll
;                     for (int bj = 0; bj < 2; ++bj) {
;                         f32x4 x0, x1;
;                         if (XF32) { x0 = *(const f32x4*)(Xin + off + bj * HALF); x1 = *(const f32x4*)(Xin + off + bj * HALF + 4); }
;                         else unpack8(xin[ai][m][bj], x0, x1);
;                         x0 += acc[ai][bj][m][0]; x1 += acc[ai][bj][m][1];
;                         *(u32x4*)(act + off + bj * HALF) = pack8(x0, x1);
;                         sq += (x0[0] * x0[0] + x0[1] * x0[1]) + (x0[2] * x0[2] + x0[3] * x0[3]) + (x1[0] * x1[0] + x1[1] * x1[1]) + (x1[2] * x1[2] + x1[3] * x1[3]);
;                     }
;                     sq += __shfl_xor(sq, 16); sq += __shfl_xor(sq, 32);
;                     if (fq == 0) ssq[(size_t)row * 32 + u.pn * 4 + wc] = sq;
;                 } else {
; #pragma unroll
;                     for (int bj = 0; bj < 2; ++bj) { float* pp = part + ((size_t)u.ks * MS + (row - MP)) * DM + col0 + bj * HALF; *(f32x4*)pp = acc[ai][bj][m][0]; *(f32x4*)(pp + 4) = acc[ai][bj][m][1]; }
;                 }
.LBB0_1224:
	s_lshl_b64 s[54:55], s[12:13], 24
	s_add_u32 s54, s67, s54
	s_waitcnt lgkmcnt(0)
	v_lshlrev_b64 v[52:53], 13, v[144:145]
	s_addc_u32 s55, s71, s55
	v_lshl_add_u64 v[52:53], s[54:55], 0, v[52:53]
	s_mov_b32 s54, 0xf8120000
	v_lshl_add_u64 v[52:53], v[142:143], 2, v[52:53]
	s_mov_b32 s55, -1
	v_lshl_add_u64 v[54:55], v[52:53], 0, s[54:55]
	v_add_co_u32_e32 v52, vcc, 0xf8120000, v52
	s_nop 1
	v_addc_co_u32_e32 v53, vcc, -1, v53, vcc
	global_store_dwordx4 v[52:53], v[48:51], off
	global_store_dwordx4 v[54:55], v[44:47], off offset:16
	global_store_dwordx4 v[54:55], v[40:43], off offset:512
	global_store_dwordx4 v[54:55], v[36:39], off offset:528
	s_cbranch_execnz .LBB0_1203
.LBB0_1225:
	v_add_u32_e32 v52, 0x90, v144
	s_waitcnt lgkmcnt(0)
	v_ashrrev_i32_e32 v53, 31, v52
	v_lshlrev_b64 v[54:55], 11, v[52:53]
	v_lshl_add_u64 v[62:63], v[54:55], 0, v[142:143]
	v_lshl_add_u64 v[64:65], v[62:63], 2, s[4:5]
	global_load_dwordx4 v[54:57], v[64:65], off
	global_load_dwordx4 v[58:61], v[64:65], off offset:16
	v_lshl_add_u64 v[62:63], v[62:63], 1, s[34:35]
	s_waitcnt vmcnt(0) lgkmcnt(0)
	v_pk_add_f32 v[56:57], v[50:51], v[56:57]
	v_pk_add_f32 v[54:55], v[48:49], v[54:55]
	v_pk_add_f32 v[60:61], v[46:47], v[60:61]
	v_pk_add_f32 v[58:59], v[44:45], v[58:59]
	v_cvt_pk_bf16_f32 v44, v54, v55
	v_cvt_pk_bf16_f32 v45, v56, v57
	v_cvt_pk_bf16_f32 v46, v58, v59
	v_cvt_pk_bf16_f32 v47, v60, v61
	global_store_dwordx4 v[62:63], v[44:47], off
	global_load_dwordx4 v[44:47], v[64:65], off offset:512
	s_nop 0
	global_load_dwordx4 v[48:51], v[64:65], off offset:528
	v_mul_f32_e32 v55, v55, v55
	v_mul_f32_e32 v57, v57, v57
	v_and_b32_e32 v65, 64, v223
	v_mul_f32_e32 v59, v59, v59
	v_fmac_f32_e32 v55, v54, v54
	v_fmac_f32_e32 v57, v56, v56
	v_xor_b32_e32 v64, 16, v223
	v_add_u32_e32 v65, 64, v65
	v_mul_f32_e32 v61, v61, v61
	v_fmac_f32_e32 v59, v58, v58
	v_add_f32_e32 v54, v55, v57
	v_cmp_lt_i32_e32 vcc, v64, v65
	v_fmac_f32_e32 v61, v60, v60
	v_add_f32_e32 v54, v54, v59
	v_cndmask_b32_e32 v64, v223, v64, vcc
	v_add_f32_e32 v54, v61, v54
	v_lshlrev_b32_e32 v64, 2, v64
	s_waitcnt vmcnt(0) lgkmcnt(0)
	v_pk_add_f32 v[42:43], v[42:43], v[46:47]
	v_pk_add_f32 v[40:41], v[40:41], v[44:45]
	v_pk_add_f32 v[46:47], v[36:37], v[48:49]
	v_mul_f32_e32 v36, v41, v41
	v_mul_f32_e32 v37, v43, v43
	v_pk_add_f32 v[44:45], v[38:39], v[50:51]
	v_mul_f32_e32 v38, v47, v47
	v_fmac_f32_e32 v36, v40, v40
	v_fmac_f32_e32 v37, v42, v42
	v_mul_f32_e32 v39, v45, v45
	v_fmac_f32_e32 v38, v46, v46
	v_add_f32_e32 v36, v36, v37
	v_fmac_f32_e32 v39, v44, v44
	v_add_f32_e32 v36, v36, v38
	v_add_f32_e32 v36, v39, v36
	v_add_f32_e32 v36, v54, v36
	ds_bpermute_b32 v37, v64, v36
	v_xor_b32_e32 v38, 32, v223
	v_cmp_lt_i32_e32 vcc, v38, v65
	s_waitcnt lgkmcnt(0)
	v_add_f32_e32 v36, v36, v37
	v_cndmask_b32_e32 v39, v223, v38, vcc
	v_lshlrev_b32_e32 v37, 2, v39
	ds_bpermute_b32 v37, v37, v36
	v_cvt_pk_bf16_f32 v38, v40, v41
	v_cvt_pk_bf16_f32 v39, v42, v43
	v_cvt_pk_bf16_f32 v40, v46, v47
	v_cvt_pk_bf16_f32 v41, v44, v45
	global_store_dwordx4 v[62:63], v[38:41], off offset:256
	s_and_saveexec_b64 s[54:55], s[40:41]
	s_cbranch_execz .LBB0_1227
	s_waitcnt lgkmcnt(0)
	v_add_f32_e32 v38, v36, v37
	s_lshl_b32 s56, s22, 2
	v_lshlrev_b64 v[36:37], 7, v[52:53]
	s_ashr_i32 s57, s56, 31
	v_lshl_add_u64 v[36:37], s[38:39], 0, v[36:37]
	v_lshl_add_u64 v[36:37], s[56:57], 2, v[36:37]
	s_lshl_b32 s56, s72, 2
	s_mov_b32 s57, s13
	v_lshl_add_u64 v[36:37], v[36:37], 0, s[56:57]
	global_store_dword v[36:37], v38, off

; DI u32x4 pack8(const f32x4 v0, const f32x4 v1) { u32x4 w; w.x = pk2(v0[0], v0[1]); w.y = pk2(v0[2], v0[3]); w.z = pk2(v1[0], v1[1]); w.w = pk2(v1[2], v1[3]); return w; }
; DI void unpack8(const u32x4 w, f32x4& v0, f32x4& v1) { v0 = (f32x4){bflo(w.x), bfhi(w.x), bflo(w.y), bfhi(w.y)}; v1 = (f32x4){bflo(w.z), bfhi(w.z), bflo(w.w), bfhi(w.w)}; }
;     DI void operator()(const f32x4 (&acc)[2][2][4][2], const Unit& u, int wr, int wc, int fr, int fq, const LAS float* rsl) const {
;     ...
;         for (int ai = 0; ai < 2; ++ai)
; #pragma unroll
;             for (int m = 0; m < 4; ++m) {
;                 const int row = row0 + ai * HALF + m * 16;
;                 if (u.ks < 0) {
;                     const size_t off = (size_t)row * DM + col0; float sq = 0.f;
; #pragma unroll
;                     for (int bj = 0; bj < 2; ++bj) {
;                         f32x4 x0, x1;
;                         if (XF32) { x0 = *(const f32x4*)(Xin + off + bj * HALF); x1 = *(const f32x4*)(Xin + off + bj * HALF + 4); }
;                         else unpack8(xin[ai][m][bj], x0, x1);
;                         x0 += acc[ai][bj][m][0]; x1 += acc[ai][bj][m][1];
;                         *(u32x4*)(act + off + bj * HALF) = pack8(x0, x1);
;                         sq += (x0[0] * x0[0] + x0[1] * x0[1]) + (x0[2] * x0[2] + x0[3] * x0[3]) + (x1[0] * x1[0] + x1[1] * x1[1]) + (x1[2] * x1[2] + x1[3] * x1[3]);
;                     }
;                     sq += __shfl_xor(sq, 16); sq += __shfl_xor(sq, 32);
;                     if (fq == 0) ssq[(size_t)row * 32 + u.pn * 4 + wc] = sq;
;                 } else {
; #pragma unroll
;                     for (int bj = 0; bj < 2; ++bj) { float* pp = part + ((size_t)u.ks * MS + (row - MP)) * DM + col0 + bj * HALF; *(f32x4*)pp = acc[ai][bj][m][0]; *(f32x4*)(pp + 4) = acc[ai][bj][m][1]; }
;                 }
.LBB0_1228:
	s_lshl_b64 s[54:55], s[12:13], 24
	s_add_u32 s54, s67, s54
	s_waitcnt lgkmcnt(0)
	v_lshlrev_b64 v[36:37], 13, v[144:145]
	s_addc_u32 s55, s71, s55
	v_lshl_add_u64 v[36:37], s[54:55], 0, v[36:37]
	s_mov_b32 s54, 0xf8140000
	v_lshl_add_u64 v[36:37], v[142:143], 2, v[36:37]
	s_mov_b32 s55, -1
	v_lshl_add_u64 v[38:39], v[36:37], 0, s[54:55]
	v_add_co_u32_e32 v36, vcc, 0xf8140000, v36
	s_nop 1
	v_addc_co_u32_e32 v37, vcc, -1, v37, vcc
	global_store_dwordx4 v[36:37], v[32:35], off
	global_store_dwordx4 v[38:39], v[28:31], off offset:16
	global_store_dwordx4 v[38:39], v[24:27], off offset:512
	global_store_dwordx4 v[38:39], v[20:23], off offset:528
	s_cbranch_execnz .LBB0_1205
.LBB0_1229:
	v_add_u32_e32 v36, 0xa0, v144
	s_waitcnt lgkmcnt(0)
	v_ashrrev_i32_e32 v37, 31, v36
	v_lshlrev_b64 v[38:39], 11, v[36:37]
	v_lshl_add_u64 v[46:47], v[38:39], 0, v[142:143]
	v_lshl_add_u64 v[48:49], v[46:47], 2, s[4:5]
	global_load_dwordx4 v[38:41], v[48:49], off
	global_load_dwordx4 v[42:45], v[48:49], off offset:16
	v_lshl_add_u64 v[46:47], v[46:47], 1, s[34:35]
	s_waitcnt vmcnt(0) lgkmcnt(0)
	v_pk_add_f32 v[40:41], v[34:35], v[40:41]
	v_pk_add_f32 v[38:39], v[32:33], v[38:39]
	v_pk_add_f32 v[44:45], v[30:31], v[44:45]
	v_pk_add_f32 v[42:43], v[28:29], v[42:43]
	v_cvt_pk_bf16_f32 v28, v38, v39
	v_cvt_pk_bf16_f32 v29, v40, v41
	v_cvt_pk_bf16_f32 v30, v42, v43
	v_cvt_pk_bf16_f32 v31, v44, v45
	global_store_dwordx4 v[46:47], v[28:31], off
	global_load_dwordx4 v[28:31], v[48:49], off offset:512
	s_nop 0
	global_load_dwordx4 v[32:35], v[48:49], off offset:528
	v_mul_f32_e32 v39, v39, v39
	v_mul_f32_e32 v41, v41, v41
	v_and_b32_e32 v49, 64, v223
	v_mul_f32_e32 v43, v43, v43
	v_fmac_f32_e32 v39, v38, v38
	v_fmac_f32_e32 v41, v40, v40
	v_xor_b32_e32 v48, 16, v223
	v_add_u32_e32 v49, 64, v49
	v_mul_f32_e32 v45, v45, v45
	v_fmac_f32_e32 v43, v42, v42
	v_add_f32_e32 v38, v39, v41
	v_cmp_lt_i32_e32 vcc, v48, v49
	v_fmac_f32_e32 v45, v44, v44
	v_add_f32_e32 v38, v38, v43
	v_cndmask_b32_e32 v48, v223, v48, vcc
	v_add_f32_e32 v38, v45, v38
	v_lshlrev_b32_e32 v48, 2, v48
	s_waitcnt vmcnt(0) lgkmcnt(0)
	v_pk_add_f32 v[26:27], v[26:27], v[30:31]
	v_pk_add_f32 v[24:25], v[24:25], v[28:29]
	v_pk_add_f32 v[30:31], v[20:21], v[32:33]
	v_mul_f32_e32 v20, v25, v25
	v_mul_f32_e32 v21, v27, v27
	v_pk_add_f32 v[28:29], v[22:23], v[34:35]
	v_mul_f32_e32 v22, v31, v31
	v_fmac_f32_e32 v20, v24, v24
	v_fmac_f32_e32 v21, v26, v26
	v_mul_f32_e32 v23, v29, v29
	v_fmac_f32_e32 v22, v30, v30
	v_add_f32_e32 v20, v20, v21
	v_fmac_f32_e32 v23, v28, v28
	v_add_f32_e32 v20, v20, v22
	v_add_f32_e32 v20, v23, v20
	v_add_f32_e32 v20, v38, v20
	ds_bpermute_b32 v21, v48, v20
	v_xor_b32_e32 v22, 32, v223
	v_cmp_lt_i32_e32 vcc, v22, v49
	s_waitcnt lgkmcnt(0)
	v_add_f32_e32 v20, v20, v21
	v_cndmask_b32_e32 v23, v223, v22, vcc
	v_lshlrev_b32_e32 v21, 2, v23
	ds_bpermute_b32 v21, v21, v20
	v_cvt_pk_bf16_f32 v22, v24, v25
	v_cvt_pk_bf16_f32 v23, v26, v27
	v_cvt_pk_bf16_f32 v24, v30, v31
	v_cvt_pk_bf16_f32 v25, v28, v29
	global_store_dwordx4 v[46:47], v[22:25], off offset:256
	s_and_saveexec_b64 s[54:55], s[40:41]
	s_cbranch_execz .LBB0_1231
	s_waitcnt lgkmcnt(0)
	v_add_f32_e32 v22, v20, v21
	s_lshl_b32 s56, s22, 2
	v_lshlrev_b64 v[20:21], 7, v[36:37]
	s_ashr_i32 s57, s56, 31
	v_lshl_add_u64 v[20:21], s[38:39], 0, v[20:21]
	v_lshl_add_u64 v[20:21], s[56:57], 2, v[20:21]
	s_lshl_b32 s56, s72, 2
	s_mov_b32 s57, s13
	v_lshl_add_u64 v[20:21], v[20:21], 0, s[56:57]
	global_store_dword v[20:21], v22, off

; DI u32x4 pack8(const f32x4 v0, const f32x4 v1) { u32x4 w; w.x = pk2(v0[0], v0[1]); w.y = pk2(v0[2], v0[3]); w.z = pk2(v1[0], v1[1]); w.w = pk2(v1[2], v1[3]); return w; }
; DI void unpack8(const u32x4 w, f32x4& v0, f32x4& v1) { v0 = (f32x4){bflo(w.x), bfhi(w.x), bflo(w.y), bfhi(w.y)}; v1 = (f32x4){bflo(w.z), bfhi(w.z), bflo(w.w), bfhi(w.w)}; }
;     DI void operator()(const f32x4 (&acc)[2][2][4][2], const Unit& u, int wr, int wc, int fr, int fq, const LAS float* rsl) const {
;     ...
;         for (int ai = 0; ai < 2; ++ai)
; #pragma unroll
;             for (int m = 0; m < 4; ++m) {
;                 const int row = row0 + ai * HALF + m * 16;
;                 if (u.ks < 0) {
;                     const size_t off = (size_t)row * DM + col0; float sq = 0.f;
; #pragma unroll
;                     for (int bj = 0; bj < 2; ++bj) {
;                         f32x4 x0, x1;
;                         if (XF32) { x0 = *(const f32x4*)(Xin + off + bj * HALF); x1 = *(const f32x4*)(Xin + off + bj * HALF + 4); }
;                         else unpack8(xin[ai][m][bj], x0, x1);
;                         x0 += acc[ai][bj][m][0]; x1 += acc[ai][bj][m][1];
;                         *(u32x4*)(act + off + bj * HALF) = pack8(x0, x1);
;                         sq += (x0[0] * x0[0] + x0[1] * x0[1]) + (x0[2] * x0[2] + x0[3] * x0[3]) + (x1[0] * x1[0] + x1[1] * x1[1]) + (x1[2] * x1[2] + x1[3] * x1[3]);
;                     }
;                     sq += __shfl_xor(sq, 16); sq += __shfl_xor(sq, 32);
;                     if (fq == 0) ssq[(size_t)row * 32 + u.pn * 4 + wc] = sq;
;                 } else {
; #pragma unroll
;                     for (int bj = 0; bj < 2; ++bj) { float* pp = part + ((size_t)u.ks * MS + (row - MP)) * DM + col0 + bj * HALF; *(f32x4*)pp = acc[ai][bj][m][0]; *(f32x4*)(pp + 4) = acc[ai][bj][m][1]; }
;                 }
.LBB0_1232:
	s_lshl_b64 s[42:43], s[12:13], 24
	s_add_u32 s42, s67, s42
	s_waitcnt lgkmcnt(0)
	v_lshlrev_b64 v[20:21], 13, v[144:145]
	s_addc_u32 s43, s71, s43
	v_lshl_add_u64 v[20:21], s[42:43], 0, v[20:21]
	s_mov_b32 s42, 0xf8160000
	v_lshl_add_u64 v[20:21], v[142:143], 2, v[20:21]
	s_mov_b32 s43, -1
	v_lshl_add_u64 v[22:23], v[20:21], 0, s[42:43]
	v_add_co_u32_e32 v20, vcc, 0xf8160000, v20
	s_nop 1
	v_addc_co_u32_e32 v21, vcc, -1, v21, vcc
	global_store_dwordx4 v[20:21], v[16:19], off
	global_store_dwordx4 v[22:23], v[12:15], off offset:16
	global_store_dwordx4 v[22:23], v[8:11], off offset:512
	global_store_dwordx4 v[22:23], v[4:7], off offset:528
	s_cbranch_execnz .LBB0_1207
.LBB0_1233:
	v_add_u32_e32 v20, 0xb0, v144
	s_waitcnt lgkmcnt(0)
	v_ashrrev_i32_e32 v21, 31, v20
	v_lshlrev_b64 v[22:23], 11, v[20:21]
	v_lshl_add_u64 v[30:31], v[22:23], 0, v[142:143]
	v_lshl_add_u64 v[32:33], v[30:31], 2, s[4:5]
	global_load_dwordx4 v[22:25], v[32:33], off
	global_load_dwordx4 v[26:29], v[32:33], off offset:16
	v_lshl_add_u64 v[30:31], v[30:31], 1, s[34:35]
	s_waitcnt vmcnt(0) lgkmcnt(0)
	v_pk_add_f32 v[24:25], v[18:19], v[24:25]
	v_pk_add_f32 v[22:23], v[16:17], v[22:23]
	v_pk_add_f32 v[28:29], v[14:15], v[28:29]
	v_pk_add_f32 v[26:27], v[12:13], v[26:27]
	v_cvt_pk_bf16_f32 v12, v22, v23
	v_cvt_pk_bf16_f32 v13, v24, v25
	v_cvt_pk_bf16_f32 v14, v26, v27
	v_cvt_pk_bf16_f32 v15, v28, v29
	global_store_dwordx4 v[30:31], v[12:15], off
	global_load_dwordx4 v[12:15], v[32:33], off offset:512
	s_nop 0
	global_load_dwordx4 v[16:19], v[32:33], off offset:528
	v_mul_f32_e32 v23, v23, v23
	v_mul_f32_e32 v25, v25, v25
	v_and_b32_e32 v33, 64, v223
	v_mul_f32_e32 v27, v27, v27
	v_fmac_f32_e32 v23, v22, v22
	v_fmac_f32_e32 v25, v24, v24
	v_xor_b32_e32 v32, 16, v223
	v_add_u32_e32 v33, 64, v33
	v_mul_f32_e32 v29, v29, v29
	v_fmac_f32_e32 v27, v26, v26
	v_add_f32_e32 v22, v23, v25
	v_cmp_lt_i32_e32 vcc, v32, v33
	v_fmac_f32_e32 v29, v28, v28
	v_add_f32_e32 v22, v22, v27
	v_cndmask_b32_e32 v32, v223, v32, vcc
	v_add_f32_e32 v22, v29, v22
	v_lshlrev_b32_e32 v32, 2, v32
	s_waitcnt vmcnt(0) lgkmcnt(0)
	v_pk_add_f32 v[10:11], v[10:11], v[14:15]
	v_pk_add_f32 v[8:9], v[8:9], v[12:13]
	v_pk_add_f32 v[14:15], v[4:5], v[16:17]
	v_mul_f32_e32 v4, v9, v9
	v_mul_f32_e32 v5, v11, v11
	v_pk_add_f32 v[12:13], v[6:7], v[18:19]
	v_mul_f32_e32 v6, v15, v15
	v_fmac_f32_e32 v4, v8, v8
	v_fmac_f32_e32 v5, v10, v10
	v_mul_f32_e32 v7, v13, v13
	v_fmac_f32_e32 v6, v14, v14
	v_add_f32_e32 v4, v4, v5
	v_fmac_f32_e32 v7, v12, v12
	v_add_f32_e32 v4, v4, v6
	v_add_f32_e32 v4, v7, v4
	v_add_f32_e32 v4, v22, v4
	ds_bpermute_b32 v5, v32, v4
	v_xor_b32_e32 v6, 32, v223
	v_cmp_lt_i32_e32 vcc, v6, v33
	s_waitcnt lgkmcnt(0)
	v_add_f32_e32 v4, v4, v5
	v_cndmask_b32_e32 v7, v223, v6, vcc
	v_lshlrev_b32_e32 v5, 2, v7
	ds_bpermute_b32 v5, v5, v4
	v_cvt_pk_bf16_f32 v6, v8, v9
	v_cvt_pk_bf16_f32 v7, v10, v11
	v_cvt_pk_bf16_f32 v8, v14, v15
	v_cvt_pk_bf16_f32 v9, v12, v13
	global_store_dwordx4 v[30:31], v[6:9], off offset:256
	s_and_saveexec_b64 s[42:43], s[40:41]
	s_cbranch_execz .LBB0_1235
	s_waitcnt lgkmcnt(0)
	v_add_f32_e32 v6, v4, v5
	s_lshl_b32 s54, s22, 2
	v_lshlrev_b64 v[4:5], 7, v[20:21]
	s_ashr_i32 s55, s54, 31
	v_lshl_add_u64 v[4:5], s[38:39], 0, v[4:5]
	v_lshl_add_u64 v[4:5], s[54:55], 2, v[4:5]
	s_lshl_b32 s12, s72, 2
	v_lshl_add_u64 v[4:5], v[4:5], 0, s[12:13]
	global_store_dword v[4:5], v6, off

; DI unsigned xb_ld(unsigned* p)              { return __hip_atomic_load(p, __ATOMIC_RELAXED, __HIP_MEMORY_SCOPE_AGENT); }
; DI void xcd_barrier_complete(unsigned* bar, unsigned x, unsigned& nloc, unsigned& nx) {
;     const unsigned G = gridDim.x * gridDim.y * gridDim.z;
;     unsigned sum, cnt, mine, sp = 0u;
;     for (;;) {
;         sum = 0u; cnt = 0u; mine = 0u;
; #pragma unroll
;         for (unsigned j = 0; j < 16; ++j) { const unsigned c = xb_ld(&bar[XB_XCNT(j)]); sum += c; cnt += (c > 0u) ? 1u : 0u; mine = (j == x) ? c : mine; }
;         if (sum == G) break;
;         __builtin_amdgcn_s_sleep(1);
;         if ((++sp & 255u) == 0u) { if (xb_ld(&bar[XB_TMO])) break; if (sp > XB_SPIN_CAP) { atomicAdd(&bar[XB_TMO], 1u); break; } }
;     }
;     nloc = mine > 0u ? mine : 1u; nx = cnt > 0u ? cnt : 1u;
; }
.LBB0_1245:
	v_mov_b64_e32 v[14:15], s[8:9]
	global_load_dword v2, v[14:15], off offset:1024 sc1
	global_load_dword v1, v[14:15], off offset:1280 sc1
	global_load_dword v4, v[14:15], off offset:1536 sc1
	s_or_b64 s[48:49], s[48:49], exec
	s_or_b64 s[46:47], s[46:47], exec
	s_waitcnt vmcnt(0) lgkmcnt(0)
	v_add_u32_e32 v5, v1, v2
	v_add_u32_e32 v6, v5, v4
	global_load_dword v5, v[14:15], off offset:1792 sc1
	s_waitcnt vmcnt(0) lgkmcnt(0)
	v_add_u32_e32 v7, v6, v5
	global_load_dword v6, v[14:15], off offset:2048 sc1
	s_waitcnt vmcnt(0) lgkmcnt(0)
	v_add_u32_e32 v8, v7, v6
	global_load_dword v7, v[14:15], off offset:2304 sc1
	s_waitcnt vmcnt(0) lgkmcnt(0)
	v_add_u32_e32 v9, v8, v7
	global_load_dword v8, v[14:15], off offset:2560 sc1
	s_waitcnt vmcnt(0) lgkmcnt(0)
	v_add_u32_e32 v10, v9, v8
	global_load_dword v9, v[14:15], off offset:2816 sc1
	s_waitcnt vmcnt(0) lgkmcnt(0)
	v_add_u32_e32 v11, v10, v9
	global_load_dword v10, v[14:15], off offset:3072 sc1
	s_waitcnt vmcnt(0) lgkmcnt(0)
	v_add_u32_e32 v12, v11, v10
	global_load_dword v11, v[14:15], off offset:3328 sc1
	s_waitcnt vmcnt(0) lgkmcnt(0)
	v_add_u32_e32 v13, v12, v11
	global_load_dword v12, v[14:15], off offset:3584 sc1
	s_waitcnt vmcnt(0) lgkmcnt(0)
	v_add_u32_e32 v16, v13, v12
	global_load_dword v13, v[14:15], off offset:3840 sc1
	v_mov_b64_e32 v[14:15], s[18:19]
	global_load_dword v14, v[14:15], off sc1
	s_waitcnt vmcnt(0) lgkmcnt(0)
	v_add_u32_e32 v16, v16, v13
	v_add_u32_e32 v18, v16, v14
	v_mov_b64_e32 v[16:17], s[34:35]
	global_load_dword v15, v[16:17], off sc1
	v_mov_b64_e32 v[16:17], s[38:39]
	global_load_dword v16, v[16:17], off sc1
	s_waitcnt vmcnt(0) lgkmcnt(0)
	v_add_u32_e32 v18, v18, v15
	v_add_u32_e32 v20, v18, v16
	v_mov_b64_e32 v[18:19], s[40:41]
	global_load_dword v17, v[18:19], off sc1
	s_waitcnt vmcnt(0) lgkmcnt(0)
	v_add_u32_e32 v18, v20, v17
	v_cmp_ne_u32_e32 vcc, s10, v18
	s_and_saveexec_b64 s[50:51], vcc
	s_cbranch_execz .LBB0_1244
	s_and_b32 s22, s12, 0xff
	s_mov_b64 s[52:53], -1
	s_cmp_eq_u32 s22, 0
	s_mov_b64 s[56:57], -1
	s_mov_b64 s[54:55], -1
	s_sleep 1
	s_cbranch_scc1 .LBB0_1248
	s_and_saveexec_b64 s[58:59], s[56:57]
	s_cbranch_execz .LBB0_1243
	s_branch .LBB0_1251

; DI unsigned xb_ld(unsigned* p)              { return __hip_atomic_load(p, __ATOMIC_RELAXED, __HIP_MEMORY_SCOPE_AGENT); }
; DI unsigned xb_add(unsigned* p, unsigned v) { return __hip_atomic_fetch_add(p, v, __ATOMIC_RELAXED, __HIP_MEMORY_SCOPE_AGENT); }
; #define XB_SPIN(cond, bar) do { unsigned _sp = 0; while (cond) { __builtin_amdgcn_s_sleep(1); \
;     if ((++_sp & 255u) == 0u) { if (xb_ld(&(bar)[XB_TMO])) break; if (_sp > XB_SPIN_CAP) { atomicAdd(&(bar)[XB_TMO], 1u); break; } } } } while (0)
; DI void xcd_barrier(const XcdBarrier& b) {
;     ...
;         const unsigned old = xb_add(&bar[XB_XSUB(b.x)], 1u);
;         const unsigned gen = old / nloc;
;         if (old + 1u == (gen + 1u) * nloc) {
;             __builtin_amdgcn_fence(__ATOMIC_RELEASE, "agent");
;             asm volatile("s_waitcnt vmcnt(0)" ::: "memory");
;             const unsigned og = xb_add(&bar[XB_TOP], 1u);
;             const unsigned tg = og / nx;
;             if (og + 1u == (tg + 1u) * nx) xb_add(&bar[XB_TOPGEN], 1u);
;             else XB_SPIN(xb_ld(&bar[XB_TOPGEN]) == tg, bar);
;             __builtin_amdgcn_fence(__ATOMIC_ACQUIRE, "agent");
;             xb_add(&bar[XB_XGEN(b.x)], 1u);
;             asm volatile("s_waitcnt vmcnt(0)" ::: "memory");
;         } else {
;             XB_SPIN(xb_ld(&bar[XB_XGEN(b.x)]) == gen, bar);
.LBB0_1255:
	v_readlane_b32 s10, v253, 48
	s_lshl_b32 s10, s10, 2
	s_add_u32 s12, s8, s10
	s_addc_u32 s10, s9, 0
	v_mov_b32_e32 v1, s12
	v_add_co_u32_e32 v6, vcc, 0x1000, v1
	v_mov_b32_e32 v1, s10
	s_nop 0
	v_addc_co_u32_e32 v7, vcc, 0, v1, vcc
	flat_atomic_add v5, v[6:7], v218 offset:1024 sc0
	v_cvt_f32_u32_e32 v1, v4
	v_sub_u32_e32 v6, 0, v4
	v_rcp_iflag_f32_e32 v1, v1
	s_nop 0
	v_mul_f32_e32 v1, 0x4f7ffffe, v1
	v_cvt_u32_f32_e32 v1, v1
	v_mul_lo_u32 v6, v6, v1
	v_mul_hi_u32 v6, v1, v6
	v_add_u32_e32 v1, v1, v6
	s_waitcnt vmcnt(0) lgkmcnt(0)
	v_mul_hi_u32 v1, v5, v1
	v_mul_lo_u32 v6, v1, v4
	v_sub_u32_e32 v6, v5, v6
	v_cmp_ge_u32_e32 vcc, v6, v4
	v_add_u32_e32 v7, 1, v1
	s_nop 0
	v_cndmask_b32_e32 v1, v1, v7, vcc
	v_sub_u32_e32 v7, v6, v4
	v_cndmask_b32_e32 v6, v6, v7, vcc
	v_cmp_ge_u32_e32 vcc, v6, v4
	v_add_u32_e32 v6, 1, v1
	s_nop 0
	v_cndmask_b32_e32 v1, v1, v6, vcc
	v_add_u32_e32 v6, 1, v5
	v_mad_u64_u32 v[4:5], s[18:19], v4, v1, v[4:5]
	v_cmp_ne_u32_e32 vcc, v6, v4
	s_and_saveexec_b64 s[18:19], vcc
	s_xor_b64 s[18:19], exec, s[18:19]
	s_cbranch_execz .LBB0_1268
	v_mov_b32_e32 v2, s12
	v_add_co_u32_e32 v4, vcc, 0x2000, v2
	v_mov_b32_e32 v2, s10
	s_nop 0
	v_addc_co_u32_e32 v5, vcc, 0, v2, vcc
	global_load_dword v2, v[4:5], off offset:1024 sc1
	s_add_u32 s38, s12, 0x2400
	s_addc_u32 s39, s10, 0
	s_waitcnt vmcnt(0) lgkmcnt(0)
	v_cmp_eq_u32_e32 vcc, v2, v1
	s_and_saveexec_b64 s[34:35], vcc
	s_cbranch_execz .LBB0_1267
	s_mov_b32 s22, 1
	s_mov_b64 s[40:41], 0
	s_branch .LBB0_1259

; DI float bflo(unsigned w) { return __uint_as_float(w << 16); }
; DI float bfhi(unsigned w) { return __uint_as_float(w & 0xffff0000u); }
; DI unsigned pk2(float a, float b) { f32x2 v = {a, b}; bf16v2 r = __builtin_convertvector(v, bf16v2); return __builtin_bit_cast(unsigned, r); }
; DI void phase_postRes(const Ctx& c, const float* xinS  ) {
;     ...
;     for (int row = MP + gw; row < M; row += NGW) {
;         const f32x4* pr = (const f32x4*)(part + (size_t)(row - MP) * DM) + c.lane; const size_t st = (size_t)MS * DM / 4;
;         u32x2* ao = (u32x2*)(act + (size_t)row * DM) + c.lane;
;         float s = 0.f;
; #pragma unroll
;         for (int j = 0; j < 8; ++j) {
;             f32x4 xi;
;             if (xinS) xi = ((const f32x4*)(xinS + (size_t)(row - MP) * DM) + c.lane)[64 * j];
;             else { const u32x2 w = ao[64 * j]; xi = (f32x4){bflo(w.x), bfhi(w.x), bflo(w.y), bfhi(w.y)}; }
;             const f32x4 v = xi + ((pr[64 * j] + pr[st + 64 * j]) + (pr[2 * st + 64 * j] + pr[3 * st + 64 * j]));
;             u32x2 w; w.x = pk2(v[0], v[1]); w.y = pk2(v[2], v[3]); ao[64 * j] = w;
;             s += (v[0] * v[0] + v[1] * v[1]) + (v[2] * v[2] + v[3] * v[3]);
;         }
;         s = wave_sum(s);
;         if (c.lane == 0) rs[row] = 1.0f / sqrtf(s * (1.0f / DM) + EPS);
;     }
.LBB0_1293:
	s_ashr_i32 s39, s38, 31
	s_lshl_b64 s[22:23], s[38:39], 13
	s_add_u32 s50, s8, s22
	v_cndmask_b32_e64 v2, 0, 1, s[34:35]
	s_addc_u32 s51, s9, s23
	v_cmp_ne_u32_e64 s[42:43], 1, v2
	s_andn2_b64 vcc, exec, s[34:35]
	v_lshlrev_b32_e32 v2, 4, v8
	s_cbranch_vccnz .LBB0_1319
	s_waitcnt lgkmcnt(0)
	v_lshl_add_u64 v[4:5], s[50:51], 0, v[2:3]
	global_load_dwordx4 v[4:7], v[4:5], off
	s_cbranch_execnz .LBB0_1296
.LBB0_1295:
	s_waitcnt vmcnt(0) lgkmcnt(0)
	global_load_dwordx2 v[6:7], v[12:13], off
	s_waitcnt vmcnt(0) lgkmcnt(0)
	v_lshlrev_b32_e32 v4, 16, v6
	v_and_b32_e32 v5, 0xffff0000, v6
	v_lshlrev_b32_e32 v6, 16, v7
	v_and_b32_e32 v7, 0xffff0000, v7
.LBB0_1296:
	s_lshl_b64 s[22:23], s[38:39], 11
	v_lshl_add_u64 v[14:15], s[22:23], 2, v[10:11]
	v_add_co_u32_e32 v20, vcc, 0x1000000, v14
	global_load_dwordx4 v[16:19], v[14:15], off
	s_nop 0
	v_addc_co_u32_e32 v21, vcc, 0, v15, vcc
	global_load_dwordx4 v[20:23], v[20:21], off
	s_waitcnt vmcnt(0) lgkmcnt(0)
	v_pk_add_f32 v[26:27], v[16:17], v[20:21]
	v_add_co_u32_e32 v16, vcc, 0x2000000, v14
	v_pk_add_f32 v[24:25], v[18:19], v[22:23]
	s_nop 0
	v_addc_co_u32_e32 v17, vcc, 0, v15, vcc
	v_add_co_u32_e32 v20, vcc, 0x3000000, v14
	global_load_dwordx4 v[16:19], v[16:17], off
	s_nop 0
	v_addc_co_u32_e32 v21, vcc, 0, v15, vcc
	global_load_dwordx4 v[20:23], v[20:21], off
	s_and_b64 vcc, exec, s[42:43]
	s_waitcnt vmcnt(0) lgkmcnt(0)
	v_pk_add_f32 v[18:19], v[18:19], v[22:23]
	v_pk_add_f32 v[16:17], v[16:17], v[20:21]
	v_pk_add_f32 v[18:19], v[24:25], v[18:19]
	v_pk_add_f32 v[20:21], v[26:27], v[16:17]
	v_pk_add_f32 v[16:17], v[6:7], v[18:19]
	v_pk_add_f32 v[18:19], v[4:5], v[20:21]
	v_cvt_pk_bf16_f32 v5, v16, v17
	v_cvt_pk_bf16_f32 v4, v18, v19
	global_store_dwordx2 v[12:13], v[4:5], off
	s_cbranch_vccnz .LBB0_1320
	v_lshl_add_u64 v[4:5], s[50:51], 0, v[2:3]
	global_load_dwordx4 v[4:7], v[4:5], off offset:1024
	s_cbranch_execnz .LBB0_1299
.LBB0_1298:
	s_waitcnt vmcnt(0) lgkmcnt(0)
	global_load_dwordx2 v[6:7], v[12:13], off offset:512
	s_waitcnt vmcnt(0) lgkmcnt(0)
	v_lshlrev_b32_e32 v4, 16, v6
	v_and_b32_e32 v5, 0xffff0000, v6
	v_lshlrev_b32_e32 v6, 16, v7
	v_and_b32_e32 v7, 0xffff0000, v7
.LBB0_1299:
	v_add_co_u32_e32 v24, vcc, 0x1000000, v14
	global_load_dwordx4 v[20:23], v[14:15], off offset:1024
	s_nop 0
	v_addc_co_u32_e32 v25, vcc, 0, v15, vcc
	global_load_dwordx4 v[24:27], v[24:25], off offset:1024
	s_waitcnt vmcnt(0) lgkmcnt(0)
	v_pk_add_f32 v[30:31], v[20:21], v[24:25]
	v_add_co_u32_e32 v20, vcc, 0x2000000, v14
	v_pk_add_f32 v[28:29], v[22:23], v[26:27]
	s_nop 0
	v_addc_co_u32_e32 v21, vcc, 0, v15, vcc
	v_add_co_u32_e32 v24, vcc, 0x3000000, v14
	global_load_dwordx4 v[20:23], v[20:21], off offset:1024
	s_nop 0
	v_addc_co_u32_e32 v25, vcc, 0, v15, vcc
	global_load_dwordx4 v[24:27], v[24:25], off offset:1024
	s_and_b64 vcc, exec, s[42:43]
	s_waitcnt vmcnt(0) lgkmcnt(0)
	v_pk_add_f32 v[22:23], v[22:23], v[26:27]
	v_pk_add_f32 v[20:21], v[20:21], v[24:25]
	v_pk_add_f32 v[22:23], v[28:29], v[22:23]
	v_pk_add_f32 v[24:25], v[30:31], v[20:21]
	v_pk_add_f32 v[20:21], v[6:7], v[22:23]
	v_pk_add_f32 v[22:23], v[4:5], v[24:25]
	v_cvt_pk_bf16_f32 v5, v20, v21
	v_cvt_pk_bf16_f32 v4, v22, v23
	global_store_dwordx2 v[12:13], v[4:5], off offset:512
	s_cbranch_vccnz .LBB0_1321
	v_lshl_add_u64 v[4:5], s[50:51], 0, v[2:3]
	global_load_dwordx4 v[4:7], v[4:5], off offset:2048
	s_cbranch_execnz .LBB0_1302
.LBB0_1301:
	s_waitcnt vmcnt(0) lgkmcnt(0)
	global_load_dwordx2 v[6:7], v[12:13], off offset:1024
	s_waitcnt vmcnt(0) lgkmcnt(0)
	v_lshlrev_b32_e32 v4, 16, v6
	v_and_b32_e32 v5, 0xffff0000, v6
	v_lshlrev_b32_e32 v6, 16, v7
	v_and_b32_e32 v7, 0xffff0000, v7
.LBB0_1302:
	v_add_co_u32_e32 v28, vcc, 0x1000000, v14
	global_load_dwordx4 v[24:27], v[14:15], off offset:2048
	s_nop 0
	v_addc_co_u32_e32 v29, vcc, 0, v15, vcc
	global_load_dwordx4 v[28:31], v[28:29], off offset:2048
	s_waitcnt vmcnt(0) lgkmcnt(0)
	v_pk_add_f32 v[34:35], v[24:25], v[28:29]
	v_add_co_u32_e32 v24, vcc, 0x2000000, v14
	v_pk_add_f32 v[32:33], v[26:27], v[30:31]
	s_nop 0
	v_addc_co_u32_e32 v25, vcc, 0, v15, vcc
	v_add_co_u32_e32 v28, vcc, 0x3000000, v14
	global_load_dwordx4 v[24:27], v[24:25], off offset:2048
	s_nop 0
	v_addc_co_u32_e32 v29, vcc, 0, v15, vcc
	global_load_dwordx4 v[28:31], v[28:29], off offset:2048
	s_and_b64 vcc, exec, s[42:43]
	s_waitcnt vmcnt(0) lgkmcnt(0)
	v_pk_add_f32 v[26:27], v[26:27], v[30:31]
	v_pk_add_f32 v[24:25], v[24:25], v[28:29]
	v_pk_add_f32 v[26:27], v[32:33], v[26:27]
	v_pk_add_f32 v[28:29], v[34:35], v[24:25]
	v_pk_add_f32 v[24:25], v[6:7], v[26:27]
	v_pk_add_f32 v[26:27], v[4:5], v[28:29]
	v_cvt_pk_bf16_f32 v5, v24, v25
	v_cvt_pk_bf16_f32 v4, v26, v27
	global_store_dwordx2 v[12:13], v[4:5], off offset:1024
	s_cbranch_vccnz .LBB0_1322
	v_lshl_add_u64 v[4:5], s[50:51], 0, v[2:3]
	global_load_dwordx4 v[4:7], v[4:5], off offset:3072
	s_cbranch_execnz .LBB0_1305
.LBB0_1304:
	s_waitcnt vmcnt(0) lgkmcnt(0)
	global_load_dwordx2 v[6:7], v[12:13], off offset:1536
	s_waitcnt vmcnt(0) lgkmcnt(0)
	v_lshlrev_b32_e32 v4, 16, v6
	v_and_b32_e32 v5, 0xffff0000, v6
	v_lshlrev_b32_e32 v6, 16, v7
	v_and_b32_e32 v7, 0xffff0000, v7
; DI float bflo(unsigned w) { return __uint_as_float(w << 16); }
; DI float bfhi(unsigned w) { return __uint_as_float(w & 0xffff0000u); }
; DI unsigned pk2(float a, float b) { f32x2 v = {a, b}; bf16v2 r = __builtin_convertvector(v, bf16v2); return __builtin_bit_cast(unsigned, r); }
; DI void phase_postRes(const Ctx& c, const float* xinS  ) {
;     ...
;     for (int row = MP + gw; row < M; row += NGW) {
;         const f32x4* pr = (const f32x4*)(part + (size_t)(row - MP) * DM) + c.lane; const size_t st = (size_t)MS * DM / 4;
;         u32x2* ao = (u32x2*)(act + (size_t)row * DM) + c.lane;
;         float s = 0.f;
; #pragma unroll
;         for (int j = 0; j < 8; ++j) {
;             f32x4 xi;
;             if (xinS) xi = ((const f32x4*)(xinS + (size_t)(row - MP) * DM) + c.lane)[64 * j];
;             else { const u32x2 w = ao[64 * j]; xi = (f32x4){bflo(w.x), bfhi(w.x), bflo(w.y), bfhi(w.y)}; }
;             const f32x4 v = xi + ((pr[64 * j] + pr[st + 64 * j]) + (pr[2 * st + 64 * j] + pr[3 * st + 64 * j]));
;             u32x2 w; w.x = pk2(v[0], v[1]); w.y = pk2(v[2], v[3]); ao[64 * j] = w;
;             s += (v[0] * v[0] + v[1] * v[1]) + (v[2] * v[2] + v[3] * v[3]);
;         }
;         s = wave_sum(s);
;         if (c.lane == 0) rs[row] = 1.0f / sqrtf(s * (1.0f / DM) + EPS);
;     }
.LBB0_1305:
	v_add_co_u32_e32 v32, vcc, 0x1000000, v14
	global_load_dwordx4 v[28:31], v[14:15], off offset:3072
	s_nop 0
	v_addc_co_u32_e32 v33, vcc, 0, v15, vcc
	global_load_dwordx4 v[32:35], v[32:33], off offset:3072
	s_waitcnt vmcnt(0) lgkmcnt(0)
	v_pk_add_f32 v[38:39], v[28:29], v[32:33]
	v_add_co_u32_e32 v28, vcc, 0x2000000, v14
	v_pk_add_f32 v[36:37], v[30:31], v[34:35]
	s_nop 0
	v_addc_co_u32_e32 v29, vcc, 0, v15, vcc
	v_add_co_u32_e32 v32, vcc, 0x3000000, v14
	global_load_dwordx4 v[28:31], v[28:29], off offset:3072
	s_nop 0
	v_addc_co_u32_e32 v33, vcc, 0, v15, vcc
	global_load_dwordx4 v[32:35], v[32:33], off offset:3072
	s_and_b64 vcc, exec, s[42:43]
	s_waitcnt vmcnt(0) lgkmcnt(0)
	v_pk_add_f32 v[30:31], v[30:31], v[34:35]
	v_pk_add_f32 v[28:29], v[28:29], v[32:33]
	v_pk_add_f32 v[30:31], v[36:37], v[30:31]
	v_pk_add_f32 v[32:33], v[38:39], v[28:29]
	v_pk_add_f32 v[28:29], v[6:7], v[30:31]
	v_pk_add_f32 v[30:31], v[4:5], v[32:33]
	v_cvt_pk_bf16_f32 v5, v28, v29
	v_cvt_pk_bf16_f32 v4, v30, v31
	global_store_dwordx2 v[12:13], v[4:5], off offset:1536
	s_cbranch_vccnz .LBB0_1323
	v_lshl_add_u64 v[4:5], s[50:51], 0, v[2:3]
	v_add_co_u32_e32 v4, vcc, 0x1000, v4
	s_nop 1
	v_addc_co_u32_e32 v5, vcc, 0, v5, vcc
	global_load_dwordx4 v[4:7], v[4:5], off
	s_cbranch_execnz .LBB0_1308
.LBB0_1307:
	s_waitcnt vmcnt(0) lgkmcnt(0)
	global_load_dwordx2 v[6:7], v[12:13], off offset:2048
	s_waitcnt vmcnt(0) lgkmcnt(0)
	v_lshlrev_b32_e32 v4, 16, v6
	v_and_b32_e32 v5, 0xffff0000, v6
	v_lshlrev_b32_e32 v6, 16, v7
	v_and_b32_e32 v7, 0xffff0000, v7
.LBB0_1308:
	v_add_co_u32_e32 v32, vcc, 0x1000, v14
	s_nop 1
	v_addc_co_u32_e32 v33, vcc, 0, v15, vcc
	v_add_co_u32_e32 v36, vcc, 0x1001000, v14
	global_load_dwordx4 v[32:35], v[32:33], off
	s_nop 0
	v_addc_co_u32_e32 v37, vcc, 0, v15, vcc
	global_load_dwordx4 v[36:39], v[36:37], off
	s_waitcnt vmcnt(0) lgkmcnt(0)
	v_pk_add_f32 v[42:43], v[32:33], v[36:37]
	v_add_co_u32_e32 v32, vcc, 0x2001000, v14
	v_pk_add_f32 v[40:41], v[34:35], v[38:39]
	s_nop 0
	v_addc_co_u32_e32 v33, vcc, 0, v15, vcc
	v_add_co_u32_e32 v36, vcc, 0x3001000, v14
	global_load_dwordx4 v[32:35], v[32:33], off
	s_nop 0
	v_addc_co_u32_e32 v37, vcc, 0, v15, vcc
	global_load_dwordx4 v[36:39], v[36:37], off
	s_and_b64 vcc, exec, s[42:43]
	s_waitcnt vmcnt(0) lgkmcnt(0)
	v_pk_add_f32 v[34:35], v[34:35], v[38:39]
	v_pk_add_f32 v[32:33], v[32:33], v[36:37]
	v_pk_add_f32 v[34:35], v[40:41], v[34:35]
	v_pk_add_f32 v[36:37], v[42:43], v[32:33]
	v_pk_add_f32 v[32:33], v[6:7], v[34:35]
	v_pk_add_f32 v[34:35], v[4:5], v[36:37]
	v_cvt_pk_bf16_f32 v5, v32, v33
	v_cvt_pk_bf16_f32 v4, v34, v35
	global_store_dwordx2 v[12:13], v[4:5], off offset:2048
	s_cbranch_vccnz .LBB0_1324
	v_lshl_add_u64 v[4:5], s[50:51], 0, v[2:3]
	v_add_co_u32_e32 v4, vcc, 0x1000, v4
	s_nop 1
	v_addc_co_u32_e32 v5, vcc, 0, v5, vcc
	global_load_dwordx4 v[4:7], v[4:5], off offset:1024
	s_cbranch_execnz .LBB0_1311
.LBB0_1310:
	s_waitcnt vmcnt(0) lgkmcnt(0)
	global_load_dwordx2 v[6:7], v[12:13], off offset:2560
	s_waitcnt vmcnt(0) lgkmcnt(0)
	v_lshlrev_b32_e32 v4, 16, v6
	v_and_b32_e32 v5, 0xffff0000, v6
	v_lshlrev_b32_e32 v6, 16, v7
	v_and_b32_e32 v7, 0xffff0000, v7
.LBB0_1311:
	v_add_co_u32_e32 v36, vcc, 0x1000, v14
	s_nop 1
	v_addc_co_u32_e32 v37, vcc, 0, v15, vcc
	v_add_co_u32_e32 v40, vcc, 0x1001000, v14
	global_load_dwordx4 v[36:39], v[36:37], off offset:1024
	s_nop 0
	v_addc_co_u32_e32 v41, vcc, 0, v15, vcc
	global_load_dwordx4 v[40:43], v[40:41], off offset:1024
	s_waitcnt vmcnt(0) lgkmcnt(0)
	v_pk_add_f32 v[52:53], v[36:37], v[40:41]
	v_add_co_u32_e32 v36, vcc, 0x2001000, v14
	v_pk_add_f32 v[50:51], v[38:39], v[42:43]
	s_nop 0
	v_addc_co_u32_e32 v37, vcc, 0, v15, vcc
	v_add_co_u32_e32 v40, vcc, 0x3001000, v14
	global_load_dwordx4 v[36:39], v[36:37], off offset:1024
	s_nop 0
	v_addc_co_u32_e32 v41, vcc, 0, v15, vcc
	global_load_dwordx4 v[40:43], v[40:41], off offset:1024
	s_and_b64 vcc, exec, s[42:43]
	s_waitcnt vmcnt(0) lgkmcnt(0)
	v_pk_add_f32 v[38:39], v[38:39], v[42:43]
	v_pk_add_f32 v[36:37], v[36:37], v[40:41]
	v_pk_add_f32 v[38:39], v[50:51], v[38:39]
	v_pk_add_f32 v[40:41], v[52:53], v[36:37]
	v_pk_add_f32 v[36:37], v[6:7], v[38:39]
	v_pk_add_f32 v[38:39], v[4:5], v[40:41]
	v_cvt_pk_bf16_f32 v5, v36, v37
	v_cvt_pk_bf16_f32 v4, v38, v39
	global_store_dwordx2 v[12:13], v[4:5], off offset:2560
	s_cbranch_vccnz .LBB0_1325
	v_lshl_add_u64 v[4:5], s[50:51], 0, v[2:3]
	v_add_co_u32_e32 v4, vcc, 0x1000, v4
	s_nop 1
	v_addc_co_u32_e32 v5, vcc, 0, v5, vcc
	global_load_dwordx4 v[4:7], v[4:5], off offset:2048
	s_cbranch_execnz .LBB0_1314
.LBB0_1313:
	s_waitcnt vmcnt(0) lgkmcnt(0)
	global_load_dwordx2 v[6:7], v[12:13], off offset:3072
	s_waitcnt vmcnt(0) lgkmcnt(0)
	v_lshlrev_b32_e32 v4, 16, v6
	v_and_b32_e32 v5, 0xffff0000, v6
	v_lshlrev_b32_e32 v6, 16, v7
	v_and_b32_e32 v7, 0xffff0000, v7
; DI float bflo(unsigned w) { return __uint_as_float(w << 16); }
; DI float bfhi(unsigned w) { return __uint_as_float(w & 0xffff0000u); }
; DI unsigned pk2(float a, float b) { f32x2 v = {a, b}; bf16v2 r = __builtin_convertvector(v, bf16v2); return __builtin_bit_cast(unsigned, r); }
; DI void phase_postRes(const Ctx& c, const float* xinS  ) {
;     ...
;     for (int row = MP + gw; row < M; row += NGW) {
;         const f32x4* pr = (const f32x4*)(part + (size_t)(row - MP) * DM) + c.lane; const size_t st = (size_t)MS * DM / 4;
;         u32x2* ao = (u32x2*)(act + (size_t)row * DM) + c.lane;
;         float s = 0.f;
; #pragma unroll
;         for (int j = 0; j < 8; ++j) {
;             f32x4 xi;
;             if (xinS) xi = ((const f32x4*)(xinS + (size_t)(row - MP) * DM) + c.lane)[64 * j];
;             else { const u32x2 w = ao[64 * j]; xi = (f32x4){bflo(w.x), bfhi(w.x), bflo(w.y), bfhi(w.y)}; }
;             const f32x4 v = xi + ((pr[64 * j] + pr[st + 64 * j]) + (pr[2 * st + 64 * j] + pr[3 * st + 64 * j]));
;             u32x2 w; w.x = pk2(v[0], v[1]); w.y = pk2(v[2], v[3]); ao[64 * j] = w;
;             s += (v[0] * v[0] + v[1] * v[1]) + (v[2] * v[2] + v[3] * v[3]);
;         }
;         s = wave_sum(s);
;         if (c.lane == 0) rs[row] = 1.0f / sqrtf(s * (1.0f / DM) + EPS);
;     }
.LBB0_1314:
	v_add_co_u32_e32 v40, vcc, 0x1000, v14
	s_nop 1
	v_addc_co_u32_e32 v41, vcc, 0, v15, vcc
	v_add_co_u32_e32 v50, vcc, 0x1001000, v14
	global_load_dwordx4 v[40:43], v[40:41], off offset:2048
	s_nop 0
	v_addc_co_u32_e32 v51, vcc, 0, v15, vcc
	global_load_dwordx4 v[50:53], v[50:51], off offset:2048
	s_waitcnt vmcnt(0) lgkmcnt(0)
	v_pk_add_f32 v[56:57], v[40:41], v[50:51]
	v_add_co_u32_e32 v40, vcc, 0x2001000, v14
	v_pk_add_f32 v[54:55], v[42:43], v[52:53]
	s_nop 0
	v_addc_co_u32_e32 v41, vcc, 0, v15, vcc
	v_add_co_u32_e32 v50, vcc, 0x3001000, v14
	global_load_dwordx4 v[40:43], v[40:41], off offset:2048
	s_nop 0
	v_addc_co_u32_e32 v51, vcc, 0, v15, vcc
	global_load_dwordx4 v[50:53], v[50:51], off offset:2048
	s_and_b64 vcc, exec, s[42:43]
	s_waitcnt vmcnt(0) lgkmcnt(0)
	v_pk_add_f32 v[42:43], v[42:43], v[52:53]
	v_pk_add_f32 v[40:41], v[40:41], v[50:51]
	v_pk_add_f32 v[42:43], v[54:55], v[42:43]
	v_pk_add_f32 v[50:51], v[56:57], v[40:41]
	v_pk_add_f32 v[40:41], v[6:7], v[42:43]
	v_pk_add_f32 v[42:43], v[4:5], v[50:51]
	v_cvt_pk_bf16_f32 v5, v40, v41
	v_cvt_pk_bf16_f32 v4, v42, v43
	global_store_dwordx2 v[12:13], v[4:5], off offset:3072
	s_cbranch_vccnz .LBB0_1326
	v_lshl_add_u64 v[4:5], s[50:51], 0, v[2:3]
	v_add_co_u32_e32 v4, vcc, 0x1000, v4
	s_nop 1
	v_addc_co_u32_e32 v5, vcc, 0, v5, vcc
	global_load_dwordx4 v[4:7], v[4:5], off offset:3072
	s_cbranch_execnz .LBB0_1317
.LBB0_1316:
	s_waitcnt vmcnt(0) lgkmcnt(0)
	global_load_dwordx2 v[6:7], v[12:13], off offset:3584
	s_waitcnt vmcnt(0) lgkmcnt(0)
	v_lshlrev_b32_e32 v4, 16, v6
	v_and_b32_e32 v5, 0xffff0000, v6
	v_lshlrev_b32_e32 v6, 16, v7
	v_and_b32_e32 v7, 0xffff0000, v7
.LBB0_1317:
	v_mul_f32_e32 v2, v19, v19
	v_mul_f32_e32 v17, v17, v17
	v_fmac_f32_e32 v2, v18, v18
	v_fmac_f32_e32 v17, v16, v16
	v_add_f32_e32 v2, v2, v17
	v_mul_f32_e32 v16, v23, v23
	v_mul_f32_e32 v17, v21, v21
	v_fmac_f32_e32 v16, v22, v22
	v_fmac_f32_e32 v17, v20, v20
	v_add_f32_e32 v16, v16, v17
	v_add_f32_e32 v2, v2, v16
	v_mul_f32_e32 v16, v27, v27
	v_mul_f32_e32 v17, v25, v25
	v_fmac_f32_e32 v16, v26, v26
	v_fmac_f32_e32 v17, v24, v24
	v_add_f32_e32 v16, v16, v17
	v_add_f32_e32 v2, v2, v16
	v_mul_f32_e32 v16, v31, v31
	v_mul_f32_e32 v17, v29, v29
	v_fmac_f32_e32 v16, v30, v30
	v_fmac_f32_e32 v17, v28, v28
	v_add_f32_e32 v16, v16, v17
	v_add_f32_e32 v2, v2, v16
	v_mul_f32_e32 v16, v35, v35
	v_mul_f32_e32 v17, v33, v33
	v_fmac_f32_e32 v16, v34, v34
	v_fmac_f32_e32 v17, v32, v32
	v_add_f32_e32 v16, v16, v17
	v_add_f32_e32 v2, v2, v16
	v_mul_f32_e32 v16, v39, v39
	v_mul_f32_e32 v17, v37, v37
	v_fmac_f32_e32 v16, v38, v38
	v_fmac_f32_e32 v17, v36, v36
	v_add_f32_e32 v16, v16, v17
	v_add_f32_e32 v2, v2, v16
	v_mul_f32_e32 v16, v43, v43
	v_mul_f32_e32 v17, v41, v41
	v_fmac_f32_e32 v16, v42, v42
	v_fmac_f32_e32 v17, v40, v40
	v_add_f32_e32 v16, v16, v17
	v_add_f32_e32 v2, v2, v16
	v_add_co_u32_e32 v16, vcc, s33, v14
	s_mov_b32 s11, 0x1001000
	s_nop 0
	v_addc_co_u32_e32 v17, vcc, 0, v15, vcc
	v_add_co_u32_e32 v20, vcc, s11, v14
	global_load_dwordx4 v[16:19], v[16:17], off offset:3072
	s_nop 0
	v_addc_co_u32_e32 v21, vcc, 0, v15, vcc
	global_load_dwordx4 v[20:23], v[20:21], off offset:3072
	s_mov_b32 s11, 0x2001000
	s_waitcnt vmcnt(0) lgkmcnt(0)
	v_pk_add_f32 v[26:27], v[16:17], v[20:21]
	v_add_co_u32_e32 v16, vcc, s11, v14
	s_mov_b32 s11, 0x3001000
	s_nop 0
	v_addc_co_u32_e32 v17, vcc, 0, v15, vcc
	v_add_co_u32_e32 v14, vcc, s11, v14
	v_pk_add_f32 v[24:25], v[18:19], v[22:23]
	s_nop 0
	v_addc_co_u32_e32 v15, vcc, 0, v15, vcc
	global_load_dwordx4 v[16:19], v[16:17], off offset:3072
	s_nop 0
	global_load_dwordx4 v[20:23], v[14:15], off offset:3072
	s_waitcnt vmcnt(0) lgkmcnt(0)
	v_pk_add_f32 v[16:17], v[16:17], v[20:21]
	v_pk_add_f32 v[14:15], v[18:19], v[22:23]
	v_pk_add_f32 v[16:17], v[26:27], v[16:17]
	v_pk_add_f32 v[14:15], v[24:25], v[14:15]
	v_pk_add_f32 v[4:5], v[4:5], v[16:17]
	v_pk_add_f32 v[6:7], v[6:7], v[14:15]
	v_cvt_pk_bf16_f32 v14, v4, v5
	v_mul_f32_e32 v5, v5, v5
	v_fmac_f32_e32 v5, v4, v4
	v_mul_f32_e32 v4, v7, v7
	v_fmac_f32_e32 v4, v6, v6
	v_add_f32_e32 v4, v5, v4
	v_add_f32_e32 v2, v2, v4
	ds_bpermute_b32 v4, v9, v2
	v_cvt_pk_bf16_f32 v15, v6, v7
	global_store_dwordx2 v[12:13], v[14:15], off offset:3584
	s_waitcnt lgkmcnt(0)
	v_add_f32_e32 v2, v2, v4
	ds_bpermute_b32 v4, v44, v2
	s_waitcnt lgkmcnt(0)
	v_add_f32_e32 v2, v2, v4
	ds_bpermute_b32 v4, v45, v2
	s_waitcnt lgkmcnt(0)
	v_add_f32_e32 v2, v2, v4
	ds_bpermute_b32 v4, v46, v2
	s_waitcnt lgkmcnt(0)
	v_add_f32_e32 v2, v2, v4
	ds_bpermute_b32 v4, v47, v2
	s_waitcnt lgkmcnt(0)
	v_add_f32_e32 v2, v2, v4
	ds_bpermute_b32 v4, v48, v2
	s_and_saveexec_b64 s[50:51], s[40:41]
	s_cbranch_execz .LBB0_1292
	s_waitcnt lgkmcnt(0)
	v_add_f32_e32 v2, v2, v4
	v_fmamk_f32 v2, v2, 0x3a000000, v220
	v_mul_f32_e32 v4, 0x4f800000, v2
	v_cmp_gt_f32_e32 vcc, s84, v2
	s_nop 1
	v_cndmask_b32_e32 v2, v2, v4, vcc
	v_sqrt_f32_e32 v4, v2
	s_nop 0
	v_add_u32_e32 v5, -1, v4
	v_fma_f32 v7, -v5, v4, v2
	v_add_u32_e32 v6, 1, v4
	v_cmp_ge_f32_e64 s[42:43], 0, v7
	s_nop 1
	v_cndmask_b32_e64 v5, v4, v5, s[42:43]
	v_fma_f32 v4, -v6, v4, v2
	v_cmp_lt_f32_e64 s[42:43], 0, v4
	s_nop 1
	v_cndmask_b32_e64 v4, v5, v6, s[42:43]
	v_mul_f32_e32 v5, 0x37800000, v4
	v_cndmask_b32_e32 v4, v4, v5, vcc
	v_cmp_class_f32_e32 vcc, v2, v221
	s_nop 1
	v_cndmask_b32_e32 v2, v4, v2, vcc
	v_div_scale_f32 v4, s[22:23], v2, v2, 1.0
	v_rcp_f32_e32 v5, v4
	s_nop 0
	v_fma_f32 v6, -v4, v5, 1.0
	v_fmac_f32_e32 v5, v6, v5
	v_div_scale_f32 v6, vcc, 1.0, v2, 1.0
	v_mul_f32_e32 v7, v6, v5
	v_fma_f32 v14, -v4, v7, v6
	v_fmac_f32_e32 v7, v14, v5
	v_fma_f32 v4, -v4, v7, v6
	v_div_fmas_f32 v4, v4, v5, v7
	v_div_fixup_f32 v2, v4, v2, 1.0
	v_mov_b64_e32 v[4:5], s[44:45]
	global_store_dword v[4:5], v2, off
	s_branch .LBB0_1292

; DI void phase_postRes(const Ctx& c, const float* xinS  ) {
;     ...
;     for (int row = c.bid * NTHR + c.tid; row < MP; row += c.G * NTHR) {
;         const f32x4* q = (const f32x4*)(ssq + (size_t)row * 32); float s = 0.f;
; #pragma unroll
;         for (int j = 0; j < 8; ++j) { const f32x4 v = q[j]; s += (v[0] + v[1]) + (v[2] + v[3]); }
;         rs[row] = 1.0f / sqrtf(s * (1.0f / DM) + EPS);
;     }
.LBB0_1329:
	global_load_dwordx4 v[10:13], v[8:9], off
	global_load_dwordx4 v[14:17], v[8:9], off offset:16
	v_add_u32_e32 v4, s18, v4
	s_waitcnt vmcnt(0) lgkmcnt(0)
	v_mov_b32_e32 v18, v10
	v_mov_b32_e32 v19, v14
	v_mov_b32_e32 v14, v11
	v_pk_add_f32 v[10:11], v[18:19], v[14:15]
	v_mov_b32_e32 v14, v12
	v_mov_b32_e32 v15, v16
	v_mov_b32_e32 v16, v13
	v_pk_add_f32 v[12:13], v[14:15], v[16:17]
	s_nop 0
	v_pk_add_f32 v[10:11], v[10:11], v[12:13]
	s_nop 0
	v_add_f32_e32 v1, 0, v10
	v_add_f32_e32 v14, v1, v11
	global_load_dwordx4 v[10:13], v[8:9], off offset:32
	s_waitcnt vmcnt(0) lgkmcnt(0)
	v_mov_b32_e32 v16, v11
	v_mov_b32_e32 v17, v12
	v_mov_b32_e32 v11, v13
	v_pk_add_f32 v[10:11], v[16:17], v[10:11]
	s_nop 0
	v_pk_add_f32 v[16:17], v[10:11], v[10:11] op_sel:[0,1] op_sel_hi:[1,0]
	global_load_dwordx4 v[10:13], v[8:9], off offset:48
	s_waitcnt vmcnt(0) lgkmcnt(0)
	v_add_f32_e32 v18, v10, v11
	v_add_f32_e32 v20, v12, v13
	global_load_dwordx4 v[10:13], v[8:9], off offset:64
	s_waitcnt vmcnt(0) lgkmcnt(0)
	v_mov_b32_e32 v15, v10
	v_mov_b32_e32 v17, v11
	v_mov_b32_e32 v19, v12
	v_mov_b32_e32 v21, v13
	v_pk_add_f32 v[10:11], v[14:15], v[16:17]
	v_pk_add_f32 v[12:13], v[18:19], v[20:21]
	s_nop 0
	v_pk_add_f32 v[10:11], v[10:11], v[12:13]
	s_nop 0
	v_pk_add_f32 v[14:15], v[10:11], v[10:11] op_sel:[0,1] op_sel_hi:[1,0]
	global_load_dwordx4 v[10:13], v[8:9], off offset:80
	s_waitcnt vmcnt(0) lgkmcnt(0)
	v_mov_b32_e32 v16, v11
	v_mov_b32_e32 v17, v12
	v_mov_b32_e32 v11, v13
	v_pk_add_f32 v[10:11], v[16:17], v[10:11]
	s_nop 0
	v_pk_add_f32 v[16:17], v[10:11], v[10:11] op_sel:[0,1] op_sel_hi:[1,0]
	global_load_dwordx4 v[10:13], v[8:9], off offset:96
	s_waitcnt vmcnt(0) lgkmcnt(0)
	v_add_f32_e32 v18, v10, v11
	v_add_f32_e32 v20, v12, v13
	global_load_dwordx4 v[10:13], v[8:9], off offset:112
	v_lshl_add_u64 v[8:9], v[8:9], 0, s[34:35]
	s_waitcnt vmcnt(0) lgkmcnt(0)
	v_mov_b32_e32 v15, v10
	v_mov_b32_e32 v17, v11
	v_mov_b32_e32 v19, v12
	v_mov_b32_e32 v21, v13
	v_pk_add_f32 v[10:11], v[14:15], v[16:17]
	v_pk_add_f32 v[12:13], v[18:19], v[20:21]
	s_nop 0
	v_pk_add_f32 v[10:11], v[10:11], v[12:13]
	s_nop 0
	v_add_f32_e32 v1, v10, v11
	v_fmamk_f32 v1, v1, 0x3a000000, v220
	v_cmp_gt_f32_e32 vcc, s84, v1
	v_mul_f32_e32 v2, 0x4f800000, v1
	s_nop 0
	v_cndmask_b32_e32 v1, v1, v2, vcc
	v_sqrt_f32_e32 v2, v1
	s_nop 0
	v_add_u32_e32 v5, -1, v2
	v_fma_f32 v10, -v5, v2, v1
	v_cmp_ge_f32_e64 s[40:41], 0, v10
	v_add_u32_e32 v10, 1, v2
	s_nop 0
	v_cndmask_b32_e64 v5, v2, v5, s[40:41]
	v_fma_f32 v2, -v10, v2, v1
	v_cmp_lt_f32_e64 s[40:41], 0, v2
	s_nop 1
	v_cndmask_b32_e64 v2, v5, v10, s[40:41]
	v_mul_f32_e32 v5, 0x37800000, v2
	v_cndmask_b32_e32 v2, v2, v5, vcc
	v_cmp_class_f32_e32 vcc, v1, v221
	s_nop 1
	v_cndmask_b32_e32 v1, v2, v1, vcc
	v_div_scale_f32 v2, s[22:23], v1, v1, 1.0
	v_rcp_f32_e32 v5, v2
	s_nop 0
	v_fma_f32 v10, -v2, v5, 1.0
	v_fmac_f32_e32 v5, v10, v5
	v_div_scale_f32 v10, vcc, 1.0, v1, 1.0
	v_mul_f32_e32 v11, v10, v5
	v_fma_f32 v12, -v2, v11, v10
	v_fmac_f32_e32 v11, v12, v5
	v_fma_f32 v2, -v2, v11, v10
	v_div_fmas_f32 v2, v2, v5, v11
	v_div_fixup_f32 v1, v2, v1, 1.0
	v_cmp_lt_i32_e32 vcc, s11, v4
	global_store_dword v[6:7], v1, off
	v_lshl_add_u64 v[6:7], v[6:7], 0, s[4:5]
	s_or_b64 s[38:39], vcc, s[38:39]
	s_andn2_b64 exec, exec, s[38:39]
	s_cbranch_execnz .LBB0_1329

; DI u32x4 pack8(const f32x4 v0, const f32x4 v1) { u32x4 w; w.x = pk2(v0[0], v0[1]); w.y = pk2(v0[2], v0[3]); w.z = pk2(v1[0], v1[1]); w.w = pk2(v1[2], v1[3]); return w; }
;     DI void operator()(const f32x4 (&acc)[2][2][4][2], const Unit& u, int wr, int wc, int fr, int fq, const LAS float* rsl) const {
;         const int row0 = u.pm * BM + wr * 64 + fr, col0 = u.pn * BM + wc * 32 + 8 * fq;
; #pragma unroll
;         for (int ai = 0; ai < 2; ++ai)
; #pragma unroll
;             for (int m = 0; m < 4; ++m) {
;                 const int row = row0 + ai * HALF + m * 16; const float s = rsl[wr * 64 + fr + ai * HALF + m * 16];
;                 bf16_t* rowp = H + (size_t)row * DFF + col0;
; #pragma unroll
;                 for (int bj = 0; bj < 2; ++bj) {
;                     f32x4 v0 = acc[ai][bj][m][0] * s, v1 = acc[ai][bj][m][1] * s;
; #pragma unroll
;                     for (int j = 0; j < 4; ++j) { v0[j] = fmaxf(v0[j], 0.f); v0[j] *= v0[j]; v1[j] = fmaxf(v1[j], 0.f); v1[j] *= v1[j]; }
;                     *(u32x4*)(rowp + bj * HALF) = pack8(v0, v1);
;                 }
;             }
.LBB0_1393:
	s_lshl_b32 s39, s64, 10
	s_and_b32 s39, s39, 0x400
	v_add_u32_e32 v152, s39, v149
	ds_read_b32 v154, v152
	v_lshl_add_u32 v146, s63, 8, v1
	v_lshl_or_b32 v144, s62, 8, v150
	v_ashrrev_i32_e32 v147, 31, v146
	v_ashrrev_i32_e32 v145, 31, v144
	v_lshlrev_b64 v[156:157], 14, v[146:147]
	s_waitcnt lgkmcnt(0)
	v_pk_mul_f32 v[124:125], v[124:125], v[154:155] op_sel_hi:[1,0]
	v_lshl_add_u64 v[156:157], s[18:19], 0, v[156:157]
	v_lshlrev_b64 v[158:159], 1, v[144:145]
	v_pk_mul_f32 v[130:131], v[130:131], v[154:155] op_sel_hi:[1,0]
	v_pk_mul_f32 v[128:129], v[128:129], v[154:155] op_sel_hi:[1,0]
	v_pk_mul_f32 v[126:127], v[126:127], v[154:155] op_sel_hi:[1,0]
	v_max_f32_e32 v124, 0, v124
	v_max_f32_e32 v125, 0, v125
	v_lshl_add_u64 v[144:145], v[156:157], 0, v[158:159]
	v_max_f32_e32 v128, 0, v128
	v_max_f32_e32 v129, 0, v129
	v_pk_mul_f32 v[156:157], v[124:125], v[124:125]
	v_max_f32_e32 v124, 0, v130
	v_max_f32_e32 v126, 0, v126
	v_max_f32_e32 v125, 0, v131
	v_max_f32_e32 v127, 0, v127
	v_pk_mul_f32 v[128:129], v[128:129], v[128:129]
	v_pk_mul_f32 v[130:131], v[124:125], v[124:125]
	v_pk_mul_f32 v[160:161], v[126:127], v[126:127]
	v_pk_mul_f32 v[116:117], v[116:117], v[154:155] op_sel_hi:[1,0]
	v_cvt_pk_bf16_f32 v124, v128, v129
	v_cvt_pk_bf16_f32 v125, v130, v131
	v_cvt_pk_bf16_f32 v126, v156, v157
	v_cvt_pk_bf16_f32 v127, v160, v161
	v_pk_mul_f32 v[122:123], v[122:123], v[154:155] op_sel_hi:[1,0]
	v_pk_mul_f32 v[120:121], v[120:121], v[154:155] op_sel_hi:[1,0]
	v_pk_mul_f32 v[118:119], v[118:119], v[154:155] op_sel_hi:[1,0]
	v_max_f32_e32 v116, 0, v116
	v_max_f32_e32 v117, 0, v117
	global_store_dwordx4 v[144:145], v[124:127], off
	v_max_f32_e32 v120, 0, v120
	v_max_f32_e32 v121, 0, v121
	v_pk_mul_f32 v[124:125], v[116:117], v[116:117]
	v_max_f32_e32 v116, 0, v122
	v_max_f32_e32 v118, 0, v118
	v_max_f32_e32 v117, 0, v123
	v_max_f32_e32 v119, 0, v119
	v_pk_mul_f32 v[120:121], v[120:121], v[120:121]
	v_pk_mul_f32 v[122:123], v[116:117], v[116:117]
	v_pk_mul_f32 v[126:127], v[118:119], v[118:119]
	v_cvt_pk_bf16_f32 v116, v120, v121
	v_cvt_pk_bf16_f32 v117, v122, v123
	v_cvt_pk_bf16_f32 v118, v124, v125
	v_cvt_pk_bf16_f32 v119, v126, v127
	global_store_dwordx4 v[144:145], v[116:119], off offset:256
	ds_read_b32 v118, v152 offset:64
	s_mov_b32 s39, 0x200000
	v_or_b32_e32 v116, 16, v146
	v_ashrrev_i32_e32 v117, 31, v116
	v_lshlrev_b64 v[116:117], 14, v[116:117]
	s_waitcnt lgkmcnt(0)
	v_pk_mul_f32 v[108:109], v[108:109], v[118:119] op_sel_hi:[1,0]
	v_pk_mul_f32 v[114:115], v[114:115], v[118:119] op_sel_hi:[1,0]
	v_pk_mul_f32 v[112:113], v[112:113], v[118:119] op_sel_hi:[1,0]
	v_pk_mul_f32 v[110:111], v[110:111], v[118:119] op_sel_hi:[1,0]
	v_max_f32_e32 v108, 0, v108
	v_max_f32_e32 v109, 0, v109
	v_max_f32_e32 v112, 0, v112
	v_max_f32_e32 v113, 0, v113
	v_pk_mul_f32 v[120:121], v[108:109], v[108:109]
	v_max_f32_e32 v108, 0, v114
	v_max_f32_e32 v110, 0, v110
	v_max_f32_e32 v109, 0, v115
	v_max_f32_e32 v111, 0, v111
	v_lshl_add_u64 v[116:117], s[18:19], 0, v[116:117]
	v_pk_mul_f32 v[112:113], v[112:113], v[112:113]
	v_pk_mul_f32 v[114:115], v[108:109], v[108:109]
	v_pk_mul_f32 v[122:123], v[110:111], v[110:111]
	v_pk_mul_f32 v[100:101], v[100:101], v[118:119] op_sel_hi:[1,0]
	v_lshl_add_u64 v[116:117], v[116:117], 0, v[158:159]
	v_cvt_pk_bf16_f32 v108, v112, v113
	v_cvt_pk_bf16_f32 v109, v114, v115
	v_cvt_pk_bf16_f32 v110, v120, v121
	v_cvt_pk_bf16_f32 v111, v122, v123
	v_pk_mul_f32 v[106:107], v[106:107], v[118:119] op_sel_hi:[1,0]
	v_pk_mul_f32 v[104:105], v[104:105], v[118:119] op_sel_hi:[1,0]
	v_pk_mul_f32 v[102:103], v[102:103], v[118:119] op_sel_hi:[1,0]
	v_max_f32_e32 v100, 0, v100
	v_max_f32_e32 v101, 0, v101
	global_store_dwordx4 v[116:117], v[108:111], off
	v_max_f32_e32 v104, 0, v104
	v_max_f32_e32 v105, 0, v105
	v_pk_mul_f32 v[108:109], v[100:101], v[100:101]
	v_max_f32_e32 v100, 0, v106
	v_max_f32_e32 v102, 0, v102
	v_max_f32_e32 v101, 0, v107
	v_max_f32_e32 v103, 0, v103
	v_pk_mul_f32 v[104:105], v[104:105], v[104:105]
	v_pk_mul_f32 v[106:107], v[100:101], v[100:101]
	v_pk_mul_f32 v[110:111], v[102:103], v[102:103]
	v_cvt_pk_bf16_f32 v100, v104, v105
	v_cvt_pk_bf16_f32 v101, v106, v107
	v_cvt_pk_bf16_f32 v102, v108, v109
	v_cvt_pk_bf16_f32 v103, v110, v111
	global_store_dwordx4 v[116:117], v[100:103], off offset:256
	ds_read_b32 v102, v152 offset:128
	s_mov_b64 s[48:49], 0x200000
	v_or_b32_e32 v100, 32, v146
	v_ashrrev_i32_e32 v101, 31, v100
	v_lshlrev_b64 v[100:101], 14, v[100:101]
	s_waitcnt lgkmcnt(0)
	v_pk_mul_f32 v[92:93], v[92:93], v[102:103] op_sel_hi:[1,0]
	v_pk_mul_f32 v[98:99], v[98:99], v[102:103] op_sel_hi:[1,0]
	v_pk_mul_f32 v[96:97], v[96:97], v[102:103] op_sel_hi:[1,0]
	v_pk_mul_f32 v[94:95], v[94:95], v[102:103] op_sel_hi:[1,0]
	v_max_f32_e32 v92, 0, v92
	v_max_f32_e32 v93, 0, v93
	v_max_f32_e32 v96, 0, v96
	v_max_f32_e32 v97, 0, v97
	v_pk_mul_f32 v[104:105], v[92:93], v[92:93]
	v_max_f32_e32 v92, 0, v98
	v_max_f32_e32 v94, 0, v94
	v_max_f32_e32 v93, 0, v99
	v_max_f32_e32 v95, 0, v95
	v_lshl_add_u64 v[100:101], s[18:19], 0, v[100:101]
	v_pk_mul_f32 v[96:97], v[96:97], v[96:97]
	v_pk_mul_f32 v[98:99], v[92:93], v[92:93]
	v_pk_mul_f32 v[106:107], v[94:95], v[94:95]
	v_pk_mul_f32 v[84:85], v[84:85], v[102:103] op_sel_hi:[1,0]
	v_lshl_add_u64 v[100:101], v[100:101], 0, v[158:159]
	v_cvt_pk_bf16_f32 v92, v96, v97
	v_cvt_pk_bf16_f32 v93, v98, v99
	v_cvt_pk_bf16_f32 v94, v104, v105
	v_cvt_pk_bf16_f32 v95, v106, v107
	v_pk_mul_f32 v[90:91], v[90:91], v[102:103] op_sel_hi:[1,0]
	v_pk_mul_f32 v[88:89], v[88:89], v[102:103] op_sel_hi:[1,0]
	v_pk_mul_f32 v[86:87], v[86:87], v[102:103] op_sel_hi:[1,0]
	v_max_f32_e32 v84, 0, v84
	v_max_f32_e32 v85, 0, v85
	global_store_dwordx4 v[100:101], v[92:95], off
	v_max_f32_e32 v88, 0, v88
	v_max_f32_e32 v89, 0, v89
	v_pk_mul_f32 v[92:93], v[84:85], v[84:85]
	v_max_f32_e32 v84, 0, v90
	v_max_f32_e32 v86, 0, v86
	v_max_f32_e32 v85, 0, v91
	v_max_f32_e32 v87, 0, v87
	v_pk_mul_f32 v[88:89], v[88:89], v[88:89]
	v_pk_mul_f32 v[90:91], v[84:85], v[84:85]
	v_pk_mul_f32 v[94:95], v[86:87], v[86:87]
	v_cvt_pk_bf16_f32 v84, v88, v89
	v_cvt_pk_bf16_f32 v85, v90, v91
	v_cvt_pk_bf16_f32 v86, v92, v93
	v_cvt_pk_bf16_f32 v87, v94, v95
	global_store_dwordx4 v[100:101], v[84:87], off offset:256
	ds_read_b32 v86, v152 offset:192
	s_waitcnt lgkmcnt(0)
; DI u32x4 pack8(const f32x4 v0, const f32x4 v1) { u32x4 w; w.x = pk2(v0[0], v0[1]); w.y = pk2(v0[2], v0[3]); w.z = pk2(v1[0], v1[1]); w.w = pk2(v1[2], v1[3]); return w; }
;     DI void operator()(const f32x4 (&acc)[2][2][4][2], const Unit& u, int wr, int wc, int fr, int fq, const LAS float* rsl) const {
;         const int row0 = u.pm * BM + wr * 64 + fr, col0 = u.pn * BM + wc * 32 + 8 * fq;
; #pragma unroll
;         for (int ai = 0; ai < 2; ++ai)
; #pragma unroll
;             for (int m = 0; m < 4; ++m) {
;                 const int row = row0 + ai * HALF + m * 16; const float s = rsl[wr * 64 + fr + ai * HALF + m * 16];
;                 bf16_t* rowp = H + (size_t)row * DFF + col0;
; #pragma unroll
;                 for (int bj = 0; bj < 2; ++bj) {
;                     f32x4 v0 = acc[ai][bj][m][0] * s, v1 = acc[ai][bj][m][1] * s;
; #pragma unroll
;                     for (int j = 0; j < 4; ++j) { v0[j] = fmaxf(v0[j], 0.f); v0[j] *= v0[j]; v1[j] = fmaxf(v1[j], 0.f); v1[j] *= v1[j]; }
;                     *(u32x4*)(rowp + bj * HALF) = pack8(v0, v1);
;                 }
;             }
	v_pk_mul_f32 v[76:77], v[76:77], v[86:87] op_sel_hi:[1,0]
	v_or_b32_e32 v84, 48, v146
	v_ashrrev_i32_e32 v85, 31, v84
	v_pk_mul_f32 v[82:83], v[82:83], v[86:87] op_sel_hi:[1,0]
	v_pk_mul_f32 v[80:81], v[80:81], v[86:87] op_sel_hi:[1,0]
	v_pk_mul_f32 v[78:79], v[78:79], v[86:87] op_sel_hi:[1,0]
	v_max_f32_e32 v76, 0, v76
	v_max_f32_e32 v77, 0, v77
	v_lshlrev_b64 v[84:85], 14, v[84:85]
	v_max_f32_e32 v80, 0, v80
	v_max_f32_e32 v81, 0, v81
	v_pk_mul_f32 v[88:89], v[76:77], v[76:77]
	v_max_f32_e32 v76, 0, v82
	v_max_f32_e32 v78, 0, v78
	v_max_f32_e32 v77, 0, v83
	v_max_f32_e32 v79, 0, v79
	v_lshl_add_u64 v[84:85], s[18:19], 0, v[84:85]
	v_pk_mul_f32 v[80:81], v[80:81], v[80:81]
	v_pk_mul_f32 v[82:83], v[76:77], v[76:77]
	v_pk_mul_f32 v[90:91], v[78:79], v[78:79]
	v_pk_mul_f32 v[68:69], v[68:69], v[86:87] op_sel_hi:[1,0]
	v_lshl_add_u64 v[84:85], v[84:85], 0, v[158:159]
	v_cvt_pk_bf16_f32 v76, v80, v81
	v_cvt_pk_bf16_f32 v77, v82, v83
	v_cvt_pk_bf16_f32 v78, v88, v89
	v_cvt_pk_bf16_f32 v79, v90, v91
	v_pk_mul_f32 v[74:75], v[74:75], v[86:87] op_sel_hi:[1,0]
	v_pk_mul_f32 v[72:73], v[72:73], v[86:87] op_sel_hi:[1,0]
	v_pk_mul_f32 v[70:71], v[70:71], v[86:87] op_sel_hi:[1,0]
	v_max_f32_e32 v68, 0, v68
	v_max_f32_e32 v69, 0, v69
	global_store_dwordx4 v[84:85], v[76:79], off
	v_max_f32_e32 v72, 0, v72
	v_max_f32_e32 v73, 0, v73
	v_pk_mul_f32 v[76:77], v[68:69], v[68:69]
	v_max_f32_e32 v68, 0, v74
	v_max_f32_e32 v70, 0, v70
	v_max_f32_e32 v69, 0, v75
	v_max_f32_e32 v71, 0, v71
	v_pk_mul_f32 v[72:73], v[72:73], v[72:73]
	v_pk_mul_f32 v[74:75], v[68:69], v[68:69]
	v_pk_mul_f32 v[78:79], v[70:71], v[70:71]
	v_cvt_pk_bf16_f32 v68, v72, v73
	v_cvt_pk_bf16_f32 v69, v74, v75
	v_cvt_pk_bf16_f32 v70, v76, v77
	v_cvt_pk_bf16_f32 v71, v78, v79
	global_store_dwordx4 v[84:85], v[68:71], off offset:256
	ds_read_b32 v68, v152 offset:512
	s_waitcnt lgkmcnt(0)
	v_pk_mul_f32 v[64:65], v[64:65], v[68:69] op_sel_hi:[1,0]
	v_pk_mul_f32 v[60:61], v[60:61], v[68:69] op_sel_hi:[1,0]
	v_pk_mul_f32 v[66:67], v[66:67], v[68:69] op_sel_hi:[1,0]
	v_pk_mul_f32 v[62:63], v[62:63], v[68:69] op_sel_hi:[1,0]
	v_max_f32_e32 v64, 0, v64
	v_max_f32_e32 v60, 0, v60
	v_max_f32_e32 v65, 0, v65
	v_max_f32_e32 v61, 0, v61
	v_pk_mul_f32 v[64:65], v[64:65], v[64:65]
	v_pk_mul_f32 v[72:73], v[60:61], v[60:61]
	v_max_f32_e32 v60, 0, v66
	v_max_f32_e32 v62, 0, v62
	v_max_f32_e32 v61, 0, v67
	v_max_f32_e32 v63, 0, v63
	v_pk_mul_f32 v[66:67], v[60:61], v[60:61]
	v_pk_mul_f32 v[74:75], v[62:63], v[62:63]
	v_cvt_pk_bf16_f32 v60, v64, v65
	v_add_co_u32_e32 v64, vcc, s39, v144
	v_pk_mul_f32 v[52:53], v[52:53], v[68:69] op_sel_hi:[1,0]
	v_cvt_pk_bf16_f32 v61, v66, v67
	v_cvt_pk_bf16_f32 v62, v72, v73
	v_cvt_pk_bf16_f32 v63, v74, v75
	v_addc_co_u32_e32 v65, vcc, 0, v145, vcc
	v_pk_mul_f32 v[58:59], v[58:59], v[68:69] op_sel_hi:[1,0]
	v_pk_mul_f32 v[56:57], v[56:57], v[68:69] op_sel_hi:[1,0]
	v_pk_mul_f32 v[54:55], v[54:55], v[68:69] op_sel_hi:[1,0]
	v_max_f32_e32 v52, 0, v52
	v_max_f32_e32 v53, 0, v53
	global_store_dwordx4 v[64:65], v[60:63], off
	v_max_f32_e32 v56, 0, v56
	v_max_f32_e32 v57, 0, v57
	v_pk_mul_f32 v[60:61], v[52:53], v[52:53]
	v_max_f32_e32 v52, 0, v58
	v_max_f32_e32 v54, 0, v54
	v_max_f32_e32 v53, 0, v59
	v_max_f32_e32 v55, 0, v55
	v_pk_mul_f32 v[56:57], v[56:57], v[56:57]
	v_pk_mul_f32 v[58:59], v[52:53], v[52:53]
	v_pk_mul_f32 v[62:63], v[54:55], v[54:55]
	v_lshl_add_u64 v[70:71], v[144:145], 0, s[48:49]
	v_cvt_pk_bf16_f32 v52, v56, v57
	v_cvt_pk_bf16_f32 v53, v58, v59
	v_cvt_pk_bf16_f32 v54, v60, v61
	v_cvt_pk_bf16_f32 v55, v62, v63
	global_store_dwordx4 v[70:71], v[52:55], off offset:256
	ds_read_b32 v52, v152 offset:576
	s_mov_b32 s39, 0x240000
	s_mov_b64 s[48:49], 0x240000
	v_lshl_add_u64 v[54:55], v[144:145], 0, s[48:49]
	s_mov_b64 s[48:49], 0x280000
	s_waitcnt lgkmcnt(0)
	v_pk_mul_f32 v[48:49], v[48:49], v[52:53] op_sel_hi:[1,0]
	v_pk_mul_f32 v[44:45], v[44:45], v[52:53] op_sel_hi:[1,0]
	v_pk_mul_f32 v[50:51], v[50:51], v[52:53] op_sel_hi:[1,0]
	v_pk_mul_f32 v[46:47], v[46:47], v[52:53] op_sel_hi:[1,0]
	v_max_f32_e32 v48, 0, v48
	v_max_f32_e32 v44, 0, v44
	v_max_f32_e32 v49, 0, v49
	v_max_f32_e32 v45, 0, v45
	v_pk_mul_f32 v[48:49], v[48:49], v[48:49]
	v_pk_mul_f32 v[56:57], v[44:45], v[44:45]
	v_max_f32_e32 v44, 0, v50
	v_max_f32_e32 v46, 0, v46
	v_max_f32_e32 v45, 0, v51
	v_max_f32_e32 v47, 0, v47
	v_pk_mul_f32 v[50:51], v[44:45], v[44:45]
	v_pk_mul_f32 v[58:59], v[46:47], v[46:47]
	v_cvt_pk_bf16_f32 v44, v48, v49
	v_add_co_u32_e32 v48, vcc, s39, v144
	v_pk_mul_f32 v[36:37], v[36:37], v[52:53] op_sel_hi:[1,0]
	v_cvt_pk_bf16_f32 v45, v50, v51
	v_cvt_pk_bf16_f32 v46, v56, v57
	v_cvt_pk_bf16_f32 v47, v58, v59
	v_addc_co_u32_e32 v49, vcc, 0, v145, vcc
	v_pk_mul_f32 v[42:43], v[42:43], v[52:53] op_sel_hi:[1,0]
	v_pk_mul_f32 v[40:41], v[40:41], v[52:53] op_sel_hi:[1,0]
	v_pk_mul_f32 v[38:39], v[38:39], v[52:53] op_sel_hi:[1,0]
	v_max_f32_e32 v36, 0, v36
	v_max_f32_e32 v37, 0, v37
	global_store_dwordx4 v[48:49], v[44:47], off
	v_max_f32_e32 v40, 0, v40
	v_max_f32_e32 v41, 0, v41
	v_pk_mul_f32 v[44:45], v[36:37], v[36:37]
	v_max_f32_e32 v36, 0, v42
	v_max_f32_e32 v38, 0, v38
	v_max_f32_e32 v37, 0, v43
	v_max_f32_e32 v39, 0, v39
	v_pk_mul_f32 v[40:41], v[40:41], v[40:41]
	v_pk_mul_f32 v[42:43], v[36:37], v[36:37]
	v_pk_mul_f32 v[46:47], v[38:39], v[38:39]
	v_cvt_pk_bf16_f32 v36, v40, v41
	v_cvt_pk_bf16_f32 v37, v42, v43
	v_cvt_pk_bf16_f32 v38, v44, v45
	v_cvt_pk_bf16_f32 v39, v46, v47
	global_store_dwordx4 v[54:55], v[36:39], off offset:256
	ds_read_b32 v36, v152 offset:640
	s_mov_b32 s39, 0x280000
	v_lshl_add_u64 v[38:39], v[144:145], 0, s[48:49]
	s_mov_b64 s[48:49], 0x2c0000
	s_waitcnt lgkmcnt(0)
; DI u32x4 pack8(const f32x4 v0, const f32x4 v1) { u32x4 w; w.x = pk2(v0[0], v0[1]); w.y = pk2(v0[2], v0[3]); w.z = pk2(v1[0], v1[1]); w.w = pk2(v1[2], v1[3]); return w; }
;     DI void operator()(const f32x4 (&acc)[2][2][4][2], const Unit& u, int wr, int wc, int fr, int fq, const LAS float* rsl) const {
;         const int row0 = u.pm * BM + wr * 64 + fr, col0 = u.pn * BM + wc * 32 + 8 * fq;
; #pragma unroll
;         for (int ai = 0; ai < 2; ++ai)
; #pragma unroll
;             for (int m = 0; m < 4; ++m) {
;                 const int row = row0 + ai * HALF + m * 16; const float s = rsl[wr * 64 + fr + ai * HALF + m * 16];
;                 bf16_t* rowp = H + (size_t)row * DFF + col0;
; #pragma unroll
;                 for (int bj = 0; bj < 2; ++bj) {
;                     f32x4 v0 = acc[ai][bj][m][0] * s, v1 = acc[ai][bj][m][1] * s;
; #pragma unroll
;                     for (int j = 0; j < 4; ++j) { v0[j] = fmaxf(v0[j], 0.f); v0[j] *= v0[j]; v1[j] = fmaxf(v1[j], 0.f); v1[j] *= v1[j]; }
;                     *(u32x4*)(rowp + bj * HALF) = pack8(v0, v1);
;                 }
;             }
	v_pk_mul_f32 v[32:33], v[32:33], v[36:37] op_sel_hi:[1,0]
	v_pk_mul_f32 v[28:29], v[28:29], v[36:37] op_sel_hi:[1,0]
	v_pk_mul_f32 v[34:35], v[34:35], v[36:37] op_sel_hi:[1,0]
	v_pk_mul_f32 v[30:31], v[30:31], v[36:37] op_sel_hi:[1,0]
	v_max_f32_e32 v32, 0, v32
	v_max_f32_e32 v28, 0, v28
	v_max_f32_e32 v33, 0, v33
	v_max_f32_e32 v29, 0, v29
	v_pk_mul_f32 v[32:33], v[32:33], v[32:33]
	v_pk_mul_f32 v[40:41], v[28:29], v[28:29]
	v_max_f32_e32 v28, 0, v34
	v_max_f32_e32 v30, 0, v30
	v_max_f32_e32 v29, 0, v35
	v_max_f32_e32 v31, 0, v31
	v_pk_mul_f32 v[34:35], v[28:29], v[28:29]
	v_pk_mul_f32 v[42:43], v[30:31], v[30:31]
	v_cvt_pk_bf16_f32 v28, v32, v33
	v_add_co_u32_e32 v32, vcc, s39, v144
	v_pk_mul_f32 v[20:21], v[20:21], v[36:37] op_sel_hi:[1,0]
	v_cvt_pk_bf16_f32 v29, v34, v35
	v_cvt_pk_bf16_f32 v30, v40, v41
	v_cvt_pk_bf16_f32 v31, v42, v43
	v_addc_co_u32_e32 v33, vcc, 0, v145, vcc
	v_pk_mul_f32 v[26:27], v[26:27], v[36:37] op_sel_hi:[1,0]
	v_pk_mul_f32 v[24:25], v[24:25], v[36:37] op_sel_hi:[1,0]
	v_pk_mul_f32 v[22:23], v[22:23], v[36:37] op_sel_hi:[1,0]
	v_max_f32_e32 v20, 0, v20
	v_max_f32_e32 v21, 0, v21
	global_store_dwordx4 v[32:33], v[28:31], off
	v_max_f32_e32 v24, 0, v24
	v_max_f32_e32 v25, 0, v25
	v_pk_mul_f32 v[28:29], v[20:21], v[20:21]
	v_max_f32_e32 v20, 0, v26
	v_max_f32_e32 v22, 0, v22
	v_max_f32_e32 v21, 0, v27
	v_max_f32_e32 v23, 0, v23
	v_pk_mul_f32 v[24:25], v[24:25], v[24:25]
	v_pk_mul_f32 v[26:27], v[20:21], v[20:21]
	v_pk_mul_f32 v[30:31], v[22:23], v[22:23]
	v_cvt_pk_bf16_f32 v20, v24, v25
	v_cvt_pk_bf16_f32 v21, v26, v27
	v_cvt_pk_bf16_f32 v22, v28, v29
	v_cvt_pk_bf16_f32 v23, v30, v31
	global_store_dwordx4 v[38:39], v[20:23], off offset:256
	ds_read_b32 v20, v152 offset:704
	s_mov_b32 s39, 0x2c0000
	v_lshl_add_u64 v[22:23], v[144:145], 0, s[48:49]
	s_waitcnt lgkmcnt(0)
	v_pk_mul_f32 v[16:17], v[16:17], v[20:21] op_sel_hi:[1,0]
	v_pk_mul_f32 v[12:13], v[12:13], v[20:21] op_sel_hi:[1,0]
	v_pk_mul_f32 v[18:19], v[18:19], v[20:21] op_sel_hi:[1,0]
	v_pk_mul_f32 v[14:15], v[14:15], v[20:21] op_sel_hi:[1,0]
	v_max_f32_e32 v16, 0, v16
	v_max_f32_e32 v12, 0, v12
	v_max_f32_e32 v17, 0, v17
	v_max_f32_e32 v13, 0, v13
	v_pk_mul_f32 v[16:17], v[16:17], v[16:17]
	v_pk_mul_f32 v[24:25], v[12:13], v[12:13]
	v_max_f32_e32 v12, 0, v18
	v_max_f32_e32 v14, 0, v14
	v_max_f32_e32 v13, 0, v19
	v_max_f32_e32 v15, 0, v15
	v_pk_mul_f32 v[18:19], v[12:13], v[12:13]
	v_pk_mul_f32 v[26:27], v[14:15], v[14:15]
	v_cvt_pk_bf16_f32 v12, v16, v17
	v_add_co_u32_e32 v16, vcc, s39, v144
	v_pk_mul_f32 v[4:5], v[4:5], v[20:21] op_sel_hi:[1,0]
	v_cvt_pk_bf16_f32 v13, v18, v19
	v_cvt_pk_bf16_f32 v14, v24, v25
	v_cvt_pk_bf16_f32 v15, v26, v27
	v_addc_co_u32_e32 v17, vcc, 0, v145, vcc
	v_pk_mul_f32 v[10:11], v[10:11], v[20:21] op_sel_hi:[1,0]
	v_pk_mul_f32 v[8:9], v[8:9], v[20:21] op_sel_hi:[1,0]
	v_pk_mul_f32 v[6:7], v[6:7], v[20:21] op_sel_hi:[1,0]
	v_max_f32_e32 v4, 0, v4
	v_max_f32_e32 v5, 0, v5
	global_store_dwordx4 v[16:17], v[12:15], off
	v_max_f32_e32 v8, 0, v8
	v_max_f32_e32 v9, 0, v9
	v_pk_mul_f32 v[12:13], v[4:5], v[4:5]
	v_max_f32_e32 v4, 0, v10
	v_max_f32_e32 v6, 0, v6
	v_max_f32_e32 v5, 0, v11
	v_max_f32_e32 v7, 0, v7
	v_pk_mul_f32 v[8:9], v[8:9], v[8:9]
	v_pk_mul_f32 v[10:11], v[4:5], v[4:5]
	v_pk_mul_f32 v[14:15], v[6:7], v[6:7]
	v_cvt_pk_bf16_f32 v4, v8, v9
	v_cvt_pk_bf16_f32 v5, v10, v11
	v_cvt_pk_bf16_f32 v6, v12, v13
	v_cvt_pk_bf16_f32 v7, v14, v15
	s_andn2_b64 vcc, exec, s[40:41]
	s_mov_b64 s[40:41], -1
	global_store_dwordx4 v[22:23], v[4:7], off offset:256
	s_cbranch_vccnz .LBB0_1386
	s_andn2_b64 vcc, exec, s[4:5]
	s_cbranch_vccnz .LBB0_1396
	s_lshl_b32 s39, s61, 10
	s_lshl_b32 s40, s42, 8
	s_and_b32 s39, s39, 0x400
	s_ashr_i32 s41, s40, 31
	s_add_i32 m0, s60, s39
	v_lshl_add_u64 v[4:5], s[40:41], 2, v[138:139]
	global_load_lds_dword v[4:5], off

;     DI void operator()(const f32x4 (&acc)[2][2][4][2], const Unit& u, int wr, int wc, int fr, int fq, const LAS float* rsl) const {
;     ...
;         u32x4 xin[2][4][2];
;         if (!XF32 && u.ks < 0) {
; #pragma unroll
;             for (int ai = 0; ai < 2; ++ai)
; #pragma unroll
;                 for (int m = 0; m < 4; ++m)
; #pragma unroll
;                     for (int bj = 0; bj < 2; ++bj) xin[ai][m][bj] = *(const u32x4*)(act + (size_t)(row0 + ai * HALF + m * 16) * DM + col0 + bj * HALF);
;         }
.LBB0_1473:
	s_cmp_gt_i32 s12, -1
	v_lshl_add_u32 v216, s78, 8, v1
	v_lshl_or_b32 v214, s27, 8, v230
	s_cselect_b64 s[52:53], -1, 0
	v_ashrrev_i32_e32 v215, 31, v214
	s_and_b64 vcc, exec, s[52:53]
	v_ashrrev_i32_e32 v217, 31, v216
	s_cbranch_vccnz .LBB0_1475
	v_or_b32_e32 v88, 16, v216
	v_ashrrev_i32_e32 v89, 31, v88
	v_lshl_add_u64 v[84:85], v[214:215], 1, s[18:19]
	v_lshlrev_b64 v[86:87], 12, v[216:217]
	v_lshlrev_b64 v[88:89], 12, v[88:89]
	v_lshl_add_u64 v[86:87], v[84:85], 0, v[86:87]
	v_lshl_add_u64 v[88:89], v[84:85], 0, v[88:89]
	global_load_dwordx4 v[192:195], v[86:87], off
	global_load_dwordx4 v[188:191], v[86:87], off offset:256
	global_load_dwordx4 v[184:187], v[88:89], off
	global_load_dwordx4 v[180:183], v[88:89], off offset:256
	v_or_b32_e32 v88, 32, v216
	v_ashrrev_i32_e32 v89, 31, v88
	v_lshlrev_b64 v[88:89], 12, v[88:89]
	v_lshl_add_u64 v[88:89], v[84:85], 0, v[88:89]
	global_load_dwordx4 v[176:179], v[88:89], off
	global_load_dwordx4 v[172:175], v[88:89], off offset:256
	v_or_b32_e32 v88, 48, v216
	v_ashrrev_i32_e32 v89, 31, v88
	v_lshlrev_b64 v[88:89], 12, v[88:89]
	v_lshl_add_u64 v[84:85], v[84:85], 0, v[88:89]
	s_mov_b64 s[42:43], 0x80000
	v_add_co_u32_e32 v88, vcc, s77, v86
	global_load_dwordx4 v[168:171], v[84:85], off
	global_load_dwordx4 v[164:167], v[84:85], off offset:256
	v_lshl_add_u64 v[84:85], v[86:87], 0, s[42:43]
	v_addc_co_u32_e32 v89, vcc, 0, v87, vcc
	s_mov_b64 s[42:43], 0x90000
	global_load_dwordx4 v[160:163], v[88:89], off
	global_load_dwordx4 v[148:151], v[84:85], off offset:256
	v_lshl_add_u64 v[84:85], v[86:87], 0, s[42:43]
	s_mov_b32 s42, 0x90000
	v_add_co_u32_e32 v88, vcc, s42, v86
	s_mov_b64 s[42:43], 0xa0000
	s_nop 0
	v_addc_co_u32_e32 v89, vcc, 0, v87, vcc
	global_load_dwordx4 v[136:139], v[88:89], off
	global_load_dwordx4 v[124:127], v[84:85], off offset:256
	v_lshl_add_u64 v[84:85], v[86:87], 0, s[42:43]
	s_mov_b32 s42, 0xa0000
	v_add_co_u32_e32 v88, vcc, s42, v86
	s_mov_b64 s[42:43], 0xb0000
	s_nop 0
	v_addc_co_u32_e32 v89, vcc, 0, v87, vcc
	global_load_dwordx4 v[112:115], v[88:89], off
	global_load_dwordx4 v[104:107], v[84:85], off offset:256
	v_lshl_add_u64 v[84:85], v[86:87], 0, s[42:43]
	s_mov_b32 s42, 0xb0000
	v_add_co_u32_e32 v86, vcc, s42, v86
	s_nop 1
	v_addc_co_u32_e32 v87, vcc, 0, v87, vcc
	global_load_dwordx4 v[88:91], v[86:87], off
	s_nop 0
	global_load_dwordx4 v[84:87], v[84:85], off offset:256

; DI u32x4 pack8(const f32x4 v0, const f32x4 v1) { u32x4 w; w.x = pk2(v0[0], v0[1]); w.y = pk2(v0[2], v0[3]); w.z = pk2(v1[0], v1[1]); w.w = pk2(v1[2], v1[3]); return w; }
; DI void unpack8(const u32x4 w, f32x4& v0, f32x4& v1) { v0 = (f32x4){bflo(w.x), bfhi(w.x), bflo(w.y), bfhi(w.y)}; v1 = (f32x4){bflo(w.z), bfhi(w.z), bflo(w.w), bfhi(w.w)}; }
;     DI void operator()(const f32x4 (&acc)[2][2][4][2], const Unit& u, int wr, int wc, int fr, int fq, const LAS float* rsl) const {
;     ...
;         for (int ai = 0; ai < 2; ++ai)
; #pragma unroll
;             for (int m = 0; m < 4; ++m) {
;                 const int row = row0 + ai * HALF + m * 16;
;                 if (u.ks < 0) {
;                     const size_t off = (size_t)row * DM + col0; float sq = 0.f;
; #pragma unroll
;                     for (int bj = 0; bj < 2; ++bj) {
;                         f32x4 x0, x1;
;                         if (XF32) { x0 = *(const f32x4*)(Xin + off + bj * HALF); x1 = *(const f32x4*)(Xin + off + bj * HALF + 4); }
;                         else unpack8(xin[ai][m][bj], x0, x1);
;                         x0 += acc[ai][bj][m][0]; x1 += acc[ai][bj][m][1];
;                         *(u32x4*)(act + off + bj * HALF) = pack8(x0, x1);
;                         sq += (x0[0] * x0[0] + x0[1] * x0[1]) + (x0[2] * x0[2] + x0[3] * x0[3]) + (x1[0] * x1[0] + x1[1] * x1[1]) + (x1[2] * x1[2] + x1[3] * x1[3]);
;                     }
;                     sq += __shfl_xor(sq, 16); sq += __shfl_xor(sq, 32);
;                     if (fq == 0) ssq[(size_t)row * 32 + u.pn * 4 + wc] = sq;
.LBB0_1493:
	s_waitcnt vmcnt(0) lgkmcnt(0)
	v_lshlrev_b32_e32 v234, 16, v192
	v_and_b32_e32 v235, 0xffff0000, v192
	v_lshlrev_b32_e32 v192, 16, v193
	v_and_b32_e32 v193, 0xffff0000, v193
	v_lshlrev_b32_e32 v236, 16, v194
	v_and_b32_e32 v237, 0xffff0000, v194
	v_lshlrev_b32_e32 v194, 16, v195
	v_and_b32_e32 v195, 0xffff0000, v195
	v_pk_add_f32 v[156:157], v[156:157], v[234:235]
	v_pk_add_f32 v[158:159], v[158:159], v[192:193]
	v_pk_add_f32 v[192:193], v[154:155], v[194:195]
	v_pk_add_f32 v[194:195], v[152:153], v[236:237]
	v_cvt_pk_bf16_f32 v152, v156, v157
	v_mul_f32_e32 v157, v157, v157
	v_fmac_f32_e32 v157, v156, v156
	v_mul_f32_e32 v156, v159, v159
	v_fmac_f32_e32 v156, v158, v158
	v_add_f32_e32 v156, v157, v156
	v_mul_f32_e32 v157, v195, v195
	v_fmac_f32_e32 v157, v194, v194
	v_add_f32_e32 v156, v157, v156
	v_mul_f32_e32 v157, v193, v193
	v_fmac_f32_e32 v157, v192, v192
	v_cvt_pk_bf16_f32 v153, v158, v159
	v_cvt_pk_bf16_f32 v155, v192, v193
	v_add_f32_e32 v192, v157, v156
	v_lshlrev_b32_e32 v156, 16, v188
	v_and_b32_e32 v157, 0xffff0000, v188
	v_lshlrev_b32_e32 v158, 16, v189
	v_and_b32_e32 v159, 0xffff0000, v189
	v_lshlrev_b32_e32 v188, 16, v190
	v_and_b32_e32 v189, 0xffff0000, v190
	v_pk_add_f32 v[146:147], v[146:147], v[158:159]
	v_pk_add_f32 v[144:145], v[144:145], v[156:157]
	v_pk_add_f32 v[158:159], v[140:141], v[188:189]
	v_mul_f32_e32 v140, v145, v145
	v_mul_f32_e32 v141, v147, v147
	v_fmac_f32_e32 v140, v144, v144
	v_fmac_f32_e32 v141, v146, v146
	v_lshlrev_b32_e32 v190, 16, v191
	v_and_b32_e32 v191, 0xffff0000, v191
	v_add_f32_e32 v140, v140, v141
	v_mul_f32_e32 v141, v159, v159
	v_pk_add_f32 v[156:157], v[142:143], v[190:191]
	v_fmac_f32_e32 v141, v158, v158
	v_add_f32_e32 v140, v141, v140
	v_mul_f32_e32 v141, v157, v157
	v_fmac_f32_e32 v141, v156, v156
	v_add_f32_e32 v140, v141, v140
	v_and_b32_e32 v141, 64, v223
	v_add_f32_e32 v143, v140, v192
	v_xor_b32_e32 v140, 16, v223
	v_add_u32_e32 v190, 64, v141
	v_cmp_lt_i32_e32 vcc, v140, v190
	v_lshlrev_b64 v[232:233], 12, v[216:217]
	v_cvt_pk_bf16_f32 v154, v194, v195
	v_cndmask_b32_e32 v140, v223, v140, vcc
	v_lshlrev_b32_e32 v140, 2, v140
	ds_bpermute_b32 v191, v140, v143
	v_lshl_add_u64 v[140:141], s[18:19], 0, v[232:233]
	v_lshl_add_u64 v[188:189], v[214:215], 1, v[140:141]
	v_xor_b32_e32 v141, 32, v223
	v_cmp_lt_i32_e32 vcc, v141, v190
	s_waitcnt lgkmcnt(0)
	v_add_f32_e32 v140, v143, v191
	v_cvt_pk_bf16_f32 v142, v144, v145
	v_cndmask_b32_e32 v141, v223, v141, vcc
	v_lshlrev_b32_e32 v141, 2, v141
	ds_bpermute_b32 v141, v141, v140
	v_cvt_pk_bf16_f32 v143, v146, v147
	v_cvt_pk_bf16_f32 v144, v158, v159
	v_cvt_pk_bf16_f32 v145, v156, v157
	global_store_dwordx4 v[188:189], v[152:155], off
	global_store_dwordx4 v[188:189], v[142:145], off offset:256
	s_and_saveexec_b64 s[52:53], s[40:41]
	s_cbranch_execz .LBB0_1495
	s_waitcnt lgkmcnt(0)
	v_add_f32_e32 v142, v140, v141
	s_lshl_b32 s54, s27, 2
	v_lshlrev_b64 v[140:141], 7, v[216:217]
	s_ashr_i32 s55, s54, 31
	v_lshl_add_u64 v[140:141], s[34:35], 0, v[140:141]
	v_lshl_add_u64 v[140:141], s[54:55], 2, v[140:141]
	s_lshl_b32 s54, s67, 2
	s_mov_b32 s55, s13
	v_lshl_add_u64 v[140:141], v[140:141], 0, s[54:55]
	global_store_dword v[140:141], v142, off

; DI u32x4 pack8(const f32x4 v0, const f32x4 v1) { u32x4 w; w.x = pk2(v0[0], v0[1]); w.y = pk2(v0[2], v0[3]); w.z = pk2(v1[0], v1[1]); w.w = pk2(v1[2], v1[3]); return w; }
; DI void unpack8(const u32x4 w, f32x4& v0, f32x4& v1) { v0 = (f32x4){bflo(w.x), bfhi(w.x), bflo(w.y), bfhi(w.y)}; v1 = (f32x4){bflo(w.z), bfhi(w.z), bflo(w.w), bfhi(w.w)}; }
;     DI void operator()(const f32x4 (&acc)[2][2][4][2], const Unit& u, int wr, int wc, int fr, int fq, const LAS float* rsl) const {
;     ...
;         for (int ai = 0; ai < 2; ++ai)
; #pragma unroll
;             for (int m = 0; m < 4; ++m) {
;                 const int row = row0 + ai * HALF + m * 16;
;                 if (u.ks < 0) {
;                     const size_t off = (size_t)row * DM + col0; float sq = 0.f;
; #pragma unroll
;                     for (int bj = 0; bj < 2; ++bj) {
;                         f32x4 x0, x1;
;                         if (XF32) { x0 = *(const f32x4*)(Xin + off + bj * HALF); x1 = *(const f32x4*)(Xin + off + bj * HALF + 4); }
;                         else unpack8(xin[ai][m][bj], x0, x1);
;                         x0 += acc[ai][bj][m][0]; x1 += acc[ai][bj][m][1];
;                         *(u32x4*)(act + off + bj * HALF) = pack8(x0, x1);
;                         sq += (x0[0] * x0[0] + x0[1] * x0[1]) + (x0[2] * x0[2] + x0[3] * x0[3]) + (x1[0] * x1[0] + x1[1] * x1[1]) + (x1[2] * x1[2] + x1[3] * x1[3]);
;                     }
;                     sq += __shfl_xor(sq, 16); sq += __shfl_xor(sq, 32);
;                     if (fq == 0) ssq[(size_t)row * 32 + u.pn * 4 + wc] = sq;
.LBB0_1497:
	s_waitcnt vmcnt(0) lgkmcnt(0)
	v_lshlrev_b32_e32 v144, 16, v184
	v_and_b32_e32 v145, 0xffff0000, v184
	v_lshlrev_b32_e32 v146, 16, v185
	v_and_b32_e32 v147, 0xffff0000, v185
	v_lshlrev_b32_e32 v152, 16, v186
	v_and_b32_e32 v153, 0xffff0000, v186
	v_pk_add_f32 v[132:133], v[132:133], v[144:145]
	v_pk_add_f32 v[134:135], v[134:135], v[146:147]
	v_pk_add_f32 v[146:147], v[128:129], v[152:153]
	v_cvt_pk_bf16_f32 v128, v132, v133
	v_mul_f32_e32 v133, v133, v133
	v_fmac_f32_e32 v133, v132, v132
	v_mul_f32_e32 v132, v135, v135
	v_fmac_f32_e32 v132, v134, v134
	v_lshlrev_b32_e32 v154, 16, v187
	v_and_b32_e32 v155, 0xffff0000, v187
	v_add_f32_e32 v132, v133, v132
	v_mul_f32_e32 v133, v147, v147
	v_pk_add_f32 v[144:145], v[130:131], v[154:155]
	v_fmac_f32_e32 v133, v146, v146
	v_add_f32_e32 v132, v133, v132
	v_mul_f32_e32 v133, v145, v145
	v_fmac_f32_e32 v133, v144, v144
	v_cvt_pk_bf16_f32 v129, v134, v135
	v_add_f32_e32 v152, v133, v132
	v_lshlrev_b32_e32 v132, 16, v180
	v_and_b32_e32 v133, 0xffff0000, v180
	v_lshlrev_b32_e32 v134, 16, v181
	v_and_b32_e32 v135, 0xffff0000, v181
	v_cvt_pk_bf16_f32 v131, v144, v145
	v_lshlrev_b32_e32 v144, 16, v182
	v_and_b32_e32 v145, 0xffff0000, v182
	v_pk_add_f32 v[122:123], v[122:123], v[134:135]
	v_pk_add_f32 v[120:121], v[120:121], v[132:133]
	v_pk_add_f32 v[134:135], v[116:117], v[144:145]
	v_mul_f32_e32 v116, v121, v121
	v_mul_f32_e32 v117, v123, v123
	v_fmac_f32_e32 v116, v120, v120
	v_fmac_f32_e32 v117, v122, v122
	v_cvt_pk_bf16_f32 v130, v146, v147
	v_lshlrev_b32_e32 v146, 16, v183
	v_and_b32_e32 v147, 0xffff0000, v183
	v_add_f32_e32 v116, v116, v117
	v_mul_f32_e32 v117, v135, v135
	v_pk_add_f32 v[132:133], v[118:119], v[146:147]
	v_fmac_f32_e32 v117, v134, v134
	v_add_f32_e32 v116, v117, v116
	v_mul_f32_e32 v117, v133, v133
	v_fmac_f32_e32 v117, v132, v132
	v_add_f32_e32 v116, v117, v116
	v_and_b32_e32 v117, 64, v223
	v_add_f32_e32 v119, v116, v152
	v_xor_b32_e32 v116, 16, v223
	v_add_u32_e32 v144, 64, v117
	v_cmp_lt_i32_e32 vcc, v116, v144
	v_or_b32_e32 v140, 16, v216
	v_ashrrev_i32_e32 v141, 31, v140
	v_cndmask_b32_e32 v116, v223, v116, vcc
	v_lshlrev_b32_e32 v116, 2, v116
	v_lshlrev_b64 v[142:143], 12, v[140:141]
	ds_bpermute_b32 v145, v116, v119
	v_lshl_add_u64 v[116:117], s[18:19], 0, v[142:143]
	v_lshl_add_u64 v[142:143], v[214:215], 1, v[116:117]
	v_xor_b32_e32 v117, 32, v223
	v_cmp_lt_i32_e32 vcc, v117, v144
	s_waitcnt lgkmcnt(0)
	v_add_f32_e32 v116, v119, v145
	v_cvt_pk_bf16_f32 v118, v120, v121
	v_cndmask_b32_e32 v117, v223, v117, vcc
	v_lshlrev_b32_e32 v117, 2, v117
	ds_bpermute_b32 v117, v117, v116
	v_cvt_pk_bf16_f32 v119, v122, v123
	v_cvt_pk_bf16_f32 v120, v134, v135
	v_cvt_pk_bf16_f32 v121, v132, v133
	global_store_dwordx4 v[142:143], v[128:131], off
	global_store_dwordx4 v[142:143], v[118:121], off offset:256
	s_and_saveexec_b64 s[52:53], s[40:41]
	s_cbranch_execz .LBB0_1499
	s_waitcnt lgkmcnt(0)
	v_add_f32_e32 v118, v116, v117
	s_lshl_b32 s54, s27, 2
	v_lshlrev_b64 v[116:117], 7, v[140:141]
	s_ashr_i32 s55, s54, 31
	v_lshl_add_u64 v[116:117], s[34:35], 0, v[116:117]
	v_lshl_add_u64 v[116:117], s[54:55], 2, v[116:117]
	s_lshl_b32 s54, s67, 2
	s_mov_b32 s55, s13
	v_lshl_add_u64 v[116:117], v[116:117], 0, s[54:55]
	global_store_dword v[116:117], v118, off

; DI u32x4 pack8(const f32x4 v0, const f32x4 v1) { u32x4 w; w.x = pk2(v0[0], v0[1]); w.y = pk2(v0[2], v0[3]); w.z = pk2(v1[0], v1[1]); w.w = pk2(v1[2], v1[3]); return w; }
; DI void unpack8(const u32x4 w, f32x4& v0, f32x4& v1) { v0 = (f32x4){bflo(w.x), bfhi(w.x), bflo(w.y), bfhi(w.y)}; v1 = (f32x4){bflo(w.z), bfhi(w.z), bflo(w.w), bfhi(w.w)}; }
;     DI void operator()(const f32x4 (&acc)[2][2][4][2], const Unit& u, int wr, int wc, int fr, int fq, const LAS float* rsl) const {
;     ...
;         for (int ai = 0; ai < 2; ++ai)
; #pragma unroll
;             for (int m = 0; m < 4; ++m) {
;                 const int row = row0 + ai * HALF + m * 16;
;                 if (u.ks < 0) {
;                     const size_t off = (size_t)row * DM + col0; float sq = 0.f;
; #pragma unroll
;                     for (int bj = 0; bj < 2; ++bj) {
;                         f32x4 x0, x1;
;                         if (XF32) { x0 = *(const f32x4*)(Xin + off + bj * HALF); x1 = *(const f32x4*)(Xin + off + bj * HALF + 4); }
;                         else unpack8(xin[ai][m][bj], x0, x1);
;                         x0 += acc[ai][bj][m][0]; x1 += acc[ai][bj][m][1];
;                         *(u32x4*)(act + off + bj * HALF) = pack8(x0, x1);
;                         sq += (x0[0] * x0[0] + x0[1] * x0[1]) + (x0[2] * x0[2] + x0[3] * x0[3]) + (x1[0] * x1[0] + x1[1] * x1[1]) + (x1[2] * x1[2] + x1[3] * x1[3]);
;                     }
;                     sq += __shfl_xor(sq, 16); sq += __shfl_xor(sq, 32);
;                     if (fq == 0) ssq[(size_t)row * 32 + u.pn * 4 + wc] = sq;
.LBB0_1501:
	s_waitcnt vmcnt(0) lgkmcnt(0)
	v_lshlrev_b32_e32 v120, 16, v176
	v_and_b32_e32 v121, 0xffff0000, v176
	v_lshlrev_b32_e32 v122, 16, v177
	v_and_b32_e32 v123, 0xffff0000, v177
	v_lshlrev_b32_e32 v128, 16, v178
	v_and_b32_e32 v129, 0xffff0000, v178
	v_pk_add_f32 v[108:109], v[108:109], v[120:121]
	v_pk_add_f32 v[110:111], v[110:111], v[122:123]
	v_pk_add_f32 v[122:123], v[100:101], v[128:129]
	v_cvt_pk_bf16_f32 v100, v108, v109
	v_mul_f32_e32 v109, v109, v109
	v_fmac_f32_e32 v109, v108, v108
	v_mul_f32_e32 v108, v111, v111
	v_fmac_f32_e32 v108, v110, v110
	v_lshlrev_b32_e32 v130, 16, v179
	v_and_b32_e32 v131, 0xffff0000, v179
	v_add_f32_e32 v108, v109, v108
	v_mul_f32_e32 v109, v123, v123
	v_pk_add_f32 v[120:121], v[102:103], v[130:131]
	v_fmac_f32_e32 v109, v122, v122
	v_add_f32_e32 v108, v109, v108
	v_mul_f32_e32 v109, v121, v121
	v_fmac_f32_e32 v109, v120, v120
	v_cvt_pk_bf16_f32 v101, v110, v111
	v_add_f32_e32 v128, v109, v108
	v_lshlrev_b32_e32 v108, 16, v172
	v_and_b32_e32 v109, 0xffff0000, v172
	v_lshlrev_b32_e32 v110, 16, v173
	v_and_b32_e32 v111, 0xffff0000, v173
	v_cvt_pk_bf16_f32 v103, v120, v121
	v_lshlrev_b32_e32 v120, 16, v174
	v_and_b32_e32 v121, 0xffff0000, v174
	v_pk_add_f32 v[98:99], v[98:99], v[110:111]
	v_pk_add_f32 v[96:97], v[96:97], v[108:109]
	v_pk_add_f32 v[110:111], v[92:93], v[120:121]
	v_mul_f32_e32 v92, v97, v97
	v_mul_f32_e32 v93, v99, v99
	v_fmac_f32_e32 v92, v96, v96
	v_fmac_f32_e32 v93, v98, v98
	v_cvt_pk_bf16_f32 v102, v122, v123
	v_lshlrev_b32_e32 v122, 16, v175
	v_and_b32_e32 v123, 0xffff0000, v175
	v_add_f32_e32 v92, v92, v93
	v_mul_f32_e32 v93, v111, v111
	v_pk_add_f32 v[108:109], v[94:95], v[122:123]
	v_fmac_f32_e32 v93, v110, v110
	v_add_f32_e32 v92, v93, v92
	v_mul_f32_e32 v93, v109, v109
	v_fmac_f32_e32 v93, v108, v108
	v_add_f32_e32 v92, v93, v92
	v_and_b32_e32 v93, 64, v223
	v_add_f32_e32 v95, v92, v128
	v_xor_b32_e32 v92, 16, v223
	v_add_u32_e32 v120, 64, v93
	v_cmp_lt_i32_e32 vcc, v92, v120
	v_or_b32_e32 v116, 32, v216
	v_ashrrev_i32_e32 v117, 31, v116
	v_cndmask_b32_e32 v92, v223, v92, vcc
	v_lshlrev_b32_e32 v92, 2, v92
	v_lshlrev_b64 v[118:119], 12, v[116:117]
	ds_bpermute_b32 v121, v92, v95
	v_lshl_add_u64 v[92:93], s[18:19], 0, v[118:119]
	v_lshl_add_u64 v[118:119], v[214:215], 1, v[92:93]
	v_xor_b32_e32 v93, 32, v223
	v_cmp_lt_i32_e32 vcc, v93, v120
	s_waitcnt lgkmcnt(0)
	v_add_f32_e32 v92, v95, v121
	v_cvt_pk_bf16_f32 v94, v96, v97
	v_cndmask_b32_e32 v93, v223, v93, vcc
	v_lshlrev_b32_e32 v93, 2, v93
	ds_bpermute_b32 v93, v93, v92
	v_cvt_pk_bf16_f32 v95, v98, v99
	v_cvt_pk_bf16_f32 v96, v110, v111
	v_cvt_pk_bf16_f32 v97, v108, v109
	global_store_dwordx4 v[118:119], v[100:103], off
	global_store_dwordx4 v[118:119], v[94:97], off offset:256
	s_and_saveexec_b64 s[52:53], s[40:41]
	s_cbranch_execz .LBB0_1503
	s_waitcnt lgkmcnt(0)
	v_add_f32_e32 v94, v92, v93
	s_lshl_b32 s54, s27, 2
	v_lshlrev_b64 v[92:93], 7, v[116:117]
	s_ashr_i32 s55, s54, 31
	v_lshl_add_u64 v[92:93], s[34:35], 0, v[92:93]
	v_lshl_add_u64 v[92:93], s[54:55], 2, v[92:93]
	s_lshl_b32 s54, s67, 2
	s_mov_b32 s55, s13
	v_lshl_add_u64 v[92:93], v[92:93], 0, s[54:55]
	global_store_dword v[92:93], v94, off

; DI u32x4 pack8(const f32x4 v0, const f32x4 v1) { u32x4 w; w.x = pk2(v0[0], v0[1]); w.y = pk2(v0[2], v0[3]); w.z = pk2(v1[0], v1[1]); w.w = pk2(v1[2], v1[3]); return w; }
; DI void unpack8(const u32x4 w, f32x4& v0, f32x4& v1) { v0 = (f32x4){bflo(w.x), bfhi(w.x), bflo(w.y), bfhi(w.y)}; v1 = (f32x4){bflo(w.z), bfhi(w.z), bflo(w.w), bfhi(w.w)}; }
;     DI void operator()(const f32x4 (&acc)[2][2][4][2], const Unit& u, int wr, int wc, int fr, int fq, const LAS float* rsl) const {
;     ...
;         for (int ai = 0; ai < 2; ++ai)
; #pragma unroll
;             for (int m = 0; m < 4; ++m) {
;                 const int row = row0 + ai * HALF + m * 16;
;                 if (u.ks < 0) {
;                     const size_t off = (size_t)row * DM + col0; float sq = 0.f;
; #pragma unroll
;                     for (int bj = 0; bj < 2; ++bj) {
;                         f32x4 x0, x1;
;                         if (XF32) { x0 = *(const f32x4*)(Xin + off + bj * HALF); x1 = *(const f32x4*)(Xin + off + bj * HALF + 4); }
;                         else unpack8(xin[ai][m][bj], x0, x1);
;                         x0 += acc[ai][bj][m][0]; x1 += acc[ai][bj][m][1];
;                         *(u32x4*)(act + off + bj * HALF) = pack8(x0, x1);
;                         sq += (x0[0] * x0[0] + x0[1] * x0[1]) + (x0[2] * x0[2] + x0[3] * x0[3]) + (x1[0] * x1[0] + x1[1] * x1[1]) + (x1[2] * x1[2] + x1[3] * x1[3]);
;                     }
;                     sq += __shfl_xor(sq, 16); sq += __shfl_xor(sq, 32);
;                     if (fq == 0) ssq[(size_t)row * 32 + u.pn * 4 + wc] = sq;
.LBB0_1505:
	s_waitcnt vmcnt(0) lgkmcnt(0)
	v_lshlrev_b32_e32 v96, 16, v168
	v_and_b32_e32 v97, 0xffff0000, v168
	v_lshlrev_b32_e32 v98, 16, v169
	v_and_b32_e32 v99, 0xffff0000, v169
	v_lshlrev_b32_e32 v100, 16, v170
	v_and_b32_e32 v101, 0xffff0000, v170
	v_pk_add_f32 v[80:81], v[80:81], v[96:97]
	v_pk_add_f32 v[82:83], v[82:83], v[98:99]
	v_pk_add_f32 v[98:99], v[76:77], v[100:101]
	v_cvt_pk_bf16_f32 v76, v80, v81
	v_mul_f32_e32 v81, v81, v81
	v_fmac_f32_e32 v81, v80, v80
	v_mul_f32_e32 v80, v83, v83
	v_fmac_f32_e32 v80, v82, v82
	v_lshlrev_b32_e32 v102, 16, v171
	v_and_b32_e32 v103, 0xffff0000, v171
	v_add_f32_e32 v80, v81, v80
	v_mul_f32_e32 v81, v99, v99
	v_pk_add_f32 v[96:97], v[78:79], v[102:103]
	v_fmac_f32_e32 v81, v98, v98
	v_add_f32_e32 v80, v81, v80
	v_mul_f32_e32 v81, v97, v97
	v_fmac_f32_e32 v81, v96, v96
	v_cvt_pk_bf16_f32 v77, v82, v83
	v_add_f32_e32 v100, v81, v80
	v_lshlrev_b32_e32 v80, 16, v164
	v_and_b32_e32 v81, 0xffff0000, v164
	v_lshlrev_b32_e32 v82, 16, v165
	v_and_b32_e32 v83, 0xffff0000, v165
	v_cvt_pk_bf16_f32 v79, v96, v97
	v_lshlrev_b32_e32 v96, 16, v166
	v_and_b32_e32 v97, 0xffff0000, v166
	v_pk_add_f32 v[74:75], v[74:75], v[82:83]
	v_pk_add_f32 v[72:73], v[72:73], v[80:81]
	v_pk_add_f32 v[82:83], v[68:69], v[96:97]
	v_mul_f32_e32 v68, v73, v73
	v_mul_f32_e32 v69, v75, v75
	v_fmac_f32_e32 v68, v72, v72
	v_fmac_f32_e32 v69, v74, v74
	v_cvt_pk_bf16_f32 v78, v98, v99
	v_lshlrev_b32_e32 v98, 16, v167
	v_and_b32_e32 v99, 0xffff0000, v167
	v_add_f32_e32 v68, v68, v69
	v_mul_f32_e32 v69, v83, v83
	v_pk_add_f32 v[80:81], v[70:71], v[98:99]
	v_fmac_f32_e32 v69, v82, v82
	v_add_f32_e32 v68, v69, v68
	v_mul_f32_e32 v69, v81, v81
	v_fmac_f32_e32 v69, v80, v80
	v_add_f32_e32 v68, v69, v68
	v_and_b32_e32 v69, 64, v223
	v_add_f32_e32 v71, v68, v100
	v_xor_b32_e32 v68, 16, v223
	v_add_u32_e32 v96, 64, v69
	v_cmp_lt_i32_e32 vcc, v68, v96
	v_or_b32_e32 v92, 48, v216
	v_ashrrev_i32_e32 v93, 31, v92
	v_cndmask_b32_e32 v68, v223, v68, vcc
	v_lshlrev_b32_e32 v68, 2, v68
	v_lshlrev_b64 v[94:95], 12, v[92:93]
	ds_bpermute_b32 v97, v68, v71
	v_lshl_add_u64 v[68:69], s[18:19], 0, v[94:95]
	v_lshl_add_u64 v[94:95], v[214:215], 1, v[68:69]
	v_xor_b32_e32 v69, 32, v223
	v_cmp_lt_i32_e32 vcc, v69, v96
	s_waitcnt lgkmcnt(0)
	v_add_f32_e32 v68, v71, v97
	v_cvt_pk_bf16_f32 v70, v72, v73
	v_cndmask_b32_e32 v69, v223, v69, vcc
	v_lshlrev_b32_e32 v69, 2, v69
	ds_bpermute_b32 v69, v69, v68
	v_cvt_pk_bf16_f32 v71, v74, v75
	v_cvt_pk_bf16_f32 v72, v82, v83
	v_cvt_pk_bf16_f32 v73, v80, v81
	global_store_dwordx4 v[94:95], v[76:79], off
	global_store_dwordx4 v[94:95], v[70:73], off offset:256
	s_and_saveexec_b64 s[52:53], s[40:41]
	s_cbranch_execz .LBB0_1507
	s_waitcnt lgkmcnt(0)
	v_add_f32_e32 v70, v68, v69
	s_lshl_b32 s54, s27, 2
	v_lshlrev_b64 v[68:69], 7, v[92:93]
	s_ashr_i32 s55, s54, 31
	v_lshl_add_u64 v[68:69], s[34:35], 0, v[68:69]
	v_lshl_add_u64 v[68:69], s[54:55], 2, v[68:69]
	s_lshl_b32 s54, s67, 2
	s_mov_b32 s55, s13
	v_lshl_add_u64 v[68:69], v[68:69], 0, s[54:55]
	global_store_dword v[68:69], v70, off

; DI u32x4 pack8(const f32x4 v0, const f32x4 v1) { u32x4 w; w.x = pk2(v0[0], v0[1]); w.y = pk2(v0[2], v0[3]); w.z = pk2(v1[0], v1[1]); w.w = pk2(v1[2], v1[3]); return w; }
; DI void unpack8(const u32x4 w, f32x4& v0, f32x4& v1) { v0 = (f32x4){bflo(w.x), bfhi(w.x), bflo(w.y), bfhi(w.y)}; v1 = (f32x4){bflo(w.z), bfhi(w.z), bflo(w.w), bfhi(w.w)}; }
;     DI void operator()(const f32x4 (&acc)[2][2][4][2], const Unit& u, int wr, int wc, int fr, int fq, const LAS float* rsl) const {
;     ...
; #pragma unroll
;         for (int ai = 0; ai < 2; ++ai)
; #pragma unroll
;             for (int m = 0; m < 4; ++m) {
;                 const int row = row0 + ai * HALF + m * 16;
;                 if (u.ks < 0) {
;                     const size_t off = (size_t)row * DM + col0; float sq = 0.f;
; #pragma unroll
;                     for (int bj = 0; bj < 2; ++bj) {
;                         f32x4 x0, x1;
;                         if (XF32) { x0 = *(const f32x4*)(Xin + off + bj * HALF); x1 = *(const f32x4*)(Xin + off + bj * HALF + 4); }
;                         else unpack8(xin[ai][m][bj], x0, x1);
;                         x0 += acc[ai][bj][m][0]; x1 += acc[ai][bj][m][1];
;                         *(u32x4*)(act + off + bj * HALF) = pack8(x0, x1);
;                         sq += (x0[0] * x0[0] + x0[1] * x0[1]) + (x0[2] * x0[2] + x0[3] * x0[3]) + (x1[0] * x1[0] + x1[1] * x1[1]) + (x1[2] * x1[2] + x1[3] * x1[3]);
;                     }
;                     sq += __shfl_xor(sq, 16); sq += __shfl_xor(sq, 32);
;                     if (fq == 0) ssq[(size_t)row * 32 + u.pn * 4 + wc] = sq;
.LBB0_1509:
	s_waitcnt vmcnt(0) lgkmcnt(0)
	v_lshlrev_b32_e32 v72, 16, v160
	v_and_b32_e32 v73, 0xffff0000, v160
	v_lshlrev_b32_e32 v74, 16, v161
	v_and_b32_e32 v75, 0xffff0000, v161
	v_lshlrev_b32_e32 v76, 16, v162
	v_and_b32_e32 v77, 0xffff0000, v162
	v_pk_add_f32 v[64:65], v[64:65], v[72:73]
	v_pk_add_f32 v[66:67], v[66:67], v[74:75]
	v_pk_add_f32 v[74:75], v[60:61], v[76:77]
	v_cvt_pk_bf16_f32 v60, v64, v65
	v_mul_f32_e32 v65, v65, v65
	v_fmac_f32_e32 v65, v64, v64
	v_mul_f32_e32 v64, v67, v67
	v_fmac_f32_e32 v64, v66, v66
	v_lshlrev_b32_e32 v78, 16, v163
	v_and_b32_e32 v79, 0xffff0000, v163
	v_add_f32_e32 v64, v65, v64
	v_mul_f32_e32 v65, v75, v75
	v_pk_add_f32 v[72:73], v[62:63], v[78:79]
	v_fmac_f32_e32 v65, v74, v74
	v_add_f32_e32 v64, v65, v64
	v_mul_f32_e32 v65, v73, v73
	v_fmac_f32_e32 v65, v72, v72
	v_cvt_pk_bf16_f32 v61, v66, v67
	v_add_f32_e32 v76, v65, v64
	v_lshlrev_b32_e32 v64, 16, v148
	v_and_b32_e32 v65, 0xffff0000, v148
	v_lshlrev_b32_e32 v66, 16, v149
	v_and_b32_e32 v67, 0xffff0000, v149
	v_cvt_pk_bf16_f32 v63, v72, v73
	v_lshlrev_b32_e32 v72, 16, v150
	v_and_b32_e32 v73, 0xffff0000, v150
	v_pk_add_f32 v[58:59], v[58:59], v[66:67]
	v_pk_add_f32 v[56:57], v[56:57], v[64:65]
	v_pk_add_f32 v[66:67], v[52:53], v[72:73]
	v_mul_f32_e32 v52, v57, v57
	v_mul_f32_e32 v53, v59, v59
	v_fmac_f32_e32 v52, v56, v56
	v_fmac_f32_e32 v53, v58, v58
	v_cvt_pk_bf16_f32 v62, v74, v75
	v_lshlrev_b32_e32 v74, 16, v151
	v_and_b32_e32 v75, 0xffff0000, v151
	v_add_f32_e32 v52, v52, v53
	v_mul_f32_e32 v53, v67, v67
	v_pk_add_f32 v[64:65], v[54:55], v[74:75]
	v_fmac_f32_e32 v53, v66, v66
	v_add_f32_e32 v52, v53, v52
	v_mul_f32_e32 v53, v65, v65
	v_fmac_f32_e32 v53, v64, v64
	v_add_f32_e32 v52, v53, v52
	v_and_b32_e32 v53, 64, v223
	v_add_f32_e32 v55, v52, v76
	v_xor_b32_e32 v52, 16, v223
	v_add_u32_e32 v72, 64, v53
	v_cmp_lt_i32_e32 vcc, v52, v72
	v_add_u32_e32 v68, 0x80, v216
	v_ashrrev_i32_e32 v69, 31, v68
	v_cndmask_b32_e32 v52, v223, v52, vcc
	v_lshlrev_b32_e32 v52, 2, v52
	v_lshlrev_b64 v[70:71], 12, v[68:69]
	ds_bpermute_b32 v73, v52, v55
	v_lshl_add_u64 v[52:53], s[18:19], 0, v[70:71]
	v_lshl_add_u64 v[70:71], v[214:215], 1, v[52:53]
	v_xor_b32_e32 v53, 32, v223
	v_cmp_lt_i32_e32 vcc, v53, v72
	s_waitcnt lgkmcnt(0)
	v_add_f32_e32 v52, v55, v73
	v_cvt_pk_bf16_f32 v54, v56, v57
	v_cndmask_b32_e32 v53, v223, v53, vcc
	v_lshlrev_b32_e32 v53, 2, v53
	ds_bpermute_b32 v53, v53, v52
	v_cvt_pk_bf16_f32 v55, v58, v59
	v_cvt_pk_bf16_f32 v56, v66, v67
	v_cvt_pk_bf16_f32 v57, v64, v65
	global_store_dwordx4 v[70:71], v[60:63], off
	global_store_dwordx4 v[70:71], v[54:57], off offset:256
	s_and_saveexec_b64 s[52:53], s[40:41]
	s_cbranch_execz .LBB0_1511
	s_waitcnt lgkmcnt(0)
	v_add_f32_e32 v54, v52, v53
	s_lshl_b32 s54, s27, 2
	v_lshlrev_b64 v[52:53], 7, v[68:69]
	s_ashr_i32 s55, s54, 31
	v_lshl_add_u64 v[52:53], s[34:35], 0, v[52:53]
	v_lshl_add_u64 v[52:53], s[54:55], 2, v[52:53]
	s_lshl_b32 s54, s67, 2
	s_mov_b32 s55, s13
	v_lshl_add_u64 v[52:53], v[52:53], 0, s[54:55]
	global_store_dword v[52:53], v54, off

; DI u32x4 pack8(const f32x4 v0, const f32x4 v1) { u32x4 w; w.x = pk2(v0[0], v0[1]); w.y = pk2(v0[2], v0[3]); w.z = pk2(v1[0], v1[1]); w.w = pk2(v1[2], v1[3]); return w; }
; DI void unpack8(const u32x4 w, f32x4& v0, f32x4& v1) { v0 = (f32x4){bflo(w.x), bfhi(w.x), bflo(w.y), bfhi(w.y)}; v1 = (f32x4){bflo(w.z), bfhi(w.z), bflo(w.w), bfhi(w.w)}; }
;     DI void operator()(const f32x4 (&acc)[2][2][4][2], const Unit& u, int wr, int wc, int fr, int fq, const LAS float* rsl) const {
;     ...
; #pragma unroll
;         for (int ai = 0; ai < 2; ++ai)
; #pragma unroll
;             for (int m = 0; m < 4; ++m) {
;                 const int row = row0 + ai * HALF + m * 16;
;                 if (u.ks < 0) {
;                     const size_t off = (size_t)row * DM + col0; float sq = 0.f;
; #pragma unroll
;                     for (int bj = 0; bj < 2; ++bj) {
;                         f32x4 x0, x1;
;                         if (XF32) { x0 = *(const f32x4*)(Xin + off + bj * HALF); x1 = *(const f32x4*)(Xin + off + bj * HALF + 4); }
;                         else unpack8(xin[ai][m][bj], x0, x1);
;                         x0 += acc[ai][bj][m][0]; x1 += acc[ai][bj][m][1];
;                         *(u32x4*)(act + off + bj * HALF) = pack8(x0, x1);
;                         sq += (x0[0] * x0[0] + x0[1] * x0[1]) + (x0[2] * x0[2] + x0[3] * x0[3]) + (x1[0] * x1[0] + x1[1] * x1[1]) + (x1[2] * x1[2] + x1[3] * x1[3]);
;                     }
;                     sq += __shfl_xor(sq, 16); sq += __shfl_xor(sq, 32);
;                     if (fq == 0) ssq[(size_t)row * 32 + u.pn * 4 + wc] = sq;
.LBB0_1513:
	s_waitcnt vmcnt(0) lgkmcnt(0)
	v_lshlrev_b32_e32 v56, 16, v136
	v_and_b32_e32 v57, 0xffff0000, v136
	v_lshlrev_b32_e32 v58, 16, v137
	v_and_b32_e32 v59, 0xffff0000, v137
	v_lshlrev_b32_e32 v60, 16, v138
	v_and_b32_e32 v61, 0xffff0000, v138
	v_pk_add_f32 v[48:49], v[48:49], v[56:57]
	v_pk_add_f32 v[50:51], v[50:51], v[58:59]
	v_pk_add_f32 v[58:59], v[44:45], v[60:61]
	v_cvt_pk_bf16_f32 v44, v48, v49
	v_mul_f32_e32 v49, v49, v49
	v_fmac_f32_e32 v49, v48, v48
	v_mul_f32_e32 v48, v51, v51
	v_fmac_f32_e32 v48, v50, v50
	v_lshlrev_b32_e32 v62, 16, v139
	v_and_b32_e32 v63, 0xffff0000, v139
	v_add_f32_e32 v48, v49, v48
	v_mul_f32_e32 v49, v59, v59
	v_pk_add_f32 v[56:57], v[46:47], v[62:63]
	v_fmac_f32_e32 v49, v58, v58
	v_add_f32_e32 v48, v49, v48
	v_mul_f32_e32 v49, v57, v57
	v_fmac_f32_e32 v49, v56, v56
	v_cvt_pk_bf16_f32 v45, v50, v51
	v_add_f32_e32 v60, v49, v48
	v_lshlrev_b32_e32 v48, 16, v124
	v_and_b32_e32 v49, 0xffff0000, v124
	v_lshlrev_b32_e32 v50, 16, v125
	v_and_b32_e32 v51, 0xffff0000, v125
	v_cvt_pk_bf16_f32 v47, v56, v57
	v_lshlrev_b32_e32 v56, 16, v126
	v_and_b32_e32 v57, 0xffff0000, v126
	v_pk_add_f32 v[42:43], v[42:43], v[50:51]
	v_pk_add_f32 v[40:41], v[40:41], v[48:49]
	v_pk_add_f32 v[50:51], v[36:37], v[56:57]
	v_mul_f32_e32 v36, v41, v41
	v_mul_f32_e32 v37, v43, v43
	v_fmac_f32_e32 v36, v40, v40
	v_fmac_f32_e32 v37, v42, v42
	v_cvt_pk_bf16_f32 v46, v58, v59
	v_lshlrev_b32_e32 v58, 16, v127
	v_and_b32_e32 v59, 0xffff0000, v127
	v_add_f32_e32 v36, v36, v37
	v_mul_f32_e32 v37, v51, v51
	v_pk_add_f32 v[48:49], v[38:39], v[58:59]
	v_fmac_f32_e32 v37, v50, v50
	v_add_f32_e32 v36, v37, v36
	v_mul_f32_e32 v37, v49, v49
	v_fmac_f32_e32 v37, v48, v48
	v_add_f32_e32 v36, v37, v36
	v_and_b32_e32 v37, 64, v223
	v_add_f32_e32 v39, v36, v60
	v_xor_b32_e32 v36, 16, v223
	v_add_u32_e32 v56, 64, v37
	v_cmp_lt_i32_e32 vcc, v36, v56
	v_add_u32_e32 v52, 0x90, v216
	v_ashrrev_i32_e32 v53, 31, v52
	v_cndmask_b32_e32 v36, v223, v36, vcc
	v_lshlrev_b32_e32 v36, 2, v36
	v_lshlrev_b64 v[54:55], 12, v[52:53]
	ds_bpermute_b32 v57, v36, v39
	v_lshl_add_u64 v[36:37], s[18:19], 0, v[54:55]
	v_lshl_add_u64 v[54:55], v[214:215], 1, v[36:37]
	v_xor_b32_e32 v37, 32, v223
	v_cmp_lt_i32_e32 vcc, v37, v56
	s_waitcnt lgkmcnt(0)
	v_add_f32_e32 v36, v39, v57
	v_cvt_pk_bf16_f32 v38, v40, v41
	v_cndmask_b32_e32 v37, v223, v37, vcc
	v_lshlrev_b32_e32 v37, 2, v37
	ds_bpermute_b32 v37, v37, v36
	v_cvt_pk_bf16_f32 v39, v42, v43
	v_cvt_pk_bf16_f32 v40, v50, v51
	v_cvt_pk_bf16_f32 v41, v48, v49
	global_store_dwordx4 v[54:55], v[44:47], off
	global_store_dwordx4 v[54:55], v[38:41], off offset:256
	s_and_saveexec_b64 s[52:53], s[40:41]
	s_cbranch_execz .LBB0_1515
	s_waitcnt lgkmcnt(0)
	v_add_f32_e32 v38, v36, v37
	s_lshl_b32 s54, s27, 2
	v_lshlrev_b64 v[36:37], 7, v[52:53]
	s_ashr_i32 s55, s54, 31
	v_lshl_add_u64 v[36:37], s[34:35], 0, v[36:37]
	v_lshl_add_u64 v[36:37], s[54:55], 2, v[36:37]
	s_lshl_b32 s54, s67, 2
	s_mov_b32 s55, s13
	v_lshl_add_u64 v[36:37], v[36:37], 0, s[54:55]
	global_store_dword v[36:37], v38, off

; DI u32x4 pack8(const f32x4 v0, const f32x4 v1) { u32x4 w; w.x = pk2(v0[0], v0[1]); w.y = pk2(v0[2], v0[3]); w.z = pk2(v1[0], v1[1]); w.w = pk2(v1[2], v1[3]); return w; }
; DI void unpack8(const u32x4 w, f32x4& v0, f32x4& v1) { v0 = (f32x4){bflo(w.x), bfhi(w.x), bflo(w.y), bfhi(w.y)}; v1 = (f32x4){bflo(w.z), bfhi(w.z), bflo(w.w), bfhi(w.w)}; }
;     DI void operator()(const f32x4 (&acc)[2][2][4][2], const Unit& u, int wr, int wc, int fr, int fq, const LAS float* rsl) const {
;     ...
; #pragma unroll
;         for (int ai = 0; ai < 2; ++ai)
; #pragma unroll
;             for (int m = 0; m < 4; ++m) {
;                 const int row = row0 + ai * HALF + m * 16;
;                 if (u.ks < 0) {
;                     const size_t off = (size_t)row * DM + col0; float sq = 0.f;
; #pragma unroll
;                     for (int bj = 0; bj < 2; ++bj) {
;                         f32x4 x0, x1;
;                         if (XF32) { x0 = *(const f32x4*)(Xin + off + bj * HALF); x1 = *(const f32x4*)(Xin + off + bj * HALF + 4); }
;                         else unpack8(xin[ai][m][bj], x0, x1);
;                         x0 += acc[ai][bj][m][0]; x1 += acc[ai][bj][m][1];
;                         *(u32x4*)(act + off + bj * HALF) = pack8(x0, x1);
;                         sq += (x0[0] * x0[0] + x0[1] * x0[1]) + (x0[2] * x0[2] + x0[3] * x0[3]) + (x1[0] * x1[0] + x1[1] * x1[1]) + (x1[2] * x1[2] + x1[3] * x1[3]);
;                     }
;                     sq += __shfl_xor(sq, 16); sq += __shfl_xor(sq, 32);
;                     if (fq == 0) ssq[(size_t)row * 32 + u.pn * 4 + wc] = sq;
.LBB0_1517:
	s_waitcnt vmcnt(0) lgkmcnt(0)
	v_lshlrev_b32_e32 v40, 16, v112
	v_and_b32_e32 v41, 0xffff0000, v112
	v_lshlrev_b32_e32 v42, 16, v113
	v_and_b32_e32 v43, 0xffff0000, v113
	v_lshlrev_b32_e32 v44, 16, v114
	v_and_b32_e32 v45, 0xffff0000, v114
	v_pk_add_f32 v[32:33], v[32:33], v[40:41]
	v_pk_add_f32 v[34:35], v[34:35], v[42:43]
	v_pk_add_f32 v[42:43], v[28:29], v[44:45]
	v_cvt_pk_bf16_f32 v28, v32, v33
	v_mul_f32_e32 v33, v33, v33
	v_fmac_f32_e32 v33, v32, v32
	v_mul_f32_e32 v32, v35, v35
	v_fmac_f32_e32 v32, v34, v34
	v_lshlrev_b32_e32 v46, 16, v115
	v_and_b32_e32 v47, 0xffff0000, v115
	v_add_f32_e32 v32, v33, v32
	v_mul_f32_e32 v33, v43, v43
	v_pk_add_f32 v[40:41], v[30:31], v[46:47]
	v_fmac_f32_e32 v33, v42, v42
	v_add_f32_e32 v32, v33, v32
	v_mul_f32_e32 v33, v41, v41
	v_fmac_f32_e32 v33, v40, v40
	v_cvt_pk_bf16_f32 v29, v34, v35
	v_add_f32_e32 v44, v33, v32
	v_lshlrev_b32_e32 v32, 16, v104
	v_and_b32_e32 v33, 0xffff0000, v104
	v_lshlrev_b32_e32 v34, 16, v105
	v_and_b32_e32 v35, 0xffff0000, v105
	v_cvt_pk_bf16_f32 v31, v40, v41
	v_lshlrev_b32_e32 v40, 16, v106
	v_and_b32_e32 v41, 0xffff0000, v106
	v_pk_add_f32 v[26:27], v[26:27], v[34:35]
	v_pk_add_f32 v[24:25], v[24:25], v[32:33]
	v_pk_add_f32 v[34:35], v[20:21], v[40:41]
	v_mul_f32_e32 v20, v25, v25
	v_mul_f32_e32 v21, v27, v27
	v_fmac_f32_e32 v20, v24, v24
	v_fmac_f32_e32 v21, v26, v26
	v_cvt_pk_bf16_f32 v30, v42, v43
	v_lshlrev_b32_e32 v42, 16, v107
	v_and_b32_e32 v43, 0xffff0000, v107
	v_add_f32_e32 v20, v20, v21
	v_mul_f32_e32 v21, v35, v35
	v_pk_add_f32 v[32:33], v[22:23], v[42:43]
	v_fmac_f32_e32 v21, v34, v34
	v_add_f32_e32 v20, v21, v20
	v_mul_f32_e32 v21, v33, v33
	v_fmac_f32_e32 v21, v32, v32
	v_add_f32_e32 v20, v21, v20
	v_and_b32_e32 v21, 64, v223
	v_add_f32_e32 v23, v20, v44
	v_xor_b32_e32 v20, 16, v223
	v_add_u32_e32 v40, 64, v21
	v_cmp_lt_i32_e32 vcc, v20, v40
	v_add_u32_e32 v36, 0xa0, v216
	v_ashrrev_i32_e32 v37, 31, v36
	v_cndmask_b32_e32 v20, v223, v20, vcc
	v_lshlrev_b32_e32 v20, 2, v20
	v_lshlrev_b64 v[38:39], 12, v[36:37]
	ds_bpermute_b32 v41, v20, v23
	v_lshl_add_u64 v[20:21], s[18:19], 0, v[38:39]
	v_lshl_add_u64 v[38:39], v[214:215], 1, v[20:21]
	v_xor_b32_e32 v21, 32, v223
	v_cmp_lt_i32_e32 vcc, v21, v40
	s_waitcnt lgkmcnt(0)
	v_add_f32_e32 v20, v23, v41
	v_cvt_pk_bf16_f32 v22, v24, v25
	v_cndmask_b32_e32 v21, v223, v21, vcc
	v_lshlrev_b32_e32 v21, 2, v21
	ds_bpermute_b32 v21, v21, v20
	v_cvt_pk_bf16_f32 v23, v26, v27
	v_cvt_pk_bf16_f32 v24, v34, v35
	v_cvt_pk_bf16_f32 v25, v32, v33
	global_store_dwordx4 v[38:39], v[28:31], off
	global_store_dwordx4 v[38:39], v[22:25], off offset:256
	s_and_saveexec_b64 s[52:53], s[40:41]
	s_cbranch_execz .LBB0_1519
	s_waitcnt lgkmcnt(0)
	v_add_f32_e32 v22, v20, v21
	s_lshl_b32 s54, s27, 2
	v_lshlrev_b64 v[20:21], 7, v[36:37]
	s_ashr_i32 s55, s54, 31
	v_lshl_add_u64 v[20:21], s[34:35], 0, v[20:21]
	v_lshl_add_u64 v[20:21], s[54:55], 2, v[20:21]
	s_lshl_b32 s54, s67, 2
	s_mov_b32 s55, s13
	v_lshl_add_u64 v[20:21], v[20:21], 0, s[54:55]
	global_store_dword v[20:21], v22, off

; DI u32x4 pack8(const f32x4 v0, const f32x4 v1) { u32x4 w; w.x = pk2(v0[0], v0[1]); w.y = pk2(v0[2], v0[3]); w.z = pk2(v1[0], v1[1]); w.w = pk2(v1[2], v1[3]); return w; }
; DI void unpack8(const u32x4 w, f32x4& v0, f32x4& v1) { v0 = (f32x4){bflo(w.x), bfhi(w.x), bflo(w.y), bfhi(w.y)}; v1 = (f32x4){bflo(w.z), bfhi(w.z), bflo(w.w), bfhi(w.w)}; }
;     DI void operator()(const f32x4 (&acc)[2][2][4][2], const Unit& u, int wr, int wc, int fr, int fq, const LAS float* rsl) const {
;     ...
; #pragma unroll
;         for (int ai = 0; ai < 2; ++ai)
; #pragma unroll
;             for (int m = 0; m < 4; ++m) {
;                 const int row = row0 + ai * HALF + m * 16;
;                 if (u.ks < 0) {
;                     const size_t off = (size_t)row * DM + col0; float sq = 0.f;
; #pragma unroll
;                     for (int bj = 0; bj < 2; ++bj) {
;                         f32x4 x0, x1;
;                         if (XF32) { x0 = *(const f32x4*)(Xin + off + bj * HALF); x1 = *(const f32x4*)(Xin + off + bj * HALF + 4); }
;                         else unpack8(xin[ai][m][bj], x0, x1);
;                         x0 += acc[ai][bj][m][0]; x1 += acc[ai][bj][m][1];
;                         *(u32x4*)(act + off + bj * HALF) = pack8(x0, x1);
;                         sq += (x0[0] * x0[0] + x0[1] * x0[1]) + (x0[2] * x0[2] + x0[3] * x0[3]) + (x1[0] * x1[0] + x1[1] * x1[1]) + (x1[2] * x1[2] + x1[3] * x1[3]);
;                     }
;                     sq += __shfl_xor(sq, 16); sq += __shfl_xor(sq, 32);
;                     if (fq == 0) ssq[(size_t)row * 32 + u.pn * 4 + wc] = sq;
.LBB0_1521:
	s_waitcnt vmcnt(0) lgkmcnt(0)
	v_lshlrev_b32_e32 v24, 16, v88
	v_and_b32_e32 v25, 0xffff0000, v88
	v_lshlrev_b32_e32 v26, 16, v89
	v_and_b32_e32 v27, 0xffff0000, v89
	v_lshlrev_b32_e32 v28, 16, v90
	v_and_b32_e32 v29, 0xffff0000, v90
	v_pk_add_f32 v[16:17], v[16:17], v[24:25]
	v_pk_add_f32 v[18:19], v[18:19], v[26:27]
	v_pk_add_f32 v[26:27], v[12:13], v[28:29]
	v_cvt_pk_bf16_f32 v12, v16, v17
	v_mul_f32_e32 v17, v17, v17
	v_fmac_f32_e32 v17, v16, v16
	v_mul_f32_e32 v16, v19, v19
	v_fmac_f32_e32 v16, v18, v18
	v_lshlrev_b32_e32 v30, 16, v91
	v_and_b32_e32 v31, 0xffff0000, v91
	v_add_f32_e32 v16, v17, v16
	v_mul_f32_e32 v17, v27, v27
	v_pk_add_f32 v[24:25], v[14:15], v[30:31]
	v_fmac_f32_e32 v17, v26, v26
	v_add_f32_e32 v16, v17, v16
	v_mul_f32_e32 v17, v25, v25
	v_fmac_f32_e32 v17, v24, v24
	v_cvt_pk_bf16_f32 v13, v18, v19
	v_add_f32_e32 v28, v17, v16
	v_lshlrev_b32_e32 v16, 16, v84
	v_and_b32_e32 v17, 0xffff0000, v84
	v_lshlrev_b32_e32 v18, 16, v85
	v_and_b32_e32 v19, 0xffff0000, v85
	v_cvt_pk_bf16_f32 v15, v24, v25
	v_lshlrev_b32_e32 v24, 16, v86
	v_and_b32_e32 v25, 0xffff0000, v86
	v_pk_add_f32 v[10:11], v[10:11], v[18:19]
	v_pk_add_f32 v[8:9], v[8:9], v[16:17]
	v_pk_add_f32 v[18:19], v[4:5], v[24:25]
	v_mul_f32_e32 v4, v9, v9
	v_mul_f32_e32 v5, v11, v11
	v_fmac_f32_e32 v4, v8, v8
	v_fmac_f32_e32 v5, v10, v10
	v_cvt_pk_bf16_f32 v14, v26, v27
	v_lshlrev_b32_e32 v26, 16, v87
	v_and_b32_e32 v27, 0xffff0000, v87
	v_add_f32_e32 v4, v4, v5
	v_mul_f32_e32 v5, v19, v19
	v_pk_add_f32 v[16:17], v[6:7], v[26:27]
	v_fmac_f32_e32 v5, v18, v18
	v_add_f32_e32 v4, v5, v4
	v_mul_f32_e32 v5, v17, v17
	v_fmac_f32_e32 v5, v16, v16
	v_add_f32_e32 v4, v5, v4
	v_and_b32_e32 v5, 64, v223
	v_add_f32_e32 v7, v4, v28
	v_xor_b32_e32 v4, 16, v223
	v_add_u32_e32 v24, 64, v5
	v_cmp_lt_i32_e32 vcc, v4, v24
	v_add_u32_e32 v20, 0xb0, v216
	v_ashrrev_i32_e32 v21, 31, v20
	v_cndmask_b32_e32 v4, v223, v4, vcc
	v_lshlrev_b32_e32 v4, 2, v4
	v_lshlrev_b64 v[22:23], 12, v[20:21]
	ds_bpermute_b32 v25, v4, v7
	v_lshl_add_u64 v[4:5], s[18:19], 0, v[22:23]
	v_lshl_add_u64 v[22:23], v[214:215], 1, v[4:5]
	v_xor_b32_e32 v5, 32, v223
	v_cmp_lt_i32_e32 vcc, v5, v24
	s_waitcnt lgkmcnt(0)
	v_add_f32_e32 v4, v7, v25
	v_cvt_pk_bf16_f32 v6, v8, v9
	v_cndmask_b32_e32 v5, v223, v5, vcc
	v_lshlrev_b32_e32 v5, 2, v5
	ds_bpermute_b32 v5, v5, v4
	v_cvt_pk_bf16_f32 v7, v10, v11
	v_cvt_pk_bf16_f32 v8, v18, v19
	v_cvt_pk_bf16_f32 v9, v16, v17
	global_store_dwordx4 v[22:23], v[12:15], off
	global_store_dwordx4 v[22:23], v[6:9], off offset:256
	s_and_saveexec_b64 s[42:43], s[40:41]
	s_cbranch_execz .LBB0_1523
	s_waitcnt lgkmcnt(0)
	v_add_f32_e32 v6, v4, v5
	s_lshl_b32 s52, s27, 2
	v_lshlrev_b64 v[4:5], 7, v[20:21]
	s_ashr_i32 s53, s52, 31
	v_lshl_add_u64 v[4:5], s[34:35], 0, v[4:5]
	v_lshl_add_u64 v[4:5], s[52:53], 2, v[4:5]
	s_lshl_b32 s12, s67, 2
	v_lshl_add_u64 v[4:5], v[4:5], 0, s[12:13]
	global_store_dword v[4:5], v6, off

; DI float bflo(unsigned w) { return __uint_as_float(w << 16); }
; DI float bfhi(unsigned w) { return __uint_as_float(w & 0xffff0000u); }
; DI unsigned pk2(float a, float b) { f32x2 v = {a, b}; bf16v2 r = __builtin_convertvector(v, bf16v2); return __builtin_bit_cast(unsigned, r); }
; DI void phase_postRes(const Ctx& c, const float* xinS  ) {
;     ...
;     for (int row = MP + gw; row < M; row += NGW) {
;         const f32x4* pr = (const f32x4*)(part + (size_t)(row - MP) * DM) + c.lane; const size_t st = (size_t)MS * DM / 4;
;         u32x2* ao = (u32x2*)(act + (size_t)row * DM) + c.lane;
;         float s = 0.f;
; #pragma unroll
;         for (int j = 0; j < 8; ++j) {
;             f32x4 xi;
;             if (xinS) xi = ((const f32x4*)(xinS + (size_t)(row - MP) * DM) + c.lane)[64 * j];
;             else { const u32x2 w = ao[64 * j]; xi = (f32x4){bflo(w.x), bfhi(w.x), bflo(w.y), bfhi(w.y)}; }
;             const f32x4 v = xi + ((pr[64 * j] + pr[st + 64 * j]) + (pr[2 * st + 64 * j] + pr[3 * st + 64 * j]));
;             u32x2 w; w.x = pk2(v[0], v[1]); w.y = pk2(v[2], v[3]); ao[64 * j] = w;
;             s += (v[0] * v[0] + v[1] * v[1]) + (v[2] * v[2] + v[3] * v[3]);
;         }
;         s = wave_sum(s);
;         if (c.lane == 0) rs[row] = 1.0f / sqrtf(s * (1.0f / DM) + EPS);
.LBB0_1578:
	s_waitcnt lgkmcnt(0)
	global_load_dwordx2 v[8:9], v[4:5], off
	global_load_dwordx4 v[10:13], v[6:7], off
	s_waitcnt vmcnt(0) lgkmcnt(0)
	v_lshlrev_b32_e32 v18, 16, v8
	v_and_b32_e32 v19, 0xffff0000, v8
	v_add_co_u32_e32 v8, vcc, 0x1000000, v6
	v_lshlrev_b32_e32 v32, 16, v9
	v_and_b32_e32 v33, 0xffff0000, v9
	v_addc_co_u32_e32 v9, vcc, 0, v7, vcc
	global_load_dwordx4 v[14:17], v[8:9], off
	s_waitcnt vmcnt(0) lgkmcnt(0)
	v_pk_add_f32 v[36:37], v[10:11], v[14:15]
	v_add_co_u32_e32 v10, vcc, 0x2000000, v6
	v_pk_add_f32 v[34:35], v[12:13], v[16:17]
	s_nop 0
	v_addc_co_u32_e32 v11, vcc, 0, v7, vcc
	v_add_co_u32_e32 v12, vcc, 0x3000000, v6
	global_load_dwordx4 v[14:17], v[10:11], off
	s_nop 0
	v_addc_co_u32_e32 v13, vcc, 0, v7, vcc
	global_load_dwordx4 v[28:31], v[12:13], off
	s_waitcnt vmcnt(0) lgkmcnt(0)
	v_pk_add_f32 v[14:15], v[14:15], v[28:29]
	v_pk_add_f32 v[16:17], v[16:17], v[30:31]
	v_pk_add_f32 v[14:15], v[36:37], v[14:15]
	v_pk_add_f32 v[16:17], v[34:35], v[16:17]
	v_pk_add_f32 v[14:15], v[14:15], v[18:19]
	v_pk_add_f32 v[16:17], v[16:17], v[32:33]
	v_mul_f32_e32 v2, v15, v15
	v_cvt_pk_bf16_f32 v18, v14, v15
	v_fmac_f32_e32 v2, v14, v14
	v_mul_f32_e32 v14, v17, v17
	v_fmac_f32_e32 v14, v16, v16
	v_add_f32_e32 v2, v2, v14
	global_load_dwordx2 v[14:15], v[4:5], off offset:512
	v_cvt_pk_bf16_f32 v19, v16, v17
	global_store_dwordx2 v[4:5], v[18:19], off
	s_waitcnt vmcnt(0) lgkmcnt(0)
	v_lshlrev_b32_e32 v18, 16, v14
	v_and_b32_e32 v19, 0xffff0000, v14
	v_lshlrev_b32_e32 v32, 16, v15
	v_and_b32_e32 v33, 0xffff0000, v15
	global_load_dwordx4 v[14:17], v[6:7], off offset:1024
	global_load_dwordx4 v[28:31], v[8:9], off offset:1024
	s_waitcnt vmcnt(0) lgkmcnt(0)
	v_pk_add_f32 v[34:35], v[16:17], v[30:31]
	v_pk_add_f32 v[36:37], v[14:15], v[28:29]
	global_load_dwordx4 v[14:17], v[10:11], off offset:1024
	global_load_dwordx4 v[28:31], v[12:13], off offset:1024
	s_waitcnt vmcnt(0) lgkmcnt(0)
	v_pk_add_f32 v[14:15], v[14:15], v[28:29]
	v_pk_add_f32 v[16:17], v[16:17], v[30:31]
	v_pk_add_f32 v[14:15], v[36:37], v[14:15]
	v_pk_add_f32 v[16:17], v[34:35], v[16:17]
	v_pk_add_f32 v[14:15], v[14:15], v[18:19]
	v_pk_add_f32 v[16:17], v[16:17], v[32:33]
	v_cvt_pk_bf16_f32 v18, v14, v15
	v_mul_f32_e32 v15, v15, v15
	v_fmac_f32_e32 v15, v14, v14
	v_mul_f32_e32 v14, v17, v17
	v_fmac_f32_e32 v14, v16, v16
	v_add_f32_e32 v14, v15, v14
	v_add_f32_e32 v2, v2, v14
	global_load_dwordx2 v[14:15], v[4:5], off offset:1024
	v_cvt_pk_bf16_f32 v19, v16, v17
	global_store_dwordx2 v[4:5], v[18:19], off offset:512
	s_waitcnt vmcnt(0) lgkmcnt(0)
	v_lshlrev_b32_e32 v18, 16, v14
	v_and_b32_e32 v19, 0xffff0000, v14
	v_lshlrev_b32_e32 v32, 16, v15
	v_and_b32_e32 v33, 0xffff0000, v15
	global_load_dwordx4 v[14:17], v[6:7], off offset:2048
	global_load_dwordx4 v[28:31], v[8:9], off offset:2048
	s_waitcnt vmcnt(0) lgkmcnt(0)
	v_pk_add_f32 v[34:35], v[16:17], v[30:31]
	v_pk_add_f32 v[36:37], v[14:15], v[28:29]
	global_load_dwordx4 v[14:17], v[10:11], off offset:2048
	global_load_dwordx4 v[28:31], v[12:13], off offset:2048
	s_waitcnt vmcnt(0) lgkmcnt(0)
	v_pk_add_f32 v[14:15], v[14:15], v[28:29]
	v_pk_add_f32 v[16:17], v[16:17], v[30:31]
	v_pk_add_f32 v[14:15], v[36:37], v[14:15]
	v_pk_add_f32 v[16:17], v[34:35], v[16:17]
	v_pk_add_f32 v[14:15], v[14:15], v[18:19]
	v_pk_add_f32 v[16:17], v[16:17], v[32:33]
	v_cvt_pk_bf16_f32 v18, v14, v15
	v_mul_f32_e32 v15, v15, v15
	v_fmac_f32_e32 v15, v14, v14
	v_mul_f32_e32 v14, v17, v17
	v_fmac_f32_e32 v14, v16, v16
	v_add_f32_e32 v14, v15, v14
	v_add_f32_e32 v2, v2, v14
	global_load_dwordx2 v[14:15], v[4:5], off offset:1536
	v_cvt_pk_bf16_f32 v19, v16, v17
	global_store_dwordx2 v[4:5], v[18:19], off offset:1024
	s_waitcnt vmcnt(0) lgkmcnt(0)
	v_lshlrev_b32_e32 v18, 16, v14
	v_and_b32_e32 v19, 0xffff0000, v14
	v_lshlrev_b32_e32 v32, 16, v15
	v_and_b32_e32 v33, 0xffff0000, v15
	global_load_dwordx4 v[14:17], v[6:7], off offset:3072
	global_load_dwordx4 v[28:31], v[8:9], off offset:3072
	s_waitcnt vmcnt(0) lgkmcnt(0)
	v_pk_add_f32 v[28:29], v[14:15], v[28:29]
	global_load_dwordx4 v[8:11], v[10:11], off offset:3072
	s_nop 0
	global_load_dwordx4 v[12:15], v[12:13], off offset:3072
	v_pk_add_f32 v[16:17], v[16:17], v[30:31]
	s_waitcnt vmcnt(0) lgkmcnt(0)
	v_pk_add_f32 v[8:9], v[8:9], v[12:13]
	v_pk_add_f32 v[10:11], v[10:11], v[14:15]
	v_pk_add_f32 v[8:9], v[28:29], v[8:9]
	v_pk_add_f32 v[10:11], v[16:17], v[10:11]
	v_pk_add_f32 v[8:9], v[8:9], v[18:19]
	v_pk_add_f32 v[10:11], v[10:11], v[32:33]
	v_cvt_pk_bf16_f32 v12, v8, v9
	v_mul_f32_e32 v9, v9, v9
	v_fmac_f32_e32 v9, v8, v8
	v_mul_f32_e32 v8, v11, v11
	v_fmac_f32_e32 v8, v10, v10
	v_add_f32_e32 v8, v9, v8
	v_add_f32_e32 v2, v2, v8
	global_load_dwordx2 v[8:9], v[4:5], off offset:2048
	v_cvt_pk_bf16_f32 v13, v10, v11
	global_store_dwordx2 v[4:5], v[12:13], off offset:1536
	s_waitcnt vmcnt(0) lgkmcnt(0)
	v_lshlrev_b32_e32 v32, 16, v8
	v_and_b32_e32 v33, 0xffff0000, v8
	v_add_co_u32_e32 v8, vcc, s33, v6
	v_lshlrev_b32_e32 v34, 16, v9
	v_and_b32_e32 v35, 0xffff0000, v9
	v_addc_co_u32_e32 v9, vcc, 0, v7, vcc
	v_add_co_u32_e32 v10, vcc, s9, v6
	global_load_dwordx4 v[12:15], v[8:9], off
	s_nop 0
	v_addc_co_u32_e32 v11, vcc, 0, v7, vcc
	global_load_dwordx4 v[16:19], v[10:11], off
	s_waitcnt vmcnt(0) lgkmcnt(0)
	v_pk_add_f32 v[38:39], v[12:13], v[16:17]
	v_add_co_u32_e32 v12, vcc, s26, v6
	v_pk_add_f32 v[36:37], v[14:15], v[18:19]
	s_nop 0
	v_addc_co_u32_e32 v13, vcc, 0, v7, vcc
	v_add_co_u32_e32 v14, vcc, s27, v6
	global_load_dwordx4 v[16:19], v[12:13], off
	s_nop 0
	v_addc_co_u32_e32 v15, vcc, 0, v7, vcc
	global_load_dwordx4 v[28:31], v[14:15], off
	s_waitcnt vmcnt(0) lgkmcnt(0)
; DI float bflo(unsigned w) { return __uint_as_float(w << 16); }
; DI float bfhi(unsigned w) { return __uint_as_float(w & 0xffff0000u); }
; DI unsigned pk2(float a, float b) { f32x2 v = {a, b}; bf16v2 r = __builtin_convertvector(v, bf16v2); return __builtin_bit_cast(unsigned, r); }
; DI void phase_postRes(const Ctx& c, const float* xinS  ) {
;     ...
;     for (int row = MP + gw; row < M; row += NGW) {
;         const f32x4* pr = (const f32x4*)(part + (size_t)(row - MP) * DM) + c.lane; const size_t st = (size_t)MS * DM / 4;
;         u32x2* ao = (u32x2*)(act + (size_t)row * DM) + c.lane;
;         float s = 0.f;
; #pragma unroll
;         for (int j = 0; j < 8; ++j) {
;             f32x4 xi;
;             if (xinS) xi = ((const f32x4*)(xinS + (size_t)(row - MP) * DM) + c.lane)[64 * j];
;             else { const u32x2 w = ao[64 * j]; xi = (f32x4){bflo(w.x), bfhi(w.x), bflo(w.y), bfhi(w.y)}; }
;             const f32x4 v = xi + ((pr[64 * j] + pr[st + 64 * j]) + (pr[2 * st + 64 * j] + pr[3 * st + 64 * j]));
;             u32x2 w; w.x = pk2(v[0], v[1]); w.y = pk2(v[2], v[3]); ao[64 * j] = w;
;             s += (v[0] * v[0] + v[1] * v[1]) + (v[2] * v[2] + v[3] * v[3]);
;         }
;         s = wave_sum(s);
;         if (c.lane == 0) rs[row] = 1.0f / sqrtf(s * (1.0f / DM) + EPS);
	v_pk_add_f32 v[16:17], v[16:17], v[28:29]
	v_pk_add_f32 v[18:19], v[18:19], v[30:31]
	v_pk_add_f32 v[16:17], v[38:39], v[16:17]
	v_pk_add_f32 v[18:19], v[36:37], v[18:19]
	v_pk_add_f32 v[16:17], v[16:17], v[32:33]
	v_pk_add_f32 v[18:19], v[18:19], v[34:35]
	v_cvt_pk_bf16_f32 v28, v16, v17
	v_mul_f32_e32 v17, v17, v17
	v_fmac_f32_e32 v17, v16, v16
	v_mul_f32_e32 v16, v19, v19
	v_fmac_f32_e32 v16, v18, v18
	v_add_f32_e32 v16, v17, v16
	v_add_f32_e32 v2, v2, v16
	global_load_dwordx2 v[16:17], v[4:5], off offset:2560
	v_cvt_pk_bf16_f32 v29, v18, v19
	global_store_dwordx2 v[4:5], v[28:29], off offset:2048
	s_waitcnt vmcnt(0) lgkmcnt(0)
	v_lshlrev_b32_e32 v32, 16, v16
	v_and_b32_e32 v33, 0xffff0000, v16
	v_lshlrev_b32_e32 v34, 16, v17
	v_and_b32_e32 v35, 0xffff0000, v17
	global_load_dwordx4 v[16:19], v[8:9], off offset:1024
	global_load_dwordx4 v[28:31], v[10:11], off offset:1024
	s_waitcnt vmcnt(0) lgkmcnt(0)
	v_pk_add_f32 v[36:37], v[18:19], v[30:31]
	v_pk_add_f32 v[38:39], v[16:17], v[28:29]
	global_load_dwordx4 v[16:19], v[12:13], off offset:1024
	global_load_dwordx4 v[28:31], v[14:15], off offset:1024
	s_waitcnt vmcnt(0) lgkmcnt(0)
	v_pk_add_f32 v[16:17], v[16:17], v[28:29]
	v_pk_add_f32 v[18:19], v[18:19], v[30:31]
	v_pk_add_f32 v[16:17], v[38:39], v[16:17]
	v_pk_add_f32 v[18:19], v[36:37], v[18:19]
	v_pk_add_f32 v[16:17], v[16:17], v[32:33]
	v_pk_add_f32 v[18:19], v[18:19], v[34:35]
	v_cvt_pk_bf16_f32 v28, v16, v17
	v_mul_f32_e32 v17, v17, v17
	v_fmac_f32_e32 v17, v16, v16
	v_mul_f32_e32 v16, v19, v19
	v_fmac_f32_e32 v16, v18, v18
	v_add_f32_e32 v16, v17, v16
	v_add_f32_e32 v2, v2, v16
	global_load_dwordx2 v[16:17], v[4:5], off offset:3072
	v_cvt_pk_bf16_f32 v29, v18, v19
	global_store_dwordx2 v[4:5], v[28:29], off offset:2560
	s_waitcnt vmcnt(0) lgkmcnt(0)
	v_lshlrev_b32_e32 v32, 16, v16
	v_and_b32_e32 v33, 0xffff0000, v16
	v_lshlrev_b32_e32 v34, 16, v17
	v_and_b32_e32 v35, 0xffff0000, v17
	global_load_dwordx4 v[16:19], v[8:9], off offset:2048
	global_load_dwordx4 v[28:31], v[10:11], off offset:2048
	s_waitcnt vmcnt(0) lgkmcnt(0)
	v_pk_add_f32 v[36:37], v[18:19], v[30:31]
	v_pk_add_f32 v[38:39], v[16:17], v[28:29]
	global_load_dwordx4 v[16:19], v[12:13], off offset:2048
	global_load_dwordx4 v[28:31], v[14:15], off offset:2048
	s_waitcnt vmcnt(0) lgkmcnt(0)
	v_pk_add_f32 v[18:19], v[18:19], v[30:31]
	v_pk_add_f32 v[16:17], v[16:17], v[28:29]
	v_pk_add_f32 v[18:19], v[36:37], v[18:19]
	v_pk_add_f32 v[16:17], v[38:39], v[16:17]
	v_pk_add_f32 v[18:19], v[18:19], v[34:35]
	v_pk_add_f32 v[16:17], v[16:17], v[32:33]
	v_cvt_pk_bf16_f32 v29, v18, v19
	v_cvt_pk_bf16_f32 v28, v16, v17
	v_mul_f32_e32 v17, v17, v17
	global_store_dwordx2 v[4:5], v[28:29], off offset:3072
	v_fmac_f32_e32 v17, v16, v16
	v_mul_f32_e32 v16, v19, v19
	v_fmac_f32_e32 v16, v18, v18
	global_load_dwordx2 v[18:19], v[4:5], off offset:3584
	global_load_dwordx4 v[28:31], v[8:9], off offset:3072
	s_nop 0
	global_load_dwordx4 v[8:11], v[10:11], off offset:3072
	v_add_f32_e32 v16, v17, v16
	v_add_f32_e32 v2, v2, v16
	s_waitcnt vmcnt(0) lgkmcnt(0)
	v_lshlrev_b32_e32 v16, 16, v18
	v_pk_add_f32 v[30:31], v[30:31], v[10:11]
	v_pk_add_f32 v[28:29], v[28:29], v[8:9]
	global_load_dwordx4 v[8:11], v[12:13], off offset:3072
	s_nop 0
	global_load_dwordx4 v[12:15], v[14:15], off offset:3072
	v_and_b32_e32 v17, 0xffff0000, v18
	v_lshlrev_b32_e32 v18, 16, v19
	v_and_b32_e32 v19, 0xffff0000, v19
	s_waitcnt vmcnt(0) lgkmcnt(0)
	v_pk_add_f32 v[8:9], v[8:9], v[12:13]
	v_pk_add_f32 v[10:11], v[10:11], v[14:15]
	v_pk_add_f32 v[8:9], v[28:29], v[8:9]
	v_pk_add_f32 v[10:11], v[30:31], v[10:11]
	v_pk_add_f32 v[8:9], v[8:9], v[16:17]
	v_pk_add_f32 v[10:11], v[10:11], v[18:19]
	v_cvt_pk_bf16_f32 v12, v8, v9
	v_mul_f32_e32 v9, v9, v9
	v_fmac_f32_e32 v9, v8, v8
	v_mul_f32_e32 v8, v11, v11
	v_fmac_f32_e32 v8, v10, v10
	v_add_f32_e32 v8, v9, v8
	v_add_f32_e32 v2, v2, v8
	ds_bpermute_b32 v8, v21, v2
	v_cvt_pk_bf16_f32 v13, v10, v11
	global_store_dwordx2 v[4:5], v[12:13], off offset:3584
	s_waitcnt lgkmcnt(0)
	v_add_f32_e32 v2, v2, v8
	ds_bpermute_b32 v8, v22, v2
	s_waitcnt lgkmcnt(0)
	v_add_f32_e32 v2, v2, v8
	ds_bpermute_b32 v8, v23, v2
	s_waitcnt lgkmcnt(0)
	v_add_f32_e32 v2, v2, v8
	ds_bpermute_b32 v8, v24, v2
	s_waitcnt lgkmcnt(0)
	v_add_f32_e32 v2, v2, v8
	ds_bpermute_b32 v8, v25, v2
	s_waitcnt lgkmcnt(0)
	v_add_f32_e32 v2, v2, v8
	ds_bpermute_b32 v8, v26, v2
	s_and_saveexec_b64 s[48:49], s[40:41]
	s_cbranch_execz .LBB0_1577
	s_waitcnt lgkmcnt(0)
	v_add_f32_e32 v2, v2, v8
	v_fmamk_f32 v2, v2, 0x3a000000, v220
	v_mul_f32_e32 v8, 0x4f800000, v2
	v_cmp_gt_f32_e32 vcc, s84, v2
	s_nop 1
	v_cndmask_b32_e32 v2, v2, v8, vcc
	v_sqrt_f32_e32 v8, v2
	s_nop 0
	v_add_u32_e32 v9, -1, v8
	v_fma_f32 v11, -v9, v8, v2
	v_add_u32_e32 v10, 1, v8
	v_cmp_ge_f32_e64 s[42:43], 0, v11
	s_nop 1
	v_cndmask_b32_e64 v9, v8, v9, s[42:43]
	v_fma_f32 v8, -v10, v8, v2
	v_cmp_lt_f32_e64 s[42:43], 0, v8
	s_nop 1
	v_cndmask_b32_e64 v8, v9, v10, s[42:43]
	v_mul_f32_e32 v9, 0x37800000, v8
	v_cndmask_b32_e32 v8, v8, v9, vcc
	v_cmp_class_f32_e32 vcc, v2, v221
	s_nop 1
	v_cndmask_b32_e32 v2, v8, v2, vcc
	v_div_scale_f32 v8, s[22:23], v2, v2, 1.0
	v_rcp_f32_e32 v9, v8
	s_nop 0
	v_fma_f32 v10, -v8, v9, 1.0
	v_fmac_f32_e32 v9, v10, v9
	v_div_scale_f32 v10, vcc, 1.0, v2, 1.0
	v_mul_f32_e32 v11, v10, v9
	v_fma_f32 v12, -v8, v11, v10
	v_fmac_f32_e32 v11, v12, v9
	v_fma_f32 v8, -v8, v11, v10
	v_div_fmas_f32 v8, v8, v9, v11
	v_div_fixup_f32 v2, v8, v2, 1.0
	v_mov_b64_e32 v[8:9], s[34:35]
	global_store_dword v[8:9], v2, off
	s_branch .LBB0_1577

; DI void phase_postRes(const Ctx& c, const float* xinS  ) {
;     ...
;     for (int row = c.bid * NTHR + c.tid; row < MP; row += c.G * NTHR) {
;         const f32x4* q = (const f32x4*)(ssq + (size_t)row * 32); float s = 0.f;
; #pragma unroll
;         for (int j = 0; j < 8; ++j) { const f32x4 v = q[j]; s += (v[0] + v[1]) + (v[2] + v[3]); }
;         rs[row] = 1.0f / sqrtf(s * (1.0f / DM) + EPS);
;     }
.LBB0_1582:
	global_load_dwordx4 v[10:13], v[8:9], off
	global_load_dwordx4 v[14:17], v[8:9], off offset:16
	v_add_u32_e32 v4, s18, v4
	s_waitcnt vmcnt(0) lgkmcnt(0)
	v_mov_b32_e32 v18, v10
	v_mov_b32_e32 v19, v14
	v_mov_b32_e32 v14, v11
	v_pk_add_f32 v[10:11], v[18:19], v[14:15]
	v_mov_b32_e32 v14, v12
	v_mov_b32_e32 v15, v16
	v_mov_b32_e32 v16, v13
	v_pk_add_f32 v[12:13], v[14:15], v[16:17]
	s_nop 0
	v_pk_add_f32 v[10:11], v[10:11], v[12:13]
	s_nop 0
	v_add_f32_e32 v2, 0, v10
	v_add_f32_e32 v14, v2, v11
	global_load_dwordx4 v[10:13], v[8:9], off offset:32
	s_waitcnt vmcnt(0) lgkmcnt(0)
	v_mov_b32_e32 v16, v11
	v_mov_b32_e32 v17, v12
	v_mov_b32_e32 v11, v13
	v_pk_add_f32 v[10:11], v[16:17], v[10:11]
	s_nop 0
	v_pk_add_f32 v[16:17], v[10:11], v[10:11] op_sel:[0,1] op_sel_hi:[1,0]
	global_load_dwordx4 v[10:13], v[8:9], off offset:48
	s_waitcnt vmcnt(0) lgkmcnt(0)
	v_add_f32_e32 v18, v10, v11
	v_add_f32_e32 v20, v12, v13
	global_load_dwordx4 v[10:13], v[8:9], off offset:64
	s_waitcnt vmcnt(0) lgkmcnt(0)
	v_mov_b32_e32 v15, v10
	v_mov_b32_e32 v17, v11
	v_mov_b32_e32 v19, v12
	v_mov_b32_e32 v21, v13
	v_pk_add_f32 v[10:11], v[14:15], v[16:17]
	v_pk_add_f32 v[12:13], v[18:19], v[20:21]
	s_nop 0
	v_pk_add_f32 v[10:11], v[10:11], v[12:13]
	s_nop 0
	v_pk_add_f32 v[14:15], v[10:11], v[10:11] op_sel:[0,1] op_sel_hi:[1,0]
	global_load_dwordx4 v[10:13], v[8:9], off offset:80
	s_waitcnt vmcnt(0) lgkmcnt(0)
	v_mov_b32_e32 v16, v11
	v_mov_b32_e32 v17, v12
	v_mov_b32_e32 v11, v13
	v_pk_add_f32 v[10:11], v[16:17], v[10:11]
	s_nop 0
	v_pk_add_f32 v[16:17], v[10:11], v[10:11] op_sel:[0,1] op_sel_hi:[1,0]
	global_load_dwordx4 v[10:13], v[8:9], off offset:96
	s_waitcnt vmcnt(0) lgkmcnt(0)
	v_add_f32_e32 v18, v10, v11
	v_add_f32_e32 v20, v12, v13
	global_load_dwordx4 v[10:13], v[8:9], off offset:112
	v_lshl_add_u64 v[8:9], v[8:9], 0, s[34:35]
	s_waitcnt vmcnt(0) lgkmcnt(0)
	v_mov_b32_e32 v15, v10
	v_mov_b32_e32 v17, v11
	v_mov_b32_e32 v19, v12
	v_mov_b32_e32 v21, v13
	v_pk_add_f32 v[10:11], v[14:15], v[16:17]
	v_pk_add_f32 v[12:13], v[18:19], v[20:21]
	s_nop 0
	v_pk_add_f32 v[10:11], v[10:11], v[12:13]
	s_nop 0
	v_add_f32_e32 v2, v10, v11
	v_fmamk_f32 v2, v2, 0x3a000000, v220
	v_cmp_gt_f32_e32 vcc, s84, v2
	v_mul_f32_e32 v5, 0x4f800000, v2
	s_nop 0
	v_cndmask_b32_e32 v2, v2, v5, vcc
	v_sqrt_f32_e32 v5, v2
	s_nop 0
	v_add_u32_e32 v10, -1, v5
	v_fma_f32 v11, -v10, v5, v2
	v_cmp_ge_f32_e64 s[40:41], 0, v11
	v_add_u32_e32 v11, 1, v5
	s_nop 0
	v_cndmask_b32_e64 v10, v5, v10, s[40:41]
	v_fma_f32 v5, -v11, v5, v2
	v_cmp_lt_f32_e64 s[40:41], 0, v5
	s_nop 1
	v_cndmask_b32_e64 v5, v10, v11, s[40:41]
	v_mul_f32_e32 v10, 0x37800000, v5
	v_cndmask_b32_e32 v5, v5, v10, vcc
	v_cmp_class_f32_e32 vcc, v2, v221
	s_nop 1
	v_cndmask_b32_e32 v2, v5, v2, vcc
	v_div_scale_f32 v5, s[22:23], v2, v2, 1.0
	v_rcp_f32_e32 v10, v5
	s_nop 0
	v_fma_f32 v11, -v5, v10, 1.0
	v_fmac_f32_e32 v10, v11, v10
	v_div_scale_f32 v11, vcc, 1.0, v2, 1.0
	v_mul_f32_e32 v12, v11, v10
	v_fma_f32 v13, -v5, v12, v11
	v_fmac_f32_e32 v12, v13, v10
	v_fma_f32 v5, -v5, v12, v11
	v_div_fmas_f32 v5, v5, v10, v12
	v_div_fixup_f32 v2, v5, v2, 1.0
	v_cmp_lt_i32_e32 vcc, s12, v4
	global_store_dword v[6:7], v2, off
	v_lshl_add_u64 v[6:7], v[6:7], 0, s[4:5]
	s_or_b64 s[38:39], vcc, s[38:39]
	s_andn2_b64 exec, exec, s[38:39]
	s_cbranch_execnz .LBB0_1582

; DI unsigned xb_ld(unsigned* p)              { return __hip_atomic_load(p, __ATOMIC_RELAXED, __HIP_MEMORY_SCOPE_AGENT); }
; DI void xcd_barrier_complete(unsigned* bar, unsigned x, unsigned& nloc, unsigned& nx) {
;     ...
;     for (;;) {
;         sum = 0u; cnt = 0u; mine = 0u;
; #pragma unroll
;         for (unsigned j = 0; j < 16; ++j) { const unsigned c = xb_ld(&bar[XB_XCNT(j)]); sum += c; cnt += (c > 0u) ? 1u : 0u; mine = (j == x) ? c : mine; }
;         if (sum == G) break;
;         __builtin_amdgcn_s_sleep(1);
;         if ((++sp & 255u) == 0u) { if (xb_ld(&bar[XB_TMO])) break; if (sp > XB_SPIN_CAP) { atomicAdd(&bar[XB_TMO], 1u); break; } }
;     }
.LBB0_1589:
	v_mov_b64_e32 v[14:15], s[8:9]
	global_load_dword v4, v[14:15], off offset:1024 sc1
	global_load_dword v2, v[14:15], off offset:1280 sc1
	global_load_dword v5, v[14:15], off offset:1536 sc1
	s_or_b64 s[48:49], s[48:49], exec
	s_or_b64 s[46:47], s[46:47], exec
	s_waitcnt vmcnt(0) lgkmcnt(0)
	v_add_u32_e32 v6, v2, v4
	v_add_u32_e32 v7, v6, v5
	global_load_dword v6, v[14:15], off offset:1792 sc1
	s_waitcnt vmcnt(0) lgkmcnt(0)
	v_add_u32_e32 v8, v7, v6
	global_load_dword v7, v[14:15], off offset:2048 sc1
	s_waitcnt vmcnt(0) lgkmcnt(0)
	v_add_u32_e32 v9, v8, v7
	global_load_dword v8, v[14:15], off offset:2304 sc1
	s_waitcnt vmcnt(0) lgkmcnt(0)
	v_add_u32_e32 v10, v9, v8
	global_load_dword v9, v[14:15], off offset:2560 sc1
	s_waitcnt vmcnt(0) lgkmcnt(0)
	v_add_u32_e32 v11, v10, v9
	global_load_dword v10, v[14:15], off offset:2816 sc1
	s_waitcnt vmcnt(0) lgkmcnt(0)
	v_add_u32_e32 v12, v11, v10
	global_load_dword v11, v[14:15], off offset:3072 sc1
	s_waitcnt vmcnt(0) lgkmcnt(0)
	v_add_u32_e32 v13, v12, v11
	global_load_dword v12, v[14:15], off offset:3328 sc1
	s_waitcnt vmcnt(0) lgkmcnt(0)
	v_add_u32_e32 v16, v13, v12
	global_load_dword v13, v[14:15], off offset:3584 sc1
	s_waitcnt vmcnt(0) lgkmcnt(0)
	v_add_u32_e32 v16, v16, v13
	global_load_dword v14, v[14:15], off offset:3840 sc1
	s_waitcnt vmcnt(0) lgkmcnt(0)
	v_add_u32_e32 v18, v16, v14
	v_mov_b64_e32 v[16:17], s[18:19]
	global_load_dword v15, v[16:17], off sc1
	v_mov_b64_e32 v[16:17], s[34:35]
	global_load_dword v16, v[16:17], off sc1
	s_waitcnt vmcnt(0) lgkmcnt(0)
	v_add_u32_e32 v18, v18, v15
	v_add_u32_e32 v20, v18, v16
	v_mov_b64_e32 v[18:19], s[38:39]
	global_load_dword v17, v[18:19], off sc1
	v_mov_b64_e32 v[18:19], s[40:41]
	global_load_dword v18, v[18:19], off sc1
	s_waitcnt vmcnt(0) lgkmcnt(0)
	v_add_u32_e32 v20, v20, v17
	v_add_u32_e32 v19, v20, v18
	v_cmp_ne_u32_e32 vcc, s12, v19
	s_and_saveexec_b64 s[50:51], vcc
	s_cbranch_execz .LBB0_1588
	s_and_b32 s23, s22, 0xff
	s_mov_b64 s[52:53], -1
	s_cmp_eq_u32 s23, 0
	s_mov_b64 s[56:57], -1
	s_mov_b64 s[54:55], -1
	s_sleep 1
	s_cbranch_scc1 .LBB0_1592
	s_and_saveexec_b64 s[58:59], s[56:57]
	s_cbranch_execz .LBB0_1587
	s_branch .LBB0_1595
.LBB0_1592:
	v_mov_b64_e32 v[20:21], s[8:9]
	global_load_dword v19, v[20:21], off offset:512 sc1
	s_mov_b64 s[56:57], 0
	s_waitcnt vmcnt(0) lgkmcnt(0)
	v_cmp_eq_u32_e32 vcc, 0, v19
	s_and_saveexec_b64 s[58:59], vcc
	s_cmp_lt_u32 s22, 0x100001
	s_cselect_b64 s[26:27], -1, 0
	s_xor_b64 s[54:55], exec, -1
	s_and_b64 s[56:57], s[26:27], exec
	s_or_b64 exec, exec, s[58:59]
	s_and_saveexec_b64 s[58:59], s[56:57]
	s_cbranch_execz .LBB0_1587

; DI unsigned xb_ld(unsigned* p)              { return __hip_atomic_load(p, __ATOMIC_RELAXED, __HIP_MEMORY_SCOPE_AGENT); }
; DI unsigned xb_add(unsigned* p, unsigned v) { return __hip_atomic_fetch_add(p, v, __ATOMIC_RELAXED, __HIP_MEMORY_SCOPE_AGENT); }
; #define XB_SPIN(cond, bar) do { unsigned _sp = 0; while (cond) { __builtin_amdgcn_s_sleep(1); \
;     if ((++_sp & 255u) == 0u) { if (xb_ld(&(bar)[XB_TMO])) break; if (_sp > XB_SPIN_CAP) { atomicAdd(&(bar)[XB_TMO], 1u); break; } } } } while (0)
; DI void xcd_barrier(const XcdBarrier& b) {
;     ...
;         __builtin_amdgcn_s_waitcnt(0);
;         unsigned nloc = b.st[0], nx = b.st[1];
;         if (nloc == 0u) { xcd_barrier_complete(bar, b.x, nloc, nx); b.st[0] = nloc; b.st[1] = nx; }
;         const unsigned old = xb_add(&bar[XB_XSUB(b.x)], 1u);
;         const unsigned gen = old / nloc;
;         if (old + 1u == (gen + 1u) * nloc) {
;             __builtin_amdgcn_fence(__ATOMIC_RELEASE, "agent");
;             asm volatile("s_waitcnt vmcnt(0)" ::: "memory");
;             const unsigned og = xb_add(&bar[XB_TOP], 1u);
;             const unsigned tg = og / nx;
;             if (og + 1u == (tg + 1u) * nx) xb_add(&bar[XB_TOPGEN], 1u);
;             else XB_SPIN(xb_ld(&bar[XB_TOPGEN]) == tg, bar);
;             __builtin_amdgcn_fence(__ATOMIC_ACQUIRE, "agent");
;             xb_add(&bar[XB_XGEN(b.x)], 1u);
;             asm volatile("s_waitcnt vmcnt(0)" ::: "memory");
;         } else {
;             XB_SPIN(xb_ld(&bar[XB_XGEN(b.x)]) == gen, bar);
.LBB0_1599:
	v_readlane_b32 s12, v253, 48
	s_lshl_b32 s12, s12, 2
	s_add_u32 s22, s8, s12
	s_addc_u32 s12, s9, 0
	v_mov_b32_e32 v5, s22
	v_add_co_u32_e32 v6, vcc, 0x1000, v5
	v_mov_b32_e32 v5, s12
	s_nop 0
	v_addc_co_u32_e32 v7, vcc, 0, v5, vcc
	flat_atomic_add v6, v[6:7], v218 offset:1024 sc0
	v_cvt_f32_u32_e32 v5, v4
	v_sub_u32_e32 v7, 0, v4
	v_rcp_iflag_f32_e32 v5, v5
	s_nop 0
	v_mul_f32_e32 v5, 0x4f7ffffe, v5
	v_cvt_u32_f32_e32 v5, v5
	v_mul_lo_u32 v7, v7, v5
	v_mul_hi_u32 v7, v5, v7
	v_add_u32_e32 v5, v5, v7
	s_waitcnt vmcnt(0) lgkmcnt(0)
	v_mul_hi_u32 v5, v6, v5
	v_mul_lo_u32 v7, v5, v4
	v_sub_u32_e32 v7, v6, v7
	v_cmp_ge_u32_e32 vcc, v7, v4
	v_add_u32_e32 v8, 1, v5
	s_nop 0
	v_cndmask_b32_e32 v5, v5, v8, vcc
	v_sub_u32_e32 v8, v7, v4
	v_cndmask_b32_e32 v7, v7, v8, vcc
	v_cmp_ge_u32_e32 vcc, v7, v4
	v_add_u32_e32 v7, 1, v5
	v_add_u32_e32 v8, 1, v6
	v_cndmask_b32_e32 v5, v5, v7, vcc
	v_mad_u64_u32 v[6:7], s[18:19], v4, v5, v[4:5]
	v_cmp_ne_u32_e32 vcc, v8, v6
	s_and_saveexec_b64 s[18:19], vcc
	s_xor_b64 s[18:19], exec, s[18:19]
	s_cbranch_execz .LBB0_1612
	v_mov_b32_e32 v2, s22
	v_add_co_u32_e32 v6, vcc, 0x2000, v2
	v_mov_b32_e32 v2, s12
	s_nop 0
	v_addc_co_u32_e32 v7, vcc, 0, v2, vcc
	global_load_dword v2, v[6:7], off offset:1024 sc1
	s_add_u32 s38, s22, 0x2400
	s_addc_u32 s39, s12, 0
	s_waitcnt vmcnt(0) lgkmcnt(0)
	v_cmp_eq_u32_e32 vcc, v2, v5
	s_and_saveexec_b64 s[34:35], vcc
	s_cbranch_execz .LBB0_1611
	s_mov_b32 s23, 1
	s_mov_b64 s[40:41], 0
	s_branch .LBB0_1603

; DI unsigned xb_ld(unsigned* p)              { return __hip_atomic_load(p, __ATOMIC_RELAXED, __HIP_MEMORY_SCOPE_AGENT); }
; #define XB_SPIN(cond, bar) do { unsigned _sp = 0; while (cond) { __builtin_amdgcn_s_sleep(1); \
;     if ((++_sp & 255u) == 0u) { if (xb_ld(&(bar)[XB_TMO])) break; if (_sp > XB_SPIN_CAP) { atomicAdd(&(bar)[XB_TMO], 1u); break; } } } } while (0)
; DI void xcd_barrier(const XcdBarrier& b) {
;     ...
;             XB_SPIN(xb_ld(&bar[XB_XGEN(b.x)]) == gen, bar);
.LBB0_1603:
	s_and_b32 s26, s23, 0xff
	s_mov_b64 s[46:47], -1
	s_cmp_lg_u32 s26, 0
	s_mov_b64 s[48:49], -1
	s_sleep 1
	s_cbranch_scc1 .LBB0_1607
	v_mov_b64_e32 v[6:7], s[8:9]
	global_load_dword v2, v[6:7], off offset:512 sc1
	s_mov_b64 s[48:49], 0
	s_mov_b64 s[50:51], -1
	s_waitcnt vmcnt(0) lgkmcnt(0)
	v_cmp_eq_u32_e32 vcc, 0, v2
	s_and_saveexec_b64 s[52:53], vcc
	s_cmp_lt_u32 s23, 0x100001
	s_cselect_b64 s[26:27], -1, 0
	s_xor_b64 s[50:51], exec, -1
	s_and_b64 s[48:49], s[26:27], exec
	s_or_b64 exec, exec, s[52:53]
.LBB0_1607:
	s_andn2_b64 s[26:27], s[44:45], exec
	s_and_b64 s[44:45], s[50:51], exec
	s_or_b64 s[44:45], s[26:27], s[44:45]
	s_and_saveexec_b64 s[50:51], s[48:49]
	s_cbranch_execz .LBB0_1602
	v_mov_b64_e32 v[6:7], s[38:39]
	global_load_dword v2, v[6:7], off sc1
	s_add_i32 s23, s23, 1
	s_or_b64 s[44:45], s[44:45], exec
	s_waitcnt vmcnt(0) lgkmcnt(0)
	v_cmp_ne_u32_e32 vcc, v2, v5
	s_orn2_b64 s[46:47], vcc, exec
	s_branch .LBB0_1602

; DI unsigned xb_ld(unsigned* p)              { return __hip_atomic_load(p, __ATOMIC_RELAXED, __HIP_MEMORY_SCOPE_AGENT); }
; DI unsigned xb_add(unsigned* p, unsigned v) { return __hip_atomic_fetch_add(p, v, __ATOMIC_RELAXED, __HIP_MEMORY_SCOPE_AGENT); }
; #define XB_SPIN(cond, bar) do { unsigned _sp = 0; while (cond) { __builtin_amdgcn_s_sleep(1); \
;     if ((++_sp & 255u) == 0u) { if (xb_ld(&(bar)[XB_TMO])) break; if (_sp > XB_SPIN_CAP) { atomicAdd(&(bar)[XB_TMO], 1u); break; } } } } while (0)
; DI void xcd_barrier(const XcdBarrier& b) {
;     ...
;         if (old + 1u == (gen + 1u) * nloc) {
;             __builtin_amdgcn_fence(__ATOMIC_RELEASE, "agent");
;             asm volatile("s_waitcnt vmcnt(0)" ::: "memory");
;             const unsigned og = xb_add(&bar[XB_TOP], 1u);
;             const unsigned tg = og / nx;
;             if (og + 1u == (tg + 1u) * nx) xb_add(&bar[XB_TOPGEN], 1u);
;             else XB_SPIN(xb_ld(&bar[XB_TOPGEN]) == tg, bar);
.LBB0_1612:
	s_andn2_saveexec_b64 s[18:19], s[18:19]
	s_cbranch_execz .LBB0_1628
	v_mov_b32_e32 v4, s8
	v_add_co_u32_e32 v4, vcc, 0x3000, v4
	v_mov_b32_e32 v5, s9
	buffer_wbl2 sc1
	s_waitcnt vmcnt(0)
	v_addc_co_u32_e32 v5, vcc, 0, v5, vcc
	flat_atomic_add v4, v[4:5], v218 offset:1024 sc0
	v_cvt_f32_u32_e32 v5, v2
	v_sub_u32_e32 v6, 0, v2
	s_mov_b64 s[38:39], -1
	v_rcp_iflag_f32_e32 v5, v5
	s_nop 0
	v_mul_f32_e32 v5, 0x4f7ffffe, v5
	v_cvt_u32_f32_e32 v5, v5
	v_mul_lo_u32 v6, v6, v5
	v_mul_hi_u32 v6, v5, v6
	v_add_u32_e32 v5, v5, v6
	s_waitcnt vmcnt(0) lgkmcnt(0)
	v_mul_hi_u32 v5, v4, v5
	v_mul_lo_u32 v6, v5, v2
	v_sub_u32_e32 v6, v4, v6
	v_cmp_ge_u32_e32 vcc, v6, v2
	v_add_u32_e32 v7, 1, v5
	s_nop 0
	v_cndmask_b32_e32 v5, v5, v7, vcc
	v_sub_u32_e32 v7, v6, v2
	v_cndmask_b32_e32 v6, v6, v7, vcc
	v_cmp_ge_u32_e32 vcc, v6, v2
	v_add_u32_e32 v6, 1, v5
	v_add_u32_e32 v7, 1, v4
	v_cndmask_b32_e32 v6, v5, v6, vcc
	v_mad_u64_u32 v[4:5], s[18:19], v2, v6, v[2:3]
	s_add_u32 s18, s8, 0x3500
	s_addc_u32 s19, s9, 0
	v_cmp_ne_u32_e32 vcc, v7, v4
	v_mov_b64_e32 v[4:5], s[18:19]
	s_and_saveexec_b64 s[34:35], vcc
	s_cbranch_execz .LBB0_1625
	v_mov_b64_e32 v[4:5], s[18:19]
	global_load_dword v2, v[4:5], off sc1
	s_mov_b64 s[42:43], 0
	s_waitcnt vmcnt(0) lgkmcnt(0)
	v_cmp_eq_u32_e32 vcc, v2, v6
	s_and_saveexec_b64 s[40:41], vcc
	s_cbranch_execz .LBB0_1624
	s_add_u32 s38, s8, 0x200
	s_addc_u32 s39, s9, 0
	s_mov_b32 s23, 1
	s_mov_b64 s[8:9], 0
	s_branch .LBB0_1617

; DI unsigned xb_ld(unsigned* p)              { return __hip_atomic_load(p, __ATOMIC_RELAXED, __HIP_MEMORY_SCOPE_AGENT); }
; #define XB_SPIN(cond, bar) do { unsigned _sp = 0; while (cond) { __builtin_amdgcn_s_sleep(1); \
;     if ((++_sp & 255u) == 0u) { if (xb_ld(&(bar)[XB_TMO])) break; if (_sp > XB_SPIN_CAP) { atomicAdd(&(bar)[XB_TMO], 1u); break; } } } } while (0)
; DI void xcd_barrier(const XcdBarrier& b) {
;     ...
;             else XB_SPIN(xb_ld(&bar[XB_TOPGEN]) == tg, bar);
.LBB0_1619:
	v_mov_b64_e32 v[4:5], s[38:39]
	global_load_dword v2, v[4:5], off sc1
	s_mov_b64 s[48:49], 0
	s_mov_b64 s[46:47], -1
	s_waitcnt vmcnt(0) lgkmcnt(0)
	v_cmp_eq_u32_e32 vcc, 0, v2
	s_and_saveexec_b64 s[50:51], vcc
	s_cmp_lt_u32 s23, 0x100001
	s_cselect_b64 s[26:27], -1, 0
	s_xor_b64 s[46:47], exec, -1
	s_and_b64 s[48:49], s[26:27], exec
	s_or_b64 exec, exec, s[50:51]
	s_and_saveexec_b64 s[50:51], s[48:49]
	s_cbranch_execz .LBB0_1616
.LBB0_1622:
	v_mov_b64_e32 v[4:5], s[18:19]
	global_load_dword v2, v[4:5], off sc1
	s_add_i32 s23, s23, 1
	s_or_b64 s[46:47], s[46:47], exec
	s_waitcnt vmcnt(0) lgkmcnt(0)
	v_cmp_ne_u32_e32 vcc, v2, v6
	s_orn2_b64 s[44:45], vcc, exec
	s_branch .LBB0_1616

; template <int I> DI const float* kin() { return (const float*)karg64<I * 8>(); }
; DI float* kout() { return (float*)karg64<200>(); }
; DI unsigned char* kws() { return (unsigned char*)karg64<208>(); }
; DI float bflo(unsigned w) { return __uint_as_float(w << 16); }
; DI float bfhi(unsigned w) { return __uint_as_float(w & 0xffff0000u); }
; DI void phase_postRes_final(const Ctx& c) {
;     const int gw = c.bid * NWAVES + c.wave, NGW = c.G * NWAVES;
;     const bf16_t* act = (const bf16_t*)(kws() + WS_ACT); const float* part = (const float*)(kws() + WS_PART); const float* ssq = (const float*)(kws() + WS_SSQ);
;     const f32x4* gp = (const f32x4*)kin<24>() + c.lane;
;     f32x4 gv[8];
; #pragma unroll
;     for (int j = 0; j < 8; ++j) gv[j] = gp[64 * j];
;     for (int row = MP + gw; row < M; row += NGW) {
;         const f32x4* pr = (const f32x4*)(part + (size_t)(row - MP) * DM) + c.lane; const size_t st = (size_t)MS * DM / 4;
;         const u32x2* ai = (const u32x2*)(act + (size_t)row * DM) + c.lane; f32x4* yr = (f32x4*)(kout() + (size_t)row * DM) + c.lane;
;         f32x4 v[8]; float s = 0.f;
; #pragma unroll
;         for (int j = 0; j < 8; ++j) { const u32x2 w = ai[64 * j]; const f32x4 xi = {bflo(w.x), bfhi(w.x), bflo(w.y), bfhi(w.y)};
;             v[j] = xi + ((pr[64 * j] + pr[st + 64 * j]) + (pr[2 * st + 64 * j] + pr[3 * st + 64 * j])); s += (v[j][0] * v[j][0] + v[j][1] * v[j][1]) + (v[j][2] * v[j][2] + v[j][3] * v[j][3]); }
.LBB0_1631:
	v_lshlrev_b32_e32 v2, 4, v1
	s_load_dwordx2 s[4:5], s[0:1], 0xd0
	s_waitcnt lgkmcnt(0)
	s_load_dwordx2 s[8:9], s[0:1], 0xd0
	s_waitcnt lgkmcnt(0)
	s_load_dwordx2 s[38:39], s[0:1], 0xd0
	s_waitcnt lgkmcnt(0)
	s_load_dwordx2 s[18:19], s[0:1], 0xc0
	s_waitcnt lgkmcnt(0)
	v_readlane_b32 s12, v253, 2
	v_lshl_add_u64 v[20:21], s[18:19], 0, v[2:3]
	v_add_co_u32_e32 v32, vcc, 0x1000, v20
	global_load_dwordx4 v[4:7], v[20:21], off
	global_load_dwordx4 v[8:11], v[20:21], off offset:1024
	global_load_dwordx4 v[12:15], v[20:21], off offset:2048
	global_load_dwordx4 v[16:19], v[20:21], off offset:3072
	v_addc_co_u32_e32 v33, vcc, 0, v21, vcc
	global_load_dwordx4 v[20:23], v[32:33], off
	global_load_dwordx4 v[24:27], v[32:33], off offset:1024
	global_load_dwordx4 v[28:31], v[32:33], off offset:2048
	s_nop 0
	global_load_dwordx4 v[32:35], v[32:33], off offset:3072
	s_add_i32 s18, s11, s12
	s_waitcnt lgkmcnt(0)
	s_lshl_b32 s34, s10, 3
	s_mov_b32 s22, 0x1001000
	s_mov_b32 s23, 0x2001000
	s_mov_b32 s26, 0x3001000
	s_movk_i32 s27, 0xf400
	s_movk_i32 s48, 0xf800
	s_cmpk_gt_i32 s18, 0x7ff
	v_lshlrev_b32_e32 v36, 3, v1
	s_cbranch_scc1 .LBB0_1634
	s_add_i32 s10, s18, 0x4000
	v_lshl_add_u64 v[38:39], s[8:9], 0, v[2:3]
	s_mov_b64 s[8:9], 0x4c656000
	s_ashr_i32 s11, s10, 31
	v_lshl_add_u64 v[38:39], v[38:39], 0, s[8:9]
	s_lshl_b64 s[8:9], s[10:11], 12
	s_add_u32 s8, s4, s8
	v_mov_b32_e32 v37, v3
	s_addc_u32 s9, s5, s9
	v_lshl_add_u64 v[40:41], s[8:9], 0, v[36:37]
	s_mov_b64 s[8:9], 0x21c56000
	v_lshl_add_u64 v[40:41], v[40:41], 0, s[8:9]
	s_lshl_b64 s[8:9], s[10:11], 13
	s_ashr_i32 s35, s34, 31
	v_or_b32_e32 v2, s8, v2
	s_lshl_b64 s[42:43], s[34:35], 12
	s_movk_i32 s11, 0xfc00
	v_or_b32_e32 v42, 0x1000, v2
	v_mov_b32_e32 v43, s9
	s_lshl_b64 s[44:45], s[34:35], 13
	s_mov_b32 s46, s18
.LBB0_1633:
	s_ashr_i32 s47, s46, 31
	s_lshl_b64 s[8:9], s[46:47], 13
	v_lshl_add_u64 v[60:61], v[38:39], 0, s[8:9]
	s_load_dwordx2 s[8:9], s[0:1], 0xc8
	s_waitcnt lgkmcnt(0)
	global_load_dwordx2 v[44:45], v[40:41], off
	v_add_co_u32_e32 v56, vcc, s97, v60
	s_brev_b32 s10, 64
	s_nop 0
	v_addc_co_u32_e32 v57, vcc, 0, v61, vcc
	v_add_co_u32_e32 v58, vcc, s10, v60
	s_mov_b32 s10, 0x3000000
	s_nop 0
	v_addc_co_u32_e32 v59, vcc, 0, v61, vcc
	v_add_co_u32_e32 v62, vcc, s10, v60
	s_add_i32 s46, s46, s34
	s_nop 0
	v_addc_co_u32_e32 v63, vcc, 0, v61, vcc
	global_load_dwordx4 v[48:51], v[56:57], off
	s_waitcnt vmcnt(0) lgkmcnt(0)
	v_lshlrev_b32_e32 v52, 16, v44
	v_and_b32_e32 v53, 0xffff0000, v44
	v_lshlrev_b32_e32 v54, 16, v45
	v_and_b32_e32 v55, 0xffff0000, v45
	global_load_dwordx4 v[44:47], v[60:61], off
	s_waitcnt vmcnt(0) lgkmcnt(0)
	v_pk_add_f32 v[64:65], v[46:47], v[50:51]
	v_pk_add_f32 v[66:67], v[44:45], v[48:49]
	global_load_dwordx4 v[44:47], v[58:59], off
	global_load_dwordx4 v[48:51], v[62:63], off
	s_waitcnt vmcnt(0) lgkmcnt(0)
	v_pk_add_f32 v[46:47], v[46:47], v[50:51]
	v_pk_add_f32 v[44:45], v[44:45], v[48:49]
	v_pk_add_f32 v[46:47], v[64:65], v[46:47]
	v_pk_add_f32 v[48:49], v[66:67], v[44:45]
	v_pk_add_f32 v[44:45], v[46:47], v[54:55]
	v_pk_add_f32 v[46:47], v[48:49], v[52:53]
	global_load_dwordx2 v[48:49], v[40:41], off offset:512
	s_waitcnt vmcnt(0) lgkmcnt(0)
	v_lshlrev_b32_e32 v64, 16, v48
	v_and_b32_e32 v65, 0xffff0000, v48
	v_lshlrev_b32_e32 v66, 16, v49
	v_and_b32_e32 v67, 0xffff0000, v49
	global_load_dwordx4 v[48:51], v[60:61], off offset:1024
	global_load_dwordx4 v[52:55], v[56:57], off offset:1024
	s_waitcnt vmcnt(0) lgkmcnt(0)
	v_pk_add_f32 v[68:69], v[50:51], v[54:55]
	v_pk_add_f32 v[70:71], v[48:49], v[52:53]
	global_load_dwordx4 v[48:51], v[58:59], off offset:1024
	global_load_dwordx4 v[52:55], v[62:63], off offset:1024
	s_waitcnt vmcnt(0) lgkmcnt(0)
	v_pk_add_f32 v[50:51], v[50:51], v[54:55]
	v_pk_add_f32 v[48:49], v[48:49], v[52:53]
	v_pk_add_f32 v[50:51], v[68:69], v[50:51]
	v_pk_add_f32 v[52:53], v[70:71], v[48:49]
	v_pk_add_f32 v[48:49], v[50:51], v[66:67]
	v_pk_add_f32 v[50:51], v[52:53], v[64:65]
	v_mov_b32_e32 v54, v47
	v_mov_b32_e32 v55, v51
	v_mov_b32_e32 v52, v46
	v_mov_b32_e32 v53, v50
	v_pk_mul_f32 v[54:55], v[54:55], v[54:55]
	v_mov_b32_e32 v64, v45
	v_mov_b32_e32 v65, v49
	v_pk_fma_f32 v[52:53], v[52:53], v[52:53], v[54:55]
	v_mov_b32_e32 v54, v44
	v_mov_b32_e32 v55, v48
	v_pk_mul_f32 v[64:65], v[64:65], v[64:65]
	s_nop 0
	v_pk_fma_f32 v[54:55], v[54:55], v[54:55], v[64:65]
	s_nop 0
	v_pk_add_f32 v[64:65], v[52:53], v[54:55]
	global_load_dwordx2 v[52:53], v[40:41], off offset:1024
	v_pk_add_f32 v[64:65], v[64:65], v[64:65] op_sel:[0,1] op_sel_hi:[1,0]
	s_waitcnt vmcnt(0) lgkmcnt(0)
	v_lshlrev_b32_e32 v70, 16, v52
	v_and_b32_e32 v71, 0xffff0000, v52
	v_lshlrev_b32_e32 v72, 16, v53
	v_and_b32_e32 v73, 0xffff0000, v53
	global_load_dwordx4 v[52:55], v[60:61], off offset:2048
	global_load_dwordx4 v[66:69], v[56:57], off offset:2048
	s_waitcnt vmcnt(0) lgkmcnt(0)
	v_pk_add_f32 v[74:75], v[54:55], v[68:69]
	v_pk_add_f32 v[76:77], v[52:53], v[66:67]
	global_load_dwordx4 v[52:55], v[58:59], off offset:2048
	global_load_dwordx4 v[66:69], v[62:63], off offset:2048
	s_waitcnt vmcnt(0) lgkmcnt(0)
	v_pk_add_f32 v[54:55], v[54:55], v[68:69]
	v_pk_add_f32 v[52:53], v[52:53], v[66:67]
	v_pk_add_f32 v[54:55], v[74:75], v[54:55]
	v_pk_add_f32 v[66:67], v[76:77], v[52:53]
	v_pk_add_f32 v[52:53], v[54:55], v[72:73]
	v_pk_add_f32 v[54:55], v[66:67], v[70:71]
	v_pk_mul_f32 v[66:67], v[52:53], v[52:53]
	v_pk_mul_f32 v[68:69], v[54:55], v[54:55]
	s_nop 0
	v_pk_mov_b32 v[70:71], v[68:69], v[66:67] op_sel:[1,0]
	v_mov_b32_e32 v69, v67
	global_load_dwordx2 v[66:67], v[40:41], off offset:1536
	v_pk_add_f32 v[80:81], v[70:71], v[68:69]
	s_waitcnt vmcnt(0) lgkmcnt(0)
; DI float* kout() { return (float*)karg64<200>(); }
; DI float bflo(unsigned w) { return __uint_as_float(w << 16); }
; DI float bfhi(unsigned w) { return __uint_as_float(w & 0xffff0000u); }
; DI void phase_postRes_final(const Ctx& c) {
;     ...
;     for (int row = MP + gw; row < M; row += NGW) {
;         const f32x4* pr = (const f32x4*)(part + (size_t)(row - MP) * DM) + c.lane; const size_t st = (size_t)MS * DM / 4;
;         const u32x2* ai = (const u32x2*)(act + (size_t)row * DM) + c.lane; f32x4* yr = (f32x4*)(kout() + (size_t)row * DM) + c.lane;
;         f32x4 v[8]; float s = 0.f;
; #pragma unroll
;         for (int j = 0; j < 8; ++j) { const u32x2 w = ai[64 * j]; const f32x4 xi = {bflo(w.x), bfhi(w.x), bflo(w.y), bfhi(w.y)};
;             v[j] = xi + ((pr[64 * j] + pr[st + 64 * j]) + (pr[2 * st + 64 * j] + pr[3 * st + 64 * j])); s += (v[j][0] * v[j][0] + v[j][1] * v[j][1]) + (v[j][2] * v[j][2] + v[j][3] * v[j][3]); }
	v_lshlrev_b32_e32 v74, 16, v66
	v_and_b32_e32 v75, 0xffff0000, v66
	v_lshlrev_b32_e32 v76, 16, v67
	v_and_b32_e32 v77, 0xffff0000, v67
	global_load_dwordx4 v[66:69], v[60:61], off offset:3072
	global_load_dwordx4 v[70:73], v[56:57], off offset:3072
	s_waitcnt vmcnt(0) lgkmcnt(0)
	v_pk_add_f32 v[72:73], v[68:69], v[72:73]
	v_pk_add_f32 v[70:71], v[66:67], v[70:71]
	global_load_dwordx4 v[56:59], v[58:59], off offset:3072
	s_nop 0
	global_load_dwordx4 v[66:69], v[62:63], off offset:3072
	s_waitcnt vmcnt(0) lgkmcnt(0)
	v_pk_add_f32 v[58:59], v[58:59], v[68:69]
	v_pk_add_f32 v[56:57], v[56:57], v[66:67]
	v_pk_add_f32 v[58:59], v[72:73], v[58:59]
	v_add_co_u32_e32 v72, vcc, s33, v60
	v_pk_add_f32 v[62:63], v[70:71], v[56:57]
	s_nop 0
	v_addc_co_u32_e32 v73, vcc, 0, v61, vcc
	v_pk_add_f32 v[56:57], v[58:59], v[76:77]
	v_pk_add_f32 v[58:59], v[62:63], v[74:75]
	v_add_co_u32_e32 v74, vcc, s22, v60
	global_load_dwordx4 v[66:69], v[72:73], off
	s_nop 0
	v_addc_co_u32_e32 v75, vcc, 0, v61, vcc
	global_load_dwordx4 v[76:79], v[74:75], off
	global_load_dwordx2 v[62:63], v[40:41], off offset:2048
	s_waitcnt vmcnt(0) lgkmcnt(0)
	v_pk_add_f32 v[86:87], v[66:67], v[76:77]
	v_add_co_u32_e32 v76, vcc, s23, v60
	v_pk_add_f32 v[84:85], v[68:69], v[78:79]
	s_nop 0
	v_addc_co_u32_e32 v77, vcc, 0, v61, vcc
	v_add_co_u32_e32 v78, vcc, s26, v60
	v_lshlrev_b32_e32 v70, 16, v62
	s_nop 0
	v_addc_co_u32_e32 v79, vcc, 0, v61, vcc
	v_and_b32_e32 v71, 0xffff0000, v62
	v_lshlrev_b32_e32 v82, 16, v63
	v_and_b32_e32 v83, 0xffff0000, v63
	global_load_dwordx4 v[66:69], v[76:77], off
	global_load_dwordx4 v[60:63], v[78:79], off
	s_waitcnt vmcnt(0) lgkmcnt(0)
	v_pk_add_f32 v[62:63], v[68:69], v[62:63]
	v_pk_add_f32 v[60:61], v[66:67], v[60:61]
	v_pk_add_f32 v[62:63], v[84:85], v[62:63]
	v_pk_add_f32 v[66:67], v[86:87], v[60:61]
	v_pk_add_f32 v[60:61], v[62:63], v[82:83]
	v_pk_add_f32 v[62:63], v[66:67], v[70:71]
	v_pk_add_f32 v[66:67], v[80:81], v[80:81] op_sel:[0,1] op_sel_hi:[1,0]
	v_mul_f32_e32 v2, v62, v62
	v_mul_f32_e32 v37, v63, v63
	v_mov_b32_e32 v65, v2
	v_mov_b32_e32 v67, v37
	v_mul_f32_e32 v2, v59, v59
	v_mul_f32_e32 v68, v60, v60
	v_pk_add_f32 v[64:65], v[64:65], v[66:67]
	v_pk_fma_f32 v[66:67], v[58:59], v[58:59], v[2:3] op_sel_hi:[1,1,0]
	v_mul_f32_e32 v2, v57, v57
	v_mul_f32_e32 v70, v61, v61
	v_mov_b32_e32 v67, v68
	v_pk_fma_f32 v[68:69], v[56:57], v[56:57], v[2:3] op_sel_hi:[1,1,0]
	s_nop 0
	v_mov_b32_e32 v69, v70
	v_pk_add_f32 v[66:67], v[66:67], v[68:69]
	s_nop 0
	v_pk_add_f32 v[80:81], v[64:65], v[66:67]
	global_load_dwordx2 v[64:65], v[40:41], off offset:2560
	s_waitcnt vmcnt(0) lgkmcnt(0)
	v_lshlrev_b32_e32 v82, 16, v64
	v_and_b32_e32 v83, 0xffff0000, v64
	v_lshlrev_b32_e32 v84, 16, v65
	v_and_b32_e32 v85, 0xffff0000, v65
	global_load_dwordx4 v[64:67], v[72:73], off offset:1024
	global_load_dwordx4 v[68:71], v[74:75], off offset:1024
	s_waitcnt vmcnt(0) lgkmcnt(0)
	v_pk_add_f32 v[86:87], v[66:67], v[70:71]
	v_pk_add_f32 v[88:89], v[64:65], v[68:69]
	global_load_dwordx4 v[64:67], v[76:77], off offset:1024
	global_load_dwordx4 v[68:71], v[78:79], off offset:1024
	s_waitcnt vmcnt(0) lgkmcnt(0)
	v_pk_add_f32 v[66:67], v[66:67], v[70:71]
	v_pk_add_f32 v[64:65], v[64:65], v[68:69]
	v_pk_add_f32 v[66:67], v[86:87], v[66:67]
	v_pk_add_f32 v[68:69], v[88:89], v[64:65]
	v_pk_add_f32 v[64:65], v[66:67], v[84:85]
	v_pk_add_f32 v[66:67], v[68:69], v[82:83]
	v_pk_mul_f32 v[68:69], v[64:65], v[64:65]
	v_pk_mul_f32 v[70:71], v[66:67], v[66:67]
	s_nop 0
	v_pk_mov_b32 v[82:83], v[70:71], v[68:69] op_sel:[1,0]
	v_mov_b32_e32 v71, v69
	global_load_dwordx2 v[68:69], v[40:41], off offset:3072
	v_pk_add_f32 v[86:87], v[82:83], v[70:71]
	s_waitcnt vmcnt(0) lgkmcnt(0)
	v_lshlrev_b32_e32 v88, 16, v68
	v_and_b32_e32 v89, 0xffff0000, v68
	v_lshlrev_b32_e32 v90, 16, v69
	v_and_b32_e32 v91, 0xffff0000, v69
	global_load_dwordx4 v[68:71], v[72:73], off offset:2048
	global_load_dwordx4 v[82:85], v[74:75], off offset:2048
	s_waitcnt vmcnt(0) lgkmcnt(0)
	v_pk_add_f32 v[92:93], v[70:71], v[84:85]
	v_pk_add_f32 v[94:95], v[68:69], v[82:83]
	global_load_dwordx4 v[68:71], v[76:77], off offset:2048
	global_load_dwordx4 v[82:85], v[78:79], off offset:2048
	s_waitcnt vmcnt(0) lgkmcnt(0)
	v_pk_add_f32 v[70:71], v[70:71], v[84:85]
	v_pk_add_f32 v[68:69], v[68:69], v[82:83]
	v_pk_add_f32 v[70:71], v[92:93], v[70:71]
	v_pk_add_f32 v[82:83], v[94:95], v[68:69]
	v_pk_add_f32 v[68:69], v[70:71], v[90:91]
	v_pk_add_f32 v[70:71], v[82:83], v[88:89]
	global_load_dwordx2 v[82:83], v[40:41], off offset:3584
	v_lshl_add_u64 v[40:41], v[40:41], 0, s[42:43]
	s_waitcnt vmcnt(0) lgkmcnt(0)
	v_lshlrev_b32_e32 v88, 16, v82
	v_and_b32_e32 v89, 0xffff0000, v82
	v_lshlrev_b32_e32 v90, 16, v83
	v_and_b32_e32 v91, 0xffff0000, v83
	global_load_dwordx4 v[82:85], v[72:73], off offset:3072
	s_nop 0
	global_load_dwordx4 v[72:75], v[74:75], off offset:3072
	s_waitcnt vmcnt(0) lgkmcnt(0)
	v_pk_add_f32 v[84:85], v[84:85], v[74:75]
	v_pk_add_f32 v[82:83], v[82:83], v[72:73]
	global_load_dwordx4 v[72:75], v[76:77], off offset:3072
	s_nop 0
	global_load_dwordx4 v[76:79], v[78:79], off offset:3072
	s_waitcnt vmcnt(0) lgkmcnt(0)
; DI void phase_postRes_final(const Ctx& c) {
;     ...
;             v[j] = xi + ((pr[64 * j] + pr[st + 64 * j]) + (pr[2 * st + 64 * j] + pr[3 * st + 64 * j])); s += (v[j][0] * v[j][0] + v[j][1] * v[j][1]) + (v[j][2] * v[j][2] + v[j][3] * v[j][3]); }
;         s = wave_sum(s); const float r = 1.0f / sqrtf(s * (1.0f / DM) + EPS);
; #pragma unroll
;         for (int j = 0; j < 8; ++j) yr[64 * j] = v[j] * r * gv[j];
;     }
	v_pk_add_f32 v[74:75], v[74:75], v[78:79]
	v_pk_add_f32 v[72:73], v[72:73], v[76:77]
	v_pk_add_f32 v[74:75], v[84:85], v[74:75]
	v_pk_add_f32 v[76:77], v[82:83], v[72:73]
	v_pk_add_f32 v[72:73], v[74:75], v[90:91]
	v_pk_add_f32 v[74:75], v[76:77], v[88:89]
	v_pk_add_f32 v[76:77], v[80:81], v[80:81] op_sel:[0,1] op_sel_hi:[1,0]
	v_mul_f32_e32 v2, v74, v74
	v_mul_f32_e32 v37, v75, v75
	v_pk_add_f32 v[78:79], v[86:87], v[86:87] op_sel:[0,1] op_sel_hi:[1,0]
	v_mov_b32_e32 v77, v2
	v_mov_b32_e32 v79, v37
	v_mul_f32_e32 v2, v71, v71
	v_pk_add_f32 v[76:77], v[76:77], v[78:79]
	v_pk_fma_f32 v[78:79], v[70:71], v[70:71], v[2:3] op_sel_hi:[1,1,0]
	v_mul_f32_e32 v2, v69, v69
	v_mul_f32_e32 v82, v72, v72
	v_mul_f32_e32 v83, v73, v73
	v_pk_fma_f32 v[80:81], v[68:69], v[68:69], v[2:3] op_sel_hi:[1,1,0]
	v_mov_b32_e32 v79, v82
	v_mov_b32_e32 v81, v83
	v_pk_add_f32 v[78:79], v[78:79], v[80:81]
	v_and_b32_e32 v37, 64, v223
	v_pk_add_f32 v[76:77], v[76:77], v[78:79]
	v_add_u32_e32 v37, 64, v37
	v_xor_b32_e32 v78, 1, v223
	v_cmp_lt_i32_e32 vcc, v78, v37
	v_add_f32_e32 v2, v76, v77
	v_lshl_add_u64 v[76:77], s[8:9], 0, v[42:43]
	v_cndmask_b32_e32 v78, v223, v78, vcc
	v_lshlrev_b32_e32 v78, 2, v78
	ds_bpermute_b32 v78, v78, v2
	v_lshl_add_u64 v[42:43], v[42:43], 0, s[44:45]
	s_waitcnt lgkmcnt(0)
	v_add_f32_e32 v2, v2, v78
	v_xor_b32_e32 v78, 2, v223
	v_cmp_lt_i32_e32 vcc, v78, v37
	s_nop 1
	v_cndmask_b32_e32 v78, v223, v78, vcc
	v_lshlrev_b32_e32 v78, 2, v78
	ds_bpermute_b32 v78, v78, v2
	s_waitcnt lgkmcnt(0)
	v_add_f32_e32 v2, v2, v78
	v_xor_b32_e32 v78, 4, v223
	v_cmp_lt_i32_e32 vcc, v78, v37
	s_nop 1
	v_cndmask_b32_e32 v78, v223, v78, vcc
	v_lshlrev_b32_e32 v78, 2, v78
	ds_bpermute_b32 v78, v78, v2
	s_waitcnt lgkmcnt(0)
	v_add_f32_e32 v2, v2, v78
	v_xor_b32_e32 v78, 8, v223
	v_cmp_lt_i32_e32 vcc, v78, v37
	s_nop 1
	v_cndmask_b32_e32 v78, v223, v78, vcc
	v_lshlrev_b32_e32 v78, 2, v78
	ds_bpermute_b32 v78, v78, v2
	s_waitcnt lgkmcnt(0)
	v_add_f32_e32 v2, v2, v78
	v_xor_b32_e32 v78, 16, v223
	v_cmp_lt_i32_e32 vcc, v78, v37
	s_nop 1
	v_cndmask_b32_e32 v78, v223, v78, vcc
	v_lshlrev_b32_e32 v78, 2, v78
	ds_bpermute_b32 v78, v78, v2
	s_waitcnt lgkmcnt(0)
	v_add_f32_e32 v2, v2, v78
	v_xor_b32_e32 v78, 32, v223
	v_cmp_lt_i32_e32 vcc, v78, v37
	s_nop 1
	v_cndmask_b32_e32 v37, v223, v78, vcc
	v_lshlrev_b32_e32 v37, 2, v37
	ds_bpermute_b32 v37, v37, v2
	s_waitcnt lgkmcnt(0)
	v_add_f32_e32 v2, v2, v37
	v_fmamk_f32 v2, v2, 0x3a000000, v220
	v_cmp_gt_f32_e32 vcc, s84, v2
	v_mul_f32_e32 v37, 0x4f800000, v2
	s_nop 0
	v_cndmask_b32_e32 v2, v2, v37, vcc
	v_sqrt_f32_e32 v37, v2
	s_nop 0
	v_add_u32_e32 v78, -1, v37
	v_fma_f32 v79, -v78, v37, v2
	v_cmp_ge_f32_e64 s[40:41], 0, v79
	v_add_u32_e32 v79, 1, v37
	s_nop 0
	v_cndmask_b32_e64 v78, v37, v78, s[40:41]
	v_fma_f32 v37, -v79, v37, v2
	v_cmp_lt_f32_e64 s[40:41], 0, v37
	s_nop 1
	v_cndmask_b32_e64 v37, v78, v79, s[40:41]
	v_mul_f32_e32 v78, 0x37800000, v37
	v_cndmask_b32_e32 v37, v37, v78, vcc
	v_cmp_class_f32_e32 vcc, v2, v221
	s_nop 1
	v_cndmask_b32_e32 v2, v37, v2, vcc
	v_div_scale_f32 v37, s[8:9], v2, v2, 1.0
	v_rcp_f32_e32 v78, v37
	s_add_i32 s8, s46, 0x4000
	s_cmpk_gt_i32 s8, 0x47ff
	v_fma_f32 v79, -v37, v78, 1.0
	v_fmac_f32_e32 v78, v79, v78
	v_div_scale_f32 v79, vcc, 1.0, v2, 1.0
	v_mul_f32_e32 v80, v79, v78
	v_fma_f32 v81, -v37, v80, v79
	v_fmac_f32_e32 v80, v81, v78
	v_fma_f32 v37, -v37, v80, v79
	v_div_fmas_f32 v37, v37, v78, v80
	v_div_fixup_f32 v2, v37, v2, 1.0
	v_pk_mul_f32 v[78:79], v[46:47], v[2:3] op_sel_hi:[1,0]
	v_pk_mul_f32 v[44:45], v[44:45], v[2:3] op_sel_hi:[1,0]
	s_nop 0
	v_pk_mul_f32 v[46:47], v[6:7], v[44:45]
	v_pk_mul_f32 v[44:45], v[4:5], v[78:79]
	v_add_co_u32_e32 v78, vcc, s88, v76
	s_nop 1
	v_addc_co_u32_e32 v79, vcc, -1, v77, vcc
	global_store_dwordx4 v[78:79], v[44:47], off
	s_nop 1
	v_pk_mul_f32 v[44:45], v[50:51], v[2:3] op_sel_hi:[1,0]
	v_pk_mul_f32 v[46:47], v[48:49], v[2:3] op_sel_hi:[1,0]
	v_add_co_u32_e32 v48, vcc, s27, v76
	v_pk_mul_f32 v[46:47], v[10:11], v[46:47]
	v_pk_mul_f32 v[44:45], v[8:9], v[44:45]
	v_addc_co_u32_e32 v49, vcc, -1, v77, vcc
	global_store_dwordx4 v[48:49], v[44:47], off
	v_add_co_u32_e32 v48, vcc, s48, v76
	s_nop 0
	v_pk_mul_f32 v[44:45], v[54:55], v[2:3] op_sel_hi:[1,0]
	v_pk_mul_f32 v[46:47], v[52:53], v[2:3] op_sel_hi:[1,0]
	v_pk_mul_f32 v[44:45], v[12:13], v[44:45]
	v_pk_mul_f32 v[46:47], v[14:15], v[46:47]
	v_addc_co_u32_e32 v49, vcc, -1, v77, vcc
	global_store_dwordx4 v[48:49], v[44:47], off
	v_add_co_u32_e32 v48, vcc, s11, v76
	s_nop 0
	v_pk_mul_f32 v[44:45], v[58:59], v[2:3] op_sel_hi:[1,0]
	v_pk_mul_f32 v[46:47], v[56:57], v[2:3] op_sel_hi:[1,0]
	v_pk_mul_f32 v[44:45], v[16:17], v[44:45]
	v_pk_mul_f32 v[46:47], v[18:19], v[46:47]
	v_addc_co_u32_e32 v49, vcc, -1, v77, vcc
	global_store_dwordx4 v[48:49], v[44:47], off
	s_nop 1
	v_pk_mul_f32 v[44:45], v[62:63], v[2:3] op_sel_hi:[1,0]
	v_pk_mul_f32 v[46:47], v[60:61], v[2:3] op_sel_hi:[1,0]
	v_pk_mul_f32 v[44:45], v[20:21], v[44:45]
	v_pk_mul_f32 v[46:47], v[22:23], v[46:47]
	global_store_dwordx4 v[76:77], v[44:47], off
	s_nop 1
	v_pk_mul_f32 v[44:45], v[66:67], v[2:3] op_sel_hi:[1,0]
	v_pk_mul_f32 v[46:47], v[64:65], v[2:3] op_sel_hi:[1,0]
	v_pk_mul_f32 v[44:45], v[24:25], v[44:45]
	v_pk_mul_f32 v[46:47], v[26:27], v[46:47]
	global_store_dwordx4 v[76:77], v[44:47], off offset:1024
	s_nop 1
	v_pk_mul_f32 v[44:45], v[70:71], v[2:3] op_sel_hi:[1,0]
	v_pk_mul_f32 v[46:47], v[68:69], v[2:3] op_sel_hi:[1,0]
	v_pk_mul_f32 v[44:45], v[28:29], v[44:45]
	v_pk_mul_f32 v[46:47], v[30:31], v[46:47]
	global_store_dwordx4 v[76:77], v[44:47], off offset:2048
	s_nop 1
	v_pk_mul_f32 v[44:45], v[74:75], v[2:3] op_sel_hi:[1,0]
	v_pk_mul_f32 v[46:47], v[72:73], v[2:3] op_sel_hi:[1,0]
	v_pk_mul_f32 v[44:45], v[32:33], v[44:45]
	v_pk_mul_f32 v[46:47], v[34:35], v[46:47]
	global_store_dwordx4 v[76:77], v[44:47], off offset:3072
	s_cbranch_scc0 .LBB0_1633

; DI float* kout() { return (float*)karg64<200>(); }
; DI float bflo(unsigned w) { return __uint_as_float(w << 16); }
; DI float bfhi(unsigned w) { return __uint_as_float(w & 0xffff0000u); }
; DI void phase_postRes_final(const Ctx& c) {
;     ...
;     for (int row = gw; row < MP; row += NGW) {
;         float s = c.lane < 32 ? ssq[(size_t)row * 32 + c.lane] : 0.f; s = wave_sum(s); const float r = 1.0f / sqrtf(s * (1.0f / DM) + EPS);
;         const u32x2* xr = (const u32x2*)(act + (size_t)row * DM) + c.lane; f32x4* yr = (f32x4*)(kout() + (size_t)row * DM) + c.lane;
; #pragma unroll
;         for (int j = 0; j < 8; ++j) { const u32x2 w = xr[64 * j]; yr[64 * j] = (f32x4){bflo(w.x), bfhi(w.x), bflo(w.y), bfhi(w.y)} * r * gv[j]; }
;     }
.LBB0_1636:
	s_or_b64 exec, exec, s[42:43]
	s_waitcnt vmcnt(0) lgkmcnt(0)
	ds_bpermute_b32 v2, v44, v1
	s_add_i32 s18, s18, s34
	v_lshl_add_u64 v[38:39], v[38:39], 0, s[8:9]
	s_cmpk_gt_i32 s18, 0x3fff
	s_waitcnt lgkmcnt(0)
	v_add_f32_e32 v1, v1, v2
	ds_bpermute_b32 v2, v45, v1
	s_waitcnt lgkmcnt(0)
	v_add_f32_e32 v1, v1, v2
	ds_bpermute_b32 v2, v46, v1
	s_waitcnt lgkmcnt(0)
	v_add_f32_e32 v1, v1, v2
	ds_bpermute_b32 v2, v47, v1
	s_waitcnt lgkmcnt(0)
	v_add_f32_e32 v1, v1, v2
	ds_bpermute_b32 v2, v48, v1
	s_waitcnt lgkmcnt(0)
	v_add_f32_e32 v1, v1, v2
	ds_bpermute_b32 v2, v49, v1
	s_waitcnt lgkmcnt(0)
	v_add_f32_e32 v1, v1, v2
	v_fmamk_f32 v1, v1, 0x3a000000, v220
	v_cmp_gt_f32_e32 vcc, s84, v1
	v_mul_f32_e32 v2, 0x4f800000, v1
	s_nop 0
	v_cndmask_b32_e32 v1, v1, v2, vcc
	v_sqrt_f32_e32 v2, v1
	s_nop 0
	v_add_u32_e32 v42, -1, v2
	v_fma_f32 v43, -v42, v2, v1
	v_cmp_ge_f32_e64 s[42:43], 0, v43
	v_add_u32_e32 v43, 1, v2
	s_nop 0
	v_cndmask_b32_e64 v42, v2, v42, s[42:43]
	v_fma_f32 v2, -v43, v2, v1
	v_cmp_lt_f32_e64 s[42:43], 0, v2
	s_nop 1
	v_cndmask_b32_e64 v2, v42, v43, s[42:43]
	v_mul_f32_e32 v42, 0x37800000, v2
	v_cndmask_b32_e32 v2, v2, v42, vcc
	v_cmp_class_f32_e32 vcc, v1, v221
	s_nop 1
	v_cndmask_b32_e32 v1, v2, v1, vcc
	v_div_scale_f32 v2, s[10:11], v1, v1, 1.0
	v_rcp_f32_e32 v42, v2
	s_load_dwordx2 s[10:11], s[0:1], 0xc8
	s_waitcnt lgkmcnt(0)
	s_nop 0
	v_fma_f32 v43, -v2, v42, 1.0
	v_fmac_f32_e32 v42, v43, v42
	v_div_scale_f32 v43, vcc, 1.0, v1, 1.0
	v_mul_f32_e32 v50, v43, v42
	v_fma_f32 v51, -v2, v50, v43
	v_fmac_f32_e32 v50, v51, v42
	v_fma_f32 v2, -v2, v50, v43
	v_div_fmas_f32 v2, v2, v42, v50
	global_load_dwordx2 v[50:51], v[36:37], off
	v_div_fixup_f32 v2, v2, v1, 1.0
	v_lshl_add_u64 v[42:43], s[10:11], 0, v[40:41]
	v_lshl_add_u64 v[40:41], v[40:41], 0, s[38:39]
	s_waitcnt vmcnt(0) lgkmcnt(0)
	v_lshlrev_b32_e32 v52, 16, v50
	v_and_b32_e32 v53, 0xffff0000, v50
	v_lshlrev_b32_e32 v50, 16, v51
	v_and_b32_e32 v51, 0xffff0000, v51
	v_pk_mul_f32 v[54:55], v[2:3], v[52:53] op_sel_hi:[0,1]
	v_pk_mul_f32 v[50:51], v[2:3], v[50:51] op_sel_hi:[0,1]
	v_pk_mul_f32 v[52:53], v[6:7], v[50:51]
	v_pk_mul_f32 v[50:51], v[4:5], v[54:55]
	v_add_co_u32_e32 v54, vcc, s88, v42
	s_nop 1
	v_addc_co_u32_e32 v55, vcc, -1, v43, vcc
	global_store_dwordx4 v[54:55], v[50:53], off
	global_load_dwordx2 v[50:51], v[36:37], off offset:512
	s_waitcnt vmcnt(0) lgkmcnt(0)
	v_lshlrev_b32_e32 v52, 16, v50
	v_and_b32_e32 v53, 0xffff0000, v50
	v_lshlrev_b32_e32 v50, 16, v51
	v_and_b32_e32 v51, 0xffff0000, v51
	v_pk_mul_f32 v[54:55], v[2:3], v[52:53] op_sel_hi:[0,1]
	v_pk_mul_f32 v[50:51], v[2:3], v[50:51] op_sel_hi:[0,1]
	v_pk_mul_f32 v[52:53], v[10:11], v[50:51]
	v_pk_mul_f32 v[50:51], v[8:9], v[54:55]
	v_add_co_u32_e32 v54, vcc, s22, v42
	s_nop 1
	v_addc_co_u32_e32 v55, vcc, -1, v43, vcc
	global_store_dwordx4 v[54:55], v[50:53], off
	global_load_dwordx2 v[50:51], v[36:37], off offset:1024
	s_waitcnt vmcnt(0) lgkmcnt(0)
	v_lshlrev_b32_e32 v52, 16, v50
	v_and_b32_e32 v53, 0xffff0000, v50
	v_lshlrev_b32_e32 v50, 16, v51
	v_and_b32_e32 v51, 0xffff0000, v51
	v_pk_mul_f32 v[54:55], v[2:3], v[52:53] op_sel_hi:[0,1]
	v_pk_mul_f32 v[50:51], v[2:3], v[50:51] op_sel_hi:[0,1]
	v_pk_mul_f32 v[52:53], v[14:15], v[50:51]
	v_pk_mul_f32 v[50:51], v[12:13], v[54:55]
	v_add_co_u32_e32 v54, vcc, s23, v42
	s_nop 1
	v_addc_co_u32_e32 v55, vcc, -1, v43, vcc
	global_store_dwordx4 v[54:55], v[50:53], off
	global_load_dwordx2 v[50:51], v[36:37], off offset:1536
	s_waitcnt vmcnt(0) lgkmcnt(0)
	v_lshlrev_b32_e32 v52, 16, v50
	v_and_b32_e32 v53, 0xffff0000, v50
	v_lshlrev_b32_e32 v50, 16, v51
	v_and_b32_e32 v51, 0xffff0000, v51
	v_pk_mul_f32 v[54:55], v[2:3], v[52:53] op_sel_hi:[0,1]
	v_pk_mul_f32 v[50:51], v[2:3], v[50:51] op_sel_hi:[0,1]
	v_pk_mul_f32 v[52:53], v[18:19], v[50:51]
	v_pk_mul_f32 v[50:51], v[16:17], v[54:55]
	v_add_co_u32_e32 v54, vcc, s12, v42
	s_nop 1
	v_addc_co_u32_e32 v55, vcc, -1, v43, vcc
	global_store_dwordx4 v[54:55], v[50:53], off
	global_load_dwordx2 v[50:51], v[36:37], off offset:2048
	s_waitcnt vmcnt(0) lgkmcnt(0)
	v_lshlrev_b32_e32 v52, 16, v50
	v_and_b32_e32 v53, 0xffff0000, v50
	v_lshlrev_b32_e32 v50, 16, v51
	v_and_b32_e32 v51, 0xffff0000, v51
	v_pk_mul_f32 v[54:55], v[2:3], v[52:53] op_sel_hi:[0,1]
	v_pk_mul_f32 v[50:51], v[2:3], v[50:51] op_sel_hi:[0,1]
	v_pk_mul_f32 v[52:53], v[22:23], v[50:51]
	v_pk_mul_f32 v[50:51], v[20:21], v[54:55]
	global_store_dwordx4 v[42:43], v[50:53], off
	global_load_dwordx2 v[50:51], v[36:37], off offset:2560
	s_waitcnt vmcnt(0) lgkmcnt(0)
	v_lshlrev_b32_e32 v52, 16, v50
	v_and_b32_e32 v53, 0xffff0000, v50
	v_lshlrev_b32_e32 v50, 16, v51
	v_and_b32_e32 v51, 0xffff0000, v51
	v_pk_mul_f32 v[54:55], v[2:3], v[52:53] op_sel_hi:[0,1]
	v_pk_mul_f32 v[50:51], v[2:3], v[50:51] op_sel_hi:[0,1]
	v_pk_mul_f32 v[52:53], v[26:27], v[50:51]
	v_pk_mul_f32 v[50:51], v[24:25], v[54:55]
	global_store_dwordx4 v[42:43], v[50:53], off offset:1024
	global_load_dwordx2 v[50:51], v[36:37], off offset:3072
	s_waitcnt vmcnt(0) lgkmcnt(0)
	v_lshlrev_b32_e32 v52, 16, v50
	v_and_b32_e32 v53, 0xffff0000, v50
	v_lshlrev_b32_e32 v50, 16, v51
	v_and_b32_e32 v51, 0xffff0000, v51
	v_pk_mul_f32 v[54:55], v[2:3], v[52:53] op_sel_hi:[0,1]
	v_pk_mul_f32 v[50:51], v[2:3], v[50:51] op_sel_hi:[0,1]
	v_pk_mul_f32 v[52:53], v[30:31], v[50:51]
	v_pk_mul_f32 v[50:51], v[28:29], v[54:55]
	global_store_dwordx4 v[42:43], v[50:53], off offset:2048
	global_load_dwordx2 v[50:51], v[36:37], off offset:3584
	v_lshl_add_u64 v[36:37], v[36:37], 0, s[4:5]
	s_waitcnt vmcnt(0) lgkmcnt(0)
	v_lshlrev_b32_e32 v52, 16, v50
	v_and_b32_e32 v53, 0xffff0000, v50
	v_lshlrev_b32_e32 v50, 16, v51
	v_and_b32_e32 v51, 0xffff0000, v51
	v_pk_mul_f32 v[54:55], v[2:3], v[52:53] op_sel_hi:[0,1]
	v_pk_mul_f32 v[50:51], v[2:3], v[50:51] op_sel_hi:[0,1]
	v_pk_mul_f32 v[52:53], v[34:35], v[50:51]
	v_pk_mul_f32 v[50:51], v[32:33], v[54:55]
	global_store_dwordx4 v[42:43], v[50:53], off offset:3072
	s_cbranch_scc0 .LBB0_1637
	s_getpc_b64 s[98:99]

; DI void phase_postRes_final(const Ctx& c) {
;     ...
;         float s = c.lane < 32 ? ssq[(size_t)row * 32 + c.lane] : 0.f; s = wave_sum(s); const float r = 1.0f / sqrtf(s * (1.0f / DM) + EPS);
.LBB0_1637:
	v_mov_b32_e32 v1, 0
	s_and_saveexec_b64 s[42:43], s[40:41]
	s_cbranch_execz .LBB0_1636
	global_load_dword v1, v[38:39], off
	s_branch .LBB0_1636
